# v-phase code placed 32 bytes later (placement trial)
# baseline (speedup 1.0000x reference)
; __device__ __forceinline__ void peer_v_tokens(int j, const LAS unsigned short* EL, const LAS unsigned char* AL  , const LAS float* ASC  , const LAS int* SAL  , ...
;     asm volatile("" : "+v"(lane));
;     const int BUF[3] = {vslot(3 * wave), vslot(3 * wave + 1), vslot(3 * wave + 2)};
;     const int g = lane >> 3, j8 = lane & 7, s16 = lane & 15, grp = lane >> 4;
;     *(LAS unsigned long long*)(ldsb + BUF[0] + 8 * s16) = 0xFEDCBA9876543210ull;
;     CFENCE();
;     const v2i cal = TR4(ldsb + BUF[0] + 8 * s16);
;     const int pc = cal.x & 15;
;     asm volatile("s_waitcnt lgkmcnt(0)" ::: "memory");
;     const unsigned cx0 = 16u * (unsigned)(j8 ^ (g >> 1)), cx1 = 16u * (unsigned)(j8 ^ (4 + (g >> 1)));
;     const int fr = (4 * (s16 >> 3) + ((s16 & 7) >> 1)) & 7;
;     int roff[4];
; #pragma unroll
;     for (int r = 0; r < 4; ++r) roff[r] = 128 * s16 + 16 * ((((grp >> 1) + 2 * r)) ^ fr) + 8 * (grp & 1);
;     ...
; #pragma unroll 1
;     for (int it = 0; it < 8; ++it) {
;         const int tl = it * 8 + wave, t = j * 64 + tl;
;         unsigned E[8];
;         { const LAS v4u* ep = (const LAS v4u*)(EL + tl * 128 + 16 * g); const v4u e0 = ep[0], e1 = ep[1];
;           E[0] = e0.x; E[1] = e0.y; E[2] = e0.z; E[3] = e0.w; E[4] = e1.x; E[5] = e1.y; E[6] = e1.z; E[7] = e1.w; }
;         uint2 hv[4]; float4 gv[4];
;         { unsigned ho = (unsigned)t * (D / 4) + (unsigned)lane; asm volatile("" : "+v"(ho)); const uint2* hp = (const uint2*)HB + ho; const float4* gp = (const float4*)fng + lane;
; #pragma unroll
;           for (int jq = 0; jq < 4; ++jq) { hv[jq] = hp[64 * jq]; gv[jq] = gp[64 * jq]; } }
;         VDMA(0, 0); VDMA(1, 1);
; #pragma unroll
;         for (int m = 0; m < 2; ++m) {
;             const int idx = lane + 64 * m, tau = idx >> 4, sr = idx & 15, k = 16 * (sr & 7) + 2 * tau + (sr >> 3);
;             const int aq = (int)*(const LAS signed char*)(AL + tl * 128 + k); const int tq = aq + 8;
;             const unsigned lo = (((unsigned)tq & 15u) ^ 8u) * 0x11111111u, hi = ((unsigned)(tq >> 4) & 15u) * 0x11111111u;
;             typedef unsigned u2v __attribute__((ext_vector_type(2)));
;             u2v l2; l2.x = lo; l2.y = lo; u2v h2; h2.x = hi; h2.y = hi;
;             *(LAS u2v*)(ATL + 8 * idx) = l2; *(LAS u2v*)(ATL + 1024 + 8 * idx) = h2;
;         }
;         const float asc = ASC[tl]; const int sa = SAL[tl];
;         CFENCE();
.LBB0_691:
	s_or_b64 exec, exec, s[10:11]
	v_mov_b32_e32 v18, v1
	s_waitcnt lgkmcnt(0)
	s_barrier
	v_readlane_b32 s70, v235, 50
	v_and_b32_e32 v19, 15, v18
	v_lshlrev_b32_e32 v58, 3, v19
	v_add_u32_e32 v20, s60, v58
	ds_write_b64 v20, v[84:85]
	v_lshrrev_b32_e32 v23, 1, v18
	v_ashrrev_i32_e32 v24, 5, v18
	v_and_b32_e32 v25, 8, v23
	ds_read_b64_tr_b4 v[20:21], v20
	v_lshl_or_b32 v19, v19, 7, v25
	v_bitop3_b32 v25, v23, v24, 7 bitop3:0x6c
	v_lshl_add_u32 v59, v25, 4, v19
	v_add_u32_e32 v25, 2, v24
	v_bitop3_b32 v25, v25, v23, 7 bitop3:0x78
	v_lshl_add_u32 v60, v25, 4, v19
	v_add_u32_e32 v25, 4, v24
	v_add_u32_e32 v24, 6, v24
	s_waitcnt lgkmcnt(0)
	v_ashrrev_i32_e32 v21, 4, v18
	v_bitop3_b32 v25, v25, v23, 7 bitop3:0x78
	v_bitop3_b32 v23, v24, v23, 7 bitop3:0x78
	v_bitop3_b32 v22, v18, v21, 7 bitop3:0x6c
	v_add_u32_e32 v21, 4, v21
	v_lshl_add_u32 v61, v25, 4, v19
	v_lshl_add_u32 v62, v23, 4, v19
	v_and_b32_e32 v19, 15, v20
	v_bitop3_b32 v21, v21, v18, 7 bitop3:0x78
	v_lshlrev_b32_e32 v63, 4, v22
	v_lshlrev_b32_e32 v22, 1, v19
	v_ashrrev_i32_e32 v19, 31, v18
	v_lshlrev_b32_e32 v64, 4, v21
	v_lshlrev_b64 v[20:21], 4, v[18:19]
	v_and_b32_e32 v25, 0x7ffffff0, v18
	v_lshl_add_u64 v[34:35], s[86:87], 0, v[20:21]
	v_lshlrev_b32_e32 v19, 4, v18
	v_lshlrev_b32_e32 v25, 1, v25
	v_lshl_add_u64 v[36:37], s[88:89], 0, v[20:21]
	v_add_u32_e32 v21, 64, v18
	s_waitcnt lgkmcnt(0)
	v_and_b32_e32 v19, 0x70, v19
	v_add3_u32 v65, s58, v22, v25
	v_ashrrev_i32_e32 v20, 3, v18
	v_ashrrev_i32_e32 v22, 3, v21
	v_lshrrev_b32_e32 v23, 3, v18
	v_bfe_u32 v24, v18, 3, 1
	v_and_b32_e32 v20, -2, v20
	v_and_b32_e32 v22, -2, v22
	v_lshlrev_b32_e32 v21, 3, v21
	v_add_u32_e32 v19, s72, v19
	v_lshlrev_b32_e32 v66, 3, v18
	v_add_u32_e32 v67, 0x200000, v63
	v_add_u32_e32 v68, 0x200000, v64
	v_add_u32_e32 v69, 0x400000, v63
	v_add_u32_e32 v70, 0x400000, v64
	v_add_u32_e32 v71, 0x600000, v63
	v_add_u32_e32 v72, 0x600000, v64
	v_add3_u32 v73, v19, v22, v24
	v_add3_u32 v74, v19, v20, v24
	v_lshl_add_u32 v75, v23, 5, s65
	v_add_u32_e32 v76, s73, v18
	s_mov_b32 s12, 0
	v_add_u32_e32 v77, s59, v21
	s_mov_b32 s13, s67
	v_readlane_b32 s71, v235, 51
	s_nop 0
	s_nop 0
	s_nop 0
	s_nop 0
	s_nop 0
	s_nop 0
	s_nop 0
	s_nop 0
	s_mov_b32 s76, s60
	s_add_i32 s77, s60, 0x800
	s_mov_b32 s78, s61
	s_add_i32 s79, s61, 0x800
	s_mov_b32 s98, s62
	s_add_i32 s99, s62, 0x800
	v_add_u32_e32 v159, s59, v66
	v_add_u32_e32 v160, s59, v58
	v_add_u32_e32 v154, s58, v66
	v_add_u32_e32 v227, 0x12000, v75
	v_lshlrev_b32_e32 v138, 1, v66
	v_add_u32_e32 v155, 0x11200, v138
	v_add_u32_e32 v156, 0x27400, v138
	global_load_dwordx4 v[210:213], v[34:35], off
	global_load_dwordx4 v[214:217], v[34:35], off offset:1024
	global_load_dwordx4 v[218:221], v[34:35], off offset:2048
	global_load_dwordx4 v[222:225], v[34:35], off offset:3072
	ds_read_b128 v[18:21], v227
	ds_read_b128 v[22:25], v227 offset:16
	v_mov_b32_e32 v138, v74
	ds_read_u8 v139, v138
	v_mov_b32_e32 v141, v73
	ds_read_u8 v140, v141
	v_mov_b32_e32 v150, v63
	v_mov_b32_e32 v151, v64
	s_waitcnt lgkmcnt(0)
	v_and_b32_e32 v78, 0xffff, v18
	v_lshrrev_b32_e32 v79, 16, v18
	v_lshl_add_u32 v78, v78, 7, v150
	v_lshl_add_u32 v79, v79, 7, v151
	s_mov_b32 m0, s76
	s_add_i32 s43, s76, 0x400
	global_load_lds_dwordx4 v78, s[50:51]
	s_mov_b32 m0, s43
	s_nop 0
	global_load_lds_dwordx4 v79, s[50:51]
	v_and_b32_e32 v78, 0xffff, v19
	v_lshrrev_b32_e32 v79, 16, v19
	v_lshl_add_u32 v78, v78, 7, v150
	v_lshl_add_u32 v79, v79, 7, v151
	s_mov_b32 m0, s77
	s_add_i32 s43, s77, 0x400
	global_load_lds_dwordx4 v78, s[50:51]
	s_mov_b32 m0, s43
	s_nop 0
	global_load_lds_dwordx4 v79, s[50:51]
	v_and_b32_e32 v78, 0xffff, v20
	v_lshrrev_b32_e32 v79, 16, v20
	v_lshl_add_u32 v78, v78, 7, v150
	v_lshl_add_u32 v79, v79, 7, v151
	s_mov_b32 m0, s78
	s_add_i32 s43, s78, 0x400
	global_load_lds_dwordx4 v78, s[50:51]
	s_mov_b32 m0, s43
	s_nop 0
	global_load_lds_dwordx4 v79, s[50:51]
	v_and_b32_e32 v78, 0xffff, v21
	v_lshrrev_b32_e32 v79, 16, v21
	v_lshl_add_u32 v78, v78, 7, v150
	v_lshl_add_u32 v79, v79, 7, v151
	s_mov_b32 m0, s79
	s_add_i32 s43, s79, 0x400
	global_load_lds_dwordx4 v78, s[50:51]
	s_mov_b32 m0, s43
	s_nop 0
	global_load_lds_dwordx4 v79, s[50:51]
	v_and_b32_e32 v78, 0xffff, v22
	v_lshrrev_b32_e32 v79, 16, v22
	v_lshl_add_u32 v78, v78, 7, v150
	v_lshl_add_u32 v79, v79, 7, v151
	s_mov_b32 m0, s98
	s_add_i32 s43, s98, 0x400
	global_load_lds_dwordx4 v78, s[50:51]
	s_mov_b32 m0, s43
	s_nop 0
	global_load_lds_dwordx4 v79, s[50:51]
	v_add_u32_e32 v143, 8, v139
	v_and_b32_e32 v142, 15, v143
	v_xor_b32_e32 v142, 8, v142
	v_bfe_u32 v144, v143, 4, 4
	v_mul_lo_u32 v142, v142, s92
	v_mul_lo_u32 v144, v144, s92
	v_mov_b32_e32 v143, v142
	v_mov_b32_e32 v145, v144
	ds_write2st64_b64 v159, v[142:143], v[144:145] offset1:2
	s_waitcnt vmcnt(10)
	ds_write_b128 v155, v[210:213]
	ds_write_b128 v155, v[214:217] offset:1024
	ds_write_b128 v156, v[218:221]
	ds_write_b128 v156, v[222:225] offset:1024
	s_waitcnt vmcnt(8)
	v_add_u32_e32 v54, s76, v59
	v_add_u32_e32 v55, s76, v60
	v_add_u32_e32 v56, s76, v61
	v_add_u32_e32 v57, s76, v62
	ds_read_b64_tr_b4 v[46:47], v160
	ds_read_b64_tr_b4 v[48:49], v160 offset:1024
	ds_read_b64_tr_b4 v[122:123], v54
	ds_read_b64_tr_b4 v[124:125], v55
	ds_read_b64_tr_b4 v[126:127], v56
	ds_read_b64_tr_b4 v[128:129], v57
	v_add_u32_e32 v147, 8, v140
	v_and_b32_e32 v146, 15, v147
	v_xor_b32_e32 v146, 8, v146
	v_bfe_u32 v148, v147, 4, 4
	v_mul_lo_u32 v146, v146, s92
	v_mul_lo_u32 v148, v148, s92
	v_mov_b32_e32 v147, v146
	v_mov_b32_e32 v149, v148
	ds_write2st64_b64 v77, v[146:147], v[148:149] offset1:2
	v_add_u32_e32 v138, 0x400, v74
	ds_read_u8 v139, v138
	v_add_u32_e32 v141, 0x400, v73
	ds_read_u8 v140, v141
	s_mov_b32 s43, s67
	v_mov_b32_e32 v138, s43
	ds_read2st64_b32 v[228:229], v138 offset1:1
	ds_read_b128 v[26:29], v227 offset:2048
	ds_read_b128 v[30:33], v227 offset:2064
	v_mov_b32_e32 v38, 0
	v_mov_b32_e32 v39, 0
	v_mov_b32_e32 v40, 0
	v_mov_b32_e32 v41, 0
	v_mov_b32_e32 v42, 0
	v_mov_b32_e32 v43, 0
	v_mov_b32_e32 v44, 0
	v_mov_b32_e32 v45, 0
	v_and_b32_e32 v78, 0xffff, v23
	v_lshrrev_b32_e32 v79, 16, v23
	v_lshl_add_u32 v78, v78, 7, v150
	v_lshl_add_u32 v79, v79, 7, v151
	s_mov_b32 m0, s99
	s_add_i32 s43, s99, 0x400
	global_load_lds_dwordx4 v78, s[50:51]
	s_mov_b32 m0, s43
	s_nop 0
	global_load_lds_dwordx4 v79, s[50:51]
	s_waitcnt vmcnt(8)
; #define TR4(p_) __builtin_amdgcn_ds_read_tr4_b64_v2i32((LAS v2i*)(p_))
; #define VDMA(st_, k_) do { _Pragma("unroll") for (int i_ = 0; i_ < 4; ++i_) { \
;         const unsigned off_ = (unsigned)((st_) >> 2) * (16384u * 128u) + (PE_ID(E, 4 * ((st_) & 3) + i_) << 7) + ((i_ & 1) ? cx1 : cx0); \
;         __builtin_amdgcn_global_load_lds((const unsigned*)(V4 + off_), (LAS unsigned*)(ldsb + BUF[k_] + 1024 * i_), 16, 0, 0); } } while (0)
; __device__ __forceinline__ void peer_v_tokens(int j, const LAS unsigned short* EL, const LAS unsigned char* AL  , const LAS float* ASC  , const LAS int* SAL  , ...
;     ...
;         for (int st = 0; st < 16; ++st) {
;             const int p = st >> 2, q = st & 3;
;             if (st < 14) VDMA(st + 2, (st + 2) % 3);
;             if (st < 14) asm volatile("s_waitcnt vmcnt(8)" ::: "memory");
;             else if (st == 14) asm volatile("s_waitcnt vmcnt(4)" ::: "memory");
;             else asm volatile("s_waitcnt vmcnt(0)" ::: "memory");
;             if (q == 0) {
; #pragma unroll
;                 for (int r = 0; r < 4; ++r) { accH[r] = 0; accL[r] = 0; } }
; #pragma unroll
;             for (int tp = 0; tp < 2; ++tp) {
;                 const v2i ao = TR4(ATL + (2 * q + tp) * 128 + 8 * s16), ah = TR4(ATL + 1024 + (2 * q + tp) * 128 + 8 * s16);
; #pragma unroll
;                 for (int r = 0; r < 4; ++r) {
;                     const v2i d = TR4(ldsb + BUF[st % 3] + 2048 * tp + roff[r]);
;                     accH[r] = __builtin_amdgcn_sdot8(d.x, ah.x, accH[r], false); accH[r] = __builtin_amdgcn_sdot8(d.y, ah.y, accH[r], false);
;                     accL[r] = __builtin_amdgcn_sdot8(d.x, ao.x, accL[r], false); accL[r] = __builtin_amdgcn_sdot8(d.y, ao.y, accL[r], false);
;                 }
;             }
	v_add_u32_e32 v54, s77, v59
	v_add_u32_e32 v55, s77, v60
	v_add_u32_e32 v56, s77, v61
	v_add_u32_e32 v57, s77, v62
	ds_read_b64_tr_b4 v[50:51], v160 offset:128
	ds_read_b64_tr_b4 v[52:53], v160 offset:1152
	ds_read_b64_tr_b4 v[130:131], v54
	ds_read_b64_tr_b4 v[132:133], v55
	ds_read_b64_tr_b4 v[134:135], v56
	ds_read_b64_tr_b4 v[136:137], v57
	s_waitcnt lgkmcnt(12)
	v_dot8c_i32_i4_e32 v38, v122, v48
	v_dot8c_i32_i4_e32 v39, v122, v46
	v_dot8c_i32_i4_e32 v40, v124, v48
	v_dot8c_i32_i4_e32 v41, v124, v46
	v_dot8c_i32_i4_e32 v42, v126, v48
	v_dot8c_i32_i4_e32 v43, v126, v46
	v_dot8c_i32_i4_e32 v44, v128, v48
	v_dot8c_i32_i4_e32 v45, v128, v46
	v_dot8c_i32_i4_e32 v38, v123, v49
	v_dot8c_i32_i4_e32 v39, v123, v47
	v_dot8c_i32_i4_e32 v40, v125, v49
	v_dot8c_i32_i4_e32 v41, v125, v47
	v_dot8c_i32_i4_e32 v42, v127, v49
	v_dot8c_i32_i4_e32 v43, v127, v47
	v_dot8c_i32_i4_e32 v44, v129, v49
	v_dot8c_i32_i4_e32 v45, v129, v47
	v_and_b32_e32 v78, 0xffff, v24
	v_lshrrev_b32_e32 v79, 16, v24
	v_lshl_add_u32 v78, v78, 7, v150
	v_lshl_add_u32 v79, v79, 7, v151
	s_mov_b32 m0, s76
	s_add_i32 s43, s76, 0x400
	global_load_lds_dwordx4 v78, s[50:51]
	s_mov_b32 m0, s43
	s_nop 0
	global_load_lds_dwordx4 v79, s[50:51]
	s_waitcnt vmcnt(8)
	v_add_u32_e32 v54, s78, v59
	v_add_u32_e32 v55, s78, v60
	v_add_u32_e32 v56, s78, v61
	v_add_u32_e32 v57, s78, v62
	ds_read_b64_tr_b4 v[46:47], v160 offset:256
	ds_read_b64_tr_b4 v[48:49], v160 offset:1280
	ds_read_b64_tr_b4 v[122:123], v54
	ds_read_b64_tr_b4 v[124:125], v55
	ds_read_b64_tr_b4 v[126:127], v56
	ds_read_b64_tr_b4 v[128:129], v57
	s_waitcnt lgkmcnt(6)
	v_dot8c_i32_i4_e32 v38, v130, v52
	v_dot8c_i32_i4_e32 v39, v130, v50
	v_dot8c_i32_i4_e32 v40, v132, v52
	v_dot8c_i32_i4_e32 v41, v132, v50
	v_dot8c_i32_i4_e32 v42, v134, v52
	v_dot8c_i32_i4_e32 v43, v134, v50
	v_dot8c_i32_i4_e32 v44, v136, v52
	v_dot8c_i32_i4_e32 v45, v136, v50
	v_dot8c_i32_i4_e32 v38, v131, v53
	v_dot8c_i32_i4_e32 v39, v131, v51
	v_dot8c_i32_i4_e32 v40, v133, v53
	v_dot8c_i32_i4_e32 v41, v133, v51
	v_dot8c_i32_i4_e32 v42, v135, v53
	v_dot8c_i32_i4_e32 v43, v135, v51
	v_dot8c_i32_i4_e32 v44, v137, v53
	v_dot8c_i32_i4_e32 v45, v137, v51
	v_and_b32_e32 v78, 0xffff, v25
	v_lshrrev_b32_e32 v79, 16, v25
	v_lshl_add_u32 v78, v78, 7, v150
	v_lshl_add_u32 v79, v79, 7, v151
	s_mov_b32 m0, s77
	s_add_i32 s43, s77, 0x400
	global_load_lds_dwordx4 v78, s[50:51]
	s_mov_b32 m0, s43
	s_nop 0
	global_load_lds_dwordx4 v79, s[50:51]
	s_waitcnt vmcnt(8)
	v_add_u32_e32 v54, s79, v59
	v_add_u32_e32 v55, s79, v60
	v_add_u32_e32 v56, s79, v61
	v_add_u32_e32 v57, s79, v62
	ds_read_b64_tr_b4 v[50:51], v160 offset:384
	ds_read_b64_tr_b4 v[52:53], v160 offset:1408
	ds_read_b64_tr_b4 v[130:131], v54
	ds_read_b64_tr_b4 v[132:133], v55
	ds_read_b64_tr_b4 v[134:135], v56
	ds_read_b64_tr_b4 v[136:137], v57
	s_waitcnt lgkmcnt(6)
	v_dot8c_i32_i4_e32 v38, v122, v48
	v_dot8c_i32_i4_e32 v39, v122, v46
	v_dot8c_i32_i4_e32 v40, v124, v48
	v_dot8c_i32_i4_e32 v41, v124, v46
	v_dot8c_i32_i4_e32 v42, v126, v48
	v_dot8c_i32_i4_e32 v43, v126, v46
	v_dot8c_i32_i4_e32 v44, v128, v48
	v_dot8c_i32_i4_e32 v45, v128, v46
	v_dot8c_i32_i4_e32 v38, v123, v49
	v_dot8c_i32_i4_e32 v39, v123, v47
	v_dot8c_i32_i4_e32 v40, v125, v49
	v_dot8c_i32_i4_e32 v41, v125, v47
	v_dot8c_i32_i4_e32 v42, v127, v49
	v_dot8c_i32_i4_e32 v43, v127, v47
	v_dot8c_i32_i4_e32 v44, v129, v49
	v_dot8c_i32_i4_e32 v45, v129, v47
	s_waitcnt lgkmcnt(15)
	v_and_b32_e32 v78, 0xffff, v26
	v_lshrrev_b32_e32 v79, 16, v26
	v_lshl_add_u32 v78, v78, 7, v150
	v_lshl_add_u32 v79, v79, 7, v151
	s_mov_b32 m0, s78
	s_add_i32 s43, s78, 0x400
	global_load_lds_dwordx4 v78, s[50:51]
	s_mov_b32 m0, s43
	s_nop 0
	global_load_lds_dwordx4 v79, s[50:51]
	s_waitcnt vmcnt(8)
	v_add_u32_e32 v54, s98, v59
	v_add_u32_e32 v55, s98, v60
	v_add_u32_e32 v56, s98, v61
	v_add_u32_e32 v57, s98, v62
	ds_read_b64_tr_b4 v[46:47], v160 offset:512
	ds_read_b64_tr_b4 v[48:49], v160 offset:1536
	ds_read_b64_tr_b4 v[122:123], v54
	ds_read_b64_tr_b4 v[124:125], v55
	ds_read_b64_tr_b4 v[126:127], v56
	ds_read_b64_tr_b4 v[128:129], v57
	s_waitcnt lgkmcnt(6)
	v_dot8c_i32_i4_e32 v38, v130, v52
	v_dot8c_i32_i4_e32 v39, v130, v50
	v_dot8c_i32_i4_e32 v40, v132, v52
	v_dot8c_i32_i4_e32 v41, v132, v50
	v_dot8c_i32_i4_e32 v42, v134, v52
	v_dot8c_i32_i4_e32 v43, v134, v50
	v_dot8c_i32_i4_e32 v44, v136, v52
	v_dot8c_i32_i4_e32 v45, v136, v50
	v_dot8c_i32_i4_e32 v38, v131, v53
	v_dot8c_i32_i4_e32 v39, v131, v51
	v_dot8c_i32_i4_e32 v40, v133, v53
	v_dot8c_i32_i4_e32 v41, v133, v51
	v_dot8c_i32_i4_e32 v42, v135, v53
	v_dot8c_i32_i4_e32 v43, v135, v51
	v_dot8c_i32_i4_e32 v44, v137, v53
	v_dot8c_i32_i4_e32 v45, v137, v51
	v_and_b32_e32 v78, 0xffff, v27
	v_lshrrev_b32_e32 v79, 16, v27
	v_lshl_add_u32 v78, v78, 7, v150
	v_lshl_add_u32 v79, v79, 7, v151
	s_mov_b32 m0, s79
	s_add_i32 s43, s79, 0x400
	global_load_lds_dwordx4 v78, s[50:51]
	s_mov_b32 m0, s43
	s_nop 0
	global_load_lds_dwordx4 v79, s[50:51]
	s_waitcnt vmcnt(8)
	v_add_u32_e32 v54, s99, v59
	v_add_u32_e32 v55, s99, v60
	v_add_u32_e32 v56, s99, v61
	v_add_u32_e32 v57, s99, v62
	ds_read_b64_tr_b4 v[50:51], v160 offset:640
	ds_read_b64_tr_b4 v[52:53], v160 offset:1664
	ds_read_b64_tr_b4 v[130:131], v54
	ds_read_b64_tr_b4 v[132:133], v55
	ds_read_b64_tr_b4 v[134:135], v56
	ds_read_b64_tr_b4 v[136:137], v57
	s_waitcnt lgkmcnt(6)
	v_dot8c_i32_i4_e32 v38, v122, v48
	v_dot8c_i32_i4_e32 v39, v122, v46
	v_dot8c_i32_i4_e32 v40, v124, v48
	v_dot8c_i32_i4_e32 v41, v124, v46
	v_dot8c_i32_i4_e32 v42, v126, v48
	v_dot8c_i32_i4_e32 v43, v126, v46
	v_dot8c_i32_i4_e32 v44, v128, v48
	v_dot8c_i32_i4_e32 v45, v128, v46
	v_dot8c_i32_i4_e32 v38, v123, v49
	v_dot8c_i32_i4_e32 v39, v123, v47
	v_dot8c_i32_i4_e32 v40, v125, v49
	v_dot8c_i32_i4_e32 v41, v125, v47
	v_dot8c_i32_i4_e32 v42, v127, v49
	v_dot8c_i32_i4_e32 v43, v127, v47
	v_dot8c_i32_i4_e32 v44, v129, v49
	v_dot8c_i32_i4_e32 v45, v129, v47
	s_waitcnt lgkmcnt(15)
; #define LAS __attribute__((address_space(3)))
; __device__ __forceinline__ void peer_v_tokens(int j, const LAS unsigned short* EL, const LAS unsigned char* AL  , const LAS float* ASC  , const LAS int* SAL  , ...
;     ...
;             const int idx = lane + 64 * m, tau = idx >> 4, sr = idx & 15, k = 16 * (sr & 7) + 2 * tau + (sr >> 3);
;             const int aq = (int)*(const LAS signed char*)(AL + tl * 128 + k); const int tq = aq + 8;
;             const unsigned lo = (((unsigned)tq & 15u) ^ 8u) * 0x11111111u, hi = ((unsigned)(tq >> 4) & 15u) * 0x11111111u;
;             typedef unsigned u2v __attribute__((ext_vector_type(2)));
;             u2v l2; l2.x = lo; l2.y = lo; u2v h2; h2.x = hi; h2.y = hi;
;             *(LAS u2v*)(ATL + 8 * idx) = l2; *(LAS u2v*)(ATL + 1024 + 8 * idx) = h2;
;         }
;         const float asc = ASC[tl]; const int sa = SAL[tl];
;         CFENCE();
;         int accH[4], accL[4];
; #pragma unroll
;         for (int st = 0; st < 16; ++st) {
;             const int p = st >> 2, q = st & 3;
;             if (st < 14) VDMA(st + 2, (st + 2) % 3);
;             if (st < 14) asm volatile("s_waitcnt vmcnt(8)" ::: "memory");
;             else if (st == 14) asm volatile("s_waitcnt vmcnt(4)" ::: "memory");
;             else asm volatile("s_waitcnt vmcnt(0)" ::: "memory");
;             if (q == 0) {
; #pragma unroll
;                 for (int r = 0; r < 4; ++r) { accH[r] = 0; accL[r] = 0; } }
; #pragma unroll
;             for (int tp = 0; tp < 2; ++tp) {
;                 const v2i ao = TR4(ATL + (2 * q + tp) * 128 + 8 * s16), ah = TR4(ATL + 1024 + (2 * q + tp) * 128 + 8 * s16);
; #pragma unroll
;                 for (int r = 0; r < 4; ++r) {
;                     const v2i d = TR4(ldsb + BUF[st % 3] + 2048 * tp + roff[r]);
;                     accH[r] = __builtin_amdgcn_sdot8(d.x, ah.x, accH[r], false); accH[r] = __builtin_amdgcn_sdot8(d.y, ah.y, accH[r], false);
;                     accL[r] = __builtin_amdgcn_sdot8(d.x, ao.x, accL[r], false); accL[r] = __builtin_amdgcn_sdot8(d.y, ao.y, accL[r], false);
;                 }
;             }
;             asm volatile("s_waitcnt lgkmcnt(0)" ::: "memory");
;             if (q == 3) {
; #pragma unroll
;                 for (int r = 0; r < 4; ++r) STASH[256 * p + 16 * (grp + 4 * r) + pc] = f2bf(asc * (float)(2 * ((accH[r] << 4) + accL[r]) + sa));
;             }
	v_add_u32_e32 v143, 8, v139
	v_and_b32_e32 v142, 15, v143
	v_xor_b32_e32 v142, 8, v142
	v_bfe_u32 v144, v143, 4, 4
	v_mul_lo_u32 v142, v142, s92
	v_mul_lo_u32 v144, v144, s92
	v_mov_b32_e32 v143, v142
	v_mov_b32_e32 v145, v144
	ds_write2st64_b64 v159, v[142:143], v[144:145] offset1:2
	v_and_b32_e32 v78, 0xffff, v28
	v_lshrrev_b32_e32 v79, 16, v28
	v_lshl_add_u32 v78, v78, 7, v150
	v_lshl_add_u32 v79, v79, 7, v151
	s_mov_b32 m0, s98
	s_add_i32 s43, s98, 0x400
	global_load_lds_dwordx4 v78, s[50:51]
	s_mov_b32 m0, s43
	s_nop 0
	global_load_lds_dwordx4 v79, s[50:51]
	s_waitcnt vmcnt(8)
	v_add_u32_e32 v54, s76, v59
	v_add_u32_e32 v55, s76, v60
	v_add_u32_e32 v56, s76, v61
	v_add_u32_e32 v57, s76, v62
	ds_read_b64_tr_b4 v[46:47], v160 offset:768
	ds_read_b64_tr_b4 v[48:49], v160 offset:1792
	ds_read_b64_tr_b4 v[122:123], v54
	ds_read_b64_tr_b4 v[124:125], v55
	ds_read_b64_tr_b4 v[126:127], v56
	ds_read_b64_tr_b4 v[128:129], v57
	s_waitcnt lgkmcnt(7)
	v_dot8c_i32_i4_e32 v38, v130, v52
	v_dot8c_i32_i4_e32 v39, v130, v50
	v_dot8c_i32_i4_e32 v40, v132, v52
	v_dot8c_i32_i4_e32 v41, v132, v50
	v_dot8c_i32_i4_e32 v42, v134, v52
	v_dot8c_i32_i4_e32 v43, v134, v50
	v_dot8c_i32_i4_e32 v44, v136, v52
	v_dot8c_i32_i4_e32 v45, v136, v50
	v_dot8c_i32_i4_e32 v38, v131, v53
	v_dot8c_i32_i4_e32 v39, v131, v51
	v_dot8c_i32_i4_e32 v40, v133, v53
	v_dot8c_i32_i4_e32 v41, v133, v51
	v_dot8c_i32_i4_e32 v42, v135, v53
	v_dot8c_i32_i4_e32 v43, v135, v51
	v_dot8c_i32_i4_e32 v44, v137, v53
	v_dot8c_i32_i4_e32 v45, v137, v51
	v_and_b32_e32 v78, 0xffff, v29
	v_lshrrev_b32_e32 v79, 16, v29
	v_lshl_add_u32 v78, v78, 7, v150
	v_lshl_add_u32 v79, v79, 7, v151
	s_mov_b32 m0, s99
	s_add_i32 s43, s99, 0x400
	global_load_lds_dwordx4 v78, s[50:51]
	s_mov_b32 m0, s43
	s_nop 0
	global_load_lds_dwordx4 v79, s[50:51]
	s_waitcnt vmcnt(8)
	v_add_u32_e32 v54, s77, v59
	v_add_u32_e32 v55, s77, v60
	v_add_u32_e32 v56, s77, v61
	v_add_u32_e32 v57, s77, v62
	ds_read_b64_tr_b4 v[50:51], v160 offset:896
	ds_read_b64_tr_b4 v[52:53], v160 offset:1920
	ds_read_b64_tr_b4 v[130:131], v54
	ds_read_b64_tr_b4 v[132:133], v55
	ds_read_b64_tr_b4 v[134:135], v56
	ds_read_b64_tr_b4 v[136:137], v57
	s_waitcnt lgkmcnt(6)
	v_dot8c_i32_i4_e32 v38, v122, v48
	v_dot8c_i32_i4_e32 v39, v122, v46
	v_dot8c_i32_i4_e32 v40, v124, v48
	v_dot8c_i32_i4_e32 v41, v124, v46
	v_dot8c_i32_i4_e32 v42, v126, v48
	v_dot8c_i32_i4_e32 v43, v126, v46
	v_dot8c_i32_i4_e32 v44, v128, v48
	v_dot8c_i32_i4_e32 v45, v128, v46
	v_dot8c_i32_i4_e32 v38, v123, v49
	v_dot8c_i32_i4_e32 v39, v123, v47
	v_dot8c_i32_i4_e32 v40, v125, v49
	v_dot8c_i32_i4_e32 v41, v125, v47
	v_dot8c_i32_i4_e32 v42, v127, v49
	v_dot8c_i32_i4_e32 v43, v127, v47
	v_dot8c_i32_i4_e32 v44, v129, v49
	v_dot8c_i32_i4_e32 v45, v129, v47
	v_and_b32_e32 v78, 0xffff, v30
	v_lshrrev_b32_e32 v79, 16, v30
	v_lshl_add_u32 v78, v78, 7, v150
	v_lshl_add_u32 v79, v79, 7, v151
	s_mov_b32 m0, s76
	s_add_i32 s43, s76, 0x400
	global_load_lds_dwordx4 v78, s[50:51]
	s_mov_b32 m0, s43
	s_nop 0
	global_load_lds_dwordx4 v79, s[50:51]
	s_waitcnt vmcnt(8)
	v_add_u32_e32 v54, s78, v59
	v_add_u32_e32 v55, s78, v60
	v_add_u32_e32 v56, s78, v61
	v_add_u32_e32 v57, s78, v62
	ds_read_b64_tr_b4 v[46:47], v160
	ds_read_b64_tr_b4 v[48:49], v160 offset:1024
	ds_read_b64_tr_b4 v[122:123], v54
	ds_read_b64_tr_b4 v[124:125], v55
	ds_read_b64_tr_b4 v[126:127], v56
	ds_read_b64_tr_b4 v[128:129], v57
	s_waitcnt lgkmcnt(6)
	v_dot8c_i32_i4_e32 v38, v130, v52
	v_dot8c_i32_i4_e32 v39, v130, v50
	v_dot8c_i32_i4_e32 v40, v132, v52
	v_dot8c_i32_i4_e32 v41, v132, v50
	v_dot8c_i32_i4_e32 v42, v134, v52
	v_dot8c_i32_i4_e32 v43, v134, v50
	v_dot8c_i32_i4_e32 v44, v136, v52
	v_dot8c_i32_i4_e32 v45, v136, v50
	v_dot8c_i32_i4_e32 v38, v131, v53
	v_dot8c_i32_i4_e32 v39, v131, v51
	v_dot8c_i32_i4_e32 v40, v133, v53
	v_dot8c_i32_i4_e32 v41, v133, v51
	v_dot8c_i32_i4_e32 v42, v135, v53
	v_dot8c_i32_i4_e32 v43, v135, v51
	v_dot8c_i32_i4_e32 v44, v137, v53
	v_dot8c_i32_i4_e32 v45, v137, v51
	s_nop 3
	s_waitcnt lgkmcnt(15)
	v_lshlrev_b32_e32 v38, 5, v38
	v_lshlrev_b32_e32 v39, 1, v39
	v_add3_u32 v38, v39, v229, v38
	v_cvt_f32_i32_e32 v38, v38
	v_mul_f32_e32 v38, v228, v38
	v_lshlrev_b32_e32 v40, 5, v40
	v_lshlrev_b32_e32 v41, 1, v41
	v_add3_u32 v40, v41, v229, v40
	v_cvt_f32_i32_e32 v40, v40
	v_mul_f32_e32 v40, v228, v40
	v_lshlrev_b32_e32 v42, 5, v42
	v_lshlrev_b32_e32 v43, 1, v43
	v_add3_u32 v42, v43, v229, v42
	v_cvt_f32_i32_e32 v42, v42
	v_mul_f32_e32 v42, v228, v42
	v_lshlrev_b32_e32 v44, 5, v44
	v_lshlrev_b32_e32 v45, 1, v45
	v_add3_u32 v44, v45, v229, v44
	v_cvt_f32_i32_e32 v44, v44
	v_mul_f32_e32 v44, v228, v44
	v_cvt_pk_bf16_f32 v162, v38, v40
	v_cvt_pk_bf16_f32 v163, v42, v44
	v_add_u32_e32 v147, 8, v140
	v_and_b32_e32 v146, 15, v147
	v_xor_b32_e32 v146, 8, v146
	v_bfe_u32 v148, v147, 4, 4
	v_mul_lo_u32 v146, v146, s92
	v_mul_lo_u32 v148, v148, s92
	v_mov_b32_e32 v147, v146
	v_mov_b32_e32 v149, v148
	ds_write2st64_b64 v77, v[146:147], v[148:149] offset1:2
	v_mov_b32_e32 v138, v74
	ds_read_u8 v139, v138
	v_mov_b32_e32 v141, v73
	ds_read_u8 v140, v141
	s_add_i32 s43, s67, 32
	v_mov_b32_e32 v138, s43
	ds_read2st64_b32 v[228:229], v138 offset1:1
	ds_read_b128 v[18:21], v227
	ds_read_b128 v[22:25], v227 offset:16
	v_add_u32_e32 v152, 0x200000, v63
	v_add_u32_e32 v153, 0x200000, v64
	v_mov_b32_e32 v38, 0
	v_mov_b32_e32 v39, 0
	v_mov_b32_e32 v40, 0
	v_mov_b32_e32 v41, 0
	v_mov_b32_e32 v42, 0
	v_mov_b32_e32 v43, 0
	v_mov_b32_e32 v44, 0
	v_mov_b32_e32 v45, 0
	v_and_b32_e32 v78, 0xffff, v31
	v_lshrrev_b32_e32 v79, 16, v31
	v_lshl_add_u32 v78, v78, 7, v150
	v_lshl_add_u32 v79, v79, 7, v151
	s_mov_b32 m0, s77
	s_add_i32 s43, s77, 0x400
	global_load_lds_dwordx4 v78, s[50:51]
	s_mov_b32 m0, s43
	s_nop 0
	global_load_lds_dwordx4 v79, s[50:51]
	s_waitcnt vmcnt(8)
; #define TR4(p_) __builtin_amdgcn_ds_read_tr4_b64_v2i32((LAS v2i*)(p_))
; #define VDMA(st_, k_) do { _Pragma("unroll") for (int i_ = 0; i_ < 4; ++i_) { \
;         const unsigned off_ = (unsigned)((st_) >> 2) * (16384u * 128u) + (PE_ID(E, 4 * ((st_) & 3) + i_) << 7) + ((i_ & 1) ? cx1 : cx0); \
;         __builtin_amdgcn_global_load_lds((const unsigned*)(V4 + off_), (LAS unsigned*)(ldsb + BUF[k_] + 1024 * i_), 16, 0, 0); } } while (0)
; __device__ __forceinline__ void peer_v_tokens(int j, const LAS unsigned short* EL, const LAS unsigned char* AL  , const LAS float* ASC  , const LAS int* SAL  , ...
;     ...
;         for (int st = 0; st < 16; ++st) {
;             const int p = st >> 2, q = st & 3;
;             if (st < 14) VDMA(st + 2, (st + 2) % 3);
;             if (st < 14) asm volatile("s_waitcnt vmcnt(8)" ::: "memory");
;             else if (st == 14) asm volatile("s_waitcnt vmcnt(4)" ::: "memory");
;             else asm volatile("s_waitcnt vmcnt(0)" ::: "memory");
;             if (q == 0) {
; #pragma unroll
;                 for (int r = 0; r < 4; ++r) { accH[r] = 0; accL[r] = 0; } }
; #pragma unroll
;             for (int tp = 0; tp < 2; ++tp) {
;                 const v2i ao = TR4(ATL + (2 * q + tp) * 128 + 8 * s16), ah = TR4(ATL + 1024 + (2 * q + tp) * 128 + 8 * s16);
; #pragma unroll
;                 for (int r = 0; r < 4; ++r) {
;                     const v2i d = TR4(ldsb + BUF[st % 3] + 2048 * tp + roff[r]);
;                     accH[r] = __builtin_amdgcn_sdot8(d.x, ah.x, accH[r], false); accH[r] = __builtin_amdgcn_sdot8(d.y, ah.y, accH[r], false);
;                     accL[r] = __builtin_amdgcn_sdot8(d.x, ao.x, accL[r], false); accL[r] = __builtin_amdgcn_sdot8(d.y, ao.y, accL[r], false);
;                 }
;             }
	v_add_u32_e32 v54, s79, v59
	v_add_u32_e32 v55, s79, v60
	v_add_u32_e32 v56, s79, v61
	v_add_u32_e32 v57, s79, v62
	ds_read_b64_tr_b4 v[50:51], v160 offset:128
	ds_read_b64_tr_b4 v[52:53], v160 offset:1152
	ds_read_b64_tr_b4 v[130:131], v54
	ds_read_b64_tr_b4 v[132:133], v55
	ds_read_b64_tr_b4 v[134:135], v56
	ds_read_b64_tr_b4 v[136:137], v57
	s_waitcnt lgkmcnt(12)
	v_dot8c_i32_i4_e32 v38, v122, v48
	v_dot8c_i32_i4_e32 v39, v122, v46
	v_dot8c_i32_i4_e32 v40, v124, v48
	v_dot8c_i32_i4_e32 v41, v124, v46
	v_dot8c_i32_i4_e32 v42, v126, v48
	v_dot8c_i32_i4_e32 v43, v126, v46
	v_dot8c_i32_i4_e32 v44, v128, v48
	v_dot8c_i32_i4_e32 v45, v128, v46
	v_dot8c_i32_i4_e32 v38, v123, v49
	v_dot8c_i32_i4_e32 v39, v123, v47
	v_dot8c_i32_i4_e32 v40, v125, v49
	v_dot8c_i32_i4_e32 v41, v125, v47
	v_dot8c_i32_i4_e32 v42, v127, v49
	v_dot8c_i32_i4_e32 v43, v127, v47
	v_dot8c_i32_i4_e32 v44, v129, v49
	v_dot8c_i32_i4_e32 v45, v129, v47
	v_and_b32_e32 v78, 0xffff, v32
	v_lshrrev_b32_e32 v79, 16, v32
	v_lshl_add_u32 v78, v78, 7, v150
	v_lshl_add_u32 v79, v79, 7, v151
	s_mov_b32 m0, s78
	s_add_i32 s43, s78, 0x400
	global_load_lds_dwordx4 v78, s[50:51]
	s_mov_b32 m0, s43
	s_nop 0
	global_load_lds_dwordx4 v79, s[50:51]
	s_waitcnt vmcnt(8)
	v_add_u32_e32 v54, s98, v59
	v_add_u32_e32 v55, s98, v60
	v_add_u32_e32 v56, s98, v61
	v_add_u32_e32 v57, s98, v62
	ds_read_b64_tr_b4 v[46:47], v160 offset:256
	ds_read_b64_tr_b4 v[48:49], v160 offset:1280
	ds_read_b64_tr_b4 v[122:123], v54
	ds_read_b64_tr_b4 v[124:125], v55
	ds_read_b64_tr_b4 v[126:127], v56
	ds_read_b64_tr_b4 v[128:129], v57
	s_waitcnt lgkmcnt(6)
	v_dot8c_i32_i4_e32 v38, v130, v52
	v_dot8c_i32_i4_e32 v39, v130, v50
	v_dot8c_i32_i4_e32 v40, v132, v52
	v_dot8c_i32_i4_e32 v41, v132, v50
	v_dot8c_i32_i4_e32 v42, v134, v52
	v_dot8c_i32_i4_e32 v43, v134, v50
	v_dot8c_i32_i4_e32 v44, v136, v52
	v_dot8c_i32_i4_e32 v45, v136, v50
	v_dot8c_i32_i4_e32 v38, v131, v53
	v_dot8c_i32_i4_e32 v39, v131, v51
	v_dot8c_i32_i4_e32 v40, v133, v53
	v_dot8c_i32_i4_e32 v41, v133, v51
	v_dot8c_i32_i4_e32 v42, v135, v53
	v_dot8c_i32_i4_e32 v43, v135, v51
	v_dot8c_i32_i4_e32 v44, v137, v53
	v_dot8c_i32_i4_e32 v45, v137, v51
	v_and_b32_e32 v78, 0xffff, v33
	v_lshrrev_b32_e32 v79, 16, v33
	v_lshl_add_u32 v78, v78, 7, v150
	v_lshl_add_u32 v79, v79, 7, v151
	s_mov_b32 m0, s79
	s_add_i32 s43, s79, 0x400
	global_load_lds_dwordx4 v78, s[50:51]
	s_mov_b32 m0, s43
	s_nop 0
	global_load_lds_dwordx4 v79, s[50:51]
	s_waitcnt vmcnt(8)
	v_add_u32_e32 v54, s99, v59
	v_add_u32_e32 v55, s99, v60
	v_add_u32_e32 v56, s99, v61
	v_add_u32_e32 v57, s99, v62
	ds_read_b64_tr_b4 v[50:51], v160 offset:384
	ds_read_b64_tr_b4 v[52:53], v160 offset:1408
	ds_read_b64_tr_b4 v[130:131], v54
	ds_read_b64_tr_b4 v[132:133], v55
	ds_read_b64_tr_b4 v[134:135], v56
	ds_read_b64_tr_b4 v[136:137], v57
	s_waitcnt lgkmcnt(6)
	v_dot8c_i32_i4_e32 v38, v122, v48
	v_dot8c_i32_i4_e32 v39, v122, v46
	v_dot8c_i32_i4_e32 v40, v124, v48
	v_dot8c_i32_i4_e32 v41, v124, v46
	v_dot8c_i32_i4_e32 v42, v126, v48
	v_dot8c_i32_i4_e32 v43, v126, v46
	v_dot8c_i32_i4_e32 v44, v128, v48
	v_dot8c_i32_i4_e32 v45, v128, v46
	v_dot8c_i32_i4_e32 v38, v123, v49
	v_dot8c_i32_i4_e32 v39, v123, v47
	v_dot8c_i32_i4_e32 v40, v125, v49
	v_dot8c_i32_i4_e32 v41, v125, v47
	v_dot8c_i32_i4_e32 v42, v127, v49
	v_dot8c_i32_i4_e32 v43, v127, v47
	v_dot8c_i32_i4_e32 v44, v129, v49
	v_dot8c_i32_i4_e32 v45, v129, v47
	s_waitcnt lgkmcnt(15)
	v_and_b32_e32 v78, 0xffff, v18
	v_lshrrev_b32_e32 v79, 16, v18
	v_lshl_add_u32 v78, v78, 7, v152
	v_lshl_add_u32 v79, v79, 7, v153
	s_mov_b32 m0, s98
	s_add_i32 s43, s98, 0x400
	global_load_lds_dwordx4 v78, s[50:51]
	s_mov_b32 m0, s43
	s_nop 0
	global_load_lds_dwordx4 v79, s[50:51]
	s_waitcnt vmcnt(8)
	v_add_u32_e32 v54, s76, v59
	v_add_u32_e32 v55, s76, v60
	v_add_u32_e32 v56, s76, v61
	v_add_u32_e32 v57, s76, v62
	ds_read_b64_tr_b4 v[46:47], v160 offset:512
	ds_read_b64_tr_b4 v[48:49], v160 offset:1536
	ds_read_b64_tr_b4 v[122:123], v54
	ds_read_b64_tr_b4 v[124:125], v55
	ds_read_b64_tr_b4 v[126:127], v56
	ds_read_b64_tr_b4 v[128:129], v57
	s_waitcnt lgkmcnt(6)
	v_dot8c_i32_i4_e32 v38, v130, v52
	v_dot8c_i32_i4_e32 v39, v130, v50
	v_dot8c_i32_i4_e32 v40, v132, v52
	v_dot8c_i32_i4_e32 v41, v132, v50
	v_dot8c_i32_i4_e32 v42, v134, v52
	v_dot8c_i32_i4_e32 v43, v134, v50
	v_dot8c_i32_i4_e32 v44, v136, v52
	v_dot8c_i32_i4_e32 v45, v136, v50
	v_dot8c_i32_i4_e32 v38, v131, v53
	v_dot8c_i32_i4_e32 v39, v131, v51
	v_dot8c_i32_i4_e32 v40, v133, v53
	v_dot8c_i32_i4_e32 v41, v133, v51
	v_dot8c_i32_i4_e32 v42, v135, v53
	v_dot8c_i32_i4_e32 v43, v135, v51
	v_dot8c_i32_i4_e32 v44, v137, v53
	v_dot8c_i32_i4_e32 v45, v137, v51
	v_and_b32_e32 v78, 0xffff, v19
	v_lshrrev_b32_e32 v79, 16, v19
	v_lshl_add_u32 v78, v78, 7, v152
	v_lshl_add_u32 v79, v79, 7, v153
	s_mov_b32 m0, s99
	s_add_i32 s43, s99, 0x400
	global_load_lds_dwordx4 v78, s[50:51]
	s_mov_b32 m0, s43
	s_nop 0
	global_load_lds_dwordx4 v79, s[50:51]
	s_waitcnt vmcnt(8)
	v_add_u32_e32 v54, s77, v59
	v_add_u32_e32 v55, s77, v60
	v_add_u32_e32 v56, s77, v61
	v_add_u32_e32 v57, s77, v62
	ds_read_b64_tr_b4 v[50:51], v160 offset:640
	ds_read_b64_tr_b4 v[52:53], v160 offset:1664
	ds_read_b64_tr_b4 v[130:131], v54
	ds_read_b64_tr_b4 v[132:133], v55
	ds_read_b64_tr_b4 v[134:135], v56
	ds_read_b64_tr_b4 v[136:137], v57
	s_waitcnt lgkmcnt(6)
	v_dot8c_i32_i4_e32 v38, v122, v48
	v_dot8c_i32_i4_e32 v39, v122, v46
	v_dot8c_i32_i4_e32 v40, v124, v48
	v_dot8c_i32_i4_e32 v41, v124, v46
	v_dot8c_i32_i4_e32 v42, v126, v48
	v_dot8c_i32_i4_e32 v43, v126, v46
	v_dot8c_i32_i4_e32 v44, v128, v48
	v_dot8c_i32_i4_e32 v45, v128, v46
	v_dot8c_i32_i4_e32 v38, v123, v49
	v_dot8c_i32_i4_e32 v39, v123, v47
	v_dot8c_i32_i4_e32 v40, v125, v49
	v_dot8c_i32_i4_e32 v41, v125, v47
	v_dot8c_i32_i4_e32 v42, v127, v49
	v_dot8c_i32_i4_e32 v43, v127, v47
	v_dot8c_i32_i4_e32 v44, v129, v49
	v_dot8c_i32_i4_e32 v45, v129, v47
	s_waitcnt lgkmcnt(15)
; __device__ __forceinline__ void peer_v_tokens(int j, const LAS unsigned short* EL, const LAS unsigned char* AL  , const LAS float* ASC  , const LAS int* SAL  , ...
;     ...
;         for (int m = 0; m < 2; ++m) {
;             const int idx = lane + 64 * m, tau = idx >> 4, sr = idx & 15, k = 16 * (sr & 7) + 2 * tau + (sr >> 3);
;             const int aq = (int)*(const LAS signed char*)(AL + tl * 128 + k); const int tq = aq + 8;
;             const unsigned lo = (((unsigned)tq & 15u) ^ 8u) * 0x11111111u, hi = ((unsigned)(tq >> 4) & 15u) * 0x11111111u;
;             typedef unsigned u2v __attribute__((ext_vector_type(2)));
;             u2v l2; l2.x = lo; l2.y = lo; u2v h2; h2.x = hi; h2.y = hi;
;             *(LAS u2v*)(ATL + 8 * idx) = l2; *(LAS u2v*)(ATL + 1024 + 8 * idx) = h2;
;         }
;         const float asc = ASC[tl]; const int sa = SAL[tl];
;         CFENCE();
;         int accH[4], accL[4];
; #pragma unroll
;         for (int st = 0; st < 16; ++st) {
;             const int p = st >> 2, q = st & 3;
;             if (st < 14) VDMA(st + 2, (st + 2) % 3);
;             if (st < 14) asm volatile("s_waitcnt vmcnt(8)" ::: "memory");
;             else if (st == 14) asm volatile("s_waitcnt vmcnt(4)" ::: "memory");
;             else asm volatile("s_waitcnt vmcnt(0)" ::: "memory");
;             if (q == 0) {
; #pragma unroll
;                 for (int r = 0; r < 4; ++r) { accH[r] = 0; accL[r] = 0; } }
; #pragma unroll
;             for (int tp = 0; tp < 2; ++tp) {
;                 const v2i ao = TR4(ATL + (2 * q + tp) * 128 + 8 * s16), ah = TR4(ATL + 1024 + (2 * q + tp) * 128 + 8 * s16);
; #pragma unroll
;                 for (int r = 0; r < 4; ++r) {
;                     const v2i d = TR4(ldsb + BUF[st % 3] + 2048 * tp + roff[r]);
;                     accH[r] = __builtin_amdgcn_sdot8(d.x, ah.x, accH[r], false); accH[r] = __builtin_amdgcn_sdot8(d.y, ah.y, accH[r], false);
;                     accL[r] = __builtin_amdgcn_sdot8(d.x, ao.x, accL[r], false); accL[r] = __builtin_amdgcn_sdot8(d.y, ao.y, accL[r], false);
;                 }
;             }
;             asm volatile("s_waitcnt lgkmcnt(0)" ::: "memory");
;             if (q == 3) {
; #pragma unroll
;                 for (int r = 0; r < 4; ++r) STASH[256 * p + 16 * (grp + 4 * r) + pc] = f2bf(asc * (float)(2 * ((accH[r] << 4) + accL[r]) + sa));
;             }
;         }
	v_add_u32_e32 v143, 8, v139
	v_and_b32_e32 v142, 15, v143
	v_xor_b32_e32 v142, 8, v142
	v_bfe_u32 v144, v143, 4, 4
	v_mul_lo_u32 v142, v142, s92
	v_mul_lo_u32 v144, v144, s92
	v_mov_b32_e32 v143, v142
	v_mov_b32_e32 v145, v144
	ds_write2st64_b64 v159, v[142:143], v[144:145] offset1:2
	v_and_b32_e32 v78, 0xffff, v20
	v_lshrrev_b32_e32 v79, 16, v20
	v_lshl_add_u32 v78, v78, 7, v152
	v_lshl_add_u32 v79, v79, 7, v153
	s_mov_b32 m0, s76
	s_add_i32 s43, s76, 0x400
	global_load_lds_dwordx4 v78, s[50:51]
	s_mov_b32 m0, s43
	s_nop 0
	global_load_lds_dwordx4 v79, s[50:51]
	s_waitcnt vmcnt(8)
	v_add_u32_e32 v54, s78, v59
	v_add_u32_e32 v55, s78, v60
	v_add_u32_e32 v56, s78, v61
	v_add_u32_e32 v57, s78, v62
	ds_read_b64_tr_b4 v[46:47], v160 offset:768
	ds_read_b64_tr_b4 v[48:49], v160 offset:1792
	ds_read_b64_tr_b4 v[122:123], v54
	ds_read_b64_tr_b4 v[124:125], v55
	ds_read_b64_tr_b4 v[126:127], v56
	ds_read_b64_tr_b4 v[128:129], v57
	s_waitcnt lgkmcnt(7)
	v_dot8c_i32_i4_e32 v38, v130, v52
	v_dot8c_i32_i4_e32 v39, v130, v50
	v_dot8c_i32_i4_e32 v40, v132, v52
	v_dot8c_i32_i4_e32 v41, v132, v50
	v_dot8c_i32_i4_e32 v42, v134, v52
	v_dot8c_i32_i4_e32 v43, v134, v50
	v_dot8c_i32_i4_e32 v44, v136, v52
	v_dot8c_i32_i4_e32 v45, v136, v50
	v_dot8c_i32_i4_e32 v38, v131, v53
	v_dot8c_i32_i4_e32 v39, v131, v51
	v_dot8c_i32_i4_e32 v40, v133, v53
	v_dot8c_i32_i4_e32 v41, v133, v51
	v_dot8c_i32_i4_e32 v42, v135, v53
	v_dot8c_i32_i4_e32 v43, v135, v51
	v_dot8c_i32_i4_e32 v44, v137, v53
	v_dot8c_i32_i4_e32 v45, v137, v51
	v_and_b32_e32 v78, 0xffff, v21
	v_lshrrev_b32_e32 v79, 16, v21
	v_lshl_add_u32 v78, v78, 7, v152
	v_lshl_add_u32 v79, v79, 7, v153
	s_mov_b32 m0, s77
	s_add_i32 s43, s77, 0x400
	global_load_lds_dwordx4 v78, s[50:51]
	s_mov_b32 m0, s43
	s_nop 0
	global_load_lds_dwordx4 v79, s[50:51]
	s_waitcnt vmcnt(8)
	v_add_u32_e32 v54, s79, v59
	v_add_u32_e32 v55, s79, v60
	v_add_u32_e32 v56, s79, v61
	v_add_u32_e32 v57, s79, v62
	ds_read_b64_tr_b4 v[50:51], v160 offset:896
	ds_read_b64_tr_b4 v[52:53], v160 offset:1920
	ds_read_b64_tr_b4 v[130:131], v54
	ds_read_b64_tr_b4 v[132:133], v55
	ds_read_b64_tr_b4 v[134:135], v56
	ds_read_b64_tr_b4 v[136:137], v57
	s_waitcnt lgkmcnt(6)
	v_dot8c_i32_i4_e32 v38, v122, v48
	v_dot8c_i32_i4_e32 v39, v122, v46
	v_dot8c_i32_i4_e32 v40, v124, v48
	v_dot8c_i32_i4_e32 v41, v124, v46
	v_dot8c_i32_i4_e32 v42, v126, v48
	v_dot8c_i32_i4_e32 v43, v126, v46
	v_dot8c_i32_i4_e32 v44, v128, v48
	v_dot8c_i32_i4_e32 v45, v128, v46
	v_dot8c_i32_i4_e32 v38, v123, v49
	v_dot8c_i32_i4_e32 v39, v123, v47
	v_dot8c_i32_i4_e32 v40, v125, v49
	v_dot8c_i32_i4_e32 v41, v125, v47
	v_dot8c_i32_i4_e32 v42, v127, v49
	v_dot8c_i32_i4_e32 v43, v127, v47
	v_dot8c_i32_i4_e32 v44, v129, v49
	v_dot8c_i32_i4_e32 v45, v129, v47
	v_and_b32_e32 v78, 0xffff, v22
	v_lshrrev_b32_e32 v79, 16, v22
	v_lshl_add_u32 v78, v78, 7, v152
	v_lshl_add_u32 v79, v79, 7, v153
	s_mov_b32 m0, s78
	s_add_i32 s43, s78, 0x400
	global_load_lds_dwordx4 v78, s[50:51]
	s_mov_b32 m0, s43
	s_nop 0
	global_load_lds_dwordx4 v79, s[50:51]
	s_waitcnt vmcnt(8)
	v_add_u32_e32 v54, s98, v59
	v_add_u32_e32 v55, s98, v60
	v_add_u32_e32 v56, s98, v61
	v_add_u32_e32 v57, s98, v62
	ds_read_b64_tr_b4 v[46:47], v160
	ds_read_b64_tr_b4 v[48:49], v160 offset:1024
	ds_read_b64_tr_b4 v[122:123], v54
	ds_read_b64_tr_b4 v[124:125], v55
	ds_read_b64_tr_b4 v[126:127], v56
	ds_read_b64_tr_b4 v[128:129], v57
	s_waitcnt lgkmcnt(6)
	v_dot8c_i32_i4_e32 v38, v130, v52
	v_dot8c_i32_i4_e32 v39, v130, v50
	v_dot8c_i32_i4_e32 v40, v132, v52
	v_dot8c_i32_i4_e32 v41, v132, v50
	v_dot8c_i32_i4_e32 v42, v134, v52
	v_dot8c_i32_i4_e32 v43, v134, v50
	v_dot8c_i32_i4_e32 v44, v136, v52
	v_dot8c_i32_i4_e32 v45, v136, v50
	v_dot8c_i32_i4_e32 v38, v131, v53
	v_dot8c_i32_i4_e32 v39, v131, v51
	v_dot8c_i32_i4_e32 v40, v133, v53
	v_dot8c_i32_i4_e32 v41, v133, v51
	v_dot8c_i32_i4_e32 v42, v135, v53
	v_dot8c_i32_i4_e32 v43, v135, v51
	v_dot8c_i32_i4_e32 v44, v137, v53
	v_dot8c_i32_i4_e32 v45, v137, v51
	s_nop 3
	s_waitcnt lgkmcnt(15)
	v_lshlrev_b32_e32 v38, 5, v38
	v_lshlrev_b32_e32 v39, 1, v39
	v_add3_u32 v38, v39, v229, v38
	v_cvt_f32_i32_e32 v38, v38
	v_mul_f32_e32 v38, v228, v38
	v_lshlrev_b32_e32 v40, 5, v40
	v_lshlrev_b32_e32 v41, 1, v41
	v_add3_u32 v40, v41, v229, v40
	v_cvt_f32_i32_e32 v40, v40
	v_mul_f32_e32 v40, v228, v40
	v_lshlrev_b32_e32 v42, 5, v42
	v_lshlrev_b32_e32 v43, 1, v43
	v_add3_u32 v42, v43, v229, v42
	v_cvt_f32_i32_e32 v42, v42
	v_mul_f32_e32 v42, v228, v42
	v_lshlrev_b32_e32 v44, 5, v44
	v_lshlrev_b32_e32 v45, 1, v45
	v_add3_u32 v44, v45, v229, v44
	v_cvt_f32_i32_e32 v44, v44
	v_mul_f32_e32 v44, v228, v44
	v_cvt_pk_bf16_f32 v170, v38, v40
	v_cvt_pk_bf16_f32 v171, v42, v44
	v_add_u32_e32 v147, 8, v140
	v_and_b32_e32 v146, 15, v147
	v_xor_b32_e32 v146, 8, v146
	v_bfe_u32 v148, v147, 4, 4
	v_mul_lo_u32 v146, v146, s92
	v_mul_lo_u32 v148, v148, s92
	v_mov_b32_e32 v147, v146
	v_mov_b32_e32 v149, v148
	ds_write2st64_b64 v77, v[146:147], v[148:149] offset1:2
	v_add_u32_e32 v138, 0x400, v74
	ds_read_u8 v139, v138
	v_add_u32_e32 v141, 0x400, v73
	ds_read_u8 v140, v141
	s_mov_b32 s43, s67
	v_mov_b32_e32 v138, s43
	ds_read2st64_b32 v[228:229], v138 offset1:1
	ds_read_b128 v[26:29], v227 offset:2048
	ds_read_b128 v[30:33], v227 offset:2064
	v_mov_b32_e32 v38, 0
	v_mov_b32_e32 v39, 0
	v_mov_b32_e32 v40, 0
	v_mov_b32_e32 v41, 0
	v_mov_b32_e32 v42, 0
	v_mov_b32_e32 v43, 0
	v_mov_b32_e32 v44, 0
	v_mov_b32_e32 v45, 0
	v_and_b32_e32 v78, 0xffff, v23
	v_lshrrev_b32_e32 v79, 16, v23
	v_lshl_add_u32 v78, v78, 7, v152
	v_lshl_add_u32 v79, v79, 7, v153
	s_mov_b32 m0, s79
	s_add_i32 s43, s79, 0x400
	global_load_lds_dwordx4 v78, s[50:51]
	s_mov_b32 m0, s43
	s_nop 0
	global_load_lds_dwordx4 v79, s[50:51]
	s_waitcnt vmcnt(8)
; #define TR4(p_) __builtin_amdgcn_ds_read_tr4_b64_v2i32((LAS v2i*)(p_))
; #define VDMA(st_, k_) do { _Pragma("unroll") for (int i_ = 0; i_ < 4; ++i_) { \
;         const unsigned off_ = (unsigned)((st_) >> 2) * (16384u * 128u) + (PE_ID(E, 4 * ((st_) & 3) + i_) << 7) + ((i_ & 1) ? cx1 : cx0); \
;         __builtin_amdgcn_global_load_lds((const unsigned*)(V4 + off_), (LAS unsigned*)(ldsb + BUF[k_] + 1024 * i_), 16, 0, 0); } } while (0)
; __device__ __forceinline__ void peer_v_tokens(int j, const LAS unsigned short* EL, const LAS unsigned char* AL  , const LAS float* ASC  , const LAS int* SAL  , ...
;     ...
;         for (int st = 0; st < 16; ++st) {
;             const int p = st >> 2, q = st & 3;
;             if (st < 14) VDMA(st + 2, (st + 2) % 3);
;             if (st < 14) asm volatile("s_waitcnt vmcnt(8)" ::: "memory");
;             else if (st == 14) asm volatile("s_waitcnt vmcnt(4)" ::: "memory");
;             else asm volatile("s_waitcnt vmcnt(0)" ::: "memory");
;             if (q == 0) {
; #pragma unroll
;                 for (int r = 0; r < 4; ++r) { accH[r] = 0; accL[r] = 0; } }
; #pragma unroll
;             for (int tp = 0; tp < 2; ++tp) {
;                 const v2i ao = TR4(ATL + (2 * q + tp) * 128 + 8 * s16), ah = TR4(ATL + 1024 + (2 * q + tp) * 128 + 8 * s16);
; #pragma unroll
;                 for (int r = 0; r < 4; ++r) {
;                     const v2i d = TR4(ldsb + BUF[st % 3] + 2048 * tp + roff[r]);
;                     accH[r] = __builtin_amdgcn_sdot8(d.x, ah.x, accH[r], false); accH[r] = __builtin_amdgcn_sdot8(d.y, ah.y, accH[r], false);
;                     accL[r] = __builtin_amdgcn_sdot8(d.x, ao.x, accL[r], false); accL[r] = __builtin_amdgcn_sdot8(d.y, ao.y, accL[r], false);
;                 }
;             }
;             asm volatile("s_waitcnt lgkmcnt(0)" ::: "memory");
	v_add_u32_e32 v54, s99, v59
	v_add_u32_e32 v55, s99, v60
	v_add_u32_e32 v56, s99, v61
	v_add_u32_e32 v57, s99, v62
	ds_read_b64_tr_b4 v[50:51], v160 offset:128
	ds_read_b64_tr_b4 v[52:53], v160 offset:1152
	ds_read_b64_tr_b4 v[130:131], v54
	ds_read_b64_tr_b4 v[132:133], v55
	ds_read_b64_tr_b4 v[134:135], v56
	ds_read_b64_tr_b4 v[136:137], v57
	s_waitcnt lgkmcnt(12)
	v_dot8c_i32_i4_e32 v38, v122, v48
	v_dot8c_i32_i4_e32 v39, v122, v46
	v_dot8c_i32_i4_e32 v40, v124, v48
	v_dot8c_i32_i4_e32 v41, v124, v46
	v_dot8c_i32_i4_e32 v42, v126, v48
	v_dot8c_i32_i4_e32 v43, v126, v46
	v_dot8c_i32_i4_e32 v44, v128, v48
	v_dot8c_i32_i4_e32 v45, v128, v46
	v_dot8c_i32_i4_e32 v38, v123, v49
	v_dot8c_i32_i4_e32 v39, v123, v47
	v_dot8c_i32_i4_e32 v40, v125, v49
	v_dot8c_i32_i4_e32 v41, v125, v47
	v_dot8c_i32_i4_e32 v42, v127, v49
	v_dot8c_i32_i4_e32 v43, v127, v47
	v_dot8c_i32_i4_e32 v44, v129, v49
	v_dot8c_i32_i4_e32 v45, v129, v47
	v_and_b32_e32 v78, 0xffff, v24
	v_lshrrev_b32_e32 v79, 16, v24
	v_lshl_add_u32 v78, v78, 7, v152
	v_lshl_add_u32 v79, v79, 7, v153
	s_mov_b32 m0, s98
	s_add_i32 s43, s98, 0x400
	global_load_lds_dwordx4 v78, s[50:51]
	s_mov_b32 m0, s43
	s_nop 0
	global_load_lds_dwordx4 v79, s[50:51]
	s_waitcnt vmcnt(8)
	v_add_u32_e32 v54, s76, v59
	v_add_u32_e32 v55, s76, v60
	v_add_u32_e32 v56, s76, v61
	v_add_u32_e32 v57, s76, v62
	ds_read_b64_tr_b4 v[46:47], v160 offset:256
	ds_read_b64_tr_b4 v[48:49], v160 offset:1280
	ds_read_b64_tr_b4 v[122:123], v54
	ds_read_b64_tr_b4 v[124:125], v55
	ds_read_b64_tr_b4 v[126:127], v56
	ds_read_b64_tr_b4 v[128:129], v57
	s_waitcnt lgkmcnt(6)
	v_dot8c_i32_i4_e32 v38, v130, v52
	v_dot8c_i32_i4_e32 v39, v130, v50
	v_dot8c_i32_i4_e32 v40, v132, v52
	v_dot8c_i32_i4_e32 v41, v132, v50
	v_dot8c_i32_i4_e32 v42, v134, v52
	v_dot8c_i32_i4_e32 v43, v134, v50
	v_dot8c_i32_i4_e32 v44, v136, v52
	v_dot8c_i32_i4_e32 v45, v136, v50
	v_dot8c_i32_i4_e32 v38, v131, v53
	v_dot8c_i32_i4_e32 v39, v131, v51
	v_dot8c_i32_i4_e32 v40, v133, v53
	v_dot8c_i32_i4_e32 v41, v133, v51
	v_dot8c_i32_i4_e32 v42, v135, v53
	v_dot8c_i32_i4_e32 v43, v135, v51
	v_dot8c_i32_i4_e32 v44, v137, v53
	v_dot8c_i32_i4_e32 v45, v137, v51
	v_and_b32_e32 v78, 0xffff, v25
	v_lshrrev_b32_e32 v79, 16, v25
	v_lshl_add_u32 v78, v78, 7, v152
	v_lshl_add_u32 v79, v79, 7, v153
	s_mov_b32 m0, s99
	s_add_i32 s43, s99, 0x400
	global_load_lds_dwordx4 v78, s[50:51]
	s_mov_b32 m0, s43
	s_nop 0
	global_load_lds_dwordx4 v79, s[50:51]
	s_waitcnt vmcnt(8)
	v_add_u32_e32 v54, s77, v59
	v_add_u32_e32 v55, s77, v60
	v_add_u32_e32 v56, s77, v61
	v_add_u32_e32 v57, s77, v62
	ds_read_b64_tr_b4 v[50:51], v160 offset:384
	ds_read_b64_tr_b4 v[52:53], v160 offset:1408
	ds_read_b64_tr_b4 v[130:131], v54
	ds_read_b64_tr_b4 v[132:133], v55
	ds_read_b64_tr_b4 v[134:135], v56
	ds_read_b64_tr_b4 v[136:137], v57
	s_waitcnt lgkmcnt(6)
	v_dot8c_i32_i4_e32 v38, v122, v48
	v_dot8c_i32_i4_e32 v39, v122, v46
	v_dot8c_i32_i4_e32 v40, v124, v48
	v_dot8c_i32_i4_e32 v41, v124, v46
	v_dot8c_i32_i4_e32 v42, v126, v48
	v_dot8c_i32_i4_e32 v43, v126, v46
	v_dot8c_i32_i4_e32 v44, v128, v48
	v_dot8c_i32_i4_e32 v45, v128, v46
	v_dot8c_i32_i4_e32 v38, v123, v49
	v_dot8c_i32_i4_e32 v39, v123, v47
	v_dot8c_i32_i4_e32 v40, v125, v49
	v_dot8c_i32_i4_e32 v41, v125, v47
	v_dot8c_i32_i4_e32 v42, v127, v49
	v_dot8c_i32_i4_e32 v43, v127, v47
	v_dot8c_i32_i4_e32 v44, v129, v49
	v_dot8c_i32_i4_e32 v45, v129, v47
	s_waitcnt lgkmcnt(15)
	v_and_b32_e32 v78, 0xffff, v26
	v_lshrrev_b32_e32 v79, 16, v26
	v_lshl_add_u32 v78, v78, 7, v152
	v_lshl_add_u32 v79, v79, 7, v153
	s_mov_b32 m0, s76
	s_add_i32 s43, s76, 0x400
	global_load_lds_dwordx4 v78, s[50:51]
	s_mov_b32 m0, s43
	s_nop 0
	global_load_lds_dwordx4 v79, s[50:51]
	s_waitcnt vmcnt(8)
	v_add_u32_e32 v54, s78, v59
	v_add_u32_e32 v55, s78, v60
	v_add_u32_e32 v56, s78, v61
	v_add_u32_e32 v57, s78, v62
	ds_read_b64_tr_b4 v[46:47], v160 offset:512
	ds_read_b64_tr_b4 v[48:49], v160 offset:1536
	ds_read_b64_tr_b4 v[122:123], v54
	ds_read_b64_tr_b4 v[124:125], v55
	ds_read_b64_tr_b4 v[126:127], v56
	ds_read_b64_tr_b4 v[128:129], v57
	s_waitcnt lgkmcnt(6)
	v_dot8c_i32_i4_e32 v38, v130, v52
	v_dot8c_i32_i4_e32 v39, v130, v50
	v_dot8c_i32_i4_e32 v40, v132, v52
	v_dot8c_i32_i4_e32 v41, v132, v50
	v_dot8c_i32_i4_e32 v42, v134, v52
	v_dot8c_i32_i4_e32 v43, v134, v50
	v_dot8c_i32_i4_e32 v44, v136, v52
	v_dot8c_i32_i4_e32 v45, v136, v50
	v_dot8c_i32_i4_e32 v38, v131, v53
	v_dot8c_i32_i4_e32 v39, v131, v51
	v_dot8c_i32_i4_e32 v40, v133, v53
	v_dot8c_i32_i4_e32 v41, v133, v51
	v_dot8c_i32_i4_e32 v42, v135, v53
	v_dot8c_i32_i4_e32 v43, v135, v51
	v_dot8c_i32_i4_e32 v44, v137, v53
	v_dot8c_i32_i4_e32 v45, v137, v51
	v_and_b32_e32 v78, 0xffff, v27
	v_lshrrev_b32_e32 v79, 16, v27
	v_lshl_add_u32 v78, v78, 7, v152
	v_lshl_add_u32 v79, v79, 7, v153
	s_mov_b32 m0, s77
	s_add_i32 s43, s77, 0x400
	global_load_lds_dwordx4 v78, s[50:51]
	s_mov_b32 m0, s43
	s_nop 0
	global_load_lds_dwordx4 v79, s[50:51]
	s_waitcnt vmcnt(8)
	v_add_u32_e32 v54, s79, v59
	v_add_u32_e32 v55, s79, v60
	v_add_u32_e32 v56, s79, v61
	v_add_u32_e32 v57, s79, v62
	ds_read_b64_tr_b4 v[50:51], v160 offset:640
	ds_read_b64_tr_b4 v[52:53], v160 offset:1664
	ds_read_b64_tr_b4 v[130:131], v54
	ds_read_b64_tr_b4 v[132:133], v55
	ds_read_b64_tr_b4 v[134:135], v56
	ds_read_b64_tr_b4 v[136:137], v57
	s_waitcnt lgkmcnt(6)
	v_dot8c_i32_i4_e32 v38, v122, v48
	v_dot8c_i32_i4_e32 v39, v122, v46
	v_dot8c_i32_i4_e32 v40, v124, v48
	v_dot8c_i32_i4_e32 v41, v124, v46
	v_dot8c_i32_i4_e32 v42, v126, v48
	v_dot8c_i32_i4_e32 v43, v126, v46
	v_dot8c_i32_i4_e32 v44, v128, v48
	v_dot8c_i32_i4_e32 v45, v128, v46
	v_dot8c_i32_i4_e32 v38, v123, v49
	v_dot8c_i32_i4_e32 v39, v123, v47
	v_dot8c_i32_i4_e32 v40, v125, v49
	v_dot8c_i32_i4_e32 v41, v125, v47
	v_dot8c_i32_i4_e32 v42, v127, v49
	v_dot8c_i32_i4_e32 v43, v127, v47
	v_dot8c_i32_i4_e32 v44, v129, v49
	v_dot8c_i32_i4_e32 v45, v129, v47
	s_waitcnt lgkmcnt(15)
; __device__ __forceinline__ void peer_v_tokens(int j, const LAS unsigned short* EL, const LAS unsigned char* AL  , const LAS float* ASC  , const LAS int* SAL  , ...
;     ...
;         for (int m = 0; m < 2; ++m) {
;             const int idx = lane + 64 * m, tau = idx >> 4, sr = idx & 15, k = 16 * (sr & 7) + 2 * tau + (sr >> 3);
;             const int aq = (int)*(const LAS signed char*)(AL + tl * 128 + k); const int tq = aq + 8;
;             const unsigned lo = (((unsigned)tq & 15u) ^ 8u) * 0x11111111u, hi = ((unsigned)(tq >> 4) & 15u) * 0x11111111u;
;             typedef unsigned u2v __attribute__((ext_vector_type(2)));
;             u2v l2; l2.x = lo; l2.y = lo; u2v h2; h2.x = hi; h2.y = hi;
;             *(LAS u2v*)(ATL + 8 * idx) = l2; *(LAS u2v*)(ATL + 1024 + 8 * idx) = h2;
;         }
;         const float asc = ASC[tl]; const int sa = SAL[tl];
;         CFENCE();
;         int accH[4], accL[4];
; #pragma unroll
;         for (int st = 0; st < 16; ++st) {
;             const int p = st >> 2, q = st & 3;
;             if (st < 14) VDMA(st + 2, (st + 2) % 3);
;             if (st < 14) asm volatile("s_waitcnt vmcnt(8)" ::: "memory");
;             else if (st == 14) asm volatile("s_waitcnt vmcnt(4)" ::: "memory");
;             else asm volatile("s_waitcnt vmcnt(0)" ::: "memory");
;             if (q == 0) {
; #pragma unroll
;                 for (int r = 0; r < 4; ++r) { accH[r] = 0; accL[r] = 0; } }
; #pragma unroll
;             for (int tp = 0; tp < 2; ++tp) {
;                 const v2i ao = TR4(ATL + (2 * q + tp) * 128 + 8 * s16), ah = TR4(ATL + 1024 + (2 * q + tp) * 128 + 8 * s16);
; #pragma unroll
;                 for (int r = 0; r < 4; ++r) {
;                     const v2i d = TR4(ldsb + BUF[st % 3] + 2048 * tp + roff[r]);
;                     accH[r] = __builtin_amdgcn_sdot8(d.x, ah.x, accH[r], false); accH[r] = __builtin_amdgcn_sdot8(d.y, ah.y, accH[r], false);
;                     accL[r] = __builtin_amdgcn_sdot8(d.x, ao.x, accL[r], false); accL[r] = __builtin_amdgcn_sdot8(d.y, ao.y, accL[r], false);
;                 }
;             }
;             asm volatile("s_waitcnt lgkmcnt(0)" ::: "memory");
;             if (q == 3) {
; #pragma unroll
;                 for (int r = 0; r < 4; ++r) STASH[256 * p + 16 * (grp + 4 * r) + pc] = f2bf(asc * (float)(2 * ((accH[r] << 4) + accL[r]) + sa));
;             }
;         }
	v_add_u32_e32 v143, 8, v139
	v_and_b32_e32 v142, 15, v143
	v_xor_b32_e32 v142, 8, v142
	v_bfe_u32 v144, v143, 4, 4
	v_mul_lo_u32 v142, v142, s92
	v_mul_lo_u32 v144, v144, s92
	v_mov_b32_e32 v143, v142
	v_mov_b32_e32 v145, v144
	ds_write2st64_b64 v159, v[142:143], v[144:145] offset1:2
	v_and_b32_e32 v78, 0xffff, v28
	v_lshrrev_b32_e32 v79, 16, v28
	v_lshl_add_u32 v78, v78, 7, v152
	v_lshl_add_u32 v79, v79, 7, v153
	s_mov_b32 m0, s78
	s_add_i32 s43, s78, 0x400
	global_load_lds_dwordx4 v78, s[50:51]
	s_mov_b32 m0, s43
	s_nop 0
	global_load_lds_dwordx4 v79, s[50:51]
	s_waitcnt vmcnt(8)
	v_add_u32_e32 v54, s98, v59
	v_add_u32_e32 v55, s98, v60
	v_add_u32_e32 v56, s98, v61
	v_add_u32_e32 v57, s98, v62
	ds_read_b64_tr_b4 v[46:47], v160 offset:768
	ds_read_b64_tr_b4 v[48:49], v160 offset:1792
	ds_read_b64_tr_b4 v[122:123], v54
	ds_read_b64_tr_b4 v[124:125], v55
	ds_read_b64_tr_b4 v[126:127], v56
	ds_read_b64_tr_b4 v[128:129], v57
	s_waitcnt lgkmcnt(7)
	v_dot8c_i32_i4_e32 v38, v130, v52
	v_dot8c_i32_i4_e32 v39, v130, v50
	v_dot8c_i32_i4_e32 v40, v132, v52
	v_dot8c_i32_i4_e32 v41, v132, v50
	v_dot8c_i32_i4_e32 v42, v134, v52
	v_dot8c_i32_i4_e32 v43, v134, v50
	v_dot8c_i32_i4_e32 v44, v136, v52
	v_dot8c_i32_i4_e32 v45, v136, v50
	v_dot8c_i32_i4_e32 v38, v131, v53
	v_dot8c_i32_i4_e32 v39, v131, v51
	v_dot8c_i32_i4_e32 v40, v133, v53
	v_dot8c_i32_i4_e32 v41, v133, v51
	v_dot8c_i32_i4_e32 v42, v135, v53
	v_dot8c_i32_i4_e32 v43, v135, v51
	v_dot8c_i32_i4_e32 v44, v137, v53
	v_dot8c_i32_i4_e32 v45, v137, v51
	v_and_b32_e32 v78, 0xffff, v29
	v_lshrrev_b32_e32 v79, 16, v29
	v_lshl_add_u32 v78, v78, 7, v152
	v_lshl_add_u32 v79, v79, 7, v153
	s_mov_b32 m0, s79
	s_add_i32 s43, s79, 0x400
	global_load_lds_dwordx4 v78, s[50:51]
	s_mov_b32 m0, s43
	s_nop 0
	global_load_lds_dwordx4 v79, s[50:51]
	s_waitcnt vmcnt(8)
	v_add_u32_e32 v54, s99, v59
	v_add_u32_e32 v55, s99, v60
	v_add_u32_e32 v56, s99, v61
	v_add_u32_e32 v57, s99, v62
	ds_read_b64_tr_b4 v[50:51], v160 offset:896
	ds_read_b64_tr_b4 v[52:53], v160 offset:1920
	ds_read_b64_tr_b4 v[130:131], v54
	ds_read_b64_tr_b4 v[132:133], v55
	ds_read_b64_tr_b4 v[134:135], v56
	ds_read_b64_tr_b4 v[136:137], v57
	s_waitcnt lgkmcnt(6)
	v_dot8c_i32_i4_e32 v38, v122, v48
	v_dot8c_i32_i4_e32 v39, v122, v46
	v_dot8c_i32_i4_e32 v40, v124, v48
	v_dot8c_i32_i4_e32 v41, v124, v46
	v_dot8c_i32_i4_e32 v42, v126, v48
	v_dot8c_i32_i4_e32 v43, v126, v46
	v_dot8c_i32_i4_e32 v44, v128, v48
	v_dot8c_i32_i4_e32 v45, v128, v46
	v_dot8c_i32_i4_e32 v38, v123, v49
	v_dot8c_i32_i4_e32 v39, v123, v47
	v_dot8c_i32_i4_e32 v40, v125, v49
	v_dot8c_i32_i4_e32 v41, v125, v47
	v_dot8c_i32_i4_e32 v42, v127, v49
	v_dot8c_i32_i4_e32 v43, v127, v47
	v_dot8c_i32_i4_e32 v44, v129, v49
	v_dot8c_i32_i4_e32 v45, v129, v47
	v_and_b32_e32 v78, 0xffff, v30
	v_lshrrev_b32_e32 v79, 16, v30
	v_lshl_add_u32 v78, v78, 7, v152
	v_lshl_add_u32 v79, v79, 7, v153
	s_mov_b32 m0, s98
	s_add_i32 s43, s98, 0x400
	global_load_lds_dwordx4 v78, s[50:51]
	s_mov_b32 m0, s43
	s_nop 0
	global_load_lds_dwordx4 v79, s[50:51]
	s_waitcnt vmcnt(8)
	v_add_u32_e32 v54, s76, v59
	v_add_u32_e32 v55, s76, v60
	v_add_u32_e32 v56, s76, v61
	v_add_u32_e32 v57, s76, v62
	ds_read_b64_tr_b4 v[46:47], v160
	ds_read_b64_tr_b4 v[48:49], v160 offset:1024
	ds_read_b64_tr_b4 v[122:123], v54
	ds_read_b64_tr_b4 v[124:125], v55
	ds_read_b64_tr_b4 v[126:127], v56
	ds_read_b64_tr_b4 v[128:129], v57
	s_waitcnt lgkmcnt(6)
	v_dot8c_i32_i4_e32 v38, v130, v52
	v_dot8c_i32_i4_e32 v39, v130, v50
	v_dot8c_i32_i4_e32 v40, v132, v52
	v_dot8c_i32_i4_e32 v41, v132, v50
	v_dot8c_i32_i4_e32 v42, v134, v52
	v_dot8c_i32_i4_e32 v43, v134, v50
	v_dot8c_i32_i4_e32 v44, v136, v52
	v_dot8c_i32_i4_e32 v45, v136, v50
	v_dot8c_i32_i4_e32 v38, v131, v53
	v_dot8c_i32_i4_e32 v39, v131, v51
	v_dot8c_i32_i4_e32 v40, v133, v53
	v_dot8c_i32_i4_e32 v41, v133, v51
	v_dot8c_i32_i4_e32 v42, v135, v53
	v_dot8c_i32_i4_e32 v43, v135, v51
	v_dot8c_i32_i4_e32 v44, v137, v53
	v_dot8c_i32_i4_e32 v45, v137, v51
	s_nop 3
	s_waitcnt lgkmcnt(15)
	v_lshlrev_b32_e32 v38, 5, v38
	v_lshlrev_b32_e32 v39, 1, v39
	v_add3_u32 v38, v39, v229, v38
	v_cvt_f32_i32_e32 v38, v38
	v_mul_f32_e32 v38, v228, v38
	v_lshlrev_b32_e32 v40, 5, v40
	v_lshlrev_b32_e32 v41, 1, v41
	v_add3_u32 v40, v41, v229, v40
	v_cvt_f32_i32_e32 v40, v40
	v_mul_f32_e32 v40, v228, v40
	v_lshlrev_b32_e32 v42, 5, v42
	v_lshlrev_b32_e32 v43, 1, v43
	v_add3_u32 v42, v43, v229, v42
	v_cvt_f32_i32_e32 v42, v42
	v_mul_f32_e32 v42, v228, v42
	v_lshlrev_b32_e32 v44, 5, v44
	v_lshlrev_b32_e32 v45, 1, v45
	v_add3_u32 v44, v45, v229, v44
	v_cvt_f32_i32_e32 v44, v44
	v_mul_f32_e32 v44, v228, v44
	v_cvt_pk_bf16_f32 v164, v38, v40
	v_cvt_pk_bf16_f32 v165, v42, v44
	v_add_u32_e32 v147, 8, v140
	v_and_b32_e32 v146, 15, v147
	v_xor_b32_e32 v146, 8, v146
	v_bfe_u32 v148, v147, 4, 4
	v_mul_lo_u32 v146, v146, s92
	v_mul_lo_u32 v148, v148, s92
	v_mov_b32_e32 v147, v146
	v_mov_b32_e32 v149, v148
	ds_write2st64_b64 v77, v[146:147], v[148:149] offset1:2
	v_mov_b32_e32 v138, v74
	ds_read_u8 v139, v138
	v_mov_b32_e32 v141, v73
	ds_read_u8 v140, v141
	s_add_i32 s43, s67, 32
	v_mov_b32_e32 v138, s43
	ds_read2st64_b32 v[228:229], v138 offset1:1
	ds_read_b128 v[18:21], v227
	ds_read_b128 v[22:25], v227 offset:16
	v_add_u32_e32 v150, 0x400000, v63
	v_add_u32_e32 v151, 0x400000, v64
	v_mov_b32_e32 v38, 0
	v_mov_b32_e32 v39, 0
	v_mov_b32_e32 v40, 0
	v_mov_b32_e32 v41, 0
	v_mov_b32_e32 v42, 0
	v_mov_b32_e32 v43, 0
	v_mov_b32_e32 v44, 0
	v_mov_b32_e32 v45, 0
	v_and_b32_e32 v78, 0xffff, v31
	v_lshrrev_b32_e32 v79, 16, v31
	v_lshl_add_u32 v78, v78, 7, v152
	v_lshl_add_u32 v79, v79, 7, v153
	s_mov_b32 m0, s99
	s_add_i32 s43, s99, 0x400
	global_load_lds_dwordx4 v78, s[50:51]
	s_mov_b32 m0, s43
	s_nop 0
	global_load_lds_dwordx4 v79, s[50:51]
	s_waitcnt vmcnt(8)
; #define TR4(p_) __builtin_amdgcn_ds_read_tr4_b64_v2i32((LAS v2i*)(p_))
; #define VDMA(st_, k_) do { _Pragma("unroll") for (int i_ = 0; i_ < 4; ++i_) { \
;         const unsigned off_ = (unsigned)((st_) >> 2) * (16384u * 128u) + (PE_ID(E, 4 * ((st_) & 3) + i_) << 7) + ((i_ & 1) ? cx1 : cx0); \
;         __builtin_amdgcn_global_load_lds((const unsigned*)(V4 + off_), (LAS unsigned*)(ldsb + BUF[k_] + 1024 * i_), 16, 0, 0); } } while (0)
; __device__ __forceinline__ void peer_v_tokens(int j, const LAS unsigned short* EL, const LAS unsigned char* AL  , const LAS float* ASC  , const LAS int* SAL  , ...
;     ...
;         for (int st = 0; st < 16; ++st) {
;             const int p = st >> 2, q = st & 3;
;             if (st < 14) VDMA(st + 2, (st + 2) % 3);
;             if (st < 14) asm volatile("s_waitcnt vmcnt(8)" ::: "memory");
;             else if (st == 14) asm volatile("s_waitcnt vmcnt(4)" ::: "memory");
;             else asm volatile("s_waitcnt vmcnt(0)" ::: "memory");
;             if (q == 0) {
; #pragma unroll
;                 for (int r = 0; r < 4; ++r) { accH[r] = 0; accL[r] = 0; } }
; #pragma unroll
;             for (int tp = 0; tp < 2; ++tp) {
;                 const v2i ao = TR4(ATL + (2 * q + tp) * 128 + 8 * s16), ah = TR4(ATL + 1024 + (2 * q + tp) * 128 + 8 * s16);
; #pragma unroll
;                 for (int r = 0; r < 4; ++r) {
;                     const v2i d = TR4(ldsb + BUF[st % 3] + 2048 * tp + roff[r]);
;                     accH[r] = __builtin_amdgcn_sdot8(d.x, ah.x, accH[r], false); accH[r] = __builtin_amdgcn_sdot8(d.y, ah.y, accH[r], false);
;                     accL[r] = __builtin_amdgcn_sdot8(d.x, ao.x, accL[r], false); accL[r] = __builtin_amdgcn_sdot8(d.y, ao.y, accL[r], false);
;                 }
;             }
;             asm volatile("s_waitcnt lgkmcnt(0)" ::: "memory");
	v_add_u32_e32 v54, s77, v59
	v_add_u32_e32 v55, s77, v60
	v_add_u32_e32 v56, s77, v61
	v_add_u32_e32 v57, s77, v62
	ds_read_b64_tr_b4 v[50:51], v160 offset:128
	ds_read_b64_tr_b4 v[52:53], v160 offset:1152
	ds_read_b64_tr_b4 v[130:131], v54
	ds_read_b64_tr_b4 v[132:133], v55
	ds_read_b64_tr_b4 v[134:135], v56
	ds_read_b64_tr_b4 v[136:137], v57
	s_waitcnt lgkmcnt(12)
	v_dot8c_i32_i4_e32 v38, v122, v48
	v_dot8c_i32_i4_e32 v39, v122, v46
	v_dot8c_i32_i4_e32 v40, v124, v48
	v_dot8c_i32_i4_e32 v41, v124, v46
	v_dot8c_i32_i4_e32 v42, v126, v48
	v_dot8c_i32_i4_e32 v43, v126, v46
	v_dot8c_i32_i4_e32 v44, v128, v48
	v_dot8c_i32_i4_e32 v45, v128, v46
	v_dot8c_i32_i4_e32 v38, v123, v49
	v_dot8c_i32_i4_e32 v39, v123, v47
	v_dot8c_i32_i4_e32 v40, v125, v49
	v_dot8c_i32_i4_e32 v41, v125, v47
	v_dot8c_i32_i4_e32 v42, v127, v49
	v_dot8c_i32_i4_e32 v43, v127, v47
	v_dot8c_i32_i4_e32 v44, v129, v49
	v_dot8c_i32_i4_e32 v45, v129, v47
	v_and_b32_e32 v78, 0xffff, v32
	v_lshrrev_b32_e32 v79, 16, v32
	v_lshl_add_u32 v78, v78, 7, v152
	v_lshl_add_u32 v79, v79, 7, v153
	s_mov_b32 m0, s76
	s_add_i32 s43, s76, 0x400
	global_load_lds_dwordx4 v78, s[50:51]
	s_mov_b32 m0, s43
	s_nop 0
	global_load_lds_dwordx4 v79, s[50:51]
	s_waitcnt vmcnt(8)
	v_add_u32_e32 v54, s78, v59
	v_add_u32_e32 v55, s78, v60
	v_add_u32_e32 v56, s78, v61
	v_add_u32_e32 v57, s78, v62
	ds_read_b64_tr_b4 v[46:47], v160 offset:256
	ds_read_b64_tr_b4 v[48:49], v160 offset:1280
	ds_read_b64_tr_b4 v[122:123], v54
	ds_read_b64_tr_b4 v[124:125], v55
	ds_read_b64_tr_b4 v[126:127], v56
	ds_read_b64_tr_b4 v[128:129], v57
	s_waitcnt lgkmcnt(6)
	v_dot8c_i32_i4_e32 v38, v130, v52
	v_dot8c_i32_i4_e32 v39, v130, v50
	v_dot8c_i32_i4_e32 v40, v132, v52
	v_dot8c_i32_i4_e32 v41, v132, v50
	v_dot8c_i32_i4_e32 v42, v134, v52
	v_dot8c_i32_i4_e32 v43, v134, v50
	v_dot8c_i32_i4_e32 v44, v136, v52
	v_dot8c_i32_i4_e32 v45, v136, v50
	v_dot8c_i32_i4_e32 v38, v131, v53
	v_dot8c_i32_i4_e32 v39, v131, v51
	v_dot8c_i32_i4_e32 v40, v133, v53
	v_dot8c_i32_i4_e32 v41, v133, v51
	v_dot8c_i32_i4_e32 v42, v135, v53
	v_dot8c_i32_i4_e32 v43, v135, v51
	v_dot8c_i32_i4_e32 v44, v137, v53
	v_dot8c_i32_i4_e32 v45, v137, v51
	v_and_b32_e32 v78, 0xffff, v33
	v_lshrrev_b32_e32 v79, 16, v33
	v_lshl_add_u32 v78, v78, 7, v152
	v_lshl_add_u32 v79, v79, 7, v153
	s_mov_b32 m0, s77
	s_add_i32 s43, s77, 0x400
	global_load_lds_dwordx4 v78, s[50:51]
	s_mov_b32 m0, s43
	s_nop 0
	global_load_lds_dwordx4 v79, s[50:51]
	s_waitcnt vmcnt(8)
	v_add_u32_e32 v54, s79, v59
	v_add_u32_e32 v55, s79, v60
	v_add_u32_e32 v56, s79, v61
	v_add_u32_e32 v57, s79, v62
	ds_read_b64_tr_b4 v[50:51], v160 offset:384
	ds_read_b64_tr_b4 v[52:53], v160 offset:1408
	ds_read_b64_tr_b4 v[130:131], v54
	ds_read_b64_tr_b4 v[132:133], v55
	ds_read_b64_tr_b4 v[134:135], v56
	ds_read_b64_tr_b4 v[136:137], v57
	s_waitcnt lgkmcnt(6)
	v_dot8c_i32_i4_e32 v38, v122, v48
	v_dot8c_i32_i4_e32 v39, v122, v46
	v_dot8c_i32_i4_e32 v40, v124, v48
	v_dot8c_i32_i4_e32 v41, v124, v46
	v_dot8c_i32_i4_e32 v42, v126, v48
	v_dot8c_i32_i4_e32 v43, v126, v46
	v_dot8c_i32_i4_e32 v44, v128, v48
	v_dot8c_i32_i4_e32 v45, v128, v46
	v_dot8c_i32_i4_e32 v38, v123, v49
	v_dot8c_i32_i4_e32 v39, v123, v47
	v_dot8c_i32_i4_e32 v40, v125, v49
	v_dot8c_i32_i4_e32 v41, v125, v47
	v_dot8c_i32_i4_e32 v42, v127, v49
	v_dot8c_i32_i4_e32 v43, v127, v47
	v_dot8c_i32_i4_e32 v44, v129, v49
	v_dot8c_i32_i4_e32 v45, v129, v47
	s_waitcnt lgkmcnt(15)
	v_and_b32_e32 v78, 0xffff, v18
	v_lshrrev_b32_e32 v79, 16, v18
	v_lshl_add_u32 v78, v78, 7, v150
	v_lshl_add_u32 v79, v79, 7, v151
	s_mov_b32 m0, s78
	s_add_i32 s43, s78, 0x400
	global_load_lds_dwordx4 v78, s[50:51]
	s_mov_b32 m0, s43
	s_nop 0
	global_load_lds_dwordx4 v79, s[50:51]
	s_waitcnt vmcnt(8)
	v_add_u32_e32 v54, s98, v59
	v_add_u32_e32 v55, s98, v60
	v_add_u32_e32 v56, s98, v61
	v_add_u32_e32 v57, s98, v62
	ds_read_b64_tr_b4 v[46:47], v160 offset:512
	ds_read_b64_tr_b4 v[48:49], v160 offset:1536
	ds_read_b64_tr_b4 v[122:123], v54
	ds_read_b64_tr_b4 v[124:125], v55
	ds_read_b64_tr_b4 v[126:127], v56
	ds_read_b64_tr_b4 v[128:129], v57
	s_waitcnt lgkmcnt(6)
	v_dot8c_i32_i4_e32 v38, v130, v52
	v_dot8c_i32_i4_e32 v39, v130, v50
	v_dot8c_i32_i4_e32 v40, v132, v52
	v_dot8c_i32_i4_e32 v41, v132, v50
	v_dot8c_i32_i4_e32 v42, v134, v52
	v_dot8c_i32_i4_e32 v43, v134, v50
	v_dot8c_i32_i4_e32 v44, v136, v52
	v_dot8c_i32_i4_e32 v45, v136, v50
	v_dot8c_i32_i4_e32 v38, v131, v53
	v_dot8c_i32_i4_e32 v39, v131, v51
	v_dot8c_i32_i4_e32 v40, v133, v53
	v_dot8c_i32_i4_e32 v41, v133, v51
	v_dot8c_i32_i4_e32 v42, v135, v53
	v_dot8c_i32_i4_e32 v43, v135, v51
	v_dot8c_i32_i4_e32 v44, v137, v53
	v_dot8c_i32_i4_e32 v45, v137, v51
	v_and_b32_e32 v78, 0xffff, v19
	v_lshrrev_b32_e32 v79, 16, v19
	v_lshl_add_u32 v78, v78, 7, v150
	v_lshl_add_u32 v79, v79, 7, v151
	s_mov_b32 m0, s79
	s_add_i32 s43, s79, 0x400
	global_load_lds_dwordx4 v78, s[50:51]
	s_mov_b32 m0, s43
	s_nop 0
	global_load_lds_dwordx4 v79, s[50:51]
	s_waitcnt vmcnt(8)
	v_add_u32_e32 v54, s99, v59
	v_add_u32_e32 v55, s99, v60
	v_add_u32_e32 v56, s99, v61
	v_add_u32_e32 v57, s99, v62
	ds_read_b64_tr_b4 v[50:51], v160 offset:640
	ds_read_b64_tr_b4 v[52:53], v160 offset:1664
	ds_read_b64_tr_b4 v[130:131], v54
	ds_read_b64_tr_b4 v[132:133], v55
	ds_read_b64_tr_b4 v[134:135], v56
	ds_read_b64_tr_b4 v[136:137], v57
	s_waitcnt lgkmcnt(6)
	v_dot8c_i32_i4_e32 v38, v122, v48
	v_dot8c_i32_i4_e32 v39, v122, v46
	v_dot8c_i32_i4_e32 v40, v124, v48
	v_dot8c_i32_i4_e32 v41, v124, v46
	v_dot8c_i32_i4_e32 v42, v126, v48
	v_dot8c_i32_i4_e32 v43, v126, v46
	v_dot8c_i32_i4_e32 v44, v128, v48
	v_dot8c_i32_i4_e32 v45, v128, v46
	v_dot8c_i32_i4_e32 v38, v123, v49
	v_dot8c_i32_i4_e32 v39, v123, v47
	v_dot8c_i32_i4_e32 v40, v125, v49
	v_dot8c_i32_i4_e32 v41, v125, v47
	v_dot8c_i32_i4_e32 v42, v127, v49
	v_dot8c_i32_i4_e32 v43, v127, v47
	v_dot8c_i32_i4_e32 v44, v129, v49
	v_dot8c_i32_i4_e32 v45, v129, v47
	s_waitcnt lgkmcnt(15)
; __device__ __forceinline__ void peer_v_tokens(int j, const LAS unsigned short* EL, const LAS unsigned char* AL  , const LAS float* ASC  , const LAS int* SAL  , ...
;     ...
;         for (int m = 0; m < 2; ++m) {
;             const int idx = lane + 64 * m, tau = idx >> 4, sr = idx & 15, k = 16 * (sr & 7) + 2 * tau + (sr >> 3);
;             const int aq = (int)*(const LAS signed char*)(AL + tl * 128 + k); const int tq = aq + 8;
;             const unsigned lo = (((unsigned)tq & 15u) ^ 8u) * 0x11111111u, hi = ((unsigned)(tq >> 4) & 15u) * 0x11111111u;
;             typedef unsigned u2v __attribute__((ext_vector_type(2)));
;             u2v l2; l2.x = lo; l2.y = lo; u2v h2; h2.x = hi; h2.y = hi;
;             *(LAS u2v*)(ATL + 8 * idx) = l2; *(LAS u2v*)(ATL + 1024 + 8 * idx) = h2;
;         }
;         const float asc = ASC[tl]; const int sa = SAL[tl];
;         CFENCE();
;         int accH[4], accL[4];
; #pragma unroll
;         for (int st = 0; st < 16; ++st) {
;             const int p = st >> 2, q = st & 3;
;             if (st < 14) VDMA(st + 2, (st + 2) % 3);
;             if (st < 14) asm volatile("s_waitcnt vmcnt(8)" ::: "memory");
;             else if (st == 14) asm volatile("s_waitcnt vmcnt(4)" ::: "memory");
;             else asm volatile("s_waitcnt vmcnt(0)" ::: "memory");
;             if (q == 0) {
; #pragma unroll
;                 for (int r = 0; r < 4; ++r) { accH[r] = 0; accL[r] = 0; } }
; #pragma unroll
;             for (int tp = 0; tp < 2; ++tp) {
;                 const v2i ao = TR4(ATL + (2 * q + tp) * 128 + 8 * s16), ah = TR4(ATL + 1024 + (2 * q + tp) * 128 + 8 * s16);
; #pragma unroll
;                 for (int r = 0; r < 4; ++r) {
;                     const v2i d = TR4(ldsb + BUF[st % 3] + 2048 * tp + roff[r]);
;                     accH[r] = __builtin_amdgcn_sdot8(d.x, ah.x, accH[r], false); accH[r] = __builtin_amdgcn_sdot8(d.y, ah.y, accH[r], false);
;                     accL[r] = __builtin_amdgcn_sdot8(d.x, ao.x, accL[r], false); accL[r] = __builtin_amdgcn_sdot8(d.y, ao.y, accL[r], false);
;                 }
;             }
;             asm volatile("s_waitcnt lgkmcnt(0)" ::: "memory");
;             if (q == 3) {
; #pragma unroll
;                 for (int r = 0; r < 4; ++r) STASH[256 * p + 16 * (grp + 4 * r) + pc] = f2bf(asc * (float)(2 * ((accH[r] << 4) + accL[r]) + sa));
;             }
;         }
	v_add_u32_e32 v143, 8, v139
	v_and_b32_e32 v142, 15, v143
	v_xor_b32_e32 v142, 8, v142
	v_bfe_u32 v144, v143, 4, 4
	v_mul_lo_u32 v142, v142, s92
	v_mul_lo_u32 v144, v144, s92
	v_mov_b32_e32 v143, v142
	v_mov_b32_e32 v145, v144
	ds_write2st64_b64 v159, v[142:143], v[144:145] offset1:2
	v_and_b32_e32 v78, 0xffff, v20
	v_lshrrev_b32_e32 v79, 16, v20
	v_lshl_add_u32 v78, v78, 7, v150
	v_lshl_add_u32 v79, v79, 7, v151
	s_mov_b32 m0, s98
	s_add_i32 s43, s98, 0x400
	global_load_lds_dwordx4 v78, s[50:51]
	s_mov_b32 m0, s43
	s_nop 0
	global_load_lds_dwordx4 v79, s[50:51]
	s_waitcnt vmcnt(8)
	v_add_u32_e32 v54, s76, v59
	v_add_u32_e32 v55, s76, v60
	v_add_u32_e32 v56, s76, v61
	v_add_u32_e32 v57, s76, v62
	ds_read_b64_tr_b4 v[46:47], v160 offset:768
	ds_read_b64_tr_b4 v[48:49], v160 offset:1792
	ds_read_b64_tr_b4 v[122:123], v54
	ds_read_b64_tr_b4 v[124:125], v55
	ds_read_b64_tr_b4 v[126:127], v56
	ds_read_b64_tr_b4 v[128:129], v57
	s_waitcnt lgkmcnt(7)
	v_dot8c_i32_i4_e32 v38, v130, v52
	v_dot8c_i32_i4_e32 v39, v130, v50
	v_dot8c_i32_i4_e32 v40, v132, v52
	v_dot8c_i32_i4_e32 v41, v132, v50
	v_dot8c_i32_i4_e32 v42, v134, v52
	v_dot8c_i32_i4_e32 v43, v134, v50
	v_dot8c_i32_i4_e32 v44, v136, v52
	v_dot8c_i32_i4_e32 v45, v136, v50
	v_dot8c_i32_i4_e32 v38, v131, v53
	v_dot8c_i32_i4_e32 v39, v131, v51
	v_dot8c_i32_i4_e32 v40, v133, v53
	v_dot8c_i32_i4_e32 v41, v133, v51
	v_dot8c_i32_i4_e32 v42, v135, v53
	v_dot8c_i32_i4_e32 v43, v135, v51
	v_dot8c_i32_i4_e32 v44, v137, v53
	v_dot8c_i32_i4_e32 v45, v137, v51
	v_and_b32_e32 v78, 0xffff, v21
	v_lshrrev_b32_e32 v79, 16, v21
	v_lshl_add_u32 v78, v78, 7, v150
	v_lshl_add_u32 v79, v79, 7, v151
	s_mov_b32 m0, s99
	s_add_i32 s43, s99, 0x400
	global_load_lds_dwordx4 v78, s[50:51]
	s_mov_b32 m0, s43
	s_nop 0
	global_load_lds_dwordx4 v79, s[50:51]
	s_waitcnt vmcnt(8)
	v_add_u32_e32 v54, s77, v59
	v_add_u32_e32 v55, s77, v60
	v_add_u32_e32 v56, s77, v61
	v_add_u32_e32 v57, s77, v62
	ds_read_b64_tr_b4 v[50:51], v160 offset:896
	ds_read_b64_tr_b4 v[52:53], v160 offset:1920
	ds_read_b64_tr_b4 v[130:131], v54
	ds_read_b64_tr_b4 v[132:133], v55
	ds_read_b64_tr_b4 v[134:135], v56
	ds_read_b64_tr_b4 v[136:137], v57
	s_waitcnt lgkmcnt(6)
	v_dot8c_i32_i4_e32 v38, v122, v48
	v_dot8c_i32_i4_e32 v39, v122, v46
	v_dot8c_i32_i4_e32 v40, v124, v48
	v_dot8c_i32_i4_e32 v41, v124, v46
	v_dot8c_i32_i4_e32 v42, v126, v48
	v_dot8c_i32_i4_e32 v43, v126, v46
	v_dot8c_i32_i4_e32 v44, v128, v48
	v_dot8c_i32_i4_e32 v45, v128, v46
	v_dot8c_i32_i4_e32 v38, v123, v49
	v_dot8c_i32_i4_e32 v39, v123, v47
	v_dot8c_i32_i4_e32 v40, v125, v49
	v_dot8c_i32_i4_e32 v41, v125, v47
	v_dot8c_i32_i4_e32 v42, v127, v49
	v_dot8c_i32_i4_e32 v43, v127, v47
	v_dot8c_i32_i4_e32 v44, v129, v49
	v_dot8c_i32_i4_e32 v45, v129, v47
	v_and_b32_e32 v78, 0xffff, v22
	v_lshrrev_b32_e32 v79, 16, v22
	v_lshl_add_u32 v78, v78, 7, v150
	v_lshl_add_u32 v79, v79, 7, v151
	s_mov_b32 m0, s76
	s_add_i32 s43, s76, 0x400
	global_load_lds_dwordx4 v78, s[50:51]
	s_mov_b32 m0, s43
	s_nop 0
	global_load_lds_dwordx4 v79, s[50:51]
	s_waitcnt vmcnt(8)
	v_add_u32_e32 v54, s78, v59
	v_add_u32_e32 v55, s78, v60
	v_add_u32_e32 v56, s78, v61
	v_add_u32_e32 v57, s78, v62
	ds_read_b64_tr_b4 v[46:47], v160
	ds_read_b64_tr_b4 v[48:49], v160 offset:1024
	ds_read_b64_tr_b4 v[122:123], v54
	ds_read_b64_tr_b4 v[124:125], v55
	ds_read_b64_tr_b4 v[126:127], v56
	ds_read_b64_tr_b4 v[128:129], v57
	s_waitcnt lgkmcnt(6)
	v_dot8c_i32_i4_e32 v38, v130, v52
	v_dot8c_i32_i4_e32 v39, v130, v50
	v_dot8c_i32_i4_e32 v40, v132, v52
	v_dot8c_i32_i4_e32 v41, v132, v50
	v_dot8c_i32_i4_e32 v42, v134, v52
	v_dot8c_i32_i4_e32 v43, v134, v50
	v_dot8c_i32_i4_e32 v44, v136, v52
	v_dot8c_i32_i4_e32 v45, v136, v50
	v_dot8c_i32_i4_e32 v38, v131, v53
	v_dot8c_i32_i4_e32 v39, v131, v51
	v_dot8c_i32_i4_e32 v40, v133, v53
	v_dot8c_i32_i4_e32 v41, v133, v51
	v_dot8c_i32_i4_e32 v42, v135, v53
	v_dot8c_i32_i4_e32 v43, v135, v51
	v_dot8c_i32_i4_e32 v44, v137, v53
	v_dot8c_i32_i4_e32 v45, v137, v51
	s_nop 3
	s_waitcnt lgkmcnt(15)
	v_lshlrev_b32_e32 v38, 5, v38
	v_lshlrev_b32_e32 v39, 1, v39
	v_add3_u32 v38, v39, v229, v38
	v_cvt_f32_i32_e32 v38, v38
	v_mul_f32_e32 v38, v228, v38
	v_lshlrev_b32_e32 v40, 5, v40
	v_lshlrev_b32_e32 v41, 1, v41
	v_add3_u32 v40, v41, v229, v40
	v_cvt_f32_i32_e32 v40, v40
	v_mul_f32_e32 v40, v228, v40
	v_lshlrev_b32_e32 v42, 5, v42
	v_lshlrev_b32_e32 v43, 1, v43
	v_add3_u32 v42, v43, v229, v42
	v_cvt_f32_i32_e32 v42, v42
	v_mul_f32_e32 v42, v228, v42
	v_lshlrev_b32_e32 v44, 5, v44
	v_lshlrev_b32_e32 v45, 1, v45
	v_add3_u32 v44, v45, v229, v44
	v_cvt_f32_i32_e32 v44, v44
	v_mul_f32_e32 v44, v228, v44
	v_cvt_pk_bf16_f32 v172, v38, v40
	v_cvt_pk_bf16_f32 v173, v42, v44
	v_add_u32_e32 v147, 8, v140
	v_and_b32_e32 v146, 15, v147
	v_xor_b32_e32 v146, 8, v146
	v_bfe_u32 v148, v147, 4, 4
	v_mul_lo_u32 v146, v146, s92
	v_mul_lo_u32 v148, v148, s92
	v_mov_b32_e32 v147, v146
	v_mov_b32_e32 v149, v148
	ds_write2st64_b64 v77, v[146:147], v[148:149] offset1:2
	v_add_u32_e32 v138, 0x400, v74
	ds_read_u8 v139, v138
	v_add_u32_e32 v141, 0x400, v73
	ds_read_u8 v140, v141
	s_mov_b32 s43, s67
	v_mov_b32_e32 v138, s43
	ds_read2st64_b32 v[228:229], v138 offset1:1
	ds_read_b128 v[26:29], v227 offset:2048
	ds_read_b128 v[30:33], v227 offset:2064
	v_mov_b32_e32 v38, 0
	v_mov_b32_e32 v39, 0
	v_mov_b32_e32 v40, 0
	v_mov_b32_e32 v41, 0
	v_mov_b32_e32 v42, 0
	v_mov_b32_e32 v43, 0
	v_mov_b32_e32 v44, 0
	v_mov_b32_e32 v45, 0
	v_and_b32_e32 v78, 0xffff, v23
	v_lshrrev_b32_e32 v79, 16, v23
	v_lshl_add_u32 v78, v78, 7, v150
	v_lshl_add_u32 v79, v79, 7, v151
	s_mov_b32 m0, s77
	s_add_i32 s43, s77, 0x400
	global_load_lds_dwordx4 v78, s[50:51]
	s_mov_b32 m0, s43
	s_nop 0
	global_load_lds_dwordx4 v79, s[50:51]
	s_waitcnt vmcnt(8)
; #define TR4(p_) __builtin_amdgcn_ds_read_tr4_b64_v2i32((LAS v2i*)(p_))
; #define VDMA(st_, k_) do { _Pragma("unroll") for (int i_ = 0; i_ < 4; ++i_) { \
;         const unsigned off_ = (unsigned)((st_) >> 2) * (16384u * 128u) + (PE_ID(E, 4 * ((st_) & 3) + i_) << 7) + ((i_ & 1) ? cx1 : cx0); \
;         __builtin_amdgcn_global_load_lds((const unsigned*)(V4 + off_), (LAS unsigned*)(ldsb + BUF[k_] + 1024 * i_), 16, 0, 0); } } while (0)
; __device__ __forceinline__ void peer_v_tokens(int j, const LAS unsigned short* EL, const LAS unsigned char* AL  , const LAS float* ASC  , const LAS int* SAL  , ...
;     ...
;         for (int st = 0; st < 16; ++st) {
;             const int p = st >> 2, q = st & 3;
;             if (st < 14) VDMA(st + 2, (st + 2) % 3);
;             if (st < 14) asm volatile("s_waitcnt vmcnt(8)" ::: "memory");
;             else if (st == 14) asm volatile("s_waitcnt vmcnt(4)" ::: "memory");
;             else asm volatile("s_waitcnt vmcnt(0)" ::: "memory");
;             if (q == 0) {
; #pragma unroll
;                 for (int r = 0; r < 4; ++r) { accH[r] = 0; accL[r] = 0; } }
; #pragma unroll
;             for (int tp = 0; tp < 2; ++tp) {
;                 const v2i ao = TR4(ATL + (2 * q + tp) * 128 + 8 * s16), ah = TR4(ATL + 1024 + (2 * q + tp) * 128 + 8 * s16);
; #pragma unroll
;                 for (int r = 0; r < 4; ++r) {
;                     const v2i d = TR4(ldsb + BUF[st % 3] + 2048 * tp + roff[r]);
;                     accH[r] = __builtin_amdgcn_sdot8(d.x, ah.x, accH[r], false); accH[r] = __builtin_amdgcn_sdot8(d.y, ah.y, accH[r], false);
;                     accL[r] = __builtin_amdgcn_sdot8(d.x, ao.x, accL[r], false); accL[r] = __builtin_amdgcn_sdot8(d.y, ao.y, accL[r], false);
;                 }
;             }
;             asm volatile("s_waitcnt lgkmcnt(0)" ::: "memory");
	v_add_u32_e32 v54, s79, v59
	v_add_u32_e32 v55, s79, v60
	v_add_u32_e32 v56, s79, v61
	v_add_u32_e32 v57, s79, v62
	ds_read_b64_tr_b4 v[50:51], v160 offset:128
	ds_read_b64_tr_b4 v[52:53], v160 offset:1152
	ds_read_b64_tr_b4 v[130:131], v54
	ds_read_b64_tr_b4 v[132:133], v55
	ds_read_b64_tr_b4 v[134:135], v56
	ds_read_b64_tr_b4 v[136:137], v57
	s_waitcnt lgkmcnt(12)
	v_dot8c_i32_i4_e32 v38, v122, v48
	v_dot8c_i32_i4_e32 v39, v122, v46
	v_dot8c_i32_i4_e32 v40, v124, v48
	v_dot8c_i32_i4_e32 v41, v124, v46
	v_dot8c_i32_i4_e32 v42, v126, v48
	v_dot8c_i32_i4_e32 v43, v126, v46
	v_dot8c_i32_i4_e32 v44, v128, v48
	v_dot8c_i32_i4_e32 v45, v128, v46
	v_dot8c_i32_i4_e32 v38, v123, v49
	v_dot8c_i32_i4_e32 v39, v123, v47
	v_dot8c_i32_i4_e32 v40, v125, v49
	v_dot8c_i32_i4_e32 v41, v125, v47
	v_dot8c_i32_i4_e32 v42, v127, v49
	v_dot8c_i32_i4_e32 v43, v127, v47
	v_dot8c_i32_i4_e32 v44, v129, v49
	v_dot8c_i32_i4_e32 v45, v129, v47
	v_and_b32_e32 v78, 0xffff, v24
	v_lshrrev_b32_e32 v79, 16, v24
	v_lshl_add_u32 v78, v78, 7, v150
	v_lshl_add_u32 v79, v79, 7, v151
	s_mov_b32 m0, s78
	s_add_i32 s43, s78, 0x400
	global_load_lds_dwordx4 v78, s[50:51]
	s_mov_b32 m0, s43
	s_nop 0
	global_load_lds_dwordx4 v79, s[50:51]
	s_waitcnt vmcnt(8)
	v_add_u32_e32 v54, s98, v59
	v_add_u32_e32 v55, s98, v60
	v_add_u32_e32 v56, s98, v61
	v_add_u32_e32 v57, s98, v62
	ds_read_b64_tr_b4 v[46:47], v160 offset:256
	ds_read_b64_tr_b4 v[48:49], v160 offset:1280
	ds_read_b64_tr_b4 v[122:123], v54
	ds_read_b64_tr_b4 v[124:125], v55
	ds_read_b64_tr_b4 v[126:127], v56
	ds_read_b64_tr_b4 v[128:129], v57
	s_waitcnt lgkmcnt(6)
	v_dot8c_i32_i4_e32 v38, v130, v52
	v_dot8c_i32_i4_e32 v39, v130, v50
	v_dot8c_i32_i4_e32 v40, v132, v52
	v_dot8c_i32_i4_e32 v41, v132, v50
	v_dot8c_i32_i4_e32 v42, v134, v52
	v_dot8c_i32_i4_e32 v43, v134, v50
	v_dot8c_i32_i4_e32 v44, v136, v52
	v_dot8c_i32_i4_e32 v45, v136, v50
	v_dot8c_i32_i4_e32 v38, v131, v53
	v_dot8c_i32_i4_e32 v39, v131, v51
	v_dot8c_i32_i4_e32 v40, v133, v53
	v_dot8c_i32_i4_e32 v41, v133, v51
	v_dot8c_i32_i4_e32 v42, v135, v53
	v_dot8c_i32_i4_e32 v43, v135, v51
	v_dot8c_i32_i4_e32 v44, v137, v53
	v_dot8c_i32_i4_e32 v45, v137, v51
	v_and_b32_e32 v78, 0xffff, v25
	v_lshrrev_b32_e32 v79, 16, v25
	v_lshl_add_u32 v78, v78, 7, v150
	v_lshl_add_u32 v79, v79, 7, v151
	s_mov_b32 m0, s79
	s_add_i32 s43, s79, 0x400
	global_load_lds_dwordx4 v78, s[50:51]
	s_mov_b32 m0, s43
	s_nop 0
	global_load_lds_dwordx4 v79, s[50:51]
	s_waitcnt vmcnt(8)
	v_add_u32_e32 v54, s99, v59
	v_add_u32_e32 v55, s99, v60
	v_add_u32_e32 v56, s99, v61
	v_add_u32_e32 v57, s99, v62
	ds_read_b64_tr_b4 v[50:51], v160 offset:384
	ds_read_b64_tr_b4 v[52:53], v160 offset:1408
	ds_read_b64_tr_b4 v[130:131], v54
	ds_read_b64_tr_b4 v[132:133], v55
	ds_read_b64_tr_b4 v[134:135], v56
	ds_read_b64_tr_b4 v[136:137], v57
	s_waitcnt lgkmcnt(6)
	v_dot8c_i32_i4_e32 v38, v122, v48
	v_dot8c_i32_i4_e32 v39, v122, v46
	v_dot8c_i32_i4_e32 v40, v124, v48
	v_dot8c_i32_i4_e32 v41, v124, v46
	v_dot8c_i32_i4_e32 v42, v126, v48
	v_dot8c_i32_i4_e32 v43, v126, v46
	v_dot8c_i32_i4_e32 v44, v128, v48
	v_dot8c_i32_i4_e32 v45, v128, v46
	v_dot8c_i32_i4_e32 v38, v123, v49
	v_dot8c_i32_i4_e32 v39, v123, v47
	v_dot8c_i32_i4_e32 v40, v125, v49
	v_dot8c_i32_i4_e32 v41, v125, v47
	v_dot8c_i32_i4_e32 v42, v127, v49
	v_dot8c_i32_i4_e32 v43, v127, v47
	v_dot8c_i32_i4_e32 v44, v129, v49
	v_dot8c_i32_i4_e32 v45, v129, v47
	s_waitcnt lgkmcnt(15)
	v_and_b32_e32 v78, 0xffff, v26
	v_lshrrev_b32_e32 v79, 16, v26
	v_lshl_add_u32 v78, v78, 7, v150
	v_lshl_add_u32 v79, v79, 7, v151
	s_mov_b32 m0, s98
	s_add_i32 s43, s98, 0x400
	global_load_lds_dwordx4 v78, s[50:51]
	s_mov_b32 m0, s43
	s_nop 0
	global_load_lds_dwordx4 v79, s[50:51]
	s_waitcnt vmcnt(8)
	v_add_u32_e32 v54, s76, v59
	v_add_u32_e32 v55, s76, v60
	v_add_u32_e32 v56, s76, v61
	v_add_u32_e32 v57, s76, v62
	ds_read_b64_tr_b4 v[46:47], v160 offset:512
	ds_read_b64_tr_b4 v[48:49], v160 offset:1536
	ds_read_b64_tr_b4 v[122:123], v54
	ds_read_b64_tr_b4 v[124:125], v55
	ds_read_b64_tr_b4 v[126:127], v56
	ds_read_b64_tr_b4 v[128:129], v57
	s_waitcnt lgkmcnt(6)
	v_dot8c_i32_i4_e32 v38, v130, v52
	v_dot8c_i32_i4_e32 v39, v130, v50
	v_dot8c_i32_i4_e32 v40, v132, v52
	v_dot8c_i32_i4_e32 v41, v132, v50
	v_dot8c_i32_i4_e32 v42, v134, v52
	v_dot8c_i32_i4_e32 v43, v134, v50
	v_dot8c_i32_i4_e32 v44, v136, v52
	v_dot8c_i32_i4_e32 v45, v136, v50
	v_dot8c_i32_i4_e32 v38, v131, v53
	v_dot8c_i32_i4_e32 v39, v131, v51
	v_dot8c_i32_i4_e32 v40, v133, v53
	v_dot8c_i32_i4_e32 v41, v133, v51
	v_dot8c_i32_i4_e32 v42, v135, v53
	v_dot8c_i32_i4_e32 v43, v135, v51
	v_dot8c_i32_i4_e32 v44, v137, v53
	v_dot8c_i32_i4_e32 v45, v137, v51
	v_and_b32_e32 v78, 0xffff, v27
	v_lshrrev_b32_e32 v79, 16, v27
	v_lshl_add_u32 v78, v78, 7, v150
	v_lshl_add_u32 v79, v79, 7, v151
	s_mov_b32 m0, s99
	s_add_i32 s43, s99, 0x400
	global_load_lds_dwordx4 v78, s[50:51]
	s_mov_b32 m0, s43
	s_nop 0
	global_load_lds_dwordx4 v79, s[50:51]
	s_waitcnt vmcnt(8)
	v_add_u32_e32 v54, s77, v59
	v_add_u32_e32 v55, s77, v60
	v_add_u32_e32 v56, s77, v61
	v_add_u32_e32 v57, s77, v62
	ds_read_b64_tr_b4 v[50:51], v160 offset:640
	ds_read_b64_tr_b4 v[52:53], v160 offset:1664
	ds_read_b64_tr_b4 v[130:131], v54
	ds_read_b64_tr_b4 v[132:133], v55
	ds_read_b64_tr_b4 v[134:135], v56
	ds_read_b64_tr_b4 v[136:137], v57
	s_waitcnt lgkmcnt(6)
	v_dot8c_i32_i4_e32 v38, v122, v48
	v_dot8c_i32_i4_e32 v39, v122, v46
	v_dot8c_i32_i4_e32 v40, v124, v48
	v_dot8c_i32_i4_e32 v41, v124, v46
	v_dot8c_i32_i4_e32 v42, v126, v48
	v_dot8c_i32_i4_e32 v43, v126, v46
	v_dot8c_i32_i4_e32 v44, v128, v48
	v_dot8c_i32_i4_e32 v45, v128, v46
	v_dot8c_i32_i4_e32 v38, v123, v49
	v_dot8c_i32_i4_e32 v39, v123, v47
	v_dot8c_i32_i4_e32 v40, v125, v49
	v_dot8c_i32_i4_e32 v41, v125, v47
	v_dot8c_i32_i4_e32 v42, v127, v49
	v_dot8c_i32_i4_e32 v43, v127, v47
	v_dot8c_i32_i4_e32 v44, v129, v49
	v_dot8c_i32_i4_e32 v45, v129, v47
	s_waitcnt lgkmcnt(15)
; __device__ __forceinline__ void peer_v_tokens(int j, const LAS unsigned short* EL, const LAS unsigned char* AL  , const LAS float* ASC  , const LAS int* SAL  , ...
;     ...
;         for (int m = 0; m < 2; ++m) {
;             const int idx = lane + 64 * m, tau = idx >> 4, sr = idx & 15, k = 16 * (sr & 7) + 2 * tau + (sr >> 3);
;             const int aq = (int)*(const LAS signed char*)(AL + tl * 128 + k); const int tq = aq + 8;
;             const unsigned lo = (((unsigned)tq & 15u) ^ 8u) * 0x11111111u, hi = ((unsigned)(tq >> 4) & 15u) * 0x11111111u;
;             typedef unsigned u2v __attribute__((ext_vector_type(2)));
;             u2v l2; l2.x = lo; l2.y = lo; u2v h2; h2.x = hi; h2.y = hi;
;             *(LAS u2v*)(ATL + 8 * idx) = l2; *(LAS u2v*)(ATL + 1024 + 8 * idx) = h2;
;         }
;         const float asc = ASC[tl]; const int sa = SAL[tl];
;         CFENCE();
;         int accH[4], accL[4];
; #pragma unroll
;         for (int st = 0; st < 16; ++st) {
;             const int p = st >> 2, q = st & 3;
;             if (st < 14) VDMA(st + 2, (st + 2) % 3);
;             if (st < 14) asm volatile("s_waitcnt vmcnt(8)" ::: "memory");
;             else if (st == 14) asm volatile("s_waitcnt vmcnt(4)" ::: "memory");
;             else asm volatile("s_waitcnt vmcnt(0)" ::: "memory");
;             if (q == 0) {
; #pragma unroll
;                 for (int r = 0; r < 4; ++r) { accH[r] = 0; accL[r] = 0; } }
; #pragma unroll
;             for (int tp = 0; tp < 2; ++tp) {
;                 const v2i ao = TR4(ATL + (2 * q + tp) * 128 + 8 * s16), ah = TR4(ATL + 1024 + (2 * q + tp) * 128 + 8 * s16);
; #pragma unroll
;                 for (int r = 0; r < 4; ++r) {
;                     const v2i d = TR4(ldsb + BUF[st % 3] + 2048 * tp + roff[r]);
;                     accH[r] = __builtin_amdgcn_sdot8(d.x, ah.x, accH[r], false); accH[r] = __builtin_amdgcn_sdot8(d.y, ah.y, accH[r], false);
;                     accL[r] = __builtin_amdgcn_sdot8(d.x, ao.x, accL[r], false); accL[r] = __builtin_amdgcn_sdot8(d.y, ao.y, accL[r], false);
;                 }
;             }
;             asm volatile("s_waitcnt lgkmcnt(0)" ::: "memory");
;             if (q == 3) {
; #pragma unroll
;                 for (int r = 0; r < 4; ++r) STASH[256 * p + 16 * (grp + 4 * r) + pc] = f2bf(asc * (float)(2 * ((accH[r] << 4) + accL[r]) + sa));
;             }
;         }
	v_add_u32_e32 v143, 8, v139
	v_and_b32_e32 v142, 15, v143
	v_xor_b32_e32 v142, 8, v142
	v_bfe_u32 v144, v143, 4, 4
	v_mul_lo_u32 v142, v142, s92
	v_mul_lo_u32 v144, v144, s92
	v_mov_b32_e32 v143, v142
	v_mov_b32_e32 v145, v144
	ds_write2st64_b64 v159, v[142:143], v[144:145] offset1:2
	v_and_b32_e32 v78, 0xffff, v28
	v_lshrrev_b32_e32 v79, 16, v28
	v_lshl_add_u32 v78, v78, 7, v150
	v_lshl_add_u32 v79, v79, 7, v151
	s_mov_b32 m0, s76
	s_add_i32 s43, s76, 0x400
	global_load_lds_dwordx4 v78, s[50:51]
	s_mov_b32 m0, s43
	s_nop 0
	global_load_lds_dwordx4 v79, s[50:51]
	s_waitcnt vmcnt(8)
	v_add_u32_e32 v54, s78, v59
	v_add_u32_e32 v55, s78, v60
	v_add_u32_e32 v56, s78, v61
	v_add_u32_e32 v57, s78, v62
	ds_read_b64_tr_b4 v[46:47], v160 offset:768
	ds_read_b64_tr_b4 v[48:49], v160 offset:1792
	ds_read_b64_tr_b4 v[122:123], v54
	ds_read_b64_tr_b4 v[124:125], v55
	ds_read_b64_tr_b4 v[126:127], v56
	ds_read_b64_tr_b4 v[128:129], v57
	s_waitcnt lgkmcnt(7)
	v_dot8c_i32_i4_e32 v38, v130, v52
	v_dot8c_i32_i4_e32 v39, v130, v50
	v_dot8c_i32_i4_e32 v40, v132, v52
	v_dot8c_i32_i4_e32 v41, v132, v50
	v_dot8c_i32_i4_e32 v42, v134, v52
	v_dot8c_i32_i4_e32 v43, v134, v50
	v_dot8c_i32_i4_e32 v44, v136, v52
	v_dot8c_i32_i4_e32 v45, v136, v50
	v_dot8c_i32_i4_e32 v38, v131, v53
	v_dot8c_i32_i4_e32 v39, v131, v51
	v_dot8c_i32_i4_e32 v40, v133, v53
	v_dot8c_i32_i4_e32 v41, v133, v51
	v_dot8c_i32_i4_e32 v42, v135, v53
	v_dot8c_i32_i4_e32 v43, v135, v51
	v_dot8c_i32_i4_e32 v44, v137, v53
	v_dot8c_i32_i4_e32 v45, v137, v51
	v_and_b32_e32 v78, 0xffff, v29
	v_lshrrev_b32_e32 v79, 16, v29
	v_lshl_add_u32 v78, v78, 7, v150
	v_lshl_add_u32 v79, v79, 7, v151
	s_mov_b32 m0, s77
	s_add_i32 s43, s77, 0x400
	global_load_lds_dwordx4 v78, s[50:51]
	s_mov_b32 m0, s43
	s_nop 0
	global_load_lds_dwordx4 v79, s[50:51]
	s_waitcnt vmcnt(8)
	v_add_u32_e32 v54, s79, v59
	v_add_u32_e32 v55, s79, v60
	v_add_u32_e32 v56, s79, v61
	v_add_u32_e32 v57, s79, v62
	ds_read_b64_tr_b4 v[50:51], v160 offset:896
	ds_read_b64_tr_b4 v[52:53], v160 offset:1920
	ds_read_b64_tr_b4 v[130:131], v54
	ds_read_b64_tr_b4 v[132:133], v55
	ds_read_b64_tr_b4 v[134:135], v56
	ds_read_b64_tr_b4 v[136:137], v57
	s_waitcnt lgkmcnt(6)
	v_dot8c_i32_i4_e32 v38, v122, v48
	v_dot8c_i32_i4_e32 v39, v122, v46
	v_dot8c_i32_i4_e32 v40, v124, v48
	v_dot8c_i32_i4_e32 v41, v124, v46
	v_dot8c_i32_i4_e32 v42, v126, v48
	v_dot8c_i32_i4_e32 v43, v126, v46
	v_dot8c_i32_i4_e32 v44, v128, v48
	v_dot8c_i32_i4_e32 v45, v128, v46
	v_dot8c_i32_i4_e32 v38, v123, v49
	v_dot8c_i32_i4_e32 v39, v123, v47
	v_dot8c_i32_i4_e32 v40, v125, v49
	v_dot8c_i32_i4_e32 v41, v125, v47
	v_dot8c_i32_i4_e32 v42, v127, v49
	v_dot8c_i32_i4_e32 v43, v127, v47
	v_dot8c_i32_i4_e32 v44, v129, v49
	v_dot8c_i32_i4_e32 v45, v129, v47
	v_and_b32_e32 v78, 0xffff, v30
	v_lshrrev_b32_e32 v79, 16, v30
	v_lshl_add_u32 v78, v78, 7, v150
	v_lshl_add_u32 v79, v79, 7, v151
	s_mov_b32 m0, s78
	s_add_i32 s43, s78, 0x400
	global_load_lds_dwordx4 v78, s[50:51]
	s_mov_b32 m0, s43
	s_nop 0
	global_load_lds_dwordx4 v79, s[50:51]
	s_waitcnt vmcnt(8)
	v_add_u32_e32 v54, s98, v59
	v_add_u32_e32 v55, s98, v60
	v_add_u32_e32 v56, s98, v61
	v_add_u32_e32 v57, s98, v62
	ds_read_b64_tr_b4 v[46:47], v160
	ds_read_b64_tr_b4 v[48:49], v160 offset:1024
	ds_read_b64_tr_b4 v[122:123], v54
	ds_read_b64_tr_b4 v[124:125], v55
	ds_read_b64_tr_b4 v[126:127], v56
	ds_read_b64_tr_b4 v[128:129], v57
	s_waitcnt lgkmcnt(6)
	v_dot8c_i32_i4_e32 v38, v130, v52
	v_dot8c_i32_i4_e32 v39, v130, v50
	v_dot8c_i32_i4_e32 v40, v132, v52
	v_dot8c_i32_i4_e32 v41, v132, v50
	v_dot8c_i32_i4_e32 v42, v134, v52
	v_dot8c_i32_i4_e32 v43, v134, v50
	v_dot8c_i32_i4_e32 v44, v136, v52
	v_dot8c_i32_i4_e32 v45, v136, v50
	v_dot8c_i32_i4_e32 v38, v131, v53
	v_dot8c_i32_i4_e32 v39, v131, v51
	v_dot8c_i32_i4_e32 v40, v133, v53
	v_dot8c_i32_i4_e32 v41, v133, v51
	v_dot8c_i32_i4_e32 v42, v135, v53
	v_dot8c_i32_i4_e32 v43, v135, v51
	v_dot8c_i32_i4_e32 v44, v137, v53
	v_dot8c_i32_i4_e32 v45, v137, v51
	s_nop 3
	s_waitcnt lgkmcnt(15)
	v_lshlrev_b32_e32 v38, 5, v38
	v_lshlrev_b32_e32 v39, 1, v39
	v_add3_u32 v38, v39, v229, v38
	v_cvt_f32_i32_e32 v38, v38
	v_mul_f32_e32 v38, v228, v38
	v_lshlrev_b32_e32 v40, 5, v40
	v_lshlrev_b32_e32 v41, 1, v41
	v_add3_u32 v40, v41, v229, v40
	v_cvt_f32_i32_e32 v40, v40
	v_mul_f32_e32 v40, v228, v40
	v_lshlrev_b32_e32 v42, 5, v42
	v_lshlrev_b32_e32 v43, 1, v43
	v_add3_u32 v42, v43, v229, v42
	v_cvt_f32_i32_e32 v42, v42
	v_mul_f32_e32 v42, v228, v42
	v_lshlrev_b32_e32 v44, 5, v44
	v_lshlrev_b32_e32 v45, 1, v45
	v_add3_u32 v44, v45, v229, v44
	v_cvt_f32_i32_e32 v44, v44
	v_mul_f32_e32 v44, v228, v44
	v_cvt_pk_bf16_f32 v166, v38, v40
	v_cvt_pk_bf16_f32 v167, v42, v44
	v_add_u32_e32 v147, 8, v140
	v_and_b32_e32 v146, 15, v147
	v_xor_b32_e32 v146, 8, v146
	v_bfe_u32 v148, v147, 4, 4
	v_mul_lo_u32 v146, v146, s92
	v_mul_lo_u32 v148, v148, s92
	v_mov_b32_e32 v147, v146
	v_mov_b32_e32 v149, v148
	ds_write2st64_b64 v77, v[146:147], v[148:149] offset1:2
	v_mov_b32_e32 v138, v74
	ds_read_u8 v139, v138
	v_mov_b32_e32 v141, v73
	ds_read_u8 v140, v141
	s_add_i32 s43, s67, 32
	v_mov_b32_e32 v138, s43
	ds_read2st64_b32 v[228:229], v138 offset1:1
	ds_read_b128 v[18:21], v227
	ds_read_b128 v[22:25], v227 offset:16
	v_add_u32_e32 v152, 0x600000, v63
	v_add_u32_e32 v153, 0x600000, v64
	v_mov_b32_e32 v38, 0
	v_mov_b32_e32 v39, 0
	v_mov_b32_e32 v40, 0
	v_mov_b32_e32 v41, 0
	v_mov_b32_e32 v42, 0
	v_mov_b32_e32 v43, 0
	v_mov_b32_e32 v44, 0
	v_mov_b32_e32 v45, 0
	v_and_b32_e32 v78, 0xffff, v31
	v_lshrrev_b32_e32 v79, 16, v31
	v_lshl_add_u32 v78, v78, 7, v150
	v_lshl_add_u32 v79, v79, 7, v151
	s_mov_b32 m0, s79
	s_add_i32 s43, s79, 0x400
	global_load_lds_dwordx4 v78, s[50:51]
	s_mov_b32 m0, s43
	s_nop 0
	global_load_lds_dwordx4 v79, s[50:51]
	s_waitcnt vmcnt(8)
; #define TR4(p_) __builtin_amdgcn_ds_read_tr4_b64_v2i32((LAS v2i*)(p_))
; #define VDMA(st_, k_) do { _Pragma("unroll") for (int i_ = 0; i_ < 4; ++i_) { \
;         const unsigned off_ = (unsigned)((st_) >> 2) * (16384u * 128u) + (PE_ID(E, 4 * ((st_) & 3) + i_) << 7) + ((i_ & 1) ? cx1 : cx0); \
;         __builtin_amdgcn_global_load_lds((const unsigned*)(V4 + off_), (LAS unsigned*)(ldsb + BUF[k_] + 1024 * i_), 16, 0, 0); } } while (0)
; __device__ __forceinline__ void peer_v_tokens(int j, const LAS unsigned short* EL, const LAS unsigned char* AL  , const LAS float* ASC  , const LAS int* SAL  , ...
;     ...
;         for (int st = 0; st < 16; ++st) {
;             const int p = st >> 2, q = st & 3;
;             if (st < 14) VDMA(st + 2, (st + 2) % 3);
;             if (st < 14) asm volatile("s_waitcnt vmcnt(8)" ::: "memory");
;             else if (st == 14) asm volatile("s_waitcnt vmcnt(4)" ::: "memory");
;             else asm volatile("s_waitcnt vmcnt(0)" ::: "memory");
;             if (q == 0) {
; #pragma unroll
;                 for (int r = 0; r < 4; ++r) { accH[r] = 0; accL[r] = 0; } }
; #pragma unroll
;             for (int tp = 0; tp < 2; ++tp) {
;                 const v2i ao = TR4(ATL + (2 * q + tp) * 128 + 8 * s16), ah = TR4(ATL + 1024 + (2 * q + tp) * 128 + 8 * s16);
; #pragma unroll
;                 for (int r = 0; r < 4; ++r) {
;                     const v2i d = TR4(ldsb + BUF[st % 3] + 2048 * tp + roff[r]);
;                     accH[r] = __builtin_amdgcn_sdot8(d.x, ah.x, accH[r], false); accH[r] = __builtin_amdgcn_sdot8(d.y, ah.y, accH[r], false);
;                     accL[r] = __builtin_amdgcn_sdot8(d.x, ao.x, accL[r], false); accL[r] = __builtin_amdgcn_sdot8(d.y, ao.y, accL[r], false);
;                 }
;             }
;             asm volatile("s_waitcnt lgkmcnt(0)" ::: "memory");
	v_add_u32_e32 v54, s99, v59
	v_add_u32_e32 v55, s99, v60
	v_add_u32_e32 v56, s99, v61
	v_add_u32_e32 v57, s99, v62
	ds_read_b64_tr_b4 v[50:51], v160 offset:128
	ds_read_b64_tr_b4 v[52:53], v160 offset:1152
	ds_read_b64_tr_b4 v[130:131], v54
	ds_read_b64_tr_b4 v[132:133], v55
	ds_read_b64_tr_b4 v[134:135], v56
	ds_read_b64_tr_b4 v[136:137], v57
	s_waitcnt lgkmcnt(12)
	v_dot8c_i32_i4_e32 v38, v122, v48
	v_dot8c_i32_i4_e32 v39, v122, v46
	v_dot8c_i32_i4_e32 v40, v124, v48
	v_dot8c_i32_i4_e32 v41, v124, v46
	v_dot8c_i32_i4_e32 v42, v126, v48
	v_dot8c_i32_i4_e32 v43, v126, v46
	v_dot8c_i32_i4_e32 v44, v128, v48
	v_dot8c_i32_i4_e32 v45, v128, v46
	v_dot8c_i32_i4_e32 v38, v123, v49
	v_dot8c_i32_i4_e32 v39, v123, v47
	v_dot8c_i32_i4_e32 v40, v125, v49
	v_dot8c_i32_i4_e32 v41, v125, v47
	v_dot8c_i32_i4_e32 v42, v127, v49
	v_dot8c_i32_i4_e32 v43, v127, v47
	v_dot8c_i32_i4_e32 v44, v129, v49
	v_dot8c_i32_i4_e32 v45, v129, v47
	v_and_b32_e32 v78, 0xffff, v32
	v_lshrrev_b32_e32 v79, 16, v32
	v_lshl_add_u32 v78, v78, 7, v150
	v_lshl_add_u32 v79, v79, 7, v151
	s_mov_b32 m0, s98
	s_add_i32 s43, s98, 0x400
	global_load_lds_dwordx4 v78, s[50:51]
	s_mov_b32 m0, s43
	s_nop 0
	global_load_lds_dwordx4 v79, s[50:51]
	s_waitcnt vmcnt(8)
	v_add_u32_e32 v54, s76, v59
	v_add_u32_e32 v55, s76, v60
	v_add_u32_e32 v56, s76, v61
	v_add_u32_e32 v57, s76, v62
	ds_read_b64_tr_b4 v[46:47], v160 offset:256
	ds_read_b64_tr_b4 v[48:49], v160 offset:1280
	ds_read_b64_tr_b4 v[122:123], v54
	ds_read_b64_tr_b4 v[124:125], v55
	ds_read_b64_tr_b4 v[126:127], v56
	ds_read_b64_tr_b4 v[128:129], v57
	s_waitcnt lgkmcnt(6)
	v_dot8c_i32_i4_e32 v38, v130, v52
	v_dot8c_i32_i4_e32 v39, v130, v50
	v_dot8c_i32_i4_e32 v40, v132, v52
	v_dot8c_i32_i4_e32 v41, v132, v50
	v_dot8c_i32_i4_e32 v42, v134, v52
	v_dot8c_i32_i4_e32 v43, v134, v50
	v_dot8c_i32_i4_e32 v44, v136, v52
	v_dot8c_i32_i4_e32 v45, v136, v50
	v_dot8c_i32_i4_e32 v38, v131, v53
	v_dot8c_i32_i4_e32 v39, v131, v51
	v_dot8c_i32_i4_e32 v40, v133, v53
	v_dot8c_i32_i4_e32 v41, v133, v51
	v_dot8c_i32_i4_e32 v42, v135, v53
	v_dot8c_i32_i4_e32 v43, v135, v51
	v_dot8c_i32_i4_e32 v44, v137, v53
	v_dot8c_i32_i4_e32 v45, v137, v51
	v_and_b32_e32 v78, 0xffff, v33
	v_lshrrev_b32_e32 v79, 16, v33
	v_lshl_add_u32 v78, v78, 7, v150
	v_lshl_add_u32 v79, v79, 7, v151
	s_mov_b32 m0, s99
	s_add_i32 s43, s99, 0x400
	global_load_lds_dwordx4 v78, s[50:51]
	s_mov_b32 m0, s43
	s_nop 0
	global_load_lds_dwordx4 v79, s[50:51]
	s_waitcnt vmcnt(8)
	v_add_u32_e32 v54, s77, v59
	v_add_u32_e32 v55, s77, v60
	v_add_u32_e32 v56, s77, v61
	v_add_u32_e32 v57, s77, v62
	ds_read_b64_tr_b4 v[50:51], v160 offset:384
	ds_read_b64_tr_b4 v[52:53], v160 offset:1408
	ds_read_b64_tr_b4 v[130:131], v54
	ds_read_b64_tr_b4 v[132:133], v55
	ds_read_b64_tr_b4 v[134:135], v56
	ds_read_b64_tr_b4 v[136:137], v57
	s_waitcnt lgkmcnt(6)
	v_dot8c_i32_i4_e32 v38, v122, v48
	v_dot8c_i32_i4_e32 v39, v122, v46
	v_dot8c_i32_i4_e32 v40, v124, v48
	v_dot8c_i32_i4_e32 v41, v124, v46
	v_dot8c_i32_i4_e32 v42, v126, v48
	v_dot8c_i32_i4_e32 v43, v126, v46
	v_dot8c_i32_i4_e32 v44, v128, v48
	v_dot8c_i32_i4_e32 v45, v128, v46
	v_dot8c_i32_i4_e32 v38, v123, v49
	v_dot8c_i32_i4_e32 v39, v123, v47
	v_dot8c_i32_i4_e32 v40, v125, v49
	v_dot8c_i32_i4_e32 v41, v125, v47
	v_dot8c_i32_i4_e32 v42, v127, v49
	v_dot8c_i32_i4_e32 v43, v127, v47
	v_dot8c_i32_i4_e32 v44, v129, v49
	v_dot8c_i32_i4_e32 v45, v129, v47
	s_waitcnt lgkmcnt(15)
	v_and_b32_e32 v78, 0xffff, v18
	v_lshrrev_b32_e32 v79, 16, v18
	v_lshl_add_u32 v78, v78, 7, v152
	v_lshl_add_u32 v79, v79, 7, v153
	s_mov_b32 m0, s76
	s_add_i32 s43, s76, 0x400
	global_load_lds_dwordx4 v78, s[50:51]
	s_mov_b32 m0, s43
	s_nop 0
	global_load_lds_dwordx4 v79, s[50:51]
	s_waitcnt vmcnt(8)
	v_add_u32_e32 v54, s78, v59
	v_add_u32_e32 v55, s78, v60
	v_add_u32_e32 v56, s78, v61
	v_add_u32_e32 v57, s78, v62
	ds_read_b64_tr_b4 v[46:47], v160 offset:512
	ds_read_b64_tr_b4 v[48:49], v160 offset:1536
	ds_read_b64_tr_b4 v[122:123], v54
	ds_read_b64_tr_b4 v[124:125], v55
	ds_read_b64_tr_b4 v[126:127], v56
	ds_read_b64_tr_b4 v[128:129], v57
	s_waitcnt lgkmcnt(6)
	v_dot8c_i32_i4_e32 v38, v130, v52
	v_dot8c_i32_i4_e32 v39, v130, v50
	v_dot8c_i32_i4_e32 v40, v132, v52
	v_dot8c_i32_i4_e32 v41, v132, v50
	v_dot8c_i32_i4_e32 v42, v134, v52
	v_dot8c_i32_i4_e32 v43, v134, v50
	v_dot8c_i32_i4_e32 v44, v136, v52
	v_dot8c_i32_i4_e32 v45, v136, v50
	v_dot8c_i32_i4_e32 v38, v131, v53
	v_dot8c_i32_i4_e32 v39, v131, v51
	v_dot8c_i32_i4_e32 v40, v133, v53
	v_dot8c_i32_i4_e32 v41, v133, v51
	v_dot8c_i32_i4_e32 v42, v135, v53
	v_dot8c_i32_i4_e32 v43, v135, v51
	v_dot8c_i32_i4_e32 v44, v137, v53
	v_dot8c_i32_i4_e32 v45, v137, v51
	v_and_b32_e32 v78, 0xffff, v19
	v_lshrrev_b32_e32 v79, 16, v19
	v_lshl_add_u32 v78, v78, 7, v152
	v_lshl_add_u32 v79, v79, 7, v153
	s_mov_b32 m0, s77
	s_add_i32 s43, s77, 0x400
	global_load_lds_dwordx4 v78, s[50:51]
	s_mov_b32 m0, s43
	s_nop 0
	global_load_lds_dwordx4 v79, s[50:51]
	s_waitcnt vmcnt(8)
	v_add_u32_e32 v54, s79, v59
	v_add_u32_e32 v55, s79, v60
	v_add_u32_e32 v56, s79, v61
	v_add_u32_e32 v57, s79, v62
	ds_read_b64_tr_b4 v[50:51], v160 offset:640
	ds_read_b64_tr_b4 v[52:53], v160 offset:1664
	ds_read_b64_tr_b4 v[130:131], v54
	ds_read_b64_tr_b4 v[132:133], v55
	ds_read_b64_tr_b4 v[134:135], v56
	ds_read_b64_tr_b4 v[136:137], v57
	s_waitcnt lgkmcnt(6)
	v_dot8c_i32_i4_e32 v38, v122, v48
	v_dot8c_i32_i4_e32 v39, v122, v46
	v_dot8c_i32_i4_e32 v40, v124, v48
	v_dot8c_i32_i4_e32 v41, v124, v46
	v_dot8c_i32_i4_e32 v42, v126, v48
	v_dot8c_i32_i4_e32 v43, v126, v46
	v_dot8c_i32_i4_e32 v44, v128, v48
	v_dot8c_i32_i4_e32 v45, v128, v46
	v_dot8c_i32_i4_e32 v38, v123, v49
	v_dot8c_i32_i4_e32 v39, v123, v47
	v_dot8c_i32_i4_e32 v40, v125, v49
	v_dot8c_i32_i4_e32 v41, v125, v47
	v_dot8c_i32_i4_e32 v42, v127, v49
	v_dot8c_i32_i4_e32 v43, v127, v47
	v_dot8c_i32_i4_e32 v44, v129, v49
	v_dot8c_i32_i4_e32 v45, v129, v47
	s_waitcnt lgkmcnt(15)
; __device__ __forceinline__ void peer_v_tokens(int j, const LAS unsigned short* EL, const LAS unsigned char* AL  , const LAS float* ASC  , const LAS int* SAL  , ...
;     ...
;         for (int m = 0; m < 2; ++m) {
;             const int idx = lane + 64 * m, tau = idx >> 4, sr = idx & 15, k = 16 * (sr & 7) + 2 * tau + (sr >> 3);
;             const int aq = (int)*(const LAS signed char*)(AL + tl * 128 + k); const int tq = aq + 8;
;             const unsigned lo = (((unsigned)tq & 15u) ^ 8u) * 0x11111111u, hi = ((unsigned)(tq >> 4) & 15u) * 0x11111111u;
;             typedef unsigned u2v __attribute__((ext_vector_type(2)));
;             u2v l2; l2.x = lo; l2.y = lo; u2v h2; h2.x = hi; h2.y = hi;
;             *(LAS u2v*)(ATL + 8 * idx) = l2; *(LAS u2v*)(ATL + 1024 + 8 * idx) = h2;
;         }
;         const float asc = ASC[tl]; const int sa = SAL[tl];
;         CFENCE();
;         int accH[4], accL[4];
; #pragma unroll
;         for (int st = 0; st < 16; ++st) {
;             const int p = st >> 2, q = st & 3;
;             if (st < 14) VDMA(st + 2, (st + 2) % 3);
;             if (st < 14) asm volatile("s_waitcnt vmcnt(8)" ::: "memory");
;             else if (st == 14) asm volatile("s_waitcnt vmcnt(4)" ::: "memory");
;             else asm volatile("s_waitcnt vmcnt(0)" ::: "memory");
;             if (q == 0) {
; #pragma unroll
;                 for (int r = 0; r < 4; ++r) { accH[r] = 0; accL[r] = 0; } }
; #pragma unroll
;             for (int tp = 0; tp < 2; ++tp) {
;                 const v2i ao = TR4(ATL + (2 * q + tp) * 128 + 8 * s16), ah = TR4(ATL + 1024 + (2 * q + tp) * 128 + 8 * s16);
; #pragma unroll
;                 for (int r = 0; r < 4; ++r) {
;                     const v2i d = TR4(ldsb + BUF[st % 3] + 2048 * tp + roff[r]);
;                     accH[r] = __builtin_amdgcn_sdot8(d.x, ah.x, accH[r], false); accH[r] = __builtin_amdgcn_sdot8(d.y, ah.y, accH[r], false);
;                     accL[r] = __builtin_amdgcn_sdot8(d.x, ao.x, accL[r], false); accL[r] = __builtin_amdgcn_sdot8(d.y, ao.y, accL[r], false);
;                 }
;             }
;             asm volatile("s_waitcnt lgkmcnt(0)" ::: "memory");
;             if (q == 3) {
; #pragma unroll
;                 for (int r = 0; r < 4; ++r) STASH[256 * p + 16 * (grp + 4 * r) + pc] = f2bf(asc * (float)(2 * ((accH[r] << 4) + accL[r]) + sa));
;             }
;         }
	v_add_u32_e32 v143, 8, v139
	v_and_b32_e32 v142, 15, v143
	v_xor_b32_e32 v142, 8, v142
	v_bfe_u32 v144, v143, 4, 4
	v_mul_lo_u32 v142, v142, s92
	v_mul_lo_u32 v144, v144, s92
	v_mov_b32_e32 v143, v142
	v_mov_b32_e32 v145, v144
	ds_write2st64_b64 v159, v[142:143], v[144:145] offset1:2
	v_and_b32_e32 v78, 0xffff, v20
	v_lshrrev_b32_e32 v79, 16, v20
	v_lshl_add_u32 v78, v78, 7, v152
	v_lshl_add_u32 v79, v79, 7, v153
	s_mov_b32 m0, s78
	s_add_i32 s43, s78, 0x400
	global_load_lds_dwordx4 v78, s[50:51]
	s_mov_b32 m0, s43
	s_nop 0
	global_load_lds_dwordx4 v79, s[50:51]
	s_waitcnt vmcnt(8)
	v_add_u32_e32 v54, s98, v59
	v_add_u32_e32 v55, s98, v60
	v_add_u32_e32 v56, s98, v61
	v_add_u32_e32 v57, s98, v62
	ds_read_b64_tr_b4 v[46:47], v160 offset:768
	ds_read_b64_tr_b4 v[48:49], v160 offset:1792
	ds_read_b64_tr_b4 v[122:123], v54
	ds_read_b64_tr_b4 v[124:125], v55
	ds_read_b64_tr_b4 v[126:127], v56
	ds_read_b64_tr_b4 v[128:129], v57
	s_waitcnt lgkmcnt(7)
	v_dot8c_i32_i4_e32 v38, v130, v52
	v_dot8c_i32_i4_e32 v39, v130, v50
	v_dot8c_i32_i4_e32 v40, v132, v52
	v_dot8c_i32_i4_e32 v41, v132, v50
	v_dot8c_i32_i4_e32 v42, v134, v52
	v_dot8c_i32_i4_e32 v43, v134, v50
	v_dot8c_i32_i4_e32 v44, v136, v52
	v_dot8c_i32_i4_e32 v45, v136, v50
	v_dot8c_i32_i4_e32 v38, v131, v53
	v_dot8c_i32_i4_e32 v39, v131, v51
	v_dot8c_i32_i4_e32 v40, v133, v53
	v_dot8c_i32_i4_e32 v41, v133, v51
	v_dot8c_i32_i4_e32 v42, v135, v53
	v_dot8c_i32_i4_e32 v43, v135, v51
	v_dot8c_i32_i4_e32 v44, v137, v53
	v_dot8c_i32_i4_e32 v45, v137, v51
	v_and_b32_e32 v78, 0xffff, v21
	v_lshrrev_b32_e32 v79, 16, v21
	v_lshl_add_u32 v78, v78, 7, v152
	v_lshl_add_u32 v79, v79, 7, v153
	s_mov_b32 m0, s79
	s_add_i32 s43, s79, 0x400
	global_load_lds_dwordx4 v78, s[50:51]
	s_mov_b32 m0, s43
	s_nop 0
	global_load_lds_dwordx4 v79, s[50:51]
	s_waitcnt vmcnt(8)
	v_add_u32_e32 v54, s99, v59
	v_add_u32_e32 v55, s99, v60
	v_add_u32_e32 v56, s99, v61
	v_add_u32_e32 v57, s99, v62
	ds_read_b64_tr_b4 v[50:51], v160 offset:896
	ds_read_b64_tr_b4 v[52:53], v160 offset:1920
	ds_read_b64_tr_b4 v[130:131], v54
	ds_read_b64_tr_b4 v[132:133], v55
	ds_read_b64_tr_b4 v[134:135], v56
	ds_read_b64_tr_b4 v[136:137], v57
	s_waitcnt lgkmcnt(6)
	v_dot8c_i32_i4_e32 v38, v122, v48
	v_dot8c_i32_i4_e32 v39, v122, v46
	v_dot8c_i32_i4_e32 v40, v124, v48
	v_dot8c_i32_i4_e32 v41, v124, v46
	v_dot8c_i32_i4_e32 v42, v126, v48
	v_dot8c_i32_i4_e32 v43, v126, v46
	v_dot8c_i32_i4_e32 v44, v128, v48
	v_dot8c_i32_i4_e32 v45, v128, v46
	v_dot8c_i32_i4_e32 v38, v123, v49
	v_dot8c_i32_i4_e32 v39, v123, v47
	v_dot8c_i32_i4_e32 v40, v125, v49
	v_dot8c_i32_i4_e32 v41, v125, v47
	v_dot8c_i32_i4_e32 v42, v127, v49
	v_dot8c_i32_i4_e32 v43, v127, v47
	v_dot8c_i32_i4_e32 v44, v129, v49
	v_dot8c_i32_i4_e32 v45, v129, v47
	v_and_b32_e32 v78, 0xffff, v22
	v_lshrrev_b32_e32 v79, 16, v22
	v_lshl_add_u32 v78, v78, 7, v152
	v_lshl_add_u32 v79, v79, 7, v153
	s_mov_b32 m0, s98
	s_add_i32 s43, s98, 0x400
	global_load_lds_dwordx4 v78, s[50:51]
	s_mov_b32 m0, s43
	s_nop 0
	global_load_lds_dwordx4 v79, s[50:51]
	s_waitcnt vmcnt(8)
	v_add_u32_e32 v54, s76, v59
	v_add_u32_e32 v55, s76, v60
	v_add_u32_e32 v56, s76, v61
	v_add_u32_e32 v57, s76, v62
	ds_read_b64_tr_b4 v[46:47], v160
	ds_read_b64_tr_b4 v[48:49], v160 offset:1024
	ds_read_b64_tr_b4 v[122:123], v54
	ds_read_b64_tr_b4 v[124:125], v55
	ds_read_b64_tr_b4 v[126:127], v56
	ds_read_b64_tr_b4 v[128:129], v57
	s_waitcnt lgkmcnt(6)
	v_dot8c_i32_i4_e32 v38, v130, v52
	v_dot8c_i32_i4_e32 v39, v130, v50
	v_dot8c_i32_i4_e32 v40, v132, v52
	v_dot8c_i32_i4_e32 v41, v132, v50
	v_dot8c_i32_i4_e32 v42, v134, v52
	v_dot8c_i32_i4_e32 v43, v134, v50
	v_dot8c_i32_i4_e32 v44, v136, v52
	v_dot8c_i32_i4_e32 v45, v136, v50
	v_dot8c_i32_i4_e32 v38, v131, v53
	v_dot8c_i32_i4_e32 v39, v131, v51
	v_dot8c_i32_i4_e32 v40, v133, v53
	v_dot8c_i32_i4_e32 v41, v133, v51
	v_dot8c_i32_i4_e32 v42, v135, v53
	v_dot8c_i32_i4_e32 v43, v135, v51
	v_dot8c_i32_i4_e32 v44, v137, v53
	v_dot8c_i32_i4_e32 v45, v137, v51
	s_nop 3
	s_waitcnt lgkmcnt(15)
	v_lshlrev_b32_e32 v38, 5, v38
	v_lshlrev_b32_e32 v39, 1, v39
	v_add3_u32 v38, v39, v229, v38
	v_cvt_f32_i32_e32 v38, v38
	v_mul_f32_e32 v38, v228, v38
	v_lshlrev_b32_e32 v40, 5, v40
	v_lshlrev_b32_e32 v41, 1, v41
	v_add3_u32 v40, v41, v229, v40
	v_cvt_f32_i32_e32 v40, v40
	v_mul_f32_e32 v40, v228, v40
	v_lshlrev_b32_e32 v42, 5, v42
	v_lshlrev_b32_e32 v43, 1, v43
	v_add3_u32 v42, v43, v229, v42
	v_cvt_f32_i32_e32 v42, v42
	v_mul_f32_e32 v42, v228, v42
	v_lshlrev_b32_e32 v44, 5, v44
	v_lshlrev_b32_e32 v45, 1, v45
	v_add3_u32 v44, v45, v229, v44
	v_cvt_f32_i32_e32 v44, v44
	v_mul_f32_e32 v44, v228, v44
	v_cvt_pk_bf16_f32 v174, v38, v40
	v_cvt_pk_bf16_f32 v175, v42, v44
	v_add_u32_e32 v147, 8, v140
	v_and_b32_e32 v146, 15, v147
	v_xor_b32_e32 v146, 8, v146
	v_bfe_u32 v148, v147, 4, 4
	v_mul_lo_u32 v146, v146, s92
	v_mul_lo_u32 v148, v148, s92
	v_mov_b32_e32 v147, v146
	v_mov_b32_e32 v149, v148
	ds_write2st64_b64 v77, v[146:147], v[148:149] offset1:2
	v_add_u32_e32 v138, 0x400, v74
	ds_read_u8 v139, v138
	v_add_u32_e32 v141, 0x400, v73
	ds_read_u8 v140, v141
	s_mov_b32 s43, s67
	v_mov_b32_e32 v138, s43
	ds_read2st64_b32 v[228:229], v138 offset1:1
	ds_read_b128 v[26:29], v227 offset:2048
	ds_read_b128 v[30:33], v227 offset:2064
	v_mov_b32_e32 v38, 0
	v_mov_b32_e32 v39, 0
	v_mov_b32_e32 v40, 0
	v_mov_b32_e32 v41, 0
	v_mov_b32_e32 v42, 0
	v_mov_b32_e32 v43, 0
	v_mov_b32_e32 v44, 0
	v_mov_b32_e32 v45, 0
	v_and_b32_e32 v78, 0xffff, v23
	v_lshrrev_b32_e32 v79, 16, v23
	v_lshl_add_u32 v78, v78, 7, v152
	v_lshl_add_u32 v79, v79, 7, v153
	s_mov_b32 m0, s99
	s_add_i32 s43, s99, 0x400
	global_load_lds_dwordx4 v78, s[50:51]
	s_mov_b32 m0, s43
	s_nop 0
	global_load_lds_dwordx4 v79, s[50:51]
	s_waitcnt vmcnt(8)
; #define TR4(p_) __builtin_amdgcn_ds_read_tr4_b64_v2i32((LAS v2i*)(p_))
; #define VDMA(st_, k_) do { _Pragma("unroll") for (int i_ = 0; i_ < 4; ++i_) { \
;         const unsigned off_ = (unsigned)((st_) >> 2) * (16384u * 128u) + (PE_ID(E, 4 * ((st_) & 3) + i_) << 7) + ((i_ & 1) ? cx1 : cx0); \
;         __builtin_amdgcn_global_load_lds((const unsigned*)(V4 + off_), (LAS unsigned*)(ldsb + BUF[k_] + 1024 * i_), 16, 0, 0); } } while (0)
; __device__ __forceinline__ void peer_v_tokens(int j, const LAS unsigned short* EL, const LAS unsigned char* AL  , const LAS float* ASC  , const LAS int* SAL  , ...
;     ...
;         for (int st = 0; st < 16; ++st) {
;             const int p = st >> 2, q = st & 3;
;             if (st < 14) VDMA(st + 2, (st + 2) % 3);
;             if (st < 14) asm volatile("s_waitcnt vmcnt(8)" ::: "memory");
;             else if (st == 14) asm volatile("s_waitcnt vmcnt(4)" ::: "memory");
;             else asm volatile("s_waitcnt vmcnt(0)" ::: "memory");
;             if (q == 0) {
; #pragma unroll
;                 for (int r = 0; r < 4; ++r) { accH[r] = 0; accL[r] = 0; } }
; #pragma unroll
;             for (int tp = 0; tp < 2; ++tp) {
;                 const v2i ao = TR4(ATL + (2 * q + tp) * 128 + 8 * s16), ah = TR4(ATL + 1024 + (2 * q + tp) * 128 + 8 * s16);
; #pragma unroll
;                 for (int r = 0; r < 4; ++r) {
;                     const v2i d = TR4(ldsb + BUF[st % 3] + 2048 * tp + roff[r]);
;                     accH[r] = __builtin_amdgcn_sdot8(d.x, ah.x, accH[r], false); accH[r] = __builtin_amdgcn_sdot8(d.y, ah.y, accH[r], false);
;                     accL[r] = __builtin_amdgcn_sdot8(d.x, ao.x, accL[r], false); accL[r] = __builtin_amdgcn_sdot8(d.y, ao.y, accL[r], false);
;                 }
;             }
;             asm volatile("s_waitcnt lgkmcnt(0)" ::: "memory");
	v_add_u32_e32 v54, s77, v59
	v_add_u32_e32 v55, s77, v60
	v_add_u32_e32 v56, s77, v61
	v_add_u32_e32 v57, s77, v62
	ds_read_b64_tr_b4 v[50:51], v160 offset:128
	ds_read_b64_tr_b4 v[52:53], v160 offset:1152
	ds_read_b64_tr_b4 v[130:131], v54
	ds_read_b64_tr_b4 v[132:133], v55
	ds_read_b64_tr_b4 v[134:135], v56
	ds_read_b64_tr_b4 v[136:137], v57
	s_waitcnt lgkmcnt(12)
	v_dot8c_i32_i4_e32 v38, v122, v48
	v_dot8c_i32_i4_e32 v39, v122, v46
	v_dot8c_i32_i4_e32 v40, v124, v48
	v_dot8c_i32_i4_e32 v41, v124, v46
	v_dot8c_i32_i4_e32 v42, v126, v48
	v_dot8c_i32_i4_e32 v43, v126, v46
	v_dot8c_i32_i4_e32 v44, v128, v48
	v_dot8c_i32_i4_e32 v45, v128, v46
	v_dot8c_i32_i4_e32 v38, v123, v49
	v_dot8c_i32_i4_e32 v39, v123, v47
	v_dot8c_i32_i4_e32 v40, v125, v49
	v_dot8c_i32_i4_e32 v41, v125, v47
	v_dot8c_i32_i4_e32 v42, v127, v49
	v_dot8c_i32_i4_e32 v43, v127, v47
	v_dot8c_i32_i4_e32 v44, v129, v49
	v_dot8c_i32_i4_e32 v45, v129, v47
	v_and_b32_e32 v78, 0xffff, v24
	v_lshrrev_b32_e32 v79, 16, v24
	v_lshl_add_u32 v78, v78, 7, v152
	v_lshl_add_u32 v79, v79, 7, v153
	s_mov_b32 m0, s76
	s_add_i32 s43, s76, 0x400
	global_load_lds_dwordx4 v78, s[50:51]
	s_mov_b32 m0, s43
	s_nop 0
	global_load_lds_dwordx4 v79, s[50:51]
	s_waitcnt vmcnt(8)
	v_add_u32_e32 v54, s78, v59
	v_add_u32_e32 v55, s78, v60
	v_add_u32_e32 v56, s78, v61
	v_add_u32_e32 v57, s78, v62
	ds_read_b64_tr_b4 v[46:47], v160 offset:256
	ds_read_b64_tr_b4 v[48:49], v160 offset:1280
	ds_read_b64_tr_b4 v[122:123], v54
	ds_read_b64_tr_b4 v[124:125], v55
	ds_read_b64_tr_b4 v[126:127], v56
	ds_read_b64_tr_b4 v[128:129], v57
	s_waitcnt lgkmcnt(6)
	v_dot8c_i32_i4_e32 v38, v130, v52
	v_dot8c_i32_i4_e32 v39, v130, v50
	v_dot8c_i32_i4_e32 v40, v132, v52
	v_dot8c_i32_i4_e32 v41, v132, v50
	v_dot8c_i32_i4_e32 v42, v134, v52
	v_dot8c_i32_i4_e32 v43, v134, v50
	v_dot8c_i32_i4_e32 v44, v136, v52
	v_dot8c_i32_i4_e32 v45, v136, v50
	v_dot8c_i32_i4_e32 v38, v131, v53
	v_dot8c_i32_i4_e32 v39, v131, v51
	v_dot8c_i32_i4_e32 v40, v133, v53
	v_dot8c_i32_i4_e32 v41, v133, v51
	v_dot8c_i32_i4_e32 v42, v135, v53
	v_dot8c_i32_i4_e32 v43, v135, v51
	v_dot8c_i32_i4_e32 v44, v137, v53
	v_dot8c_i32_i4_e32 v45, v137, v51
	v_and_b32_e32 v78, 0xffff, v25
	v_lshrrev_b32_e32 v79, 16, v25
	v_lshl_add_u32 v78, v78, 7, v152
	v_lshl_add_u32 v79, v79, 7, v153
	s_mov_b32 m0, s77
	s_add_i32 s43, s77, 0x400
	global_load_lds_dwordx4 v78, s[50:51]
	s_mov_b32 m0, s43
	s_nop 0
	global_load_lds_dwordx4 v79, s[50:51]
	s_waitcnt vmcnt(8)
	v_add_u32_e32 v54, s79, v59
	v_add_u32_e32 v55, s79, v60
	v_add_u32_e32 v56, s79, v61
	v_add_u32_e32 v57, s79, v62
	ds_read_b64_tr_b4 v[50:51], v160 offset:384
	ds_read_b64_tr_b4 v[52:53], v160 offset:1408
	ds_read_b64_tr_b4 v[130:131], v54
	ds_read_b64_tr_b4 v[132:133], v55
	ds_read_b64_tr_b4 v[134:135], v56
	ds_read_b64_tr_b4 v[136:137], v57
	s_waitcnt lgkmcnt(6)
	v_dot8c_i32_i4_e32 v38, v122, v48
	v_dot8c_i32_i4_e32 v39, v122, v46
	v_dot8c_i32_i4_e32 v40, v124, v48
	v_dot8c_i32_i4_e32 v41, v124, v46
	v_dot8c_i32_i4_e32 v42, v126, v48
	v_dot8c_i32_i4_e32 v43, v126, v46
	v_dot8c_i32_i4_e32 v44, v128, v48
	v_dot8c_i32_i4_e32 v45, v128, v46
	v_dot8c_i32_i4_e32 v38, v123, v49
	v_dot8c_i32_i4_e32 v39, v123, v47
	v_dot8c_i32_i4_e32 v40, v125, v49
	v_dot8c_i32_i4_e32 v41, v125, v47
	v_dot8c_i32_i4_e32 v42, v127, v49
	v_dot8c_i32_i4_e32 v43, v127, v47
	v_dot8c_i32_i4_e32 v44, v129, v49
	v_dot8c_i32_i4_e32 v45, v129, v47
	s_waitcnt lgkmcnt(15)
	v_and_b32_e32 v78, 0xffff, v26
	v_lshrrev_b32_e32 v79, 16, v26
	v_lshl_add_u32 v78, v78, 7, v152
	v_lshl_add_u32 v79, v79, 7, v153
	s_mov_b32 m0, s78
	s_add_i32 s43, s78, 0x400
	global_load_lds_dwordx4 v78, s[50:51]
	s_mov_b32 m0, s43
	s_nop 0
	global_load_lds_dwordx4 v79, s[50:51]
	s_waitcnt vmcnt(8)
	v_add_u32_e32 v54, s98, v59
	v_add_u32_e32 v55, s98, v60
	v_add_u32_e32 v56, s98, v61
	v_add_u32_e32 v57, s98, v62
	ds_read_b64_tr_b4 v[46:47], v160 offset:512
	ds_read_b64_tr_b4 v[48:49], v160 offset:1536
	ds_read_b64_tr_b4 v[122:123], v54
	ds_read_b64_tr_b4 v[124:125], v55
	ds_read_b64_tr_b4 v[126:127], v56
	ds_read_b64_tr_b4 v[128:129], v57
	s_waitcnt lgkmcnt(6)
	v_dot8c_i32_i4_e32 v38, v130, v52
	v_dot8c_i32_i4_e32 v39, v130, v50
	v_dot8c_i32_i4_e32 v40, v132, v52
	v_dot8c_i32_i4_e32 v41, v132, v50
	v_dot8c_i32_i4_e32 v42, v134, v52
	v_dot8c_i32_i4_e32 v43, v134, v50
	v_dot8c_i32_i4_e32 v44, v136, v52
	v_dot8c_i32_i4_e32 v45, v136, v50
	v_dot8c_i32_i4_e32 v38, v131, v53
	v_dot8c_i32_i4_e32 v39, v131, v51
	v_dot8c_i32_i4_e32 v40, v133, v53
	v_dot8c_i32_i4_e32 v41, v133, v51
	v_dot8c_i32_i4_e32 v42, v135, v53
	v_dot8c_i32_i4_e32 v43, v135, v51
	v_dot8c_i32_i4_e32 v44, v137, v53
	v_dot8c_i32_i4_e32 v45, v137, v51
	v_and_b32_e32 v78, 0xffff, v27
	v_lshrrev_b32_e32 v79, 16, v27
	v_lshl_add_u32 v78, v78, 7, v152
	v_lshl_add_u32 v79, v79, 7, v153
	s_mov_b32 m0, s79
	s_add_i32 s43, s79, 0x400
	global_load_lds_dwordx4 v78, s[50:51]
	s_mov_b32 m0, s43
	s_nop 0
	global_load_lds_dwordx4 v79, s[50:51]
	s_waitcnt vmcnt(8)
	v_add_u32_e32 v54, s99, v59
	v_add_u32_e32 v55, s99, v60
	v_add_u32_e32 v56, s99, v61
	v_add_u32_e32 v57, s99, v62
	ds_read_b64_tr_b4 v[50:51], v160 offset:640
	ds_read_b64_tr_b4 v[52:53], v160 offset:1664
	ds_read_b64_tr_b4 v[130:131], v54
	ds_read_b64_tr_b4 v[132:133], v55
	ds_read_b64_tr_b4 v[134:135], v56
	ds_read_b64_tr_b4 v[136:137], v57
	s_waitcnt lgkmcnt(6)
	v_dot8c_i32_i4_e32 v38, v122, v48
	v_dot8c_i32_i4_e32 v39, v122, v46
	v_dot8c_i32_i4_e32 v40, v124, v48
	v_dot8c_i32_i4_e32 v41, v124, v46
	v_dot8c_i32_i4_e32 v42, v126, v48
	v_dot8c_i32_i4_e32 v43, v126, v46
	v_dot8c_i32_i4_e32 v44, v128, v48
	v_dot8c_i32_i4_e32 v45, v128, v46
	v_dot8c_i32_i4_e32 v38, v123, v49
	v_dot8c_i32_i4_e32 v39, v123, v47
	v_dot8c_i32_i4_e32 v40, v125, v49
	v_dot8c_i32_i4_e32 v41, v125, v47
	v_dot8c_i32_i4_e32 v42, v127, v49
	v_dot8c_i32_i4_e32 v43, v127, v47
	v_dot8c_i32_i4_e32 v44, v129, v49
	v_dot8c_i32_i4_e32 v45, v129, v47
	s_waitcnt lgkmcnt(15)
; __device__ __forceinline__ bf16 f2bf(float f) { return (bf16)f2bfu(f); }
; #define TR4(p_) __builtin_amdgcn_ds_read_tr4_b64_v2i32((LAS v2i*)(p_))
; __device__ __forceinline__ void peer_v_tokens(int j, const LAS unsigned short* EL, const LAS unsigned char* AL  , const LAS float* ASC  , const LAS int* SAL  , ...
;     ...
;         { unsigned ho = (unsigned)t * (D / 4) + (unsigned)lane; asm volatile("" : "+v"(ho)); const uint2* hp = (const uint2*)HB + ho; const float4* gp = (const float4*)fng + lane;
; #pragma unroll
;           for (int jq = 0; jq < 4; ++jq) { hv[jq] = hp[64 * jq]; gv[jq] = gp[64 * jq]; } }
;     ...
;         for (int st = 0; st < 16; ++st) {
;             const int p = st >> 2, q = st & 3;
;             if (st < 14) VDMA(st + 2, (st + 2) % 3);
;             if (st < 14) asm volatile("s_waitcnt vmcnt(8)" ::: "memory");
;             else if (st == 14) asm volatile("s_waitcnt vmcnt(4)" ::: "memory");
;             else asm volatile("s_waitcnt vmcnt(0)" ::: "memory");
;             if (q == 0) {
; #pragma unroll
;                 for (int r = 0; r < 4; ++r) { accH[r] = 0; accL[r] = 0; } }
; #pragma unroll
;             for (int tp = 0; tp < 2; ++tp) {
;                 const v2i ao = TR4(ATL + (2 * q + tp) * 128 + 8 * s16), ah = TR4(ATL + 1024 + (2 * q + tp) * 128 + 8 * s16);
; #pragma unroll
;                 for (int r = 0; r < 4; ++r) {
;                     const v2i d = TR4(ldsb + BUF[st % 3] + 2048 * tp + roff[r]);
;                     accH[r] = __builtin_amdgcn_sdot8(d.x, ah.x, accH[r], false); accH[r] = __builtin_amdgcn_sdot8(d.y, ah.y, accH[r], false);
;                     accL[r] = __builtin_amdgcn_sdot8(d.x, ao.x, accL[r], false); accL[r] = __builtin_amdgcn_sdot8(d.y, ao.y, accL[r], false);
;                 }
;             }
;             asm volatile("s_waitcnt lgkmcnt(0)" ::: "memory");
;             if (q == 3) {
; #pragma unroll
;                 for (int r = 0; r < 4; ++r) STASH[256 * p + 16 * (grp + 4 * r) + pc] = f2bf(asc * (float)(2 * ((accH[r] << 4) + accL[r]) + sa));
;             }
;         }
	v_add_u32_e32 v143, 8, v139
	v_and_b32_e32 v142, 15, v143
	v_xor_b32_e32 v142, 8, v142
	v_bfe_u32 v144, v143, 4, 4
	v_mul_lo_u32 v142, v142, s92
	v_mul_lo_u32 v144, v144, s92
	v_mov_b32_e32 v143, v142
	v_mov_b32_e32 v145, v144
	ds_write2st64_b64 v159, v[142:143], v[144:145] offset1:2
	v_and_b32_e32 v78, 0xffff, v28
	v_lshrrev_b32_e32 v79, 16, v28
	v_lshl_add_u32 v78, v78, 7, v152
	v_lshl_add_u32 v79, v79, 7, v153
	s_mov_b32 m0, s98
	s_add_i32 s43, s98, 0x400
	global_load_lds_dwordx4 v78, s[50:51]
	s_mov_b32 m0, s43
	s_nop 0
	global_load_lds_dwordx4 v79, s[50:51]
	s_waitcnt vmcnt(8)
	v_add_u32_e32 v54, s76, v59
	v_add_u32_e32 v55, s76, v60
	v_add_u32_e32 v56, s76, v61
	v_add_u32_e32 v57, s76, v62
	ds_read_b64_tr_b4 v[46:47], v160 offset:768
	ds_read_b64_tr_b4 v[48:49], v160 offset:1792
	ds_read_b64_tr_b4 v[122:123], v54
	ds_read_b64_tr_b4 v[124:125], v55
	ds_read_b64_tr_b4 v[126:127], v56
	ds_read_b64_tr_b4 v[128:129], v57
	s_waitcnt lgkmcnt(7)
	v_dot8c_i32_i4_e32 v38, v130, v52
	v_dot8c_i32_i4_e32 v39, v130, v50
	v_dot8c_i32_i4_e32 v40, v132, v52
	v_dot8c_i32_i4_e32 v41, v132, v50
	v_dot8c_i32_i4_e32 v42, v134, v52
	v_dot8c_i32_i4_e32 v43, v134, v50
	v_dot8c_i32_i4_e32 v44, v136, v52
	v_dot8c_i32_i4_e32 v45, v136, v50
	v_dot8c_i32_i4_e32 v38, v131, v53
	v_dot8c_i32_i4_e32 v39, v131, v51
	v_dot8c_i32_i4_e32 v40, v133, v53
	v_dot8c_i32_i4_e32 v41, v133, v51
	v_dot8c_i32_i4_e32 v42, v135, v53
	v_dot8c_i32_i4_e32 v43, v135, v51
	v_dot8c_i32_i4_e32 v44, v137, v53
	v_dot8c_i32_i4_e32 v45, v137, v51
	v_and_b32_e32 v78, 0xffff, v29
	v_lshrrev_b32_e32 v79, 16, v29
	v_lshl_add_u32 v78, v78, 7, v152
	v_lshl_add_u32 v79, v79, 7, v153
	s_mov_b32 m0, s99
	s_add_i32 s43, s99, 0x400
	global_load_lds_dwordx4 v78, s[50:51]
	s_mov_b32 m0, s43
	s_nop 0
	global_load_lds_dwordx4 v79, s[50:51]
	s_waitcnt vmcnt(8)
	v_add_u32_e32 v54, s77, v59
	v_add_u32_e32 v55, s77, v60
	v_add_u32_e32 v56, s77, v61
	v_add_u32_e32 v57, s77, v62
	ds_read_b64_tr_b4 v[50:51], v160 offset:896
	ds_read_b64_tr_b4 v[52:53], v160 offset:1920
	ds_read_b64_tr_b4 v[130:131], v54
	ds_read_b64_tr_b4 v[132:133], v55
	ds_read_b64_tr_b4 v[134:135], v56
	ds_read_b64_tr_b4 v[136:137], v57
	s_waitcnt lgkmcnt(6)
	v_dot8c_i32_i4_e32 v38, v122, v48
	v_dot8c_i32_i4_e32 v39, v122, v46
	v_dot8c_i32_i4_e32 v40, v124, v48
	v_dot8c_i32_i4_e32 v41, v124, v46
	v_dot8c_i32_i4_e32 v42, v126, v48
	v_dot8c_i32_i4_e32 v43, v126, v46
	v_dot8c_i32_i4_e32 v44, v128, v48
	v_dot8c_i32_i4_e32 v45, v128, v46
	v_dot8c_i32_i4_e32 v38, v123, v49
	v_dot8c_i32_i4_e32 v39, v123, v47
	v_dot8c_i32_i4_e32 v40, v125, v49
	v_dot8c_i32_i4_e32 v41, v125, v47
	v_dot8c_i32_i4_e32 v42, v127, v49
	v_dot8c_i32_i4_e32 v43, v127, v47
	v_dot8c_i32_i4_e32 v44, v129, v49
	v_dot8c_i32_i4_e32 v45, v129, v47
	v_and_b32_e32 v78, 0xffff, v30
	v_lshrrev_b32_e32 v79, 16, v30
	v_lshl_add_u32 v78, v78, 7, v152
	v_lshl_add_u32 v79, v79, 7, v153
	s_mov_b32 m0, s76
	s_add_i32 s43, s76, 0x400
	global_load_lds_dwordx4 v78, s[50:51]
	s_mov_b32 m0, s43
	s_nop 0
	global_load_lds_dwordx4 v79, s[50:51]
	s_waitcnt vmcnt(8)
	v_add_u32_e32 v54, s78, v59
	v_add_u32_e32 v55, s78, v60
	v_add_u32_e32 v56, s78, v61
	v_add_u32_e32 v57, s78, v62
	ds_read_b64_tr_b4 v[46:47], v160
	ds_read_b64_tr_b4 v[48:49], v160 offset:1024
	ds_read_b64_tr_b4 v[122:123], v54
	ds_read_b64_tr_b4 v[124:125], v55
	ds_read_b64_tr_b4 v[126:127], v56
	ds_read_b64_tr_b4 v[128:129], v57
	s_waitcnt lgkmcnt(6)
	v_dot8c_i32_i4_e32 v38, v130, v52
	v_dot8c_i32_i4_e32 v39, v130, v50
	v_dot8c_i32_i4_e32 v40, v132, v52
	v_dot8c_i32_i4_e32 v41, v132, v50
	v_dot8c_i32_i4_e32 v42, v134, v52
	v_dot8c_i32_i4_e32 v43, v134, v50
	v_dot8c_i32_i4_e32 v44, v136, v52
	v_dot8c_i32_i4_e32 v45, v136, v50
	v_dot8c_i32_i4_e32 v38, v131, v53
	v_dot8c_i32_i4_e32 v39, v131, v51
	v_dot8c_i32_i4_e32 v40, v133, v53
	v_dot8c_i32_i4_e32 v41, v133, v51
	v_dot8c_i32_i4_e32 v42, v135, v53
	v_dot8c_i32_i4_e32 v43, v135, v51
	v_dot8c_i32_i4_e32 v44, v137, v53
	v_dot8c_i32_i4_e32 v45, v137, v51
	s_nop 3
	s_waitcnt lgkmcnt(15)
	v_lshlrev_b32_e32 v38, 5, v38
	v_lshlrev_b32_e32 v39, 1, v39
	v_add3_u32 v38, v39, v229, v38
	v_cvt_f32_i32_e32 v38, v38
	v_mul_f32_e32 v38, v228, v38
	v_lshlrev_b32_e32 v40, 5, v40
	v_lshlrev_b32_e32 v41, 1, v41
	v_add3_u32 v40, v41, v229, v40
	v_cvt_f32_i32_e32 v40, v40
	v_mul_f32_e32 v40, v228, v40
	v_lshlrev_b32_e32 v42, 5, v42
	v_lshlrev_b32_e32 v43, 1, v43
	v_add3_u32 v42, v43, v229, v42
	v_cvt_f32_i32_e32 v42, v42
	v_mul_f32_e32 v42, v228, v42
	v_lshlrev_b32_e32 v44, 5, v44
	v_lshlrev_b32_e32 v45, 1, v45
	v_add3_u32 v44, v45, v229, v44
	v_cvt_f32_i32_e32 v44, v44
	v_mul_f32_e32 v44, v228, v44
	v_cvt_pk_bf16_f32 v168, v38, v40
	v_cvt_pk_bf16_f32 v169, v42, v44
	s_add_i32 s43, s40, 0
	s_lshl_b32 s43, s43, 11
	v_add_u32_e32 v138, s43, v66
	global_load_dwordx2 v[194:195], v138, s[70:71]
	global_load_dwordx2 v[196:197], v138, s[70:71] offset:512
	global_load_dwordx2 v[198:199], v138, s[70:71] offset:1024
	global_load_dwordx2 v[200:201], v138, s[70:71] offset:1536
	v_add_u32_e32 v147, 8, v140
	v_and_b32_e32 v146, 15, v147
	v_xor_b32_e32 v146, 8, v146
	v_bfe_u32 v148, v147, 4, 4
	v_mul_lo_u32 v146, v146, s92
	v_mul_lo_u32 v148, v148, s92
	v_mov_b32_e32 v147, v146
	v_mov_b32_e32 v149, v148
	ds_write2st64_b64 v77, v[146:147], v[148:149] offset1:2
	v_add_u32_e32 v138, 0x800, v74
	ds_read_u8 v139, v138
	v_add_u32_e32 v141, 0x800, v73
	ds_read_u8 v140, v141
	s_add_i32 s43, s67, 32
	v_mov_b32_e32 v138, s43
	ds_read2st64_b32 v[228:229], v138 offset1:1
	ds_read_b128 v[18:21], v227 offset:4096
	ds_read_b128 v[22:25], v227 offset:4112
	v_mov_b32_e32 v150, v63
	v_mov_b32_e32 v151, v64
	v_mov_b32_e32 v38, 0
	v_mov_b32_e32 v39, 0
	v_mov_b32_e32 v40, 0
	v_mov_b32_e32 v41, 0
	v_mov_b32_e32 v42, 0
	v_mov_b32_e32 v43, 0
	v_mov_b32_e32 v44, 0
	v_mov_b32_e32 v45, 0
	v_and_b32_e32 v78, 0xffff, v31
	v_lshrrev_b32_e32 v79, 16, v31
	v_lshl_add_u32 v78, v78, 7, v152
	v_lshl_add_u32 v79, v79, 7, v153
	s_mov_b32 m0, s77
	s_add_i32 s43, s77, 0x400
	global_load_lds_dwordx4 v78, s[50:51]
	s_mov_b32 m0, s43
	s_nop 0
	global_load_lds_dwordx4 v79, s[50:51]
	s_waitcnt vmcnt(12)
; #define TR4(p_) __builtin_amdgcn_ds_read_tr4_b64_v2i32((LAS v2i*)(p_))
; #define VDMA(st_, k_) do { _Pragma("unroll") for (int i_ = 0; i_ < 4; ++i_) { \
;         const unsigned off_ = (unsigned)((st_) >> 2) * (16384u * 128u) + (PE_ID(E, 4 * ((st_) & 3) + i_) << 7) + ((i_ & 1) ? cx1 : cx0); \
;         __builtin_amdgcn_global_load_lds((const unsigned*)(V4 + off_), (LAS unsigned*)(ldsb + BUF[k_] + 1024 * i_), 16, 0, 0); } } while (0)
; __device__ __forceinline__ void peer_v_tokens(int j, const LAS unsigned short* EL, const LAS unsigned char* AL  , const LAS float* ASC  , const LAS int* SAL  , ...
;     ...
;         for (int st = 0; st < 16; ++st) {
;             const int p = st >> 2, q = st & 3;
;             if (st < 14) VDMA(st + 2, (st + 2) % 3);
;             if (st < 14) asm volatile("s_waitcnt vmcnt(8)" ::: "memory");
;             else if (st == 14) asm volatile("s_waitcnt vmcnt(4)" ::: "memory");
;             else asm volatile("s_waitcnt vmcnt(0)" ::: "memory");
;             if (q == 0) {
; #pragma unroll
;                 for (int r = 0; r < 4; ++r) { accH[r] = 0; accL[r] = 0; } }
; #pragma unroll
;             for (int tp = 0; tp < 2; ++tp) {
;                 const v2i ao = TR4(ATL + (2 * q + tp) * 128 + 8 * s16), ah = TR4(ATL + 1024 + (2 * q + tp) * 128 + 8 * s16);
; #pragma unroll
;                 for (int r = 0; r < 4; ++r) {
;                     const v2i d = TR4(ldsb + BUF[st % 3] + 2048 * tp + roff[r]);
;                     accH[r] = __builtin_amdgcn_sdot8(d.x, ah.x, accH[r], false); accH[r] = __builtin_amdgcn_sdot8(d.y, ah.y, accH[r], false);
;                     accL[r] = __builtin_amdgcn_sdot8(d.x, ao.x, accL[r], false); accL[r] = __builtin_amdgcn_sdot8(d.y, ao.y, accL[r], false);
;                 }
;             }
;             asm volatile("s_waitcnt lgkmcnt(0)" ::: "memory");
	v_add_u32_e32 v54, s79, v59
	v_add_u32_e32 v55, s79, v60
	v_add_u32_e32 v56, s79, v61
	v_add_u32_e32 v57, s79, v62
	ds_read_b64_tr_b4 v[50:51], v160 offset:128
	ds_read_b64_tr_b4 v[52:53], v160 offset:1152
	ds_read_b64_tr_b4 v[130:131], v54
	ds_read_b64_tr_b4 v[132:133], v55
	ds_read_b64_tr_b4 v[134:135], v56
	ds_read_b64_tr_b4 v[136:137], v57
	s_waitcnt lgkmcnt(12)
	v_dot8c_i32_i4_e32 v38, v122, v48
	v_dot8c_i32_i4_e32 v39, v122, v46
	v_dot8c_i32_i4_e32 v40, v124, v48
	v_dot8c_i32_i4_e32 v41, v124, v46
	v_dot8c_i32_i4_e32 v42, v126, v48
	v_dot8c_i32_i4_e32 v43, v126, v46
	v_dot8c_i32_i4_e32 v44, v128, v48
	v_dot8c_i32_i4_e32 v45, v128, v46
	v_dot8c_i32_i4_e32 v38, v123, v49
	v_dot8c_i32_i4_e32 v39, v123, v47
	v_dot8c_i32_i4_e32 v40, v125, v49
	v_dot8c_i32_i4_e32 v41, v125, v47
	v_dot8c_i32_i4_e32 v42, v127, v49
	v_dot8c_i32_i4_e32 v43, v127, v47
	v_dot8c_i32_i4_e32 v44, v129, v49
	v_dot8c_i32_i4_e32 v45, v129, v47
	v_and_b32_e32 v78, 0xffff, v32
	v_lshrrev_b32_e32 v79, 16, v32
	v_lshl_add_u32 v78, v78, 7, v152
	v_lshl_add_u32 v79, v79, 7, v153
	s_mov_b32 m0, s78
	s_add_i32 s43, s78, 0x400
	global_load_lds_dwordx4 v78, s[50:51]
	s_mov_b32 m0, s43
	s_nop 0
	global_load_lds_dwordx4 v79, s[50:51]
	s_waitcnt vmcnt(12)
	v_add_u32_e32 v54, s98, v59
	v_add_u32_e32 v55, s98, v60
	v_add_u32_e32 v56, s98, v61
	v_add_u32_e32 v57, s98, v62
	ds_read_b64_tr_b4 v[46:47], v160 offset:256
	ds_read_b64_tr_b4 v[48:49], v160 offset:1280
	ds_read_b64_tr_b4 v[122:123], v54
	ds_read_b64_tr_b4 v[124:125], v55
	ds_read_b64_tr_b4 v[126:127], v56
	ds_read_b64_tr_b4 v[128:129], v57
	s_waitcnt lgkmcnt(6)
	v_dot8c_i32_i4_e32 v38, v130, v52
	v_dot8c_i32_i4_e32 v39, v130, v50
	v_dot8c_i32_i4_e32 v40, v132, v52
	v_dot8c_i32_i4_e32 v41, v132, v50
	v_dot8c_i32_i4_e32 v42, v134, v52
	v_dot8c_i32_i4_e32 v43, v134, v50
	v_dot8c_i32_i4_e32 v44, v136, v52
	v_dot8c_i32_i4_e32 v45, v136, v50
	v_dot8c_i32_i4_e32 v38, v131, v53
	v_dot8c_i32_i4_e32 v39, v131, v51
	v_dot8c_i32_i4_e32 v40, v133, v53
	v_dot8c_i32_i4_e32 v41, v133, v51
	v_dot8c_i32_i4_e32 v42, v135, v53
	v_dot8c_i32_i4_e32 v43, v135, v51
	v_dot8c_i32_i4_e32 v44, v137, v53
	v_dot8c_i32_i4_e32 v45, v137, v51
	v_and_b32_e32 v78, 0xffff, v33
	v_lshrrev_b32_e32 v79, 16, v33
	v_lshl_add_u32 v78, v78, 7, v152
	v_lshl_add_u32 v79, v79, 7, v153
	s_mov_b32 m0, s79
	s_add_i32 s43, s79, 0x400
	global_load_lds_dwordx4 v78, s[50:51]
	s_mov_b32 m0, s43
	s_nop 0
	global_load_lds_dwordx4 v79, s[50:51]
	s_waitcnt vmcnt(12)
	v_add_u32_e32 v54, s99, v59
	v_add_u32_e32 v55, s99, v60
	v_add_u32_e32 v56, s99, v61
	v_add_u32_e32 v57, s99, v62
	ds_read_b64_tr_b4 v[50:51], v160 offset:384
	ds_read_b64_tr_b4 v[52:53], v160 offset:1408
	ds_read_b64_tr_b4 v[130:131], v54
	ds_read_b64_tr_b4 v[132:133], v55
	ds_read_b64_tr_b4 v[134:135], v56
	ds_read_b64_tr_b4 v[136:137], v57
	s_waitcnt lgkmcnt(6)
	v_dot8c_i32_i4_e32 v38, v122, v48
	v_dot8c_i32_i4_e32 v39, v122, v46
	v_dot8c_i32_i4_e32 v40, v124, v48
	v_dot8c_i32_i4_e32 v41, v124, v46
	v_dot8c_i32_i4_e32 v42, v126, v48
	v_dot8c_i32_i4_e32 v43, v126, v46
	v_dot8c_i32_i4_e32 v44, v128, v48
	v_dot8c_i32_i4_e32 v45, v128, v46
	v_dot8c_i32_i4_e32 v38, v123, v49
	v_dot8c_i32_i4_e32 v39, v123, v47
	v_dot8c_i32_i4_e32 v40, v125, v49
	v_dot8c_i32_i4_e32 v41, v125, v47
	v_dot8c_i32_i4_e32 v42, v127, v49
	v_dot8c_i32_i4_e32 v43, v127, v47
	v_dot8c_i32_i4_e32 v44, v129, v49
	v_dot8c_i32_i4_e32 v45, v129, v47
	s_waitcnt lgkmcnt(15)
	v_and_b32_e32 v78, 0xffff, v18
	v_lshrrev_b32_e32 v79, 16, v18
	v_lshl_add_u32 v78, v78, 7, v150
	v_lshl_add_u32 v79, v79, 7, v151
	s_mov_b32 m0, s98
	s_add_i32 s43, s98, 0x400
	global_load_lds_dwordx4 v78, s[50:51]
	s_mov_b32 m0, s43
	s_nop 0
	global_load_lds_dwordx4 v79, s[50:51]
	s_waitcnt vmcnt(12)
	v_add_u32_e32 v54, s76, v59
	v_add_u32_e32 v55, s76, v60
	v_add_u32_e32 v56, s76, v61
	v_add_u32_e32 v57, s76, v62
	ds_read_b64_tr_b4 v[46:47], v160 offset:512
	ds_read_b64_tr_b4 v[48:49], v160 offset:1536
	ds_read_b64_tr_b4 v[122:123], v54
	ds_read_b64_tr_b4 v[124:125], v55
	ds_read_b64_tr_b4 v[126:127], v56
	ds_read_b64_tr_b4 v[128:129], v57
	s_waitcnt lgkmcnt(6)
	v_dot8c_i32_i4_e32 v38, v130, v52
	v_dot8c_i32_i4_e32 v39, v130, v50
	v_dot8c_i32_i4_e32 v40, v132, v52
	v_dot8c_i32_i4_e32 v41, v132, v50
	v_dot8c_i32_i4_e32 v42, v134, v52
	v_dot8c_i32_i4_e32 v43, v134, v50
	v_dot8c_i32_i4_e32 v44, v136, v52
	v_dot8c_i32_i4_e32 v45, v136, v50
	v_dot8c_i32_i4_e32 v38, v131, v53
	v_dot8c_i32_i4_e32 v39, v131, v51
	v_dot8c_i32_i4_e32 v40, v133, v53
	v_dot8c_i32_i4_e32 v41, v133, v51
	v_dot8c_i32_i4_e32 v42, v135, v53
	v_dot8c_i32_i4_e32 v43, v135, v51
	v_dot8c_i32_i4_e32 v44, v137, v53
	v_dot8c_i32_i4_e32 v45, v137, v51
	v_and_b32_e32 v78, 0xffff, v19
	v_lshrrev_b32_e32 v79, 16, v19
	v_lshl_add_u32 v78, v78, 7, v150
	v_lshl_add_u32 v79, v79, 7, v151
	s_mov_b32 m0, s99
	s_add_i32 s43, s99, 0x400
	global_load_lds_dwordx4 v78, s[50:51]
	s_mov_b32 m0, s43
	s_nop 0
	global_load_lds_dwordx4 v79, s[50:51]
	s_waitcnt vmcnt(8)
	v_add_u32_e32 v54, s77, v59
	v_add_u32_e32 v55, s77, v60
	v_add_u32_e32 v56, s77, v61
	v_add_u32_e32 v57, s77, v62
	ds_read_b64_tr_b4 v[50:51], v160 offset:640
	ds_read_b64_tr_b4 v[52:53], v160 offset:1664
	ds_read_b64_tr_b4 v[130:131], v54
	ds_read_b64_tr_b4 v[132:133], v55
	ds_read_b64_tr_b4 v[134:135], v56
	ds_read_b64_tr_b4 v[136:137], v57
	s_waitcnt lgkmcnt(6)
	v_dot8c_i32_i4_e32 v38, v122, v48
	v_dot8c_i32_i4_e32 v39, v122, v46
	v_dot8c_i32_i4_e32 v40, v124, v48
	v_dot8c_i32_i4_e32 v41, v124, v46
	v_dot8c_i32_i4_e32 v42, v126, v48
	v_dot8c_i32_i4_e32 v43, v126, v46
	v_dot8c_i32_i4_e32 v44, v128, v48
	v_dot8c_i32_i4_e32 v45, v128, v46
	v_dot8c_i32_i4_e32 v38, v123, v49
	v_dot8c_i32_i4_e32 v39, v123, v47
	v_dot8c_i32_i4_e32 v40, v125, v49
	v_dot8c_i32_i4_e32 v41, v125, v47
	v_dot8c_i32_i4_e32 v42, v127, v49
	v_dot8c_i32_i4_e32 v43, v127, v47
	v_dot8c_i32_i4_e32 v44, v129, v49
	v_dot8c_i32_i4_e32 v45, v129, v47
	s_waitcnt lgkmcnt(15)
; __device__ __forceinline__ void peer_v_tokens(int j, const LAS unsigned short* EL, const LAS unsigned char* AL  , const LAS float* ASC  , const LAS int* SAL  , ...
;     ...
;         for (int m = 0; m < 2; ++m) {
;             const int idx = lane + 64 * m, tau = idx >> 4, sr = idx & 15, k = 16 * (sr & 7) + 2 * tau + (sr >> 3);
;             const int aq = (int)*(const LAS signed char*)(AL + tl * 128 + k); const int tq = aq + 8;
;             const unsigned lo = (((unsigned)tq & 15u) ^ 8u) * 0x11111111u, hi = ((unsigned)(tq >> 4) & 15u) * 0x11111111u;
;             typedef unsigned u2v __attribute__((ext_vector_type(2)));
;             u2v l2; l2.x = lo; l2.y = lo; u2v h2; h2.x = hi; h2.y = hi;
;             *(LAS u2v*)(ATL + 8 * idx) = l2; *(LAS u2v*)(ATL + 1024 + 8 * idx) = h2;
;         }
;         const float asc = ASC[tl]; const int sa = SAL[tl];
;         CFENCE();
;         int accH[4], accL[4];
; #pragma unroll
;         for (int st = 0; st < 16; ++st) {
;             const int p = st >> 2, q = st & 3;
;             if (st < 14) VDMA(st + 2, (st + 2) % 3);
;             if (st < 14) asm volatile("s_waitcnt vmcnt(8)" ::: "memory");
;             else if (st == 14) asm volatile("s_waitcnt vmcnt(4)" ::: "memory");
;             else asm volatile("s_waitcnt vmcnt(0)" ::: "memory");
;             if (q == 0) {
; #pragma unroll
;                 for (int r = 0; r < 4; ++r) { accH[r] = 0; accL[r] = 0; } }
; #pragma unroll
;             for (int tp = 0; tp < 2; ++tp) {
;                 const v2i ao = TR4(ATL + (2 * q + tp) * 128 + 8 * s16), ah = TR4(ATL + 1024 + (2 * q + tp) * 128 + 8 * s16);
; #pragma unroll
;                 for (int r = 0; r < 4; ++r) {
;                     const v2i d = TR4(ldsb + BUF[st % 3] + 2048 * tp + roff[r]);
;                     accH[r] = __builtin_amdgcn_sdot8(d.x, ah.x, accH[r], false); accH[r] = __builtin_amdgcn_sdot8(d.y, ah.y, accH[r], false);
;                     accL[r] = __builtin_amdgcn_sdot8(d.x, ao.x, accL[r], false); accL[r] = __builtin_amdgcn_sdot8(d.y, ao.y, accL[r], false);
;                 }
;             }
;             asm volatile("s_waitcnt lgkmcnt(0)" ::: "memory");
;             if (q == 3) {
; #pragma unroll
;                 for (int r = 0; r < 4; ++r) STASH[256 * p + 16 * (grp + 4 * r) + pc] = f2bf(asc * (float)(2 * ((accH[r] << 4) + accL[r]) + sa));
;             }
;         }
	v_add_u32_e32 v143, 8, v139
	v_and_b32_e32 v142, 15, v143
	v_xor_b32_e32 v142, 8, v142
	v_bfe_u32 v144, v143, 4, 4
	v_mul_lo_u32 v142, v142, s92
	v_mul_lo_u32 v144, v144, s92
	v_mov_b32_e32 v143, v142
	v_mov_b32_e32 v145, v144
	ds_write2st64_b64 v159, v[142:143], v[144:145] offset1:2
	v_and_b32_e32 v78, 0xffff, v20
	v_lshrrev_b32_e32 v79, 16, v20
	v_lshl_add_u32 v78, v78, 7, v150
	v_lshl_add_u32 v79, v79, 7, v151
	s_mov_b32 m0, s76
	s_add_i32 s43, s76, 0x400
	global_load_lds_dwordx4 v78, s[50:51]
	s_mov_b32 m0, s43
	s_nop 0
	global_load_lds_dwordx4 v79, s[50:51]
	s_waitcnt vmcnt(8)
	v_add_u32_e32 v54, s78, v59
	v_add_u32_e32 v55, s78, v60
	v_add_u32_e32 v56, s78, v61
	v_add_u32_e32 v57, s78, v62
	ds_read_b64_tr_b4 v[46:47], v160 offset:768
	ds_read_b64_tr_b4 v[48:49], v160 offset:1792
	ds_read_b64_tr_b4 v[122:123], v54
	ds_read_b64_tr_b4 v[124:125], v55
	ds_read_b64_tr_b4 v[126:127], v56
	ds_read_b64_tr_b4 v[128:129], v57
	s_waitcnt lgkmcnt(7)
	v_dot8c_i32_i4_e32 v38, v130, v52
	v_dot8c_i32_i4_e32 v39, v130, v50
	v_dot8c_i32_i4_e32 v40, v132, v52
	v_dot8c_i32_i4_e32 v41, v132, v50
	v_dot8c_i32_i4_e32 v42, v134, v52
	v_dot8c_i32_i4_e32 v43, v134, v50
	v_dot8c_i32_i4_e32 v44, v136, v52
	v_dot8c_i32_i4_e32 v45, v136, v50
	v_dot8c_i32_i4_e32 v38, v131, v53
	v_dot8c_i32_i4_e32 v39, v131, v51
	v_dot8c_i32_i4_e32 v40, v133, v53
	v_dot8c_i32_i4_e32 v41, v133, v51
	v_dot8c_i32_i4_e32 v42, v135, v53
	v_dot8c_i32_i4_e32 v43, v135, v51
	v_dot8c_i32_i4_e32 v44, v137, v53
	v_dot8c_i32_i4_e32 v45, v137, v51
	v_and_b32_e32 v78, 0xffff, v21
	v_lshrrev_b32_e32 v79, 16, v21
	v_lshl_add_u32 v78, v78, 7, v150
	v_lshl_add_u32 v79, v79, 7, v151
	s_mov_b32 m0, s77
	s_add_i32 s43, s77, 0x400
	global_load_lds_dwordx4 v78, s[50:51]
	s_mov_b32 m0, s43
	s_nop 0
	global_load_lds_dwordx4 v79, s[50:51]
	s_waitcnt vmcnt(8)
	v_add_u32_e32 v54, s79, v59
	v_add_u32_e32 v55, s79, v60
	v_add_u32_e32 v56, s79, v61
	v_add_u32_e32 v57, s79, v62
	ds_read_b64_tr_b4 v[50:51], v160 offset:896
	ds_read_b64_tr_b4 v[52:53], v160 offset:1920
	ds_read_b64_tr_b4 v[130:131], v54
	ds_read_b64_tr_b4 v[132:133], v55
	ds_read_b64_tr_b4 v[134:135], v56
	ds_read_b64_tr_b4 v[136:137], v57
	s_waitcnt lgkmcnt(6)
	v_dot8c_i32_i4_e32 v38, v122, v48
	v_dot8c_i32_i4_e32 v39, v122, v46
	v_dot8c_i32_i4_e32 v40, v124, v48
	v_dot8c_i32_i4_e32 v41, v124, v46
	v_dot8c_i32_i4_e32 v42, v126, v48
	v_dot8c_i32_i4_e32 v43, v126, v46
	v_dot8c_i32_i4_e32 v44, v128, v48
	v_dot8c_i32_i4_e32 v45, v128, v46
	v_dot8c_i32_i4_e32 v38, v123, v49
	v_dot8c_i32_i4_e32 v39, v123, v47
	v_dot8c_i32_i4_e32 v40, v125, v49
	v_dot8c_i32_i4_e32 v41, v125, v47
	v_dot8c_i32_i4_e32 v42, v127, v49
	v_dot8c_i32_i4_e32 v43, v127, v47
	v_dot8c_i32_i4_e32 v44, v129, v49
	v_dot8c_i32_i4_e32 v45, v129, v47
	v_and_b32_e32 v78, 0xffff, v22
	v_lshrrev_b32_e32 v79, 16, v22
	v_lshl_add_u32 v78, v78, 7, v150
	v_lshl_add_u32 v79, v79, 7, v151
	s_mov_b32 m0, s78
	s_add_i32 s43, s78, 0x400
	global_load_lds_dwordx4 v78, s[50:51]
	s_mov_b32 m0, s43
	s_nop 0
	global_load_lds_dwordx4 v79, s[50:51]
	s_waitcnt vmcnt(8)
	v_add_u32_e32 v54, s98, v59
	v_add_u32_e32 v55, s98, v60
	v_add_u32_e32 v56, s98, v61
	v_add_u32_e32 v57, s98, v62
	ds_read_b64_tr_b4 v[46:47], v160
	ds_read_b64_tr_b4 v[48:49], v160 offset:1024
	ds_read_b64_tr_b4 v[122:123], v54
	ds_read_b64_tr_b4 v[124:125], v55
	ds_read_b64_tr_b4 v[126:127], v56
	ds_read_b64_tr_b4 v[128:129], v57
	s_waitcnt lgkmcnt(6)
	v_dot8c_i32_i4_e32 v38, v130, v52
	v_dot8c_i32_i4_e32 v39, v130, v50
	v_dot8c_i32_i4_e32 v40, v132, v52
	v_dot8c_i32_i4_e32 v41, v132, v50
	v_dot8c_i32_i4_e32 v42, v134, v52
	v_dot8c_i32_i4_e32 v43, v134, v50
	v_dot8c_i32_i4_e32 v44, v136, v52
	v_dot8c_i32_i4_e32 v45, v136, v50
	v_dot8c_i32_i4_e32 v38, v131, v53
	v_dot8c_i32_i4_e32 v39, v131, v51
	v_dot8c_i32_i4_e32 v40, v133, v53
	v_dot8c_i32_i4_e32 v41, v133, v51
	v_dot8c_i32_i4_e32 v42, v135, v53
	v_dot8c_i32_i4_e32 v43, v135, v51
	v_dot8c_i32_i4_e32 v44, v137, v53
	v_dot8c_i32_i4_e32 v45, v137, v51
	s_nop 3
	s_waitcnt lgkmcnt(15)
	v_lshlrev_b32_e32 v38, 5, v38
	v_lshlrev_b32_e32 v39, 1, v39
	v_add3_u32 v38, v39, v229, v38
	v_cvt_f32_i32_e32 v38, v38
	v_mul_f32_e32 v38, v228, v38
	v_lshlrev_b32_e32 v40, 5, v40
	v_lshlrev_b32_e32 v41, 1, v41
	v_add3_u32 v40, v41, v229, v40
	v_cvt_f32_i32_e32 v40, v40
	v_mul_f32_e32 v40, v228, v40
	v_lshlrev_b32_e32 v42, 5, v42
	v_lshlrev_b32_e32 v43, 1, v43
	v_add3_u32 v42, v43, v229, v42
	v_cvt_f32_i32_e32 v42, v42
	v_mul_f32_e32 v42, v228, v42
	v_lshlrev_b32_e32 v44, 5, v44
	v_lshlrev_b32_e32 v45, 1, v45
	v_add3_u32 v44, v45, v229, v44
	v_cvt_f32_i32_e32 v44, v44
	v_mul_f32_e32 v44, v228, v44
	v_cvt_pk_bf16_f32 v176, v38, v40
	v_cvt_pk_bf16_f32 v177, v42, v44
	v_add_u32_e32 v147, 8, v140
	v_and_b32_e32 v146, 15, v147
	v_xor_b32_e32 v146, 8, v146
	v_bfe_u32 v148, v147, 4, 4
	v_mul_lo_u32 v146, v146, s92
	v_mul_lo_u32 v148, v148, s92
	v_mov_b32_e32 v147, v146
	v_mov_b32_e32 v149, v148
	ds_write2st64_b64 v77, v[146:147], v[148:149] offset1:2
	v_add_u32_e32 v138, 0xc00, v74
	ds_read_u8 v139, v138
	v_add_u32_e32 v141, 0xc00, v73
	ds_read_u8 v140, v141
	s_add_i32 s43, s67, 64
	v_mov_b32_e32 v138, s43
	ds_read2st64_b32 v[228:229], v138 offset1:1
	ds_read_b128 v[26:29], v227 offset:6144
	ds_read_b128 v[30:33], v227 offset:6160
	v_mov_b32_e32 v38, 0
	v_mov_b32_e32 v39, 0
	v_mov_b32_e32 v40, 0
	v_mov_b32_e32 v41, 0
	v_mov_b32_e32 v42, 0
	v_mov_b32_e32 v43, 0
	v_mov_b32_e32 v44, 0
	v_mov_b32_e32 v45, 0
	v_and_b32_e32 v78, 0xffff, v23
	v_lshrrev_b32_e32 v79, 16, v23
	v_lshl_add_u32 v78, v78, 7, v150
	v_lshl_add_u32 v79, v79, 7, v151
	s_mov_b32 m0, s79
	s_add_i32 s43, s79, 0x400
	global_load_lds_dwordx4 v78, s[50:51]
	s_mov_b32 m0, s43
	s_nop 0
	global_load_lds_dwordx4 v79, s[50:51]
	s_waitcnt vmcnt(8)
; #define LAS __attribute__((address_space(3)))
; __device__ __forceinline__ bf16 f2bf(float f) { return (bf16)f2bfu(f); }
; #define TR4(p_) __builtin_amdgcn_ds_read_tr4_b64_v2i32((LAS v2i*)(p_))
; #define CFENCE() asm volatile("" ::: "memory")
; __device__ __forceinline__ void peer_v_tokens(int j, const LAS unsigned short* EL, const LAS unsigned char* AL  , const LAS float* ASC  , const LAS int* SAL  , ...
;     ...
;         for (int st = 0; st < 16; ++st) {
;             const int p = st >> 2, q = st & 3;
;             if (st < 14) VDMA(st + 2, (st + 2) % 3);
;             if (st < 14) asm volatile("s_waitcnt vmcnt(8)" ::: "memory");
;             else if (st == 14) asm volatile("s_waitcnt vmcnt(4)" ::: "memory");
;             else asm volatile("s_waitcnt vmcnt(0)" ::: "memory");
;             if (q == 0) {
; #pragma unroll
;                 for (int r = 0; r < 4; ++r) { accH[r] = 0; accL[r] = 0; } }
; #pragma unroll
;             for (int tp = 0; tp < 2; ++tp) {
;                 const v2i ao = TR4(ATL + (2 * q + tp) * 128 + 8 * s16), ah = TR4(ATL + 1024 + (2 * q + tp) * 128 + 8 * s16);
; #pragma unroll
;                 for (int r = 0; r < 4; ++r) {
;                     const v2i d = TR4(ldsb + BUF[st % 3] + 2048 * tp + roff[r]);
;                     accH[r] = __builtin_amdgcn_sdot8(d.x, ah.x, accH[r], false); accH[r] = __builtin_amdgcn_sdot8(d.y, ah.y, accH[r], false);
;                     accL[r] = __builtin_amdgcn_sdot8(d.x, ao.x, accL[r], false); accL[r] = __builtin_amdgcn_sdot8(d.y, ao.y, accL[r], false);
;                 }
;             }
;             asm volatile("s_waitcnt lgkmcnt(0)" ::: "memory");
;             if (q == 3) {
; #pragma unroll
;                 for (int r = 0; r < 4; ++r) STASH[256 * p + 16 * (grp + 4 * r) + pc] = f2bf(asc * (float)(2 * ((accH[r] << 4) + accL[r]) + sa));
;             }
;         }
;         CFENCE();
;         {
;             float4 v[4]; float ss = 0.f;
; #pragma unroll
;             for (int jq = 0; jq < 4; ++jq) { typedef unsigned u2v __attribute__((ext_vector_type(2))); const u2v pw = *(const LAS u2v*)(STASH + 4 * lane + 256 * jq); const uint2 hw = hv[jq];
	v_add_u32_e32 v54, s99, v59
	v_add_u32_e32 v55, s99, v60
	v_add_u32_e32 v56, s99, v61
	v_add_u32_e32 v57, s99, v62
	ds_read_b64_tr_b4 v[50:51], v160 offset:128
	ds_read_b64_tr_b4 v[52:53], v160 offset:1152
	ds_read_b64_tr_b4 v[130:131], v54
	ds_read_b64_tr_b4 v[132:133], v55
	ds_read_b64_tr_b4 v[134:135], v56
	ds_read_b64_tr_b4 v[136:137], v57
	s_waitcnt lgkmcnt(12)
	v_dot8c_i32_i4_e32 v38, v122, v48
	v_dot8c_i32_i4_e32 v39, v122, v46
	v_dot8c_i32_i4_e32 v40, v124, v48
	v_dot8c_i32_i4_e32 v41, v124, v46
	v_dot8c_i32_i4_e32 v42, v126, v48
	v_dot8c_i32_i4_e32 v43, v126, v46
	v_dot8c_i32_i4_e32 v44, v128, v48
	v_dot8c_i32_i4_e32 v45, v128, v46
	v_dot8c_i32_i4_e32 v38, v123, v49
	v_dot8c_i32_i4_e32 v39, v123, v47
	v_dot8c_i32_i4_e32 v40, v125, v49
	v_dot8c_i32_i4_e32 v41, v125, v47
	v_dot8c_i32_i4_e32 v42, v127, v49
	v_dot8c_i32_i4_e32 v43, v127, v47
	v_dot8c_i32_i4_e32 v44, v129, v49
	v_dot8c_i32_i4_e32 v45, v129, v47
	v_and_b32_e32 v78, 0xffff, v24
	v_lshrrev_b32_e32 v79, 16, v24
	v_lshl_add_u32 v78, v78, 7, v150
	v_lshl_add_u32 v79, v79, 7, v151
	s_mov_b32 m0, s98
	s_add_i32 s43, s98, 0x400
	global_load_lds_dwordx4 v78, s[50:51]
	s_mov_b32 m0, s43
	s_nop 0
	global_load_lds_dwordx4 v79, s[50:51]
	s_waitcnt vmcnt(8)
	v_add_u32_e32 v54, s76, v59
	v_add_u32_e32 v55, s76, v60
	v_add_u32_e32 v56, s76, v61
	v_add_u32_e32 v57, s76, v62
	ds_read_b64_tr_b4 v[46:47], v160 offset:256
	ds_read_b64_tr_b4 v[48:49], v160 offset:1280
	ds_read_b64_tr_b4 v[122:123], v54
	ds_read_b64_tr_b4 v[124:125], v55
	ds_read_b64_tr_b4 v[126:127], v56
	ds_read_b64_tr_b4 v[128:129], v57
	s_waitcnt lgkmcnt(6)
	v_dot8c_i32_i4_e32 v38, v130, v52
	v_dot8c_i32_i4_e32 v39, v130, v50
	v_dot8c_i32_i4_e32 v40, v132, v52
	v_dot8c_i32_i4_e32 v41, v132, v50
	v_dot8c_i32_i4_e32 v42, v134, v52
	v_dot8c_i32_i4_e32 v43, v134, v50
	v_dot8c_i32_i4_e32 v44, v136, v52
	v_dot8c_i32_i4_e32 v45, v136, v50
	v_dot8c_i32_i4_e32 v38, v131, v53
	v_dot8c_i32_i4_e32 v39, v131, v51
	v_dot8c_i32_i4_e32 v40, v133, v53
	v_dot8c_i32_i4_e32 v41, v133, v51
	v_dot8c_i32_i4_e32 v42, v135, v53
	v_dot8c_i32_i4_e32 v43, v135, v51
	v_dot8c_i32_i4_e32 v44, v137, v53
	v_dot8c_i32_i4_e32 v45, v137, v51
	ds_write_b16 v65, v162
	ds_write_b16_d16_hi v65, v162 offset:128
	ds_write_b16 v65, v163 offset:256
	ds_write_b16_d16_hi v65, v163 offset:384
	ds_write_b16 v65, v164 offset:512
	ds_write_b16_d16_hi v65, v164 offset:640
	ds_write_b16 v65, v165 offset:768
	ds_write_b16_d16_hi v65, v165 offset:896
	ds_write_b16 v65, v166 offset:1024
	ds_write_b16_d16_hi v65, v166 offset:1152
	ds_write_b16 v65, v167 offset:1280
	ds_write_b16_d16_hi v65, v167 offset:1408
	ds_write_b16 v65, v168 offset:1536
	ds_write_b16_d16_hi v65, v168 offset:1664
	ds_write_b16 v65, v169 offset:1792
	ds_write_b16_d16_hi v65, v169 offset:1920
	ds_read_b64 v[202:203], v154
	ds_read_b64 v[204:205], v154 offset:512
	ds_read_b64 v[206:207], v154 offset:1024
	ds_read_b64 v[208:209], v154 offset:1536
	v_and_b32_e32 v78, 0xffff, v25
	v_lshrrev_b32_e32 v79, 16, v25
	v_lshl_add_u32 v78, v78, 7, v150
	v_lshl_add_u32 v79, v79, 7, v151
	s_mov_b32 m0, s99
	s_add_i32 s43, s99, 0x400
	global_load_lds_dwordx4 v78, s[50:51]
	s_mov_b32 m0, s43
	s_nop 0
	global_load_lds_dwordx4 v79, s[50:51]
	s_waitcnt vmcnt(8)
	v_add_u32_e32 v54, s77, v59
	v_add_u32_e32 v55, s77, v60
	v_add_u32_e32 v56, s77, v61
	v_add_u32_e32 v57, s77, v62
	ds_read_b64_tr_b4 v[50:51], v160 offset:384
	ds_read_b64_tr_b4 v[52:53], v160 offset:1408
	ds_read_b64_tr_b4 v[130:131], v54
	ds_read_b64_tr_b4 v[132:133], v55
	ds_read_b64_tr_b4 v[134:135], v56
	ds_read_b64_tr_b4 v[136:137], v57
	s_waitcnt lgkmcnt(15)
	v_dot8c_i32_i4_e32 v38, v122, v48
	v_dot8c_i32_i4_e32 v39, v122, v46
	v_dot8c_i32_i4_e32 v40, v124, v48
	v_dot8c_i32_i4_e32 v41, v124, v46
	v_dot8c_i32_i4_e32 v42, v126, v48
	v_dot8c_i32_i4_e32 v43, v126, v46
	v_dot8c_i32_i4_e32 v44, v128, v48
	v_dot8c_i32_i4_e32 v45, v128, v46
	v_dot8c_i32_i4_e32 v38, v123, v49
	v_dot8c_i32_i4_e32 v39, v123, v47
	v_dot8c_i32_i4_e32 v40, v125, v49
	v_dot8c_i32_i4_e32 v41, v125, v47
	v_dot8c_i32_i4_e32 v42, v127, v49
	v_dot8c_i32_i4_e32 v43, v127, v47
	v_dot8c_i32_i4_e32 v44, v129, v49
	v_dot8c_i32_i4_e32 v45, v129, v47
	s_waitcnt lgkmcnt(15)
	v_and_b32_e32 v78, 0xffff, v26
	v_lshrrev_b32_e32 v79, 16, v26
	v_lshl_add_u32 v78, v78, 7, v150
	v_lshl_add_u32 v79, v79, 7, v151
	s_mov_b32 m0, s76
	s_add_i32 s43, s76, 0x400
	global_load_lds_dwordx4 v78, s[50:51]
	s_mov_b32 m0, s43
	s_nop 0
	global_load_lds_dwordx4 v79, s[50:51]
	s_waitcnt vmcnt(8)
	v_add_u32_e32 v54, s78, v59
	v_add_u32_e32 v55, s78, v60
	v_add_u32_e32 v56, s78, v61
	v_add_u32_e32 v57, s78, v62
	ds_read_b64_tr_b4 v[46:47], v160 offset:512
	ds_read_b64_tr_b4 v[48:49], v160 offset:1536
	ds_read_b64_tr_b4 v[122:123], v54
	ds_read_b64_tr_b4 v[124:125], v55
	ds_read_b64_tr_b4 v[126:127], v56
	ds_read_b64_tr_b4 v[128:129], v57
	s_waitcnt lgkmcnt(6)
	v_dot8c_i32_i4_e32 v38, v130, v52
	v_dot8c_i32_i4_e32 v39, v130, v50
	v_dot8c_i32_i4_e32 v40, v132, v52
	v_dot8c_i32_i4_e32 v41, v132, v50
	v_dot8c_i32_i4_e32 v42, v134, v52
	v_dot8c_i32_i4_e32 v43, v134, v50
	v_dot8c_i32_i4_e32 v44, v136, v52
	v_dot8c_i32_i4_e32 v45, v136, v50
	v_dot8c_i32_i4_e32 v38, v131, v53
	v_dot8c_i32_i4_e32 v39, v131, v51
	v_dot8c_i32_i4_e32 v40, v133, v53
	v_dot8c_i32_i4_e32 v41, v133, v51
	v_dot8c_i32_i4_e32 v42, v135, v53
	v_dot8c_i32_i4_e32 v43, v135, v51
	v_dot8c_i32_i4_e32 v44, v137, v53
	v_dot8c_i32_i4_e32 v45, v137, v51
	v_and_b32_e32 v78, 0xffff, v27
	v_lshrrev_b32_e32 v79, 16, v27
	v_lshl_add_u32 v78, v78, 7, v150
	v_lshl_add_u32 v79, v79, 7, v151
	s_mov_b32 m0, s77
	s_add_i32 s43, s77, 0x400
	global_load_lds_dwordx4 v78, s[50:51]
	s_mov_b32 m0, s43
	s_nop 0
	global_load_lds_dwordx4 v79, s[50:51]
	s_waitcnt vmcnt(8)
; #define TR4(p_) __builtin_amdgcn_ds_read_tr4_b64_v2i32((LAS v2i*)(p_))
; #define VDMA(st_, k_) do { _Pragma("unroll") for (int i_ = 0; i_ < 4; ++i_) { \
;         const unsigned off_ = (unsigned)((st_) >> 2) * (16384u * 128u) + (PE_ID(E, 4 * ((st_) & 3) + i_) << 7) + ((i_ & 1) ? cx1 : cx0); \
;         __builtin_amdgcn_global_load_lds((const unsigned*)(V4 + off_), (LAS unsigned*)(ldsb + BUF[k_] + 1024 * i_), 16, 0, 0); } } while (0)
; __device__ __forceinline__ void peer_v_tokens(int j, const LAS unsigned short* EL, const LAS unsigned char* AL  , const LAS float* ASC  , const LAS int* SAL  , ...
;     ...
;         for (int st = 0; st < 16; ++st) {
;             const int p = st >> 2, q = st & 3;
;             if (st < 14) VDMA(st + 2, (st + 2) % 3);
;             if (st < 14) asm volatile("s_waitcnt vmcnt(8)" ::: "memory");
;             else if (st == 14) asm volatile("s_waitcnt vmcnt(4)" ::: "memory");
;             else asm volatile("s_waitcnt vmcnt(0)" ::: "memory");
;             if (q == 0) {
; #pragma unroll
;                 for (int r = 0; r < 4; ++r) { accH[r] = 0; accL[r] = 0; } }
; #pragma unroll
;             for (int tp = 0; tp < 2; ++tp) {
;                 const v2i ao = TR4(ATL + (2 * q + tp) * 128 + 8 * s16), ah = TR4(ATL + 1024 + (2 * q + tp) * 128 + 8 * s16);
; #pragma unroll
;                 for (int r = 0; r < 4; ++r) {
;                     const v2i d = TR4(ldsb + BUF[st % 3] + 2048 * tp + roff[r]);
;                     accH[r] = __builtin_amdgcn_sdot8(d.x, ah.x, accH[r], false); accH[r] = __builtin_amdgcn_sdot8(d.y, ah.y, accH[r], false);
;                     accL[r] = __builtin_amdgcn_sdot8(d.x, ao.x, accL[r], false); accL[r] = __builtin_amdgcn_sdot8(d.y, ao.y, accL[r], false);
;                 }
;             }
;             asm volatile("s_waitcnt lgkmcnt(0)" ::: "memory");
	v_add_u32_e32 v54, s79, v59
	v_add_u32_e32 v55, s79, v60
	v_add_u32_e32 v56, s79, v61
	v_add_u32_e32 v57, s79, v62
	ds_read_b64_tr_b4 v[50:51], v160 offset:640
	ds_read_b64_tr_b4 v[52:53], v160 offset:1664
	ds_read_b64_tr_b4 v[130:131], v54
	ds_read_b64_tr_b4 v[132:133], v55
	ds_read_b64_tr_b4 v[134:135], v56
	ds_read_b64_tr_b4 v[136:137], v57
	s_waitcnt lgkmcnt(6)
	v_dot8c_i32_i4_e32 v38, v122, v48
	v_dot8c_i32_i4_e32 v39, v122, v46
	v_dot8c_i32_i4_e32 v40, v124, v48
	v_dot8c_i32_i4_e32 v41, v124, v46
	v_dot8c_i32_i4_e32 v42, v126, v48
	v_dot8c_i32_i4_e32 v43, v126, v46
	v_dot8c_i32_i4_e32 v44, v128, v48
	v_dot8c_i32_i4_e32 v45, v128, v46
	v_dot8c_i32_i4_e32 v38, v123, v49
	v_dot8c_i32_i4_e32 v39, v123, v47
	v_dot8c_i32_i4_e32 v40, v125, v49
	v_dot8c_i32_i4_e32 v41, v125, v47
	v_dot8c_i32_i4_e32 v42, v127, v49
	v_dot8c_i32_i4_e32 v43, v127, v47
	v_dot8c_i32_i4_e32 v44, v129, v49
	v_dot8c_i32_i4_e32 v45, v129, v47
	s_waitcnt lgkmcnt(15)
	v_add_u32_e32 v143, 8, v139
	v_and_b32_e32 v142, 15, v143
	v_xor_b32_e32 v142, 8, v142
	v_bfe_u32 v144, v143, 4, 4
	v_mul_lo_u32 v142, v142, s92
	v_mul_lo_u32 v144, v144, s92
	v_mov_b32_e32 v143, v142
	v_mov_b32_e32 v145, v144
	ds_write2st64_b64 v159, v[142:143], v[144:145] offset1:2
	v_and_b32_e32 v78, 0xffff, v28
	v_lshrrev_b32_e32 v79, 16, v28
	v_lshl_add_u32 v78, v78, 7, v150
	v_lshl_add_u32 v79, v79, 7, v151
	s_mov_b32 m0, s78
	s_add_i32 s43, s78, 0x400
	global_load_lds_dwordx4 v78, s[50:51]
	s_mov_b32 m0, s43
	s_nop 0
	global_load_lds_dwordx4 v79, s[50:51]
	s_waitcnt vmcnt(8)
	v_add_u32_e32 v54, s98, v59
	v_add_u32_e32 v55, s98, v60
	v_add_u32_e32 v56, s98, v61
	v_add_u32_e32 v57, s98, v62
	ds_read_b64_tr_b4 v[46:47], v160 offset:768
	ds_read_b64_tr_b4 v[48:49], v160 offset:1792
	ds_read_b64_tr_b4 v[122:123], v54
	ds_read_b64_tr_b4 v[124:125], v55
	ds_read_b64_tr_b4 v[126:127], v56
	ds_read_b64_tr_b4 v[128:129], v57
	s_waitcnt lgkmcnt(7)
	v_dot8c_i32_i4_e32 v38, v130, v52
	v_dot8c_i32_i4_e32 v39, v130, v50
	v_dot8c_i32_i4_e32 v40, v132, v52
	v_dot8c_i32_i4_e32 v41, v132, v50
	v_dot8c_i32_i4_e32 v42, v134, v52
	v_dot8c_i32_i4_e32 v43, v134, v50
	v_dot8c_i32_i4_e32 v44, v136, v52
	v_dot8c_i32_i4_e32 v45, v136, v50
	v_dot8c_i32_i4_e32 v38, v131, v53
	v_dot8c_i32_i4_e32 v39, v131, v51
	v_dot8c_i32_i4_e32 v40, v133, v53
	v_dot8c_i32_i4_e32 v41, v133, v51
	v_dot8c_i32_i4_e32 v42, v135, v53
	v_dot8c_i32_i4_e32 v43, v135, v51
	v_dot8c_i32_i4_e32 v44, v137, v53
	v_dot8c_i32_i4_e32 v45, v137, v51
	v_and_b32_e32 v78, 0xffff, v29
	v_lshrrev_b32_e32 v79, 16, v29
	v_lshl_add_u32 v78, v78, 7, v150
	v_lshl_add_u32 v79, v79, 7, v151
	s_mov_b32 m0, s79
	s_add_i32 s43, s79, 0x400
	global_load_lds_dwordx4 v78, s[50:51]
	s_mov_b32 m0, s43
	s_nop 0
	global_load_lds_dwordx4 v79, s[50:51]
	s_waitcnt vmcnt(8)
	v_add_u32_e32 v54, s99, v59
	v_add_u32_e32 v55, s99, v60
	v_add_u32_e32 v56, s99, v61
	v_add_u32_e32 v57, s99, v62
	ds_read_b64_tr_b4 v[50:51], v160 offset:896
	ds_read_b64_tr_b4 v[52:53], v160 offset:1920
	ds_read_b64_tr_b4 v[130:131], v54
	ds_read_b64_tr_b4 v[132:133], v55
	ds_read_b64_tr_b4 v[134:135], v56
	ds_read_b64_tr_b4 v[136:137], v57
	s_waitcnt lgkmcnt(6)
	v_dot8c_i32_i4_e32 v38, v122, v48
	v_dot8c_i32_i4_e32 v39, v122, v46
	v_dot8c_i32_i4_e32 v40, v124, v48
	v_dot8c_i32_i4_e32 v41, v124, v46
	v_dot8c_i32_i4_e32 v42, v126, v48
	v_dot8c_i32_i4_e32 v43, v126, v46
	v_dot8c_i32_i4_e32 v44, v128, v48
	v_dot8c_i32_i4_e32 v45, v128, v46
	v_dot8c_i32_i4_e32 v38, v123, v49
	v_dot8c_i32_i4_e32 v39, v123, v47
	v_dot8c_i32_i4_e32 v40, v125, v49
	v_dot8c_i32_i4_e32 v41, v125, v47
	v_dot8c_i32_i4_e32 v42, v127, v49
	v_dot8c_i32_i4_e32 v43, v127, v47
	v_dot8c_i32_i4_e32 v44, v129, v49
	v_dot8c_i32_i4_e32 v45, v129, v47
	v_and_b32_e32 v78, 0xffff, v30
	v_lshrrev_b32_e32 v79, 16, v30
	v_lshl_add_u32 v78, v78, 7, v150
	v_lshl_add_u32 v79, v79, 7, v151
	s_mov_b32 m0, s98
	s_add_i32 s43, s98, 0x400
	global_load_lds_dwordx4 v78, s[50:51]
	s_mov_b32 m0, s43
	s_nop 0
	global_load_lds_dwordx4 v79, s[50:51]
	s_waitcnt vmcnt(8)
	v_add_u32_e32 v54, s76, v59
	v_add_u32_e32 v55, s76, v60
	v_add_u32_e32 v56, s76, v61
	v_add_u32_e32 v57, s76, v62
	ds_read_b64_tr_b4 v[46:47], v160
	ds_read_b64_tr_b4 v[48:49], v160 offset:1024
	ds_read_b64_tr_b4 v[122:123], v54
	ds_read_b64_tr_b4 v[124:125], v55
	ds_read_b64_tr_b4 v[126:127], v56
	ds_read_b64_tr_b4 v[128:129], v57
	s_waitcnt lgkmcnt(6)
	v_dot8c_i32_i4_e32 v38, v130, v52
	v_dot8c_i32_i4_e32 v39, v130, v50
	v_dot8c_i32_i4_e32 v40, v132, v52
	v_dot8c_i32_i4_e32 v41, v132, v50
	v_dot8c_i32_i4_e32 v42, v134, v52
	v_dot8c_i32_i4_e32 v43, v134, v50
	v_dot8c_i32_i4_e32 v44, v136, v52
	v_dot8c_i32_i4_e32 v45, v136, v50
	v_dot8c_i32_i4_e32 v38, v131, v53
	v_dot8c_i32_i4_e32 v39, v131, v51
	v_dot8c_i32_i4_e32 v40, v133, v53
	v_dot8c_i32_i4_e32 v41, v133, v51
	v_dot8c_i32_i4_e32 v42, v135, v53
	v_dot8c_i32_i4_e32 v43, v135, v51
	v_dot8c_i32_i4_e32 v44, v137, v53
	v_dot8c_i32_i4_e32 v45, v137, v51
	s_nop 3
	s_waitcnt lgkmcnt(15)
; #define LAS __attribute__((address_space(3)))
; __device__ __forceinline__ bf16 f2bf(float f) { return (bf16)f2bfu(f); }
; __device__ __forceinline__ void peer_v_tokens(int j, const LAS unsigned short* EL, const LAS unsigned char* AL  , const LAS float* ASC  , const LAS int* SAL  , ...
;     ...
;             if (q == 3) {
; #pragma unroll
;                 for (int r = 0; r < 4; ++r) STASH[256 * p + 16 * (grp + 4 * r) + pc] = f2bf(asc * (float)(2 * ((accH[r] << 4) + accL[r]) + sa));
;             }
;         }
;     ...
;         {
;             float4 v[4]; float ss = 0.f;
; #pragma unroll
;             for (int jq = 0; jq < 4; ++jq) { typedef unsigned u2v __attribute__((ext_vector_type(2))); const u2v pw = *(const LAS u2v*)(STASH + 4 * lane + 256 * jq); const uint2 hw = hv[jq];
;                 v[jq] = make_float4(__uint_as_float(hw.x << 16) + __uint_as_float(pw.x << 16), __uint_as_float(hw.x & 0xffff0000u) + __uint_as_float(pw.x & 0xffff0000u),
;                                     __uint_as_float(hw.y << 16) + __uint_as_float(pw.y << 16), __uint_as_float(hw.y & 0xffff0000u) + __uint_as_float(pw.y & 0xffff0000u));
;                 ss += v[jq].x * v[jq].x + v[jq].y * v[jq].y + v[jq].z * v[jq].z + v[jq].w * v[jq].w; }
;             ss = wave_sum(ss);
;             const float r3 = rsqrtf(ss * (1.f / D) + EPS);
	v_lshlrev_b32_e32 v38, 5, v38
	v_lshlrev_b32_e32 v39, 1, v39
	v_add3_u32 v38, v39, v229, v38
	v_cvt_f32_i32_e32 v38, v38
	v_mul_f32_e32 v38, v228, v38
	v_lshlrev_b32_e32 v40, 5, v40
	v_lshlrev_b32_e32 v41, 1, v41
	v_add3_u32 v40, v41, v229, v40
	v_cvt_f32_i32_e32 v40, v40
	v_mul_f32_e32 v40, v228, v40
	v_lshlrev_b32_e32 v42, 5, v42
	v_lshlrev_b32_e32 v43, 1, v43
	v_add3_u32 v42, v43, v229, v42
	v_cvt_f32_i32_e32 v42, v42
	v_mul_f32_e32 v42, v228, v42
	v_lshlrev_b32_e32 v44, 5, v44
	v_lshlrev_b32_e32 v45, 1, v45
	v_add3_u32 v44, v45, v229, v44
	v_cvt_f32_i32_e32 v44, v44
	v_mul_f32_e32 v44, v228, v44
	v_cvt_pk_bf16_f32 v178, v38, v40
	v_cvt_pk_bf16_f32 v179, v42, v44
	v_add_u32_e32 v147, 8, v140
	v_and_b32_e32 v146, 15, v147
	v_xor_b32_e32 v146, 8, v146
	v_bfe_u32 v148, v147, 4, 4
	v_mul_lo_u32 v146, v146, s92
	v_mul_lo_u32 v148, v148, s92
	v_mov_b32_e32 v147, v146
	v_mov_b32_e32 v149, v148
	ds_write2st64_b64 v77, v[146:147], v[148:149] offset1:2
	v_add_u32_e32 v138, 0x800, v74
	ds_read_u8 v139, v138
	v_add_u32_e32 v141, 0x800, v73
	ds_read_u8 v140, v141
	s_add_i32 s43, s67, 96
	v_mov_b32_e32 v138, s43
	ds_read2st64_b32 v[228:229], v138 offset1:1
	ds_read_b128 v[18:21], v227 offset:4096
	ds_read_b128 v[22:25], v227 offset:4112
	v_add_u32_e32 v152, 0x200000, v63
	v_add_u32_e32 v153, 0x200000, v64
	v_mov_b32_e32 v38, 0
	v_mov_b32_e32 v39, 0
	v_mov_b32_e32 v40, 0
	v_mov_b32_e32 v41, 0
	v_mov_b32_e32 v42, 0
	v_mov_b32_e32 v43, 0
	v_mov_b32_e32 v44, 0
	v_mov_b32_e32 v45, 0
	v_and_b32_e32 v78, 0xffff, v31
	v_lshrrev_b32_e32 v79, 16, v31
	v_lshl_add_u32 v78, v78, 7, v150
	v_lshl_add_u32 v79, v79, 7, v151
	s_mov_b32 m0, s99
	s_add_i32 s43, s99, 0x400
	global_load_lds_dwordx4 v78, s[50:51]
	s_mov_b32 m0, s43
	s_nop 0
	global_load_lds_dwordx4 v79, s[50:51]
	s_waitcnt vmcnt(8)
	v_add_u32_e32 v54, s77, v59
	v_add_u32_e32 v55, s77, v60
	v_add_u32_e32 v56, s77, v61
	v_add_u32_e32 v57, s77, v62
	ds_read_b64_tr_b4 v[50:51], v160 offset:128
	ds_read_b64_tr_b4 v[52:53], v160 offset:1152
	ds_read_b64_tr_b4 v[130:131], v54
	ds_read_b64_tr_b4 v[132:133], v55
	ds_read_b64_tr_b4 v[134:135], v56
	ds_read_b64_tr_b4 v[136:137], v57
	s_waitcnt lgkmcnt(12)
	s_waitcnt vmcnt(34) lgkmcnt(15)
	v_lshlrev_b32_e32 v210, 16, v194
	v_and_b32_e32 v211, 0xffff0000, v194
	v_lshlrev_b32_e32 v142, 16, v202
	v_and_b32_e32 v143, 0xffff0000, v202
	v_add_f32_e32 v210, v210, v142
	v_add_f32_e32 v211, v211, v143
	v_lshlrev_b32_e32 v212, 16, v195
	v_and_b32_e32 v213, 0xffff0000, v195
	v_lshlrev_b32_e32 v142, 16, v203
	v_and_b32_e32 v143, 0xffff0000, v203
	v_add_f32_e32 v212, v212, v142
	v_add_f32_e32 v213, v213, v143
	v_lshlrev_b32_e32 v214, 16, v196
	v_and_b32_e32 v215, 0xffff0000, v196
	v_lshlrev_b32_e32 v142, 16, v204
	v_and_b32_e32 v143, 0xffff0000, v204
	v_add_f32_e32 v214, v214, v142
	v_add_f32_e32 v215, v215, v143
	v_lshlrev_b32_e32 v216, 16, v197
	v_and_b32_e32 v217, 0xffff0000, v197
	v_lshlrev_b32_e32 v142, 16, v205
	v_and_b32_e32 v143, 0xffff0000, v205
	v_add_f32_e32 v216, v216, v142
	v_add_f32_e32 v217, v217, v143
	v_lshlrev_b32_e32 v218, 16, v198
	v_and_b32_e32 v219, 0xffff0000, v198
	v_lshlrev_b32_e32 v142, 16, v206
	v_and_b32_e32 v143, 0xffff0000, v206
	v_add_f32_e32 v218, v218, v142
	v_add_f32_e32 v219, v219, v143
	v_lshlrev_b32_e32 v220, 16, v199
	v_and_b32_e32 v221, 0xffff0000, v199
	v_lshlrev_b32_e32 v142, 16, v207
	v_and_b32_e32 v143, 0xffff0000, v207
	v_add_f32_e32 v220, v220, v142
	v_add_f32_e32 v221, v221, v143
	v_lshlrev_b32_e32 v222, 16, v200
	v_and_b32_e32 v223, 0xffff0000, v200
	v_lshlrev_b32_e32 v142, 16, v208
	v_and_b32_e32 v143, 0xffff0000, v208
	v_add_f32_e32 v222, v222, v142
	v_add_f32_e32 v223, v223, v143
	v_lshlrev_b32_e32 v224, 16, v201
	v_and_b32_e32 v225, 0xffff0000, v201
	v_lshlrev_b32_e32 v142, 16, v209
	v_and_b32_e32 v143, 0xffff0000, v209
	v_add_f32_e32 v224, v224, v142
	v_add_f32_e32 v225, v225, v143
	v_mov_b32_e32 v144, 0
	v_mul_f32_e32 v145, v210, v210
	v_fmac_f32_e32 v145, v211, v211
	v_fmac_f32_e32 v145, v212, v212
	v_fmac_f32_e32 v145, v213, v213
	v_add_f32_e32 v144, v144, v145
	v_mul_f32_e32 v145, v214, v214
	v_fmac_f32_e32 v145, v215, v215
	v_fmac_f32_e32 v145, v216, v216
	v_fmac_f32_e32 v145, v217, v217
	v_add_f32_e32 v144, v144, v145
	v_mul_f32_e32 v145, v218, v218
	v_fmac_f32_e32 v145, v219, v219
	v_fmac_f32_e32 v145, v220, v220
	v_fmac_f32_e32 v145, v221, v221
	v_add_f32_e32 v144, v144, v145
	v_mul_f32_e32 v145, v222, v222
	v_fmac_f32_e32 v145, v223, v223
	v_fmac_f32_e32 v145, v224, v224
	v_fmac_f32_e32 v145, v225, v225
	v_add_f32_e32 v144, v144, v145
	s_nop 1
	v_add_f32_dpp v144, v144, v144 quad_perm:[1,0,3,2] row_mask:0xf bank_mask:0xf bound_ctrl:1
	s_nop 1
	v_add_f32_dpp v144, v144, v144 quad_perm:[2,3,0,1] row_mask:0xf bank_mask:0xf bound_ctrl:1
	s_nop 1
	v_add_f32_dpp v144, v144, v144 row_half_mirror row_mask:0xf bank_mask:0xf bound_ctrl:1
	s_nop 1
	v_add_f32_dpp v144, v144, v144 row_mirror row_mask:0xf bank_mask:0xf bound_ctrl:1
	s_nop 1
	v_readlane_b32 s10, v144, 0
	v_readlane_b32 s11, v144, 16
	v_readlane_b32 s14, v144, 32
	v_readlane_b32 s15, v144, 48
	s_nop 3
	v_mov_b32_e32 v144, s11
	v_mov_b32_e32 v145, s15
	v_add_f32_e32 v144, s10, v144
	v_add_f32_e32 v145, s14, v145
	v_add_f32_e32 v144, v144, v145
	v_fmamk_f32 v144, v144, 0x3a800000, v111
	v_rsq_f32_e32 v144, v144
	s_nop 0
	v_mul_f32_e32 v210, v210, v144
	v_mul_f32_e32 v211, v211, v144
	v_mul_f32_e32 v212, v212, v144
	v_mul_f32_e32 v213, v213, v144
	v_mul_f32_e32 v214, v214, v144
	v_mul_f32_e32 v215, v215, v144
	v_mul_f32_e32 v216, v216, v144
	v_mul_f32_e32 v217, v217, v144
	v_mul_f32_e32 v218, v218, v144
	v_mul_f32_e32 v219, v219, v144
	v_mul_f32_e32 v220, v220, v144
	v_mul_f32_e32 v221, v221, v144
	v_mul_f32_e32 v222, v222, v144
	v_mul_f32_e32 v223, v223, v144
	v_mul_f32_e32 v224, v224, v144
	v_mul_f32_e32 v225, v225, v144
	v_dot8c_i32_i4_e32 v38, v122, v48
	v_dot8c_i32_i4_e32 v39, v122, v46
	v_dot8c_i32_i4_e32 v40, v124, v48
	v_dot8c_i32_i4_e32 v41, v124, v46
	v_dot8c_i32_i4_e32 v42, v126, v48
	v_dot8c_i32_i4_e32 v43, v126, v46
	v_dot8c_i32_i4_e32 v44, v128, v48
	v_dot8c_i32_i4_e32 v45, v128, v46
	v_dot8c_i32_i4_e32 v38, v123, v49
	v_dot8c_i32_i4_e32 v39, v123, v47
	v_dot8c_i32_i4_e32 v40, v125, v49
	v_dot8c_i32_i4_e32 v41, v125, v47
	v_dot8c_i32_i4_e32 v42, v127, v49
	v_dot8c_i32_i4_e32 v43, v127, v47
	v_dot8c_i32_i4_e32 v44, v129, v49
	v_dot8c_i32_i4_e32 v45, v129, v47
	v_and_b32_e32 v78, 0xffff, v32
	v_lshrrev_b32_e32 v79, 16, v32
	v_lshl_add_u32 v78, v78, 7, v150
	v_lshl_add_u32 v79, v79, 7, v151
	s_mov_b32 m0, s76
	s_add_i32 s43, s76, 0x400
	global_load_lds_dwordx4 v78, s[50:51]
	s_mov_b32 m0, s43
	s_nop 0
	global_load_lds_dwordx4 v79, s[50:51]
	s_waitcnt vmcnt(8)
; #define TR4(p_) __builtin_amdgcn_ds_read_tr4_b64_v2i32((LAS v2i*)(p_))
; #define VDMA(st_, k_) do { _Pragma("unroll") for (int i_ = 0; i_ < 4; ++i_) { \
;         const unsigned off_ = (unsigned)((st_) >> 2) * (16384u * 128u) + (PE_ID(E, 4 * ((st_) & 3) + i_) << 7) + ((i_ & 1) ? cx1 : cx0); \
;         __builtin_amdgcn_global_load_lds((const unsigned*)(V4 + off_), (LAS unsigned*)(ldsb + BUF[k_] + 1024 * i_), 16, 0, 0); } } while (0)
; __device__ __forceinline__ void peer_v_tokens(int j, const LAS unsigned short* EL, const LAS unsigned char* AL  , const LAS float* ASC  , const LAS int* SAL  , ...
;     ...
;         for (int st = 0; st < 16; ++st) {
;             const int p = st >> 2, q = st & 3;
;             if (st < 14) VDMA(st + 2, (st + 2) % 3);
;             if (st < 14) asm volatile("s_waitcnt vmcnt(8)" ::: "memory");
;             else if (st == 14) asm volatile("s_waitcnt vmcnt(4)" ::: "memory");
;             else asm volatile("s_waitcnt vmcnt(0)" ::: "memory");
;             if (q == 0) {
; #pragma unroll
;                 for (int r = 0; r < 4; ++r) { accH[r] = 0; accL[r] = 0; } }
; #pragma unroll
;             for (int tp = 0; tp < 2; ++tp) {
;                 const v2i ao = TR4(ATL + (2 * q + tp) * 128 + 8 * s16), ah = TR4(ATL + 1024 + (2 * q + tp) * 128 + 8 * s16);
; #pragma unroll
;                 for (int r = 0; r < 4; ++r) {
;                     const v2i d = TR4(ldsb + BUF[st % 3] + 2048 * tp + roff[r]);
;                     accH[r] = __builtin_amdgcn_sdot8(d.x, ah.x, accH[r], false); accH[r] = __builtin_amdgcn_sdot8(d.y, ah.y, accH[r], false);
;                     accL[r] = __builtin_amdgcn_sdot8(d.x, ao.x, accL[r], false); accL[r] = __builtin_amdgcn_sdot8(d.y, ao.y, accL[r], false);
;                 }
;             }
;             asm volatile("s_waitcnt lgkmcnt(0)" ::: "memory");
	v_add_u32_e32 v54, s78, v59
	v_add_u32_e32 v55, s78, v60
	v_add_u32_e32 v56, s78, v61
	v_add_u32_e32 v57, s78, v62
	ds_read_b64_tr_b4 v[46:47], v160 offset:256
	ds_read_b64_tr_b4 v[48:49], v160 offset:1280
	ds_read_b64_tr_b4 v[122:123], v54
	ds_read_b64_tr_b4 v[124:125], v55
	ds_read_b64_tr_b4 v[126:127], v56
	ds_read_b64_tr_b4 v[128:129], v57
	s_waitcnt lgkmcnt(6)
	v_dot8c_i32_i4_e32 v38, v130, v52
	v_dot8c_i32_i4_e32 v39, v130, v50
	v_dot8c_i32_i4_e32 v40, v132, v52
	v_dot8c_i32_i4_e32 v41, v132, v50
	v_dot8c_i32_i4_e32 v42, v134, v52
	v_dot8c_i32_i4_e32 v43, v134, v50
	v_dot8c_i32_i4_e32 v44, v136, v52
	v_dot8c_i32_i4_e32 v45, v136, v50
	v_dot8c_i32_i4_e32 v38, v131, v53
	v_dot8c_i32_i4_e32 v39, v131, v51
	v_dot8c_i32_i4_e32 v40, v133, v53
	v_dot8c_i32_i4_e32 v41, v133, v51
	v_dot8c_i32_i4_e32 v42, v135, v53
	v_dot8c_i32_i4_e32 v43, v135, v51
	v_dot8c_i32_i4_e32 v44, v137, v53
	v_dot8c_i32_i4_e32 v45, v137, v51
	v_and_b32_e32 v78, 0xffff, v33
	v_lshrrev_b32_e32 v79, 16, v33
	v_lshl_add_u32 v78, v78, 7, v150
	v_lshl_add_u32 v79, v79, 7, v151
	s_mov_b32 m0, s77
	s_add_i32 s43, s77, 0x400
	global_load_lds_dwordx4 v78, s[50:51]
	s_mov_b32 m0, s43
	s_nop 0
	global_load_lds_dwordx4 v79, s[50:51]
	s_waitcnt vmcnt(8)
	v_add_u32_e32 v54, s79, v59
	v_add_u32_e32 v55, s79, v60
	v_add_u32_e32 v56, s79, v61
	v_add_u32_e32 v57, s79, v62
	ds_read_b64_tr_b4 v[50:51], v160 offset:384
	ds_read_b64_tr_b4 v[52:53], v160 offset:1408
	ds_read_b64_tr_b4 v[130:131], v54
	ds_read_b64_tr_b4 v[132:133], v55
	ds_read_b64_tr_b4 v[134:135], v56
	ds_read_b64_tr_b4 v[136:137], v57
	s_waitcnt lgkmcnt(6)
	v_dot8c_i32_i4_e32 v38, v122, v48
	v_dot8c_i32_i4_e32 v39, v122, v46
	v_dot8c_i32_i4_e32 v40, v124, v48
	v_dot8c_i32_i4_e32 v41, v124, v46
	v_dot8c_i32_i4_e32 v42, v126, v48
	v_dot8c_i32_i4_e32 v43, v126, v46
	v_dot8c_i32_i4_e32 v44, v128, v48
	v_dot8c_i32_i4_e32 v45, v128, v46
	v_dot8c_i32_i4_e32 v38, v123, v49
	v_dot8c_i32_i4_e32 v39, v123, v47
	v_dot8c_i32_i4_e32 v40, v125, v49
	v_dot8c_i32_i4_e32 v41, v125, v47
	v_dot8c_i32_i4_e32 v42, v127, v49
	v_dot8c_i32_i4_e32 v43, v127, v47
	v_dot8c_i32_i4_e32 v44, v129, v49
	v_dot8c_i32_i4_e32 v45, v129, v47
	s_waitcnt lgkmcnt(15)
	v_and_b32_e32 v78, 0xffff, v18
	v_lshrrev_b32_e32 v79, 16, v18
	v_lshl_add_u32 v78, v78, 7, v152
	v_lshl_add_u32 v79, v79, 7, v153
	s_mov_b32 m0, s78
	s_add_i32 s43, s78, 0x400
	global_load_lds_dwordx4 v78, s[50:51]
	s_mov_b32 m0, s43
	s_nop 0
	global_load_lds_dwordx4 v79, s[50:51]
	s_waitcnt vmcnt(8)
	v_add_u32_e32 v54, s98, v59
	v_add_u32_e32 v55, s98, v60
	v_add_u32_e32 v56, s98, v61
	v_add_u32_e32 v57, s98, v62
	ds_read_b64_tr_b4 v[46:47], v160 offset:512
	ds_read_b64_tr_b4 v[48:49], v160 offset:1536
	ds_read_b64_tr_b4 v[122:123], v54
	ds_read_b64_tr_b4 v[124:125], v55
	ds_read_b64_tr_b4 v[126:127], v56
	ds_read_b64_tr_b4 v[128:129], v57
	s_waitcnt lgkmcnt(6)
	v_dot8c_i32_i4_e32 v38, v130, v52
	v_dot8c_i32_i4_e32 v39, v130, v50
	v_dot8c_i32_i4_e32 v40, v132, v52
	v_dot8c_i32_i4_e32 v41, v132, v50
	v_dot8c_i32_i4_e32 v42, v134, v52
	v_dot8c_i32_i4_e32 v43, v134, v50
	v_dot8c_i32_i4_e32 v44, v136, v52
	v_dot8c_i32_i4_e32 v45, v136, v50
	v_dot8c_i32_i4_e32 v38, v131, v53
	v_dot8c_i32_i4_e32 v39, v131, v51
	v_dot8c_i32_i4_e32 v40, v133, v53
	v_dot8c_i32_i4_e32 v41, v133, v51
	v_dot8c_i32_i4_e32 v42, v135, v53
	v_dot8c_i32_i4_e32 v43, v135, v51
	v_dot8c_i32_i4_e32 v44, v137, v53
	v_dot8c_i32_i4_e32 v45, v137, v51
	v_and_b32_e32 v78, 0xffff, v19
	v_lshrrev_b32_e32 v79, 16, v19
	v_lshl_add_u32 v78, v78, 7, v152
	v_lshl_add_u32 v79, v79, 7, v153
	s_mov_b32 m0, s79
	s_add_i32 s43, s79, 0x400
	global_load_lds_dwordx4 v78, s[50:51]
	s_mov_b32 m0, s43
	s_nop 0
	global_load_lds_dwordx4 v79, s[50:51]
	s_waitcnt vmcnt(8)
	v_add_u32_e32 v54, s99, v59
	v_add_u32_e32 v55, s99, v60
	v_add_u32_e32 v56, s99, v61
	v_add_u32_e32 v57, s99, v62
	ds_read_b64_tr_b4 v[50:51], v160 offset:640
	ds_read_b64_tr_b4 v[52:53], v160 offset:1664
	ds_read_b64_tr_b4 v[130:131], v54
	ds_read_b64_tr_b4 v[132:133], v55
	ds_read_b64_tr_b4 v[134:135], v56
	ds_read_b64_tr_b4 v[136:137], v57
	s_waitcnt lgkmcnt(6)
	v_dot8c_i32_i4_e32 v38, v122, v48
	v_dot8c_i32_i4_e32 v39, v122, v46
	v_dot8c_i32_i4_e32 v40, v124, v48
	v_dot8c_i32_i4_e32 v41, v124, v46
	v_dot8c_i32_i4_e32 v42, v126, v48
	v_dot8c_i32_i4_e32 v43, v126, v46
	v_dot8c_i32_i4_e32 v44, v128, v48
	v_dot8c_i32_i4_e32 v45, v128, v46
	v_dot8c_i32_i4_e32 v38, v123, v49
	v_dot8c_i32_i4_e32 v39, v123, v47
	v_dot8c_i32_i4_e32 v40, v125, v49
	v_dot8c_i32_i4_e32 v41, v125, v47
	v_dot8c_i32_i4_e32 v42, v127, v49
	v_dot8c_i32_i4_e32 v43, v127, v47
	v_dot8c_i32_i4_e32 v44, v129, v49
	v_dot8c_i32_i4_e32 v45, v129, v47
	s_waitcnt lgkmcnt(15)
	v_add_u32_e32 v143, 8, v139
	v_and_b32_e32 v142, 15, v143
	v_xor_b32_e32 v142, 8, v142
	v_bfe_u32 v144, v143, 4, 4
	v_mul_lo_u32 v142, v142, s92
	v_mul_lo_u32 v144, v144, s92
	v_mov_b32_e32 v143, v142
	v_mov_b32_e32 v145, v144
	ds_write2st64_b64 v159, v[142:143], v[144:145] offset1:2
	v_and_b32_e32 v78, 0xffff, v20
	v_lshrrev_b32_e32 v79, 16, v20
	v_lshl_add_u32 v78, v78, 7, v152
	v_lshl_add_u32 v79, v79, 7, v153
	s_mov_b32 m0, s98
	s_add_i32 s43, s98, 0x400
	global_load_lds_dwordx4 v78, s[50:51]
	s_mov_b32 m0, s43
	s_nop 0
	global_load_lds_dwordx4 v79, s[50:51]
	s_waitcnt vmcnt(8)
	v_add_u32_e32 v54, s76, v59
	v_add_u32_e32 v55, s76, v60
	v_add_u32_e32 v56, s76, v61
	v_add_u32_e32 v57, s76, v62
	ds_read_b64_tr_b4 v[46:47], v160 offset:768
	ds_read_b64_tr_b4 v[48:49], v160 offset:1792
	ds_read_b64_tr_b4 v[122:123], v54
	ds_read_b64_tr_b4 v[124:125], v55
	ds_read_b64_tr_b4 v[126:127], v56
	ds_read_b64_tr_b4 v[128:129], v57
	s_waitcnt lgkmcnt(7)
; __device__ __forceinline__ void peer_v_tokens(int j, const LAS unsigned short* EL, const LAS unsigned char* AL  , const LAS float* ASC  , const LAS int* SAL  , ...
;     ...
;         for (int st = 0; st < 16; ++st) {
;             const int p = st >> 2, q = st & 3;
;             if (st < 14) VDMA(st + 2, (st + 2) % 3);
;             if (st < 14) asm volatile("s_waitcnt vmcnt(8)" ::: "memory");
;             else if (st == 14) asm volatile("s_waitcnt vmcnt(4)" ::: "memory");
;             else asm volatile("s_waitcnt vmcnt(0)" ::: "memory");
;             if (q == 0) {
; #pragma unroll
;                 for (int r = 0; r < 4; ++r) { accH[r] = 0; accL[r] = 0; } }
; #pragma unroll
;             for (int tp = 0; tp < 2; ++tp) {
;                 const v2i ao = TR4(ATL + (2 * q + tp) * 128 + 8 * s16), ah = TR4(ATL + 1024 + (2 * q + tp) * 128 + 8 * s16);
; #pragma unroll
;                 for (int r = 0; r < 4; ++r) {
;                     const v2i d = TR4(ldsb + BUF[st % 3] + 2048 * tp + roff[r]);
;                     accH[r] = __builtin_amdgcn_sdot8(d.x, ah.x, accH[r], false); accH[r] = __builtin_amdgcn_sdot8(d.y, ah.y, accH[r], false);
;                     accL[r] = __builtin_amdgcn_sdot8(d.x, ao.x, accL[r], false); accL[r] = __builtin_amdgcn_sdot8(d.y, ao.y, accL[r], false);
;                 }
;             }
;             asm volatile("s_waitcnt lgkmcnt(0)" ::: "memory");
;             if (q == 3) {
; #pragma unroll
;                 for (int r = 0; r < 4; ++r) STASH[256 * p + 16 * (grp + 4 * r) + pc] = f2bf(asc * (float)(2 * ((accH[r] << 4) + accL[r]) + sa));
;             }
;         }
;         CFENCE();
;         {
;             float4 v[4]; float ss = 0.f;
; #pragma unroll
;             for (int jq = 0; jq < 4; ++jq) { typedef unsigned u2v __attribute__((ext_vector_type(2))); const u2v pw = *(const LAS u2v*)(STASH + 4 * lane + 256 * jq); const uint2 hw = hv[jq];
;                 v[jq] = make_float4(__uint_as_float(hw.x << 16) + __uint_as_float(pw.x << 16), __uint_as_float(hw.x & 0xffff0000u) + __uint_as_float(pw.x & 0xffff0000u),
;                                     __uint_as_float(hw.y << 16) + __uint_as_float(pw.y << 16), __uint_as_float(hw.y & 0xffff0000u) + __uint_as_float(pw.y & 0xffff0000u));
;                 ss += v[jq].x * v[jq].x + v[jq].y * v[jq].y + v[jq].z * v[jq].z + v[jq].w * v[jq].w; }
;             ss = wave_sum(ss);
	v_dot8c_i32_i4_e32 v38, v130, v52
	v_dot8c_i32_i4_e32 v39, v130, v50
	v_dot8c_i32_i4_e32 v40, v132, v52
	v_dot8c_i32_i4_e32 v41, v132, v50
	v_dot8c_i32_i4_e32 v42, v134, v52
	v_dot8c_i32_i4_e32 v43, v134, v50
	v_dot8c_i32_i4_e32 v44, v136, v52
	v_dot8c_i32_i4_e32 v45, v136, v50
	v_dot8c_i32_i4_e32 v38, v131, v53
	v_dot8c_i32_i4_e32 v39, v131, v51
	v_dot8c_i32_i4_e32 v40, v133, v53
	v_dot8c_i32_i4_e32 v41, v133, v51
	v_dot8c_i32_i4_e32 v42, v135, v53
	v_dot8c_i32_i4_e32 v43, v135, v51
	v_dot8c_i32_i4_e32 v44, v137, v53
	v_dot8c_i32_i4_e32 v45, v137, v51
	v_and_b32_e32 v78, 0xffff, v21
	v_lshrrev_b32_e32 v79, 16, v21
	v_lshl_add_u32 v78, v78, 7, v152
	v_lshl_add_u32 v79, v79, 7, v153
	s_mov_b32 m0, s99
	s_add_i32 s43, s99, 0x400
	global_load_lds_dwordx4 v78, s[50:51]
	s_mov_b32 m0, s43
	s_nop 0
	global_load_lds_dwordx4 v79, s[50:51]
	s_waitcnt vmcnt(8)
	v_add_u32_e32 v54, s77, v59
	v_add_u32_e32 v55, s77, v60
	v_add_u32_e32 v56, s77, v61
	v_add_u32_e32 v57, s77, v62
	ds_read_b64_tr_b4 v[50:51], v160 offset:896
	ds_read_b64_tr_b4 v[52:53], v160 offset:1920
	ds_read_b64_tr_b4 v[130:131], v54
	ds_read_b64_tr_b4 v[132:133], v55
	ds_read_b64_tr_b4 v[134:135], v56
	ds_read_b64_tr_b4 v[136:137], v57
	s_waitcnt lgkmcnt(6)
	v_dot8c_i32_i4_e32 v38, v122, v48
	v_dot8c_i32_i4_e32 v39, v122, v46
	v_dot8c_i32_i4_e32 v40, v124, v48
	v_dot8c_i32_i4_e32 v41, v124, v46
	v_dot8c_i32_i4_e32 v42, v126, v48
	v_dot8c_i32_i4_e32 v43, v126, v46
	v_dot8c_i32_i4_e32 v44, v128, v48
	v_dot8c_i32_i4_e32 v45, v128, v46
	v_dot8c_i32_i4_e32 v38, v123, v49
	v_dot8c_i32_i4_e32 v39, v123, v47
	v_dot8c_i32_i4_e32 v40, v125, v49
	v_dot8c_i32_i4_e32 v41, v125, v47
	v_dot8c_i32_i4_e32 v42, v127, v49
	v_dot8c_i32_i4_e32 v43, v127, v47
	v_dot8c_i32_i4_e32 v44, v129, v49
	v_dot8c_i32_i4_e32 v45, v129, v47
	v_and_b32_e32 v78, 0xffff, v22
	v_lshrrev_b32_e32 v79, 16, v22
	v_lshl_add_u32 v78, v78, 7, v152
	v_lshl_add_u32 v79, v79, 7, v153
	s_mov_b32 m0, s76
	s_add_i32 s43, s76, 0x400
	global_load_lds_dwordx4 v78, s[50:51]
	s_mov_b32 m0, s43
	s_nop 0
	global_load_lds_dwordx4 v79, s[50:51]
	s_waitcnt vmcnt(8)
	v_add_u32_e32 v54, s78, v59
	v_add_u32_e32 v55, s78, v60
	v_add_u32_e32 v56, s78, v61
	v_add_u32_e32 v57, s78, v62
	ds_read_b64_tr_b4 v[46:47], v160
	ds_read_b64_tr_b4 v[48:49], v160 offset:1024
	ds_read_b64_tr_b4 v[122:123], v54
	ds_read_b64_tr_b4 v[124:125], v55
	ds_read_b64_tr_b4 v[126:127], v56
	ds_read_b64_tr_b4 v[128:129], v57
	s_waitcnt lgkmcnt(6)
	v_dot8c_i32_i4_e32 v38, v130, v52
	v_dot8c_i32_i4_e32 v39, v130, v50
	v_dot8c_i32_i4_e32 v40, v132, v52
	v_dot8c_i32_i4_e32 v41, v132, v50
	v_dot8c_i32_i4_e32 v42, v134, v52
	v_dot8c_i32_i4_e32 v43, v134, v50
	v_dot8c_i32_i4_e32 v44, v136, v52
	v_dot8c_i32_i4_e32 v45, v136, v50
	v_dot8c_i32_i4_e32 v38, v131, v53
	v_dot8c_i32_i4_e32 v39, v131, v51
	v_dot8c_i32_i4_e32 v40, v133, v53
	v_dot8c_i32_i4_e32 v41, v133, v51
	v_dot8c_i32_i4_e32 v42, v135, v53
	v_dot8c_i32_i4_e32 v43, v135, v51
	v_dot8c_i32_i4_e32 v44, v137, v53
	v_dot8c_i32_i4_e32 v45, v137, v51
	s_nop 3
	s_waitcnt lgkmcnt(15)
	v_lshlrev_b32_e32 v38, 5, v38
	v_lshlrev_b32_e32 v39, 1, v39
	v_add3_u32 v38, v39, v229, v38
	v_cvt_f32_i32_e32 v38, v38
	v_mul_f32_e32 v38, v228, v38
	v_lshlrev_b32_e32 v40, 5, v40
	v_lshlrev_b32_e32 v41, 1, v41
	v_add3_u32 v40, v41, v229, v40
	v_cvt_f32_i32_e32 v40, v40
	v_mul_f32_e32 v40, v228, v40
	v_lshlrev_b32_e32 v42, 5, v42
	v_lshlrev_b32_e32 v43, 1, v43
	v_add3_u32 v42, v43, v229, v42
	v_cvt_f32_i32_e32 v42, v42
	v_mul_f32_e32 v42, v228, v42
	v_lshlrev_b32_e32 v44, 5, v44
	v_lshlrev_b32_e32 v45, 1, v45
	v_add3_u32 v44, v45, v229, v44
	v_cvt_f32_i32_e32 v44, v44
	v_mul_f32_e32 v44, v228, v44
	v_cvt_pk_bf16_f32 v186, v38, v40
	v_cvt_pk_bf16_f32 v187, v42, v44
	ds_read_b128 v[252:255], v155
	s_add_i32 s44, s40, 0
	s_ashr_i32 s45, s44, 31
	s_lshl_b64 s[44:45], s[44:45], 12
	v_lshl_add_u64 v[80:81], v[36:37], 0, s[44:45]
	s_waitcnt lgkmcnt(0)
	v_mul_f32_e32 v210, v210, v252
	v_mul_f32_e32 v211, v211, v253
	v_mul_f32_e32 v212, v212, v254
	v_mul_f32_e32 v213, v213, v255
	global_store_dwordx4 v[80:81], v[210:213], off nt
	s_add_i32 s43, s40, 8
	s_lshl_b32 s43, s43, 11
	v_add_u32_e32 v138, s43, v66
	global_load_dwordx2 v[194:195], v138, s[70:71]
	global_load_dwordx2 v[196:197], v138, s[70:71] offset:512
	global_load_dwordx2 v[198:199], v138, s[70:71] offset:1024
	global_load_dwordx2 v[200:201], v138, s[70:71] offset:1536
	v_add_u32_e32 v147, 8, v140
	v_and_b32_e32 v146, 15, v147
	v_xor_b32_e32 v146, 8, v146
	v_bfe_u32 v148, v147, 4, 4
	v_mul_lo_u32 v146, v146, s92
	v_mul_lo_u32 v148, v148, s92
	v_mov_b32_e32 v147, v146
	v_mov_b32_e32 v149, v148
	ds_write2st64_b64 v77, v[146:147], v[148:149] offset1:2
	v_add_u32_e32 v138, 0xc00, v74
	ds_read_u8 v139, v138
	v_add_u32_e32 v141, 0xc00, v73
	ds_read_u8 v140, v141
	s_add_i32 s43, s67, 64
	v_mov_b32_e32 v138, s43
	ds_read2st64_b32 v[228:229], v138 offset1:1
	ds_read_b128 v[26:29], v227 offset:6144
	ds_read_b128 v[30:33], v227 offset:6160
	v_mov_b32_e32 v38, 0
	v_mov_b32_e32 v39, 0
	v_mov_b32_e32 v40, 0
	v_mov_b32_e32 v41, 0
	v_mov_b32_e32 v42, 0
	v_mov_b32_e32 v43, 0
	v_mov_b32_e32 v44, 0
	v_mov_b32_e32 v45, 0
	v_and_b32_e32 v78, 0xffff, v23
	v_lshrrev_b32_e32 v79, 16, v23
	v_lshl_add_u32 v78, v78, 7, v152
	v_lshl_add_u32 v79, v79, 7, v153
	s_mov_b32 m0, s77
	s_add_i32 s43, s77, 0x400
	global_load_lds_dwordx4 v78, s[50:51]
	s_mov_b32 m0, s43
	s_nop 0
	global_load_lds_dwordx4 v79, s[50:51]
	s_waitcnt vmcnt(13)
	v_add_u32_e32 v54, s79, v59
	v_add_u32_e32 v55, s79, v60
	v_add_u32_e32 v56, s79, v61
	v_add_u32_e32 v57, s79, v62
	ds_read_b64_tr_b4 v[50:51], v160 offset:128
	ds_read_b64_tr_b4 v[52:53], v160 offset:1152
	ds_read_b64_tr_b4 v[130:131], v54
	ds_read_b64_tr_b4 v[132:133], v55
	ds_read_b64_tr_b4 v[134:135], v56
	ds_read_b64_tr_b4 v[136:137], v57
	s_waitcnt lgkmcnt(13)
; #define TR4(p_) __builtin_amdgcn_ds_read_tr4_b64_v2i32((LAS v2i*)(p_))
; #define VDMA(st_, k_) do { _Pragma("unroll") for (int i_ = 0; i_ < 4; ++i_) { \
;         const unsigned off_ = (unsigned)((st_) >> 2) * (16384u * 128u) + (PE_ID(E, 4 * ((st_) & 3) + i_) << 7) + ((i_ & 1) ? cx1 : cx0); \
;         __builtin_amdgcn_global_load_lds((const unsigned*)(V4 + off_), (LAS unsigned*)(ldsb + BUF[k_] + 1024 * i_), 16, 0, 0); } } while (0)
; __device__ __forceinline__ void peer_v_tokens(int j, const LAS unsigned short* EL, const LAS unsigned char* AL  , const LAS float* ASC  , const LAS int* SAL  , ...
;     ...
;         for (int st = 0; st < 16; ++st) {
;             const int p = st >> 2, q = st & 3;
;             if (st < 14) VDMA(st + 2, (st + 2) % 3);
;             if (st < 14) asm volatile("s_waitcnt vmcnt(8)" ::: "memory");
;             else if (st == 14) asm volatile("s_waitcnt vmcnt(4)" ::: "memory");
;             else asm volatile("s_waitcnt vmcnt(0)" ::: "memory");
;             if (q == 0) {
; #pragma unroll
;                 for (int r = 0; r < 4; ++r) { accH[r] = 0; accL[r] = 0; } }
; #pragma unroll
;             for (int tp = 0; tp < 2; ++tp) {
;                 const v2i ao = TR4(ATL + (2 * q + tp) * 128 + 8 * s16), ah = TR4(ATL + 1024 + (2 * q + tp) * 128 + 8 * s16);
; #pragma unroll
;                 for (int r = 0; r < 4; ++r) {
;                     const v2i d = TR4(ldsb + BUF[st % 3] + 2048 * tp + roff[r]);
;                     accH[r] = __builtin_amdgcn_sdot8(d.x, ah.x, accH[r], false); accH[r] = __builtin_amdgcn_sdot8(d.y, ah.y, accH[r], false);
;                     accL[r] = __builtin_amdgcn_sdot8(d.x, ao.x, accL[r], false); accL[r] = __builtin_amdgcn_sdot8(d.y, ao.y, accL[r], false);
;                 }
;             }
;             asm volatile("s_waitcnt lgkmcnt(0)" ::: "memory");
	v_dot8c_i32_i4_e32 v38, v122, v48
	v_dot8c_i32_i4_e32 v39, v122, v46
	v_dot8c_i32_i4_e32 v40, v124, v48
	v_dot8c_i32_i4_e32 v41, v124, v46
	v_dot8c_i32_i4_e32 v42, v126, v48
	v_dot8c_i32_i4_e32 v43, v126, v46
	v_dot8c_i32_i4_e32 v44, v128, v48
	v_dot8c_i32_i4_e32 v45, v128, v46
	v_dot8c_i32_i4_e32 v38, v123, v49
	v_dot8c_i32_i4_e32 v39, v123, v47
	v_dot8c_i32_i4_e32 v40, v125, v49
	v_dot8c_i32_i4_e32 v41, v125, v47
	v_dot8c_i32_i4_e32 v42, v127, v49
	v_dot8c_i32_i4_e32 v43, v127, v47
	v_dot8c_i32_i4_e32 v44, v129, v49
	v_dot8c_i32_i4_e32 v45, v129, v47
	v_and_b32_e32 v78, 0xffff, v24
	v_lshrrev_b32_e32 v79, 16, v24
	v_lshl_add_u32 v78, v78, 7, v152
	v_lshl_add_u32 v79, v79, 7, v153
	s_mov_b32 m0, s78
	s_add_i32 s43, s78, 0x400
	global_load_lds_dwordx4 v78, s[50:51]
	s_mov_b32 m0, s43
	s_nop 0
	global_load_lds_dwordx4 v79, s[50:51]
	s_waitcnt vmcnt(13)
	v_add_u32_e32 v54, s98, v59
	v_add_u32_e32 v55, s98, v60
	v_add_u32_e32 v56, s98, v61
	v_add_u32_e32 v57, s98, v62
	ds_read_b64_tr_b4 v[46:47], v160 offset:256
	ds_read_b64_tr_b4 v[48:49], v160 offset:1280
	ds_read_b64_tr_b4 v[122:123], v54
	ds_read_b64_tr_b4 v[124:125], v55
	ds_read_b64_tr_b4 v[126:127], v56
	ds_read_b64_tr_b4 v[128:129], v57
	s_waitcnt lgkmcnt(6)
	v_dot8c_i32_i4_e32 v38, v130, v52
	v_dot8c_i32_i4_e32 v39, v130, v50
	v_dot8c_i32_i4_e32 v40, v132, v52
	v_dot8c_i32_i4_e32 v41, v132, v50
	v_dot8c_i32_i4_e32 v42, v134, v52
	v_dot8c_i32_i4_e32 v43, v134, v50
	v_dot8c_i32_i4_e32 v44, v136, v52
	v_dot8c_i32_i4_e32 v45, v136, v50
	v_dot8c_i32_i4_e32 v38, v131, v53
	v_dot8c_i32_i4_e32 v39, v131, v51
	v_dot8c_i32_i4_e32 v40, v133, v53
	v_dot8c_i32_i4_e32 v41, v133, v51
	v_dot8c_i32_i4_e32 v42, v135, v53
	v_dot8c_i32_i4_e32 v43, v135, v51
	v_dot8c_i32_i4_e32 v44, v137, v53
	v_dot8c_i32_i4_e32 v45, v137, v51
	v_and_b32_e32 v78, 0xffff, v25
	v_lshrrev_b32_e32 v79, 16, v25
	v_lshl_add_u32 v78, v78, 7, v152
	v_lshl_add_u32 v79, v79, 7, v153
	s_mov_b32 m0, s79
	s_add_i32 s43, s79, 0x400
	global_load_lds_dwordx4 v78, s[50:51]
	s_mov_b32 m0, s43
	s_nop 0
	global_load_lds_dwordx4 v79, s[50:51]
	s_waitcnt vmcnt(13)
	v_add_u32_e32 v54, s99, v59
	v_add_u32_e32 v55, s99, v60
	v_add_u32_e32 v56, s99, v61
	v_add_u32_e32 v57, s99, v62
	ds_read_b64_tr_b4 v[50:51], v160 offset:384
	ds_read_b64_tr_b4 v[52:53], v160 offset:1408
	ds_read_b64_tr_b4 v[130:131], v54
	ds_read_b64_tr_b4 v[132:133], v55
	ds_read_b64_tr_b4 v[134:135], v56
	ds_read_b64_tr_b4 v[136:137], v57
	s_waitcnt lgkmcnt(6)
	v_dot8c_i32_i4_e32 v38, v122, v48
	v_dot8c_i32_i4_e32 v39, v122, v46
	v_dot8c_i32_i4_e32 v40, v124, v48
	v_dot8c_i32_i4_e32 v41, v124, v46
	v_dot8c_i32_i4_e32 v42, v126, v48
	v_dot8c_i32_i4_e32 v43, v126, v46
	v_dot8c_i32_i4_e32 v44, v128, v48
	v_dot8c_i32_i4_e32 v45, v128, v46
	v_dot8c_i32_i4_e32 v38, v123, v49
	v_dot8c_i32_i4_e32 v39, v123, v47
	v_dot8c_i32_i4_e32 v40, v125, v49
	v_dot8c_i32_i4_e32 v41, v125, v47
	v_dot8c_i32_i4_e32 v42, v127, v49
	v_dot8c_i32_i4_e32 v43, v127, v47
	v_dot8c_i32_i4_e32 v44, v129, v49
	v_dot8c_i32_i4_e32 v45, v129, v47
	s_waitcnt lgkmcnt(15)
	v_and_b32_e32 v78, 0xffff, v26
	v_lshrrev_b32_e32 v79, 16, v26
	v_lshl_add_u32 v78, v78, 7, v152
	v_lshl_add_u32 v79, v79, 7, v153
	s_mov_b32 m0, s98
	s_add_i32 s43, s98, 0x400
	global_load_lds_dwordx4 v78, s[50:51]
	s_mov_b32 m0, s43
	s_nop 0
	global_load_lds_dwordx4 v79, s[50:51]
	s_waitcnt vmcnt(13)
	v_add_u32_e32 v54, s76, v59
	v_add_u32_e32 v55, s76, v60
	v_add_u32_e32 v56, s76, v61
	v_add_u32_e32 v57, s76, v62
	ds_read_b64_tr_b4 v[46:47], v160 offset:512
	ds_read_b64_tr_b4 v[48:49], v160 offset:1536
	ds_read_b64_tr_b4 v[122:123], v54
	ds_read_b64_tr_b4 v[124:125], v55
	ds_read_b64_tr_b4 v[126:127], v56
	ds_read_b64_tr_b4 v[128:129], v57
	s_waitcnt lgkmcnt(6)
	v_dot8c_i32_i4_e32 v38, v130, v52
	v_dot8c_i32_i4_e32 v39, v130, v50
	v_dot8c_i32_i4_e32 v40, v132, v52
	v_dot8c_i32_i4_e32 v41, v132, v50
	v_dot8c_i32_i4_e32 v42, v134, v52
	v_dot8c_i32_i4_e32 v43, v134, v50
	v_dot8c_i32_i4_e32 v44, v136, v52
	v_dot8c_i32_i4_e32 v45, v136, v50
	v_dot8c_i32_i4_e32 v38, v131, v53
	v_dot8c_i32_i4_e32 v39, v131, v51
	v_dot8c_i32_i4_e32 v40, v133, v53
	v_dot8c_i32_i4_e32 v41, v133, v51
	v_dot8c_i32_i4_e32 v42, v135, v53
	v_dot8c_i32_i4_e32 v43, v135, v51
	v_dot8c_i32_i4_e32 v44, v137, v53
	v_dot8c_i32_i4_e32 v45, v137, v51
	v_and_b32_e32 v78, 0xffff, v27
	v_lshrrev_b32_e32 v79, 16, v27
	v_lshl_add_u32 v78, v78, 7, v152
	v_lshl_add_u32 v79, v79, 7, v153
	s_mov_b32 m0, s99
	s_add_i32 s43, s99, 0x400
	global_load_lds_dwordx4 v78, s[50:51]
	s_mov_b32 m0, s43
	s_nop 0
	global_load_lds_dwordx4 v79, s[50:51]
	s_waitcnt vmcnt(8)
	v_add_u32_e32 v54, s77, v59
	v_add_u32_e32 v55, s77, v60
	v_add_u32_e32 v56, s77, v61
	v_add_u32_e32 v57, s77, v62
	ds_read_b64_tr_b4 v[50:51], v160 offset:640
	ds_read_b64_tr_b4 v[52:53], v160 offset:1664
	ds_read_b64_tr_b4 v[130:131], v54
	ds_read_b64_tr_b4 v[132:133], v55
	ds_read_b64_tr_b4 v[134:135], v56
	ds_read_b64_tr_b4 v[136:137], v57
	s_waitcnt lgkmcnt(6)
	v_dot8c_i32_i4_e32 v38, v122, v48
	v_dot8c_i32_i4_e32 v39, v122, v46
	v_dot8c_i32_i4_e32 v40, v124, v48
	v_dot8c_i32_i4_e32 v41, v124, v46
	v_dot8c_i32_i4_e32 v42, v126, v48
	v_dot8c_i32_i4_e32 v43, v126, v46
	v_dot8c_i32_i4_e32 v44, v128, v48
	v_dot8c_i32_i4_e32 v45, v128, v46
	v_dot8c_i32_i4_e32 v38, v123, v49
	v_dot8c_i32_i4_e32 v39, v123, v47
	v_dot8c_i32_i4_e32 v40, v125, v49
	v_dot8c_i32_i4_e32 v41, v125, v47
	v_dot8c_i32_i4_e32 v42, v127, v49
	v_dot8c_i32_i4_e32 v43, v127, v47
	v_dot8c_i32_i4_e32 v44, v129, v49
	v_dot8c_i32_i4_e32 v45, v129, v47
	s_waitcnt lgkmcnt(15)
; __device__ __forceinline__ void peer_v_tokens(int j, const LAS unsigned short* EL, const LAS unsigned char* AL  , const LAS float* ASC  , const LAS int* SAL  , ...
;     ...
;         for (int st = 0; st < 16; ++st) {
;             const int p = st >> 2, q = st & 3;
;             if (st < 14) VDMA(st + 2, (st + 2) % 3);
;             if (st < 14) asm volatile("s_waitcnt vmcnt(8)" ::: "memory");
;             else if (st == 14) asm volatile("s_waitcnt vmcnt(4)" ::: "memory");
;             else asm volatile("s_waitcnt vmcnt(0)" ::: "memory");
;             if (q == 0) {
; #pragma unroll
;                 for (int r = 0; r < 4; ++r) { accH[r] = 0; accL[r] = 0; } }
; #pragma unroll
;             for (int tp = 0; tp < 2; ++tp) {
;                 const v2i ao = TR4(ATL + (2 * q + tp) * 128 + 8 * s16), ah = TR4(ATL + 1024 + (2 * q + tp) * 128 + 8 * s16);
; #pragma unroll
;                 for (int r = 0; r < 4; ++r) {
;                     const v2i d = TR4(ldsb + BUF[st % 3] + 2048 * tp + roff[r]);
;                     accH[r] = __builtin_amdgcn_sdot8(d.x, ah.x, accH[r], false); accH[r] = __builtin_amdgcn_sdot8(d.y, ah.y, accH[r], false);
;                     accL[r] = __builtin_amdgcn_sdot8(d.x, ao.x, accL[r], false); accL[r] = __builtin_amdgcn_sdot8(d.y, ao.y, accL[r], false);
;                 }
;             }
;             asm volatile("s_waitcnt lgkmcnt(0)" ::: "memory");
;             if (q == 3) {
; #pragma unroll
;                 for (int r = 0; r < 4; ++r) STASH[256 * p + 16 * (grp + 4 * r) + pc] = f2bf(asc * (float)(2 * ((accH[r] << 4) + accL[r]) + sa));
;             }
;         }
;         CFENCE();
;         {
;             float4 v[4]; float ss = 0.f;
; #pragma unroll
;             for (int jq = 0; jq < 4; ++jq) { typedef unsigned u2v __attribute__((ext_vector_type(2))); const u2v pw = *(const LAS u2v*)(STASH + 4 * lane + 256 * jq); const uint2 hw = hv[jq];
;                 v[jq] = make_float4(__uint_as_float(hw.x << 16) + __uint_as_float(pw.x << 16), __uint_as_float(hw.x & 0xffff0000u) + __uint_as_float(pw.x & 0xffff0000u),
;                                     __uint_as_float(hw.y << 16) + __uint_as_float(pw.y << 16), __uint_as_float(hw.y & 0xffff0000u) + __uint_as_float(pw.y & 0xffff0000u));
;                 ss += v[jq].x * v[jq].x + v[jq].y * v[jq].y + v[jq].z * v[jq].z + v[jq].w * v[jq].w; }
;             ss = wave_sum(ss);
	v_add_u32_e32 v143, 8, v139
	v_and_b32_e32 v142, 15, v143
	v_xor_b32_e32 v142, 8, v142
	v_bfe_u32 v144, v143, 4, 4
	v_mul_lo_u32 v142, v142, s92
	v_mul_lo_u32 v144, v144, s92
	v_mov_b32_e32 v143, v142
	v_mov_b32_e32 v145, v144
	ds_write2st64_b64 v159, v[142:143], v[144:145] offset1:2
	v_and_b32_e32 v78, 0xffff, v28
	v_lshrrev_b32_e32 v79, 16, v28
	v_lshl_add_u32 v78, v78, 7, v152
	v_lshl_add_u32 v79, v79, 7, v153
	s_mov_b32 m0, s76
	s_add_i32 s43, s76, 0x400
	global_load_lds_dwordx4 v78, s[50:51]
	s_mov_b32 m0, s43
	s_nop 0
	global_load_lds_dwordx4 v79, s[50:51]
	s_waitcnt vmcnt(8)
	v_add_u32_e32 v54, s78, v59
	v_add_u32_e32 v55, s78, v60
	v_add_u32_e32 v56, s78, v61
	v_add_u32_e32 v57, s78, v62
	ds_read_b64_tr_b4 v[46:47], v160 offset:768
	ds_read_b64_tr_b4 v[48:49], v160 offset:1792
	ds_read_b64_tr_b4 v[122:123], v54
	ds_read_b64_tr_b4 v[124:125], v55
	ds_read_b64_tr_b4 v[126:127], v56
	ds_read_b64_tr_b4 v[128:129], v57
	s_waitcnt lgkmcnt(7)
	v_dot8c_i32_i4_e32 v38, v130, v52
	v_dot8c_i32_i4_e32 v39, v130, v50
	v_dot8c_i32_i4_e32 v40, v132, v52
	v_dot8c_i32_i4_e32 v41, v132, v50
	v_dot8c_i32_i4_e32 v42, v134, v52
	v_dot8c_i32_i4_e32 v43, v134, v50
	v_dot8c_i32_i4_e32 v44, v136, v52
	v_dot8c_i32_i4_e32 v45, v136, v50
	v_dot8c_i32_i4_e32 v38, v131, v53
	v_dot8c_i32_i4_e32 v39, v131, v51
	v_dot8c_i32_i4_e32 v40, v133, v53
	v_dot8c_i32_i4_e32 v41, v133, v51
	v_dot8c_i32_i4_e32 v42, v135, v53
	v_dot8c_i32_i4_e32 v43, v135, v51
	v_dot8c_i32_i4_e32 v44, v137, v53
	v_dot8c_i32_i4_e32 v45, v137, v51
	v_and_b32_e32 v78, 0xffff, v29
	v_lshrrev_b32_e32 v79, 16, v29
	v_lshl_add_u32 v78, v78, 7, v152
	v_lshl_add_u32 v79, v79, 7, v153
	s_mov_b32 m0, s77
	s_add_i32 s43, s77, 0x400
	global_load_lds_dwordx4 v78, s[50:51]
	s_mov_b32 m0, s43
	s_nop 0
	global_load_lds_dwordx4 v79, s[50:51]
	s_waitcnt vmcnt(8)
	v_add_u32_e32 v54, s79, v59
	v_add_u32_e32 v55, s79, v60
	v_add_u32_e32 v56, s79, v61
	v_add_u32_e32 v57, s79, v62
	ds_read_b64_tr_b4 v[50:51], v160 offset:896
	ds_read_b64_tr_b4 v[52:53], v160 offset:1920
	ds_read_b64_tr_b4 v[130:131], v54
	ds_read_b64_tr_b4 v[132:133], v55
	ds_read_b64_tr_b4 v[134:135], v56
	ds_read_b64_tr_b4 v[136:137], v57
	s_waitcnt lgkmcnt(6)
	v_dot8c_i32_i4_e32 v38, v122, v48
	v_dot8c_i32_i4_e32 v39, v122, v46
	v_dot8c_i32_i4_e32 v40, v124, v48
	v_dot8c_i32_i4_e32 v41, v124, v46
	v_dot8c_i32_i4_e32 v42, v126, v48
	v_dot8c_i32_i4_e32 v43, v126, v46
	v_dot8c_i32_i4_e32 v44, v128, v48
	v_dot8c_i32_i4_e32 v45, v128, v46
	v_dot8c_i32_i4_e32 v38, v123, v49
	v_dot8c_i32_i4_e32 v39, v123, v47
	v_dot8c_i32_i4_e32 v40, v125, v49
	v_dot8c_i32_i4_e32 v41, v125, v47
	v_dot8c_i32_i4_e32 v42, v127, v49
	v_dot8c_i32_i4_e32 v43, v127, v47
	v_dot8c_i32_i4_e32 v44, v129, v49
	v_dot8c_i32_i4_e32 v45, v129, v47
	v_and_b32_e32 v78, 0xffff, v30
	v_lshrrev_b32_e32 v79, 16, v30
	v_lshl_add_u32 v78, v78, 7, v152
	v_lshl_add_u32 v79, v79, 7, v153
	s_mov_b32 m0, s78
	s_add_i32 s43, s78, 0x400
	global_load_lds_dwordx4 v78, s[50:51]
	s_mov_b32 m0, s43
	s_nop 0
	global_load_lds_dwordx4 v79, s[50:51]
	s_waitcnt vmcnt(8)
	v_add_u32_e32 v54, s98, v59
	v_add_u32_e32 v55, s98, v60
	v_add_u32_e32 v56, s98, v61
	v_add_u32_e32 v57, s98, v62
	ds_read_b64_tr_b4 v[46:47], v160
	ds_read_b64_tr_b4 v[48:49], v160 offset:1024
	ds_read_b64_tr_b4 v[122:123], v54
	ds_read_b64_tr_b4 v[124:125], v55
	ds_read_b64_tr_b4 v[126:127], v56
	ds_read_b64_tr_b4 v[128:129], v57
	s_waitcnt lgkmcnt(6)
	v_dot8c_i32_i4_e32 v38, v130, v52
	v_dot8c_i32_i4_e32 v39, v130, v50
	v_dot8c_i32_i4_e32 v40, v132, v52
	v_dot8c_i32_i4_e32 v41, v132, v50
	v_dot8c_i32_i4_e32 v42, v134, v52
	v_dot8c_i32_i4_e32 v43, v134, v50
	v_dot8c_i32_i4_e32 v44, v136, v52
	v_dot8c_i32_i4_e32 v45, v136, v50
	v_dot8c_i32_i4_e32 v38, v131, v53
	v_dot8c_i32_i4_e32 v39, v131, v51
	v_dot8c_i32_i4_e32 v40, v133, v53
	v_dot8c_i32_i4_e32 v41, v133, v51
	v_dot8c_i32_i4_e32 v42, v135, v53
	v_dot8c_i32_i4_e32 v43, v135, v51
	v_dot8c_i32_i4_e32 v44, v137, v53
	v_dot8c_i32_i4_e32 v45, v137, v51
	s_nop 3
	s_waitcnt lgkmcnt(15)
	v_lshlrev_b32_e32 v38, 5, v38
	v_lshlrev_b32_e32 v39, 1, v39
	v_add3_u32 v38, v39, v229, v38
	v_cvt_f32_i32_e32 v38, v38
	v_mul_f32_e32 v38, v228, v38
	v_lshlrev_b32_e32 v40, 5, v40
	v_lshlrev_b32_e32 v41, 1, v41
	v_add3_u32 v40, v41, v229, v40
	v_cvt_f32_i32_e32 v40, v40
	v_mul_f32_e32 v40, v228, v40
	v_lshlrev_b32_e32 v42, 5, v42
	v_lshlrev_b32_e32 v43, 1, v43
	v_add3_u32 v42, v43, v229, v42
	v_cvt_f32_i32_e32 v42, v42
	v_mul_f32_e32 v42, v228, v42
	v_lshlrev_b32_e32 v44, 5, v44
	v_lshlrev_b32_e32 v45, 1, v45
	v_add3_u32 v44, v45, v229, v44
	v_cvt_f32_i32_e32 v44, v44
	v_mul_f32_e32 v44, v228, v44
	v_cvt_pk_bf16_f32 v180, v38, v40
	v_cvt_pk_bf16_f32 v181, v42, v44
	ds_read_b128 v[252:255], v155 offset:1024
	s_add_i32 s44, s40, 0
	s_ashr_i32 s45, s44, 31
	s_lshl_b64 s[44:45], s[44:45], 12
	v_lshl_add_u64 v[80:81], v[36:37], 0, s[44:45]
	s_waitcnt lgkmcnt(0)
	v_mul_f32_e32 v214, v214, v252
	v_mul_f32_e32 v215, v215, v253
	v_mul_f32_e32 v216, v216, v254
	v_mul_f32_e32 v217, v217, v255
	global_store_dwordx4 v[80:81], v[214:217], off offset:1024 nt
	v_add_u32_e32 v147, 8, v140
	v_and_b32_e32 v146, 15, v147
	v_xor_b32_e32 v146, 8, v146
	v_bfe_u32 v148, v147, 4, 4
	v_mul_lo_u32 v146, v146, s92
	v_mul_lo_u32 v148, v148, s92
	v_mov_b32_e32 v147, v146
	v_mov_b32_e32 v149, v148
	ds_write2st64_b64 v77, v[146:147], v[148:149] offset1:2
	v_add_u32_e32 v138, 0x800, v74
	ds_read_u8 v139, v138
	v_add_u32_e32 v141, 0x800, v73
	ds_read_u8 v140, v141
	s_add_i32 s43, s67, 96
	v_mov_b32_e32 v138, s43
	ds_read2st64_b32 v[228:229], v138 offset1:1
	ds_read_b128 v[18:21], v227 offset:4096
	ds_read_b128 v[22:25], v227 offset:4112
	v_add_u32_e32 v150, 0x400000, v63
	v_add_u32_e32 v151, 0x400000, v64
	v_mov_b32_e32 v38, 0
	v_mov_b32_e32 v39, 0
	v_mov_b32_e32 v40, 0
	v_mov_b32_e32 v41, 0
	v_mov_b32_e32 v42, 0
	v_mov_b32_e32 v43, 0
	v_mov_b32_e32 v44, 0
	v_mov_b32_e32 v45, 0
	v_and_b32_e32 v78, 0xffff, v31
	v_lshrrev_b32_e32 v79, 16, v31
	v_lshl_add_u32 v78, v78, 7, v152
	v_lshl_add_u32 v79, v79, 7, v153
	s_mov_b32 m0, s79
	s_add_i32 s43, s79, 0x400
	global_load_lds_dwordx4 v78, s[50:51]
	s_mov_b32 m0, s43
	s_nop 0
	global_load_lds_dwordx4 v79, s[50:51]
	s_waitcnt vmcnt(9)
; #define LAS __attribute__((address_space(3)))
; __device__ __forceinline__ bf16 f2bf(float f) { return (bf16)f2bfu(f); }
; #define TR4(p_) __builtin_amdgcn_ds_read_tr4_b64_v2i32((LAS v2i*)(p_))
; #define CFENCE() asm volatile("" ::: "memory")
; __device__ __forceinline__ void peer_v_tokens(int j, const LAS unsigned short* EL, const LAS unsigned char* AL  , const LAS float* ASC  , const LAS int* SAL  , ...
;     ...
;         for (int st = 0; st < 16; ++st) {
;             const int p = st >> 2, q = st & 3;
;             if (st < 14) VDMA(st + 2, (st + 2) % 3);
;             if (st < 14) asm volatile("s_waitcnt vmcnt(8)" ::: "memory");
;             else if (st == 14) asm volatile("s_waitcnt vmcnt(4)" ::: "memory");
;             else asm volatile("s_waitcnt vmcnt(0)" ::: "memory");
;             if (q == 0) {
; #pragma unroll
;                 for (int r = 0; r < 4; ++r) { accH[r] = 0; accL[r] = 0; } }
; #pragma unroll
;             for (int tp = 0; tp < 2; ++tp) {
;                 const v2i ao = TR4(ATL + (2 * q + tp) * 128 + 8 * s16), ah = TR4(ATL + 1024 + (2 * q + tp) * 128 + 8 * s16);
; #pragma unroll
;                 for (int r = 0; r < 4; ++r) {
;                     const v2i d = TR4(ldsb + BUF[st % 3] + 2048 * tp + roff[r]);
;                     accH[r] = __builtin_amdgcn_sdot8(d.x, ah.x, accH[r], false); accH[r] = __builtin_amdgcn_sdot8(d.y, ah.y, accH[r], false);
;                     accL[r] = __builtin_amdgcn_sdot8(d.x, ao.x, accL[r], false); accL[r] = __builtin_amdgcn_sdot8(d.y, ao.y, accL[r], false);
;                 }
;             }
;             asm volatile("s_waitcnt lgkmcnt(0)" ::: "memory");
;             if (q == 3) {
; #pragma unroll
;                 for (int r = 0; r < 4; ++r) STASH[256 * p + 16 * (grp + 4 * r) + pc] = f2bf(asc * (float)(2 * ((accH[r] << 4) + accL[r]) + sa));
;             }
;         }
;         CFENCE();
;         {
;             float4 v[4]; float ss = 0.f;
; #pragma unroll
;             for (int jq = 0; jq < 4; ++jq) { typedef unsigned u2v __attribute__((ext_vector_type(2))); const u2v pw = *(const LAS u2v*)(STASH + 4 * lane + 256 * jq); const uint2 hw = hv[jq];
	v_add_u32_e32 v54, s99, v59
	v_add_u32_e32 v55, s99, v60
	v_add_u32_e32 v56, s99, v61
	v_add_u32_e32 v57, s99, v62
	ds_read_b64_tr_b4 v[50:51], v160 offset:128
	ds_read_b64_tr_b4 v[52:53], v160 offset:1152
	ds_read_b64_tr_b4 v[130:131], v54
	ds_read_b64_tr_b4 v[132:133], v55
	ds_read_b64_tr_b4 v[134:135], v56
	ds_read_b64_tr_b4 v[136:137], v57
	s_waitcnt lgkmcnt(13)
	v_dot8c_i32_i4_e32 v38, v122, v48
	v_dot8c_i32_i4_e32 v39, v122, v46
	v_dot8c_i32_i4_e32 v40, v124, v48
	v_dot8c_i32_i4_e32 v41, v124, v46
	v_dot8c_i32_i4_e32 v42, v126, v48
	v_dot8c_i32_i4_e32 v43, v126, v46
	v_dot8c_i32_i4_e32 v44, v128, v48
	v_dot8c_i32_i4_e32 v45, v128, v46
	v_dot8c_i32_i4_e32 v38, v123, v49
	v_dot8c_i32_i4_e32 v39, v123, v47
	v_dot8c_i32_i4_e32 v40, v125, v49
	v_dot8c_i32_i4_e32 v41, v125, v47
	v_dot8c_i32_i4_e32 v42, v127, v49
	v_dot8c_i32_i4_e32 v43, v127, v47
	v_dot8c_i32_i4_e32 v44, v129, v49
	v_dot8c_i32_i4_e32 v45, v129, v47
	v_and_b32_e32 v78, 0xffff, v32
	v_lshrrev_b32_e32 v79, 16, v32
	v_lshl_add_u32 v78, v78, 7, v152
	v_lshl_add_u32 v79, v79, 7, v153
	s_mov_b32 m0, s98
	s_add_i32 s43, s98, 0x400
	global_load_lds_dwordx4 v78, s[50:51]
	s_mov_b32 m0, s43
	s_nop 0
	global_load_lds_dwordx4 v79, s[50:51]
	s_waitcnt vmcnt(9)
	v_add_u32_e32 v54, s76, v59
	v_add_u32_e32 v55, s76, v60
	v_add_u32_e32 v56, s76, v61
	v_add_u32_e32 v57, s76, v62
	ds_read_b64_tr_b4 v[46:47], v160 offset:256
	ds_read_b64_tr_b4 v[48:49], v160 offset:1280
	ds_read_b64_tr_b4 v[122:123], v54
	ds_read_b64_tr_b4 v[124:125], v55
	ds_read_b64_tr_b4 v[126:127], v56
	ds_read_b64_tr_b4 v[128:129], v57
	s_waitcnt lgkmcnt(6)
	v_dot8c_i32_i4_e32 v38, v130, v52
	v_dot8c_i32_i4_e32 v39, v130, v50
	v_dot8c_i32_i4_e32 v40, v132, v52
	v_dot8c_i32_i4_e32 v41, v132, v50
	v_dot8c_i32_i4_e32 v42, v134, v52
	v_dot8c_i32_i4_e32 v43, v134, v50
	v_dot8c_i32_i4_e32 v44, v136, v52
	v_dot8c_i32_i4_e32 v45, v136, v50
	v_dot8c_i32_i4_e32 v38, v131, v53
	v_dot8c_i32_i4_e32 v39, v131, v51
	v_dot8c_i32_i4_e32 v40, v133, v53
	v_dot8c_i32_i4_e32 v41, v133, v51
	v_dot8c_i32_i4_e32 v42, v135, v53
	v_dot8c_i32_i4_e32 v43, v135, v51
	v_dot8c_i32_i4_e32 v44, v137, v53
	v_dot8c_i32_i4_e32 v45, v137, v51
	ds_write_b16 v65, v170
	ds_write_b16_d16_hi v65, v170 offset:128
	ds_write_b16 v65, v171 offset:256
	ds_write_b16_d16_hi v65, v171 offset:384
	ds_write_b16 v65, v172 offset:512
	ds_write_b16_d16_hi v65, v172 offset:640
	ds_write_b16 v65, v173 offset:768
	ds_write_b16_d16_hi v65, v173 offset:896
	ds_write_b16 v65, v174 offset:1024
	ds_write_b16_d16_hi v65, v174 offset:1152
	ds_write_b16 v65, v175 offset:1280
	ds_write_b16_d16_hi v65, v175 offset:1408
	ds_write_b16 v65, v176 offset:1536
	ds_write_b16_d16_hi v65, v176 offset:1664
	ds_write_b16 v65, v177 offset:1792
	ds_write_b16_d16_hi v65, v177 offset:1920
	ds_read_b64 v[202:203], v154
	ds_read_b64 v[204:205], v154 offset:512
	ds_read_b64 v[206:207], v154 offset:1024
	ds_read_b64 v[208:209], v154 offset:1536
	v_and_b32_e32 v78, 0xffff, v33
	v_lshrrev_b32_e32 v79, 16, v33
	v_lshl_add_u32 v78, v78, 7, v152
	v_lshl_add_u32 v79, v79, 7, v153
	s_mov_b32 m0, s99
	s_add_i32 s43, s99, 0x400
	global_load_lds_dwordx4 v78, s[50:51]
	s_mov_b32 m0, s43
	s_nop 0
	global_load_lds_dwordx4 v79, s[50:51]
	s_waitcnt vmcnt(9)
	v_add_u32_e32 v54, s77, v59
	v_add_u32_e32 v55, s77, v60
	v_add_u32_e32 v56, s77, v61
	v_add_u32_e32 v57, s77, v62
	ds_read_b64_tr_b4 v[50:51], v160 offset:384
	ds_read_b64_tr_b4 v[52:53], v160 offset:1408
	ds_read_b64_tr_b4 v[130:131], v54
	ds_read_b64_tr_b4 v[132:133], v55
	ds_read_b64_tr_b4 v[134:135], v56
	ds_read_b64_tr_b4 v[136:137], v57
	s_waitcnt lgkmcnt(15)
	v_dot8c_i32_i4_e32 v38, v122, v48
	v_dot8c_i32_i4_e32 v39, v122, v46
	v_dot8c_i32_i4_e32 v40, v124, v48
	v_dot8c_i32_i4_e32 v41, v124, v46
	v_dot8c_i32_i4_e32 v42, v126, v48
	v_dot8c_i32_i4_e32 v43, v126, v46
	v_dot8c_i32_i4_e32 v44, v128, v48
	v_dot8c_i32_i4_e32 v45, v128, v46
	v_dot8c_i32_i4_e32 v38, v123, v49
	v_dot8c_i32_i4_e32 v39, v123, v47
	v_dot8c_i32_i4_e32 v40, v125, v49
	v_dot8c_i32_i4_e32 v41, v125, v47
	v_dot8c_i32_i4_e32 v42, v127, v49
	v_dot8c_i32_i4_e32 v43, v127, v47
	v_dot8c_i32_i4_e32 v44, v129, v49
	v_dot8c_i32_i4_e32 v45, v129, v47
	s_waitcnt lgkmcnt(15)
	v_and_b32_e32 v78, 0xffff, v18
	v_lshrrev_b32_e32 v79, 16, v18
	v_lshl_add_u32 v78, v78, 7, v150
	v_lshl_add_u32 v79, v79, 7, v151
	s_mov_b32 m0, s76
	s_add_i32 s43, s76, 0x400
	global_load_lds_dwordx4 v78, s[50:51]
	s_mov_b32 m0, s43
	s_nop 0
	global_load_lds_dwordx4 v79, s[50:51]
	s_waitcnt vmcnt(9)
	v_add_u32_e32 v54, s78, v59
	v_add_u32_e32 v55, s78, v60
	v_add_u32_e32 v56, s78, v61
	v_add_u32_e32 v57, s78, v62
	ds_read_b64_tr_b4 v[46:47], v160 offset:512
	ds_read_b64_tr_b4 v[48:49], v160 offset:1536
	ds_read_b64_tr_b4 v[122:123], v54
	ds_read_b64_tr_b4 v[124:125], v55
	ds_read_b64_tr_b4 v[126:127], v56
	ds_read_b64_tr_b4 v[128:129], v57
	s_waitcnt lgkmcnt(6)
	v_dot8c_i32_i4_e32 v38, v130, v52
	v_dot8c_i32_i4_e32 v39, v130, v50
	v_dot8c_i32_i4_e32 v40, v132, v52
	v_dot8c_i32_i4_e32 v41, v132, v50
	v_dot8c_i32_i4_e32 v42, v134, v52
	v_dot8c_i32_i4_e32 v43, v134, v50
	v_dot8c_i32_i4_e32 v44, v136, v52
	v_dot8c_i32_i4_e32 v45, v136, v50
	v_dot8c_i32_i4_e32 v38, v131, v53
	v_dot8c_i32_i4_e32 v39, v131, v51
	v_dot8c_i32_i4_e32 v40, v133, v53
	v_dot8c_i32_i4_e32 v41, v133, v51
	v_dot8c_i32_i4_e32 v42, v135, v53
	v_dot8c_i32_i4_e32 v43, v135, v51
	v_dot8c_i32_i4_e32 v44, v137, v53
	v_dot8c_i32_i4_e32 v45, v137, v51
	v_and_b32_e32 v78, 0xffff, v19
	v_lshrrev_b32_e32 v79, 16, v19
	v_lshl_add_u32 v78, v78, 7, v150
	v_lshl_add_u32 v79, v79, 7, v151
	s_mov_b32 m0, s77
	s_add_i32 s43, s77, 0x400
	global_load_lds_dwordx4 v78, s[50:51]
	s_mov_b32 m0, s43
	s_nop 0
	global_load_lds_dwordx4 v79, s[50:51]
	s_waitcnt vmcnt(8)
; __device__ __forceinline__ bf16 f2bf(float f) { return (bf16)f2bfu(f); }
; #define TR4(p_) __builtin_amdgcn_ds_read_tr4_b64_v2i32((LAS v2i*)(p_))
; #define VDMA(st_, k_) do { _Pragma("unroll") for (int i_ = 0; i_ < 4; ++i_) { \
;         const unsigned off_ = (unsigned)((st_) >> 2) * (16384u * 128u) + (PE_ID(E, 4 * ((st_) & 3) + i_) << 7) + ((i_ & 1) ? cx1 : cx0); \
;         __builtin_amdgcn_global_load_lds((const unsigned*)(V4 + off_), (LAS unsigned*)(ldsb + BUF[k_] + 1024 * i_), 16, 0, 0); } } while (0)
; __device__ __forceinline__ void peer_v_tokens(int j, const LAS unsigned short* EL, const LAS unsigned char* AL  , const LAS float* ASC  , const LAS int* SAL  , ...
;     ...
;         for (int st = 0; st < 16; ++st) {
;             const int p = st >> 2, q = st & 3;
;             if (st < 14) VDMA(st + 2, (st + 2) % 3);
;             if (st < 14) asm volatile("s_waitcnt vmcnt(8)" ::: "memory");
;             else if (st == 14) asm volatile("s_waitcnt vmcnt(4)" ::: "memory");
;             else asm volatile("s_waitcnt vmcnt(0)" ::: "memory");
;             if (q == 0) {
; #pragma unroll
;                 for (int r = 0; r < 4; ++r) { accH[r] = 0; accL[r] = 0; } }
; #pragma unroll
;             for (int tp = 0; tp < 2; ++tp) {
;                 const v2i ao = TR4(ATL + (2 * q + tp) * 128 + 8 * s16), ah = TR4(ATL + 1024 + (2 * q + tp) * 128 + 8 * s16);
; #pragma unroll
;                 for (int r = 0; r < 4; ++r) {
;                     const v2i d = TR4(ldsb + BUF[st % 3] + 2048 * tp + roff[r]);
;                     accH[r] = __builtin_amdgcn_sdot8(d.x, ah.x, accH[r], false); accH[r] = __builtin_amdgcn_sdot8(d.y, ah.y, accH[r], false);
;                     accL[r] = __builtin_amdgcn_sdot8(d.x, ao.x, accL[r], false); accL[r] = __builtin_amdgcn_sdot8(d.y, ao.y, accL[r], false);
;                 }
;             }
;             asm volatile("s_waitcnt lgkmcnt(0)" ::: "memory");
;             if (q == 3) {
; #pragma unroll
;                 for (int r = 0; r < 4; ++r) STASH[256 * p + 16 * (grp + 4 * r) + pc] = f2bf(asc * (float)(2 * ((accH[r] << 4) + accL[r]) + sa));
	v_add_u32_e32 v54, s79, v59
	v_add_u32_e32 v55, s79, v60
	v_add_u32_e32 v56, s79, v61
	v_add_u32_e32 v57, s79, v62
	ds_read_b64_tr_b4 v[50:51], v160 offset:640
	ds_read_b64_tr_b4 v[52:53], v160 offset:1664
	ds_read_b64_tr_b4 v[130:131], v54
	ds_read_b64_tr_b4 v[132:133], v55
	ds_read_b64_tr_b4 v[134:135], v56
	ds_read_b64_tr_b4 v[136:137], v57
	s_waitcnt lgkmcnt(6)
	v_dot8c_i32_i4_e32 v38, v122, v48
	v_dot8c_i32_i4_e32 v39, v122, v46
	v_dot8c_i32_i4_e32 v40, v124, v48
	v_dot8c_i32_i4_e32 v41, v124, v46
	v_dot8c_i32_i4_e32 v42, v126, v48
	v_dot8c_i32_i4_e32 v43, v126, v46
	v_dot8c_i32_i4_e32 v44, v128, v48
	v_dot8c_i32_i4_e32 v45, v128, v46
	v_dot8c_i32_i4_e32 v38, v123, v49
	v_dot8c_i32_i4_e32 v39, v123, v47
	v_dot8c_i32_i4_e32 v40, v125, v49
	v_dot8c_i32_i4_e32 v41, v125, v47
	v_dot8c_i32_i4_e32 v42, v127, v49
	v_dot8c_i32_i4_e32 v43, v127, v47
	v_dot8c_i32_i4_e32 v44, v129, v49
	v_dot8c_i32_i4_e32 v45, v129, v47
	s_waitcnt lgkmcnt(15)
	v_add_u32_e32 v143, 8, v139
	v_and_b32_e32 v142, 15, v143
	v_xor_b32_e32 v142, 8, v142
	v_bfe_u32 v144, v143, 4, 4
	v_mul_lo_u32 v142, v142, s92
	v_mul_lo_u32 v144, v144, s92
	v_mov_b32_e32 v143, v142
	v_mov_b32_e32 v145, v144
	ds_write2st64_b64 v159, v[142:143], v[144:145] offset1:2
	v_and_b32_e32 v78, 0xffff, v20
	v_lshrrev_b32_e32 v79, 16, v20
	v_lshl_add_u32 v78, v78, 7, v150
	v_lshl_add_u32 v79, v79, 7, v151
	s_mov_b32 m0, s78
	s_add_i32 s43, s78, 0x400
	global_load_lds_dwordx4 v78, s[50:51]
	s_mov_b32 m0, s43
	s_nop 0
	global_load_lds_dwordx4 v79, s[50:51]
	s_waitcnt vmcnt(8)
	v_add_u32_e32 v54, s98, v59
	v_add_u32_e32 v55, s98, v60
	v_add_u32_e32 v56, s98, v61
	v_add_u32_e32 v57, s98, v62
	ds_read_b64_tr_b4 v[46:47], v160 offset:768
	ds_read_b64_tr_b4 v[48:49], v160 offset:1792
	ds_read_b64_tr_b4 v[122:123], v54
	ds_read_b64_tr_b4 v[124:125], v55
	ds_read_b64_tr_b4 v[126:127], v56
	ds_read_b64_tr_b4 v[128:129], v57
	s_waitcnt lgkmcnt(7)
	v_dot8c_i32_i4_e32 v38, v130, v52
	v_dot8c_i32_i4_e32 v39, v130, v50
	v_dot8c_i32_i4_e32 v40, v132, v52
	v_dot8c_i32_i4_e32 v41, v132, v50
	v_dot8c_i32_i4_e32 v42, v134, v52
	v_dot8c_i32_i4_e32 v43, v134, v50
	v_dot8c_i32_i4_e32 v44, v136, v52
	v_dot8c_i32_i4_e32 v45, v136, v50
	v_dot8c_i32_i4_e32 v38, v131, v53
	v_dot8c_i32_i4_e32 v39, v131, v51
	v_dot8c_i32_i4_e32 v40, v133, v53
	v_dot8c_i32_i4_e32 v41, v133, v51
	v_dot8c_i32_i4_e32 v42, v135, v53
	v_dot8c_i32_i4_e32 v43, v135, v51
	v_dot8c_i32_i4_e32 v44, v137, v53
	v_dot8c_i32_i4_e32 v45, v137, v51
	v_and_b32_e32 v78, 0xffff, v21
	v_lshrrev_b32_e32 v79, 16, v21
	v_lshl_add_u32 v78, v78, 7, v150
	v_lshl_add_u32 v79, v79, 7, v151
	s_mov_b32 m0, s79
	s_add_i32 s43, s79, 0x400
	global_load_lds_dwordx4 v78, s[50:51]
	s_mov_b32 m0, s43
	s_nop 0
	global_load_lds_dwordx4 v79, s[50:51]
	s_waitcnt vmcnt(8)
	v_add_u32_e32 v54, s99, v59
	v_add_u32_e32 v55, s99, v60
	v_add_u32_e32 v56, s99, v61
	v_add_u32_e32 v57, s99, v62
	ds_read_b64_tr_b4 v[50:51], v160 offset:896
	ds_read_b64_tr_b4 v[52:53], v160 offset:1920
	ds_read_b64_tr_b4 v[130:131], v54
	ds_read_b64_tr_b4 v[132:133], v55
	ds_read_b64_tr_b4 v[134:135], v56
	ds_read_b64_tr_b4 v[136:137], v57
	s_waitcnt lgkmcnt(6)
	v_dot8c_i32_i4_e32 v38, v122, v48
	v_dot8c_i32_i4_e32 v39, v122, v46
	v_dot8c_i32_i4_e32 v40, v124, v48
	v_dot8c_i32_i4_e32 v41, v124, v46
	v_dot8c_i32_i4_e32 v42, v126, v48
	v_dot8c_i32_i4_e32 v43, v126, v46
	v_dot8c_i32_i4_e32 v44, v128, v48
	v_dot8c_i32_i4_e32 v45, v128, v46
	v_dot8c_i32_i4_e32 v38, v123, v49
	v_dot8c_i32_i4_e32 v39, v123, v47
	v_dot8c_i32_i4_e32 v40, v125, v49
	v_dot8c_i32_i4_e32 v41, v125, v47
	v_dot8c_i32_i4_e32 v42, v127, v49
	v_dot8c_i32_i4_e32 v43, v127, v47
	v_dot8c_i32_i4_e32 v44, v129, v49
	v_dot8c_i32_i4_e32 v45, v129, v47
	v_and_b32_e32 v78, 0xffff, v22
	v_lshrrev_b32_e32 v79, 16, v22
	v_lshl_add_u32 v78, v78, 7, v150
	v_lshl_add_u32 v79, v79, 7, v151
	s_mov_b32 m0, s98
	s_add_i32 s43, s98, 0x400
	global_load_lds_dwordx4 v78, s[50:51]
	s_mov_b32 m0, s43
	s_nop 0
	global_load_lds_dwordx4 v79, s[50:51]
	s_waitcnt vmcnt(8)
	v_add_u32_e32 v54, s76, v59
	v_add_u32_e32 v55, s76, v60
	v_add_u32_e32 v56, s76, v61
	v_add_u32_e32 v57, s76, v62
	ds_read_b64_tr_b4 v[46:47], v160
	ds_read_b64_tr_b4 v[48:49], v160 offset:1024
	ds_read_b64_tr_b4 v[122:123], v54
	ds_read_b64_tr_b4 v[124:125], v55
	ds_read_b64_tr_b4 v[126:127], v56
	ds_read_b64_tr_b4 v[128:129], v57
	s_waitcnt lgkmcnt(6)
	v_dot8c_i32_i4_e32 v38, v130, v52
	v_dot8c_i32_i4_e32 v39, v130, v50
	v_dot8c_i32_i4_e32 v40, v132, v52
	v_dot8c_i32_i4_e32 v41, v132, v50
	v_dot8c_i32_i4_e32 v42, v134, v52
	v_dot8c_i32_i4_e32 v43, v134, v50
	v_dot8c_i32_i4_e32 v44, v136, v52
	v_dot8c_i32_i4_e32 v45, v136, v50
	v_dot8c_i32_i4_e32 v38, v131, v53
	v_dot8c_i32_i4_e32 v39, v131, v51
	v_dot8c_i32_i4_e32 v40, v133, v53
	v_dot8c_i32_i4_e32 v41, v133, v51
	v_dot8c_i32_i4_e32 v42, v135, v53
	v_dot8c_i32_i4_e32 v43, v135, v51
	v_dot8c_i32_i4_e32 v44, v137, v53
	v_dot8c_i32_i4_e32 v45, v137, v51
	s_nop 3
	s_waitcnt lgkmcnt(15)
	v_lshlrev_b32_e32 v38, 5, v38
	v_lshlrev_b32_e32 v39, 1, v39
	v_add3_u32 v38, v39, v229, v38
	v_cvt_f32_i32_e32 v38, v38
	v_mul_f32_e32 v38, v228, v38
	v_lshlrev_b32_e32 v40, 5, v40
	v_lshlrev_b32_e32 v41, 1, v41
	v_add3_u32 v40, v41, v229, v40
	v_cvt_f32_i32_e32 v40, v40
	v_mul_f32_e32 v40, v228, v40
	v_lshlrev_b32_e32 v42, 5, v42
	v_lshlrev_b32_e32 v43, 1, v43
	v_add3_u32 v42, v43, v229, v42
	v_cvt_f32_i32_e32 v42, v42
	v_mul_f32_e32 v42, v228, v42
	v_lshlrev_b32_e32 v44, 5, v44
	v_lshlrev_b32_e32 v45, 1, v45
	v_add3_u32 v44, v45, v229, v44
	v_cvt_f32_i32_e32 v44, v44
	v_mul_f32_e32 v44, v228, v44
	v_cvt_pk_bf16_f32 v188, v38, v40
	v_cvt_pk_bf16_f32 v189, v42, v44
	ds_read_b128 v[252:255], v156
	s_add_i32 s44, s40, 0
	s_ashr_i32 s45, s44, 31
	s_lshl_b64 s[44:45], s[44:45], 12
	v_lshl_add_u64 v[80:81], v[36:37], 0, s[44:45]
	s_waitcnt lgkmcnt(0)
; #define LAS __attribute__((address_space(3)))
; __device__ __forceinline__ void peer_v_tokens(int j, const LAS unsigned short* EL, const LAS unsigned char* AL  , const LAS float* ASC  , const LAS int* SAL  , ...
;     ...
; #pragma unroll 1
;     for (int it = 0; it < 8; ++it) {
;         const int tl = it * 8 + wave, t = j * 64 + tl;
;         unsigned E[8];
;         { const LAS v4u* ep = (const LAS v4u*)(EL + tl * 128 + 16 * g); const v4u e0 = ep[0], e1 = ep[1];
;     ...
;         {
;             float4 v[4]; float ss = 0.f;
; #pragma unroll
;             for (int jq = 0; jq < 4; ++jq) { typedef unsigned u2v __attribute__((ext_vector_type(2))); const u2v pw = *(const LAS u2v*)(STASH + 4 * lane + 256 * jq); const uint2 hw = hv[jq];
;                 v[jq] = make_float4(__uint_as_float(hw.x << 16) + __uint_as_float(pw.x << 16), __uint_as_float(hw.x & 0xffff0000u) + __uint_as_float(pw.x & 0xffff0000u),
;                                     __uint_as_float(hw.y << 16) + __uint_as_float(pw.y << 16), __uint_as_float(hw.y & 0xffff0000u) + __uint_as_float(pw.y & 0xffff0000u));
;                 ss += v[jq].x * v[jq].x + v[jq].y * v[jq].y + v[jq].z * v[jq].z + v[jq].w * v[jq].w; }
;             ss = wave_sum(ss);
;             const float r3 = rsqrtf(ss * (1.f / D) + EPS);
;             float4* op = (float4*)(outp + (size_t)t * D) + lane;
; #pragma unroll
;             for (int jq = 0; jq < 4; ++jq) { typedef float f4v __attribute__((ext_vector_type(4))); f4v o4; o4.x = v[jq].x * r3 * gv[jq].x; o4.y = v[jq].y * r3 * gv[jq].y; o4.z = v[jq].z * r3 * gv[jq].z; o4.w = v[jq].w * r3 * gv[jq].w;
;                 __builtin_nontemporal_store(o4, (f4v*)op + 64 * jq); }
	v_mul_f32_e32 v218, v218, v252
	v_mul_f32_e32 v219, v219, v253
	v_mul_f32_e32 v220, v220, v254
	v_mul_f32_e32 v221, v221, v255
	global_store_dwordx4 v[80:81], v[218:221], off offset:2048 nt
	v_add_u32_e32 v147, 8, v140
	v_and_b32_e32 v146, 15, v147
	v_xor_b32_e32 v146, 8, v146
	v_bfe_u32 v148, v147, 4, 4
	v_mul_lo_u32 v146, v146, s92
	v_mul_lo_u32 v148, v148, s92
	v_mov_b32_e32 v147, v146
	v_mov_b32_e32 v149, v148
	ds_write2st64_b64 v77, v[146:147], v[148:149] offset1:2
	v_add_u32_e32 v138, 0xc00, v74
	ds_read_u8 v139, v138
	v_add_u32_e32 v141, 0xc00, v73
	ds_read_u8 v140, v141
	s_add_i32 s43, s67, 64
	v_mov_b32_e32 v138, s43
	ds_read2st64_b32 v[228:229], v138 offset1:1
	ds_read_b128 v[26:29], v227 offset:6144
	ds_read_b128 v[30:33], v227 offset:6160
	v_mov_b32_e32 v38, 0
	v_mov_b32_e32 v39, 0
	v_mov_b32_e32 v40, 0
	v_mov_b32_e32 v41, 0
	v_mov_b32_e32 v42, 0
	v_mov_b32_e32 v43, 0
	v_mov_b32_e32 v44, 0
	v_mov_b32_e32 v45, 0
	v_and_b32_e32 v78, 0xffff, v23
	v_lshrrev_b32_e32 v79, 16, v23
	v_lshl_add_u32 v78, v78, 7, v150
	v_lshl_add_u32 v79, v79, 7, v151
	s_mov_b32 m0, s99
	s_add_i32 s43, s99, 0x400
	global_load_lds_dwordx4 v78, s[50:51]
	s_mov_b32 m0, s43
	s_nop 0
	global_load_lds_dwordx4 v79, s[50:51]
	s_waitcnt vmcnt(9)
	v_add_u32_e32 v54, s77, v59
	v_add_u32_e32 v55, s77, v60
	v_add_u32_e32 v56, s77, v61
	v_add_u32_e32 v57, s77, v62
	ds_read_b64_tr_b4 v[50:51], v160 offset:128
	ds_read_b64_tr_b4 v[52:53], v160 offset:1152
	ds_read_b64_tr_b4 v[130:131], v54
	ds_read_b64_tr_b4 v[132:133], v55
	ds_read_b64_tr_b4 v[134:135], v56
	ds_read_b64_tr_b4 v[136:137], v57
	s_waitcnt lgkmcnt(13)
	s_waitcnt vmcnt(36) lgkmcnt(15)
	v_lshlrev_b32_e32 v236, 16, v194
	v_and_b32_e32 v237, 0xffff0000, v194
	v_lshlrev_b32_e32 v142, 16, v202
	v_and_b32_e32 v143, 0xffff0000, v202
	v_add_f32_e32 v236, v236, v142
	v_add_f32_e32 v237, v237, v143
	v_lshlrev_b32_e32 v238, 16, v195
	v_and_b32_e32 v239, 0xffff0000, v195
	v_lshlrev_b32_e32 v142, 16, v203
	v_and_b32_e32 v143, 0xffff0000, v203
	v_add_f32_e32 v238, v238, v142
	v_add_f32_e32 v239, v239, v143
	v_lshlrev_b32_e32 v240, 16, v196
	v_and_b32_e32 v241, 0xffff0000, v196
	v_lshlrev_b32_e32 v142, 16, v204
	v_and_b32_e32 v143, 0xffff0000, v204
	v_add_f32_e32 v240, v240, v142
	v_add_f32_e32 v241, v241, v143
	v_lshlrev_b32_e32 v242, 16, v197
	v_and_b32_e32 v243, 0xffff0000, v197
	v_lshlrev_b32_e32 v142, 16, v205
	v_and_b32_e32 v143, 0xffff0000, v205
	v_add_f32_e32 v242, v242, v142
	v_add_f32_e32 v243, v243, v143
	v_lshlrev_b32_e32 v244, 16, v198
	v_and_b32_e32 v245, 0xffff0000, v198
	v_lshlrev_b32_e32 v142, 16, v206
	v_and_b32_e32 v143, 0xffff0000, v206
	v_add_f32_e32 v244, v244, v142
	v_add_f32_e32 v245, v245, v143
	v_lshlrev_b32_e32 v246, 16, v199
	v_and_b32_e32 v247, 0xffff0000, v199
	v_lshlrev_b32_e32 v142, 16, v207
	v_and_b32_e32 v143, 0xffff0000, v207
	v_add_f32_e32 v246, v246, v142
	v_add_f32_e32 v247, v247, v143
	v_lshlrev_b32_e32 v248, 16, v200
	v_and_b32_e32 v249, 0xffff0000, v200
	v_lshlrev_b32_e32 v142, 16, v208
	v_and_b32_e32 v143, 0xffff0000, v208
	v_add_f32_e32 v248, v248, v142
	v_add_f32_e32 v249, v249, v143
	v_lshlrev_b32_e32 v250, 16, v201
	v_and_b32_e32 v251, 0xffff0000, v201
	v_lshlrev_b32_e32 v142, 16, v209
	v_and_b32_e32 v143, 0xffff0000, v209
	v_add_f32_e32 v250, v250, v142
	v_add_f32_e32 v251, v251, v143
	v_mov_b32_e32 v144, 0
	v_mul_f32_e32 v145, v236, v236
	v_fmac_f32_e32 v145, v237, v237
	v_fmac_f32_e32 v145, v238, v238
	v_fmac_f32_e32 v145, v239, v239
	v_add_f32_e32 v144, v144, v145
	v_mul_f32_e32 v145, v240, v240
	v_fmac_f32_e32 v145, v241, v241
	v_fmac_f32_e32 v145, v242, v242
	v_fmac_f32_e32 v145, v243, v243
	v_add_f32_e32 v144, v144, v145
	v_mul_f32_e32 v145, v244, v244
	v_fmac_f32_e32 v145, v245, v245
	v_fmac_f32_e32 v145, v246, v246
	v_fmac_f32_e32 v145, v247, v247
	v_add_f32_e32 v144, v144, v145
	v_mul_f32_e32 v145, v248, v248
	v_fmac_f32_e32 v145, v249, v249
	v_fmac_f32_e32 v145, v250, v250
	v_fmac_f32_e32 v145, v251, v251
	v_add_f32_e32 v144, v144, v145
	s_nop 1
	v_add_f32_dpp v144, v144, v144 quad_perm:[1,0,3,2] row_mask:0xf bank_mask:0xf bound_ctrl:1
	s_nop 1
	v_add_f32_dpp v144, v144, v144 quad_perm:[2,3,0,1] row_mask:0xf bank_mask:0xf bound_ctrl:1
	s_nop 1
	v_add_f32_dpp v144, v144, v144 row_half_mirror row_mask:0xf bank_mask:0xf bound_ctrl:1
	s_nop 1
	v_add_f32_dpp v144, v144, v144 row_mirror row_mask:0xf bank_mask:0xf bound_ctrl:1
	s_nop 1
	v_readlane_b32 s10, v144, 0
	v_readlane_b32 s11, v144, 16
	v_readlane_b32 s14, v144, 32
	v_readlane_b32 s15, v144, 48
	s_nop 3
	v_mov_b32_e32 v144, s11
	v_mov_b32_e32 v145, s15
	v_add_f32_e32 v144, s10, v144
	v_add_f32_e32 v145, s14, v145
	v_add_f32_e32 v144, v144, v145
	v_fmamk_f32 v144, v144, 0x3a800000, v111
	v_rsq_f32_e32 v144, v144
	s_nop 0
	v_mul_f32_e32 v236, v236, v144
	v_mul_f32_e32 v237, v237, v144
	v_mul_f32_e32 v238, v238, v144
	v_mul_f32_e32 v239, v239, v144
	v_mul_f32_e32 v240, v240, v144
	v_mul_f32_e32 v241, v241, v144
	v_mul_f32_e32 v242, v242, v144
	v_mul_f32_e32 v243, v243, v144
	v_mul_f32_e32 v244, v244, v144
	v_mul_f32_e32 v245, v245, v144
	v_mul_f32_e32 v246, v246, v144
	v_mul_f32_e32 v247, v247, v144
	v_mul_f32_e32 v248, v248, v144
	v_mul_f32_e32 v249, v249, v144
	v_mul_f32_e32 v250, v250, v144
	v_mul_f32_e32 v251, v251, v144
	v_dot8c_i32_i4_e32 v38, v122, v48
	v_dot8c_i32_i4_e32 v39, v122, v46
	v_dot8c_i32_i4_e32 v40, v124, v48
	v_dot8c_i32_i4_e32 v41, v124, v46
	v_dot8c_i32_i4_e32 v42, v126, v48
	v_dot8c_i32_i4_e32 v43, v126, v46
	v_dot8c_i32_i4_e32 v44, v128, v48
	v_dot8c_i32_i4_e32 v45, v128, v46
	v_dot8c_i32_i4_e32 v38, v123, v49
	v_dot8c_i32_i4_e32 v39, v123, v47
	v_dot8c_i32_i4_e32 v40, v125, v49
	v_dot8c_i32_i4_e32 v41, v125, v47
	v_dot8c_i32_i4_e32 v42, v127, v49
	v_dot8c_i32_i4_e32 v43, v127, v47
	v_dot8c_i32_i4_e32 v44, v129, v49
	v_dot8c_i32_i4_e32 v45, v129, v47
	v_and_b32_e32 v78, 0xffff, v24
	v_lshrrev_b32_e32 v79, 16, v24
	v_lshl_add_u32 v78, v78, 7, v150
	v_lshl_add_u32 v79, v79, 7, v151
	s_mov_b32 m0, s76
	s_add_i32 s43, s76, 0x400
	global_load_lds_dwordx4 v78, s[50:51]
	s_mov_b32 m0, s43
	s_nop 0
	global_load_lds_dwordx4 v79, s[50:51]
	s_waitcnt vmcnt(9)
; #define TR4(p_) __builtin_amdgcn_ds_read_tr4_b64_v2i32((LAS v2i*)(p_))
; #define VDMA(st_, k_) do { _Pragma("unroll") for (int i_ = 0; i_ < 4; ++i_) { \
;         const unsigned off_ = (unsigned)((st_) >> 2) * (16384u * 128u) + (PE_ID(E, 4 * ((st_) & 3) + i_) << 7) + ((i_ & 1) ? cx1 : cx0); \
;         __builtin_amdgcn_global_load_lds((const unsigned*)(V4 + off_), (LAS unsigned*)(ldsb + BUF[k_] + 1024 * i_), 16, 0, 0); } } while (0)
; __device__ __forceinline__ void peer_v_tokens(int j, const LAS unsigned short* EL, const LAS unsigned char* AL  , const LAS float* ASC  , const LAS int* SAL  , ...
;     ...
;         for (int st = 0; st < 16; ++st) {
;             const int p = st >> 2, q = st & 3;
;             if (st < 14) VDMA(st + 2, (st + 2) % 3);
;             if (st < 14) asm volatile("s_waitcnt vmcnt(8)" ::: "memory");
;             else if (st == 14) asm volatile("s_waitcnt vmcnt(4)" ::: "memory");
;             else asm volatile("s_waitcnt vmcnt(0)" ::: "memory");
;             if (q == 0) {
; #pragma unroll
;                 for (int r = 0; r < 4; ++r) { accH[r] = 0; accL[r] = 0; } }
; #pragma unroll
;             for (int tp = 0; tp < 2; ++tp) {
;                 const v2i ao = TR4(ATL + (2 * q + tp) * 128 + 8 * s16), ah = TR4(ATL + 1024 + (2 * q + tp) * 128 + 8 * s16);
; #pragma unroll
;                 for (int r = 0; r < 4; ++r) {
;                     const v2i d = TR4(ldsb + BUF[st % 3] + 2048 * tp + roff[r]);
;                     accH[r] = __builtin_amdgcn_sdot8(d.x, ah.x, accH[r], false); accH[r] = __builtin_amdgcn_sdot8(d.y, ah.y, accH[r], false);
;                     accL[r] = __builtin_amdgcn_sdot8(d.x, ao.x, accL[r], false); accL[r] = __builtin_amdgcn_sdot8(d.y, ao.y, accL[r], false);
;                 }
;             }
	v_add_u32_e32 v54, s78, v59
	v_add_u32_e32 v55, s78, v60
	v_add_u32_e32 v56, s78, v61
	v_add_u32_e32 v57, s78, v62
	ds_read_b64_tr_b4 v[46:47], v160 offset:256
	ds_read_b64_tr_b4 v[48:49], v160 offset:1280
	ds_read_b64_tr_b4 v[122:123], v54
	ds_read_b64_tr_b4 v[124:125], v55
	ds_read_b64_tr_b4 v[126:127], v56
	ds_read_b64_tr_b4 v[128:129], v57
	s_waitcnt lgkmcnt(6)
	v_dot8c_i32_i4_e32 v38, v130, v52
	v_dot8c_i32_i4_e32 v39, v130, v50
	v_dot8c_i32_i4_e32 v40, v132, v52
	v_dot8c_i32_i4_e32 v41, v132, v50
	v_dot8c_i32_i4_e32 v42, v134, v52
	v_dot8c_i32_i4_e32 v43, v134, v50
	v_dot8c_i32_i4_e32 v44, v136, v52
	v_dot8c_i32_i4_e32 v45, v136, v50
	v_dot8c_i32_i4_e32 v38, v131, v53
	v_dot8c_i32_i4_e32 v39, v131, v51
	v_dot8c_i32_i4_e32 v40, v133, v53
	v_dot8c_i32_i4_e32 v41, v133, v51
	v_dot8c_i32_i4_e32 v42, v135, v53
	v_dot8c_i32_i4_e32 v43, v135, v51
	v_dot8c_i32_i4_e32 v44, v137, v53
	v_dot8c_i32_i4_e32 v45, v137, v51
	v_and_b32_e32 v78, 0xffff, v25
	v_lshrrev_b32_e32 v79, 16, v25
	v_lshl_add_u32 v78, v78, 7, v150
	v_lshl_add_u32 v79, v79, 7, v151
	s_mov_b32 m0, s77
	s_add_i32 s43, s77, 0x400
	global_load_lds_dwordx4 v78, s[50:51]
	s_mov_b32 m0, s43
	s_nop 0
	global_load_lds_dwordx4 v79, s[50:51]
	s_waitcnt vmcnt(9)
	v_add_u32_e32 v54, s79, v59
	v_add_u32_e32 v55, s79, v60
	v_add_u32_e32 v56, s79, v61
	v_add_u32_e32 v57, s79, v62
	ds_read_b64_tr_b4 v[50:51], v160 offset:384
	ds_read_b64_tr_b4 v[52:53], v160 offset:1408
	ds_read_b64_tr_b4 v[130:131], v54
	ds_read_b64_tr_b4 v[132:133], v55
	ds_read_b64_tr_b4 v[134:135], v56
	ds_read_b64_tr_b4 v[136:137], v57
	s_waitcnt lgkmcnt(6)
	v_dot8c_i32_i4_e32 v38, v122, v48
	v_dot8c_i32_i4_e32 v39, v122, v46
	v_dot8c_i32_i4_e32 v40, v124, v48
	v_dot8c_i32_i4_e32 v41, v124, v46
	v_dot8c_i32_i4_e32 v42, v126, v48
	v_dot8c_i32_i4_e32 v43, v126, v46
	v_dot8c_i32_i4_e32 v44, v128, v48
	v_dot8c_i32_i4_e32 v45, v128, v46
	v_dot8c_i32_i4_e32 v38, v123, v49
	v_dot8c_i32_i4_e32 v39, v123, v47
	v_dot8c_i32_i4_e32 v40, v125, v49
	v_dot8c_i32_i4_e32 v41, v125, v47
	v_dot8c_i32_i4_e32 v42, v127, v49
	v_dot8c_i32_i4_e32 v43, v127, v47
	v_dot8c_i32_i4_e32 v44, v129, v49
	v_dot8c_i32_i4_e32 v45, v129, v47
	s_waitcnt lgkmcnt(15)
	v_and_b32_e32 v78, 0xffff, v26
	v_lshrrev_b32_e32 v79, 16, v26
	v_lshl_add_u32 v78, v78, 7, v150
	v_lshl_add_u32 v79, v79, 7, v151
	s_mov_b32 m0, s78
	s_add_i32 s43, s78, 0x400
	global_load_lds_dwordx4 v78, s[50:51]
	s_mov_b32 m0, s43
	s_nop 0
	global_load_lds_dwordx4 v79, s[50:51]
	s_waitcnt vmcnt(9)
	v_add_u32_e32 v54, s98, v59
	v_add_u32_e32 v55, s98, v60
	v_add_u32_e32 v56, s98, v61
	v_add_u32_e32 v57, s98, v62
	ds_read_b64_tr_b4 v[46:47], v160 offset:512
	ds_read_b64_tr_b4 v[48:49], v160 offset:1536
	ds_read_b64_tr_b4 v[122:123], v54
	ds_read_b64_tr_b4 v[124:125], v55
	ds_read_b64_tr_b4 v[126:127], v56
	ds_read_b64_tr_b4 v[128:129], v57
	s_waitcnt lgkmcnt(6)
	v_dot8c_i32_i4_e32 v38, v130, v52
	v_dot8c_i32_i4_e32 v39, v130, v50
	v_dot8c_i32_i4_e32 v40, v132, v52
	v_dot8c_i32_i4_e32 v41, v132, v50
	v_dot8c_i32_i4_e32 v42, v134, v52
	v_dot8c_i32_i4_e32 v43, v134, v50
	v_dot8c_i32_i4_e32 v44, v136, v52
	v_dot8c_i32_i4_e32 v45, v136, v50
	v_dot8c_i32_i4_e32 v38, v131, v53
	v_dot8c_i32_i4_e32 v39, v131, v51
	v_dot8c_i32_i4_e32 v40, v133, v53
	v_dot8c_i32_i4_e32 v41, v133, v51
	v_dot8c_i32_i4_e32 v42, v135, v53
	v_dot8c_i32_i4_e32 v43, v135, v51
	v_dot8c_i32_i4_e32 v44, v137, v53
	v_dot8c_i32_i4_e32 v45, v137, v51
	v_and_b32_e32 v78, 0xffff, v27
	v_lshrrev_b32_e32 v79, 16, v27
	v_lshl_add_u32 v78, v78, 7, v150
	v_lshl_add_u32 v79, v79, 7, v151
	s_mov_b32 m0, s79
	s_add_i32 s43, s79, 0x400
	global_load_lds_dwordx4 v78, s[50:51]
	s_mov_b32 m0, s43
	s_nop 0
	global_load_lds_dwordx4 v79, s[50:51]
	s_waitcnt vmcnt(8)
	v_add_u32_e32 v54, s99, v59
	v_add_u32_e32 v55, s99, v60
	v_add_u32_e32 v56, s99, v61
	v_add_u32_e32 v57, s99, v62
	ds_read_b64_tr_b4 v[50:51], v160 offset:640
	ds_read_b64_tr_b4 v[52:53], v160 offset:1664
	ds_read_b64_tr_b4 v[130:131], v54
	ds_read_b64_tr_b4 v[132:133], v55
	ds_read_b64_tr_b4 v[134:135], v56
	ds_read_b64_tr_b4 v[136:137], v57
	s_waitcnt lgkmcnt(6)
	v_dot8c_i32_i4_e32 v38, v122, v48
	v_dot8c_i32_i4_e32 v39, v122, v46
	v_dot8c_i32_i4_e32 v40, v124, v48
	v_dot8c_i32_i4_e32 v41, v124, v46
	v_dot8c_i32_i4_e32 v42, v126, v48
	v_dot8c_i32_i4_e32 v43, v126, v46
	v_dot8c_i32_i4_e32 v44, v128, v48
	v_dot8c_i32_i4_e32 v45, v128, v46
	v_dot8c_i32_i4_e32 v38, v123, v49
	v_dot8c_i32_i4_e32 v39, v123, v47
	v_dot8c_i32_i4_e32 v40, v125, v49
	v_dot8c_i32_i4_e32 v41, v125, v47
	v_dot8c_i32_i4_e32 v42, v127, v49
	v_dot8c_i32_i4_e32 v43, v127, v47
	v_dot8c_i32_i4_e32 v44, v129, v49
	v_dot8c_i32_i4_e32 v45, v129, v47
	s_waitcnt lgkmcnt(15)
	v_add_u32_e32 v143, 8, v139
	v_and_b32_e32 v142, 15, v143
	v_xor_b32_e32 v142, 8, v142
	v_bfe_u32 v144, v143, 4, 4
	v_mul_lo_u32 v142, v142, s92
	v_mul_lo_u32 v144, v144, s92
	v_mov_b32_e32 v143, v142
	v_mov_b32_e32 v145, v144
	ds_write2st64_b64 v159, v[142:143], v[144:145] offset1:2
	v_and_b32_e32 v78, 0xffff, v28
	v_lshrrev_b32_e32 v79, 16, v28
	v_lshl_add_u32 v78, v78, 7, v150
	v_lshl_add_u32 v79, v79, 7, v151
	s_mov_b32 m0, s98
	s_add_i32 s43, s98, 0x400
	global_load_lds_dwordx4 v78, s[50:51]
	s_mov_b32 m0, s43
	s_nop 0
	global_load_lds_dwordx4 v79, s[50:51]
	s_waitcnt vmcnt(8)
	v_add_u32_e32 v54, s76, v59
	v_add_u32_e32 v55, s76, v60
	v_add_u32_e32 v56, s76, v61
	v_add_u32_e32 v57, s76, v62
	ds_read_b64_tr_b4 v[46:47], v160 offset:768
	ds_read_b64_tr_b4 v[48:49], v160 offset:1792
	ds_read_b64_tr_b4 v[122:123], v54
	ds_read_b64_tr_b4 v[124:125], v55
	ds_read_b64_tr_b4 v[126:127], v56
	ds_read_b64_tr_b4 v[128:129], v57
	s_waitcnt lgkmcnt(7)
; __device__ __forceinline__ void peer_v_tokens(int j, const LAS unsigned short* EL, const LAS unsigned char* AL  , const LAS float* ASC  , const LAS int* SAL  , ...
;     ...
;         for (int st = 0; st < 16; ++st) {
;             const int p = st >> 2, q = st & 3;
;             if (st < 14) VDMA(st + 2, (st + 2) % 3);
;             if (st < 14) asm volatile("s_waitcnt vmcnt(8)" ::: "memory");
;             else if (st == 14) asm volatile("s_waitcnt vmcnt(4)" ::: "memory");
;             else asm volatile("s_waitcnt vmcnt(0)" ::: "memory");
;             if (q == 0) {
; #pragma unroll
;                 for (int r = 0; r < 4; ++r) { accH[r] = 0; accL[r] = 0; } }
; #pragma unroll
;             for (int tp = 0; tp < 2; ++tp) {
;                 const v2i ao = TR4(ATL + (2 * q + tp) * 128 + 8 * s16), ah = TR4(ATL + 1024 + (2 * q + tp) * 128 + 8 * s16);
; #pragma unroll
;                 for (int r = 0; r < 4; ++r) {
;                     const v2i d = TR4(ldsb + BUF[st % 3] + 2048 * tp + roff[r]);
;                     accH[r] = __builtin_amdgcn_sdot8(d.x, ah.x, accH[r], false); accH[r] = __builtin_amdgcn_sdot8(d.y, ah.y, accH[r], false);
;                     accL[r] = __builtin_amdgcn_sdot8(d.x, ao.x, accL[r], false); accL[r] = __builtin_amdgcn_sdot8(d.y, ao.y, accL[r], false);
;                 }
;             }
;             asm volatile("s_waitcnt lgkmcnt(0)" ::: "memory");
;             if (q == 3) {
; #pragma unroll
;                 for (int r = 0; r < 4; ++r) STASH[256 * p + 16 * (grp + 4 * r) + pc] = f2bf(asc * (float)(2 * ((accH[r] << 4) + accL[r]) + sa));
;             }
;         }
;         CFENCE();
;         {
;             float4 v[4]; float ss = 0.f;
; #pragma unroll
;             for (int jq = 0; jq < 4; ++jq) { typedef unsigned u2v __attribute__((ext_vector_type(2))); const u2v pw = *(const LAS u2v*)(STASH + 4 * lane + 256 * jq); const uint2 hw = hv[jq];
;                 v[jq] = make_float4(__uint_as_float(hw.x << 16) + __uint_as_float(pw.x << 16), __uint_as_float(hw.x & 0xffff0000u) + __uint_as_float(pw.x & 0xffff0000u),
;                                     __uint_as_float(hw.y << 16) + __uint_as_float(pw.y << 16), __uint_as_float(hw.y & 0xffff0000u) + __uint_as_float(pw.y & 0xffff0000u));
;                 ss += v[jq].x * v[jq].x + v[jq].y * v[jq].y + v[jq].z * v[jq].z + v[jq].w * v[jq].w; }
;             ss = wave_sum(ss);
	v_dot8c_i32_i4_e32 v38, v130, v52
	v_dot8c_i32_i4_e32 v39, v130, v50
	v_dot8c_i32_i4_e32 v40, v132, v52
	v_dot8c_i32_i4_e32 v41, v132, v50
	v_dot8c_i32_i4_e32 v42, v134, v52
	v_dot8c_i32_i4_e32 v43, v134, v50
	v_dot8c_i32_i4_e32 v44, v136, v52
	v_dot8c_i32_i4_e32 v45, v136, v50
	v_dot8c_i32_i4_e32 v38, v131, v53
	v_dot8c_i32_i4_e32 v39, v131, v51
	v_dot8c_i32_i4_e32 v40, v133, v53
	v_dot8c_i32_i4_e32 v41, v133, v51
	v_dot8c_i32_i4_e32 v42, v135, v53
	v_dot8c_i32_i4_e32 v43, v135, v51
	v_dot8c_i32_i4_e32 v44, v137, v53
	v_dot8c_i32_i4_e32 v45, v137, v51
	v_and_b32_e32 v78, 0xffff, v29
	v_lshrrev_b32_e32 v79, 16, v29
	v_lshl_add_u32 v78, v78, 7, v150
	v_lshl_add_u32 v79, v79, 7, v151
	s_mov_b32 m0, s99
	s_add_i32 s43, s99, 0x400
	global_load_lds_dwordx4 v78, s[50:51]
	s_mov_b32 m0, s43
	s_nop 0
	global_load_lds_dwordx4 v79, s[50:51]
	s_waitcnt vmcnt(8)
	v_add_u32_e32 v54, s77, v59
	v_add_u32_e32 v55, s77, v60
	v_add_u32_e32 v56, s77, v61
	v_add_u32_e32 v57, s77, v62
	ds_read_b64_tr_b4 v[50:51], v160 offset:896
	ds_read_b64_tr_b4 v[52:53], v160 offset:1920
	ds_read_b64_tr_b4 v[130:131], v54
	ds_read_b64_tr_b4 v[132:133], v55
	ds_read_b64_tr_b4 v[134:135], v56
	ds_read_b64_tr_b4 v[136:137], v57
	s_waitcnt lgkmcnt(6)
	v_dot8c_i32_i4_e32 v38, v122, v48
	v_dot8c_i32_i4_e32 v39, v122, v46
	v_dot8c_i32_i4_e32 v40, v124, v48
	v_dot8c_i32_i4_e32 v41, v124, v46
	v_dot8c_i32_i4_e32 v42, v126, v48
	v_dot8c_i32_i4_e32 v43, v126, v46
	v_dot8c_i32_i4_e32 v44, v128, v48
	v_dot8c_i32_i4_e32 v45, v128, v46
	v_dot8c_i32_i4_e32 v38, v123, v49
	v_dot8c_i32_i4_e32 v39, v123, v47
	v_dot8c_i32_i4_e32 v40, v125, v49
	v_dot8c_i32_i4_e32 v41, v125, v47
	v_dot8c_i32_i4_e32 v42, v127, v49
	v_dot8c_i32_i4_e32 v43, v127, v47
	v_dot8c_i32_i4_e32 v44, v129, v49
	v_dot8c_i32_i4_e32 v45, v129, v47
	v_and_b32_e32 v78, 0xffff, v30
	v_lshrrev_b32_e32 v79, 16, v30
	v_lshl_add_u32 v78, v78, 7, v150
	v_lshl_add_u32 v79, v79, 7, v151
	s_mov_b32 m0, s76
	s_add_i32 s43, s76, 0x400
	global_load_lds_dwordx4 v78, s[50:51]
	s_mov_b32 m0, s43
	s_nop 0
	global_load_lds_dwordx4 v79, s[50:51]
	s_waitcnt vmcnt(8)
	v_add_u32_e32 v54, s78, v59
	v_add_u32_e32 v55, s78, v60
	v_add_u32_e32 v56, s78, v61
	v_add_u32_e32 v57, s78, v62
	ds_read_b64_tr_b4 v[46:47], v160
	ds_read_b64_tr_b4 v[48:49], v160 offset:1024
	ds_read_b64_tr_b4 v[122:123], v54
	ds_read_b64_tr_b4 v[124:125], v55
	ds_read_b64_tr_b4 v[126:127], v56
	ds_read_b64_tr_b4 v[128:129], v57
	s_waitcnt lgkmcnt(6)
	v_dot8c_i32_i4_e32 v38, v130, v52
	v_dot8c_i32_i4_e32 v39, v130, v50
	v_dot8c_i32_i4_e32 v40, v132, v52
	v_dot8c_i32_i4_e32 v41, v132, v50
	v_dot8c_i32_i4_e32 v42, v134, v52
	v_dot8c_i32_i4_e32 v43, v134, v50
	v_dot8c_i32_i4_e32 v44, v136, v52
	v_dot8c_i32_i4_e32 v45, v136, v50
	v_dot8c_i32_i4_e32 v38, v131, v53
	v_dot8c_i32_i4_e32 v39, v131, v51
	v_dot8c_i32_i4_e32 v40, v133, v53
	v_dot8c_i32_i4_e32 v41, v133, v51
	v_dot8c_i32_i4_e32 v42, v135, v53
	v_dot8c_i32_i4_e32 v43, v135, v51
	v_dot8c_i32_i4_e32 v44, v137, v53
	v_dot8c_i32_i4_e32 v45, v137, v51
	s_nop 3
	s_waitcnt lgkmcnt(15)
	v_lshlrev_b32_e32 v38, 5, v38
	v_lshlrev_b32_e32 v39, 1, v39
	v_add3_u32 v38, v39, v229, v38
	v_cvt_f32_i32_e32 v38, v38
	v_mul_f32_e32 v38, v228, v38
	v_lshlrev_b32_e32 v40, 5, v40
	v_lshlrev_b32_e32 v41, 1, v41
	v_add3_u32 v40, v41, v229, v40
	v_cvt_f32_i32_e32 v40, v40
	v_mul_f32_e32 v40, v228, v40
	v_lshlrev_b32_e32 v42, 5, v42
	v_lshlrev_b32_e32 v43, 1, v43
	v_add3_u32 v42, v43, v229, v42
	v_cvt_f32_i32_e32 v42, v42
	v_mul_f32_e32 v42, v228, v42
	v_lshlrev_b32_e32 v44, 5, v44
	v_lshlrev_b32_e32 v45, 1, v45
	v_add3_u32 v44, v45, v229, v44
	v_cvt_f32_i32_e32 v44, v44
	v_mul_f32_e32 v44, v228, v44
	v_cvt_pk_bf16_f32 v182, v38, v40
	v_cvt_pk_bf16_f32 v183, v42, v44
	ds_read_b128 v[252:255], v156 offset:1024
	s_add_i32 s44, s40, 0
	s_ashr_i32 s45, s44, 31
	s_lshl_b64 s[44:45], s[44:45], 12
	v_lshl_add_u64 v[80:81], v[36:37], 0, s[44:45]
	s_waitcnt lgkmcnt(0)
	v_mul_f32_e32 v222, v222, v252
	v_mul_f32_e32 v223, v223, v253
	v_mul_f32_e32 v224, v224, v254
	v_mul_f32_e32 v225, v225, v255
	global_store_dwordx4 v[80:81], v[222:225], off offset:3072 nt
	ds_read_b128 v[252:255], v155
	s_add_i32 s44, s40, 8
	s_ashr_i32 s45, s44, 31
	s_lshl_b64 s[44:45], s[44:45], 12
	v_lshl_add_u64 v[80:81], v[36:37], 0, s[44:45]
	s_waitcnt lgkmcnt(0)
	v_mul_f32_e32 v236, v236, v252
	v_mul_f32_e32 v237, v237, v253
	v_mul_f32_e32 v238, v238, v254
	v_mul_f32_e32 v239, v239, v255
	global_store_dwordx4 v[80:81], v[236:239], off nt
	v_add_u32_e32 v147, 8, v140
	v_and_b32_e32 v146, 15, v147
	v_xor_b32_e32 v146, 8, v146
	v_bfe_u32 v148, v147, 4, 4
	v_mul_lo_u32 v146, v146, s92
	v_mul_lo_u32 v148, v148, s92
	v_mov_b32_e32 v147, v146
	v_mov_b32_e32 v149, v148
	ds_write2st64_b64 v77, v[146:147], v[148:149] offset1:2
	v_add_u32_e32 v138, 0x800, v74
	ds_read_u8 v139, v138
	v_add_u32_e32 v141, 0x800, v73
	ds_read_u8 v140, v141
	s_add_i32 s43, s67, 96
	v_mov_b32_e32 v138, s43
	ds_read2st64_b32 v[228:229], v138 offset1:1
	ds_read_b128 v[18:21], v227 offset:4096
	ds_read_b128 v[22:25], v227 offset:4112
	v_add_u32_e32 v152, 0x600000, v63
	v_add_u32_e32 v153, 0x600000, v64
	v_mov_b32_e32 v38, 0
	v_mov_b32_e32 v39, 0
	v_mov_b32_e32 v40, 0
	v_mov_b32_e32 v41, 0
	v_mov_b32_e32 v42, 0
	v_mov_b32_e32 v43, 0
	v_mov_b32_e32 v44, 0
	v_mov_b32_e32 v45, 0
	v_and_b32_e32 v78, 0xffff, v31
	v_lshrrev_b32_e32 v79, 16, v31
	v_lshl_add_u32 v78, v78, 7, v150
	v_lshl_add_u32 v79, v79, 7, v151
	s_mov_b32 m0, s77
	s_add_i32 s43, s77, 0x400
	global_load_lds_dwordx4 v78, s[50:51]
	s_mov_b32 m0, s43
	s_nop 0
	global_load_lds_dwordx4 v79, s[50:51]
	s_waitcnt vmcnt(10)
; #define TR4(p_) __builtin_amdgcn_ds_read_tr4_b64_v2i32((LAS v2i*)(p_))
; #define VDMA(st_, k_) do { _Pragma("unroll") for (int i_ = 0; i_ < 4; ++i_) { \
;         const unsigned off_ = (unsigned)((st_) >> 2) * (16384u * 128u) + (PE_ID(E, 4 * ((st_) & 3) + i_) << 7) + ((i_ & 1) ? cx1 : cx0); \
;         __builtin_amdgcn_global_load_lds((const unsigned*)(V4 + off_), (LAS unsigned*)(ldsb + BUF[k_] + 1024 * i_), 16, 0, 0); } } while (0)
; __device__ __forceinline__ void peer_v_tokens(int j, const LAS unsigned short* EL, const LAS unsigned char* AL  , const LAS float* ASC  , const LAS int* SAL  , ...
;     ...
;         for (int st = 0; st < 16; ++st) {
;             const int p = st >> 2, q = st & 3;
;             if (st < 14) VDMA(st + 2, (st + 2) % 3);
;             if (st < 14) asm volatile("s_waitcnt vmcnt(8)" ::: "memory");
;             else if (st == 14) asm volatile("s_waitcnt vmcnt(4)" ::: "memory");
;             else asm volatile("s_waitcnt vmcnt(0)" ::: "memory");
;             if (q == 0) {
; #pragma unroll
;                 for (int r = 0; r < 4; ++r) { accH[r] = 0; accL[r] = 0; } }
; #pragma unroll
;             for (int tp = 0; tp < 2; ++tp) {
;                 const v2i ao = TR4(ATL + (2 * q + tp) * 128 + 8 * s16), ah = TR4(ATL + 1024 + (2 * q + tp) * 128 + 8 * s16);
; #pragma unroll
;                 for (int r = 0; r < 4; ++r) {
;                     const v2i d = TR4(ldsb + BUF[st % 3] + 2048 * tp + roff[r]);
;                     accH[r] = __builtin_amdgcn_sdot8(d.x, ah.x, accH[r], false); accH[r] = __builtin_amdgcn_sdot8(d.y, ah.y, accH[r], false);
;                     accL[r] = __builtin_amdgcn_sdot8(d.x, ao.x, accL[r], false); accL[r] = __builtin_amdgcn_sdot8(d.y, ao.y, accL[r], false);
;                 }
;             }
	v_add_u32_e32 v54, s79, v59
	v_add_u32_e32 v55, s79, v60
	v_add_u32_e32 v56, s79, v61
	v_add_u32_e32 v57, s79, v62
	ds_read_b64_tr_b4 v[50:51], v160 offset:128
	ds_read_b64_tr_b4 v[52:53], v160 offset:1152
	ds_read_b64_tr_b4 v[130:131], v54
	ds_read_b64_tr_b4 v[132:133], v55
	ds_read_b64_tr_b4 v[134:135], v56
	ds_read_b64_tr_b4 v[136:137], v57
	s_waitcnt lgkmcnt(14)
	v_dot8c_i32_i4_e32 v38, v122, v48
	v_dot8c_i32_i4_e32 v39, v122, v46
	v_dot8c_i32_i4_e32 v40, v124, v48
	v_dot8c_i32_i4_e32 v41, v124, v46
	v_dot8c_i32_i4_e32 v42, v126, v48
	v_dot8c_i32_i4_e32 v43, v126, v46
	v_dot8c_i32_i4_e32 v44, v128, v48
	v_dot8c_i32_i4_e32 v45, v128, v46
	v_dot8c_i32_i4_e32 v38, v123, v49
	v_dot8c_i32_i4_e32 v39, v123, v47
	v_dot8c_i32_i4_e32 v40, v125, v49
	v_dot8c_i32_i4_e32 v41, v125, v47
	v_dot8c_i32_i4_e32 v42, v127, v49
	v_dot8c_i32_i4_e32 v43, v127, v47
	v_dot8c_i32_i4_e32 v44, v129, v49
	v_dot8c_i32_i4_e32 v45, v129, v47
	v_and_b32_e32 v78, 0xffff, v32
	v_lshrrev_b32_e32 v79, 16, v32
	v_lshl_add_u32 v78, v78, 7, v150
	v_lshl_add_u32 v79, v79, 7, v151
	s_mov_b32 m0, s78
	s_add_i32 s43, s78, 0x400
	global_load_lds_dwordx4 v78, s[50:51]
	s_mov_b32 m0, s43
	s_nop 0
	global_load_lds_dwordx4 v79, s[50:51]
	s_waitcnt vmcnt(10)
	v_add_u32_e32 v54, s98, v59
	v_add_u32_e32 v55, s98, v60
	v_add_u32_e32 v56, s98, v61
	v_add_u32_e32 v57, s98, v62
	ds_read_b64_tr_b4 v[46:47], v160 offset:256
	ds_read_b64_tr_b4 v[48:49], v160 offset:1280
	ds_read_b64_tr_b4 v[122:123], v54
	ds_read_b64_tr_b4 v[124:125], v55
	ds_read_b64_tr_b4 v[126:127], v56
	ds_read_b64_tr_b4 v[128:129], v57
	s_waitcnt lgkmcnt(6)
	v_dot8c_i32_i4_e32 v38, v130, v52
	v_dot8c_i32_i4_e32 v39, v130, v50
	v_dot8c_i32_i4_e32 v40, v132, v52
	v_dot8c_i32_i4_e32 v41, v132, v50
	v_dot8c_i32_i4_e32 v42, v134, v52
	v_dot8c_i32_i4_e32 v43, v134, v50
	v_dot8c_i32_i4_e32 v44, v136, v52
	v_dot8c_i32_i4_e32 v45, v136, v50
	v_dot8c_i32_i4_e32 v38, v131, v53
	v_dot8c_i32_i4_e32 v39, v131, v51
	v_dot8c_i32_i4_e32 v40, v133, v53
	v_dot8c_i32_i4_e32 v41, v133, v51
	v_dot8c_i32_i4_e32 v42, v135, v53
	v_dot8c_i32_i4_e32 v43, v135, v51
	v_dot8c_i32_i4_e32 v44, v137, v53
	v_dot8c_i32_i4_e32 v45, v137, v51
	v_and_b32_e32 v78, 0xffff, v33
	v_lshrrev_b32_e32 v79, 16, v33
	v_lshl_add_u32 v78, v78, 7, v150
	v_lshl_add_u32 v79, v79, 7, v151
	s_mov_b32 m0, s79
	s_add_i32 s43, s79, 0x400
	global_load_lds_dwordx4 v78, s[50:51]
	s_mov_b32 m0, s43
	s_nop 0
	global_load_lds_dwordx4 v79, s[50:51]
	s_waitcnt vmcnt(10)
	v_add_u32_e32 v54, s99, v59
	v_add_u32_e32 v55, s99, v60
	v_add_u32_e32 v56, s99, v61
	v_add_u32_e32 v57, s99, v62
	ds_read_b64_tr_b4 v[50:51], v160 offset:384
	ds_read_b64_tr_b4 v[52:53], v160 offset:1408
	ds_read_b64_tr_b4 v[130:131], v54
	ds_read_b64_tr_b4 v[132:133], v55
	ds_read_b64_tr_b4 v[134:135], v56
	ds_read_b64_tr_b4 v[136:137], v57
	s_waitcnt lgkmcnt(6)
	v_dot8c_i32_i4_e32 v38, v122, v48
	v_dot8c_i32_i4_e32 v39, v122, v46
	v_dot8c_i32_i4_e32 v40, v124, v48
	v_dot8c_i32_i4_e32 v41, v124, v46
	v_dot8c_i32_i4_e32 v42, v126, v48
	v_dot8c_i32_i4_e32 v43, v126, v46
	v_dot8c_i32_i4_e32 v44, v128, v48
	v_dot8c_i32_i4_e32 v45, v128, v46
	v_dot8c_i32_i4_e32 v38, v123, v49
	v_dot8c_i32_i4_e32 v39, v123, v47
	v_dot8c_i32_i4_e32 v40, v125, v49
	v_dot8c_i32_i4_e32 v41, v125, v47
	v_dot8c_i32_i4_e32 v42, v127, v49
	v_dot8c_i32_i4_e32 v43, v127, v47
	v_dot8c_i32_i4_e32 v44, v129, v49
	v_dot8c_i32_i4_e32 v45, v129, v47
	s_waitcnt lgkmcnt(15)
	v_and_b32_e32 v78, 0xffff, v18
	v_lshrrev_b32_e32 v79, 16, v18
	v_lshl_add_u32 v78, v78, 7, v152
	v_lshl_add_u32 v79, v79, 7, v153
	s_mov_b32 m0, s98
	s_add_i32 s43, s98, 0x400
	global_load_lds_dwordx4 v78, s[50:51]
	s_mov_b32 m0, s43
	s_nop 0
	global_load_lds_dwordx4 v79, s[50:51]
	s_waitcnt vmcnt(10)
	v_add_u32_e32 v54, s76, v59
	v_add_u32_e32 v55, s76, v60
	v_add_u32_e32 v56, s76, v61
	v_add_u32_e32 v57, s76, v62
	ds_read_b64_tr_b4 v[46:47], v160 offset:512
	ds_read_b64_tr_b4 v[48:49], v160 offset:1536
	ds_read_b64_tr_b4 v[122:123], v54
	ds_read_b64_tr_b4 v[124:125], v55
	ds_read_b64_tr_b4 v[126:127], v56
	ds_read_b64_tr_b4 v[128:129], v57
	s_waitcnt lgkmcnt(6)
	v_dot8c_i32_i4_e32 v38, v130, v52
	v_dot8c_i32_i4_e32 v39, v130, v50
	v_dot8c_i32_i4_e32 v40, v132, v52
	v_dot8c_i32_i4_e32 v41, v132, v50
	v_dot8c_i32_i4_e32 v42, v134, v52
	v_dot8c_i32_i4_e32 v43, v134, v50
	v_dot8c_i32_i4_e32 v44, v136, v52
	v_dot8c_i32_i4_e32 v45, v136, v50
	v_dot8c_i32_i4_e32 v38, v131, v53
	v_dot8c_i32_i4_e32 v39, v131, v51
	v_dot8c_i32_i4_e32 v40, v133, v53
	v_dot8c_i32_i4_e32 v41, v133, v51
	v_dot8c_i32_i4_e32 v42, v135, v53
	v_dot8c_i32_i4_e32 v43, v135, v51
	v_dot8c_i32_i4_e32 v44, v137, v53
	v_dot8c_i32_i4_e32 v45, v137, v51
	v_and_b32_e32 v78, 0xffff, v19
	v_lshrrev_b32_e32 v79, 16, v19
	v_lshl_add_u32 v78, v78, 7, v152
	v_lshl_add_u32 v79, v79, 7, v153
	s_mov_b32 m0, s99
	s_add_i32 s43, s99, 0x400
	global_load_lds_dwordx4 v78, s[50:51]
	s_mov_b32 m0, s43
	s_nop 0
	global_load_lds_dwordx4 v79, s[50:51]
	s_waitcnt vmcnt(8)
	v_add_u32_e32 v54, s77, v59
	v_add_u32_e32 v55, s77, v60
	v_add_u32_e32 v56, s77, v61
	v_add_u32_e32 v57, s77, v62
	ds_read_b64_tr_b4 v[50:51], v160 offset:640
	ds_read_b64_tr_b4 v[52:53], v160 offset:1664
	ds_read_b64_tr_b4 v[130:131], v54
	ds_read_b64_tr_b4 v[132:133], v55
	ds_read_b64_tr_b4 v[134:135], v56
	ds_read_b64_tr_b4 v[136:137], v57
	s_waitcnt lgkmcnt(6)
	v_dot8c_i32_i4_e32 v38, v122, v48
	v_dot8c_i32_i4_e32 v39, v122, v46
	v_dot8c_i32_i4_e32 v40, v124, v48
	v_dot8c_i32_i4_e32 v41, v124, v46
	v_dot8c_i32_i4_e32 v42, v126, v48
	v_dot8c_i32_i4_e32 v43, v126, v46
	v_dot8c_i32_i4_e32 v44, v128, v48
	v_dot8c_i32_i4_e32 v45, v128, v46
	v_dot8c_i32_i4_e32 v38, v123, v49
	v_dot8c_i32_i4_e32 v39, v123, v47
	v_dot8c_i32_i4_e32 v40, v125, v49
	v_dot8c_i32_i4_e32 v41, v125, v47
	v_dot8c_i32_i4_e32 v42, v127, v49
	v_dot8c_i32_i4_e32 v43, v127, v47
	v_dot8c_i32_i4_e32 v44, v129, v49
	v_dot8c_i32_i4_e32 v45, v129, v47
	s_waitcnt lgkmcnt(15)
; __device__ __forceinline__ bf16 f2bf(float f) { return (bf16)f2bfu(f); }
; #define TR4(p_) __builtin_amdgcn_ds_read_tr4_b64_v2i32((LAS v2i*)(p_))
; __device__ __forceinline__ void peer_v_tokens(int j, const LAS unsigned short* EL, const LAS unsigned char* AL  , const LAS float* ASC  , const LAS int* SAL  , ...
;     ...
;         for (int st = 0; st < 16; ++st) {
;             const int p = st >> 2, q = st & 3;
;             if (st < 14) VDMA(st + 2, (st + 2) % 3);
;             if (st < 14) asm volatile("s_waitcnt vmcnt(8)" ::: "memory");
;             else if (st == 14) asm volatile("s_waitcnt vmcnt(4)" ::: "memory");
;             else asm volatile("s_waitcnt vmcnt(0)" ::: "memory");
;             if (q == 0) {
; #pragma unroll
;                 for (int r = 0; r < 4; ++r) { accH[r] = 0; accL[r] = 0; } }
; #pragma unroll
;             for (int tp = 0; tp < 2; ++tp) {
;                 const v2i ao = TR4(ATL + (2 * q + tp) * 128 + 8 * s16), ah = TR4(ATL + 1024 + (2 * q + tp) * 128 + 8 * s16);
; #pragma unroll
;                 for (int r = 0; r < 4; ++r) {
;                     const v2i d = TR4(ldsb + BUF[st % 3] + 2048 * tp + roff[r]);
;                     accH[r] = __builtin_amdgcn_sdot8(d.x, ah.x, accH[r], false); accH[r] = __builtin_amdgcn_sdot8(d.y, ah.y, accH[r], false);
;                     accL[r] = __builtin_amdgcn_sdot8(d.x, ao.x, accL[r], false); accL[r] = __builtin_amdgcn_sdot8(d.y, ao.y, accL[r], false);
;                 }
;             }
;             asm volatile("s_waitcnt lgkmcnt(0)" ::: "memory");
;             if (q == 3) {
; #pragma unroll
;                 for (int r = 0; r < 4; ++r) STASH[256 * p + 16 * (grp + 4 * r) + pc] = f2bf(asc * (float)(2 * ((accH[r] << 4) + accL[r]) + sa));
;     ...
;             float4* op = (float4*)(outp + (size_t)t * D) + lane;
; #pragma unroll
;             for (int jq = 0; jq < 4; ++jq) { typedef float f4v __attribute__((ext_vector_type(4))); f4v o4; o4.x = v[jq].x * r3 * gv[jq].x; o4.y = v[jq].y * r3 * gv[jq].y; o4.z = v[jq].z * r3 * gv[jq].z; o4.w = v[jq].w * r3 * gv[jq].w;
;                 __builtin_nontemporal_store(o4, (f4v*)op + 64 * jq); }
	v_add_u32_e32 v143, 8, v139
	v_and_b32_e32 v142, 15, v143
	v_xor_b32_e32 v142, 8, v142
	v_bfe_u32 v144, v143, 4, 4
	v_mul_lo_u32 v142, v142, s92
	v_mul_lo_u32 v144, v144, s92
	v_mov_b32_e32 v143, v142
	v_mov_b32_e32 v145, v144
	ds_write2st64_b64 v159, v[142:143], v[144:145] offset1:2
	v_and_b32_e32 v78, 0xffff, v20
	v_lshrrev_b32_e32 v79, 16, v20
	v_lshl_add_u32 v78, v78, 7, v152
	v_lshl_add_u32 v79, v79, 7, v153
	s_mov_b32 m0, s76
	s_add_i32 s43, s76, 0x400
	global_load_lds_dwordx4 v78, s[50:51]
	s_mov_b32 m0, s43
	s_nop 0
	global_load_lds_dwordx4 v79, s[50:51]
	s_waitcnt vmcnt(8)
	v_add_u32_e32 v54, s78, v59
	v_add_u32_e32 v55, s78, v60
	v_add_u32_e32 v56, s78, v61
	v_add_u32_e32 v57, s78, v62
	ds_read_b64_tr_b4 v[46:47], v160 offset:768
	ds_read_b64_tr_b4 v[48:49], v160 offset:1792
	ds_read_b64_tr_b4 v[122:123], v54
	ds_read_b64_tr_b4 v[124:125], v55
	ds_read_b64_tr_b4 v[126:127], v56
	ds_read_b64_tr_b4 v[128:129], v57
	s_waitcnt lgkmcnt(7)
	v_dot8c_i32_i4_e32 v38, v130, v52
	v_dot8c_i32_i4_e32 v39, v130, v50
	v_dot8c_i32_i4_e32 v40, v132, v52
	v_dot8c_i32_i4_e32 v41, v132, v50
	v_dot8c_i32_i4_e32 v42, v134, v52
	v_dot8c_i32_i4_e32 v43, v134, v50
	v_dot8c_i32_i4_e32 v44, v136, v52
	v_dot8c_i32_i4_e32 v45, v136, v50
	v_dot8c_i32_i4_e32 v38, v131, v53
	v_dot8c_i32_i4_e32 v39, v131, v51
	v_dot8c_i32_i4_e32 v40, v133, v53
	v_dot8c_i32_i4_e32 v41, v133, v51
	v_dot8c_i32_i4_e32 v42, v135, v53
	v_dot8c_i32_i4_e32 v43, v135, v51
	v_dot8c_i32_i4_e32 v44, v137, v53
	v_dot8c_i32_i4_e32 v45, v137, v51
	v_and_b32_e32 v78, 0xffff, v21
	v_lshrrev_b32_e32 v79, 16, v21
	v_lshl_add_u32 v78, v78, 7, v152
	v_lshl_add_u32 v79, v79, 7, v153
	s_mov_b32 m0, s77
	s_add_i32 s43, s77, 0x400
	global_load_lds_dwordx4 v78, s[50:51]
	s_mov_b32 m0, s43
	s_nop 0
	global_load_lds_dwordx4 v79, s[50:51]
	s_waitcnt vmcnt(8)
	v_add_u32_e32 v54, s79, v59
	v_add_u32_e32 v55, s79, v60
	v_add_u32_e32 v56, s79, v61
	v_add_u32_e32 v57, s79, v62
	ds_read_b64_tr_b4 v[50:51], v160 offset:896
	ds_read_b64_tr_b4 v[52:53], v160 offset:1920
	ds_read_b64_tr_b4 v[130:131], v54
	ds_read_b64_tr_b4 v[132:133], v55
	ds_read_b64_tr_b4 v[134:135], v56
	ds_read_b64_tr_b4 v[136:137], v57
	s_waitcnt lgkmcnt(6)
	v_dot8c_i32_i4_e32 v38, v122, v48
	v_dot8c_i32_i4_e32 v39, v122, v46
	v_dot8c_i32_i4_e32 v40, v124, v48
	v_dot8c_i32_i4_e32 v41, v124, v46
	v_dot8c_i32_i4_e32 v42, v126, v48
	v_dot8c_i32_i4_e32 v43, v126, v46
	v_dot8c_i32_i4_e32 v44, v128, v48
	v_dot8c_i32_i4_e32 v45, v128, v46
	v_dot8c_i32_i4_e32 v38, v123, v49
	v_dot8c_i32_i4_e32 v39, v123, v47
	v_dot8c_i32_i4_e32 v40, v125, v49
	v_dot8c_i32_i4_e32 v41, v125, v47
	v_dot8c_i32_i4_e32 v42, v127, v49
	v_dot8c_i32_i4_e32 v43, v127, v47
	v_dot8c_i32_i4_e32 v44, v129, v49
	v_dot8c_i32_i4_e32 v45, v129, v47
	v_and_b32_e32 v78, 0xffff, v22
	v_lshrrev_b32_e32 v79, 16, v22
	v_lshl_add_u32 v78, v78, 7, v152
	v_lshl_add_u32 v79, v79, 7, v153
	s_mov_b32 m0, s78
	s_add_i32 s43, s78, 0x400
	global_load_lds_dwordx4 v78, s[50:51]
	s_mov_b32 m0, s43
	s_nop 0
	global_load_lds_dwordx4 v79, s[50:51]
	s_waitcnt vmcnt(8)
	v_add_u32_e32 v54, s98, v59
	v_add_u32_e32 v55, s98, v60
	v_add_u32_e32 v56, s98, v61
	v_add_u32_e32 v57, s98, v62
	ds_read_b64_tr_b4 v[46:47], v160
	ds_read_b64_tr_b4 v[48:49], v160 offset:1024
	ds_read_b64_tr_b4 v[122:123], v54
	ds_read_b64_tr_b4 v[124:125], v55
	ds_read_b64_tr_b4 v[126:127], v56
	ds_read_b64_tr_b4 v[128:129], v57
	s_waitcnt lgkmcnt(6)
	v_dot8c_i32_i4_e32 v38, v130, v52
	v_dot8c_i32_i4_e32 v39, v130, v50
	v_dot8c_i32_i4_e32 v40, v132, v52
	v_dot8c_i32_i4_e32 v41, v132, v50
	v_dot8c_i32_i4_e32 v42, v134, v52
	v_dot8c_i32_i4_e32 v43, v134, v50
	v_dot8c_i32_i4_e32 v44, v136, v52
	v_dot8c_i32_i4_e32 v45, v136, v50
	v_dot8c_i32_i4_e32 v38, v131, v53
	v_dot8c_i32_i4_e32 v39, v131, v51
	v_dot8c_i32_i4_e32 v40, v133, v53
	v_dot8c_i32_i4_e32 v41, v133, v51
	v_dot8c_i32_i4_e32 v42, v135, v53
	v_dot8c_i32_i4_e32 v43, v135, v51
	v_dot8c_i32_i4_e32 v44, v137, v53
	v_dot8c_i32_i4_e32 v45, v137, v51
	s_nop 3
	s_waitcnt lgkmcnt(15)
	v_lshlrev_b32_e32 v38, 5, v38
	v_lshlrev_b32_e32 v39, 1, v39
	v_add3_u32 v38, v39, v229, v38
	v_cvt_f32_i32_e32 v38, v38
	v_mul_f32_e32 v38, v228, v38
	v_lshlrev_b32_e32 v40, 5, v40
	v_lshlrev_b32_e32 v41, 1, v41
	v_add3_u32 v40, v41, v229, v40
	v_cvt_f32_i32_e32 v40, v40
	v_mul_f32_e32 v40, v228, v40
	v_lshlrev_b32_e32 v42, 5, v42
	v_lshlrev_b32_e32 v43, 1, v43
	v_add3_u32 v42, v43, v229, v42
	v_cvt_f32_i32_e32 v42, v42
	v_mul_f32_e32 v42, v228, v42
	v_lshlrev_b32_e32 v44, 5, v44
	v_lshlrev_b32_e32 v45, 1, v45
	v_add3_u32 v44, v45, v229, v44
	v_cvt_f32_i32_e32 v44, v44
	v_mul_f32_e32 v44, v228, v44
	v_cvt_pk_bf16_f32 v190, v38, v40
	v_cvt_pk_bf16_f32 v191, v42, v44
	ds_read_b128 v[252:255], v155 offset:1024
	s_add_i32 s44, s40, 8
	s_ashr_i32 s45, s44, 31
	s_lshl_b64 s[44:45], s[44:45], 12
	v_lshl_add_u64 v[80:81], v[36:37], 0, s[44:45]
	s_waitcnt lgkmcnt(0)
	v_mul_f32_e32 v240, v240, v252
	v_mul_f32_e32 v241, v241, v253
	v_mul_f32_e32 v242, v242, v254
	v_mul_f32_e32 v243, v243, v255
	global_store_dwordx4 v[80:81], v[240:243], off offset:1024 nt
	v_add_u32_e32 v147, 8, v140
	v_and_b32_e32 v146, 15, v147
	v_xor_b32_e32 v146, 8, v146
	v_bfe_u32 v148, v147, 4, 4
	v_mul_lo_u32 v146, v146, s92
	v_mul_lo_u32 v148, v148, s92
	v_mov_b32_e32 v147, v146
	v_mov_b32_e32 v149, v148
	ds_write2st64_b64 v77, v[146:147], v[148:149] offset1:2
	v_add_u32_e32 v138, 0xc00, v74
	ds_read_u8 v139, v138
	v_add_u32_e32 v141, 0xc00, v73
	ds_read_u8 v140, v141
	s_add_i32 s43, s67, 64
	v_mov_b32_e32 v138, s43
	ds_read2st64_b32 v[228:229], v138 offset1:1
	ds_read_b128 v[26:29], v227 offset:6144
	ds_read_b128 v[30:33], v227 offset:6160
	v_mov_b32_e32 v38, 0
	v_mov_b32_e32 v39, 0
	v_mov_b32_e32 v40, 0
	v_mov_b32_e32 v41, 0
	v_mov_b32_e32 v42, 0
	v_mov_b32_e32 v43, 0
	v_mov_b32_e32 v44, 0
	v_mov_b32_e32 v45, 0
	v_and_b32_e32 v78, 0xffff, v23
	v_lshrrev_b32_e32 v79, 16, v23
	v_lshl_add_u32 v78, v78, 7, v152
	v_lshl_add_u32 v79, v79, 7, v153
	s_mov_b32 m0, s79
	s_add_i32 s43, s79, 0x400
	global_load_lds_dwordx4 v78, s[50:51]
	s_mov_b32 m0, s43
	s_nop 0
	global_load_lds_dwordx4 v79, s[50:51]
	s_waitcnt vmcnt(9)
; #define TR4(p_) __builtin_amdgcn_ds_read_tr4_b64_v2i32((LAS v2i*)(p_))
; #define VDMA(st_, k_) do { _Pragma("unroll") for (int i_ = 0; i_ < 4; ++i_) { \
;         const unsigned off_ = (unsigned)((st_) >> 2) * (16384u * 128u) + (PE_ID(E, 4 * ((st_) & 3) + i_) << 7) + ((i_ & 1) ? cx1 : cx0); \
;         __builtin_amdgcn_global_load_lds((const unsigned*)(V4 + off_), (LAS unsigned*)(ldsb + BUF[k_] + 1024 * i_), 16, 0, 0); } } while (0)
; __device__ __forceinline__ void peer_v_tokens(int j, const LAS unsigned short* EL, const LAS unsigned char* AL  , const LAS float* ASC  , const LAS int* SAL  , ...
;     ...
;         for (int st = 0; st < 16; ++st) {
;             const int p = st >> 2, q = st & 3;
;             if (st < 14) VDMA(st + 2, (st + 2) % 3);
;             if (st < 14) asm volatile("s_waitcnt vmcnt(8)" ::: "memory");
;             else if (st == 14) asm volatile("s_waitcnt vmcnt(4)" ::: "memory");
;             else asm volatile("s_waitcnt vmcnt(0)" ::: "memory");
;             if (q == 0) {
; #pragma unroll
;                 for (int r = 0; r < 4; ++r) { accH[r] = 0; accL[r] = 0; } }
; #pragma unroll
;             for (int tp = 0; tp < 2; ++tp) {
;                 const v2i ao = TR4(ATL + (2 * q + tp) * 128 + 8 * s16), ah = TR4(ATL + 1024 + (2 * q + tp) * 128 + 8 * s16);
; #pragma unroll
;                 for (int r = 0; r < 4; ++r) {
;                     const v2i d = TR4(ldsb + BUF[st % 3] + 2048 * tp + roff[r]);
;                     accH[r] = __builtin_amdgcn_sdot8(d.x, ah.x, accH[r], false); accH[r] = __builtin_amdgcn_sdot8(d.y, ah.y, accH[r], false);
;                     accL[r] = __builtin_amdgcn_sdot8(d.x, ao.x, accL[r], false); accL[r] = __builtin_amdgcn_sdot8(d.y, ao.y, accL[r], false);
;                 }
;             }
	v_add_u32_e32 v54, s99, v59
	v_add_u32_e32 v55, s99, v60
	v_add_u32_e32 v56, s99, v61
	v_add_u32_e32 v57, s99, v62
	ds_read_b64_tr_b4 v[50:51], v160 offset:128
	ds_read_b64_tr_b4 v[52:53], v160 offset:1152
	ds_read_b64_tr_b4 v[130:131], v54
	ds_read_b64_tr_b4 v[132:133], v55
	ds_read_b64_tr_b4 v[134:135], v56
	ds_read_b64_tr_b4 v[136:137], v57
	s_waitcnt lgkmcnt(13)
	v_dot8c_i32_i4_e32 v38, v122, v48
	v_dot8c_i32_i4_e32 v39, v122, v46
	v_dot8c_i32_i4_e32 v40, v124, v48
	v_dot8c_i32_i4_e32 v41, v124, v46
	v_dot8c_i32_i4_e32 v42, v126, v48
	v_dot8c_i32_i4_e32 v43, v126, v46
	v_dot8c_i32_i4_e32 v44, v128, v48
	v_dot8c_i32_i4_e32 v45, v128, v46
	v_dot8c_i32_i4_e32 v38, v123, v49
	v_dot8c_i32_i4_e32 v39, v123, v47
	v_dot8c_i32_i4_e32 v40, v125, v49
	v_dot8c_i32_i4_e32 v41, v125, v47
	v_dot8c_i32_i4_e32 v42, v127, v49
	v_dot8c_i32_i4_e32 v43, v127, v47
	v_dot8c_i32_i4_e32 v44, v129, v49
	v_dot8c_i32_i4_e32 v45, v129, v47
	v_and_b32_e32 v78, 0xffff, v24
	v_lshrrev_b32_e32 v79, 16, v24
	v_lshl_add_u32 v78, v78, 7, v152
	v_lshl_add_u32 v79, v79, 7, v153
	s_mov_b32 m0, s98
	s_add_i32 s43, s98, 0x400
	global_load_lds_dwordx4 v78, s[50:51]
	s_mov_b32 m0, s43
	s_nop 0
	global_load_lds_dwordx4 v79, s[50:51]
	s_waitcnt vmcnt(9)
	v_add_u32_e32 v54, s76, v59
	v_add_u32_e32 v55, s76, v60
	v_add_u32_e32 v56, s76, v61
	v_add_u32_e32 v57, s76, v62
	ds_read_b64_tr_b4 v[46:47], v160 offset:256
	ds_read_b64_tr_b4 v[48:49], v160 offset:1280
	ds_read_b64_tr_b4 v[122:123], v54
	ds_read_b64_tr_b4 v[124:125], v55
	ds_read_b64_tr_b4 v[126:127], v56
	ds_read_b64_tr_b4 v[128:129], v57
	s_waitcnt lgkmcnt(6)
	v_dot8c_i32_i4_e32 v38, v130, v52
	v_dot8c_i32_i4_e32 v39, v130, v50
	v_dot8c_i32_i4_e32 v40, v132, v52
	v_dot8c_i32_i4_e32 v41, v132, v50
	v_dot8c_i32_i4_e32 v42, v134, v52
	v_dot8c_i32_i4_e32 v43, v134, v50
	v_dot8c_i32_i4_e32 v44, v136, v52
	v_dot8c_i32_i4_e32 v45, v136, v50
	v_dot8c_i32_i4_e32 v38, v131, v53
	v_dot8c_i32_i4_e32 v39, v131, v51
	v_dot8c_i32_i4_e32 v40, v133, v53
	v_dot8c_i32_i4_e32 v41, v133, v51
	v_dot8c_i32_i4_e32 v42, v135, v53
	v_dot8c_i32_i4_e32 v43, v135, v51
	v_dot8c_i32_i4_e32 v44, v137, v53
	v_dot8c_i32_i4_e32 v45, v137, v51
	v_and_b32_e32 v78, 0xffff, v25
	v_lshrrev_b32_e32 v79, 16, v25
	v_lshl_add_u32 v78, v78, 7, v152
	v_lshl_add_u32 v79, v79, 7, v153
	s_mov_b32 m0, s99
	s_add_i32 s43, s99, 0x400
	global_load_lds_dwordx4 v78, s[50:51]
	s_mov_b32 m0, s43
	s_nop 0
	global_load_lds_dwordx4 v79, s[50:51]
	s_waitcnt vmcnt(9)
	v_add_u32_e32 v54, s77, v59
	v_add_u32_e32 v55, s77, v60
	v_add_u32_e32 v56, s77, v61
	v_add_u32_e32 v57, s77, v62
	ds_read_b64_tr_b4 v[50:51], v160 offset:384
	ds_read_b64_tr_b4 v[52:53], v160 offset:1408
	ds_read_b64_tr_b4 v[130:131], v54
	ds_read_b64_tr_b4 v[132:133], v55
	ds_read_b64_tr_b4 v[134:135], v56
	ds_read_b64_tr_b4 v[136:137], v57
	s_waitcnt lgkmcnt(6)
	v_dot8c_i32_i4_e32 v38, v122, v48
	v_dot8c_i32_i4_e32 v39, v122, v46
	v_dot8c_i32_i4_e32 v40, v124, v48
	v_dot8c_i32_i4_e32 v41, v124, v46
	v_dot8c_i32_i4_e32 v42, v126, v48
	v_dot8c_i32_i4_e32 v43, v126, v46
	v_dot8c_i32_i4_e32 v44, v128, v48
	v_dot8c_i32_i4_e32 v45, v128, v46
	v_dot8c_i32_i4_e32 v38, v123, v49
	v_dot8c_i32_i4_e32 v39, v123, v47
	v_dot8c_i32_i4_e32 v40, v125, v49
	v_dot8c_i32_i4_e32 v41, v125, v47
	v_dot8c_i32_i4_e32 v42, v127, v49
	v_dot8c_i32_i4_e32 v43, v127, v47
	v_dot8c_i32_i4_e32 v44, v129, v49
	v_dot8c_i32_i4_e32 v45, v129, v47
	s_waitcnt lgkmcnt(15)
	v_and_b32_e32 v78, 0xffff, v26
	v_lshrrev_b32_e32 v79, 16, v26
	v_lshl_add_u32 v78, v78, 7, v152
	v_lshl_add_u32 v79, v79, 7, v153
	s_mov_b32 m0, s76
	s_add_i32 s43, s76, 0x400
	global_load_lds_dwordx4 v78, s[50:51]
	s_mov_b32 m0, s43
	s_nop 0
	global_load_lds_dwordx4 v79, s[50:51]
	s_waitcnt vmcnt(9)
	v_add_u32_e32 v54, s78, v59
	v_add_u32_e32 v55, s78, v60
	v_add_u32_e32 v56, s78, v61
	v_add_u32_e32 v57, s78, v62
	ds_read_b64_tr_b4 v[46:47], v160 offset:512
	ds_read_b64_tr_b4 v[48:49], v160 offset:1536
	ds_read_b64_tr_b4 v[122:123], v54
	ds_read_b64_tr_b4 v[124:125], v55
	ds_read_b64_tr_b4 v[126:127], v56
	ds_read_b64_tr_b4 v[128:129], v57
	s_waitcnt lgkmcnt(6)
	v_dot8c_i32_i4_e32 v38, v130, v52
	v_dot8c_i32_i4_e32 v39, v130, v50
	v_dot8c_i32_i4_e32 v40, v132, v52
	v_dot8c_i32_i4_e32 v41, v132, v50
	v_dot8c_i32_i4_e32 v42, v134, v52
	v_dot8c_i32_i4_e32 v43, v134, v50
	v_dot8c_i32_i4_e32 v44, v136, v52
	v_dot8c_i32_i4_e32 v45, v136, v50
	v_dot8c_i32_i4_e32 v38, v131, v53
	v_dot8c_i32_i4_e32 v39, v131, v51
	v_dot8c_i32_i4_e32 v40, v133, v53
	v_dot8c_i32_i4_e32 v41, v133, v51
	v_dot8c_i32_i4_e32 v42, v135, v53
	v_dot8c_i32_i4_e32 v43, v135, v51
	v_dot8c_i32_i4_e32 v44, v137, v53
	v_dot8c_i32_i4_e32 v45, v137, v51
	v_and_b32_e32 v78, 0xffff, v27
	v_lshrrev_b32_e32 v79, 16, v27
	v_lshl_add_u32 v78, v78, 7, v152
	v_lshl_add_u32 v79, v79, 7, v153
	s_mov_b32 m0, s77
	s_add_i32 s43, s77, 0x400
	global_load_lds_dwordx4 v78, s[50:51]
	s_mov_b32 m0, s43
	s_nop 0
	global_load_lds_dwordx4 v79, s[50:51]
	s_waitcnt vmcnt(8)
	v_add_u32_e32 v54, s79, v59
	v_add_u32_e32 v55, s79, v60
	v_add_u32_e32 v56, s79, v61
	v_add_u32_e32 v57, s79, v62
	ds_read_b64_tr_b4 v[50:51], v160 offset:640
	ds_read_b64_tr_b4 v[52:53], v160 offset:1664
	ds_read_b64_tr_b4 v[130:131], v54
	ds_read_b64_tr_b4 v[132:133], v55
	ds_read_b64_tr_b4 v[134:135], v56
	ds_read_b64_tr_b4 v[136:137], v57
	s_waitcnt lgkmcnt(6)
	v_dot8c_i32_i4_e32 v38, v122, v48
	v_dot8c_i32_i4_e32 v39, v122, v46
	v_dot8c_i32_i4_e32 v40, v124, v48
	v_dot8c_i32_i4_e32 v41, v124, v46
	v_dot8c_i32_i4_e32 v42, v126, v48
	v_dot8c_i32_i4_e32 v43, v126, v46
	v_dot8c_i32_i4_e32 v44, v128, v48
	v_dot8c_i32_i4_e32 v45, v128, v46
	v_dot8c_i32_i4_e32 v38, v123, v49
	v_dot8c_i32_i4_e32 v39, v123, v47
	v_dot8c_i32_i4_e32 v40, v125, v49
	v_dot8c_i32_i4_e32 v41, v125, v47
	v_dot8c_i32_i4_e32 v42, v127, v49
	v_dot8c_i32_i4_e32 v43, v127, v47
	v_dot8c_i32_i4_e32 v44, v129, v49
	v_dot8c_i32_i4_e32 v45, v129, v47
	s_waitcnt lgkmcnt(15)
; __device__ __forceinline__ bf16 f2bf(float f) { return (bf16)f2bfu(f); }
; #define TR4(p_) __builtin_amdgcn_ds_read_tr4_b64_v2i32((LAS v2i*)(p_))
; #define VDMA(st_, k_) do { _Pragma("unroll") for (int i_ = 0; i_ < 4; ++i_) { \
;         const unsigned off_ = (unsigned)((st_) >> 2) * (16384u * 128u) + (PE_ID(E, 4 * ((st_) & 3) + i_) << 7) + ((i_ & 1) ? cx1 : cx0); \
;         __builtin_amdgcn_global_load_lds((const unsigned*)(V4 + off_), (LAS unsigned*)(ldsb + BUF[k_] + 1024 * i_), 16, 0, 0); } } while (0)
; __device__ __forceinline__ void peer_v_tokens(int j, const LAS unsigned short* EL, const LAS unsigned char* AL  , const LAS float* ASC  , const LAS int* SAL  , ...
;     ...
;         for (int st = 0; st < 16; ++st) {
;             const int p = st >> 2, q = st & 3;
;             if (st < 14) VDMA(st + 2, (st + 2) % 3);
;             if (st < 14) asm volatile("s_waitcnt vmcnt(8)" ::: "memory");
;             else if (st == 14) asm volatile("s_waitcnt vmcnt(4)" ::: "memory");
;             else asm volatile("s_waitcnt vmcnt(0)" ::: "memory");
;             if (q == 0) {
; #pragma unroll
;                 for (int r = 0; r < 4; ++r) { accH[r] = 0; accL[r] = 0; } }
; #pragma unroll
;             for (int tp = 0; tp < 2; ++tp) {
;                 const v2i ao = TR4(ATL + (2 * q + tp) * 128 + 8 * s16), ah = TR4(ATL + 1024 + (2 * q + tp) * 128 + 8 * s16);
; #pragma unroll
;                 for (int r = 0; r < 4; ++r) {
;                     const v2i d = TR4(ldsb + BUF[st % 3] + 2048 * tp + roff[r]);
;                     accH[r] = __builtin_amdgcn_sdot8(d.x, ah.x, accH[r], false); accH[r] = __builtin_amdgcn_sdot8(d.y, ah.y, accH[r], false);
;                     accL[r] = __builtin_amdgcn_sdot8(d.x, ao.x, accL[r], false); accL[r] = __builtin_amdgcn_sdot8(d.y, ao.y, accL[r], false);
;                 }
;             }
;             asm volatile("s_waitcnt lgkmcnt(0)" ::: "memory");
;             if (q == 3) {
; #pragma unroll
;                 for (int r = 0; r < 4; ++r) STASH[256 * p + 16 * (grp + 4 * r) + pc] = f2bf(asc * (float)(2 * ((accH[r] << 4) + accL[r]) + sa));
	v_add_u32_e32 v143, 8, v139
	v_and_b32_e32 v142, 15, v143
	v_xor_b32_e32 v142, 8, v142
	v_bfe_u32 v144, v143, 4, 4
	v_mul_lo_u32 v142, v142, s92
	v_mul_lo_u32 v144, v144, s92
	v_mov_b32_e32 v143, v142
	v_mov_b32_e32 v145, v144
	ds_write2st64_b64 v159, v[142:143], v[144:145] offset1:2
	v_and_b32_e32 v78, 0xffff, v28
	v_lshrrev_b32_e32 v79, 16, v28
	v_lshl_add_u32 v78, v78, 7, v152
	v_lshl_add_u32 v79, v79, 7, v153
	s_mov_b32 m0, s78
	s_add_i32 s43, s78, 0x400
	global_load_lds_dwordx4 v78, s[50:51]
	s_mov_b32 m0, s43
	s_nop 0
	global_load_lds_dwordx4 v79, s[50:51]
	s_waitcnt vmcnt(8)
	v_add_u32_e32 v54, s98, v59
	v_add_u32_e32 v55, s98, v60
	v_add_u32_e32 v56, s98, v61
	v_add_u32_e32 v57, s98, v62
	ds_read_b64_tr_b4 v[46:47], v160 offset:768
	ds_read_b64_tr_b4 v[48:49], v160 offset:1792
	ds_read_b64_tr_b4 v[122:123], v54
	ds_read_b64_tr_b4 v[124:125], v55
	ds_read_b64_tr_b4 v[126:127], v56
	ds_read_b64_tr_b4 v[128:129], v57
	s_waitcnt lgkmcnt(7)
	v_dot8c_i32_i4_e32 v38, v130, v52
	v_dot8c_i32_i4_e32 v39, v130, v50
	v_dot8c_i32_i4_e32 v40, v132, v52
	v_dot8c_i32_i4_e32 v41, v132, v50
	v_dot8c_i32_i4_e32 v42, v134, v52
	v_dot8c_i32_i4_e32 v43, v134, v50
	v_dot8c_i32_i4_e32 v44, v136, v52
	v_dot8c_i32_i4_e32 v45, v136, v50
	v_dot8c_i32_i4_e32 v38, v131, v53
	v_dot8c_i32_i4_e32 v39, v131, v51
	v_dot8c_i32_i4_e32 v40, v133, v53
	v_dot8c_i32_i4_e32 v41, v133, v51
	v_dot8c_i32_i4_e32 v42, v135, v53
	v_dot8c_i32_i4_e32 v43, v135, v51
	v_dot8c_i32_i4_e32 v44, v137, v53
	v_dot8c_i32_i4_e32 v45, v137, v51
	v_and_b32_e32 v78, 0xffff, v29
	v_lshrrev_b32_e32 v79, 16, v29
	v_lshl_add_u32 v78, v78, 7, v152
	v_lshl_add_u32 v79, v79, 7, v153
	s_mov_b32 m0, s79
	s_add_i32 s43, s79, 0x400
	global_load_lds_dwordx4 v78, s[50:51]
	s_mov_b32 m0, s43
	s_nop 0
	global_load_lds_dwordx4 v79, s[50:51]
	s_waitcnt vmcnt(8)
	v_add_u32_e32 v54, s99, v59
	v_add_u32_e32 v55, s99, v60
	v_add_u32_e32 v56, s99, v61
	v_add_u32_e32 v57, s99, v62
	ds_read_b64_tr_b4 v[50:51], v160 offset:896
	ds_read_b64_tr_b4 v[52:53], v160 offset:1920
	ds_read_b64_tr_b4 v[130:131], v54
	ds_read_b64_tr_b4 v[132:133], v55
	ds_read_b64_tr_b4 v[134:135], v56
	ds_read_b64_tr_b4 v[136:137], v57
	s_waitcnt lgkmcnt(6)
	v_dot8c_i32_i4_e32 v38, v122, v48
	v_dot8c_i32_i4_e32 v39, v122, v46
	v_dot8c_i32_i4_e32 v40, v124, v48
	v_dot8c_i32_i4_e32 v41, v124, v46
	v_dot8c_i32_i4_e32 v42, v126, v48
	v_dot8c_i32_i4_e32 v43, v126, v46
	v_dot8c_i32_i4_e32 v44, v128, v48
	v_dot8c_i32_i4_e32 v45, v128, v46
	v_dot8c_i32_i4_e32 v38, v123, v49
	v_dot8c_i32_i4_e32 v39, v123, v47
	v_dot8c_i32_i4_e32 v40, v125, v49
	v_dot8c_i32_i4_e32 v41, v125, v47
	v_dot8c_i32_i4_e32 v42, v127, v49
	v_dot8c_i32_i4_e32 v43, v127, v47
	v_dot8c_i32_i4_e32 v44, v129, v49
	v_dot8c_i32_i4_e32 v45, v129, v47
	v_and_b32_e32 v78, 0xffff, v30
	v_lshrrev_b32_e32 v79, 16, v30
	v_lshl_add_u32 v78, v78, 7, v152
	v_lshl_add_u32 v79, v79, 7, v153
	s_mov_b32 m0, s98
	s_add_i32 s43, s98, 0x400
	global_load_lds_dwordx4 v78, s[50:51]
	s_mov_b32 m0, s43
	s_nop 0
	global_load_lds_dwordx4 v79, s[50:51]
	s_waitcnt vmcnt(8)
	v_add_u32_e32 v54, s76, v59
	v_add_u32_e32 v55, s76, v60
	v_add_u32_e32 v56, s76, v61
	v_add_u32_e32 v57, s76, v62
	ds_read_b64_tr_b4 v[46:47], v160
	ds_read_b64_tr_b4 v[48:49], v160 offset:1024
	ds_read_b64_tr_b4 v[122:123], v54
	ds_read_b64_tr_b4 v[124:125], v55
	ds_read_b64_tr_b4 v[126:127], v56
	ds_read_b64_tr_b4 v[128:129], v57
	s_waitcnt lgkmcnt(6)
	v_dot8c_i32_i4_e32 v38, v130, v52
	v_dot8c_i32_i4_e32 v39, v130, v50
	v_dot8c_i32_i4_e32 v40, v132, v52
	v_dot8c_i32_i4_e32 v41, v132, v50
	v_dot8c_i32_i4_e32 v42, v134, v52
	v_dot8c_i32_i4_e32 v43, v134, v50
	v_dot8c_i32_i4_e32 v44, v136, v52
	v_dot8c_i32_i4_e32 v45, v136, v50
	v_dot8c_i32_i4_e32 v38, v131, v53
	v_dot8c_i32_i4_e32 v39, v131, v51
	v_dot8c_i32_i4_e32 v40, v133, v53
	v_dot8c_i32_i4_e32 v41, v133, v51
	v_dot8c_i32_i4_e32 v42, v135, v53
	v_dot8c_i32_i4_e32 v43, v135, v51
	v_dot8c_i32_i4_e32 v44, v137, v53
	v_dot8c_i32_i4_e32 v45, v137, v51
	s_nop 3
	s_waitcnt lgkmcnt(15)
	v_lshlrev_b32_e32 v38, 5, v38
	v_lshlrev_b32_e32 v39, 1, v39
	v_add3_u32 v38, v39, v229, v38
	v_cvt_f32_i32_e32 v38, v38
	v_mul_f32_e32 v38, v228, v38
	v_lshlrev_b32_e32 v40, 5, v40
	v_lshlrev_b32_e32 v41, 1, v41
	v_add3_u32 v40, v41, v229, v40
	v_cvt_f32_i32_e32 v40, v40
	v_mul_f32_e32 v40, v228, v40
	v_lshlrev_b32_e32 v42, 5, v42
	v_lshlrev_b32_e32 v43, 1, v43
	v_add3_u32 v42, v43, v229, v42
	v_cvt_f32_i32_e32 v42, v42
	v_mul_f32_e32 v42, v228, v42
	v_lshlrev_b32_e32 v44, 5, v44
	v_lshlrev_b32_e32 v45, 1, v45
	v_add3_u32 v44, v45, v229, v44
	v_cvt_f32_i32_e32 v44, v44
	v_mul_f32_e32 v44, v228, v44
	v_cvt_pk_bf16_f32 v184, v38, v40
	v_cvt_pk_bf16_f32 v185, v42, v44
	ds_read_b128 v[252:255], v156
	s_add_i32 s44, s40, 8
	s_ashr_i32 s45, s44, 31
	s_lshl_b64 s[44:45], s[44:45], 12
	v_lshl_add_u64 v[80:81], v[36:37], 0, s[44:45]
	s_waitcnt lgkmcnt(0)
; #define TR4(p_) __builtin_amdgcn_ds_read_tr4_b64_v2i32((LAS v2i*)(p_))
; #define VDMA(st_, k_) do { _Pragma("unroll") for (int i_ = 0; i_ < 4; ++i_) { \
;         const unsigned off_ = (unsigned)((st_) >> 2) * (16384u * 128u) + (PE_ID(E, 4 * ((st_) & 3) + i_) << 7) + ((i_ & 1) ? cx1 : cx0); \
;         __builtin_amdgcn_global_load_lds((const unsigned*)(V4 + off_), (LAS unsigned*)(ldsb + BUF[k_] + 1024 * i_), 16, 0, 0); } } while (0)
; __device__ __forceinline__ void peer_v_tokens(int j, const LAS unsigned short* EL, const LAS unsigned char* AL  , const LAS float* ASC  , const LAS int* SAL  , ...
;     ...
;         { unsigned ho = (unsigned)t * (D / 4) + (unsigned)lane; asm volatile("" : "+v"(ho)); const uint2* hp = (const uint2*)HB + ho; const float4* gp = (const float4*)fng + lane;
; #pragma unroll
;           for (int jq = 0; jq < 4; ++jq) { hv[jq] = hp[64 * jq]; gv[jq] = gp[64 * jq]; } }
;     ...
;         for (int st = 0; st < 16; ++st) {
;             const int p = st >> 2, q = st & 3;
;             if (st < 14) VDMA(st + 2, (st + 2) % 3);
;             if (st < 14) asm volatile("s_waitcnt vmcnt(8)" ::: "memory");
;             else if (st == 14) asm volatile("s_waitcnt vmcnt(4)" ::: "memory");
;             else asm volatile("s_waitcnt vmcnt(0)" ::: "memory");
;             if (q == 0) {
; #pragma unroll
;                 for (int r = 0; r < 4; ++r) { accH[r] = 0; accL[r] = 0; } }
; #pragma unroll
;             for (int tp = 0; tp < 2; ++tp) {
;                 const v2i ao = TR4(ATL + (2 * q + tp) * 128 + 8 * s16), ah = TR4(ATL + 1024 + (2 * q + tp) * 128 + 8 * s16);
; #pragma unroll
;                 for (int r = 0; r < 4; ++r) {
;                     const v2i d = TR4(ldsb + BUF[st % 3] + 2048 * tp + roff[r]);
;                     accH[r] = __builtin_amdgcn_sdot8(d.x, ah.x, accH[r], false); accH[r] = __builtin_amdgcn_sdot8(d.y, ah.y, accH[r], false);
;                     accL[r] = __builtin_amdgcn_sdot8(d.x, ao.x, accL[r], false); accL[r] = __builtin_amdgcn_sdot8(d.y, ao.y, accL[r], false);
;                 }
;             }
;     ...
;             for (int jq = 0; jq < 4; ++jq) { typedef float f4v __attribute__((ext_vector_type(4))); f4v o4; o4.x = v[jq].x * r3 * gv[jq].x; o4.y = v[jq].y * r3 * gv[jq].y; o4.z = v[jq].z * r3 * gv[jq].z; o4.w = v[jq].w * r3 * gv[jq].w;
;                 __builtin_nontemporal_store(o4, (f4v*)op + 64 * jq); }
	v_mul_f32_e32 v244, v244, v252
	v_mul_f32_e32 v245, v245, v253
	v_mul_f32_e32 v246, v246, v254
	v_mul_f32_e32 v247, v247, v255
	global_store_dwordx4 v[80:81], v[244:247], off offset:2048 nt
	s_add_i32 s43, s40, 16
	s_lshl_b32 s43, s43, 11
	v_add_u32_e32 v138, s43, v66
	global_load_dwordx2 v[194:195], v138, s[70:71]
	global_load_dwordx2 v[196:197], v138, s[70:71] offset:512
	global_load_dwordx2 v[198:199], v138, s[70:71] offset:1024
	global_load_dwordx2 v[200:201], v138, s[70:71] offset:1536
	v_add_u32_e32 v147, 8, v140
	v_and_b32_e32 v146, 15, v147
	v_xor_b32_e32 v146, 8, v146
	v_bfe_u32 v148, v147, 4, 4
	v_mul_lo_u32 v146, v146, s92
	v_mul_lo_u32 v148, v148, s92
	v_mov_b32_e32 v147, v146
	v_mov_b32_e32 v149, v148
	ds_write2st64_b64 v77, v[146:147], v[148:149] offset1:2
	v_add_u32_e32 v138, 0x1000, v74
	ds_read_u8 v139, v138
	v_add_u32_e32 v141, 0x1000, v73
	ds_read_u8 v140, v141
	s_add_i32 s43, s67, 96
	v_mov_b32_e32 v138, s43
	ds_read2st64_b32 v[228:229], v138 offset1:1
	ds_read_b128 v[18:21], v227 offset:8192
	ds_read_b128 v[22:25], v227 offset:8208
	v_mov_b32_e32 v150, v63
	v_mov_b32_e32 v151, v64
	v_mov_b32_e32 v38, 0
	v_mov_b32_e32 v39, 0
	v_mov_b32_e32 v40, 0
	v_mov_b32_e32 v41, 0
	v_mov_b32_e32 v42, 0
	v_mov_b32_e32 v43, 0
	v_mov_b32_e32 v44, 0
	v_mov_b32_e32 v45, 0
	v_and_b32_e32 v78, 0xffff, v31
	v_lshrrev_b32_e32 v79, 16, v31
	v_lshl_add_u32 v78, v78, 7, v152
	v_lshl_add_u32 v79, v79, 7, v153
	s_mov_b32 m0, s99
	s_add_i32 s43, s99, 0x400
	global_load_lds_dwordx4 v78, s[50:51]
	s_mov_b32 m0, s43
	s_nop 0
	global_load_lds_dwordx4 v79, s[50:51]
	s_waitcnt vmcnt(13)
	v_add_u32_e32 v54, s77, v59
	v_add_u32_e32 v55, s77, v60
	v_add_u32_e32 v56, s77, v61
	v_add_u32_e32 v57, s77, v62
	ds_read_b64_tr_b4 v[50:51], v160 offset:128
	ds_read_b64_tr_b4 v[52:53], v160 offset:1152
	ds_read_b64_tr_b4 v[130:131], v54
	ds_read_b64_tr_b4 v[132:133], v55
	ds_read_b64_tr_b4 v[134:135], v56
	ds_read_b64_tr_b4 v[136:137], v57
	s_waitcnt lgkmcnt(13)
	v_dot8c_i32_i4_e32 v38, v122, v48
	v_dot8c_i32_i4_e32 v39, v122, v46
	v_dot8c_i32_i4_e32 v40, v124, v48
	v_dot8c_i32_i4_e32 v41, v124, v46
	v_dot8c_i32_i4_e32 v42, v126, v48
	v_dot8c_i32_i4_e32 v43, v126, v46
	v_dot8c_i32_i4_e32 v44, v128, v48
	v_dot8c_i32_i4_e32 v45, v128, v46
	v_dot8c_i32_i4_e32 v38, v123, v49
	v_dot8c_i32_i4_e32 v39, v123, v47
	v_dot8c_i32_i4_e32 v40, v125, v49
	v_dot8c_i32_i4_e32 v41, v125, v47
	v_dot8c_i32_i4_e32 v42, v127, v49
	v_dot8c_i32_i4_e32 v43, v127, v47
	v_dot8c_i32_i4_e32 v44, v129, v49
	v_dot8c_i32_i4_e32 v45, v129, v47
	v_and_b32_e32 v78, 0xffff, v32
	v_lshrrev_b32_e32 v79, 16, v32
	v_lshl_add_u32 v78, v78, 7, v152
	v_lshl_add_u32 v79, v79, 7, v153
	s_mov_b32 m0, s76
	s_add_i32 s43, s76, 0x400
	global_load_lds_dwordx4 v78, s[50:51]
	s_mov_b32 m0, s43
	s_nop 0
	global_load_lds_dwordx4 v79, s[50:51]
	s_waitcnt vmcnt(13)
	v_add_u32_e32 v54, s78, v59
	v_add_u32_e32 v55, s78, v60
	v_add_u32_e32 v56, s78, v61
	v_add_u32_e32 v57, s78, v62
	ds_read_b64_tr_b4 v[46:47], v160 offset:256
	ds_read_b64_tr_b4 v[48:49], v160 offset:1280
	ds_read_b64_tr_b4 v[122:123], v54
	ds_read_b64_tr_b4 v[124:125], v55
	ds_read_b64_tr_b4 v[126:127], v56
	ds_read_b64_tr_b4 v[128:129], v57
	s_waitcnt lgkmcnt(6)
	v_dot8c_i32_i4_e32 v38, v130, v52
	v_dot8c_i32_i4_e32 v39, v130, v50
	v_dot8c_i32_i4_e32 v40, v132, v52
	v_dot8c_i32_i4_e32 v41, v132, v50
	v_dot8c_i32_i4_e32 v42, v134, v52
	v_dot8c_i32_i4_e32 v43, v134, v50
	v_dot8c_i32_i4_e32 v44, v136, v52
	v_dot8c_i32_i4_e32 v45, v136, v50
	v_dot8c_i32_i4_e32 v38, v131, v53
	v_dot8c_i32_i4_e32 v39, v131, v51
	v_dot8c_i32_i4_e32 v40, v133, v53
	v_dot8c_i32_i4_e32 v41, v133, v51
	v_dot8c_i32_i4_e32 v42, v135, v53
	v_dot8c_i32_i4_e32 v43, v135, v51
	v_dot8c_i32_i4_e32 v44, v137, v53
	v_dot8c_i32_i4_e32 v45, v137, v51
	v_and_b32_e32 v78, 0xffff, v33
	v_lshrrev_b32_e32 v79, 16, v33
	v_lshl_add_u32 v78, v78, 7, v152
	v_lshl_add_u32 v79, v79, 7, v153
	s_mov_b32 m0, s77
	s_add_i32 s43, s77, 0x400
	global_load_lds_dwordx4 v78, s[50:51]
	s_mov_b32 m0, s43
	s_nop 0
	global_load_lds_dwordx4 v79, s[50:51]
	s_waitcnt vmcnt(13)
	v_add_u32_e32 v54, s79, v59
	v_add_u32_e32 v55, s79, v60
	v_add_u32_e32 v56, s79, v61
	v_add_u32_e32 v57, s79, v62
	ds_read_b64_tr_b4 v[50:51], v160 offset:384
	ds_read_b64_tr_b4 v[52:53], v160 offset:1408
	ds_read_b64_tr_b4 v[130:131], v54
	ds_read_b64_tr_b4 v[132:133], v55
	ds_read_b64_tr_b4 v[134:135], v56
	ds_read_b64_tr_b4 v[136:137], v57
	s_waitcnt lgkmcnt(6)
	v_dot8c_i32_i4_e32 v38, v122, v48
	v_dot8c_i32_i4_e32 v39, v122, v46
	v_dot8c_i32_i4_e32 v40, v124, v48
	v_dot8c_i32_i4_e32 v41, v124, v46
	v_dot8c_i32_i4_e32 v42, v126, v48
	v_dot8c_i32_i4_e32 v43, v126, v46
	v_dot8c_i32_i4_e32 v44, v128, v48
	v_dot8c_i32_i4_e32 v45, v128, v46
	v_dot8c_i32_i4_e32 v38, v123, v49
	v_dot8c_i32_i4_e32 v39, v123, v47
	v_dot8c_i32_i4_e32 v40, v125, v49
	v_dot8c_i32_i4_e32 v41, v125, v47
	v_dot8c_i32_i4_e32 v42, v127, v49
	v_dot8c_i32_i4_e32 v43, v127, v47
	v_dot8c_i32_i4_e32 v44, v129, v49
	v_dot8c_i32_i4_e32 v45, v129, v47
	s_waitcnt lgkmcnt(15)
	v_and_b32_e32 v78, 0xffff, v18
	v_lshrrev_b32_e32 v79, 16, v18
	v_lshl_add_u32 v78, v78, 7, v150
	v_lshl_add_u32 v79, v79, 7, v151
	s_mov_b32 m0, s78
	s_add_i32 s43, s78, 0x400
	global_load_lds_dwordx4 v78, s[50:51]
	s_mov_b32 m0, s43
	s_nop 0
	global_load_lds_dwordx4 v79, s[50:51]
	s_waitcnt vmcnt(13)
	v_add_u32_e32 v54, s98, v59
	v_add_u32_e32 v55, s98, v60
	v_add_u32_e32 v56, s98, v61
	v_add_u32_e32 v57, s98, v62
	ds_read_b64_tr_b4 v[46:47], v160 offset:512
	ds_read_b64_tr_b4 v[48:49], v160 offset:1536
	ds_read_b64_tr_b4 v[122:123], v54
	ds_read_b64_tr_b4 v[124:125], v55
	ds_read_b64_tr_b4 v[126:127], v56
	ds_read_b64_tr_b4 v[128:129], v57
	s_waitcnt lgkmcnt(6)
; #define TR4(p_) __builtin_amdgcn_ds_read_tr4_b64_v2i32((LAS v2i*)(p_))
; #define VDMA(st_, k_) do { _Pragma("unroll") for (int i_ = 0; i_ < 4; ++i_) { \
;         const unsigned off_ = (unsigned)((st_) >> 2) * (16384u * 128u) + (PE_ID(E, 4 * ((st_) & 3) + i_) << 7) + ((i_ & 1) ? cx1 : cx0); \
;         __builtin_amdgcn_global_load_lds((const unsigned*)(V4 + off_), (LAS unsigned*)(ldsb + BUF[k_] + 1024 * i_), 16, 0, 0); } } while (0)
; __device__ __forceinline__ void peer_v_tokens(int j, const LAS unsigned short* EL, const LAS unsigned char* AL  , const LAS float* ASC  , const LAS int* SAL  , ...
;     ...
;         for (int st = 0; st < 16; ++st) {
;             const int p = st >> 2, q = st & 3;
;             if (st < 14) VDMA(st + 2, (st + 2) % 3);
;             if (st < 14) asm volatile("s_waitcnt vmcnt(8)" ::: "memory");
;             else if (st == 14) asm volatile("s_waitcnt vmcnt(4)" ::: "memory");
;             else asm volatile("s_waitcnt vmcnt(0)" ::: "memory");
;             if (q == 0) {
; #pragma unroll
;                 for (int r = 0; r < 4; ++r) { accH[r] = 0; accL[r] = 0; } }
; #pragma unroll
;             for (int tp = 0; tp < 2; ++tp) {
;                 const v2i ao = TR4(ATL + (2 * q + tp) * 128 + 8 * s16), ah = TR4(ATL + 1024 + (2 * q + tp) * 128 + 8 * s16);
; #pragma unroll
;                 for (int r = 0; r < 4; ++r) {
;                     const v2i d = TR4(ldsb + BUF[st % 3] + 2048 * tp + roff[r]);
;                     accH[r] = __builtin_amdgcn_sdot8(d.x, ah.x, accH[r], false); accH[r] = __builtin_amdgcn_sdot8(d.y, ah.y, accH[r], false);
;                     accL[r] = __builtin_amdgcn_sdot8(d.x, ao.x, accL[r], false); accL[r] = __builtin_amdgcn_sdot8(d.y, ao.y, accL[r], false);
;                 }
;             }
	v_dot8c_i32_i4_e32 v38, v130, v52
	v_dot8c_i32_i4_e32 v39, v130, v50
	v_dot8c_i32_i4_e32 v40, v132, v52
	v_dot8c_i32_i4_e32 v41, v132, v50
	v_dot8c_i32_i4_e32 v42, v134, v52
	v_dot8c_i32_i4_e32 v43, v134, v50
	v_dot8c_i32_i4_e32 v44, v136, v52
	v_dot8c_i32_i4_e32 v45, v136, v50
	v_dot8c_i32_i4_e32 v38, v131, v53
	v_dot8c_i32_i4_e32 v39, v131, v51
	v_dot8c_i32_i4_e32 v40, v133, v53
	v_dot8c_i32_i4_e32 v41, v133, v51
	v_dot8c_i32_i4_e32 v42, v135, v53
	v_dot8c_i32_i4_e32 v43, v135, v51
	v_dot8c_i32_i4_e32 v44, v137, v53
	v_dot8c_i32_i4_e32 v45, v137, v51
	v_and_b32_e32 v78, 0xffff, v19
	v_lshrrev_b32_e32 v79, 16, v19
	v_lshl_add_u32 v78, v78, 7, v150
	v_lshl_add_u32 v79, v79, 7, v151
	s_mov_b32 m0, s79
	s_add_i32 s43, s79, 0x400
	global_load_lds_dwordx4 v78, s[50:51]
	s_mov_b32 m0, s43
	s_nop 0
	global_load_lds_dwordx4 v79, s[50:51]
	s_waitcnt vmcnt(8)
	v_add_u32_e32 v54, s99, v59
	v_add_u32_e32 v55, s99, v60
	v_add_u32_e32 v56, s99, v61
	v_add_u32_e32 v57, s99, v62
	ds_read_b64_tr_b4 v[50:51], v160 offset:640
	ds_read_b64_tr_b4 v[52:53], v160 offset:1664
	ds_read_b64_tr_b4 v[130:131], v54
	ds_read_b64_tr_b4 v[132:133], v55
	ds_read_b64_tr_b4 v[134:135], v56
	ds_read_b64_tr_b4 v[136:137], v57
	s_waitcnt lgkmcnt(6)
	v_dot8c_i32_i4_e32 v38, v122, v48
	v_dot8c_i32_i4_e32 v39, v122, v46
	v_dot8c_i32_i4_e32 v40, v124, v48
	v_dot8c_i32_i4_e32 v41, v124, v46
	v_dot8c_i32_i4_e32 v42, v126, v48
	v_dot8c_i32_i4_e32 v43, v126, v46
	v_dot8c_i32_i4_e32 v44, v128, v48
	v_dot8c_i32_i4_e32 v45, v128, v46
	v_dot8c_i32_i4_e32 v38, v123, v49
	v_dot8c_i32_i4_e32 v39, v123, v47
	v_dot8c_i32_i4_e32 v40, v125, v49
	v_dot8c_i32_i4_e32 v41, v125, v47
	v_dot8c_i32_i4_e32 v42, v127, v49
	v_dot8c_i32_i4_e32 v43, v127, v47
	v_dot8c_i32_i4_e32 v44, v129, v49
	v_dot8c_i32_i4_e32 v45, v129, v47
	s_waitcnt lgkmcnt(15)
	v_add_u32_e32 v143, 8, v139
	v_and_b32_e32 v142, 15, v143
	v_xor_b32_e32 v142, 8, v142
	v_bfe_u32 v144, v143, 4, 4
	v_mul_lo_u32 v142, v142, s92
	v_mul_lo_u32 v144, v144, s92
	v_mov_b32_e32 v143, v142
	v_mov_b32_e32 v145, v144
	ds_write2st64_b64 v159, v[142:143], v[144:145] offset1:2
	v_and_b32_e32 v78, 0xffff, v20
	v_lshrrev_b32_e32 v79, 16, v20
	v_lshl_add_u32 v78, v78, 7, v150
	v_lshl_add_u32 v79, v79, 7, v151
	s_mov_b32 m0, s98
	s_add_i32 s43, s98, 0x400
	global_load_lds_dwordx4 v78, s[50:51]
	s_mov_b32 m0, s43
	s_nop 0
	global_load_lds_dwordx4 v79, s[50:51]
	s_waitcnt vmcnt(8)
	v_add_u32_e32 v54, s76, v59
	v_add_u32_e32 v55, s76, v60
	v_add_u32_e32 v56, s76, v61
	v_add_u32_e32 v57, s76, v62
	ds_read_b64_tr_b4 v[46:47], v160 offset:768
	ds_read_b64_tr_b4 v[48:49], v160 offset:1792
	ds_read_b64_tr_b4 v[122:123], v54
	ds_read_b64_tr_b4 v[124:125], v55
	ds_read_b64_tr_b4 v[126:127], v56
	ds_read_b64_tr_b4 v[128:129], v57
	s_waitcnt lgkmcnt(7)
	v_dot8c_i32_i4_e32 v38, v130, v52
	v_dot8c_i32_i4_e32 v39, v130, v50
	v_dot8c_i32_i4_e32 v40, v132, v52
	v_dot8c_i32_i4_e32 v41, v132, v50
	v_dot8c_i32_i4_e32 v42, v134, v52
	v_dot8c_i32_i4_e32 v43, v134, v50
	v_dot8c_i32_i4_e32 v44, v136, v52
	v_dot8c_i32_i4_e32 v45, v136, v50
	v_dot8c_i32_i4_e32 v38, v131, v53
	v_dot8c_i32_i4_e32 v39, v131, v51
	v_dot8c_i32_i4_e32 v40, v133, v53
	v_dot8c_i32_i4_e32 v41, v133, v51
	v_dot8c_i32_i4_e32 v42, v135, v53
	v_dot8c_i32_i4_e32 v43, v135, v51
	v_dot8c_i32_i4_e32 v44, v137, v53
	v_dot8c_i32_i4_e32 v45, v137, v51
	v_and_b32_e32 v78, 0xffff, v21
	v_lshrrev_b32_e32 v79, 16, v21
	v_lshl_add_u32 v78, v78, 7, v150
	v_lshl_add_u32 v79, v79, 7, v151
	s_mov_b32 m0, s99
	s_add_i32 s43, s99, 0x400
	global_load_lds_dwordx4 v78, s[50:51]
	s_mov_b32 m0, s43
	s_nop 0
	global_load_lds_dwordx4 v79, s[50:51]
	s_waitcnt vmcnt(8)
	v_add_u32_e32 v54, s77, v59
	v_add_u32_e32 v55, s77, v60
	v_add_u32_e32 v56, s77, v61
	v_add_u32_e32 v57, s77, v62
	ds_read_b64_tr_b4 v[50:51], v160 offset:896
	ds_read_b64_tr_b4 v[52:53], v160 offset:1920
	ds_read_b64_tr_b4 v[130:131], v54
	ds_read_b64_tr_b4 v[132:133], v55
	ds_read_b64_tr_b4 v[134:135], v56
	ds_read_b64_tr_b4 v[136:137], v57
	s_waitcnt lgkmcnt(6)
	v_dot8c_i32_i4_e32 v38, v122, v48
	v_dot8c_i32_i4_e32 v39, v122, v46
	v_dot8c_i32_i4_e32 v40, v124, v48
	v_dot8c_i32_i4_e32 v41, v124, v46
	v_dot8c_i32_i4_e32 v42, v126, v48
	v_dot8c_i32_i4_e32 v43, v126, v46
	v_dot8c_i32_i4_e32 v44, v128, v48
	v_dot8c_i32_i4_e32 v45, v128, v46
	v_dot8c_i32_i4_e32 v38, v123, v49
	v_dot8c_i32_i4_e32 v39, v123, v47
	v_dot8c_i32_i4_e32 v40, v125, v49
	v_dot8c_i32_i4_e32 v41, v125, v47
	v_dot8c_i32_i4_e32 v42, v127, v49
	v_dot8c_i32_i4_e32 v43, v127, v47
	v_dot8c_i32_i4_e32 v44, v129, v49
	v_dot8c_i32_i4_e32 v45, v129, v47
	v_and_b32_e32 v78, 0xffff, v22
	v_lshrrev_b32_e32 v79, 16, v22
	v_lshl_add_u32 v78, v78, 7, v150
	v_lshl_add_u32 v79, v79, 7, v151
	s_mov_b32 m0, s76
	s_add_i32 s43, s76, 0x400
	global_load_lds_dwordx4 v78, s[50:51]
	s_mov_b32 m0, s43
	s_nop 0
	global_load_lds_dwordx4 v79, s[50:51]
	s_waitcnt vmcnt(8)
	v_add_u32_e32 v54, s78, v59
	v_add_u32_e32 v55, s78, v60
	v_add_u32_e32 v56, s78, v61
	v_add_u32_e32 v57, s78, v62
	ds_read_b64_tr_b4 v[46:47], v160
	ds_read_b64_tr_b4 v[48:49], v160 offset:1024
	ds_read_b64_tr_b4 v[122:123], v54
	ds_read_b64_tr_b4 v[124:125], v55
	ds_read_b64_tr_b4 v[126:127], v56
	ds_read_b64_tr_b4 v[128:129], v57
	s_waitcnt lgkmcnt(6)
	v_dot8c_i32_i4_e32 v38, v130, v52
	v_dot8c_i32_i4_e32 v39, v130, v50
	v_dot8c_i32_i4_e32 v40, v132, v52
	v_dot8c_i32_i4_e32 v41, v132, v50
	v_dot8c_i32_i4_e32 v42, v134, v52
	v_dot8c_i32_i4_e32 v43, v134, v50
	v_dot8c_i32_i4_e32 v44, v136, v52
	v_dot8c_i32_i4_e32 v45, v136, v50
	v_dot8c_i32_i4_e32 v38, v131, v53
	v_dot8c_i32_i4_e32 v39, v131, v51
	v_dot8c_i32_i4_e32 v40, v133, v53
	v_dot8c_i32_i4_e32 v41, v133, v51
	v_dot8c_i32_i4_e32 v42, v135, v53
	v_dot8c_i32_i4_e32 v43, v135, v51
	v_dot8c_i32_i4_e32 v44, v137, v53
	v_dot8c_i32_i4_e32 v45, v137, v51
	s_nop 3
	s_waitcnt lgkmcnt(15)
; #define LAS __attribute__((address_space(3)))
; __device__ __forceinline__ bf16 f2bf(float f) { return (bf16)f2bfu(f); }
; __device__ __forceinline__ void peer_v_tokens(int j, const LAS unsigned short* EL, const LAS unsigned char* AL  , const LAS float* ASC  , const LAS int* SAL  , ...
;     ...
;             if (q == 3) {
; #pragma unroll
;                 for (int r = 0; r < 4; ++r) STASH[256 * p + 16 * (grp + 4 * r) + pc] = f2bf(asc * (float)(2 * ((accH[r] << 4) + accL[r]) + sa));
;             }
;     ...
;         {
;             float4 v[4]; float ss = 0.f;
; #pragma unroll
;             for (int jq = 0; jq < 4; ++jq) { typedef unsigned u2v __attribute__((ext_vector_type(2))); const u2v pw = *(const LAS u2v*)(STASH + 4 * lane + 256 * jq); const uint2 hw = hv[jq];
;                 v[jq] = make_float4(__uint_as_float(hw.x << 16) + __uint_as_float(pw.x << 16), __uint_as_float(hw.x & 0xffff0000u) + __uint_as_float(pw.x & 0xffff0000u),
	v_lshlrev_b32_e32 v38, 5, v38
	v_lshlrev_b32_e32 v39, 1, v39
	v_add3_u32 v38, v39, v229, v38
	v_cvt_f32_i32_e32 v38, v38
	v_mul_f32_e32 v38, v228, v38
	v_lshlrev_b32_e32 v40, 5, v40
	v_lshlrev_b32_e32 v41, 1, v41
	v_add3_u32 v40, v41, v229, v40
	v_cvt_f32_i32_e32 v40, v40
	v_mul_f32_e32 v40, v228, v40
	v_lshlrev_b32_e32 v42, 5, v42
	v_lshlrev_b32_e32 v43, 1, v43
	v_add3_u32 v42, v43, v229, v42
	v_cvt_f32_i32_e32 v42, v42
	v_mul_f32_e32 v42, v228, v42
	v_lshlrev_b32_e32 v44, 5, v44
	v_lshlrev_b32_e32 v45, 1, v45
	v_add3_u32 v44, v45, v229, v44
	v_cvt_f32_i32_e32 v44, v44
	v_mul_f32_e32 v44, v228, v44
	v_cvt_pk_bf16_f32 v192, v38, v40
	v_cvt_pk_bf16_f32 v193, v42, v44
	ds_read_b128 v[252:255], v156 offset:1024
	s_add_i32 s44, s40, 8
	s_ashr_i32 s45, s44, 31
	s_lshl_b64 s[44:45], s[44:45], 12
	v_lshl_add_u64 v[80:81], v[36:37], 0, s[44:45]
	s_waitcnt lgkmcnt(0)
	v_mul_f32_e32 v248, v248, v252
	v_mul_f32_e32 v249, v249, v253
	v_mul_f32_e32 v250, v250, v254
	v_mul_f32_e32 v251, v251, v255
	global_store_dwordx4 v[80:81], v[248:251], off offset:3072 nt
	v_add_u32_e32 v147, 8, v140
	v_and_b32_e32 v146, 15, v147
	v_xor_b32_e32 v146, 8, v146
	v_bfe_u32 v148, v147, 4, 4
	v_mul_lo_u32 v146, v146, s92
	v_mul_lo_u32 v148, v148, s92
	v_mov_b32_e32 v147, v146
	v_mov_b32_e32 v149, v148
	ds_write2st64_b64 v77, v[146:147], v[148:149] offset1:2
	v_add_u32_e32 v138, 0x1400, v74
	ds_read_u8 v139, v138
	v_add_u32_e32 v141, 0x1400, v73
	ds_read_u8 v140, v141
	s_add_i32 s43, s67, 128
	v_mov_b32_e32 v138, s43
	ds_read2st64_b32 v[228:229], v138 offset1:1
	ds_read_b128 v[26:29], v227 offset:10240
	ds_read_b128 v[30:33], v227 offset:10256
	v_mov_b32_e32 v38, 0
	v_mov_b32_e32 v39, 0
	v_mov_b32_e32 v40, 0
	v_mov_b32_e32 v41, 0
	v_mov_b32_e32 v42, 0
	v_mov_b32_e32 v43, 0
	v_mov_b32_e32 v44, 0
	v_mov_b32_e32 v45, 0
	v_and_b32_e32 v78, 0xffff, v23
	v_lshrrev_b32_e32 v79, 16, v23
	v_lshl_add_u32 v78, v78, 7, v150
	v_lshl_add_u32 v79, v79, 7, v151
	s_mov_b32 m0, s77
	s_add_i32 s43, s77, 0x400
	global_load_lds_dwordx4 v78, s[50:51]
	s_mov_b32 m0, s43
	s_nop 0
	global_load_lds_dwordx4 v79, s[50:51]
	s_waitcnt vmcnt(9)
	v_add_u32_e32 v54, s79, v59
	v_add_u32_e32 v55, s79, v60
	v_add_u32_e32 v56, s79, v61
	v_add_u32_e32 v57, s79, v62
	ds_read_b64_tr_b4 v[50:51], v160 offset:128
	ds_read_b64_tr_b4 v[52:53], v160 offset:1152
	ds_read_b64_tr_b4 v[130:131], v54
	ds_read_b64_tr_b4 v[132:133], v55
	ds_read_b64_tr_b4 v[134:135], v56
	ds_read_b64_tr_b4 v[136:137], v57
	s_waitcnt lgkmcnt(13)
	v_dot8c_i32_i4_e32 v38, v122, v48
	v_dot8c_i32_i4_e32 v39, v122, v46
	v_dot8c_i32_i4_e32 v40, v124, v48
	v_dot8c_i32_i4_e32 v41, v124, v46
	v_dot8c_i32_i4_e32 v42, v126, v48
	v_dot8c_i32_i4_e32 v43, v126, v46
	v_dot8c_i32_i4_e32 v44, v128, v48
	v_dot8c_i32_i4_e32 v45, v128, v46
	v_dot8c_i32_i4_e32 v38, v123, v49
	v_dot8c_i32_i4_e32 v39, v123, v47
	v_dot8c_i32_i4_e32 v40, v125, v49
	v_dot8c_i32_i4_e32 v41, v125, v47
	v_dot8c_i32_i4_e32 v42, v127, v49
	v_dot8c_i32_i4_e32 v43, v127, v47
	v_dot8c_i32_i4_e32 v44, v129, v49
	v_dot8c_i32_i4_e32 v45, v129, v47
	v_and_b32_e32 v78, 0xffff, v24
	v_lshrrev_b32_e32 v79, 16, v24
	v_lshl_add_u32 v78, v78, 7, v150
	v_lshl_add_u32 v79, v79, 7, v151
	s_mov_b32 m0, s78
	s_add_i32 s43, s78, 0x400
	global_load_lds_dwordx4 v78, s[50:51]
	s_mov_b32 m0, s43
	s_nop 0
	global_load_lds_dwordx4 v79, s[50:51]
	s_waitcnt vmcnt(9)
	v_add_u32_e32 v54, s98, v59
	v_add_u32_e32 v55, s98, v60
	v_add_u32_e32 v56, s98, v61
	v_add_u32_e32 v57, s98, v62
	ds_read_b64_tr_b4 v[46:47], v160 offset:256
	ds_read_b64_tr_b4 v[48:49], v160 offset:1280
	ds_read_b64_tr_b4 v[122:123], v54
	ds_read_b64_tr_b4 v[124:125], v55
	ds_read_b64_tr_b4 v[126:127], v56
	ds_read_b64_tr_b4 v[128:129], v57
	s_waitcnt lgkmcnt(6)
	v_dot8c_i32_i4_e32 v38, v130, v52
	v_dot8c_i32_i4_e32 v39, v130, v50
	v_dot8c_i32_i4_e32 v40, v132, v52
	v_dot8c_i32_i4_e32 v41, v132, v50
	v_dot8c_i32_i4_e32 v42, v134, v52
	v_dot8c_i32_i4_e32 v43, v134, v50
	v_dot8c_i32_i4_e32 v44, v136, v52
	v_dot8c_i32_i4_e32 v45, v136, v50
	v_dot8c_i32_i4_e32 v38, v131, v53
	v_dot8c_i32_i4_e32 v39, v131, v51
	v_dot8c_i32_i4_e32 v40, v133, v53
	v_dot8c_i32_i4_e32 v41, v133, v51
	v_dot8c_i32_i4_e32 v42, v135, v53
	v_dot8c_i32_i4_e32 v43, v135, v51
	v_dot8c_i32_i4_e32 v44, v137, v53
	v_dot8c_i32_i4_e32 v45, v137, v51
	ds_write_b16 v65, v178
	ds_write_b16_d16_hi v65, v178 offset:128
	ds_write_b16 v65, v179 offset:256
	ds_write_b16_d16_hi v65, v179 offset:384
	ds_write_b16 v65, v180 offset:512
	ds_write_b16_d16_hi v65, v180 offset:640
	ds_write_b16 v65, v181 offset:768
	ds_write_b16_d16_hi v65, v181 offset:896
	ds_write_b16 v65, v182 offset:1024
	ds_write_b16_d16_hi v65, v182 offset:1152
	ds_write_b16 v65, v183 offset:1280
	ds_write_b16_d16_hi v65, v183 offset:1408
	ds_write_b16 v65, v184 offset:1536
	ds_write_b16_d16_hi v65, v184 offset:1664
	ds_write_b16 v65, v185 offset:1792
	ds_write_b16_d16_hi v65, v185 offset:1920
	ds_read_b64 v[202:203], v154
	ds_read_b64 v[204:205], v154 offset:512
	ds_read_b64 v[206:207], v154 offset:1024
	ds_read_b64 v[208:209], v154 offset:1536
	v_and_b32_e32 v78, 0xffff, v25
	v_lshrrev_b32_e32 v79, 16, v25
	v_lshl_add_u32 v78, v78, 7, v150
	v_lshl_add_u32 v79, v79, 7, v151
	s_mov_b32 m0, s79
	s_add_i32 s43, s79, 0x400
	global_load_lds_dwordx4 v78, s[50:51]
	s_mov_b32 m0, s43
	s_nop 0
	global_load_lds_dwordx4 v79, s[50:51]
	s_waitcnt vmcnt(9)
	v_add_u32_e32 v54, s99, v59
	v_add_u32_e32 v55, s99, v60
	v_add_u32_e32 v56, s99, v61
	v_add_u32_e32 v57, s99, v62
	ds_read_b64_tr_b4 v[50:51], v160 offset:384
	ds_read_b64_tr_b4 v[52:53], v160 offset:1408
	ds_read_b64_tr_b4 v[130:131], v54
	ds_read_b64_tr_b4 v[132:133], v55
	ds_read_b64_tr_b4 v[134:135], v56
	ds_read_b64_tr_b4 v[136:137], v57
	s_waitcnt lgkmcnt(15)
; #define TR4(p_) __builtin_amdgcn_ds_read_tr4_b64_v2i32((LAS v2i*)(p_))
; #define VDMA(st_, k_) do { _Pragma("unroll") for (int i_ = 0; i_ < 4; ++i_) { \
;         const unsigned off_ = (unsigned)((st_) >> 2) * (16384u * 128u) + (PE_ID(E, 4 * ((st_) & 3) + i_) << 7) + ((i_ & 1) ? cx1 : cx0); \
;         __builtin_amdgcn_global_load_lds((const unsigned*)(V4 + off_), (LAS unsigned*)(ldsb + BUF[k_] + 1024 * i_), 16, 0, 0); } } while (0)
; __device__ __forceinline__ void peer_v_tokens(int j, const LAS unsigned short* EL, const LAS unsigned char* AL  , const LAS float* ASC  , const LAS int* SAL  , ...
;     ...
;         for (int st = 0; st < 16; ++st) {
;             const int p = st >> 2, q = st & 3;
;             if (st < 14) VDMA(st + 2, (st + 2) % 3);
;             if (st < 14) asm volatile("s_waitcnt vmcnt(8)" ::: "memory");
;             else if (st == 14) asm volatile("s_waitcnt vmcnt(4)" ::: "memory");
;             else asm volatile("s_waitcnt vmcnt(0)" ::: "memory");
;             if (q == 0) {
; #pragma unroll
;                 for (int r = 0; r < 4; ++r) { accH[r] = 0; accL[r] = 0; } }
; #pragma unroll
;             for (int tp = 0; tp < 2; ++tp) {
;                 const v2i ao = TR4(ATL + (2 * q + tp) * 128 + 8 * s16), ah = TR4(ATL + 1024 + (2 * q + tp) * 128 + 8 * s16);
; #pragma unroll
;                 for (int r = 0; r < 4; ++r) {
;                     const v2i d = TR4(ldsb + BUF[st % 3] + 2048 * tp + roff[r]);
;                     accH[r] = __builtin_amdgcn_sdot8(d.x, ah.x, accH[r], false); accH[r] = __builtin_amdgcn_sdot8(d.y, ah.y, accH[r], false);
;                     accL[r] = __builtin_amdgcn_sdot8(d.x, ao.x, accL[r], false); accL[r] = __builtin_amdgcn_sdot8(d.y, ao.y, accL[r], false);
;                 }
;             }
	v_dot8c_i32_i4_e32 v38, v122, v48
	v_dot8c_i32_i4_e32 v39, v122, v46
	v_dot8c_i32_i4_e32 v40, v124, v48
	v_dot8c_i32_i4_e32 v41, v124, v46
	v_dot8c_i32_i4_e32 v42, v126, v48
	v_dot8c_i32_i4_e32 v43, v126, v46
	v_dot8c_i32_i4_e32 v44, v128, v48
	v_dot8c_i32_i4_e32 v45, v128, v46
	v_dot8c_i32_i4_e32 v38, v123, v49
	v_dot8c_i32_i4_e32 v39, v123, v47
	v_dot8c_i32_i4_e32 v40, v125, v49
	v_dot8c_i32_i4_e32 v41, v125, v47
	v_dot8c_i32_i4_e32 v42, v127, v49
	v_dot8c_i32_i4_e32 v43, v127, v47
	v_dot8c_i32_i4_e32 v44, v129, v49
	v_dot8c_i32_i4_e32 v45, v129, v47
	s_waitcnt lgkmcnt(15)
	v_and_b32_e32 v78, 0xffff, v26
	v_lshrrev_b32_e32 v79, 16, v26
	v_lshl_add_u32 v78, v78, 7, v150
	v_lshl_add_u32 v79, v79, 7, v151
	s_mov_b32 m0, s98
	s_add_i32 s43, s98, 0x400
	global_load_lds_dwordx4 v78, s[50:51]
	s_mov_b32 m0, s43
	s_nop 0
	global_load_lds_dwordx4 v79, s[50:51]
	s_waitcnt vmcnt(9)
	v_add_u32_e32 v54, s76, v59
	v_add_u32_e32 v55, s76, v60
	v_add_u32_e32 v56, s76, v61
	v_add_u32_e32 v57, s76, v62
	ds_read_b64_tr_b4 v[46:47], v160 offset:512
	ds_read_b64_tr_b4 v[48:49], v160 offset:1536
	ds_read_b64_tr_b4 v[122:123], v54
	ds_read_b64_tr_b4 v[124:125], v55
	ds_read_b64_tr_b4 v[126:127], v56
	ds_read_b64_tr_b4 v[128:129], v57
	s_waitcnt lgkmcnt(6)
	v_dot8c_i32_i4_e32 v38, v130, v52
	v_dot8c_i32_i4_e32 v39, v130, v50
	v_dot8c_i32_i4_e32 v40, v132, v52
	v_dot8c_i32_i4_e32 v41, v132, v50
	v_dot8c_i32_i4_e32 v42, v134, v52
	v_dot8c_i32_i4_e32 v43, v134, v50
	v_dot8c_i32_i4_e32 v44, v136, v52
	v_dot8c_i32_i4_e32 v45, v136, v50
	v_dot8c_i32_i4_e32 v38, v131, v53
	v_dot8c_i32_i4_e32 v39, v131, v51
	v_dot8c_i32_i4_e32 v40, v133, v53
	v_dot8c_i32_i4_e32 v41, v133, v51
	v_dot8c_i32_i4_e32 v42, v135, v53
	v_dot8c_i32_i4_e32 v43, v135, v51
	v_dot8c_i32_i4_e32 v44, v137, v53
	v_dot8c_i32_i4_e32 v45, v137, v51
	v_and_b32_e32 v78, 0xffff, v27
	v_lshrrev_b32_e32 v79, 16, v27
	v_lshl_add_u32 v78, v78, 7, v150
	v_lshl_add_u32 v79, v79, 7, v151
	s_mov_b32 m0, s99
	s_add_i32 s43, s99, 0x400
	global_load_lds_dwordx4 v78, s[50:51]
	s_mov_b32 m0, s43
	s_nop 0
	global_load_lds_dwordx4 v79, s[50:51]
	s_waitcnt vmcnt(8)
	v_add_u32_e32 v54, s77, v59
	v_add_u32_e32 v55, s77, v60
	v_add_u32_e32 v56, s77, v61
	v_add_u32_e32 v57, s77, v62
	ds_read_b64_tr_b4 v[50:51], v160 offset:640
	ds_read_b64_tr_b4 v[52:53], v160 offset:1664
	ds_read_b64_tr_b4 v[130:131], v54
	ds_read_b64_tr_b4 v[132:133], v55
	ds_read_b64_tr_b4 v[134:135], v56
	ds_read_b64_tr_b4 v[136:137], v57
	s_waitcnt lgkmcnt(6)
	v_dot8c_i32_i4_e32 v38, v122, v48
	v_dot8c_i32_i4_e32 v39, v122, v46
	v_dot8c_i32_i4_e32 v40, v124, v48
	v_dot8c_i32_i4_e32 v41, v124, v46
	v_dot8c_i32_i4_e32 v42, v126, v48
	v_dot8c_i32_i4_e32 v43, v126, v46
	v_dot8c_i32_i4_e32 v44, v128, v48
	v_dot8c_i32_i4_e32 v45, v128, v46
	v_dot8c_i32_i4_e32 v38, v123, v49
	v_dot8c_i32_i4_e32 v39, v123, v47
	v_dot8c_i32_i4_e32 v40, v125, v49
	v_dot8c_i32_i4_e32 v41, v125, v47
	v_dot8c_i32_i4_e32 v42, v127, v49
	v_dot8c_i32_i4_e32 v43, v127, v47
	v_dot8c_i32_i4_e32 v44, v129, v49
	v_dot8c_i32_i4_e32 v45, v129, v47
	s_waitcnt lgkmcnt(15)
	v_add_u32_e32 v143, 8, v139
	v_and_b32_e32 v142, 15, v143
	v_xor_b32_e32 v142, 8, v142
	v_bfe_u32 v144, v143, 4, 4
	v_mul_lo_u32 v142, v142, s92
	v_mul_lo_u32 v144, v144, s92
	v_mov_b32_e32 v143, v142
	v_mov_b32_e32 v145, v144
	ds_write2st64_b64 v159, v[142:143], v[144:145] offset1:2
	v_and_b32_e32 v78, 0xffff, v28
	v_lshrrev_b32_e32 v79, 16, v28
	v_lshl_add_u32 v78, v78, 7, v150
	v_lshl_add_u32 v79, v79, 7, v151
	s_mov_b32 m0, s76
	s_add_i32 s43, s76, 0x400
	global_load_lds_dwordx4 v78, s[50:51]
	s_mov_b32 m0, s43
	s_nop 0
	global_load_lds_dwordx4 v79, s[50:51]
	s_waitcnt vmcnt(8)
	v_add_u32_e32 v54, s78, v59
	v_add_u32_e32 v55, s78, v60
	v_add_u32_e32 v56, s78, v61
	v_add_u32_e32 v57, s78, v62
	ds_read_b64_tr_b4 v[46:47], v160 offset:768
	ds_read_b64_tr_b4 v[48:49], v160 offset:1792
	ds_read_b64_tr_b4 v[122:123], v54
	ds_read_b64_tr_b4 v[124:125], v55
	ds_read_b64_tr_b4 v[126:127], v56
	ds_read_b64_tr_b4 v[128:129], v57
	s_waitcnt lgkmcnt(7)
	v_dot8c_i32_i4_e32 v38, v130, v52
	v_dot8c_i32_i4_e32 v39, v130, v50
	v_dot8c_i32_i4_e32 v40, v132, v52
	v_dot8c_i32_i4_e32 v41, v132, v50
	v_dot8c_i32_i4_e32 v42, v134, v52
	v_dot8c_i32_i4_e32 v43, v134, v50
	v_dot8c_i32_i4_e32 v44, v136, v52
	v_dot8c_i32_i4_e32 v45, v136, v50
	v_dot8c_i32_i4_e32 v38, v131, v53
	v_dot8c_i32_i4_e32 v39, v131, v51
	v_dot8c_i32_i4_e32 v40, v133, v53
	v_dot8c_i32_i4_e32 v41, v133, v51
	v_dot8c_i32_i4_e32 v42, v135, v53
	v_dot8c_i32_i4_e32 v43, v135, v51
	v_dot8c_i32_i4_e32 v44, v137, v53
	v_dot8c_i32_i4_e32 v45, v137, v51
	v_and_b32_e32 v78, 0xffff, v29
	v_lshrrev_b32_e32 v79, 16, v29
	v_lshl_add_u32 v78, v78, 7, v150
	v_lshl_add_u32 v79, v79, 7, v151
	s_mov_b32 m0, s77
	s_add_i32 s43, s77, 0x400
	global_load_lds_dwordx4 v78, s[50:51]
	s_mov_b32 m0, s43
	s_nop 0
	global_load_lds_dwordx4 v79, s[50:51]
	s_waitcnt vmcnt(8)
	v_add_u32_e32 v54, s79, v59
	v_add_u32_e32 v55, s79, v60
	v_add_u32_e32 v56, s79, v61
	v_add_u32_e32 v57, s79, v62
	ds_read_b64_tr_b4 v[50:51], v160 offset:896
	ds_read_b64_tr_b4 v[52:53], v160 offset:1920
	ds_read_b64_tr_b4 v[130:131], v54
	ds_read_b64_tr_b4 v[132:133], v55
	ds_read_b64_tr_b4 v[134:135], v56
	ds_read_b64_tr_b4 v[136:137], v57
	s_waitcnt lgkmcnt(6)
; __device__ __forceinline__ void peer_v_tokens(int j, const LAS unsigned short* EL, const LAS unsigned char* AL  , const LAS float* ASC  , const LAS int* SAL  , ...
;     ...
; #pragma unroll 1
;     ...
;         for (int st = 0; st < 16; ++st) {
;             const int p = st >> 2, q = st & 3;
;             if (st < 14) VDMA(st + 2, (st + 2) % 3);
;             if (st < 14) asm volatile("s_waitcnt vmcnt(8)" ::: "memory");
;             else if (st == 14) asm volatile("s_waitcnt vmcnt(4)" ::: "memory");
;             else asm volatile("s_waitcnt vmcnt(0)" ::: "memory");
;             if (q == 0) {
; #pragma unroll
;                 for (int r = 0; r < 4; ++r) { accH[r] = 0; accL[r] = 0; } }
; #pragma unroll
;             for (int tp = 0; tp < 2; ++tp) {
;                 const v2i ao = TR4(ATL + (2 * q + tp) * 128 + 8 * s16), ah = TR4(ATL + 1024 + (2 * q + tp) * 128 + 8 * s16);
; #pragma unroll
;                 for (int r = 0; r < 4; ++r) {
;                     const v2i d = TR4(ldsb + BUF[st % 3] + 2048 * tp + roff[r]);
;                     accH[r] = __builtin_amdgcn_sdot8(d.x, ah.x, accH[r], false); accH[r] = __builtin_amdgcn_sdot8(d.y, ah.y, accH[r], false);
;                     accL[r] = __builtin_amdgcn_sdot8(d.x, ao.x, accL[r], false); accL[r] = __builtin_amdgcn_sdot8(d.y, ao.y, accL[r], false);
;                 }
;             }
;             asm volatile("s_waitcnt lgkmcnt(0)" ::: "memory");
;             if (q == 3) {
; #pragma unroll
;                 for (int r = 0; r < 4; ++r) STASH[256 * p + 16 * (grp + 4 * r) + pc] = f2bf(asc * (float)(2 * ((accH[r] << 4) + accL[r]) + sa));
;             }
;         }
;         CFENCE();
;         {
;             float4 v[4]; float ss = 0.f;
; #pragma unroll
;             for (int jq = 0; jq < 4; ++jq) { typedef unsigned u2v __attribute__((ext_vector_type(2))); const u2v pw = *(const LAS u2v*)(STASH + 4 * lane + 256 * jq); const uint2 hw = hv[jq];
;                 v[jq] = make_float4(__uint_as_float(hw.x << 16) + __uint_as_float(pw.x << 16), __uint_as_float(hw.x & 0xffff0000u) + __uint_as_float(pw.x & 0xffff0000u),
;                                     __uint_as_float(hw.y << 16) + __uint_as_float(pw.y << 16), __uint_as_float(hw.y & 0xffff0000u) + __uint_as_float(pw.y & 0xffff0000u));
;                 ss += v[jq].x * v[jq].x + v[jq].y * v[jq].y + v[jq].z * v[jq].z + v[jq].w * v[jq].w; }
	v_dot8c_i32_i4_e32 v38, v122, v48
	v_dot8c_i32_i4_e32 v39, v122, v46
	v_dot8c_i32_i4_e32 v40, v124, v48
	v_dot8c_i32_i4_e32 v41, v124, v46
	v_dot8c_i32_i4_e32 v42, v126, v48
	v_dot8c_i32_i4_e32 v43, v126, v46
	v_dot8c_i32_i4_e32 v44, v128, v48
	v_dot8c_i32_i4_e32 v45, v128, v46
	v_dot8c_i32_i4_e32 v38, v123, v49
	v_dot8c_i32_i4_e32 v39, v123, v47
	v_dot8c_i32_i4_e32 v40, v125, v49
	v_dot8c_i32_i4_e32 v41, v125, v47
	v_dot8c_i32_i4_e32 v42, v127, v49
	v_dot8c_i32_i4_e32 v43, v127, v47
	v_dot8c_i32_i4_e32 v44, v129, v49
	v_dot8c_i32_i4_e32 v45, v129, v47
	v_and_b32_e32 v78, 0xffff, v30
	v_lshrrev_b32_e32 v79, 16, v30
	v_lshl_add_u32 v78, v78, 7, v150
	v_lshl_add_u32 v79, v79, 7, v151
	s_mov_b32 m0, s78
	s_add_i32 s43, s78, 0x400
	global_load_lds_dwordx4 v78, s[50:51]
	s_mov_b32 m0, s43
	s_nop 0
	global_load_lds_dwordx4 v79, s[50:51]
	s_waitcnt vmcnt(8)
	v_add_u32_e32 v54, s98, v59
	v_add_u32_e32 v55, s98, v60
	v_add_u32_e32 v56, s98, v61
	v_add_u32_e32 v57, s98, v62
	ds_read_b64_tr_b4 v[46:47], v160
	ds_read_b64_tr_b4 v[48:49], v160 offset:1024
	ds_read_b64_tr_b4 v[122:123], v54
	ds_read_b64_tr_b4 v[124:125], v55
	ds_read_b64_tr_b4 v[126:127], v56
	ds_read_b64_tr_b4 v[128:129], v57
	s_waitcnt lgkmcnt(6)
	v_dot8c_i32_i4_e32 v38, v130, v52
	v_dot8c_i32_i4_e32 v39, v130, v50
	v_dot8c_i32_i4_e32 v40, v132, v52
	v_dot8c_i32_i4_e32 v41, v132, v50
	v_dot8c_i32_i4_e32 v42, v134, v52
	v_dot8c_i32_i4_e32 v43, v134, v50
	v_dot8c_i32_i4_e32 v44, v136, v52
	v_dot8c_i32_i4_e32 v45, v136, v50
	v_dot8c_i32_i4_e32 v38, v131, v53
	v_dot8c_i32_i4_e32 v39, v131, v51
	v_dot8c_i32_i4_e32 v40, v133, v53
	v_dot8c_i32_i4_e32 v41, v133, v51
	v_dot8c_i32_i4_e32 v42, v135, v53
	v_dot8c_i32_i4_e32 v43, v135, v51
	v_dot8c_i32_i4_e32 v44, v137, v53
	v_dot8c_i32_i4_e32 v45, v137, v51
	s_nop 3
	s_waitcnt lgkmcnt(15)
	v_lshlrev_b32_e32 v38, 5, v38
	v_lshlrev_b32_e32 v39, 1, v39
	v_add3_u32 v38, v39, v229, v38
	v_cvt_f32_i32_e32 v38, v38
	v_mul_f32_e32 v38, v228, v38
	v_lshlrev_b32_e32 v40, 5, v40
	v_lshlrev_b32_e32 v41, 1, v41
	v_add3_u32 v40, v41, v229, v40
	v_cvt_f32_i32_e32 v40, v40
	v_mul_f32_e32 v40, v228, v40
	v_lshlrev_b32_e32 v42, 5, v42
	v_lshlrev_b32_e32 v43, 1, v43
	v_add3_u32 v42, v43, v229, v42
	v_cvt_f32_i32_e32 v42, v42
	v_mul_f32_e32 v42, v228, v42
	v_lshlrev_b32_e32 v44, 5, v44
	v_lshlrev_b32_e32 v45, 1, v45
	v_add3_u32 v44, v45, v229, v44
	v_cvt_f32_i32_e32 v44, v44
	v_mul_f32_e32 v44, v228, v44
	v_cvt_pk_bf16_f32 v162, v38, v40
	v_cvt_pk_bf16_f32 v163, v42, v44
	v_add_u32_e32 v147, 8, v140
	v_and_b32_e32 v146, 15, v147
	v_xor_b32_e32 v146, 8, v146
	v_bfe_u32 v148, v147, 4, 4
	v_mul_lo_u32 v146, v146, s92
	v_mul_lo_u32 v148, v148, s92
	v_mov_b32_e32 v147, v146
	v_mov_b32_e32 v149, v148
	ds_write2st64_b64 v77, v[146:147], v[148:149] offset1:2
	v_add_u32_e32 v138, 0x1000, v74
	ds_read_u8 v139, v138
	v_add_u32_e32 v141, 0x1000, v73
	ds_read_u8 v140, v141
	s_add_i32 s43, s67, 160
	v_mov_b32_e32 v138, s43
	ds_read2st64_b32 v[228:229], v138 offset1:1
	ds_read_b128 v[18:21], v227 offset:8192
	ds_read_b128 v[22:25], v227 offset:8208
	v_add_u32_e32 v152, 0x200000, v63
	v_add_u32_e32 v153, 0x200000, v64
	v_mov_b32_e32 v38, 0
	v_mov_b32_e32 v39, 0
	v_mov_b32_e32 v40, 0
	v_mov_b32_e32 v41, 0
	v_mov_b32_e32 v42, 0
	v_mov_b32_e32 v43, 0
	v_mov_b32_e32 v44, 0
	v_mov_b32_e32 v45, 0
	v_and_b32_e32 v78, 0xffff, v31
	v_lshrrev_b32_e32 v79, 16, v31
	v_lshl_add_u32 v78, v78, 7, v150
	v_lshl_add_u32 v79, v79, 7, v151
	s_mov_b32 m0, s79
	s_add_i32 s43, s79, 0x400
	global_load_lds_dwordx4 v78, s[50:51]
	s_mov_b32 m0, s43
	s_nop 0
	global_load_lds_dwordx4 v79, s[50:51]
	s_waitcnt vmcnt(8)
	v_add_u32_e32 v54, s99, v59
	v_add_u32_e32 v55, s99, v60
	v_add_u32_e32 v56, s99, v61
	v_add_u32_e32 v57, s99, v62
	ds_read_b64_tr_b4 v[50:51], v160 offset:128
	ds_read_b64_tr_b4 v[52:53], v160 offset:1152
	ds_read_b64_tr_b4 v[130:131], v54
	ds_read_b64_tr_b4 v[132:133], v55
	ds_read_b64_tr_b4 v[134:135], v56
	ds_read_b64_tr_b4 v[136:137], v57
	s_waitcnt lgkmcnt(12)
	s_waitcnt vmcnt(35) lgkmcnt(15)
	v_lshlrev_b32_e32 v210, 16, v194
	v_and_b32_e32 v211, 0xffff0000, v194
	v_lshlrev_b32_e32 v142, 16, v202
	v_and_b32_e32 v143, 0xffff0000, v202
	v_add_f32_e32 v210, v210, v142
	v_add_f32_e32 v211, v211, v143
	v_lshlrev_b32_e32 v212, 16, v195
	v_and_b32_e32 v213, 0xffff0000, v195
	v_lshlrev_b32_e32 v142, 16, v203
	v_and_b32_e32 v143, 0xffff0000, v203
	v_add_f32_e32 v212, v212, v142
	v_add_f32_e32 v213, v213, v143
	v_lshlrev_b32_e32 v214, 16, v196
	v_and_b32_e32 v215, 0xffff0000, v196
	v_lshlrev_b32_e32 v142, 16, v204
	v_and_b32_e32 v143, 0xffff0000, v204
	v_add_f32_e32 v214, v214, v142
	v_add_f32_e32 v215, v215, v143
	v_lshlrev_b32_e32 v216, 16, v197
	v_and_b32_e32 v217, 0xffff0000, v197
	v_lshlrev_b32_e32 v142, 16, v205
	v_and_b32_e32 v143, 0xffff0000, v205
	v_add_f32_e32 v216, v216, v142
	v_add_f32_e32 v217, v217, v143
	v_lshlrev_b32_e32 v218, 16, v198
	v_and_b32_e32 v219, 0xffff0000, v198
	v_lshlrev_b32_e32 v142, 16, v206
	v_and_b32_e32 v143, 0xffff0000, v206
	v_add_f32_e32 v218, v218, v142
	v_add_f32_e32 v219, v219, v143
	v_lshlrev_b32_e32 v220, 16, v199
	v_and_b32_e32 v221, 0xffff0000, v199
	v_lshlrev_b32_e32 v142, 16, v207
	v_and_b32_e32 v143, 0xffff0000, v207
	v_add_f32_e32 v220, v220, v142
	v_add_f32_e32 v221, v221, v143
	v_lshlrev_b32_e32 v222, 16, v200
	v_and_b32_e32 v223, 0xffff0000, v200
	v_lshlrev_b32_e32 v142, 16, v208
	v_and_b32_e32 v143, 0xffff0000, v208
	v_add_f32_e32 v222, v222, v142
	v_add_f32_e32 v223, v223, v143
	v_lshlrev_b32_e32 v224, 16, v201
	v_and_b32_e32 v225, 0xffff0000, v201
	v_lshlrev_b32_e32 v142, 16, v209
	v_and_b32_e32 v143, 0xffff0000, v209
	v_add_f32_e32 v224, v224, v142
; #define TR4(p_) __builtin_amdgcn_ds_read_tr4_b64_v2i32((LAS v2i*)(p_))
; #define VDMA(st_, k_) do { _Pragma("unroll") for (int i_ = 0; i_ < 4; ++i_) { \
;         const unsigned off_ = (unsigned)((st_) >> 2) * (16384u * 128u) + (PE_ID(E, 4 * ((st_) & 3) + i_) << 7) + ((i_ & 1) ? cx1 : cx0); \
;         __builtin_amdgcn_global_load_lds((const unsigned*)(V4 + off_), (LAS unsigned*)(ldsb + BUF[k_] + 1024 * i_), 16, 0, 0); } } while (0)
; __device__ __forceinline__ void peer_v_tokens(int j, const LAS unsigned short* EL, const LAS unsigned char* AL  , const LAS float* ASC  , const LAS int* SAL  , ...
;     ...
;         for (int st = 0; st < 16; ++st) {
;             const int p = st >> 2, q = st & 3;
;             if (st < 14) VDMA(st + 2, (st + 2) % 3);
;             if (st < 14) asm volatile("s_waitcnt vmcnt(8)" ::: "memory");
;             else if (st == 14) asm volatile("s_waitcnt vmcnt(4)" ::: "memory");
;             else asm volatile("s_waitcnt vmcnt(0)" ::: "memory");
;             if (q == 0) {
; #pragma unroll
;                 for (int r = 0; r < 4; ++r) { accH[r] = 0; accL[r] = 0; } }
; #pragma unroll
;             for (int tp = 0; tp < 2; ++tp) {
;                 const v2i ao = TR4(ATL + (2 * q + tp) * 128 + 8 * s16), ah = TR4(ATL + 1024 + (2 * q + tp) * 128 + 8 * s16);
; #pragma unroll
;                 for (int r = 0; r < 4; ++r) {
;                     const v2i d = TR4(ldsb + BUF[st % 3] + 2048 * tp + roff[r]);
;                     accH[r] = __builtin_amdgcn_sdot8(d.x, ah.x, accH[r], false); accH[r] = __builtin_amdgcn_sdot8(d.y, ah.y, accH[r], false);
;                     accL[r] = __builtin_amdgcn_sdot8(d.x, ao.x, accL[r], false); accL[r] = __builtin_amdgcn_sdot8(d.y, ao.y, accL[r], false);
;                 }
;             }
;     ...
;                 ss += v[jq].x * v[jq].x + v[jq].y * v[jq].y + v[jq].z * v[jq].z + v[jq].w * v[jq].w; }
;             ss = wave_sum(ss);
;             const float r3 = rsqrtf(ss * (1.f / D) + EPS);
	v_add_f32_e32 v225, v225, v143
	v_mov_b32_e32 v144, 0
	v_mul_f32_e32 v145, v210, v210
	v_fmac_f32_e32 v145, v211, v211
	v_fmac_f32_e32 v145, v212, v212
	v_fmac_f32_e32 v145, v213, v213
	v_add_f32_e32 v144, v144, v145
	v_mul_f32_e32 v145, v214, v214
	v_fmac_f32_e32 v145, v215, v215
	v_fmac_f32_e32 v145, v216, v216
	v_fmac_f32_e32 v145, v217, v217
	v_add_f32_e32 v144, v144, v145
	v_mul_f32_e32 v145, v218, v218
	v_fmac_f32_e32 v145, v219, v219
	v_fmac_f32_e32 v145, v220, v220
	v_fmac_f32_e32 v145, v221, v221
	v_add_f32_e32 v144, v144, v145
	v_mul_f32_e32 v145, v222, v222
	v_fmac_f32_e32 v145, v223, v223
	v_fmac_f32_e32 v145, v224, v224
	v_fmac_f32_e32 v145, v225, v225
	v_add_f32_e32 v144, v144, v145
	s_nop 1
	v_add_f32_dpp v144, v144, v144 quad_perm:[1,0,3,2] row_mask:0xf bank_mask:0xf bound_ctrl:1
	s_nop 1
	v_add_f32_dpp v144, v144, v144 quad_perm:[2,3,0,1] row_mask:0xf bank_mask:0xf bound_ctrl:1
	s_nop 1
	v_add_f32_dpp v144, v144, v144 row_half_mirror row_mask:0xf bank_mask:0xf bound_ctrl:1
	s_nop 1
	v_add_f32_dpp v144, v144, v144 row_mirror row_mask:0xf bank_mask:0xf bound_ctrl:1
	s_nop 1
	v_readlane_b32 s10, v144, 0
	v_readlane_b32 s11, v144, 16
	v_readlane_b32 s14, v144, 32
	v_readlane_b32 s15, v144, 48
	s_nop 3
	v_mov_b32_e32 v144, s11
	v_mov_b32_e32 v145, s15
	v_add_f32_e32 v144, s10, v144
	v_add_f32_e32 v145, s14, v145
	v_add_f32_e32 v144, v144, v145
	v_fmamk_f32 v144, v144, 0x3a800000, v111
	v_rsq_f32_e32 v144, v144
	s_nop 0
	v_mul_f32_e32 v210, v210, v144
	v_mul_f32_e32 v211, v211, v144
	v_mul_f32_e32 v212, v212, v144
	v_mul_f32_e32 v213, v213, v144
	v_mul_f32_e32 v214, v214, v144
	v_mul_f32_e32 v215, v215, v144
	v_mul_f32_e32 v216, v216, v144
	v_mul_f32_e32 v217, v217, v144
	v_mul_f32_e32 v218, v218, v144
	v_mul_f32_e32 v219, v219, v144
	v_mul_f32_e32 v220, v220, v144
	v_mul_f32_e32 v221, v221, v144
	v_mul_f32_e32 v222, v222, v144
	v_mul_f32_e32 v223, v223, v144
	v_mul_f32_e32 v224, v224, v144
	v_mul_f32_e32 v225, v225, v144
	v_dot8c_i32_i4_e32 v38, v122, v48
	v_dot8c_i32_i4_e32 v39, v122, v46
	v_dot8c_i32_i4_e32 v40, v124, v48
	v_dot8c_i32_i4_e32 v41, v124, v46
	v_dot8c_i32_i4_e32 v42, v126, v48
	v_dot8c_i32_i4_e32 v43, v126, v46
	v_dot8c_i32_i4_e32 v44, v128, v48
	v_dot8c_i32_i4_e32 v45, v128, v46
	v_dot8c_i32_i4_e32 v38, v123, v49
	v_dot8c_i32_i4_e32 v39, v123, v47
	v_dot8c_i32_i4_e32 v40, v125, v49
	v_dot8c_i32_i4_e32 v41, v125, v47
	v_dot8c_i32_i4_e32 v42, v127, v49
	v_dot8c_i32_i4_e32 v43, v127, v47
	v_dot8c_i32_i4_e32 v44, v129, v49
	v_dot8c_i32_i4_e32 v45, v129, v47
	v_and_b32_e32 v78, 0xffff, v32
	v_lshrrev_b32_e32 v79, 16, v32
	v_lshl_add_u32 v78, v78, 7, v150
	v_lshl_add_u32 v79, v79, 7, v151
	s_mov_b32 m0, s98
	s_add_i32 s43, s98, 0x400
	global_load_lds_dwordx4 v78, s[50:51]
	s_mov_b32 m0, s43
	s_nop 0
	global_load_lds_dwordx4 v79, s[50:51]
	s_waitcnt vmcnt(8)
	v_add_u32_e32 v54, s76, v59
	v_add_u32_e32 v55, s76, v60
	v_add_u32_e32 v56, s76, v61
	v_add_u32_e32 v57, s76, v62
	ds_read_b64_tr_b4 v[46:47], v160 offset:256
	ds_read_b64_tr_b4 v[48:49], v160 offset:1280
	ds_read_b64_tr_b4 v[122:123], v54
	ds_read_b64_tr_b4 v[124:125], v55
	ds_read_b64_tr_b4 v[126:127], v56
	ds_read_b64_tr_b4 v[128:129], v57
	s_waitcnt lgkmcnt(6)
	v_dot8c_i32_i4_e32 v38, v130, v52
	v_dot8c_i32_i4_e32 v39, v130, v50
	v_dot8c_i32_i4_e32 v40, v132, v52
	v_dot8c_i32_i4_e32 v41, v132, v50
	v_dot8c_i32_i4_e32 v42, v134, v52
	v_dot8c_i32_i4_e32 v43, v134, v50
	v_dot8c_i32_i4_e32 v44, v136, v52
	v_dot8c_i32_i4_e32 v45, v136, v50
	v_dot8c_i32_i4_e32 v38, v131, v53
	v_dot8c_i32_i4_e32 v39, v131, v51
	v_dot8c_i32_i4_e32 v40, v133, v53
	v_dot8c_i32_i4_e32 v41, v133, v51
	v_dot8c_i32_i4_e32 v42, v135, v53
	v_dot8c_i32_i4_e32 v43, v135, v51
	v_dot8c_i32_i4_e32 v44, v137, v53
	v_dot8c_i32_i4_e32 v45, v137, v51
	v_and_b32_e32 v78, 0xffff, v33
	v_lshrrev_b32_e32 v79, 16, v33
	v_lshl_add_u32 v78, v78, 7, v150
	v_lshl_add_u32 v79, v79, 7, v151
	s_mov_b32 m0, s99
	s_add_i32 s43, s99, 0x400
	global_load_lds_dwordx4 v78, s[50:51]
	s_mov_b32 m0, s43
	s_nop 0
	global_load_lds_dwordx4 v79, s[50:51]
	s_waitcnt vmcnt(8)
	v_add_u32_e32 v54, s77, v59
	v_add_u32_e32 v55, s77, v60
	v_add_u32_e32 v56, s77, v61
	v_add_u32_e32 v57, s77, v62
	ds_read_b64_tr_b4 v[50:51], v160 offset:384
	ds_read_b64_tr_b4 v[52:53], v160 offset:1408
	ds_read_b64_tr_b4 v[130:131], v54
	ds_read_b64_tr_b4 v[132:133], v55
	ds_read_b64_tr_b4 v[134:135], v56
	ds_read_b64_tr_b4 v[136:137], v57
	s_waitcnt lgkmcnt(6)
	v_dot8c_i32_i4_e32 v38, v122, v48
	v_dot8c_i32_i4_e32 v39, v122, v46
	v_dot8c_i32_i4_e32 v40, v124, v48
	v_dot8c_i32_i4_e32 v41, v124, v46
	v_dot8c_i32_i4_e32 v42, v126, v48
	v_dot8c_i32_i4_e32 v43, v126, v46
	v_dot8c_i32_i4_e32 v44, v128, v48
	v_dot8c_i32_i4_e32 v45, v128, v46
	v_dot8c_i32_i4_e32 v38, v123, v49
	v_dot8c_i32_i4_e32 v39, v123, v47
	v_dot8c_i32_i4_e32 v40, v125, v49
	v_dot8c_i32_i4_e32 v41, v125, v47
	v_dot8c_i32_i4_e32 v42, v127, v49
	v_dot8c_i32_i4_e32 v43, v127, v47
	v_dot8c_i32_i4_e32 v44, v129, v49
	v_dot8c_i32_i4_e32 v45, v129, v47
	s_waitcnt lgkmcnt(15)
	v_and_b32_e32 v78, 0xffff, v18
	v_lshrrev_b32_e32 v79, 16, v18
	v_lshl_add_u32 v78, v78, 7, v152
	v_lshl_add_u32 v79, v79, 7, v153
	s_mov_b32 m0, s76
	s_add_i32 s43, s76, 0x400
	global_load_lds_dwordx4 v78, s[50:51]
	s_mov_b32 m0, s43
	s_nop 0
	global_load_lds_dwordx4 v79, s[50:51]
	s_waitcnt vmcnt(8)
	v_add_u32_e32 v54, s78, v59
	v_add_u32_e32 v55, s78, v60
	v_add_u32_e32 v56, s78, v61
	v_add_u32_e32 v57, s78, v62
	ds_read_b64_tr_b4 v[46:47], v160 offset:512
	ds_read_b64_tr_b4 v[48:49], v160 offset:1536
	ds_read_b64_tr_b4 v[122:123], v54
	ds_read_b64_tr_b4 v[124:125], v55
	ds_read_b64_tr_b4 v[126:127], v56
	ds_read_b64_tr_b4 v[128:129], v57
	s_waitcnt lgkmcnt(6)
; #define TR4(p_) __builtin_amdgcn_ds_read_tr4_b64_v2i32((LAS v2i*)(p_))
; #define VDMA(st_, k_) do { _Pragma("unroll") for (int i_ = 0; i_ < 4; ++i_) { \
;         const unsigned off_ = (unsigned)((st_) >> 2) * (16384u * 128u) + (PE_ID(E, 4 * ((st_) & 3) + i_) << 7) + ((i_ & 1) ? cx1 : cx0); \
;         __builtin_amdgcn_global_load_lds((const unsigned*)(V4 + off_), (LAS unsigned*)(ldsb + BUF[k_] + 1024 * i_), 16, 0, 0); } } while (0)
; __device__ __forceinline__ void peer_v_tokens(int j, const LAS unsigned short* EL, const LAS unsigned char* AL  , const LAS float* ASC  , const LAS int* SAL  , ...
;     ...
;         for (int st = 0; st < 16; ++st) {
;             const int p = st >> 2, q = st & 3;
;             if (st < 14) VDMA(st + 2, (st + 2) % 3);
;             if (st < 14) asm volatile("s_waitcnt vmcnt(8)" ::: "memory");
;             else if (st == 14) asm volatile("s_waitcnt vmcnt(4)" ::: "memory");
;             else asm volatile("s_waitcnt vmcnt(0)" ::: "memory");
;             if (q == 0) {
; #pragma unroll
;                 for (int r = 0; r < 4; ++r) { accH[r] = 0; accL[r] = 0; } }
; #pragma unroll
;             for (int tp = 0; tp < 2; ++tp) {
;                 const v2i ao = TR4(ATL + (2 * q + tp) * 128 + 8 * s16), ah = TR4(ATL + 1024 + (2 * q + tp) * 128 + 8 * s16);
; #pragma unroll
;                 for (int r = 0; r < 4; ++r) {
;                     const v2i d = TR4(ldsb + BUF[st % 3] + 2048 * tp + roff[r]);
;                     accH[r] = __builtin_amdgcn_sdot8(d.x, ah.x, accH[r], false); accH[r] = __builtin_amdgcn_sdot8(d.y, ah.y, accH[r], false);
;                     accL[r] = __builtin_amdgcn_sdot8(d.x, ao.x, accL[r], false); accL[r] = __builtin_amdgcn_sdot8(d.y, ao.y, accL[r], false);
;                 }
;             }
	v_dot8c_i32_i4_e32 v38, v130, v52
	v_dot8c_i32_i4_e32 v39, v130, v50
	v_dot8c_i32_i4_e32 v40, v132, v52
	v_dot8c_i32_i4_e32 v41, v132, v50
	v_dot8c_i32_i4_e32 v42, v134, v52
	v_dot8c_i32_i4_e32 v43, v134, v50
	v_dot8c_i32_i4_e32 v44, v136, v52
	v_dot8c_i32_i4_e32 v45, v136, v50
	v_dot8c_i32_i4_e32 v38, v131, v53
	v_dot8c_i32_i4_e32 v39, v131, v51
	v_dot8c_i32_i4_e32 v40, v133, v53
	v_dot8c_i32_i4_e32 v41, v133, v51
	v_dot8c_i32_i4_e32 v42, v135, v53
	v_dot8c_i32_i4_e32 v43, v135, v51
	v_dot8c_i32_i4_e32 v44, v137, v53
	v_dot8c_i32_i4_e32 v45, v137, v51
	v_and_b32_e32 v78, 0xffff, v19
	v_lshrrev_b32_e32 v79, 16, v19
	v_lshl_add_u32 v78, v78, 7, v152
	v_lshl_add_u32 v79, v79, 7, v153
	s_mov_b32 m0, s77
	s_add_i32 s43, s77, 0x400
	global_load_lds_dwordx4 v78, s[50:51]
	s_mov_b32 m0, s43
	s_nop 0
	global_load_lds_dwordx4 v79, s[50:51]
	s_waitcnt vmcnt(8)
	v_add_u32_e32 v54, s79, v59
	v_add_u32_e32 v55, s79, v60
	v_add_u32_e32 v56, s79, v61
	v_add_u32_e32 v57, s79, v62
	ds_read_b64_tr_b4 v[50:51], v160 offset:640
	ds_read_b64_tr_b4 v[52:53], v160 offset:1664
	ds_read_b64_tr_b4 v[130:131], v54
	ds_read_b64_tr_b4 v[132:133], v55
	ds_read_b64_tr_b4 v[134:135], v56
	ds_read_b64_tr_b4 v[136:137], v57
	s_waitcnt lgkmcnt(6)
	v_dot8c_i32_i4_e32 v38, v122, v48
	v_dot8c_i32_i4_e32 v39, v122, v46
	v_dot8c_i32_i4_e32 v40, v124, v48
	v_dot8c_i32_i4_e32 v41, v124, v46
	v_dot8c_i32_i4_e32 v42, v126, v48
	v_dot8c_i32_i4_e32 v43, v126, v46
	v_dot8c_i32_i4_e32 v44, v128, v48
	v_dot8c_i32_i4_e32 v45, v128, v46
	v_dot8c_i32_i4_e32 v38, v123, v49
	v_dot8c_i32_i4_e32 v39, v123, v47
	v_dot8c_i32_i4_e32 v40, v125, v49
	v_dot8c_i32_i4_e32 v41, v125, v47
	v_dot8c_i32_i4_e32 v42, v127, v49
	v_dot8c_i32_i4_e32 v43, v127, v47
	v_dot8c_i32_i4_e32 v44, v129, v49
	v_dot8c_i32_i4_e32 v45, v129, v47
	s_waitcnt lgkmcnt(15)
	v_add_u32_e32 v143, 8, v139
	v_and_b32_e32 v142, 15, v143
	v_xor_b32_e32 v142, 8, v142
	v_bfe_u32 v144, v143, 4, 4
	v_mul_lo_u32 v142, v142, s92
	v_mul_lo_u32 v144, v144, s92
	v_mov_b32_e32 v143, v142
	v_mov_b32_e32 v145, v144
	ds_write2st64_b64 v159, v[142:143], v[144:145] offset1:2
	v_and_b32_e32 v78, 0xffff, v20
	v_lshrrev_b32_e32 v79, 16, v20
	v_lshl_add_u32 v78, v78, 7, v152
	v_lshl_add_u32 v79, v79, 7, v153
	s_mov_b32 m0, s78
	s_add_i32 s43, s78, 0x400
	global_load_lds_dwordx4 v78, s[50:51]
	s_mov_b32 m0, s43
	s_nop 0
	global_load_lds_dwordx4 v79, s[50:51]
	s_waitcnt vmcnt(8)
	v_add_u32_e32 v54, s98, v59
	v_add_u32_e32 v55, s98, v60
	v_add_u32_e32 v56, s98, v61
	v_add_u32_e32 v57, s98, v62
	ds_read_b64_tr_b4 v[46:47], v160 offset:768
	ds_read_b64_tr_b4 v[48:49], v160 offset:1792
	ds_read_b64_tr_b4 v[122:123], v54
	ds_read_b64_tr_b4 v[124:125], v55
	ds_read_b64_tr_b4 v[126:127], v56
	ds_read_b64_tr_b4 v[128:129], v57
	s_waitcnt lgkmcnt(7)
	v_dot8c_i32_i4_e32 v38, v130, v52
	v_dot8c_i32_i4_e32 v39, v130, v50
	v_dot8c_i32_i4_e32 v40, v132, v52
	v_dot8c_i32_i4_e32 v41, v132, v50
	v_dot8c_i32_i4_e32 v42, v134, v52
	v_dot8c_i32_i4_e32 v43, v134, v50
	v_dot8c_i32_i4_e32 v44, v136, v52
	v_dot8c_i32_i4_e32 v45, v136, v50
	v_dot8c_i32_i4_e32 v38, v131, v53
	v_dot8c_i32_i4_e32 v39, v131, v51
	v_dot8c_i32_i4_e32 v40, v133, v53
	v_dot8c_i32_i4_e32 v41, v133, v51
	v_dot8c_i32_i4_e32 v42, v135, v53
	v_dot8c_i32_i4_e32 v43, v135, v51
	v_dot8c_i32_i4_e32 v44, v137, v53
	v_dot8c_i32_i4_e32 v45, v137, v51
	v_and_b32_e32 v78, 0xffff, v21
	v_lshrrev_b32_e32 v79, 16, v21
	v_lshl_add_u32 v78, v78, 7, v152
	v_lshl_add_u32 v79, v79, 7, v153
	s_mov_b32 m0, s79
	s_add_i32 s43, s79, 0x400
	global_load_lds_dwordx4 v78, s[50:51]
	s_mov_b32 m0, s43
	s_nop 0
	global_load_lds_dwordx4 v79, s[50:51]
	s_waitcnt vmcnt(8)
	v_add_u32_e32 v54, s99, v59
	v_add_u32_e32 v55, s99, v60
	v_add_u32_e32 v56, s99, v61
	v_add_u32_e32 v57, s99, v62
	ds_read_b64_tr_b4 v[50:51], v160 offset:896
	ds_read_b64_tr_b4 v[52:53], v160 offset:1920
	ds_read_b64_tr_b4 v[130:131], v54
	ds_read_b64_tr_b4 v[132:133], v55
	ds_read_b64_tr_b4 v[134:135], v56
	ds_read_b64_tr_b4 v[136:137], v57
	s_waitcnt lgkmcnt(6)
	v_dot8c_i32_i4_e32 v38, v122, v48
	v_dot8c_i32_i4_e32 v39, v122, v46
	v_dot8c_i32_i4_e32 v40, v124, v48
	v_dot8c_i32_i4_e32 v41, v124, v46
	v_dot8c_i32_i4_e32 v42, v126, v48
	v_dot8c_i32_i4_e32 v43, v126, v46
	v_dot8c_i32_i4_e32 v44, v128, v48
	v_dot8c_i32_i4_e32 v45, v128, v46
	v_dot8c_i32_i4_e32 v38, v123, v49
	v_dot8c_i32_i4_e32 v39, v123, v47
	v_dot8c_i32_i4_e32 v40, v125, v49
	v_dot8c_i32_i4_e32 v41, v125, v47
	v_dot8c_i32_i4_e32 v42, v127, v49
	v_dot8c_i32_i4_e32 v43, v127, v47
	v_dot8c_i32_i4_e32 v44, v129, v49
	v_dot8c_i32_i4_e32 v45, v129, v47
	v_and_b32_e32 v78, 0xffff, v22
	v_lshrrev_b32_e32 v79, 16, v22
	v_lshl_add_u32 v78, v78, 7, v152
	v_lshl_add_u32 v79, v79, 7, v153
	s_mov_b32 m0, s98
	s_add_i32 s43, s98, 0x400
	global_load_lds_dwordx4 v78, s[50:51]
	s_mov_b32 m0, s43
	s_nop 0
	global_load_lds_dwordx4 v79, s[50:51]
	s_waitcnt vmcnt(8)
	v_add_u32_e32 v54, s76, v59
	v_add_u32_e32 v55, s76, v60
	v_add_u32_e32 v56, s76, v61
	v_add_u32_e32 v57, s76, v62
	ds_read_b64_tr_b4 v[46:47], v160
	ds_read_b64_tr_b4 v[48:49], v160 offset:1024
	ds_read_b64_tr_b4 v[122:123], v54
	ds_read_b64_tr_b4 v[124:125], v55
	ds_read_b64_tr_b4 v[126:127], v56
	ds_read_b64_tr_b4 v[128:129], v57
	s_waitcnt lgkmcnt(6)
	v_dot8c_i32_i4_e32 v38, v130, v52
	v_dot8c_i32_i4_e32 v39, v130, v50
	v_dot8c_i32_i4_e32 v40, v132, v52
	v_dot8c_i32_i4_e32 v41, v132, v50
	v_dot8c_i32_i4_e32 v42, v134, v52
	v_dot8c_i32_i4_e32 v43, v134, v50
	v_dot8c_i32_i4_e32 v44, v136, v52
	v_dot8c_i32_i4_e32 v45, v136, v50
	v_dot8c_i32_i4_e32 v38, v131, v53
	v_dot8c_i32_i4_e32 v39, v131, v51
	v_dot8c_i32_i4_e32 v40, v133, v53
	v_dot8c_i32_i4_e32 v41, v133, v51
	v_dot8c_i32_i4_e32 v42, v135, v53
	v_dot8c_i32_i4_e32 v43, v135, v51
	v_dot8c_i32_i4_e32 v44, v137, v53
	v_dot8c_i32_i4_e32 v45, v137, v51
	s_nop 3
	s_waitcnt lgkmcnt(15)
; __device__ __forceinline__ bf16 f2bf(float f) { return (bf16)f2bfu(f); }
; __device__ __forceinline__ void peer_v_tokens(int j, const LAS unsigned short* EL, const LAS unsigned char* AL  , const LAS float* ASC  , const LAS int* SAL  , ...
;     ...
;         { unsigned ho = (unsigned)t * (D / 4) + (unsigned)lane; asm volatile("" : "+v"(ho)); const uint2* hp = (const uint2*)HB + ho; const float4* gp = (const float4*)fng + lane;
; #pragma unroll
;           for (int jq = 0; jq < 4; ++jq) { hv[jq] = hp[64 * jq]; gv[jq] = gp[64 * jq]; } }
;     ...
;             if (q == 3) {
; #pragma unroll
;                 for (int r = 0; r < 4; ++r) STASH[256 * p + 16 * (grp + 4 * r) + pc] = f2bf(asc * (float)(2 * ((accH[r] << 4) + accL[r]) + sa));
;     ...
;             float4* op = (float4*)(outp + (size_t)t * D) + lane;
; #pragma unroll
;             for (int jq = 0; jq < 4; ++jq) { typedef float f4v __attribute__((ext_vector_type(4))); f4v o4; o4.x = v[jq].x * r3 * gv[jq].x; o4.y = v[jq].y * r3 * gv[jq].y; o4.z = v[jq].z * r3 * gv[jq].z; o4.w = v[jq].w * r3 * gv[jq].w;
;                 __builtin_nontemporal_store(o4, (f4v*)op + 64 * jq); }
	v_lshlrev_b32_e32 v38, 5, v38
	v_lshlrev_b32_e32 v39, 1, v39
	v_add3_u32 v38, v39, v229, v38
	v_cvt_f32_i32_e32 v38, v38
	v_mul_f32_e32 v38, v228, v38
	v_lshlrev_b32_e32 v40, 5, v40
	v_lshlrev_b32_e32 v41, 1, v41
	v_add3_u32 v40, v41, v229, v40
	v_cvt_f32_i32_e32 v40, v40
	v_mul_f32_e32 v40, v228, v40
	v_lshlrev_b32_e32 v42, 5, v42
	v_lshlrev_b32_e32 v43, 1, v43
	v_add3_u32 v42, v43, v229, v42
	v_cvt_f32_i32_e32 v42, v42
	v_mul_f32_e32 v42, v228, v42
	v_lshlrev_b32_e32 v44, 5, v44
	v_lshlrev_b32_e32 v45, 1, v45
	v_add3_u32 v44, v45, v229, v44
	v_cvt_f32_i32_e32 v44, v44
	v_mul_f32_e32 v44, v228, v44
	v_cvt_pk_bf16_f32 v170, v38, v40
	v_cvt_pk_bf16_f32 v171, v42, v44
	ds_read_b128 v[252:255], v155
	s_add_i32 s44, s40, 16
	s_ashr_i32 s45, s44, 31
	s_lshl_b64 s[44:45], s[44:45], 12
	v_lshl_add_u64 v[80:81], v[36:37], 0, s[44:45]
	s_waitcnt lgkmcnt(0)
	v_mul_f32_e32 v210, v210, v252
	v_mul_f32_e32 v211, v211, v253
	v_mul_f32_e32 v212, v212, v254
	v_mul_f32_e32 v213, v213, v255
	global_store_dwordx4 v[80:81], v[210:213], off nt
	s_add_i32 s43, s40, 24
	s_lshl_b32 s43, s43, 11
	v_add_u32_e32 v138, s43, v66
	global_load_dwordx2 v[194:195], v138, s[70:71]
	global_load_dwordx2 v[196:197], v138, s[70:71] offset:512
	global_load_dwordx2 v[198:199], v138, s[70:71] offset:1024
	global_load_dwordx2 v[200:201], v138, s[70:71] offset:1536
	v_add_u32_e32 v147, 8, v140
	v_and_b32_e32 v146, 15, v147
	v_xor_b32_e32 v146, 8, v146
	v_bfe_u32 v148, v147, 4, 4
	v_mul_lo_u32 v146, v146, s92
	v_mul_lo_u32 v148, v148, s92
	v_mov_b32_e32 v147, v146
	v_mov_b32_e32 v149, v148
	ds_write2st64_b64 v77, v[146:147], v[148:149] offset1:2
	v_add_u32_e32 v138, 0x1400, v74
	ds_read_u8 v139, v138
	v_add_u32_e32 v141, 0x1400, v73
	ds_read_u8 v140, v141
	s_add_i32 s43, s67, 128
	v_mov_b32_e32 v138, s43
	ds_read2st64_b32 v[228:229], v138 offset1:1
	ds_read_b128 v[26:29], v227 offset:10240
	ds_read_b128 v[30:33], v227 offset:10256
	v_mov_b32_e32 v38, 0
	v_mov_b32_e32 v39, 0
	v_mov_b32_e32 v40, 0
	v_mov_b32_e32 v41, 0
	v_mov_b32_e32 v42, 0
	v_mov_b32_e32 v43, 0
	v_mov_b32_e32 v44, 0
	v_mov_b32_e32 v45, 0
	v_and_b32_e32 v78, 0xffff, v23
	v_lshrrev_b32_e32 v79, 16, v23
	v_lshl_add_u32 v78, v78, 7, v152
	v_lshl_add_u32 v79, v79, 7, v153
	s_mov_b32 m0, s99
	s_add_i32 s43, s99, 0x400
	global_load_lds_dwordx4 v78, s[50:51]
	s_mov_b32 m0, s43
	s_nop 0
	global_load_lds_dwordx4 v79, s[50:51]
	s_waitcnt vmcnt(13)
	v_add_u32_e32 v54, s77, v59
	v_add_u32_e32 v55, s77, v60
	v_add_u32_e32 v56, s77, v61
	v_add_u32_e32 v57, s77, v62
	ds_read_b64_tr_b4 v[50:51], v160 offset:128
	ds_read_b64_tr_b4 v[52:53], v160 offset:1152
	ds_read_b64_tr_b4 v[130:131], v54
	ds_read_b64_tr_b4 v[132:133], v55
	ds_read_b64_tr_b4 v[134:135], v56
	ds_read_b64_tr_b4 v[136:137], v57
	s_waitcnt lgkmcnt(13)
	v_dot8c_i32_i4_e32 v38, v122, v48
	v_dot8c_i32_i4_e32 v39, v122, v46
	v_dot8c_i32_i4_e32 v40, v124, v48
	v_dot8c_i32_i4_e32 v41, v124, v46
	v_dot8c_i32_i4_e32 v42, v126, v48
	v_dot8c_i32_i4_e32 v43, v126, v46
	v_dot8c_i32_i4_e32 v44, v128, v48
	v_dot8c_i32_i4_e32 v45, v128, v46
	v_dot8c_i32_i4_e32 v38, v123, v49
	v_dot8c_i32_i4_e32 v39, v123, v47
	v_dot8c_i32_i4_e32 v40, v125, v49
	v_dot8c_i32_i4_e32 v41, v125, v47
	v_dot8c_i32_i4_e32 v42, v127, v49
	v_dot8c_i32_i4_e32 v43, v127, v47
	v_dot8c_i32_i4_e32 v44, v129, v49
	v_dot8c_i32_i4_e32 v45, v129, v47
	v_and_b32_e32 v78, 0xffff, v24
	v_lshrrev_b32_e32 v79, 16, v24
	v_lshl_add_u32 v78, v78, 7, v152
	v_lshl_add_u32 v79, v79, 7, v153
	s_mov_b32 m0, s76
	s_add_i32 s43, s76, 0x400
	global_load_lds_dwordx4 v78, s[50:51]
	s_mov_b32 m0, s43
	s_nop 0
	global_load_lds_dwordx4 v79, s[50:51]
	s_waitcnt vmcnt(13)
	v_add_u32_e32 v54, s78, v59
	v_add_u32_e32 v55, s78, v60
	v_add_u32_e32 v56, s78, v61
	v_add_u32_e32 v57, s78, v62
	ds_read_b64_tr_b4 v[46:47], v160 offset:256
	ds_read_b64_tr_b4 v[48:49], v160 offset:1280
	ds_read_b64_tr_b4 v[122:123], v54
	ds_read_b64_tr_b4 v[124:125], v55
	ds_read_b64_tr_b4 v[126:127], v56
	ds_read_b64_tr_b4 v[128:129], v57
	s_waitcnt lgkmcnt(6)
	v_dot8c_i32_i4_e32 v38, v130, v52
	v_dot8c_i32_i4_e32 v39, v130, v50
	v_dot8c_i32_i4_e32 v40, v132, v52
	v_dot8c_i32_i4_e32 v41, v132, v50
	v_dot8c_i32_i4_e32 v42, v134, v52
	v_dot8c_i32_i4_e32 v43, v134, v50
	v_dot8c_i32_i4_e32 v44, v136, v52
	v_dot8c_i32_i4_e32 v45, v136, v50
	v_dot8c_i32_i4_e32 v38, v131, v53
	v_dot8c_i32_i4_e32 v39, v131, v51
	v_dot8c_i32_i4_e32 v40, v133, v53
	v_dot8c_i32_i4_e32 v41, v133, v51
	v_dot8c_i32_i4_e32 v42, v135, v53
	v_dot8c_i32_i4_e32 v43, v135, v51
	v_dot8c_i32_i4_e32 v44, v137, v53
	v_dot8c_i32_i4_e32 v45, v137, v51
	v_and_b32_e32 v78, 0xffff, v25
	v_lshrrev_b32_e32 v79, 16, v25
	v_lshl_add_u32 v78, v78, 7, v152
	v_lshl_add_u32 v79, v79, 7, v153
	s_mov_b32 m0, s77
	s_add_i32 s43, s77, 0x400
	global_load_lds_dwordx4 v78, s[50:51]
	s_mov_b32 m0, s43
	s_nop 0
	global_load_lds_dwordx4 v79, s[50:51]
	s_waitcnt vmcnt(13)
	v_add_u32_e32 v54, s79, v59
	v_add_u32_e32 v55, s79, v60
	v_add_u32_e32 v56, s79, v61
	v_add_u32_e32 v57, s79, v62
	ds_read_b64_tr_b4 v[50:51], v160 offset:384
	ds_read_b64_tr_b4 v[52:53], v160 offset:1408
	ds_read_b64_tr_b4 v[130:131], v54
	ds_read_b64_tr_b4 v[132:133], v55
	ds_read_b64_tr_b4 v[134:135], v56
	ds_read_b64_tr_b4 v[136:137], v57
	s_waitcnt lgkmcnt(6)
	v_dot8c_i32_i4_e32 v38, v122, v48
	v_dot8c_i32_i4_e32 v39, v122, v46
	v_dot8c_i32_i4_e32 v40, v124, v48
	v_dot8c_i32_i4_e32 v41, v124, v46
	v_dot8c_i32_i4_e32 v42, v126, v48
	v_dot8c_i32_i4_e32 v43, v126, v46
	v_dot8c_i32_i4_e32 v44, v128, v48
	v_dot8c_i32_i4_e32 v45, v128, v46
	v_dot8c_i32_i4_e32 v38, v123, v49
	v_dot8c_i32_i4_e32 v39, v123, v47
	v_dot8c_i32_i4_e32 v40, v125, v49
	v_dot8c_i32_i4_e32 v41, v125, v47
	v_dot8c_i32_i4_e32 v42, v127, v49
	v_dot8c_i32_i4_e32 v43, v127, v47
	v_dot8c_i32_i4_e32 v44, v129, v49
	v_dot8c_i32_i4_e32 v45, v129, v47
	s_waitcnt lgkmcnt(15)
; #define TR4(p_) __builtin_amdgcn_ds_read_tr4_b64_v2i32((LAS v2i*)(p_))
; #define VDMA(st_, k_) do { _Pragma("unroll") for (int i_ = 0; i_ < 4; ++i_) { \
;         const unsigned off_ = (unsigned)((st_) >> 2) * (16384u * 128u) + (PE_ID(E, 4 * ((st_) & 3) + i_) << 7) + ((i_ & 1) ? cx1 : cx0); \
;         __builtin_amdgcn_global_load_lds((const unsigned*)(V4 + off_), (LAS unsigned*)(ldsb + BUF[k_] + 1024 * i_), 16, 0, 0); } } while (0)
; __device__ __forceinline__ void peer_v_tokens(int j, const LAS unsigned short* EL, const LAS unsigned char* AL  , const LAS float* ASC  , const LAS int* SAL  , ...
;     ...
;         for (int st = 0; st < 16; ++st) {
;             const int p = st >> 2, q = st & 3;
;             if (st < 14) VDMA(st + 2, (st + 2) % 3);
;             if (st < 14) asm volatile("s_waitcnt vmcnt(8)" ::: "memory");
;             else if (st == 14) asm volatile("s_waitcnt vmcnt(4)" ::: "memory");
;             else asm volatile("s_waitcnt vmcnt(0)" ::: "memory");
;             if (q == 0) {
; #pragma unroll
;                 for (int r = 0; r < 4; ++r) { accH[r] = 0; accL[r] = 0; } }
; #pragma unroll
;             for (int tp = 0; tp < 2; ++tp) {
;                 const v2i ao = TR4(ATL + (2 * q + tp) * 128 + 8 * s16), ah = TR4(ATL + 1024 + (2 * q + tp) * 128 + 8 * s16);
; #pragma unroll
;                 for (int r = 0; r < 4; ++r) {
;                     const v2i d = TR4(ldsb + BUF[st % 3] + 2048 * tp + roff[r]);
;                     accH[r] = __builtin_amdgcn_sdot8(d.x, ah.x, accH[r], false); accH[r] = __builtin_amdgcn_sdot8(d.y, ah.y, accH[r], false);
;                     accL[r] = __builtin_amdgcn_sdot8(d.x, ao.x, accL[r], false); accL[r] = __builtin_amdgcn_sdot8(d.y, ao.y, accL[r], false);
;                 }
;             }
	v_and_b32_e32 v78, 0xffff, v26
	v_lshrrev_b32_e32 v79, 16, v26
	v_lshl_add_u32 v78, v78, 7, v152
	v_lshl_add_u32 v79, v79, 7, v153
	s_mov_b32 m0, s78
	s_add_i32 s43, s78, 0x400
	global_load_lds_dwordx4 v78, s[50:51]
	s_mov_b32 m0, s43
	s_nop 0
	global_load_lds_dwordx4 v79, s[50:51]
	s_waitcnt vmcnt(13)
	v_add_u32_e32 v54, s98, v59
	v_add_u32_e32 v55, s98, v60
	v_add_u32_e32 v56, s98, v61
	v_add_u32_e32 v57, s98, v62
	ds_read_b64_tr_b4 v[46:47], v160 offset:512
	ds_read_b64_tr_b4 v[48:49], v160 offset:1536
	ds_read_b64_tr_b4 v[122:123], v54
	ds_read_b64_tr_b4 v[124:125], v55
	ds_read_b64_tr_b4 v[126:127], v56
	ds_read_b64_tr_b4 v[128:129], v57
	s_waitcnt lgkmcnt(6)
	v_dot8c_i32_i4_e32 v38, v130, v52
	v_dot8c_i32_i4_e32 v39, v130, v50
	v_dot8c_i32_i4_e32 v40, v132, v52
	v_dot8c_i32_i4_e32 v41, v132, v50
	v_dot8c_i32_i4_e32 v42, v134, v52
	v_dot8c_i32_i4_e32 v43, v134, v50
	v_dot8c_i32_i4_e32 v44, v136, v52
	v_dot8c_i32_i4_e32 v45, v136, v50
	v_dot8c_i32_i4_e32 v38, v131, v53
	v_dot8c_i32_i4_e32 v39, v131, v51
	v_dot8c_i32_i4_e32 v40, v133, v53
	v_dot8c_i32_i4_e32 v41, v133, v51
	v_dot8c_i32_i4_e32 v42, v135, v53
	v_dot8c_i32_i4_e32 v43, v135, v51
	v_dot8c_i32_i4_e32 v44, v137, v53
	v_dot8c_i32_i4_e32 v45, v137, v51
	v_and_b32_e32 v78, 0xffff, v27
	v_lshrrev_b32_e32 v79, 16, v27
	v_lshl_add_u32 v78, v78, 7, v152
	v_lshl_add_u32 v79, v79, 7, v153
	s_mov_b32 m0, s79
	s_add_i32 s43, s79, 0x400
	global_load_lds_dwordx4 v78, s[50:51]
	s_mov_b32 m0, s43
	s_nop 0
	global_load_lds_dwordx4 v79, s[50:51]
	s_waitcnt vmcnt(8)
	v_add_u32_e32 v54, s99, v59
	v_add_u32_e32 v55, s99, v60
	v_add_u32_e32 v56, s99, v61
	v_add_u32_e32 v57, s99, v62
	ds_read_b64_tr_b4 v[50:51], v160 offset:640
	ds_read_b64_tr_b4 v[52:53], v160 offset:1664
	ds_read_b64_tr_b4 v[130:131], v54
	ds_read_b64_tr_b4 v[132:133], v55
	ds_read_b64_tr_b4 v[134:135], v56
	ds_read_b64_tr_b4 v[136:137], v57
	s_waitcnt lgkmcnt(6)
	v_dot8c_i32_i4_e32 v38, v122, v48
	v_dot8c_i32_i4_e32 v39, v122, v46
	v_dot8c_i32_i4_e32 v40, v124, v48
	v_dot8c_i32_i4_e32 v41, v124, v46
	v_dot8c_i32_i4_e32 v42, v126, v48
	v_dot8c_i32_i4_e32 v43, v126, v46
	v_dot8c_i32_i4_e32 v44, v128, v48
	v_dot8c_i32_i4_e32 v45, v128, v46
	v_dot8c_i32_i4_e32 v38, v123, v49
	v_dot8c_i32_i4_e32 v39, v123, v47
	v_dot8c_i32_i4_e32 v40, v125, v49
	v_dot8c_i32_i4_e32 v41, v125, v47
	v_dot8c_i32_i4_e32 v42, v127, v49
	v_dot8c_i32_i4_e32 v43, v127, v47
	v_dot8c_i32_i4_e32 v44, v129, v49
	v_dot8c_i32_i4_e32 v45, v129, v47
	s_waitcnt lgkmcnt(15)
	v_add_u32_e32 v143, 8, v139
	v_and_b32_e32 v142, 15, v143
	v_xor_b32_e32 v142, 8, v142
	v_bfe_u32 v144, v143, 4, 4
	v_mul_lo_u32 v142, v142, s92
	v_mul_lo_u32 v144, v144, s92
	v_mov_b32_e32 v143, v142
	v_mov_b32_e32 v145, v144
	ds_write2st64_b64 v159, v[142:143], v[144:145] offset1:2
	v_and_b32_e32 v78, 0xffff, v28
	v_lshrrev_b32_e32 v79, 16, v28
	v_lshl_add_u32 v78, v78, 7, v152
	v_lshl_add_u32 v79, v79, 7, v153
	s_mov_b32 m0, s98
	s_add_i32 s43, s98, 0x400
	global_load_lds_dwordx4 v78, s[50:51]
	s_mov_b32 m0, s43
	s_nop 0
	global_load_lds_dwordx4 v79, s[50:51]
	s_waitcnt vmcnt(8)
	v_add_u32_e32 v54, s76, v59
	v_add_u32_e32 v55, s76, v60
	v_add_u32_e32 v56, s76, v61
	v_add_u32_e32 v57, s76, v62
	ds_read_b64_tr_b4 v[46:47], v160 offset:768
	ds_read_b64_tr_b4 v[48:49], v160 offset:1792
	ds_read_b64_tr_b4 v[122:123], v54
	ds_read_b64_tr_b4 v[124:125], v55
	ds_read_b64_tr_b4 v[126:127], v56
	ds_read_b64_tr_b4 v[128:129], v57
	s_waitcnt lgkmcnt(7)
	v_dot8c_i32_i4_e32 v38, v130, v52
	v_dot8c_i32_i4_e32 v39, v130, v50
	v_dot8c_i32_i4_e32 v40, v132, v52
	v_dot8c_i32_i4_e32 v41, v132, v50
	v_dot8c_i32_i4_e32 v42, v134, v52
	v_dot8c_i32_i4_e32 v43, v134, v50
	v_dot8c_i32_i4_e32 v44, v136, v52
	v_dot8c_i32_i4_e32 v45, v136, v50
	v_dot8c_i32_i4_e32 v38, v131, v53
	v_dot8c_i32_i4_e32 v39, v131, v51
	v_dot8c_i32_i4_e32 v40, v133, v53
	v_dot8c_i32_i4_e32 v41, v133, v51
	v_dot8c_i32_i4_e32 v42, v135, v53
	v_dot8c_i32_i4_e32 v43, v135, v51
	v_dot8c_i32_i4_e32 v44, v137, v53
	v_dot8c_i32_i4_e32 v45, v137, v51
	v_and_b32_e32 v78, 0xffff, v29
	v_lshrrev_b32_e32 v79, 16, v29
	v_lshl_add_u32 v78, v78, 7, v152
	v_lshl_add_u32 v79, v79, 7, v153
	s_mov_b32 m0, s99
	s_add_i32 s43, s99, 0x400
	global_load_lds_dwordx4 v78, s[50:51]
	s_mov_b32 m0, s43
	s_nop 0
	global_load_lds_dwordx4 v79, s[50:51]
	s_waitcnt vmcnt(8)
	v_add_u32_e32 v54, s77, v59
	v_add_u32_e32 v55, s77, v60
	v_add_u32_e32 v56, s77, v61
	v_add_u32_e32 v57, s77, v62
	ds_read_b64_tr_b4 v[50:51], v160 offset:896
	ds_read_b64_tr_b4 v[52:53], v160 offset:1920
	ds_read_b64_tr_b4 v[130:131], v54
	ds_read_b64_tr_b4 v[132:133], v55
	ds_read_b64_tr_b4 v[134:135], v56
	ds_read_b64_tr_b4 v[136:137], v57
	s_waitcnt lgkmcnt(6)
	v_dot8c_i32_i4_e32 v38, v122, v48
	v_dot8c_i32_i4_e32 v39, v122, v46
	v_dot8c_i32_i4_e32 v40, v124, v48
	v_dot8c_i32_i4_e32 v41, v124, v46
	v_dot8c_i32_i4_e32 v42, v126, v48
	v_dot8c_i32_i4_e32 v43, v126, v46
	v_dot8c_i32_i4_e32 v44, v128, v48
	v_dot8c_i32_i4_e32 v45, v128, v46
	v_dot8c_i32_i4_e32 v38, v123, v49
	v_dot8c_i32_i4_e32 v39, v123, v47
	v_dot8c_i32_i4_e32 v40, v125, v49
	v_dot8c_i32_i4_e32 v41, v125, v47
	v_dot8c_i32_i4_e32 v42, v127, v49
	v_dot8c_i32_i4_e32 v43, v127, v47
	v_dot8c_i32_i4_e32 v44, v129, v49
	v_dot8c_i32_i4_e32 v45, v129, v47
	v_and_b32_e32 v78, 0xffff, v30
	v_lshrrev_b32_e32 v79, 16, v30
	v_lshl_add_u32 v78, v78, 7, v152
	v_lshl_add_u32 v79, v79, 7, v153
	s_mov_b32 m0, s76
	s_add_i32 s43, s76, 0x400
	global_load_lds_dwordx4 v78, s[50:51]
	s_mov_b32 m0, s43
	s_nop 0
	global_load_lds_dwordx4 v79, s[50:51]
	s_waitcnt vmcnt(8)
; __device__ __forceinline__ bf16 f2bf(float f) { return (bf16)f2bfu(f); }
; #define TR4(p_) __builtin_amdgcn_ds_read_tr4_b64_v2i32((LAS v2i*)(p_))
; #define VDMA(st_, k_) do { _Pragma("unroll") for (int i_ = 0; i_ < 4; ++i_) { \
;         const unsigned off_ = (unsigned)((st_) >> 2) * (16384u * 128u) + (PE_ID(E, 4 * ((st_) & 3) + i_) << 7) + ((i_ & 1) ? cx1 : cx0); \
;         __builtin_amdgcn_global_load_lds((const unsigned*)(V4 + off_), (LAS unsigned*)(ldsb + BUF[k_] + 1024 * i_), 16, 0, 0); } } while (0)
; __device__ __forceinline__ void peer_v_tokens(int j, const LAS unsigned short* EL, const LAS unsigned char* AL  , const LAS float* ASC  , const LAS int* SAL  , ...
;     ...
;         for (int st = 0; st < 16; ++st) {
;             const int p = st >> 2, q = st & 3;
;             if (st < 14) VDMA(st + 2, (st + 2) % 3);
;             if (st < 14) asm volatile("s_waitcnt vmcnt(8)" ::: "memory");
;             else if (st == 14) asm volatile("s_waitcnt vmcnt(4)" ::: "memory");
;             else asm volatile("s_waitcnt vmcnt(0)" ::: "memory");
;             if (q == 0) {
; #pragma unroll
;                 for (int r = 0; r < 4; ++r) { accH[r] = 0; accL[r] = 0; } }
; #pragma unroll
;             for (int tp = 0; tp < 2; ++tp) {
;                 const v2i ao = TR4(ATL + (2 * q + tp) * 128 + 8 * s16), ah = TR4(ATL + 1024 + (2 * q + tp) * 128 + 8 * s16);
; #pragma unroll
;                 for (int r = 0; r < 4; ++r) {
;                     const v2i d = TR4(ldsb + BUF[st % 3] + 2048 * tp + roff[r]);
;                     accH[r] = __builtin_amdgcn_sdot8(d.x, ah.x, accH[r], false); accH[r] = __builtin_amdgcn_sdot8(d.y, ah.y, accH[r], false);
;                     accL[r] = __builtin_amdgcn_sdot8(d.x, ao.x, accL[r], false); accL[r] = __builtin_amdgcn_sdot8(d.y, ao.y, accL[r], false);
;                 }
;             }
;             asm volatile("s_waitcnt lgkmcnt(0)" ::: "memory");
;             if (q == 3) {
; #pragma unroll
;                 for (int r = 0; r < 4; ++r) STASH[256 * p + 16 * (grp + 4 * r) + pc] = f2bf(asc * (float)(2 * ((accH[r] << 4) + accL[r]) + sa));
;             }
	v_add_u32_e32 v54, s78, v59
	v_add_u32_e32 v55, s78, v60
	v_add_u32_e32 v56, s78, v61
	v_add_u32_e32 v57, s78, v62
	ds_read_b64_tr_b4 v[46:47], v160
	ds_read_b64_tr_b4 v[48:49], v160 offset:1024
	ds_read_b64_tr_b4 v[122:123], v54
	ds_read_b64_tr_b4 v[124:125], v55
	ds_read_b64_tr_b4 v[126:127], v56
	ds_read_b64_tr_b4 v[128:129], v57
	s_waitcnt lgkmcnt(6)
	v_dot8c_i32_i4_e32 v38, v130, v52
	v_dot8c_i32_i4_e32 v39, v130, v50
	v_dot8c_i32_i4_e32 v40, v132, v52
	v_dot8c_i32_i4_e32 v41, v132, v50
	v_dot8c_i32_i4_e32 v42, v134, v52
	v_dot8c_i32_i4_e32 v43, v134, v50
	v_dot8c_i32_i4_e32 v44, v136, v52
	v_dot8c_i32_i4_e32 v45, v136, v50
	v_dot8c_i32_i4_e32 v38, v131, v53
	v_dot8c_i32_i4_e32 v39, v131, v51
	v_dot8c_i32_i4_e32 v40, v133, v53
	v_dot8c_i32_i4_e32 v41, v133, v51
	v_dot8c_i32_i4_e32 v42, v135, v53
	v_dot8c_i32_i4_e32 v43, v135, v51
	v_dot8c_i32_i4_e32 v44, v137, v53
	v_dot8c_i32_i4_e32 v45, v137, v51
	s_nop 3
	s_waitcnt lgkmcnt(15)
	v_lshlrev_b32_e32 v38, 5, v38
	v_lshlrev_b32_e32 v39, 1, v39
	v_add3_u32 v38, v39, v229, v38
	v_cvt_f32_i32_e32 v38, v38
	v_mul_f32_e32 v38, v228, v38
	v_lshlrev_b32_e32 v40, 5, v40
	v_lshlrev_b32_e32 v41, 1, v41
	v_add3_u32 v40, v41, v229, v40
	v_cvt_f32_i32_e32 v40, v40
	v_mul_f32_e32 v40, v228, v40
	v_lshlrev_b32_e32 v42, 5, v42
	v_lshlrev_b32_e32 v43, 1, v43
	v_add3_u32 v42, v43, v229, v42
	v_cvt_f32_i32_e32 v42, v42
	v_mul_f32_e32 v42, v228, v42
	v_lshlrev_b32_e32 v44, 5, v44
	v_lshlrev_b32_e32 v45, 1, v45
	v_add3_u32 v44, v45, v229, v44
	v_cvt_f32_i32_e32 v44, v44
	v_mul_f32_e32 v44, v228, v44
	v_cvt_pk_bf16_f32 v164, v38, v40
	v_cvt_pk_bf16_f32 v165, v42, v44
	ds_read_b128 v[252:255], v155 offset:1024
	s_add_i32 s44, s40, 16
	s_ashr_i32 s45, s44, 31
	s_lshl_b64 s[44:45], s[44:45], 12
	v_lshl_add_u64 v[80:81], v[36:37], 0, s[44:45]
	s_waitcnt lgkmcnt(0)
	v_mul_f32_e32 v214, v214, v252
	v_mul_f32_e32 v215, v215, v253
	v_mul_f32_e32 v216, v216, v254
	v_mul_f32_e32 v217, v217, v255
	global_store_dwordx4 v[80:81], v[214:217], off offset:1024 nt
	v_add_u32_e32 v147, 8, v140
	v_and_b32_e32 v146, 15, v147
	v_xor_b32_e32 v146, 8, v146
	v_bfe_u32 v148, v147, 4, 4
	v_mul_lo_u32 v146, v146, s92
	v_mul_lo_u32 v148, v148, s92
	v_mov_b32_e32 v147, v146
	v_mov_b32_e32 v149, v148
	ds_write2st64_b64 v77, v[146:147], v[148:149] offset1:2
	v_add_u32_e32 v138, 0x1000, v74
	ds_read_u8 v139, v138
	v_add_u32_e32 v141, 0x1000, v73
	ds_read_u8 v140, v141
	s_add_i32 s43, s67, 160
	v_mov_b32_e32 v138, s43
	ds_read2st64_b32 v[228:229], v138 offset1:1
	ds_read_b128 v[18:21], v227 offset:8192
	ds_read_b128 v[22:25], v227 offset:8208
	v_add_u32_e32 v150, 0x400000, v63
	v_add_u32_e32 v151, 0x400000, v64
	v_mov_b32_e32 v38, 0
	v_mov_b32_e32 v39, 0
	v_mov_b32_e32 v40, 0
	v_mov_b32_e32 v41, 0
	v_mov_b32_e32 v42, 0
	v_mov_b32_e32 v43, 0
	v_mov_b32_e32 v44, 0
	v_mov_b32_e32 v45, 0
	v_and_b32_e32 v78, 0xffff, v31
	v_lshrrev_b32_e32 v79, 16, v31
	v_lshl_add_u32 v78, v78, 7, v152
	v_lshl_add_u32 v79, v79, 7, v153
	s_mov_b32 m0, s77
	s_add_i32 s43, s77, 0x400
	global_load_lds_dwordx4 v78, s[50:51]
	s_mov_b32 m0, s43
	s_nop 0
	global_load_lds_dwordx4 v79, s[50:51]
	s_waitcnt vmcnt(9)
	v_add_u32_e32 v54, s79, v59
	v_add_u32_e32 v55, s79, v60
	v_add_u32_e32 v56, s79, v61
	v_add_u32_e32 v57, s79, v62
	ds_read_b64_tr_b4 v[50:51], v160 offset:128
	ds_read_b64_tr_b4 v[52:53], v160 offset:1152
	ds_read_b64_tr_b4 v[130:131], v54
	ds_read_b64_tr_b4 v[132:133], v55
	ds_read_b64_tr_b4 v[134:135], v56
	ds_read_b64_tr_b4 v[136:137], v57
	s_waitcnt lgkmcnt(13)
	v_dot8c_i32_i4_e32 v38, v122, v48
	v_dot8c_i32_i4_e32 v39, v122, v46
	v_dot8c_i32_i4_e32 v40, v124, v48
	v_dot8c_i32_i4_e32 v41, v124, v46
	v_dot8c_i32_i4_e32 v42, v126, v48
	v_dot8c_i32_i4_e32 v43, v126, v46
	v_dot8c_i32_i4_e32 v44, v128, v48
	v_dot8c_i32_i4_e32 v45, v128, v46
	v_dot8c_i32_i4_e32 v38, v123, v49
	v_dot8c_i32_i4_e32 v39, v123, v47
	v_dot8c_i32_i4_e32 v40, v125, v49
	v_dot8c_i32_i4_e32 v41, v125, v47
	v_dot8c_i32_i4_e32 v42, v127, v49
	v_dot8c_i32_i4_e32 v43, v127, v47
	v_dot8c_i32_i4_e32 v44, v129, v49
	v_dot8c_i32_i4_e32 v45, v129, v47
	v_and_b32_e32 v78, 0xffff, v32
	v_lshrrev_b32_e32 v79, 16, v32
	v_lshl_add_u32 v78, v78, 7, v152
	v_lshl_add_u32 v79, v79, 7, v153
	s_mov_b32 m0, s78
	s_add_i32 s43, s78, 0x400
	global_load_lds_dwordx4 v78, s[50:51]
	s_mov_b32 m0, s43
	s_nop 0
	global_load_lds_dwordx4 v79, s[50:51]
	s_waitcnt vmcnt(9)
	v_add_u32_e32 v54, s98, v59
	v_add_u32_e32 v55, s98, v60
	v_add_u32_e32 v56, s98, v61
	v_add_u32_e32 v57, s98, v62
	ds_read_b64_tr_b4 v[46:47], v160 offset:256
	ds_read_b64_tr_b4 v[48:49], v160 offset:1280
	ds_read_b64_tr_b4 v[122:123], v54
	ds_read_b64_tr_b4 v[124:125], v55
	ds_read_b64_tr_b4 v[126:127], v56
	ds_read_b64_tr_b4 v[128:129], v57
	s_waitcnt lgkmcnt(6)
	v_dot8c_i32_i4_e32 v38, v130, v52
	v_dot8c_i32_i4_e32 v39, v130, v50
	v_dot8c_i32_i4_e32 v40, v132, v52
	v_dot8c_i32_i4_e32 v41, v132, v50
	v_dot8c_i32_i4_e32 v42, v134, v52
	v_dot8c_i32_i4_e32 v43, v134, v50
	v_dot8c_i32_i4_e32 v44, v136, v52
	v_dot8c_i32_i4_e32 v45, v136, v50
	v_dot8c_i32_i4_e32 v38, v131, v53
	v_dot8c_i32_i4_e32 v39, v131, v51
	v_dot8c_i32_i4_e32 v40, v133, v53
	v_dot8c_i32_i4_e32 v41, v133, v51
	v_dot8c_i32_i4_e32 v42, v135, v53
	v_dot8c_i32_i4_e32 v43, v135, v51
	v_dot8c_i32_i4_e32 v44, v137, v53
	v_dot8c_i32_i4_e32 v45, v137, v51
	ds_write_b16 v65, v186
	ds_write_b16_d16_hi v65, v186 offset:128
	ds_write_b16 v65, v187 offset:256
	ds_write_b16_d16_hi v65, v187 offset:384
	ds_write_b16 v65, v188 offset:512
	ds_write_b16_d16_hi v65, v188 offset:640
	ds_write_b16 v65, v189 offset:768
	ds_write_b16_d16_hi v65, v189 offset:896
	ds_write_b16 v65, v190 offset:1024
	ds_write_b16_d16_hi v65, v190 offset:1152
	ds_write_b16 v65, v191 offset:1280
	ds_write_b16_d16_hi v65, v191 offset:1408
	ds_write_b16 v65, v192 offset:1536
	ds_write_b16_d16_hi v65, v192 offset:1664
	ds_write_b16 v65, v193 offset:1792
	ds_write_b16_d16_hi v65, v193 offset:1920
	ds_read_b64 v[202:203], v154
	ds_read_b64 v[204:205], v154 offset:512
	ds_read_b64 v[206:207], v154 offset:1024
	ds_read_b64 v[208:209], v154 offset:1536
	v_and_b32_e32 v78, 0xffff, v33
	v_lshrrev_b32_e32 v79, 16, v33
	v_lshl_add_u32 v78, v78, 7, v152
	v_lshl_add_u32 v79, v79, 7, v153
	s_mov_b32 m0, s79
	s_add_i32 s43, s79, 0x400
	global_load_lds_dwordx4 v78, s[50:51]
	s_mov_b32 m0, s43
	s_nop 0
	global_load_lds_dwordx4 v79, s[50:51]
	s_waitcnt vmcnt(9)
; #define TR4(p_) __builtin_amdgcn_ds_read_tr4_b64_v2i32((LAS v2i*)(p_))
; #define VDMA(st_, k_) do { _Pragma("unroll") for (int i_ = 0; i_ < 4; ++i_) { \
;         const unsigned off_ = (unsigned)((st_) >> 2) * (16384u * 128u) + (PE_ID(E, 4 * ((st_) & 3) + i_) << 7) + ((i_ & 1) ? cx1 : cx0); \
;         __builtin_amdgcn_global_load_lds((const unsigned*)(V4 + off_), (LAS unsigned*)(ldsb + BUF[k_] + 1024 * i_), 16, 0, 0); } } while (0)
; __device__ __forceinline__ void peer_v_tokens(int j, const LAS unsigned short* EL, const LAS unsigned char* AL  , const LAS float* ASC  , const LAS int* SAL  , ...
;     ...
;         for (int st = 0; st < 16; ++st) {
;             const int p = st >> 2, q = st & 3;
;             if (st < 14) VDMA(st + 2, (st + 2) % 3);
;             if (st < 14) asm volatile("s_waitcnt vmcnt(8)" ::: "memory");
;             else if (st == 14) asm volatile("s_waitcnt vmcnt(4)" ::: "memory");
;             else asm volatile("s_waitcnt vmcnt(0)" ::: "memory");
;             if (q == 0) {
; #pragma unroll
;                 for (int r = 0; r < 4; ++r) { accH[r] = 0; accL[r] = 0; } }
; #pragma unroll
;             for (int tp = 0; tp < 2; ++tp) {
;                 const v2i ao = TR4(ATL + (2 * q + tp) * 128 + 8 * s16), ah = TR4(ATL + 1024 + (2 * q + tp) * 128 + 8 * s16);
; #pragma unroll
;                 for (int r = 0; r < 4; ++r) {
;                     const v2i d = TR4(ldsb + BUF[st % 3] + 2048 * tp + roff[r]);
;                     accH[r] = __builtin_amdgcn_sdot8(d.x, ah.x, accH[r], false); accH[r] = __builtin_amdgcn_sdot8(d.y, ah.y, accH[r], false);
;                     accL[r] = __builtin_amdgcn_sdot8(d.x, ao.x, accL[r], false); accL[r] = __builtin_amdgcn_sdot8(d.y, ao.y, accL[r], false);
;                 }
;             }
	v_add_u32_e32 v54, s99, v59
	v_add_u32_e32 v55, s99, v60
	v_add_u32_e32 v56, s99, v61
	v_add_u32_e32 v57, s99, v62
	ds_read_b64_tr_b4 v[50:51], v160 offset:384
	ds_read_b64_tr_b4 v[52:53], v160 offset:1408
	ds_read_b64_tr_b4 v[130:131], v54
	ds_read_b64_tr_b4 v[132:133], v55
	ds_read_b64_tr_b4 v[134:135], v56
	ds_read_b64_tr_b4 v[136:137], v57
	s_waitcnt lgkmcnt(15)
	v_dot8c_i32_i4_e32 v38, v122, v48
	v_dot8c_i32_i4_e32 v39, v122, v46
	v_dot8c_i32_i4_e32 v40, v124, v48
	v_dot8c_i32_i4_e32 v41, v124, v46
	v_dot8c_i32_i4_e32 v42, v126, v48
	v_dot8c_i32_i4_e32 v43, v126, v46
	v_dot8c_i32_i4_e32 v44, v128, v48
	v_dot8c_i32_i4_e32 v45, v128, v46
	v_dot8c_i32_i4_e32 v38, v123, v49
	v_dot8c_i32_i4_e32 v39, v123, v47
	v_dot8c_i32_i4_e32 v40, v125, v49
	v_dot8c_i32_i4_e32 v41, v125, v47
	v_dot8c_i32_i4_e32 v42, v127, v49
	v_dot8c_i32_i4_e32 v43, v127, v47
	v_dot8c_i32_i4_e32 v44, v129, v49
	v_dot8c_i32_i4_e32 v45, v129, v47
	s_waitcnt lgkmcnt(15)
	v_and_b32_e32 v78, 0xffff, v18
	v_lshrrev_b32_e32 v79, 16, v18
	v_lshl_add_u32 v78, v78, 7, v150
	v_lshl_add_u32 v79, v79, 7, v151
	s_mov_b32 m0, s98
	s_add_i32 s43, s98, 0x400
	global_load_lds_dwordx4 v78, s[50:51]
	s_mov_b32 m0, s43
	s_nop 0
	global_load_lds_dwordx4 v79, s[50:51]
	s_waitcnt vmcnt(9)
	v_add_u32_e32 v54, s76, v59
	v_add_u32_e32 v55, s76, v60
	v_add_u32_e32 v56, s76, v61
	v_add_u32_e32 v57, s76, v62
	ds_read_b64_tr_b4 v[46:47], v160 offset:512
	ds_read_b64_tr_b4 v[48:49], v160 offset:1536
	ds_read_b64_tr_b4 v[122:123], v54
	ds_read_b64_tr_b4 v[124:125], v55
	ds_read_b64_tr_b4 v[126:127], v56
	ds_read_b64_tr_b4 v[128:129], v57
	s_waitcnt lgkmcnt(6)
	v_dot8c_i32_i4_e32 v38, v130, v52
	v_dot8c_i32_i4_e32 v39, v130, v50
	v_dot8c_i32_i4_e32 v40, v132, v52
	v_dot8c_i32_i4_e32 v41, v132, v50
	v_dot8c_i32_i4_e32 v42, v134, v52
	v_dot8c_i32_i4_e32 v43, v134, v50
	v_dot8c_i32_i4_e32 v44, v136, v52
	v_dot8c_i32_i4_e32 v45, v136, v50
	v_dot8c_i32_i4_e32 v38, v131, v53
	v_dot8c_i32_i4_e32 v39, v131, v51
	v_dot8c_i32_i4_e32 v40, v133, v53
	v_dot8c_i32_i4_e32 v41, v133, v51
	v_dot8c_i32_i4_e32 v42, v135, v53
	v_dot8c_i32_i4_e32 v43, v135, v51
	v_dot8c_i32_i4_e32 v44, v137, v53
	v_dot8c_i32_i4_e32 v45, v137, v51
	v_and_b32_e32 v78, 0xffff, v19
	v_lshrrev_b32_e32 v79, 16, v19
	v_lshl_add_u32 v78, v78, 7, v150
	v_lshl_add_u32 v79, v79, 7, v151
	s_mov_b32 m0, s99
	s_add_i32 s43, s99, 0x400
	global_load_lds_dwordx4 v78, s[50:51]
	s_mov_b32 m0, s43
	s_nop 0
	global_load_lds_dwordx4 v79, s[50:51]
	s_waitcnt vmcnt(8)
	v_add_u32_e32 v54, s77, v59
	v_add_u32_e32 v55, s77, v60
	v_add_u32_e32 v56, s77, v61
	v_add_u32_e32 v57, s77, v62
	ds_read_b64_tr_b4 v[50:51], v160 offset:640
	ds_read_b64_tr_b4 v[52:53], v160 offset:1664
	ds_read_b64_tr_b4 v[130:131], v54
	ds_read_b64_tr_b4 v[132:133], v55
	ds_read_b64_tr_b4 v[134:135], v56
	ds_read_b64_tr_b4 v[136:137], v57
	s_waitcnt lgkmcnt(6)
	v_dot8c_i32_i4_e32 v38, v122, v48
	v_dot8c_i32_i4_e32 v39, v122, v46
	v_dot8c_i32_i4_e32 v40, v124, v48
	v_dot8c_i32_i4_e32 v41, v124, v46
	v_dot8c_i32_i4_e32 v42, v126, v48
	v_dot8c_i32_i4_e32 v43, v126, v46
	v_dot8c_i32_i4_e32 v44, v128, v48
	v_dot8c_i32_i4_e32 v45, v128, v46
	v_dot8c_i32_i4_e32 v38, v123, v49
	v_dot8c_i32_i4_e32 v39, v123, v47
	v_dot8c_i32_i4_e32 v40, v125, v49
	v_dot8c_i32_i4_e32 v41, v125, v47
	v_dot8c_i32_i4_e32 v42, v127, v49
	v_dot8c_i32_i4_e32 v43, v127, v47
	v_dot8c_i32_i4_e32 v44, v129, v49
	v_dot8c_i32_i4_e32 v45, v129, v47
	s_waitcnt lgkmcnt(15)
	v_add_u32_e32 v143, 8, v139
	v_and_b32_e32 v142, 15, v143
	v_xor_b32_e32 v142, 8, v142
	v_bfe_u32 v144, v143, 4, 4
	v_mul_lo_u32 v142, v142, s92
	v_mul_lo_u32 v144, v144, s92
	v_mov_b32_e32 v143, v142
	v_mov_b32_e32 v145, v144
	ds_write2st64_b64 v159, v[142:143], v[144:145] offset1:2
	v_and_b32_e32 v78, 0xffff, v20
	v_lshrrev_b32_e32 v79, 16, v20
	v_lshl_add_u32 v78, v78, 7, v150
	v_lshl_add_u32 v79, v79, 7, v151
	s_mov_b32 m0, s76
	s_add_i32 s43, s76, 0x400
	global_load_lds_dwordx4 v78, s[50:51]
	s_mov_b32 m0, s43
	s_nop 0
	global_load_lds_dwordx4 v79, s[50:51]
	s_waitcnt vmcnt(8)
	v_add_u32_e32 v54, s78, v59
	v_add_u32_e32 v55, s78, v60
	v_add_u32_e32 v56, s78, v61
	v_add_u32_e32 v57, s78, v62
	ds_read_b64_tr_b4 v[46:47], v160 offset:768
	ds_read_b64_tr_b4 v[48:49], v160 offset:1792
	ds_read_b64_tr_b4 v[122:123], v54
	ds_read_b64_tr_b4 v[124:125], v55
	ds_read_b64_tr_b4 v[126:127], v56
	ds_read_b64_tr_b4 v[128:129], v57
	s_waitcnt lgkmcnt(7)
	v_dot8c_i32_i4_e32 v38, v130, v52
	v_dot8c_i32_i4_e32 v39, v130, v50
	v_dot8c_i32_i4_e32 v40, v132, v52
	v_dot8c_i32_i4_e32 v41, v132, v50
	v_dot8c_i32_i4_e32 v42, v134, v52
	v_dot8c_i32_i4_e32 v43, v134, v50
	v_dot8c_i32_i4_e32 v44, v136, v52
	v_dot8c_i32_i4_e32 v45, v136, v50
	v_dot8c_i32_i4_e32 v38, v131, v53
	v_dot8c_i32_i4_e32 v39, v131, v51
	v_dot8c_i32_i4_e32 v40, v133, v53
	v_dot8c_i32_i4_e32 v41, v133, v51
	v_dot8c_i32_i4_e32 v42, v135, v53
	v_dot8c_i32_i4_e32 v43, v135, v51
	v_dot8c_i32_i4_e32 v44, v137, v53
	v_dot8c_i32_i4_e32 v45, v137, v51
	v_and_b32_e32 v78, 0xffff, v21
	v_lshrrev_b32_e32 v79, 16, v21
	v_lshl_add_u32 v78, v78, 7, v150
	v_lshl_add_u32 v79, v79, 7, v151
	s_mov_b32 m0, s77
	s_add_i32 s43, s77, 0x400
	global_load_lds_dwordx4 v78, s[50:51]
	s_mov_b32 m0, s43
	s_nop 0
	global_load_lds_dwordx4 v79, s[50:51]
	s_waitcnt vmcnt(8)
	v_add_u32_e32 v54, s79, v59
	v_add_u32_e32 v55, s79, v60
	v_add_u32_e32 v56, s79, v61
	v_add_u32_e32 v57, s79, v62
	ds_read_b64_tr_b4 v[50:51], v160 offset:896
	ds_read_b64_tr_b4 v[52:53], v160 offset:1920
	ds_read_b64_tr_b4 v[130:131], v54
	ds_read_b64_tr_b4 v[132:133], v55
	ds_read_b64_tr_b4 v[134:135], v56
	ds_read_b64_tr_b4 v[136:137], v57
	s_waitcnt lgkmcnt(6)
; __device__ __forceinline__ bf16 f2bf(float f) { return (bf16)f2bfu(f); }
; #define TR4(p_) __builtin_amdgcn_ds_read_tr4_b64_v2i32((LAS v2i*)(p_))
; __device__ __forceinline__ void peer_v_tokens(int j, const LAS unsigned short* EL, const LAS unsigned char* AL  , const LAS float* ASC  , const LAS int* SAL  , ...
;     ...
;         for (int st = 0; st < 16; ++st) {
;             const int p = st >> 2, q = st & 3;
;             if (st < 14) VDMA(st + 2, (st + 2) % 3);
;             if (st < 14) asm volatile("s_waitcnt vmcnt(8)" ::: "memory");
;             else if (st == 14) asm volatile("s_waitcnt vmcnt(4)" ::: "memory");
;             else asm volatile("s_waitcnt vmcnt(0)" ::: "memory");
;             if (q == 0) {
; #pragma unroll
;                 for (int r = 0; r < 4; ++r) { accH[r] = 0; accL[r] = 0; } }
; #pragma unroll
;             for (int tp = 0; tp < 2; ++tp) {
;                 const v2i ao = TR4(ATL + (2 * q + tp) * 128 + 8 * s16), ah = TR4(ATL + 1024 + (2 * q + tp) * 128 + 8 * s16);
; #pragma unroll
;                 for (int r = 0; r < 4; ++r) {
;                     const v2i d = TR4(ldsb + BUF[st % 3] + 2048 * tp + roff[r]);
;                     accH[r] = __builtin_amdgcn_sdot8(d.x, ah.x, accH[r], false); accH[r] = __builtin_amdgcn_sdot8(d.y, ah.y, accH[r], false);
;                     accL[r] = __builtin_amdgcn_sdot8(d.x, ao.x, accL[r], false); accL[r] = __builtin_amdgcn_sdot8(d.y, ao.y, accL[r], false);
;                 }
;             }
;             asm volatile("s_waitcnt lgkmcnt(0)" ::: "memory");
;             if (q == 3) {
; #pragma unroll
;                 for (int r = 0; r < 4; ++r) STASH[256 * p + 16 * (grp + 4 * r) + pc] = f2bf(asc * (float)(2 * ((accH[r] << 4) + accL[r]) + sa));
;     ...
;             float4* op = (float4*)(outp + (size_t)t * D) + lane;
; #pragma unroll
;             for (int jq = 0; jq < 4; ++jq) { typedef float f4v __attribute__((ext_vector_type(4))); f4v o4; o4.x = v[jq].x * r3 * gv[jq].x; o4.y = v[jq].y * r3 * gv[jq].y; o4.z = v[jq].z * r3 * gv[jq].z; o4.w = v[jq].w * r3 * gv[jq].w;
;                 __builtin_nontemporal_store(o4, (f4v*)op + 64 * jq); }
	v_dot8c_i32_i4_e32 v38, v122, v48
	v_dot8c_i32_i4_e32 v39, v122, v46
	v_dot8c_i32_i4_e32 v40, v124, v48
	v_dot8c_i32_i4_e32 v41, v124, v46
	v_dot8c_i32_i4_e32 v42, v126, v48
	v_dot8c_i32_i4_e32 v43, v126, v46
	v_dot8c_i32_i4_e32 v44, v128, v48
	v_dot8c_i32_i4_e32 v45, v128, v46
	v_dot8c_i32_i4_e32 v38, v123, v49
	v_dot8c_i32_i4_e32 v39, v123, v47
	v_dot8c_i32_i4_e32 v40, v125, v49
	v_dot8c_i32_i4_e32 v41, v125, v47
	v_dot8c_i32_i4_e32 v42, v127, v49
	v_dot8c_i32_i4_e32 v43, v127, v47
	v_dot8c_i32_i4_e32 v44, v129, v49
	v_dot8c_i32_i4_e32 v45, v129, v47
	v_and_b32_e32 v78, 0xffff, v22
	v_lshrrev_b32_e32 v79, 16, v22
	v_lshl_add_u32 v78, v78, 7, v150
	v_lshl_add_u32 v79, v79, 7, v151
	s_mov_b32 m0, s78
	s_add_i32 s43, s78, 0x400
	global_load_lds_dwordx4 v78, s[50:51]
	s_mov_b32 m0, s43
	s_nop 0
	global_load_lds_dwordx4 v79, s[50:51]
	s_waitcnt vmcnt(8)
	v_add_u32_e32 v54, s98, v59
	v_add_u32_e32 v55, s98, v60
	v_add_u32_e32 v56, s98, v61
	v_add_u32_e32 v57, s98, v62
	ds_read_b64_tr_b4 v[46:47], v160
	ds_read_b64_tr_b4 v[48:49], v160 offset:1024
	ds_read_b64_tr_b4 v[122:123], v54
	ds_read_b64_tr_b4 v[124:125], v55
	ds_read_b64_tr_b4 v[126:127], v56
	ds_read_b64_tr_b4 v[128:129], v57
	s_waitcnt lgkmcnt(6)
	v_dot8c_i32_i4_e32 v38, v130, v52
	v_dot8c_i32_i4_e32 v39, v130, v50
	v_dot8c_i32_i4_e32 v40, v132, v52
	v_dot8c_i32_i4_e32 v41, v132, v50
	v_dot8c_i32_i4_e32 v42, v134, v52
	v_dot8c_i32_i4_e32 v43, v134, v50
	v_dot8c_i32_i4_e32 v44, v136, v52
	v_dot8c_i32_i4_e32 v45, v136, v50
	v_dot8c_i32_i4_e32 v38, v131, v53
	v_dot8c_i32_i4_e32 v39, v131, v51
	v_dot8c_i32_i4_e32 v40, v133, v53
	v_dot8c_i32_i4_e32 v41, v133, v51
	v_dot8c_i32_i4_e32 v42, v135, v53
	v_dot8c_i32_i4_e32 v43, v135, v51
	v_dot8c_i32_i4_e32 v44, v137, v53
	v_dot8c_i32_i4_e32 v45, v137, v51
	s_nop 3
	s_waitcnt lgkmcnt(15)
	v_lshlrev_b32_e32 v38, 5, v38
	v_lshlrev_b32_e32 v39, 1, v39
	v_add3_u32 v38, v39, v229, v38
	v_cvt_f32_i32_e32 v38, v38
	v_mul_f32_e32 v38, v228, v38
	v_lshlrev_b32_e32 v40, 5, v40
	v_lshlrev_b32_e32 v41, 1, v41
	v_add3_u32 v40, v41, v229, v40
	v_cvt_f32_i32_e32 v40, v40
	v_mul_f32_e32 v40, v228, v40
	v_lshlrev_b32_e32 v42, 5, v42
	v_lshlrev_b32_e32 v43, 1, v43
	v_add3_u32 v42, v43, v229, v42
	v_cvt_f32_i32_e32 v42, v42
	v_mul_f32_e32 v42, v228, v42
	v_lshlrev_b32_e32 v44, 5, v44
	v_lshlrev_b32_e32 v45, 1, v45
	v_add3_u32 v44, v45, v229, v44
	v_cvt_f32_i32_e32 v44, v44
	v_mul_f32_e32 v44, v228, v44
	v_cvt_pk_bf16_f32 v172, v38, v40
	v_cvt_pk_bf16_f32 v173, v42, v44
	ds_read_b128 v[252:255], v156
	s_add_i32 s44, s40, 16
	s_ashr_i32 s45, s44, 31
	s_lshl_b64 s[44:45], s[44:45], 12
	v_lshl_add_u64 v[80:81], v[36:37], 0, s[44:45]
	s_waitcnt lgkmcnt(0)
	v_mul_f32_e32 v218, v218, v252
	v_mul_f32_e32 v219, v219, v253
	v_mul_f32_e32 v220, v220, v254
	v_mul_f32_e32 v221, v221, v255
	global_store_dwordx4 v[80:81], v[218:221], off offset:2048 nt
	v_add_u32_e32 v147, 8, v140
	v_and_b32_e32 v146, 15, v147
	v_xor_b32_e32 v146, 8, v146
	v_bfe_u32 v148, v147, 4, 4
	v_mul_lo_u32 v146, v146, s92
	v_mul_lo_u32 v148, v148, s92
	v_mov_b32_e32 v147, v146
	v_mov_b32_e32 v149, v148
	ds_write2st64_b64 v77, v[146:147], v[148:149] offset1:2
	v_add_u32_e32 v138, 0x1400, v74
	ds_read_u8 v139, v138
	v_add_u32_e32 v141, 0x1400, v73
	ds_read_u8 v140, v141
	s_add_i32 s43, s67, 128
	v_mov_b32_e32 v138, s43
	ds_read2st64_b32 v[228:229], v138 offset1:1
	ds_read_b128 v[26:29], v227 offset:10240
	ds_read_b128 v[30:33], v227 offset:10256
	v_mov_b32_e32 v38, 0
	v_mov_b32_e32 v39, 0
	v_mov_b32_e32 v40, 0
	v_mov_b32_e32 v41, 0
	v_mov_b32_e32 v42, 0
	v_mov_b32_e32 v43, 0
	v_mov_b32_e32 v44, 0
	v_mov_b32_e32 v45, 0
	v_and_b32_e32 v78, 0xffff, v23
	v_lshrrev_b32_e32 v79, 16, v23
	v_lshl_add_u32 v78, v78, 7, v150
	v_lshl_add_u32 v79, v79, 7, v151
	s_mov_b32 m0, s79
	s_add_i32 s43, s79, 0x400
	global_load_lds_dwordx4 v78, s[50:51]
	s_mov_b32 m0, s43
	s_nop 0
	global_load_lds_dwordx4 v79, s[50:51]
	s_waitcnt vmcnt(9)
	v_add_u32_e32 v54, s99, v59
	v_add_u32_e32 v55, s99, v60
	v_add_u32_e32 v56, s99, v61
	v_add_u32_e32 v57, s99, v62
	ds_read_b64_tr_b4 v[50:51], v160 offset:128
	ds_read_b64_tr_b4 v[52:53], v160 offset:1152
	ds_read_b64_tr_b4 v[130:131], v54
	ds_read_b64_tr_b4 v[132:133], v55
	ds_read_b64_tr_b4 v[134:135], v56
	ds_read_b64_tr_b4 v[136:137], v57
	s_waitcnt lgkmcnt(13)
	s_waitcnt vmcnt(36) lgkmcnt(15)
; #define LAS __attribute__((address_space(3)))
; #define TR4(p_) __builtin_amdgcn_ds_read_tr4_b64_v2i32((LAS v2i*)(p_))
; __device__ __forceinline__ void peer_v_tokens(int j, const LAS unsigned short* EL, const LAS unsigned char* AL  , const LAS float* ASC  , const LAS int* SAL  , ...
;     ...
;         for (int st = 0; st < 16; ++st) {
;             const int p = st >> 2, q = st & 3;
;             if (st < 14) VDMA(st + 2, (st + 2) % 3);
;             if (st < 14) asm volatile("s_waitcnt vmcnt(8)" ::: "memory");
;             else if (st == 14) asm volatile("s_waitcnt vmcnt(4)" ::: "memory");
;             else asm volatile("s_waitcnt vmcnt(0)" ::: "memory");
;             if (q == 0) {
; #pragma unroll
;                 for (int r = 0; r < 4; ++r) { accH[r] = 0; accL[r] = 0; } }
; #pragma unroll
;             for (int tp = 0; tp < 2; ++tp) {
;                 const v2i ao = TR4(ATL + (2 * q + tp) * 128 + 8 * s16), ah = TR4(ATL + 1024 + (2 * q + tp) * 128 + 8 * s16);
; #pragma unroll
;                 for (int r = 0; r < 4; ++r) {
;                     const v2i d = TR4(ldsb + BUF[st % 3] + 2048 * tp + roff[r]);
;                     accH[r] = __builtin_amdgcn_sdot8(d.x, ah.x, accH[r], false); accH[r] = __builtin_amdgcn_sdot8(d.y, ah.y, accH[r], false);
;                     accL[r] = __builtin_amdgcn_sdot8(d.x, ao.x, accL[r], false); accL[r] = __builtin_amdgcn_sdot8(d.y, ao.y, accL[r], false);
;                 }
;             }
;     ...
;         {
;             float4 v[4]; float ss = 0.f;
; #pragma unroll
;             for (int jq = 0; jq < 4; ++jq) { typedef unsigned u2v __attribute__((ext_vector_type(2))); const u2v pw = *(const LAS u2v*)(STASH + 4 * lane + 256 * jq); const uint2 hw = hv[jq];
;                 v[jq] = make_float4(__uint_as_float(hw.x << 16) + __uint_as_float(pw.x << 16), __uint_as_float(hw.x & 0xffff0000u) + __uint_as_float(pw.x & 0xffff0000u),
;                                     __uint_as_float(hw.y << 16) + __uint_as_float(pw.y << 16), __uint_as_float(hw.y & 0xffff0000u) + __uint_as_float(pw.y & 0xffff0000u));
;                 ss += v[jq].x * v[jq].x + v[jq].y * v[jq].y + v[jq].z * v[jq].z + v[jq].w * v[jq].w; }
;             ss = wave_sum(ss);
;             const float r3 = rsqrtf(ss * (1.f / D) + EPS);
	v_lshlrev_b32_e32 v236, 16, v194
	v_and_b32_e32 v237, 0xffff0000, v194
	v_lshlrev_b32_e32 v142, 16, v202
	v_and_b32_e32 v143, 0xffff0000, v202
	v_add_f32_e32 v236, v236, v142
	v_add_f32_e32 v237, v237, v143
	v_lshlrev_b32_e32 v238, 16, v195
	v_and_b32_e32 v239, 0xffff0000, v195
	v_lshlrev_b32_e32 v142, 16, v203
	v_and_b32_e32 v143, 0xffff0000, v203
	v_add_f32_e32 v238, v238, v142
	v_add_f32_e32 v239, v239, v143
	v_lshlrev_b32_e32 v240, 16, v196
	v_and_b32_e32 v241, 0xffff0000, v196
	v_lshlrev_b32_e32 v142, 16, v204
	v_and_b32_e32 v143, 0xffff0000, v204
	v_add_f32_e32 v240, v240, v142
	v_add_f32_e32 v241, v241, v143
	v_lshlrev_b32_e32 v242, 16, v197
	v_and_b32_e32 v243, 0xffff0000, v197
	v_lshlrev_b32_e32 v142, 16, v205
	v_and_b32_e32 v143, 0xffff0000, v205
	v_add_f32_e32 v242, v242, v142
	v_add_f32_e32 v243, v243, v143
	v_lshlrev_b32_e32 v244, 16, v198
	v_and_b32_e32 v245, 0xffff0000, v198
	v_lshlrev_b32_e32 v142, 16, v206
	v_and_b32_e32 v143, 0xffff0000, v206
	v_add_f32_e32 v244, v244, v142
	v_add_f32_e32 v245, v245, v143
	v_lshlrev_b32_e32 v246, 16, v199
	v_and_b32_e32 v247, 0xffff0000, v199
	v_lshlrev_b32_e32 v142, 16, v207
	v_and_b32_e32 v143, 0xffff0000, v207
	v_add_f32_e32 v246, v246, v142
	v_add_f32_e32 v247, v247, v143
	v_lshlrev_b32_e32 v248, 16, v200
	v_and_b32_e32 v249, 0xffff0000, v200
	v_lshlrev_b32_e32 v142, 16, v208
	v_and_b32_e32 v143, 0xffff0000, v208
	v_add_f32_e32 v248, v248, v142
	v_add_f32_e32 v249, v249, v143
	v_lshlrev_b32_e32 v250, 16, v201
	v_and_b32_e32 v251, 0xffff0000, v201
	v_lshlrev_b32_e32 v142, 16, v209
	v_and_b32_e32 v143, 0xffff0000, v209
	v_add_f32_e32 v250, v250, v142
	v_add_f32_e32 v251, v251, v143
	v_mov_b32_e32 v144, 0
	v_mul_f32_e32 v145, v236, v236
	v_fmac_f32_e32 v145, v237, v237
	v_fmac_f32_e32 v145, v238, v238
	v_fmac_f32_e32 v145, v239, v239
	v_add_f32_e32 v144, v144, v145
	v_mul_f32_e32 v145, v240, v240
	v_fmac_f32_e32 v145, v241, v241
	v_fmac_f32_e32 v145, v242, v242
	v_fmac_f32_e32 v145, v243, v243
	v_add_f32_e32 v144, v144, v145
	v_mul_f32_e32 v145, v244, v244
	v_fmac_f32_e32 v145, v245, v245
	v_fmac_f32_e32 v145, v246, v246
	v_fmac_f32_e32 v145, v247, v247
	v_add_f32_e32 v144, v144, v145
	v_mul_f32_e32 v145, v248, v248
	v_fmac_f32_e32 v145, v249, v249
	v_fmac_f32_e32 v145, v250, v250
	v_fmac_f32_e32 v145, v251, v251
	v_add_f32_e32 v144, v144, v145
	s_nop 1
	v_add_f32_dpp v144, v144, v144 quad_perm:[1,0,3,2] row_mask:0xf bank_mask:0xf bound_ctrl:1
	s_nop 1
	v_add_f32_dpp v144, v144, v144 quad_perm:[2,3,0,1] row_mask:0xf bank_mask:0xf bound_ctrl:1
	s_nop 1
	v_add_f32_dpp v144, v144, v144 row_half_mirror row_mask:0xf bank_mask:0xf bound_ctrl:1
	s_nop 1
	v_add_f32_dpp v144, v144, v144 row_mirror row_mask:0xf bank_mask:0xf bound_ctrl:1
	s_nop 1
	v_readlane_b32 s10, v144, 0
	v_readlane_b32 s11, v144, 16
	v_readlane_b32 s14, v144, 32
	v_readlane_b32 s15, v144, 48
	s_nop 3
	v_mov_b32_e32 v144, s11
	v_mov_b32_e32 v145, s15
	v_add_f32_e32 v144, s10, v144
	v_add_f32_e32 v145, s14, v145
	v_add_f32_e32 v144, v144, v145
	v_fmamk_f32 v144, v144, 0x3a800000, v111
	v_rsq_f32_e32 v144, v144
	s_nop 0
	v_mul_f32_e32 v236, v236, v144
	v_mul_f32_e32 v237, v237, v144
	v_mul_f32_e32 v238, v238, v144
	v_mul_f32_e32 v239, v239, v144
	v_mul_f32_e32 v240, v240, v144
	v_mul_f32_e32 v241, v241, v144
	v_mul_f32_e32 v242, v242, v144
	v_mul_f32_e32 v243, v243, v144
	v_mul_f32_e32 v244, v244, v144
	v_mul_f32_e32 v245, v245, v144
	v_mul_f32_e32 v246, v246, v144
	v_mul_f32_e32 v247, v247, v144
	v_mul_f32_e32 v248, v248, v144
	v_mul_f32_e32 v249, v249, v144
	v_mul_f32_e32 v250, v250, v144
	v_mul_f32_e32 v251, v251, v144
	v_dot8c_i32_i4_e32 v38, v122, v48
	v_dot8c_i32_i4_e32 v39, v122, v46
	v_dot8c_i32_i4_e32 v40, v124, v48
	v_dot8c_i32_i4_e32 v41, v124, v46
	v_dot8c_i32_i4_e32 v42, v126, v48
	v_dot8c_i32_i4_e32 v43, v126, v46
	v_dot8c_i32_i4_e32 v44, v128, v48
	v_dot8c_i32_i4_e32 v45, v128, v46
	v_dot8c_i32_i4_e32 v38, v123, v49
	v_dot8c_i32_i4_e32 v39, v123, v47
	v_dot8c_i32_i4_e32 v40, v125, v49
	v_dot8c_i32_i4_e32 v41, v125, v47
	v_dot8c_i32_i4_e32 v42, v127, v49
	v_dot8c_i32_i4_e32 v43, v127, v47
	v_dot8c_i32_i4_e32 v44, v129, v49
	v_dot8c_i32_i4_e32 v45, v129, v47
	v_and_b32_e32 v78, 0xffff, v24
	v_lshrrev_b32_e32 v79, 16, v24
	v_lshl_add_u32 v78, v78, 7, v150
	v_lshl_add_u32 v79, v79, 7, v151
	s_mov_b32 m0, s98
	s_add_i32 s43, s98, 0x400
	global_load_lds_dwordx4 v78, s[50:51]
	s_mov_b32 m0, s43
	s_nop 0
	global_load_lds_dwordx4 v79, s[50:51]
	s_waitcnt vmcnt(9)
	v_add_u32_e32 v54, s76, v59
	v_add_u32_e32 v55, s76, v60
	v_add_u32_e32 v56, s76, v61
	v_add_u32_e32 v57, s76, v62
	ds_read_b64_tr_b4 v[46:47], v160 offset:256
	ds_read_b64_tr_b4 v[48:49], v160 offset:1280
	ds_read_b64_tr_b4 v[122:123], v54
	ds_read_b64_tr_b4 v[124:125], v55
	ds_read_b64_tr_b4 v[126:127], v56
	ds_read_b64_tr_b4 v[128:129], v57
	s_waitcnt lgkmcnt(6)
	v_dot8c_i32_i4_e32 v38, v130, v52
	v_dot8c_i32_i4_e32 v39, v130, v50
	v_dot8c_i32_i4_e32 v40, v132, v52
	v_dot8c_i32_i4_e32 v41, v132, v50
	v_dot8c_i32_i4_e32 v42, v134, v52
	v_dot8c_i32_i4_e32 v43, v134, v50
	v_dot8c_i32_i4_e32 v44, v136, v52
	v_dot8c_i32_i4_e32 v45, v136, v50
	v_dot8c_i32_i4_e32 v38, v131, v53
	v_dot8c_i32_i4_e32 v39, v131, v51
	v_dot8c_i32_i4_e32 v40, v133, v53
	v_dot8c_i32_i4_e32 v41, v133, v51
	v_dot8c_i32_i4_e32 v42, v135, v53
	v_dot8c_i32_i4_e32 v43, v135, v51
	v_dot8c_i32_i4_e32 v44, v137, v53
	v_dot8c_i32_i4_e32 v45, v137, v51
	v_and_b32_e32 v78, 0xffff, v25
	v_lshrrev_b32_e32 v79, 16, v25
	v_lshl_add_u32 v78, v78, 7, v150
	v_lshl_add_u32 v79, v79, 7, v151
	s_mov_b32 m0, s99
	s_add_i32 s43, s99, 0x400
	global_load_lds_dwordx4 v78, s[50:51]
	s_mov_b32 m0, s43
	s_nop 0
	global_load_lds_dwordx4 v79, s[50:51]
	s_waitcnt vmcnt(9)
; #define LAS __attribute__((address_space(3)))
; #define TR4(p_) __builtin_amdgcn_ds_read_tr4_b64_v2i32((LAS v2i*)(p_))
; __device__ __forceinline__ void peer_v_tokens(int j, const LAS unsigned short* EL, const LAS unsigned char* AL  , const LAS float* ASC  , const LAS int* SAL  , ...
;     ...
;             const int idx = lane + 64 * m, tau = idx >> 4, sr = idx & 15, k = 16 * (sr & 7) + 2 * tau + (sr >> 3);
;             const int aq = (int)*(const LAS signed char*)(AL + tl * 128 + k); const int tq = aq + 8;
;             const unsigned lo = (((unsigned)tq & 15u) ^ 8u) * 0x11111111u, hi = ((unsigned)(tq >> 4) & 15u) * 0x11111111u;
;             typedef unsigned u2v __attribute__((ext_vector_type(2)));
;             u2v l2; l2.x = lo; l2.y = lo; u2v h2; h2.x = hi; h2.y = hi;
;             *(LAS u2v*)(ATL + 8 * idx) = l2; *(LAS u2v*)(ATL + 1024 + 8 * idx) = h2;
;     ...
;         for (int st = 0; st < 16; ++st) {
;             const int p = st >> 2, q = st & 3;
;             if (st < 14) VDMA(st + 2, (st + 2) % 3);
;             if (st < 14) asm volatile("s_waitcnt vmcnt(8)" ::: "memory");
;             else if (st == 14) asm volatile("s_waitcnt vmcnt(4)" ::: "memory");
;             else asm volatile("s_waitcnt vmcnt(0)" ::: "memory");
;             if (q == 0) {
; #pragma unroll
;                 for (int r = 0; r < 4; ++r) { accH[r] = 0; accL[r] = 0; } }
; #pragma unroll
;             for (int tp = 0; tp < 2; ++tp) {
;                 const v2i ao = TR4(ATL + (2 * q + tp) * 128 + 8 * s16), ah = TR4(ATL + 1024 + (2 * q + tp) * 128 + 8 * s16);
; #pragma unroll
;                 for (int r = 0; r < 4; ++r) {
;                     const v2i d = TR4(ldsb + BUF[st % 3] + 2048 * tp + roff[r]);
;                     accH[r] = __builtin_amdgcn_sdot8(d.x, ah.x, accH[r], false); accH[r] = __builtin_amdgcn_sdot8(d.y, ah.y, accH[r], false);
;                     accL[r] = __builtin_amdgcn_sdot8(d.x, ao.x, accL[r], false); accL[r] = __builtin_amdgcn_sdot8(d.y, ao.y, accL[r], false);
;                 }
;             }
;             asm volatile("s_waitcnt lgkmcnt(0)" ::: "memory");
	v_add_u32_e32 v54, s77, v59
	v_add_u32_e32 v55, s77, v60
	v_add_u32_e32 v56, s77, v61
	v_add_u32_e32 v57, s77, v62
	ds_read_b64_tr_b4 v[50:51], v160 offset:384
	ds_read_b64_tr_b4 v[52:53], v160 offset:1408
	ds_read_b64_tr_b4 v[130:131], v54
	ds_read_b64_tr_b4 v[132:133], v55
	ds_read_b64_tr_b4 v[134:135], v56
	ds_read_b64_tr_b4 v[136:137], v57
	s_waitcnt lgkmcnt(6)
	v_dot8c_i32_i4_e32 v38, v122, v48
	v_dot8c_i32_i4_e32 v39, v122, v46
	v_dot8c_i32_i4_e32 v40, v124, v48
	v_dot8c_i32_i4_e32 v41, v124, v46
	v_dot8c_i32_i4_e32 v42, v126, v48
	v_dot8c_i32_i4_e32 v43, v126, v46
	v_dot8c_i32_i4_e32 v44, v128, v48
	v_dot8c_i32_i4_e32 v45, v128, v46
	v_dot8c_i32_i4_e32 v38, v123, v49
	v_dot8c_i32_i4_e32 v39, v123, v47
	v_dot8c_i32_i4_e32 v40, v125, v49
	v_dot8c_i32_i4_e32 v41, v125, v47
	v_dot8c_i32_i4_e32 v42, v127, v49
	v_dot8c_i32_i4_e32 v43, v127, v47
	v_dot8c_i32_i4_e32 v44, v129, v49
	v_dot8c_i32_i4_e32 v45, v129, v47
	s_waitcnt lgkmcnt(15)
	v_and_b32_e32 v78, 0xffff, v26
	v_lshrrev_b32_e32 v79, 16, v26
	v_lshl_add_u32 v78, v78, 7, v150
	v_lshl_add_u32 v79, v79, 7, v151
	s_mov_b32 m0, s76
	s_add_i32 s43, s76, 0x400
	global_load_lds_dwordx4 v78, s[50:51]
	s_mov_b32 m0, s43
	s_nop 0
	global_load_lds_dwordx4 v79, s[50:51]
	s_waitcnt vmcnt(9)
	v_add_u32_e32 v54, s78, v59
	v_add_u32_e32 v55, s78, v60
	v_add_u32_e32 v56, s78, v61
	v_add_u32_e32 v57, s78, v62
	ds_read_b64_tr_b4 v[46:47], v160 offset:512
	ds_read_b64_tr_b4 v[48:49], v160 offset:1536
	ds_read_b64_tr_b4 v[122:123], v54
	ds_read_b64_tr_b4 v[124:125], v55
	ds_read_b64_tr_b4 v[126:127], v56
	ds_read_b64_tr_b4 v[128:129], v57
	s_waitcnt lgkmcnt(6)
	v_dot8c_i32_i4_e32 v38, v130, v52
	v_dot8c_i32_i4_e32 v39, v130, v50
	v_dot8c_i32_i4_e32 v40, v132, v52
	v_dot8c_i32_i4_e32 v41, v132, v50
	v_dot8c_i32_i4_e32 v42, v134, v52
	v_dot8c_i32_i4_e32 v43, v134, v50
	v_dot8c_i32_i4_e32 v44, v136, v52
	v_dot8c_i32_i4_e32 v45, v136, v50
	v_dot8c_i32_i4_e32 v38, v131, v53
	v_dot8c_i32_i4_e32 v39, v131, v51
	v_dot8c_i32_i4_e32 v40, v133, v53
	v_dot8c_i32_i4_e32 v41, v133, v51
	v_dot8c_i32_i4_e32 v42, v135, v53
	v_dot8c_i32_i4_e32 v43, v135, v51
	v_dot8c_i32_i4_e32 v44, v137, v53
	v_dot8c_i32_i4_e32 v45, v137, v51
	v_and_b32_e32 v78, 0xffff, v27
	v_lshrrev_b32_e32 v79, 16, v27
	v_lshl_add_u32 v78, v78, 7, v150
	v_lshl_add_u32 v79, v79, 7, v151
	s_mov_b32 m0, s77
	s_add_i32 s43, s77, 0x400
	global_load_lds_dwordx4 v78, s[50:51]
	s_mov_b32 m0, s43
	s_nop 0
	global_load_lds_dwordx4 v79, s[50:51]
	s_waitcnt vmcnt(8)
	v_add_u32_e32 v54, s79, v59
	v_add_u32_e32 v55, s79, v60
	v_add_u32_e32 v56, s79, v61
	v_add_u32_e32 v57, s79, v62
	ds_read_b64_tr_b4 v[50:51], v160 offset:640
	ds_read_b64_tr_b4 v[52:53], v160 offset:1664
	ds_read_b64_tr_b4 v[130:131], v54
	ds_read_b64_tr_b4 v[132:133], v55
	ds_read_b64_tr_b4 v[134:135], v56
	ds_read_b64_tr_b4 v[136:137], v57
	s_waitcnt lgkmcnt(6)
	v_dot8c_i32_i4_e32 v38, v122, v48
	v_dot8c_i32_i4_e32 v39, v122, v46
	v_dot8c_i32_i4_e32 v40, v124, v48
	v_dot8c_i32_i4_e32 v41, v124, v46
	v_dot8c_i32_i4_e32 v42, v126, v48
	v_dot8c_i32_i4_e32 v43, v126, v46
	v_dot8c_i32_i4_e32 v44, v128, v48
	v_dot8c_i32_i4_e32 v45, v128, v46
	v_dot8c_i32_i4_e32 v38, v123, v49
	v_dot8c_i32_i4_e32 v39, v123, v47
	v_dot8c_i32_i4_e32 v40, v125, v49
	v_dot8c_i32_i4_e32 v41, v125, v47
	v_dot8c_i32_i4_e32 v42, v127, v49
	v_dot8c_i32_i4_e32 v43, v127, v47
	v_dot8c_i32_i4_e32 v44, v129, v49
	v_dot8c_i32_i4_e32 v45, v129, v47
	s_waitcnt lgkmcnt(15)
	v_add_u32_e32 v143, 8, v139
	v_and_b32_e32 v142, 15, v143
	v_xor_b32_e32 v142, 8, v142
	v_bfe_u32 v144, v143, 4, 4
	v_mul_lo_u32 v142, v142, s92
	v_mul_lo_u32 v144, v144, s92
	v_mov_b32_e32 v143, v142
	v_mov_b32_e32 v145, v144
	ds_write2st64_b64 v159, v[142:143], v[144:145] offset1:2
	v_and_b32_e32 v78, 0xffff, v28
	v_lshrrev_b32_e32 v79, 16, v28
	v_lshl_add_u32 v78, v78, 7, v150
	v_lshl_add_u32 v79, v79, 7, v151
	s_mov_b32 m0, s78
	s_add_i32 s43, s78, 0x400
	global_load_lds_dwordx4 v78, s[50:51]
	s_mov_b32 m0, s43
	s_nop 0
	global_load_lds_dwordx4 v79, s[50:51]
	s_waitcnt vmcnt(8)
	v_add_u32_e32 v54, s98, v59
	v_add_u32_e32 v55, s98, v60
	v_add_u32_e32 v56, s98, v61
	v_add_u32_e32 v57, s98, v62
	ds_read_b64_tr_b4 v[46:47], v160 offset:768
	ds_read_b64_tr_b4 v[48:49], v160 offset:1792
	ds_read_b64_tr_b4 v[122:123], v54
	ds_read_b64_tr_b4 v[124:125], v55
	ds_read_b64_tr_b4 v[126:127], v56
	ds_read_b64_tr_b4 v[128:129], v57
	s_waitcnt lgkmcnt(7)
	v_dot8c_i32_i4_e32 v38, v130, v52
	v_dot8c_i32_i4_e32 v39, v130, v50
	v_dot8c_i32_i4_e32 v40, v132, v52
	v_dot8c_i32_i4_e32 v41, v132, v50
	v_dot8c_i32_i4_e32 v42, v134, v52
	v_dot8c_i32_i4_e32 v43, v134, v50
	v_dot8c_i32_i4_e32 v44, v136, v52
	v_dot8c_i32_i4_e32 v45, v136, v50
	v_dot8c_i32_i4_e32 v38, v131, v53
	v_dot8c_i32_i4_e32 v39, v131, v51
	v_dot8c_i32_i4_e32 v40, v133, v53
	v_dot8c_i32_i4_e32 v41, v133, v51
	v_dot8c_i32_i4_e32 v42, v135, v53
	v_dot8c_i32_i4_e32 v43, v135, v51
	v_dot8c_i32_i4_e32 v44, v137, v53
	v_dot8c_i32_i4_e32 v45, v137, v51
	v_and_b32_e32 v78, 0xffff, v29
	v_lshrrev_b32_e32 v79, 16, v29
	v_lshl_add_u32 v78, v78, 7, v150
	v_lshl_add_u32 v79, v79, 7, v151
	s_mov_b32 m0, s79
	s_add_i32 s43, s79, 0x400
	global_load_lds_dwordx4 v78, s[50:51]
	s_mov_b32 m0, s43
	s_nop 0
	global_load_lds_dwordx4 v79, s[50:51]
	s_waitcnt vmcnt(8)
	v_add_u32_e32 v54, s99, v59
	v_add_u32_e32 v55, s99, v60
	v_add_u32_e32 v56, s99, v61
	v_add_u32_e32 v57, s99, v62
	ds_read_b64_tr_b4 v[50:51], v160 offset:896
	ds_read_b64_tr_b4 v[52:53], v160 offset:1920
	ds_read_b64_tr_b4 v[130:131], v54
	ds_read_b64_tr_b4 v[132:133], v55
	ds_read_b64_tr_b4 v[134:135], v56
	ds_read_b64_tr_b4 v[136:137], v57
	s_waitcnt lgkmcnt(6)
; #define LAS __attribute__((address_space(3)))
; __device__ __forceinline__ void peer_v_tokens(int j, const LAS unsigned short* EL, const LAS unsigned char* AL  , const LAS float* ASC  , const LAS int* SAL  , ...
;     ...
;         const int tl = it * 8 + wave, t = j * 64 + tl;
;         unsigned E[8];
;         { const LAS v4u* ep = (const LAS v4u*)(EL + tl * 128 + 16 * g); const v4u e0 = ep[0], e1 = ep[1];
;           E[0] = e0.x; E[1] = e0.y; E[2] = e0.z; E[3] = e0.w; E[4] = e1.x; E[5] = e1.y; E[6] = e1.z; E[7] = e1.w; }
;         uint2 hv[4]; float4 gv[4];
;         { unsigned ho = (unsigned)t * (D / 4) + (unsigned)lane; asm volatile("" : "+v"(ho)); const uint2* hp = (const uint2*)HB + ho; const float4* gp = (const float4*)fng + lane;
; #pragma unroll
;           for (int jq = 0; jq < 4; ++jq) { hv[jq] = hp[64 * jq]; gv[jq] = gp[64 * jq]; } }
;         VDMA(0, 0); VDMA(1, 1);
; #pragma unroll
;         for (int m = 0; m < 2; ++m) {
;     ...
;         for (int st = 0; st < 16; ++st) {
;             const int p = st >> 2, q = st & 3;
;             if (st < 14) VDMA(st + 2, (st + 2) % 3);
;             if (st < 14) asm volatile("s_waitcnt vmcnt(8)" ::: "memory");
;             else if (st == 14) asm volatile("s_waitcnt vmcnt(4)" ::: "memory");
;             else asm volatile("s_waitcnt vmcnt(0)" ::: "memory");
;             if (q == 0) {
; #pragma unroll
;                 for (int r = 0; r < 4; ++r) { accH[r] = 0; accL[r] = 0; } }
; #pragma unroll
;             for (int tp = 0; tp < 2; ++tp) {
;                 const v2i ao = TR4(ATL + (2 * q + tp) * 128 + 8 * s16), ah = TR4(ATL + 1024 + (2 * q + tp) * 128 + 8 * s16);
; #pragma unroll
;                 for (int r = 0; r < 4; ++r) {
;                     const v2i d = TR4(ldsb + BUF[st % 3] + 2048 * tp + roff[r]);
;                     accH[r] = __builtin_amdgcn_sdot8(d.x, ah.x, accH[r], false); accH[r] = __builtin_amdgcn_sdot8(d.y, ah.y, accH[r], false);
;                     accL[r] = __builtin_amdgcn_sdot8(d.x, ao.x, accL[r], false); accL[r] = __builtin_amdgcn_sdot8(d.y, ao.y, accL[r], false);
;                 }
;             }
;             asm volatile("s_waitcnt lgkmcnt(0)" ::: "memory");
;             if (q == 3) {
; #pragma unroll
;                 for (int r = 0; r < 4; ++r) STASH[256 * p + 16 * (grp + 4 * r) + pc] = f2bf(asc * (float)(2 * ((accH[r] << 4) + accL[r]) + sa));
	v_dot8c_i32_i4_e32 v38, v122, v48
	v_dot8c_i32_i4_e32 v39, v122, v46
	v_dot8c_i32_i4_e32 v40, v124, v48
	v_dot8c_i32_i4_e32 v41, v124, v46
	v_dot8c_i32_i4_e32 v42, v126, v48
	v_dot8c_i32_i4_e32 v43, v126, v46
	v_dot8c_i32_i4_e32 v44, v128, v48
	v_dot8c_i32_i4_e32 v45, v128, v46
	v_dot8c_i32_i4_e32 v38, v123, v49
	v_dot8c_i32_i4_e32 v39, v123, v47
	v_dot8c_i32_i4_e32 v40, v125, v49
	v_dot8c_i32_i4_e32 v41, v125, v47
	v_dot8c_i32_i4_e32 v42, v127, v49
	v_dot8c_i32_i4_e32 v43, v127, v47
	v_dot8c_i32_i4_e32 v44, v129, v49
	v_dot8c_i32_i4_e32 v45, v129, v47
	v_and_b32_e32 v78, 0xffff, v30
	v_lshrrev_b32_e32 v79, 16, v30
	v_lshl_add_u32 v78, v78, 7, v150
	v_lshl_add_u32 v79, v79, 7, v151
	s_mov_b32 m0, s98
	s_add_i32 s43, s98, 0x400
	global_load_lds_dwordx4 v78, s[50:51]
	s_mov_b32 m0, s43
	s_nop 0
	global_load_lds_dwordx4 v79, s[50:51]
	s_waitcnt vmcnt(8)
	v_add_u32_e32 v54, s76, v59
	v_add_u32_e32 v55, s76, v60
	v_add_u32_e32 v56, s76, v61
	v_add_u32_e32 v57, s76, v62
	ds_read_b64_tr_b4 v[46:47], v160
	ds_read_b64_tr_b4 v[48:49], v160 offset:1024
	ds_read_b64_tr_b4 v[122:123], v54
	ds_read_b64_tr_b4 v[124:125], v55
	ds_read_b64_tr_b4 v[126:127], v56
	ds_read_b64_tr_b4 v[128:129], v57
	s_waitcnt lgkmcnt(6)
	v_dot8c_i32_i4_e32 v38, v130, v52
	v_dot8c_i32_i4_e32 v39, v130, v50
	v_dot8c_i32_i4_e32 v40, v132, v52
	v_dot8c_i32_i4_e32 v41, v132, v50
	v_dot8c_i32_i4_e32 v42, v134, v52
	v_dot8c_i32_i4_e32 v43, v134, v50
	v_dot8c_i32_i4_e32 v44, v136, v52
	v_dot8c_i32_i4_e32 v45, v136, v50
	v_dot8c_i32_i4_e32 v38, v131, v53
	v_dot8c_i32_i4_e32 v39, v131, v51
	v_dot8c_i32_i4_e32 v40, v133, v53
	v_dot8c_i32_i4_e32 v41, v133, v51
	v_dot8c_i32_i4_e32 v42, v135, v53
	v_dot8c_i32_i4_e32 v43, v135, v51
	v_dot8c_i32_i4_e32 v44, v137, v53
	v_dot8c_i32_i4_e32 v45, v137, v51
	s_nop 3
	s_waitcnt lgkmcnt(15)
	v_lshlrev_b32_e32 v38, 5, v38
	v_lshlrev_b32_e32 v39, 1, v39
	v_add3_u32 v38, v39, v229, v38
	v_cvt_f32_i32_e32 v38, v38
	v_mul_f32_e32 v38, v228, v38
	v_lshlrev_b32_e32 v40, 5, v40
	v_lshlrev_b32_e32 v41, 1, v41
	v_add3_u32 v40, v41, v229, v40
	v_cvt_f32_i32_e32 v40, v40
	v_mul_f32_e32 v40, v228, v40
	v_lshlrev_b32_e32 v42, 5, v42
	v_lshlrev_b32_e32 v43, 1, v43
	v_add3_u32 v42, v43, v229, v42
	v_cvt_f32_i32_e32 v42, v42
	v_mul_f32_e32 v42, v228, v42
	v_lshlrev_b32_e32 v44, 5, v44
	v_lshlrev_b32_e32 v45, 1, v45
	v_add3_u32 v44, v45, v229, v44
	v_cvt_f32_i32_e32 v44, v44
	v_mul_f32_e32 v44, v228, v44
	v_cvt_pk_bf16_f32 v166, v38, v40
	v_cvt_pk_bf16_f32 v167, v42, v44
	ds_read_b128 v[252:255], v156 offset:1024
	s_add_i32 s44, s40, 16
	s_ashr_i32 s45, s44, 31
	s_lshl_b64 s[44:45], s[44:45], 12
	v_lshl_add_u64 v[80:81], v[36:37], 0, s[44:45]
	s_waitcnt lgkmcnt(0)
	v_mul_f32_e32 v222, v222, v252
	v_mul_f32_e32 v223, v223, v253
	v_mul_f32_e32 v224, v224, v254
	v_mul_f32_e32 v225, v225, v255
	global_store_dwordx4 v[80:81], v[222:225], off offset:3072 nt
	ds_read_b128 v[252:255], v155
	s_add_i32 s44, s40, 24
	s_ashr_i32 s45, s44, 31
	s_lshl_b64 s[44:45], s[44:45], 12
	v_lshl_add_u64 v[80:81], v[36:37], 0, s[44:45]
	s_waitcnt lgkmcnt(0)
	v_mul_f32_e32 v236, v236, v252
	v_mul_f32_e32 v237, v237, v253
	v_mul_f32_e32 v238, v238, v254
	v_mul_f32_e32 v239, v239, v255
	global_store_dwordx4 v[80:81], v[236:239], off nt
	v_add_u32_e32 v147, 8, v140
	v_and_b32_e32 v146, 15, v147
	v_xor_b32_e32 v146, 8, v146
	v_bfe_u32 v148, v147, 4, 4
	v_mul_lo_u32 v146, v146, s92
	v_mul_lo_u32 v148, v148, s92
	v_mov_b32_e32 v147, v146
	v_mov_b32_e32 v149, v148
	ds_write2st64_b64 v77, v[146:147], v[148:149] offset1:2
	v_add_u32_e32 v138, 0x1000, v74
	ds_read_u8 v139, v138
	v_add_u32_e32 v141, 0x1000, v73
	ds_read_u8 v140, v141
	s_add_i32 s43, s67, 160
	v_mov_b32_e32 v138, s43
	ds_read2st64_b32 v[228:229], v138 offset1:1
	ds_read_b128 v[18:21], v227 offset:8192
	ds_read_b128 v[22:25], v227 offset:8208
	v_add_u32_e32 v152, 0x600000, v63
	v_add_u32_e32 v153, 0x600000, v64
	v_mov_b32_e32 v38, 0
	v_mov_b32_e32 v39, 0
	v_mov_b32_e32 v40, 0
	v_mov_b32_e32 v41, 0
	v_mov_b32_e32 v42, 0
	v_mov_b32_e32 v43, 0
	v_mov_b32_e32 v44, 0
	v_mov_b32_e32 v45, 0
	v_and_b32_e32 v78, 0xffff, v31
	v_lshrrev_b32_e32 v79, 16, v31
	v_lshl_add_u32 v78, v78, 7, v150
	v_lshl_add_u32 v79, v79, 7, v151
	s_mov_b32 m0, s99
	s_add_i32 s43, s99, 0x400
	global_load_lds_dwordx4 v78, s[50:51]
	s_mov_b32 m0, s43
	s_nop 0
	global_load_lds_dwordx4 v79, s[50:51]
	s_waitcnt vmcnt(10)
	v_add_u32_e32 v54, s77, v59
	v_add_u32_e32 v55, s77, v60
	v_add_u32_e32 v56, s77, v61
	v_add_u32_e32 v57, s77, v62
	ds_read_b64_tr_b4 v[50:51], v160 offset:128
	ds_read_b64_tr_b4 v[52:53], v160 offset:1152
	ds_read_b64_tr_b4 v[130:131], v54
	ds_read_b64_tr_b4 v[132:133], v55
	ds_read_b64_tr_b4 v[134:135], v56
	ds_read_b64_tr_b4 v[136:137], v57
	s_waitcnt lgkmcnt(14)
	v_dot8c_i32_i4_e32 v38, v122, v48
	v_dot8c_i32_i4_e32 v39, v122, v46
	v_dot8c_i32_i4_e32 v40, v124, v48
	v_dot8c_i32_i4_e32 v41, v124, v46
	v_dot8c_i32_i4_e32 v42, v126, v48
	v_dot8c_i32_i4_e32 v43, v126, v46
	v_dot8c_i32_i4_e32 v44, v128, v48
	v_dot8c_i32_i4_e32 v45, v128, v46
	v_dot8c_i32_i4_e32 v38, v123, v49
	v_dot8c_i32_i4_e32 v39, v123, v47
	v_dot8c_i32_i4_e32 v40, v125, v49
	v_dot8c_i32_i4_e32 v41, v125, v47
	v_dot8c_i32_i4_e32 v42, v127, v49
	v_dot8c_i32_i4_e32 v43, v127, v47
	v_dot8c_i32_i4_e32 v44, v129, v49
	v_dot8c_i32_i4_e32 v45, v129, v47
	v_and_b32_e32 v78, 0xffff, v32
	v_lshrrev_b32_e32 v79, 16, v32
	v_lshl_add_u32 v78, v78, 7, v150
	v_lshl_add_u32 v79, v79, 7, v151
	s_mov_b32 m0, s76
	s_add_i32 s43, s76, 0x400
	global_load_lds_dwordx4 v78, s[50:51]
	s_mov_b32 m0, s43
	s_nop 0
	global_load_lds_dwordx4 v79, s[50:51]
	s_waitcnt vmcnt(10)
; #define LAS __attribute__((address_space(3)))
; #define TR4(p_) __builtin_amdgcn_ds_read_tr4_b64_v2i32((LAS v2i*)(p_))
; __device__ __forceinline__ void peer_v_tokens(int j, const LAS unsigned short* EL, const LAS unsigned char* AL  , const LAS float* ASC  , const LAS int* SAL  , ...
;     ...
;             const int idx = lane + 64 * m, tau = idx >> 4, sr = idx & 15, k = 16 * (sr & 7) + 2 * tau + (sr >> 3);
;             const int aq = (int)*(const LAS signed char*)(AL + tl * 128 + k); const int tq = aq + 8;
;             const unsigned lo = (((unsigned)tq & 15u) ^ 8u) * 0x11111111u, hi = ((unsigned)(tq >> 4) & 15u) * 0x11111111u;
;             typedef unsigned u2v __attribute__((ext_vector_type(2)));
;             u2v l2; l2.x = lo; l2.y = lo; u2v h2; h2.x = hi; h2.y = hi;
;             *(LAS u2v*)(ATL + 8 * idx) = l2; *(LAS u2v*)(ATL + 1024 + 8 * idx) = h2;
;     ...
;         for (int st = 0; st < 16; ++st) {
;             const int p = st >> 2, q = st & 3;
;             if (st < 14) VDMA(st + 2, (st + 2) % 3);
;             if (st < 14) asm volatile("s_waitcnt vmcnt(8)" ::: "memory");
;             else if (st == 14) asm volatile("s_waitcnt vmcnt(4)" ::: "memory");
;             else asm volatile("s_waitcnt vmcnt(0)" ::: "memory");
;             if (q == 0) {
; #pragma unroll
;                 for (int r = 0; r < 4; ++r) { accH[r] = 0; accL[r] = 0; } }
; #pragma unroll
;             for (int tp = 0; tp < 2; ++tp) {
;                 const v2i ao = TR4(ATL + (2 * q + tp) * 128 + 8 * s16), ah = TR4(ATL + 1024 + (2 * q + tp) * 128 + 8 * s16);
; #pragma unroll
;                 for (int r = 0; r < 4; ++r) {
;                     const v2i d = TR4(ldsb + BUF[st % 3] + 2048 * tp + roff[r]);
;                     accH[r] = __builtin_amdgcn_sdot8(d.x, ah.x, accH[r], false); accH[r] = __builtin_amdgcn_sdot8(d.y, ah.y, accH[r], false);
;                     accL[r] = __builtin_amdgcn_sdot8(d.x, ao.x, accL[r], false); accL[r] = __builtin_amdgcn_sdot8(d.y, ao.y, accL[r], false);
;                 }
;             }
;             asm volatile("s_waitcnt lgkmcnt(0)" ::: "memory");
	v_add_u32_e32 v54, s78, v59
	v_add_u32_e32 v55, s78, v60
	v_add_u32_e32 v56, s78, v61
	v_add_u32_e32 v57, s78, v62
	ds_read_b64_tr_b4 v[46:47], v160 offset:256
	ds_read_b64_tr_b4 v[48:49], v160 offset:1280
	ds_read_b64_tr_b4 v[122:123], v54
	ds_read_b64_tr_b4 v[124:125], v55
	ds_read_b64_tr_b4 v[126:127], v56
	ds_read_b64_tr_b4 v[128:129], v57
	s_waitcnt lgkmcnt(6)
	v_dot8c_i32_i4_e32 v38, v130, v52
	v_dot8c_i32_i4_e32 v39, v130, v50
	v_dot8c_i32_i4_e32 v40, v132, v52
	v_dot8c_i32_i4_e32 v41, v132, v50
	v_dot8c_i32_i4_e32 v42, v134, v52
	v_dot8c_i32_i4_e32 v43, v134, v50
	v_dot8c_i32_i4_e32 v44, v136, v52
	v_dot8c_i32_i4_e32 v45, v136, v50
	v_dot8c_i32_i4_e32 v38, v131, v53
	v_dot8c_i32_i4_e32 v39, v131, v51
	v_dot8c_i32_i4_e32 v40, v133, v53
	v_dot8c_i32_i4_e32 v41, v133, v51
	v_dot8c_i32_i4_e32 v42, v135, v53
	v_dot8c_i32_i4_e32 v43, v135, v51
	v_dot8c_i32_i4_e32 v44, v137, v53
	v_dot8c_i32_i4_e32 v45, v137, v51
	v_and_b32_e32 v78, 0xffff, v33
	v_lshrrev_b32_e32 v79, 16, v33
	v_lshl_add_u32 v78, v78, 7, v150
	v_lshl_add_u32 v79, v79, 7, v151
	s_mov_b32 m0, s77
	s_add_i32 s43, s77, 0x400
	global_load_lds_dwordx4 v78, s[50:51]
	s_mov_b32 m0, s43
	s_nop 0
	global_load_lds_dwordx4 v79, s[50:51]
	s_waitcnt vmcnt(10)
	v_add_u32_e32 v54, s79, v59
	v_add_u32_e32 v55, s79, v60
	v_add_u32_e32 v56, s79, v61
	v_add_u32_e32 v57, s79, v62
	ds_read_b64_tr_b4 v[50:51], v160 offset:384
	ds_read_b64_tr_b4 v[52:53], v160 offset:1408
	ds_read_b64_tr_b4 v[130:131], v54
	ds_read_b64_tr_b4 v[132:133], v55
	ds_read_b64_tr_b4 v[134:135], v56
	ds_read_b64_tr_b4 v[136:137], v57
	s_waitcnt lgkmcnt(6)
	v_dot8c_i32_i4_e32 v38, v122, v48
	v_dot8c_i32_i4_e32 v39, v122, v46
	v_dot8c_i32_i4_e32 v40, v124, v48
	v_dot8c_i32_i4_e32 v41, v124, v46
	v_dot8c_i32_i4_e32 v42, v126, v48
	v_dot8c_i32_i4_e32 v43, v126, v46
	v_dot8c_i32_i4_e32 v44, v128, v48
	v_dot8c_i32_i4_e32 v45, v128, v46
	v_dot8c_i32_i4_e32 v38, v123, v49
	v_dot8c_i32_i4_e32 v39, v123, v47
	v_dot8c_i32_i4_e32 v40, v125, v49
	v_dot8c_i32_i4_e32 v41, v125, v47
	v_dot8c_i32_i4_e32 v42, v127, v49
	v_dot8c_i32_i4_e32 v43, v127, v47
	v_dot8c_i32_i4_e32 v44, v129, v49
	v_dot8c_i32_i4_e32 v45, v129, v47
	s_waitcnt lgkmcnt(15)
	v_and_b32_e32 v78, 0xffff, v18
	v_lshrrev_b32_e32 v79, 16, v18
	v_lshl_add_u32 v78, v78, 7, v152
	v_lshl_add_u32 v79, v79, 7, v153
	s_mov_b32 m0, s78
	s_add_i32 s43, s78, 0x400
	global_load_lds_dwordx4 v78, s[50:51]
	s_mov_b32 m0, s43
	s_nop 0
	global_load_lds_dwordx4 v79, s[50:51]
	s_waitcnt vmcnt(10)
	v_add_u32_e32 v54, s98, v59
	v_add_u32_e32 v55, s98, v60
	v_add_u32_e32 v56, s98, v61
	v_add_u32_e32 v57, s98, v62
	ds_read_b64_tr_b4 v[46:47], v160 offset:512
	ds_read_b64_tr_b4 v[48:49], v160 offset:1536
	ds_read_b64_tr_b4 v[122:123], v54
	ds_read_b64_tr_b4 v[124:125], v55
	ds_read_b64_tr_b4 v[126:127], v56
	ds_read_b64_tr_b4 v[128:129], v57
	s_waitcnt lgkmcnt(6)
	v_dot8c_i32_i4_e32 v38, v130, v52
	v_dot8c_i32_i4_e32 v39, v130, v50
	v_dot8c_i32_i4_e32 v40, v132, v52
	v_dot8c_i32_i4_e32 v41, v132, v50
	v_dot8c_i32_i4_e32 v42, v134, v52
	v_dot8c_i32_i4_e32 v43, v134, v50
	v_dot8c_i32_i4_e32 v44, v136, v52
	v_dot8c_i32_i4_e32 v45, v136, v50
	v_dot8c_i32_i4_e32 v38, v131, v53
	v_dot8c_i32_i4_e32 v39, v131, v51
	v_dot8c_i32_i4_e32 v40, v133, v53
	v_dot8c_i32_i4_e32 v41, v133, v51
	v_dot8c_i32_i4_e32 v42, v135, v53
	v_dot8c_i32_i4_e32 v43, v135, v51
	v_dot8c_i32_i4_e32 v44, v137, v53
	v_dot8c_i32_i4_e32 v45, v137, v51
	v_and_b32_e32 v78, 0xffff, v19
	v_lshrrev_b32_e32 v79, 16, v19
	v_lshl_add_u32 v78, v78, 7, v152
	v_lshl_add_u32 v79, v79, 7, v153
	s_mov_b32 m0, s79
	s_add_i32 s43, s79, 0x400
	global_load_lds_dwordx4 v78, s[50:51]
	s_mov_b32 m0, s43
	s_nop 0
	global_load_lds_dwordx4 v79, s[50:51]
	s_waitcnt vmcnt(8)
	v_add_u32_e32 v54, s99, v59
	v_add_u32_e32 v55, s99, v60
	v_add_u32_e32 v56, s99, v61
	v_add_u32_e32 v57, s99, v62
	ds_read_b64_tr_b4 v[50:51], v160 offset:640
	ds_read_b64_tr_b4 v[52:53], v160 offset:1664
	ds_read_b64_tr_b4 v[130:131], v54
	ds_read_b64_tr_b4 v[132:133], v55
	ds_read_b64_tr_b4 v[134:135], v56
	ds_read_b64_tr_b4 v[136:137], v57
	s_waitcnt lgkmcnt(6)
	v_dot8c_i32_i4_e32 v38, v122, v48
	v_dot8c_i32_i4_e32 v39, v122, v46
	v_dot8c_i32_i4_e32 v40, v124, v48
	v_dot8c_i32_i4_e32 v41, v124, v46
	v_dot8c_i32_i4_e32 v42, v126, v48
	v_dot8c_i32_i4_e32 v43, v126, v46
	v_dot8c_i32_i4_e32 v44, v128, v48
	v_dot8c_i32_i4_e32 v45, v128, v46
	v_dot8c_i32_i4_e32 v38, v123, v49
	v_dot8c_i32_i4_e32 v39, v123, v47
	v_dot8c_i32_i4_e32 v40, v125, v49
	v_dot8c_i32_i4_e32 v41, v125, v47
	v_dot8c_i32_i4_e32 v42, v127, v49
	v_dot8c_i32_i4_e32 v43, v127, v47
	v_dot8c_i32_i4_e32 v44, v129, v49
	v_dot8c_i32_i4_e32 v45, v129, v47
	s_waitcnt lgkmcnt(15)
	v_add_u32_e32 v143, 8, v139
	v_and_b32_e32 v142, 15, v143
	v_xor_b32_e32 v142, 8, v142
	v_bfe_u32 v144, v143, 4, 4
	v_mul_lo_u32 v142, v142, s92
	v_mul_lo_u32 v144, v144, s92
	v_mov_b32_e32 v143, v142
	v_mov_b32_e32 v145, v144
	ds_write2st64_b64 v159, v[142:143], v[144:145] offset1:2
	v_and_b32_e32 v78, 0xffff, v20
	v_lshrrev_b32_e32 v79, 16, v20
	v_lshl_add_u32 v78, v78, 7, v152
	v_lshl_add_u32 v79, v79, 7, v153
	s_mov_b32 m0, s98
	s_add_i32 s43, s98, 0x400
	global_load_lds_dwordx4 v78, s[50:51]
	s_mov_b32 m0, s43
	s_nop 0
	global_load_lds_dwordx4 v79, s[50:51]
	s_waitcnt vmcnt(8)
	v_add_u32_e32 v54, s76, v59
	v_add_u32_e32 v55, s76, v60
	v_add_u32_e32 v56, s76, v61
	v_add_u32_e32 v57, s76, v62
	ds_read_b64_tr_b4 v[46:47], v160 offset:768
	ds_read_b64_tr_b4 v[48:49], v160 offset:1792
	ds_read_b64_tr_b4 v[122:123], v54
	ds_read_b64_tr_b4 v[124:125], v55
	ds_read_b64_tr_b4 v[126:127], v56
	ds_read_b64_tr_b4 v[128:129], v57
	s_waitcnt lgkmcnt(7)
; #define LAS __attribute__((address_space(3)))
; __device__ __forceinline__ void peer_v_tokens(int j, const LAS unsigned short* EL, const LAS unsigned char* AL  , const LAS float* ASC  , const LAS int* SAL  , ...
;     ...
;         const int tl = it * 8 + wave, t = j * 64 + tl;
;         unsigned E[8];
;         { const LAS v4u* ep = (const LAS v4u*)(EL + tl * 128 + 16 * g); const v4u e0 = ep[0], e1 = ep[1];
;           E[0] = e0.x; E[1] = e0.y; E[2] = e0.z; E[3] = e0.w; E[4] = e1.x; E[5] = e1.y; E[6] = e1.z; E[7] = e1.w; }
;         uint2 hv[4]; float4 gv[4];
;         { unsigned ho = (unsigned)t * (D / 4) + (unsigned)lane; asm volatile("" : "+v"(ho)); const uint2* hp = (const uint2*)HB + ho; const float4* gp = (const float4*)fng + lane;
; #pragma unroll
;           for (int jq = 0; jq < 4; ++jq) { hv[jq] = hp[64 * jq]; gv[jq] = gp[64 * jq]; } }
;         VDMA(0, 0); VDMA(1, 1);
; #pragma unroll
;         for (int m = 0; m < 2; ++m) {
;     ...
;         for (int st = 0; st < 16; ++st) {
;             const int p = st >> 2, q = st & 3;
;             if (st < 14) VDMA(st + 2, (st + 2) % 3);
;             if (st < 14) asm volatile("s_waitcnt vmcnt(8)" ::: "memory");
;             else if (st == 14) asm volatile("s_waitcnt vmcnt(4)" ::: "memory");
;             else asm volatile("s_waitcnt vmcnt(0)" ::: "memory");
;             if (q == 0) {
; #pragma unroll
;                 for (int r = 0; r < 4; ++r) { accH[r] = 0; accL[r] = 0; } }
; #pragma unroll
;             for (int tp = 0; tp < 2; ++tp) {
;                 const v2i ao = TR4(ATL + (2 * q + tp) * 128 + 8 * s16), ah = TR4(ATL + 1024 + (2 * q + tp) * 128 + 8 * s16);
; #pragma unroll
;                 for (int r = 0; r < 4; ++r) {
;                     const v2i d = TR4(ldsb + BUF[st % 3] + 2048 * tp + roff[r]);
;                     accH[r] = __builtin_amdgcn_sdot8(d.x, ah.x, accH[r], false); accH[r] = __builtin_amdgcn_sdot8(d.y, ah.y, accH[r], false);
;                     accL[r] = __builtin_amdgcn_sdot8(d.x, ao.x, accL[r], false); accL[r] = __builtin_amdgcn_sdot8(d.y, ao.y, accL[r], false);
;                 }
;             }
;             asm volatile("s_waitcnt lgkmcnt(0)" ::: "memory");
;             if (q == 3) {
; #pragma unroll
;                 for (int r = 0; r < 4; ++r) STASH[256 * p + 16 * (grp + 4 * r) + pc] = f2bf(asc * (float)(2 * ((accH[r] << 4) + accL[r]) + sa));
	v_dot8c_i32_i4_e32 v38, v130, v52
	v_dot8c_i32_i4_e32 v39, v130, v50
	v_dot8c_i32_i4_e32 v40, v132, v52
	v_dot8c_i32_i4_e32 v41, v132, v50
	v_dot8c_i32_i4_e32 v42, v134, v52
	v_dot8c_i32_i4_e32 v43, v134, v50
	v_dot8c_i32_i4_e32 v44, v136, v52
	v_dot8c_i32_i4_e32 v45, v136, v50
	v_dot8c_i32_i4_e32 v38, v131, v53
	v_dot8c_i32_i4_e32 v39, v131, v51
	v_dot8c_i32_i4_e32 v40, v133, v53
	v_dot8c_i32_i4_e32 v41, v133, v51
	v_dot8c_i32_i4_e32 v42, v135, v53
	v_dot8c_i32_i4_e32 v43, v135, v51
	v_dot8c_i32_i4_e32 v44, v137, v53
	v_dot8c_i32_i4_e32 v45, v137, v51
	v_and_b32_e32 v78, 0xffff, v21
	v_lshrrev_b32_e32 v79, 16, v21
	v_lshl_add_u32 v78, v78, 7, v152
	v_lshl_add_u32 v79, v79, 7, v153
	s_mov_b32 m0, s99
	s_add_i32 s43, s99, 0x400
	global_load_lds_dwordx4 v78, s[50:51]
	s_mov_b32 m0, s43
	s_nop 0
	global_load_lds_dwordx4 v79, s[50:51]
	s_waitcnt vmcnt(8)
	v_add_u32_e32 v54, s77, v59
	v_add_u32_e32 v55, s77, v60
	v_add_u32_e32 v56, s77, v61
	v_add_u32_e32 v57, s77, v62
	ds_read_b64_tr_b4 v[50:51], v160 offset:896
	ds_read_b64_tr_b4 v[52:53], v160 offset:1920
	ds_read_b64_tr_b4 v[130:131], v54
	ds_read_b64_tr_b4 v[132:133], v55
	ds_read_b64_tr_b4 v[134:135], v56
	ds_read_b64_tr_b4 v[136:137], v57
	s_waitcnt lgkmcnt(6)
	v_dot8c_i32_i4_e32 v38, v122, v48
	v_dot8c_i32_i4_e32 v39, v122, v46
	v_dot8c_i32_i4_e32 v40, v124, v48
	v_dot8c_i32_i4_e32 v41, v124, v46
	v_dot8c_i32_i4_e32 v42, v126, v48
	v_dot8c_i32_i4_e32 v43, v126, v46
	v_dot8c_i32_i4_e32 v44, v128, v48
	v_dot8c_i32_i4_e32 v45, v128, v46
	v_dot8c_i32_i4_e32 v38, v123, v49
	v_dot8c_i32_i4_e32 v39, v123, v47
	v_dot8c_i32_i4_e32 v40, v125, v49
	v_dot8c_i32_i4_e32 v41, v125, v47
	v_dot8c_i32_i4_e32 v42, v127, v49
	v_dot8c_i32_i4_e32 v43, v127, v47
	v_dot8c_i32_i4_e32 v44, v129, v49
	v_dot8c_i32_i4_e32 v45, v129, v47
	v_and_b32_e32 v78, 0xffff, v22
	v_lshrrev_b32_e32 v79, 16, v22
	v_lshl_add_u32 v78, v78, 7, v152
	v_lshl_add_u32 v79, v79, 7, v153
	s_mov_b32 m0, s76
	s_add_i32 s43, s76, 0x400
	global_load_lds_dwordx4 v78, s[50:51]
	s_mov_b32 m0, s43
	s_nop 0
	global_load_lds_dwordx4 v79, s[50:51]
	s_waitcnt vmcnt(8)
	v_add_u32_e32 v54, s78, v59
	v_add_u32_e32 v55, s78, v60
	v_add_u32_e32 v56, s78, v61
	v_add_u32_e32 v57, s78, v62
	ds_read_b64_tr_b4 v[46:47], v160
	ds_read_b64_tr_b4 v[48:49], v160 offset:1024
	ds_read_b64_tr_b4 v[122:123], v54
	ds_read_b64_tr_b4 v[124:125], v55
	ds_read_b64_tr_b4 v[126:127], v56
	ds_read_b64_tr_b4 v[128:129], v57
	s_waitcnt lgkmcnt(6)
	v_dot8c_i32_i4_e32 v38, v130, v52
	v_dot8c_i32_i4_e32 v39, v130, v50
	v_dot8c_i32_i4_e32 v40, v132, v52
	v_dot8c_i32_i4_e32 v41, v132, v50
	v_dot8c_i32_i4_e32 v42, v134, v52
	v_dot8c_i32_i4_e32 v43, v134, v50
	v_dot8c_i32_i4_e32 v44, v136, v52
	v_dot8c_i32_i4_e32 v45, v136, v50
	v_dot8c_i32_i4_e32 v38, v131, v53
	v_dot8c_i32_i4_e32 v39, v131, v51
	v_dot8c_i32_i4_e32 v40, v133, v53
	v_dot8c_i32_i4_e32 v41, v133, v51
	v_dot8c_i32_i4_e32 v42, v135, v53
	v_dot8c_i32_i4_e32 v43, v135, v51
	v_dot8c_i32_i4_e32 v44, v137, v53
	v_dot8c_i32_i4_e32 v45, v137, v51
	s_nop 3
	s_waitcnt lgkmcnt(15)
	v_lshlrev_b32_e32 v38, 5, v38
	v_lshlrev_b32_e32 v39, 1, v39
	v_add3_u32 v38, v39, v229, v38
	v_cvt_f32_i32_e32 v38, v38
	v_mul_f32_e32 v38, v228, v38
	v_lshlrev_b32_e32 v40, 5, v40
	v_lshlrev_b32_e32 v41, 1, v41
	v_add3_u32 v40, v41, v229, v40
	v_cvt_f32_i32_e32 v40, v40
	v_mul_f32_e32 v40, v228, v40
	v_lshlrev_b32_e32 v42, 5, v42
	v_lshlrev_b32_e32 v43, 1, v43
	v_add3_u32 v42, v43, v229, v42
	v_cvt_f32_i32_e32 v42, v42
	v_mul_f32_e32 v42, v228, v42
	v_lshlrev_b32_e32 v44, 5, v44
	v_lshlrev_b32_e32 v45, 1, v45
	v_add3_u32 v44, v45, v229, v44
	v_cvt_f32_i32_e32 v44, v44
	v_mul_f32_e32 v44, v228, v44
	v_cvt_pk_bf16_f32 v174, v38, v40
	v_cvt_pk_bf16_f32 v175, v42, v44
	ds_read_b128 v[252:255], v155 offset:1024
	s_add_i32 s44, s40, 24
	s_ashr_i32 s45, s44, 31
	s_lshl_b64 s[44:45], s[44:45], 12
	v_lshl_add_u64 v[80:81], v[36:37], 0, s[44:45]
	s_waitcnt lgkmcnt(0)
	v_mul_f32_e32 v240, v240, v252
	v_mul_f32_e32 v241, v241, v253
	v_mul_f32_e32 v242, v242, v254
	v_mul_f32_e32 v243, v243, v255
	global_store_dwordx4 v[80:81], v[240:243], off offset:1024 nt
	v_add_u32_e32 v147, 8, v140
	v_and_b32_e32 v146, 15, v147
	v_xor_b32_e32 v146, 8, v146
	v_bfe_u32 v148, v147, 4, 4
	v_mul_lo_u32 v146, v146, s92
	v_mul_lo_u32 v148, v148, s92
	v_mov_b32_e32 v147, v146
	v_mov_b32_e32 v149, v148
	ds_write2st64_b64 v77, v[146:147], v[148:149] offset1:2
	v_add_u32_e32 v138, 0x1400, v74
	ds_read_u8 v139, v138
	v_add_u32_e32 v141, 0x1400, v73
	ds_read_u8 v140, v141
	s_add_i32 s43, s67, 128
	v_mov_b32_e32 v138, s43
	ds_read2st64_b32 v[228:229], v138 offset1:1
	ds_read_b128 v[26:29], v227 offset:10240
	ds_read_b128 v[30:33], v227 offset:10256
	v_mov_b32_e32 v38, 0
	v_mov_b32_e32 v39, 0
	v_mov_b32_e32 v40, 0
	v_mov_b32_e32 v41, 0
	v_mov_b32_e32 v42, 0
	v_mov_b32_e32 v43, 0
	v_mov_b32_e32 v44, 0
	v_mov_b32_e32 v45, 0
	v_and_b32_e32 v78, 0xffff, v23
	v_lshrrev_b32_e32 v79, 16, v23
	v_lshl_add_u32 v78, v78, 7, v152
	v_lshl_add_u32 v79, v79, 7, v153
	s_mov_b32 m0, s77
	s_add_i32 s43, s77, 0x400
	global_load_lds_dwordx4 v78, s[50:51]
	s_mov_b32 m0, s43
	s_nop 0
	global_load_lds_dwordx4 v79, s[50:51]
	s_waitcnt vmcnt(9)
	v_add_u32_e32 v54, s79, v59
	v_add_u32_e32 v55, s79, v60
	v_add_u32_e32 v56, s79, v61
	v_add_u32_e32 v57, s79, v62
	ds_read_b64_tr_b4 v[50:51], v160 offset:128
	ds_read_b64_tr_b4 v[52:53], v160 offset:1152
	ds_read_b64_tr_b4 v[130:131], v54
	ds_read_b64_tr_b4 v[132:133], v55
	ds_read_b64_tr_b4 v[134:135], v56
	ds_read_b64_tr_b4 v[136:137], v57
	s_waitcnt lgkmcnt(13)
; #define TR4(p_) __builtin_amdgcn_ds_read_tr4_b64_v2i32((LAS v2i*)(p_))
; #define VDMA(st_, k_) do { _Pragma("unroll") for (int i_ = 0; i_ < 4; ++i_) { \
;         const unsigned off_ = (unsigned)((st_) >> 2) * (16384u * 128u) + (PE_ID(E, 4 * ((st_) & 3) + i_) << 7) + ((i_ & 1) ? cx1 : cx0); \
;         __builtin_amdgcn_global_load_lds((const unsigned*)(V4 + off_), (LAS unsigned*)(ldsb + BUF[k_] + 1024 * i_), 16, 0, 0); } } while (0)
; __device__ __forceinline__ void peer_v_tokens(int j, const LAS unsigned short* EL, const LAS unsigned char* AL  , const LAS float* ASC  , const LAS int* SAL  , ...
;     ...
;         for (int st = 0; st < 16; ++st) {
;             const int p = st >> 2, q = st & 3;
;             if (st < 14) VDMA(st + 2, (st + 2) % 3);
;             if (st < 14) asm volatile("s_waitcnt vmcnt(8)" ::: "memory");
;             else if (st == 14) asm volatile("s_waitcnt vmcnt(4)" ::: "memory");
;             else asm volatile("s_waitcnt vmcnt(0)" ::: "memory");
;             if (q == 0) {
; #pragma unroll
;                 for (int r = 0; r < 4; ++r) { accH[r] = 0; accL[r] = 0; } }
; #pragma unroll
;             for (int tp = 0; tp < 2; ++tp) {
;                 const v2i ao = TR4(ATL + (2 * q + tp) * 128 + 8 * s16), ah = TR4(ATL + 1024 + (2 * q + tp) * 128 + 8 * s16);
; #pragma unroll
;                 for (int r = 0; r < 4; ++r) {
;                     const v2i d = TR4(ldsb + BUF[st % 3] + 2048 * tp + roff[r]);
;                     accH[r] = __builtin_amdgcn_sdot8(d.x, ah.x, accH[r], false); accH[r] = __builtin_amdgcn_sdot8(d.y, ah.y, accH[r], false);
;                     accL[r] = __builtin_amdgcn_sdot8(d.x, ao.x, accL[r], false); accL[r] = __builtin_amdgcn_sdot8(d.y, ao.y, accL[r], false);
;                 }
;             }
;             asm volatile("s_waitcnt lgkmcnt(0)" ::: "memory");
	v_dot8c_i32_i4_e32 v38, v122, v48
	v_dot8c_i32_i4_e32 v39, v122, v46
	v_dot8c_i32_i4_e32 v40, v124, v48
	v_dot8c_i32_i4_e32 v41, v124, v46
	v_dot8c_i32_i4_e32 v42, v126, v48
	v_dot8c_i32_i4_e32 v43, v126, v46
	v_dot8c_i32_i4_e32 v44, v128, v48
	v_dot8c_i32_i4_e32 v45, v128, v46
	v_dot8c_i32_i4_e32 v38, v123, v49
	v_dot8c_i32_i4_e32 v39, v123, v47
	v_dot8c_i32_i4_e32 v40, v125, v49
	v_dot8c_i32_i4_e32 v41, v125, v47
	v_dot8c_i32_i4_e32 v42, v127, v49
	v_dot8c_i32_i4_e32 v43, v127, v47
	v_dot8c_i32_i4_e32 v44, v129, v49
	v_dot8c_i32_i4_e32 v45, v129, v47
	v_and_b32_e32 v78, 0xffff, v24
	v_lshrrev_b32_e32 v79, 16, v24
	v_lshl_add_u32 v78, v78, 7, v152
	v_lshl_add_u32 v79, v79, 7, v153
	s_mov_b32 m0, s78
	s_add_i32 s43, s78, 0x400
	global_load_lds_dwordx4 v78, s[50:51]
	s_mov_b32 m0, s43
	s_nop 0
	global_load_lds_dwordx4 v79, s[50:51]
	s_waitcnt vmcnt(9)
	v_add_u32_e32 v54, s98, v59
	v_add_u32_e32 v55, s98, v60
	v_add_u32_e32 v56, s98, v61
	v_add_u32_e32 v57, s98, v62
	ds_read_b64_tr_b4 v[46:47], v160 offset:256
	ds_read_b64_tr_b4 v[48:49], v160 offset:1280
	ds_read_b64_tr_b4 v[122:123], v54
	ds_read_b64_tr_b4 v[124:125], v55
	ds_read_b64_tr_b4 v[126:127], v56
	ds_read_b64_tr_b4 v[128:129], v57
	s_waitcnt lgkmcnt(6)
	v_dot8c_i32_i4_e32 v38, v130, v52
	v_dot8c_i32_i4_e32 v39, v130, v50
	v_dot8c_i32_i4_e32 v40, v132, v52
	v_dot8c_i32_i4_e32 v41, v132, v50
	v_dot8c_i32_i4_e32 v42, v134, v52
	v_dot8c_i32_i4_e32 v43, v134, v50
	v_dot8c_i32_i4_e32 v44, v136, v52
	v_dot8c_i32_i4_e32 v45, v136, v50
	v_dot8c_i32_i4_e32 v38, v131, v53
	v_dot8c_i32_i4_e32 v39, v131, v51
	v_dot8c_i32_i4_e32 v40, v133, v53
	v_dot8c_i32_i4_e32 v41, v133, v51
	v_dot8c_i32_i4_e32 v42, v135, v53
	v_dot8c_i32_i4_e32 v43, v135, v51
	v_dot8c_i32_i4_e32 v44, v137, v53
	v_dot8c_i32_i4_e32 v45, v137, v51
	v_and_b32_e32 v78, 0xffff, v25
	v_lshrrev_b32_e32 v79, 16, v25
	v_lshl_add_u32 v78, v78, 7, v152
	v_lshl_add_u32 v79, v79, 7, v153
	s_mov_b32 m0, s79
	s_add_i32 s43, s79, 0x400
	global_load_lds_dwordx4 v78, s[50:51]
	s_mov_b32 m0, s43
	s_nop 0
	global_load_lds_dwordx4 v79, s[50:51]
	s_waitcnt vmcnt(9)
	v_add_u32_e32 v54, s99, v59
	v_add_u32_e32 v55, s99, v60
	v_add_u32_e32 v56, s99, v61
	v_add_u32_e32 v57, s99, v62
	ds_read_b64_tr_b4 v[50:51], v160 offset:384
	ds_read_b64_tr_b4 v[52:53], v160 offset:1408
	ds_read_b64_tr_b4 v[130:131], v54
	ds_read_b64_tr_b4 v[132:133], v55
	ds_read_b64_tr_b4 v[134:135], v56
	ds_read_b64_tr_b4 v[136:137], v57
	s_waitcnt lgkmcnt(6)
	v_dot8c_i32_i4_e32 v38, v122, v48
	v_dot8c_i32_i4_e32 v39, v122, v46
	v_dot8c_i32_i4_e32 v40, v124, v48
	v_dot8c_i32_i4_e32 v41, v124, v46
	v_dot8c_i32_i4_e32 v42, v126, v48
	v_dot8c_i32_i4_e32 v43, v126, v46
	v_dot8c_i32_i4_e32 v44, v128, v48
	v_dot8c_i32_i4_e32 v45, v128, v46
	v_dot8c_i32_i4_e32 v38, v123, v49
	v_dot8c_i32_i4_e32 v39, v123, v47
	v_dot8c_i32_i4_e32 v40, v125, v49
	v_dot8c_i32_i4_e32 v41, v125, v47
	v_dot8c_i32_i4_e32 v42, v127, v49
	v_dot8c_i32_i4_e32 v43, v127, v47
	v_dot8c_i32_i4_e32 v44, v129, v49
	v_dot8c_i32_i4_e32 v45, v129, v47
	s_waitcnt lgkmcnt(15)
	v_and_b32_e32 v78, 0xffff, v26
	v_lshrrev_b32_e32 v79, 16, v26
	v_lshl_add_u32 v78, v78, 7, v152
	v_lshl_add_u32 v79, v79, 7, v153
	s_mov_b32 m0, s98
	s_add_i32 s43, s98, 0x400
	global_load_lds_dwordx4 v78, s[50:51]
	s_mov_b32 m0, s43
	s_nop 0
	global_load_lds_dwordx4 v79, s[50:51]
	s_waitcnt vmcnt(9)
	v_add_u32_e32 v54, s76, v59
	v_add_u32_e32 v55, s76, v60
	v_add_u32_e32 v56, s76, v61
	v_add_u32_e32 v57, s76, v62
	ds_read_b64_tr_b4 v[46:47], v160 offset:512
	ds_read_b64_tr_b4 v[48:49], v160 offset:1536
	ds_read_b64_tr_b4 v[122:123], v54
	ds_read_b64_tr_b4 v[124:125], v55
	ds_read_b64_tr_b4 v[126:127], v56
	ds_read_b64_tr_b4 v[128:129], v57
	s_waitcnt lgkmcnt(6)
	v_dot8c_i32_i4_e32 v38, v130, v52
	v_dot8c_i32_i4_e32 v39, v130, v50
	v_dot8c_i32_i4_e32 v40, v132, v52
	v_dot8c_i32_i4_e32 v41, v132, v50
	v_dot8c_i32_i4_e32 v42, v134, v52
	v_dot8c_i32_i4_e32 v43, v134, v50
	v_dot8c_i32_i4_e32 v44, v136, v52
	v_dot8c_i32_i4_e32 v45, v136, v50
	v_dot8c_i32_i4_e32 v38, v131, v53
	v_dot8c_i32_i4_e32 v39, v131, v51
	v_dot8c_i32_i4_e32 v40, v133, v53
	v_dot8c_i32_i4_e32 v41, v133, v51
	v_dot8c_i32_i4_e32 v42, v135, v53
	v_dot8c_i32_i4_e32 v43, v135, v51
	v_dot8c_i32_i4_e32 v44, v137, v53
	v_dot8c_i32_i4_e32 v45, v137, v51
	v_and_b32_e32 v78, 0xffff, v27
	v_lshrrev_b32_e32 v79, 16, v27
	v_lshl_add_u32 v78, v78, 7, v152
	v_lshl_add_u32 v79, v79, 7, v153
	s_mov_b32 m0, s99
	s_add_i32 s43, s99, 0x400
	global_load_lds_dwordx4 v78, s[50:51]
	s_mov_b32 m0, s43
	s_nop 0
	global_load_lds_dwordx4 v79, s[50:51]
	s_waitcnt vmcnt(8)
	v_add_u32_e32 v54, s77, v59
	v_add_u32_e32 v55, s77, v60
	v_add_u32_e32 v56, s77, v61
	v_add_u32_e32 v57, s77, v62
	ds_read_b64_tr_b4 v[50:51], v160 offset:640
	ds_read_b64_tr_b4 v[52:53], v160 offset:1664
	ds_read_b64_tr_b4 v[130:131], v54
	ds_read_b64_tr_b4 v[132:133], v55
	ds_read_b64_tr_b4 v[134:135], v56
	ds_read_b64_tr_b4 v[136:137], v57
	s_waitcnt lgkmcnt(6)
	v_dot8c_i32_i4_e32 v38, v122, v48
	v_dot8c_i32_i4_e32 v39, v122, v46
	v_dot8c_i32_i4_e32 v40, v124, v48
	v_dot8c_i32_i4_e32 v41, v124, v46
	v_dot8c_i32_i4_e32 v42, v126, v48
	v_dot8c_i32_i4_e32 v43, v126, v46
	v_dot8c_i32_i4_e32 v44, v128, v48
	v_dot8c_i32_i4_e32 v45, v128, v46
	v_dot8c_i32_i4_e32 v38, v123, v49
	v_dot8c_i32_i4_e32 v39, v123, v47
	v_dot8c_i32_i4_e32 v40, v125, v49
	v_dot8c_i32_i4_e32 v41, v125, v47
	v_dot8c_i32_i4_e32 v42, v127, v49
	v_dot8c_i32_i4_e32 v43, v127, v47
	v_dot8c_i32_i4_e32 v44, v129, v49
	v_dot8c_i32_i4_e32 v45, v129, v47
	s_waitcnt lgkmcnt(15)
; #define LAS __attribute__((address_space(3)))
; __device__ __forceinline__ bf16 f2bf(float f) { return (bf16)f2bfu(f); }
; #define TR4(p_) __builtin_amdgcn_ds_read_tr4_b64_v2i32((LAS v2i*)(p_))
; __device__ __forceinline__ void peer_v_tokens(int j, const LAS unsigned short* EL, const LAS unsigned char* AL  , const LAS float* ASC  , const LAS int* SAL  , ...
;     ...
;             const int idx = lane + 64 * m, tau = idx >> 4, sr = idx & 15, k = 16 * (sr & 7) + 2 * tau + (sr >> 3);
;             const int aq = (int)*(const LAS signed char*)(AL + tl * 128 + k); const int tq = aq + 8;
;             const unsigned lo = (((unsigned)tq & 15u) ^ 8u) * 0x11111111u, hi = ((unsigned)(tq >> 4) & 15u) * 0x11111111u;
;             typedef unsigned u2v __attribute__((ext_vector_type(2)));
;             u2v l2; l2.x = lo; l2.y = lo; u2v h2; h2.x = hi; h2.y = hi;
;             *(LAS u2v*)(ATL + 8 * idx) = l2; *(LAS u2v*)(ATL + 1024 + 8 * idx) = h2;
;     ...
;         for (int st = 0; st < 16; ++st) {
;             const int p = st >> 2, q = st & 3;
;             if (st < 14) VDMA(st + 2, (st + 2) % 3);
;             if (st < 14) asm volatile("s_waitcnt vmcnt(8)" ::: "memory");
;             else if (st == 14) asm volatile("s_waitcnt vmcnt(4)" ::: "memory");
;             else asm volatile("s_waitcnt vmcnt(0)" ::: "memory");
;             if (q == 0) {
; #pragma unroll
;                 for (int r = 0; r < 4; ++r) { accH[r] = 0; accL[r] = 0; } }
; #pragma unroll
;             for (int tp = 0; tp < 2; ++tp) {
;                 const v2i ao = TR4(ATL + (2 * q + tp) * 128 + 8 * s16), ah = TR4(ATL + 1024 + (2 * q + tp) * 128 + 8 * s16);
; #pragma unroll
;                 for (int r = 0; r < 4; ++r) {
;                     const v2i d = TR4(ldsb + BUF[st % 3] + 2048 * tp + roff[r]);
;                     accH[r] = __builtin_amdgcn_sdot8(d.x, ah.x, accH[r], false); accH[r] = __builtin_amdgcn_sdot8(d.y, ah.y, accH[r], false);
;                     accL[r] = __builtin_amdgcn_sdot8(d.x, ao.x, accL[r], false); accL[r] = __builtin_amdgcn_sdot8(d.y, ao.y, accL[r], false);
;                 }
;             }
;             asm volatile("s_waitcnt lgkmcnt(0)" ::: "memory");
;             if (q == 3) {
; #pragma unroll
;                 for (int r = 0; r < 4; ++r) STASH[256 * p + 16 * (grp + 4 * r) + pc] = f2bf(asc * (float)(2 * ((accH[r] << 4) + accL[r]) + sa));
	v_add_u32_e32 v143, 8, v139
	v_and_b32_e32 v142, 15, v143
	v_xor_b32_e32 v142, 8, v142
	v_bfe_u32 v144, v143, 4, 4
	v_mul_lo_u32 v142, v142, s92
	v_mul_lo_u32 v144, v144, s92
	v_mov_b32_e32 v143, v142
	v_mov_b32_e32 v145, v144
	ds_write2st64_b64 v159, v[142:143], v[144:145] offset1:2
	v_and_b32_e32 v78, 0xffff, v28
	v_lshrrev_b32_e32 v79, 16, v28
	v_lshl_add_u32 v78, v78, 7, v152
	v_lshl_add_u32 v79, v79, 7, v153
	s_mov_b32 m0, s76
	s_add_i32 s43, s76, 0x400
	global_load_lds_dwordx4 v78, s[50:51]
	s_mov_b32 m0, s43
	s_nop 0
	global_load_lds_dwordx4 v79, s[50:51]
	s_waitcnt vmcnt(8)
	v_add_u32_e32 v54, s78, v59
	v_add_u32_e32 v55, s78, v60
	v_add_u32_e32 v56, s78, v61
	v_add_u32_e32 v57, s78, v62
	ds_read_b64_tr_b4 v[46:47], v160 offset:768
	ds_read_b64_tr_b4 v[48:49], v160 offset:1792
	ds_read_b64_tr_b4 v[122:123], v54
	ds_read_b64_tr_b4 v[124:125], v55
	ds_read_b64_tr_b4 v[126:127], v56
	ds_read_b64_tr_b4 v[128:129], v57
	s_waitcnt lgkmcnt(7)
	v_dot8c_i32_i4_e32 v38, v130, v52
	v_dot8c_i32_i4_e32 v39, v130, v50
	v_dot8c_i32_i4_e32 v40, v132, v52
	v_dot8c_i32_i4_e32 v41, v132, v50
	v_dot8c_i32_i4_e32 v42, v134, v52
	v_dot8c_i32_i4_e32 v43, v134, v50
	v_dot8c_i32_i4_e32 v44, v136, v52
	v_dot8c_i32_i4_e32 v45, v136, v50
	v_dot8c_i32_i4_e32 v38, v131, v53
	v_dot8c_i32_i4_e32 v39, v131, v51
	v_dot8c_i32_i4_e32 v40, v133, v53
	v_dot8c_i32_i4_e32 v41, v133, v51
	v_dot8c_i32_i4_e32 v42, v135, v53
	v_dot8c_i32_i4_e32 v43, v135, v51
	v_dot8c_i32_i4_e32 v44, v137, v53
	v_dot8c_i32_i4_e32 v45, v137, v51
	v_and_b32_e32 v78, 0xffff, v29
	v_lshrrev_b32_e32 v79, 16, v29
	v_lshl_add_u32 v78, v78, 7, v152
	v_lshl_add_u32 v79, v79, 7, v153
	s_mov_b32 m0, s77
	s_add_i32 s43, s77, 0x400
	global_load_lds_dwordx4 v78, s[50:51]
	s_mov_b32 m0, s43
	s_nop 0
	global_load_lds_dwordx4 v79, s[50:51]
	s_waitcnt vmcnt(8)
	v_add_u32_e32 v54, s79, v59
	v_add_u32_e32 v55, s79, v60
	v_add_u32_e32 v56, s79, v61
	v_add_u32_e32 v57, s79, v62
	ds_read_b64_tr_b4 v[50:51], v160 offset:896
	ds_read_b64_tr_b4 v[52:53], v160 offset:1920
	ds_read_b64_tr_b4 v[130:131], v54
	ds_read_b64_tr_b4 v[132:133], v55
	ds_read_b64_tr_b4 v[134:135], v56
	ds_read_b64_tr_b4 v[136:137], v57
	s_waitcnt lgkmcnt(6)
	v_dot8c_i32_i4_e32 v38, v122, v48
	v_dot8c_i32_i4_e32 v39, v122, v46
	v_dot8c_i32_i4_e32 v40, v124, v48
	v_dot8c_i32_i4_e32 v41, v124, v46
	v_dot8c_i32_i4_e32 v42, v126, v48
	v_dot8c_i32_i4_e32 v43, v126, v46
	v_dot8c_i32_i4_e32 v44, v128, v48
	v_dot8c_i32_i4_e32 v45, v128, v46
	v_dot8c_i32_i4_e32 v38, v123, v49
	v_dot8c_i32_i4_e32 v39, v123, v47
	v_dot8c_i32_i4_e32 v40, v125, v49
	v_dot8c_i32_i4_e32 v41, v125, v47
	v_dot8c_i32_i4_e32 v42, v127, v49
	v_dot8c_i32_i4_e32 v43, v127, v47
	v_dot8c_i32_i4_e32 v44, v129, v49
	v_dot8c_i32_i4_e32 v45, v129, v47
	v_and_b32_e32 v78, 0xffff, v30
	v_lshrrev_b32_e32 v79, 16, v30
	v_lshl_add_u32 v78, v78, 7, v152
	v_lshl_add_u32 v79, v79, 7, v153
	s_mov_b32 m0, s78
	s_add_i32 s43, s78, 0x400
	global_load_lds_dwordx4 v78, s[50:51]
	s_mov_b32 m0, s43
	s_nop 0
	global_load_lds_dwordx4 v79, s[50:51]
	s_waitcnt vmcnt(8)
	v_add_u32_e32 v54, s98, v59
	v_add_u32_e32 v55, s98, v60
	v_add_u32_e32 v56, s98, v61
	v_add_u32_e32 v57, s98, v62
	ds_read_b64_tr_b4 v[46:47], v160
	ds_read_b64_tr_b4 v[48:49], v160 offset:1024
	ds_read_b64_tr_b4 v[122:123], v54
	ds_read_b64_tr_b4 v[124:125], v55
	ds_read_b64_tr_b4 v[126:127], v56
	ds_read_b64_tr_b4 v[128:129], v57
	s_waitcnt lgkmcnt(6)
	v_dot8c_i32_i4_e32 v38, v130, v52
	v_dot8c_i32_i4_e32 v39, v130, v50
	v_dot8c_i32_i4_e32 v40, v132, v52
	v_dot8c_i32_i4_e32 v41, v132, v50
	v_dot8c_i32_i4_e32 v42, v134, v52
	v_dot8c_i32_i4_e32 v43, v134, v50
	v_dot8c_i32_i4_e32 v44, v136, v52
	v_dot8c_i32_i4_e32 v45, v136, v50
	v_dot8c_i32_i4_e32 v38, v131, v53
	v_dot8c_i32_i4_e32 v39, v131, v51
	v_dot8c_i32_i4_e32 v40, v133, v53
	v_dot8c_i32_i4_e32 v41, v133, v51
	v_dot8c_i32_i4_e32 v42, v135, v53
	v_dot8c_i32_i4_e32 v43, v135, v51
	v_dot8c_i32_i4_e32 v44, v137, v53
	v_dot8c_i32_i4_e32 v45, v137, v51
	s_nop 3
	s_waitcnt lgkmcnt(15)
	v_lshlrev_b32_e32 v38, 5, v38
	v_lshlrev_b32_e32 v39, 1, v39
	v_add3_u32 v38, v39, v229, v38
	v_cvt_f32_i32_e32 v38, v38
	v_mul_f32_e32 v38, v228, v38
	v_lshlrev_b32_e32 v40, 5, v40
	v_lshlrev_b32_e32 v41, 1, v41
	v_add3_u32 v40, v41, v229, v40
	v_cvt_f32_i32_e32 v40, v40
	v_mul_f32_e32 v40, v228, v40
	v_lshlrev_b32_e32 v42, 5, v42
	v_lshlrev_b32_e32 v43, 1, v43
	v_add3_u32 v42, v43, v229, v42
	v_cvt_f32_i32_e32 v42, v42
	v_mul_f32_e32 v42, v228, v42
	v_lshlrev_b32_e32 v44, 5, v44
	v_lshlrev_b32_e32 v45, 1, v45
	v_add3_u32 v44, v45, v229, v44
	v_cvt_f32_i32_e32 v44, v44
	v_mul_f32_e32 v44, v228, v44
	v_cvt_pk_bf16_f32 v168, v38, v40
	v_cvt_pk_bf16_f32 v169, v42, v44
	ds_read_b128 v[252:255], v156
	s_add_i32 s44, s40, 24
	s_ashr_i32 s45, s44, 31
	s_lshl_b64 s[44:45], s[44:45], 12
	v_lshl_add_u64 v[80:81], v[36:37], 0, s[44:45]
	s_waitcnt lgkmcnt(0)
; __device__ __forceinline__ void peer_v_tokens(int j, const LAS unsigned short* EL, const LAS unsigned char* AL  , const LAS float* ASC  , const LAS int* SAL  , ...
;     ...
;         const int tl = it * 8 + wave, t = j * 64 + tl;
;         unsigned E[8];
;         { const LAS v4u* ep = (const LAS v4u*)(EL + tl * 128 + 16 * g); const v4u e0 = ep[0], e1 = ep[1];
;           E[0] = e0.x; E[1] = e0.y; E[2] = e0.z; E[3] = e0.w; E[4] = e1.x; E[5] = e1.y; E[6] = e1.z; E[7] = e1.w; }
;         uint2 hv[4]; float4 gv[4];
;         { unsigned ho = (unsigned)t * (D / 4) + (unsigned)lane; asm volatile("" : "+v"(ho)); const uint2* hp = (const uint2*)HB + ho; const float4* gp = (const float4*)fng + lane;
; #pragma unroll
;           for (int jq = 0; jq < 4; ++jq) { hv[jq] = hp[64 * jq]; gv[jq] = gp[64 * jq]; } }
;         VDMA(0, 0); VDMA(1, 1);
; #pragma unroll
;         for (int m = 0; m < 2; ++m) {
;             const int idx = lane + 64 * m, tau = idx >> 4, sr = idx & 15, k = 16 * (sr & 7) + 2 * tau + (sr >> 3);
;             const int aq = (int)*(const LAS signed char*)(AL + tl * 128 + k); const int tq = aq + 8;
;             const unsigned lo = (((unsigned)tq & 15u) ^ 8u) * 0x11111111u, hi = ((unsigned)(tq >> 4) & 15u) * 0x11111111u;
;             typedef unsigned u2v __attribute__((ext_vector_type(2)));
;             u2v l2; l2.x = lo; l2.y = lo; u2v h2; h2.x = hi; h2.y = hi;
;             *(LAS u2v*)(ATL + 8 * idx) = l2; *(LAS u2v*)(ATL + 1024 + 8 * idx) = h2;
;         }
;         const float asc = ASC[tl]; const int sa = SAL[tl];
;         CFENCE();
;         int accH[4], accL[4];
; #pragma unroll
;         for (int st = 0; st < 16; ++st) {
;             const int p = st >> 2, q = st & 3;
;             if (st < 14) VDMA(st + 2, (st + 2) % 3);
;             if (st < 14) asm volatile("s_waitcnt vmcnt(8)" ::: "memory");
;             else if (st == 14) asm volatile("s_waitcnt vmcnt(4)" ::: "memory");
;             else asm volatile("s_waitcnt vmcnt(0)" ::: "memory");
;             if (q == 0) {
; #pragma unroll
;                 for (int r = 0; r < 4; ++r) { accH[r] = 0; accL[r] = 0; } }
; #pragma unroll
;             for (int tp = 0; tp < 2; ++tp) {
;                 const v2i ao = TR4(ATL + (2 * q + tp) * 128 + 8 * s16), ah = TR4(ATL + 1024 + (2 * q + tp) * 128 + 8 * s16);
; #pragma unroll
;                 for (int r = 0; r < 4; ++r) {
	v_mul_f32_e32 v244, v244, v252
	v_mul_f32_e32 v245, v245, v253
	v_mul_f32_e32 v246, v246, v254
	v_mul_f32_e32 v247, v247, v255
	global_store_dwordx4 v[80:81], v[244:247], off offset:2048 nt
	s_add_i32 s43, s40, 32
	s_lshl_b32 s43, s43, 11
	v_add_u32_e32 v138, s43, v66
	global_load_dwordx2 v[194:195], v138, s[70:71]
	global_load_dwordx2 v[196:197], v138, s[70:71] offset:512
	global_load_dwordx2 v[198:199], v138, s[70:71] offset:1024
	global_load_dwordx2 v[200:201], v138, s[70:71] offset:1536
	v_add_u32_e32 v147, 8, v140
	v_and_b32_e32 v146, 15, v147
	v_xor_b32_e32 v146, 8, v146
	v_bfe_u32 v148, v147, 4, 4
	v_mul_lo_u32 v146, v146, s92
	v_mul_lo_u32 v148, v148, s92
	v_mov_b32_e32 v147, v146
	v_mov_b32_e32 v149, v148
	ds_write2st64_b64 v77, v[146:147], v[148:149] offset1:2
	v_add_u32_e32 v138, 0x1800, v74
	ds_read_u8 v139, v138
	v_add_u32_e32 v141, 0x1800, v73
	ds_read_u8 v140, v141
	s_add_i32 s43, s67, 160
	v_mov_b32_e32 v138, s43
	ds_read2st64_b32 v[228:229], v138 offset1:1
	ds_read_b128 v[18:21], v227 offset:12288
	ds_read_b128 v[22:25], v227 offset:12304
	v_mov_b32_e32 v150, v63
	v_mov_b32_e32 v151, v64
	v_mov_b32_e32 v38, 0
	v_mov_b32_e32 v39, 0
	v_mov_b32_e32 v40, 0
	v_mov_b32_e32 v41, 0
	v_mov_b32_e32 v42, 0
	v_mov_b32_e32 v43, 0
	v_mov_b32_e32 v44, 0
	v_mov_b32_e32 v45, 0
	v_and_b32_e32 v78, 0xffff, v31
	v_lshrrev_b32_e32 v79, 16, v31
	v_lshl_add_u32 v78, v78, 7, v152
	v_lshl_add_u32 v79, v79, 7, v153
	s_mov_b32 m0, s79
	s_add_i32 s43, s79, 0x400
	global_load_lds_dwordx4 v78, s[50:51]
	s_mov_b32 m0, s43
	s_nop 0
	global_load_lds_dwordx4 v79, s[50:51]
	s_waitcnt vmcnt(13)
	v_add_u32_e32 v54, s99, v59
	v_add_u32_e32 v55, s99, v60
	v_add_u32_e32 v56, s99, v61
	v_add_u32_e32 v57, s99, v62
	ds_read_b64_tr_b4 v[50:51], v160 offset:128
	ds_read_b64_tr_b4 v[52:53], v160 offset:1152
	ds_read_b64_tr_b4 v[130:131], v54
	ds_read_b64_tr_b4 v[132:133], v55
	ds_read_b64_tr_b4 v[134:135], v56
	ds_read_b64_tr_b4 v[136:137], v57
	s_waitcnt lgkmcnt(13)
	v_dot8c_i32_i4_e32 v38, v122, v48
	v_dot8c_i32_i4_e32 v39, v122, v46
	v_dot8c_i32_i4_e32 v40, v124, v48
	v_dot8c_i32_i4_e32 v41, v124, v46
	v_dot8c_i32_i4_e32 v42, v126, v48
	v_dot8c_i32_i4_e32 v43, v126, v46
	v_dot8c_i32_i4_e32 v44, v128, v48
	v_dot8c_i32_i4_e32 v45, v128, v46
	v_dot8c_i32_i4_e32 v38, v123, v49
	v_dot8c_i32_i4_e32 v39, v123, v47
	v_dot8c_i32_i4_e32 v40, v125, v49
	v_dot8c_i32_i4_e32 v41, v125, v47
	v_dot8c_i32_i4_e32 v42, v127, v49
	v_dot8c_i32_i4_e32 v43, v127, v47
	v_dot8c_i32_i4_e32 v44, v129, v49
	v_dot8c_i32_i4_e32 v45, v129, v47
	v_and_b32_e32 v78, 0xffff, v32
	v_lshrrev_b32_e32 v79, 16, v32
	v_lshl_add_u32 v78, v78, 7, v152
	v_lshl_add_u32 v79, v79, 7, v153
	s_mov_b32 m0, s98
	s_add_i32 s43, s98, 0x400
	global_load_lds_dwordx4 v78, s[50:51]
	s_mov_b32 m0, s43
	s_nop 0
	global_load_lds_dwordx4 v79, s[50:51]
	s_waitcnt vmcnt(13)
	v_add_u32_e32 v54, s76, v59
	v_add_u32_e32 v55, s76, v60
	v_add_u32_e32 v56, s76, v61
	v_add_u32_e32 v57, s76, v62
	ds_read_b64_tr_b4 v[46:47], v160 offset:256
	ds_read_b64_tr_b4 v[48:49], v160 offset:1280
	ds_read_b64_tr_b4 v[122:123], v54
	ds_read_b64_tr_b4 v[124:125], v55
	ds_read_b64_tr_b4 v[126:127], v56
	ds_read_b64_tr_b4 v[128:129], v57
	s_waitcnt lgkmcnt(6)
	v_dot8c_i32_i4_e32 v38, v130, v52
	v_dot8c_i32_i4_e32 v39, v130, v50
	v_dot8c_i32_i4_e32 v40, v132, v52
	v_dot8c_i32_i4_e32 v41, v132, v50
	v_dot8c_i32_i4_e32 v42, v134, v52
	v_dot8c_i32_i4_e32 v43, v134, v50
	v_dot8c_i32_i4_e32 v44, v136, v52
	v_dot8c_i32_i4_e32 v45, v136, v50
	v_dot8c_i32_i4_e32 v38, v131, v53
	v_dot8c_i32_i4_e32 v39, v131, v51
	v_dot8c_i32_i4_e32 v40, v133, v53
	v_dot8c_i32_i4_e32 v41, v133, v51
	v_dot8c_i32_i4_e32 v42, v135, v53
	v_dot8c_i32_i4_e32 v43, v135, v51
	v_dot8c_i32_i4_e32 v44, v137, v53
	v_dot8c_i32_i4_e32 v45, v137, v51
	v_and_b32_e32 v78, 0xffff, v33
	v_lshrrev_b32_e32 v79, 16, v33
	v_lshl_add_u32 v78, v78, 7, v152
	v_lshl_add_u32 v79, v79, 7, v153
	s_mov_b32 m0, s99
	s_add_i32 s43, s99, 0x400
	global_load_lds_dwordx4 v78, s[50:51]
	s_mov_b32 m0, s43
	s_nop 0
	global_load_lds_dwordx4 v79, s[50:51]
	s_waitcnt vmcnt(13)
	v_add_u32_e32 v54, s77, v59
	v_add_u32_e32 v55, s77, v60
	v_add_u32_e32 v56, s77, v61
	v_add_u32_e32 v57, s77, v62
	ds_read_b64_tr_b4 v[50:51], v160 offset:384
	ds_read_b64_tr_b4 v[52:53], v160 offset:1408
	ds_read_b64_tr_b4 v[130:131], v54
	ds_read_b64_tr_b4 v[132:133], v55
	ds_read_b64_tr_b4 v[134:135], v56
	ds_read_b64_tr_b4 v[136:137], v57
	s_waitcnt lgkmcnt(6)
	v_dot8c_i32_i4_e32 v38, v122, v48
	v_dot8c_i32_i4_e32 v39, v122, v46
	v_dot8c_i32_i4_e32 v40, v124, v48
	v_dot8c_i32_i4_e32 v41, v124, v46
	v_dot8c_i32_i4_e32 v42, v126, v48
	v_dot8c_i32_i4_e32 v43, v126, v46
	v_dot8c_i32_i4_e32 v44, v128, v48
	v_dot8c_i32_i4_e32 v45, v128, v46
	v_dot8c_i32_i4_e32 v38, v123, v49
	v_dot8c_i32_i4_e32 v39, v123, v47
	v_dot8c_i32_i4_e32 v40, v125, v49
	v_dot8c_i32_i4_e32 v41, v125, v47
	v_dot8c_i32_i4_e32 v42, v127, v49
	v_dot8c_i32_i4_e32 v43, v127, v47
	v_dot8c_i32_i4_e32 v44, v129, v49
	v_dot8c_i32_i4_e32 v45, v129, v47
	s_waitcnt lgkmcnt(15)
	v_and_b32_e32 v78, 0xffff, v18
	v_lshrrev_b32_e32 v79, 16, v18
	v_lshl_add_u32 v78, v78, 7, v150
	v_lshl_add_u32 v79, v79, 7, v151
	s_mov_b32 m0, s76
	s_add_i32 s43, s76, 0x400
	global_load_lds_dwordx4 v78, s[50:51]
	s_mov_b32 m0, s43
	s_nop 0
	global_load_lds_dwordx4 v79, s[50:51]
	s_waitcnt vmcnt(13)
	v_add_u32_e32 v54, s78, v59
	v_add_u32_e32 v55, s78, v60
	v_add_u32_e32 v56, s78, v61
	v_add_u32_e32 v57, s78, v62
	ds_read_b64_tr_b4 v[46:47], v160 offset:512
	ds_read_b64_tr_b4 v[48:49], v160 offset:1536
	ds_read_b64_tr_b4 v[122:123], v54
	ds_read_b64_tr_b4 v[124:125], v55
	ds_read_b64_tr_b4 v[126:127], v56
	ds_read_b64_tr_b4 v[128:129], v57
	s_waitcnt lgkmcnt(6)
; #define LAS __attribute__((address_space(3)))
; __device__ __forceinline__ bf16 f2bf(float f) { return (bf16)f2bfu(f); }
; #define TR4(p_) __builtin_amdgcn_ds_read_tr4_b64_v2i32((LAS v2i*)(p_))
; __device__ __forceinline__ void peer_v_tokens(int j, const LAS unsigned short* EL, const LAS unsigned char* AL  , const LAS float* ASC  , const LAS int* SAL  , ...
;     ...
;             const int idx = lane + 64 * m, tau = idx >> 4, sr = idx & 15, k = 16 * (sr & 7) + 2 * tau + (sr >> 3);
;             const int aq = (int)*(const LAS signed char*)(AL + tl * 128 + k); const int tq = aq + 8;
;             const unsigned lo = (((unsigned)tq & 15u) ^ 8u) * 0x11111111u, hi = ((unsigned)(tq >> 4) & 15u) * 0x11111111u;
;             typedef unsigned u2v __attribute__((ext_vector_type(2)));
;             u2v l2; l2.x = lo; l2.y = lo; u2v h2; h2.x = hi; h2.y = hi;
;             *(LAS u2v*)(ATL + 8 * idx) = l2; *(LAS u2v*)(ATL + 1024 + 8 * idx) = h2;
;     ...
;         for (int st = 0; st < 16; ++st) {
;             const int p = st >> 2, q = st & 3;
;             if (st < 14) VDMA(st + 2, (st + 2) % 3);
;             if (st < 14) asm volatile("s_waitcnt vmcnt(8)" ::: "memory");
;             else if (st == 14) asm volatile("s_waitcnt vmcnt(4)" ::: "memory");
;             else asm volatile("s_waitcnt vmcnt(0)" ::: "memory");
;             if (q == 0) {
; #pragma unroll
;                 for (int r = 0; r < 4; ++r) { accH[r] = 0; accL[r] = 0; } }
; #pragma unroll
;             for (int tp = 0; tp < 2; ++tp) {
;                 const v2i ao = TR4(ATL + (2 * q + tp) * 128 + 8 * s16), ah = TR4(ATL + 1024 + (2 * q + tp) * 128 + 8 * s16);
; #pragma unroll
;                 for (int r = 0; r < 4; ++r) {
;                     const v2i d = TR4(ldsb + BUF[st % 3] + 2048 * tp + roff[r]);
;                     accH[r] = __builtin_amdgcn_sdot8(d.x, ah.x, accH[r], false); accH[r] = __builtin_amdgcn_sdot8(d.y, ah.y, accH[r], false);
;                     accL[r] = __builtin_amdgcn_sdot8(d.x, ao.x, accL[r], false); accL[r] = __builtin_amdgcn_sdot8(d.y, ao.y, accL[r], false);
;                 }
;             }
;             asm volatile("s_waitcnt lgkmcnt(0)" ::: "memory");
;             if (q == 3) {
; #pragma unroll
;                 for (int r = 0; r < 4; ++r) STASH[256 * p + 16 * (grp + 4 * r) + pc] = f2bf(asc * (float)(2 * ((accH[r] << 4) + accL[r]) + sa));
	v_dot8c_i32_i4_e32 v38, v130, v52
	v_dot8c_i32_i4_e32 v39, v130, v50
	v_dot8c_i32_i4_e32 v40, v132, v52
	v_dot8c_i32_i4_e32 v41, v132, v50
	v_dot8c_i32_i4_e32 v42, v134, v52
	v_dot8c_i32_i4_e32 v43, v134, v50
	v_dot8c_i32_i4_e32 v44, v136, v52
	v_dot8c_i32_i4_e32 v45, v136, v50
	v_dot8c_i32_i4_e32 v38, v131, v53
	v_dot8c_i32_i4_e32 v39, v131, v51
	v_dot8c_i32_i4_e32 v40, v133, v53
	v_dot8c_i32_i4_e32 v41, v133, v51
	v_dot8c_i32_i4_e32 v42, v135, v53
	v_dot8c_i32_i4_e32 v43, v135, v51
	v_dot8c_i32_i4_e32 v44, v137, v53
	v_dot8c_i32_i4_e32 v45, v137, v51
	v_and_b32_e32 v78, 0xffff, v19
	v_lshrrev_b32_e32 v79, 16, v19
	v_lshl_add_u32 v78, v78, 7, v150
	v_lshl_add_u32 v79, v79, 7, v151
	s_mov_b32 m0, s77
	s_add_i32 s43, s77, 0x400
	global_load_lds_dwordx4 v78, s[50:51]
	s_mov_b32 m0, s43
	s_nop 0
	global_load_lds_dwordx4 v79, s[50:51]
	s_waitcnt vmcnt(8)
	v_add_u32_e32 v54, s79, v59
	v_add_u32_e32 v55, s79, v60
	v_add_u32_e32 v56, s79, v61
	v_add_u32_e32 v57, s79, v62
	ds_read_b64_tr_b4 v[50:51], v160 offset:640
	ds_read_b64_tr_b4 v[52:53], v160 offset:1664
	ds_read_b64_tr_b4 v[130:131], v54
	ds_read_b64_tr_b4 v[132:133], v55
	ds_read_b64_tr_b4 v[134:135], v56
	ds_read_b64_tr_b4 v[136:137], v57
	s_waitcnt lgkmcnt(6)
	v_dot8c_i32_i4_e32 v38, v122, v48
	v_dot8c_i32_i4_e32 v39, v122, v46
	v_dot8c_i32_i4_e32 v40, v124, v48
	v_dot8c_i32_i4_e32 v41, v124, v46
	v_dot8c_i32_i4_e32 v42, v126, v48
	v_dot8c_i32_i4_e32 v43, v126, v46
	v_dot8c_i32_i4_e32 v44, v128, v48
	v_dot8c_i32_i4_e32 v45, v128, v46
	v_dot8c_i32_i4_e32 v38, v123, v49
	v_dot8c_i32_i4_e32 v39, v123, v47
	v_dot8c_i32_i4_e32 v40, v125, v49
	v_dot8c_i32_i4_e32 v41, v125, v47
	v_dot8c_i32_i4_e32 v42, v127, v49
	v_dot8c_i32_i4_e32 v43, v127, v47
	v_dot8c_i32_i4_e32 v44, v129, v49
	v_dot8c_i32_i4_e32 v45, v129, v47
	s_waitcnt lgkmcnt(15)
	v_add_u32_e32 v143, 8, v139
	v_and_b32_e32 v142, 15, v143
	v_xor_b32_e32 v142, 8, v142
	v_bfe_u32 v144, v143, 4, 4
	v_mul_lo_u32 v142, v142, s92
	v_mul_lo_u32 v144, v144, s92
	v_mov_b32_e32 v143, v142
	v_mov_b32_e32 v145, v144
	ds_write2st64_b64 v159, v[142:143], v[144:145] offset1:2
	v_and_b32_e32 v78, 0xffff, v20
	v_lshrrev_b32_e32 v79, 16, v20
	v_lshl_add_u32 v78, v78, 7, v150
	v_lshl_add_u32 v79, v79, 7, v151
	s_mov_b32 m0, s78
	s_add_i32 s43, s78, 0x400
	global_load_lds_dwordx4 v78, s[50:51]
	s_mov_b32 m0, s43
	s_nop 0
	global_load_lds_dwordx4 v79, s[50:51]
	s_waitcnt vmcnt(8)
	v_add_u32_e32 v54, s98, v59
	v_add_u32_e32 v55, s98, v60
	v_add_u32_e32 v56, s98, v61
	v_add_u32_e32 v57, s98, v62
	ds_read_b64_tr_b4 v[46:47], v160 offset:768
	ds_read_b64_tr_b4 v[48:49], v160 offset:1792
	ds_read_b64_tr_b4 v[122:123], v54
	ds_read_b64_tr_b4 v[124:125], v55
	ds_read_b64_tr_b4 v[126:127], v56
	ds_read_b64_tr_b4 v[128:129], v57
	s_waitcnt lgkmcnt(7)
	v_dot8c_i32_i4_e32 v38, v130, v52
	v_dot8c_i32_i4_e32 v39, v130, v50
	v_dot8c_i32_i4_e32 v40, v132, v52
	v_dot8c_i32_i4_e32 v41, v132, v50
	v_dot8c_i32_i4_e32 v42, v134, v52
	v_dot8c_i32_i4_e32 v43, v134, v50
	v_dot8c_i32_i4_e32 v44, v136, v52
	v_dot8c_i32_i4_e32 v45, v136, v50
	v_dot8c_i32_i4_e32 v38, v131, v53
	v_dot8c_i32_i4_e32 v39, v131, v51
	v_dot8c_i32_i4_e32 v40, v133, v53
	v_dot8c_i32_i4_e32 v41, v133, v51
	v_dot8c_i32_i4_e32 v42, v135, v53
	v_dot8c_i32_i4_e32 v43, v135, v51
	v_dot8c_i32_i4_e32 v44, v137, v53
	v_dot8c_i32_i4_e32 v45, v137, v51
	v_and_b32_e32 v78, 0xffff, v21
	v_lshrrev_b32_e32 v79, 16, v21
	v_lshl_add_u32 v78, v78, 7, v150
	v_lshl_add_u32 v79, v79, 7, v151
	s_mov_b32 m0, s79
	s_add_i32 s43, s79, 0x400
	global_load_lds_dwordx4 v78, s[50:51]
	s_mov_b32 m0, s43
	s_nop 0
	global_load_lds_dwordx4 v79, s[50:51]
	s_waitcnt vmcnt(8)
	v_add_u32_e32 v54, s99, v59
	v_add_u32_e32 v55, s99, v60
	v_add_u32_e32 v56, s99, v61
	v_add_u32_e32 v57, s99, v62
	ds_read_b64_tr_b4 v[50:51], v160 offset:896
	ds_read_b64_tr_b4 v[52:53], v160 offset:1920
	ds_read_b64_tr_b4 v[130:131], v54
	ds_read_b64_tr_b4 v[132:133], v55
	ds_read_b64_tr_b4 v[134:135], v56
	ds_read_b64_tr_b4 v[136:137], v57
	s_waitcnt lgkmcnt(6)
	v_dot8c_i32_i4_e32 v38, v122, v48
	v_dot8c_i32_i4_e32 v39, v122, v46
	v_dot8c_i32_i4_e32 v40, v124, v48
	v_dot8c_i32_i4_e32 v41, v124, v46
	v_dot8c_i32_i4_e32 v42, v126, v48
	v_dot8c_i32_i4_e32 v43, v126, v46
	v_dot8c_i32_i4_e32 v44, v128, v48
	v_dot8c_i32_i4_e32 v45, v128, v46
	v_dot8c_i32_i4_e32 v38, v123, v49
	v_dot8c_i32_i4_e32 v39, v123, v47
	v_dot8c_i32_i4_e32 v40, v125, v49
	v_dot8c_i32_i4_e32 v41, v125, v47
	v_dot8c_i32_i4_e32 v42, v127, v49
	v_dot8c_i32_i4_e32 v43, v127, v47
	v_dot8c_i32_i4_e32 v44, v129, v49
	v_dot8c_i32_i4_e32 v45, v129, v47
	v_and_b32_e32 v78, 0xffff, v22
	v_lshrrev_b32_e32 v79, 16, v22
	v_lshl_add_u32 v78, v78, 7, v150
	v_lshl_add_u32 v79, v79, 7, v151
	s_mov_b32 m0, s98
	s_add_i32 s43, s98, 0x400
	global_load_lds_dwordx4 v78, s[50:51]
	s_mov_b32 m0, s43
	s_nop 0
	global_load_lds_dwordx4 v79, s[50:51]
	s_waitcnt vmcnt(8)
	v_add_u32_e32 v54, s76, v59
	v_add_u32_e32 v55, s76, v60
	v_add_u32_e32 v56, s76, v61
	v_add_u32_e32 v57, s76, v62
	ds_read_b64_tr_b4 v[46:47], v160
	ds_read_b64_tr_b4 v[48:49], v160 offset:1024
	ds_read_b64_tr_b4 v[122:123], v54
	ds_read_b64_tr_b4 v[124:125], v55
	ds_read_b64_tr_b4 v[126:127], v56
	ds_read_b64_tr_b4 v[128:129], v57
	s_waitcnt lgkmcnt(6)
	v_dot8c_i32_i4_e32 v38, v130, v52
	v_dot8c_i32_i4_e32 v39, v130, v50
	v_dot8c_i32_i4_e32 v40, v132, v52
	v_dot8c_i32_i4_e32 v41, v132, v50
	v_dot8c_i32_i4_e32 v42, v134, v52
	v_dot8c_i32_i4_e32 v43, v134, v50
	v_dot8c_i32_i4_e32 v44, v136, v52
	v_dot8c_i32_i4_e32 v45, v136, v50
	v_dot8c_i32_i4_e32 v38, v131, v53
	v_dot8c_i32_i4_e32 v39, v131, v51
	v_dot8c_i32_i4_e32 v40, v133, v53
	v_dot8c_i32_i4_e32 v41, v133, v51
	v_dot8c_i32_i4_e32 v42, v135, v53
	v_dot8c_i32_i4_e32 v43, v135, v51
	v_dot8c_i32_i4_e32 v44, v137, v53
	v_dot8c_i32_i4_e32 v45, v137, v51
	s_nop 3
	s_waitcnt lgkmcnt(15)
; __device__ __forceinline__ void peer_v_tokens(int j, const LAS unsigned short* EL, const LAS unsigned char* AL  , const LAS float* ASC  , const LAS int* SAL  , ...
;     ...
;         const int tl = it * 8 + wave, t = j * 64 + tl;
;         unsigned E[8];
;         { const LAS v4u* ep = (const LAS v4u*)(EL + tl * 128 + 16 * g); const v4u e0 = ep[0], e1 = ep[1];
;           E[0] = e0.x; E[1] = e0.y; E[2] = e0.z; E[3] = e0.w; E[4] = e1.x; E[5] = e1.y; E[6] = e1.z; E[7] = e1.w; }
;         uint2 hv[4]; float4 gv[4];
;         { unsigned ho = (unsigned)t * (D / 4) + (unsigned)lane; asm volatile("" : "+v"(ho)); const uint2* hp = (const uint2*)HB + ho; const float4* gp = (const float4*)fng + lane;
; #pragma unroll
;           for (int jq = 0; jq < 4; ++jq) { hv[jq] = hp[64 * jq]; gv[jq] = gp[64 * jq]; } }
;         VDMA(0, 0); VDMA(1, 1);
; #pragma unroll
;         for (int m = 0; m < 2; ++m) {
;             const int idx = lane + 64 * m, tau = idx >> 4, sr = idx & 15, k = 16 * (sr & 7) + 2 * tau + (sr >> 3);
;             const int aq = (int)*(const LAS signed char*)(AL + tl * 128 + k); const int tq = aq + 8;
;             const unsigned lo = (((unsigned)tq & 15u) ^ 8u) * 0x11111111u, hi = ((unsigned)(tq >> 4) & 15u) * 0x11111111u;
;             typedef unsigned u2v __attribute__((ext_vector_type(2)));
;             u2v l2; l2.x = lo; l2.y = lo; u2v h2; h2.x = hi; h2.y = hi;
;             *(LAS u2v*)(ATL + 8 * idx) = l2; *(LAS u2v*)(ATL + 1024 + 8 * idx) = h2;
;         }
;         const float asc = ASC[tl]; const int sa = SAL[tl];
;         CFENCE();
;         int accH[4], accL[4];
; #pragma unroll
;         for (int st = 0; st < 16; ++st) {
;             const int p = st >> 2, q = st & 3;
;             if (st < 14) VDMA(st + 2, (st + 2) % 3);
;             if (st < 14) asm volatile("s_waitcnt vmcnt(8)" ::: "memory");
;             else if (st == 14) asm volatile("s_waitcnt vmcnt(4)" ::: "memory");
;             else asm volatile("s_waitcnt vmcnt(0)" ::: "memory");
;             if (q == 0) {
; #pragma unroll
;                 for (int r = 0; r < 4; ++r) { accH[r] = 0; accL[r] = 0; } }
; #pragma unroll
;             for (int tp = 0; tp < 2; ++tp) {
;                 const v2i ao = TR4(ATL + (2 * q + tp) * 128 + 8 * s16), ah = TR4(ATL + 1024 + (2 * q + tp) * 128 + 8 * s16);
; #pragma unroll
;                 for (int r = 0; r < 4; ++r) {
	v_lshlrev_b32_e32 v38, 5, v38
	v_lshlrev_b32_e32 v39, 1, v39
	v_add3_u32 v38, v39, v229, v38
	v_cvt_f32_i32_e32 v38, v38
	v_mul_f32_e32 v38, v228, v38
	v_lshlrev_b32_e32 v40, 5, v40
	v_lshlrev_b32_e32 v41, 1, v41
	v_add3_u32 v40, v41, v229, v40
	v_cvt_f32_i32_e32 v40, v40
	v_mul_f32_e32 v40, v228, v40
	v_lshlrev_b32_e32 v42, 5, v42
	v_lshlrev_b32_e32 v43, 1, v43
	v_add3_u32 v42, v43, v229, v42
	v_cvt_f32_i32_e32 v42, v42
	v_mul_f32_e32 v42, v228, v42
	v_lshlrev_b32_e32 v44, 5, v44
	v_lshlrev_b32_e32 v45, 1, v45
	v_add3_u32 v44, v45, v229, v44
	v_cvt_f32_i32_e32 v44, v44
	v_mul_f32_e32 v44, v228, v44
	v_cvt_pk_bf16_f32 v176, v38, v40
	v_cvt_pk_bf16_f32 v177, v42, v44
	ds_read_b128 v[252:255], v156 offset:1024
	s_add_i32 s44, s40, 24
	s_ashr_i32 s45, s44, 31
	s_lshl_b64 s[44:45], s[44:45], 12
	v_lshl_add_u64 v[80:81], v[36:37], 0, s[44:45]
	s_waitcnt lgkmcnt(0)
	v_mul_f32_e32 v248, v248, v252
	v_mul_f32_e32 v249, v249, v253
	v_mul_f32_e32 v250, v250, v254
	v_mul_f32_e32 v251, v251, v255
	global_store_dwordx4 v[80:81], v[248:251], off offset:3072 nt
	v_add_u32_e32 v147, 8, v140
	v_and_b32_e32 v146, 15, v147
	v_xor_b32_e32 v146, 8, v146
	v_bfe_u32 v148, v147, 4, 4
	v_mul_lo_u32 v146, v146, s92
	v_mul_lo_u32 v148, v148, s92
	v_mov_b32_e32 v147, v146
	v_mov_b32_e32 v149, v148
	ds_write2st64_b64 v77, v[146:147], v[148:149] offset1:2
	v_add_u32_e32 v138, 0x1c00, v74
	ds_read_u8 v139, v138
	v_add_u32_e32 v141, 0x1c00, v73
	ds_read_u8 v140, v141
	s_add_i32 s43, s67, 192
	v_mov_b32_e32 v138, s43
	ds_read2st64_b32 v[228:229], v138 offset1:1
	ds_read_b128 v[26:29], v227 offset:14336
	ds_read_b128 v[30:33], v227 offset:14352
	v_mov_b32_e32 v38, 0
	v_mov_b32_e32 v39, 0
	v_mov_b32_e32 v40, 0
	v_mov_b32_e32 v41, 0
	v_mov_b32_e32 v42, 0
	v_mov_b32_e32 v43, 0
	v_mov_b32_e32 v44, 0
	v_mov_b32_e32 v45, 0
	v_and_b32_e32 v78, 0xffff, v23
	v_lshrrev_b32_e32 v79, 16, v23
	v_lshl_add_u32 v78, v78, 7, v150
	v_lshl_add_u32 v79, v79, 7, v151
	s_mov_b32 m0, s99
	s_add_i32 s43, s99, 0x400
	global_load_lds_dwordx4 v78, s[50:51]
	s_mov_b32 m0, s43
	s_nop 0
	global_load_lds_dwordx4 v79, s[50:51]
	s_waitcnt vmcnt(9)
	v_add_u32_e32 v54, s77, v59
	v_add_u32_e32 v55, s77, v60
	v_add_u32_e32 v56, s77, v61
	v_add_u32_e32 v57, s77, v62
	ds_read_b64_tr_b4 v[50:51], v160 offset:128
	ds_read_b64_tr_b4 v[52:53], v160 offset:1152
	ds_read_b64_tr_b4 v[130:131], v54
	ds_read_b64_tr_b4 v[132:133], v55
	ds_read_b64_tr_b4 v[134:135], v56
	ds_read_b64_tr_b4 v[136:137], v57
	s_waitcnt lgkmcnt(13)
	v_dot8c_i32_i4_e32 v38, v122, v48
	v_dot8c_i32_i4_e32 v39, v122, v46
	v_dot8c_i32_i4_e32 v40, v124, v48
	v_dot8c_i32_i4_e32 v41, v124, v46
	v_dot8c_i32_i4_e32 v42, v126, v48
	v_dot8c_i32_i4_e32 v43, v126, v46
	v_dot8c_i32_i4_e32 v44, v128, v48
	v_dot8c_i32_i4_e32 v45, v128, v46
	v_dot8c_i32_i4_e32 v38, v123, v49
	v_dot8c_i32_i4_e32 v39, v123, v47
	v_dot8c_i32_i4_e32 v40, v125, v49
	v_dot8c_i32_i4_e32 v41, v125, v47
	v_dot8c_i32_i4_e32 v42, v127, v49
	v_dot8c_i32_i4_e32 v43, v127, v47
	v_dot8c_i32_i4_e32 v44, v129, v49
	v_dot8c_i32_i4_e32 v45, v129, v47
	v_and_b32_e32 v78, 0xffff, v24
	v_lshrrev_b32_e32 v79, 16, v24
	v_lshl_add_u32 v78, v78, 7, v150
	v_lshl_add_u32 v79, v79, 7, v151
	s_mov_b32 m0, s76
	s_add_i32 s43, s76, 0x400
	global_load_lds_dwordx4 v78, s[50:51]
	s_mov_b32 m0, s43
	s_nop 0
	global_load_lds_dwordx4 v79, s[50:51]
	s_waitcnt vmcnt(9)
	v_add_u32_e32 v54, s78, v59
	v_add_u32_e32 v55, s78, v60
	v_add_u32_e32 v56, s78, v61
	v_add_u32_e32 v57, s78, v62
	ds_read_b64_tr_b4 v[46:47], v160 offset:256
	ds_read_b64_tr_b4 v[48:49], v160 offset:1280
	ds_read_b64_tr_b4 v[122:123], v54
	ds_read_b64_tr_b4 v[124:125], v55
	ds_read_b64_tr_b4 v[126:127], v56
	ds_read_b64_tr_b4 v[128:129], v57
	s_waitcnt lgkmcnt(6)
	v_dot8c_i32_i4_e32 v38, v130, v52
	v_dot8c_i32_i4_e32 v39, v130, v50
	v_dot8c_i32_i4_e32 v40, v132, v52
	v_dot8c_i32_i4_e32 v41, v132, v50
	v_dot8c_i32_i4_e32 v42, v134, v52
	v_dot8c_i32_i4_e32 v43, v134, v50
	v_dot8c_i32_i4_e32 v44, v136, v52
	v_dot8c_i32_i4_e32 v45, v136, v50
	v_dot8c_i32_i4_e32 v38, v131, v53
	v_dot8c_i32_i4_e32 v39, v131, v51
	v_dot8c_i32_i4_e32 v40, v133, v53
	v_dot8c_i32_i4_e32 v41, v133, v51
	v_dot8c_i32_i4_e32 v42, v135, v53
	v_dot8c_i32_i4_e32 v43, v135, v51
	v_dot8c_i32_i4_e32 v44, v137, v53
	v_dot8c_i32_i4_e32 v45, v137, v51
	ds_write_b16 v65, v162
	ds_write_b16_d16_hi v65, v162 offset:128
	ds_write_b16 v65, v163 offset:256
	ds_write_b16_d16_hi v65, v163 offset:384
	ds_write_b16 v65, v164 offset:512
	ds_write_b16_d16_hi v65, v164 offset:640
	ds_write_b16 v65, v165 offset:768
	ds_write_b16_d16_hi v65, v165 offset:896
	ds_write_b16 v65, v166 offset:1024
	ds_write_b16_d16_hi v65, v166 offset:1152
	ds_write_b16 v65, v167 offset:1280
	ds_write_b16_d16_hi v65, v167 offset:1408
	ds_write_b16 v65, v168 offset:1536
	ds_write_b16_d16_hi v65, v168 offset:1664
	ds_write_b16 v65, v169 offset:1792
	ds_write_b16_d16_hi v65, v169 offset:1920
	ds_read_b64 v[202:203], v154
	ds_read_b64 v[204:205], v154 offset:512
	ds_read_b64 v[206:207], v154 offset:1024
	ds_read_b64 v[208:209], v154 offset:1536
	v_and_b32_e32 v78, 0xffff, v25
	v_lshrrev_b32_e32 v79, 16, v25
	v_lshl_add_u32 v78, v78, 7, v150
	v_lshl_add_u32 v79, v79, 7, v151
	s_mov_b32 m0, s77
	s_add_i32 s43, s77, 0x400
	global_load_lds_dwordx4 v78, s[50:51]
	s_mov_b32 m0, s43
	s_nop 0
	global_load_lds_dwordx4 v79, s[50:51]
	s_waitcnt vmcnt(9)
	v_add_u32_e32 v54, s79, v59
	v_add_u32_e32 v55, s79, v60
	v_add_u32_e32 v56, s79, v61
	v_add_u32_e32 v57, s79, v62
	ds_read_b64_tr_b4 v[50:51], v160 offset:384
	ds_read_b64_tr_b4 v[52:53], v160 offset:1408
	ds_read_b64_tr_b4 v[130:131], v54
	ds_read_b64_tr_b4 v[132:133], v55
	ds_read_b64_tr_b4 v[134:135], v56
	ds_read_b64_tr_b4 v[136:137], v57
	s_waitcnt lgkmcnt(15)
; #define LAS __attribute__((address_space(3)))
; #define TR4(p_) __builtin_amdgcn_ds_read_tr4_b64_v2i32((LAS v2i*)(p_))
; __device__ __forceinline__ void peer_v_tokens(int j, const LAS unsigned short* EL, const LAS unsigned char* AL  , const LAS float* ASC  , const LAS int* SAL  , ...
;     ...
;             const int idx = lane + 64 * m, tau = idx >> 4, sr = idx & 15, k = 16 * (sr & 7) + 2 * tau + (sr >> 3);
;             const int aq = (int)*(const LAS signed char*)(AL + tl * 128 + k); const int tq = aq + 8;
;             const unsigned lo = (((unsigned)tq & 15u) ^ 8u) * 0x11111111u, hi = ((unsigned)(tq >> 4) & 15u) * 0x11111111u;
;             typedef unsigned u2v __attribute__((ext_vector_type(2)));
;             u2v l2; l2.x = lo; l2.y = lo; u2v h2; h2.x = hi; h2.y = hi;
;             *(LAS u2v*)(ATL + 8 * idx) = l2; *(LAS u2v*)(ATL + 1024 + 8 * idx) = h2;
;     ...
;         for (int st = 0; st < 16; ++st) {
;             const int p = st >> 2, q = st & 3;
;             if (st < 14) VDMA(st + 2, (st + 2) % 3);
;             if (st < 14) asm volatile("s_waitcnt vmcnt(8)" ::: "memory");
;             else if (st == 14) asm volatile("s_waitcnt vmcnt(4)" ::: "memory");
;             else asm volatile("s_waitcnt vmcnt(0)" ::: "memory");
;             if (q == 0) {
; #pragma unroll
;                 for (int r = 0; r < 4; ++r) { accH[r] = 0; accL[r] = 0; } }
; #pragma unroll
;             for (int tp = 0; tp < 2; ++tp) {
;                 const v2i ao = TR4(ATL + (2 * q + tp) * 128 + 8 * s16), ah = TR4(ATL + 1024 + (2 * q + tp) * 128 + 8 * s16);
; #pragma unroll
;                 for (int r = 0; r < 4; ++r) {
;                     const v2i d = TR4(ldsb + BUF[st % 3] + 2048 * tp + roff[r]);
;                     accH[r] = __builtin_amdgcn_sdot8(d.x, ah.x, accH[r], false); accH[r] = __builtin_amdgcn_sdot8(d.y, ah.y, accH[r], false);
;                     accL[r] = __builtin_amdgcn_sdot8(d.x, ao.x, accL[r], false); accL[r] = __builtin_amdgcn_sdot8(d.y, ao.y, accL[r], false);
;                 }
;             }
;             asm volatile("s_waitcnt lgkmcnt(0)" ::: "memory");
	v_dot8c_i32_i4_e32 v38, v122, v48
	v_dot8c_i32_i4_e32 v39, v122, v46
	v_dot8c_i32_i4_e32 v40, v124, v48
	v_dot8c_i32_i4_e32 v41, v124, v46
	v_dot8c_i32_i4_e32 v42, v126, v48
	v_dot8c_i32_i4_e32 v43, v126, v46
	v_dot8c_i32_i4_e32 v44, v128, v48
	v_dot8c_i32_i4_e32 v45, v128, v46
	v_dot8c_i32_i4_e32 v38, v123, v49
	v_dot8c_i32_i4_e32 v39, v123, v47
	v_dot8c_i32_i4_e32 v40, v125, v49
	v_dot8c_i32_i4_e32 v41, v125, v47
	v_dot8c_i32_i4_e32 v42, v127, v49
	v_dot8c_i32_i4_e32 v43, v127, v47
	v_dot8c_i32_i4_e32 v44, v129, v49
	v_dot8c_i32_i4_e32 v45, v129, v47
	s_waitcnt lgkmcnt(15)
	v_and_b32_e32 v78, 0xffff, v26
	v_lshrrev_b32_e32 v79, 16, v26
	v_lshl_add_u32 v78, v78, 7, v150
	v_lshl_add_u32 v79, v79, 7, v151
	s_mov_b32 m0, s78
	s_add_i32 s43, s78, 0x400
	global_load_lds_dwordx4 v78, s[50:51]
	s_mov_b32 m0, s43
	s_nop 0
	global_load_lds_dwordx4 v79, s[50:51]
	s_waitcnt vmcnt(9)
	v_add_u32_e32 v54, s98, v59
	v_add_u32_e32 v55, s98, v60
	v_add_u32_e32 v56, s98, v61
	v_add_u32_e32 v57, s98, v62
	ds_read_b64_tr_b4 v[46:47], v160 offset:512
	ds_read_b64_tr_b4 v[48:49], v160 offset:1536
	ds_read_b64_tr_b4 v[122:123], v54
	ds_read_b64_tr_b4 v[124:125], v55
	ds_read_b64_tr_b4 v[126:127], v56
	ds_read_b64_tr_b4 v[128:129], v57
	s_waitcnt lgkmcnt(6)
	v_dot8c_i32_i4_e32 v38, v130, v52
	v_dot8c_i32_i4_e32 v39, v130, v50
	v_dot8c_i32_i4_e32 v40, v132, v52
	v_dot8c_i32_i4_e32 v41, v132, v50
	v_dot8c_i32_i4_e32 v42, v134, v52
	v_dot8c_i32_i4_e32 v43, v134, v50
	v_dot8c_i32_i4_e32 v44, v136, v52
	v_dot8c_i32_i4_e32 v45, v136, v50
	v_dot8c_i32_i4_e32 v38, v131, v53
	v_dot8c_i32_i4_e32 v39, v131, v51
	v_dot8c_i32_i4_e32 v40, v133, v53
	v_dot8c_i32_i4_e32 v41, v133, v51
	v_dot8c_i32_i4_e32 v42, v135, v53
	v_dot8c_i32_i4_e32 v43, v135, v51
	v_dot8c_i32_i4_e32 v44, v137, v53
	v_dot8c_i32_i4_e32 v45, v137, v51
	v_and_b32_e32 v78, 0xffff, v27
	v_lshrrev_b32_e32 v79, 16, v27
	v_lshl_add_u32 v78, v78, 7, v150
	v_lshl_add_u32 v79, v79, 7, v151
	s_mov_b32 m0, s79
	s_add_i32 s43, s79, 0x400
	global_load_lds_dwordx4 v78, s[50:51]
	s_mov_b32 m0, s43
	s_nop 0
	global_load_lds_dwordx4 v79, s[50:51]
	s_waitcnt vmcnt(8)
	v_add_u32_e32 v54, s99, v59
	v_add_u32_e32 v55, s99, v60
	v_add_u32_e32 v56, s99, v61
	v_add_u32_e32 v57, s99, v62
	ds_read_b64_tr_b4 v[50:51], v160 offset:640
	ds_read_b64_tr_b4 v[52:53], v160 offset:1664
	ds_read_b64_tr_b4 v[130:131], v54
	ds_read_b64_tr_b4 v[132:133], v55
	ds_read_b64_tr_b4 v[134:135], v56
	ds_read_b64_tr_b4 v[136:137], v57
	s_waitcnt lgkmcnt(6)
	v_dot8c_i32_i4_e32 v38, v122, v48
	v_dot8c_i32_i4_e32 v39, v122, v46
	v_dot8c_i32_i4_e32 v40, v124, v48
	v_dot8c_i32_i4_e32 v41, v124, v46
	v_dot8c_i32_i4_e32 v42, v126, v48
	v_dot8c_i32_i4_e32 v43, v126, v46
	v_dot8c_i32_i4_e32 v44, v128, v48
	v_dot8c_i32_i4_e32 v45, v128, v46
	v_dot8c_i32_i4_e32 v38, v123, v49
	v_dot8c_i32_i4_e32 v39, v123, v47
	v_dot8c_i32_i4_e32 v40, v125, v49
	v_dot8c_i32_i4_e32 v41, v125, v47
	v_dot8c_i32_i4_e32 v42, v127, v49
	v_dot8c_i32_i4_e32 v43, v127, v47
	v_dot8c_i32_i4_e32 v44, v129, v49
	v_dot8c_i32_i4_e32 v45, v129, v47
	s_waitcnt lgkmcnt(15)
	v_add_u32_e32 v143, 8, v139
	v_and_b32_e32 v142, 15, v143
	v_xor_b32_e32 v142, 8, v142
	v_bfe_u32 v144, v143, 4, 4
	v_mul_lo_u32 v142, v142, s92
	v_mul_lo_u32 v144, v144, s92
	v_mov_b32_e32 v143, v142
	v_mov_b32_e32 v145, v144
	ds_write2st64_b64 v159, v[142:143], v[144:145] offset1:2
	v_and_b32_e32 v78, 0xffff, v28
	v_lshrrev_b32_e32 v79, 16, v28
	v_lshl_add_u32 v78, v78, 7, v150
	v_lshl_add_u32 v79, v79, 7, v151
	s_mov_b32 m0, s98
	s_add_i32 s43, s98, 0x400
	global_load_lds_dwordx4 v78, s[50:51]
	s_mov_b32 m0, s43
	s_nop 0
	global_load_lds_dwordx4 v79, s[50:51]
	s_waitcnt vmcnt(8)
	v_add_u32_e32 v54, s76, v59
	v_add_u32_e32 v55, s76, v60
	v_add_u32_e32 v56, s76, v61
	v_add_u32_e32 v57, s76, v62
	ds_read_b64_tr_b4 v[46:47], v160 offset:768
	ds_read_b64_tr_b4 v[48:49], v160 offset:1792
	ds_read_b64_tr_b4 v[122:123], v54
	ds_read_b64_tr_b4 v[124:125], v55
	ds_read_b64_tr_b4 v[126:127], v56
	ds_read_b64_tr_b4 v[128:129], v57
	s_waitcnt lgkmcnt(7)
	v_dot8c_i32_i4_e32 v38, v130, v52
	v_dot8c_i32_i4_e32 v39, v130, v50
	v_dot8c_i32_i4_e32 v40, v132, v52
	v_dot8c_i32_i4_e32 v41, v132, v50
	v_dot8c_i32_i4_e32 v42, v134, v52
	v_dot8c_i32_i4_e32 v43, v134, v50
	v_dot8c_i32_i4_e32 v44, v136, v52
	v_dot8c_i32_i4_e32 v45, v136, v50
	v_dot8c_i32_i4_e32 v38, v131, v53
	v_dot8c_i32_i4_e32 v39, v131, v51
	v_dot8c_i32_i4_e32 v40, v133, v53
	v_dot8c_i32_i4_e32 v41, v133, v51
	v_dot8c_i32_i4_e32 v42, v135, v53
	v_dot8c_i32_i4_e32 v43, v135, v51
	v_dot8c_i32_i4_e32 v44, v137, v53
	v_dot8c_i32_i4_e32 v45, v137, v51
	v_and_b32_e32 v78, 0xffff, v29
	v_lshrrev_b32_e32 v79, 16, v29
	v_lshl_add_u32 v78, v78, 7, v150
	v_lshl_add_u32 v79, v79, 7, v151
	s_mov_b32 m0, s99
	s_add_i32 s43, s99, 0x400
	global_load_lds_dwordx4 v78, s[50:51]
	s_mov_b32 m0, s43
	s_nop 0
	global_load_lds_dwordx4 v79, s[50:51]
	s_waitcnt vmcnt(8)
	v_add_u32_e32 v54, s77, v59
	v_add_u32_e32 v55, s77, v60
	v_add_u32_e32 v56, s77, v61
	v_add_u32_e32 v57, s77, v62
	ds_read_b64_tr_b4 v[50:51], v160 offset:896
	ds_read_b64_tr_b4 v[52:53], v160 offset:1920
	ds_read_b64_tr_b4 v[130:131], v54
	ds_read_b64_tr_b4 v[132:133], v55
	ds_read_b64_tr_b4 v[134:135], v56
	ds_read_b64_tr_b4 v[136:137], v57
	s_waitcnt lgkmcnt(6)
; __device__ __forceinline__ void peer_v_tokens(int j, const LAS unsigned short* EL, const LAS unsigned char* AL  , const LAS float* ASC  , const LAS int* SAL  , ...
;     ...
;         const int tl = it * 8 + wave, t = j * 64 + tl;
;         unsigned E[8];
;         { const LAS v4u* ep = (const LAS v4u*)(EL + tl * 128 + 16 * g); const v4u e0 = ep[0], e1 = ep[1];
;           E[0] = e0.x; E[1] = e0.y; E[2] = e0.z; E[3] = e0.w; E[4] = e1.x; E[5] = e1.y; E[6] = e1.z; E[7] = e1.w; }
;         uint2 hv[4]; float4 gv[4];
;         { unsigned ho = (unsigned)t * (D / 4) + (unsigned)lane; asm volatile("" : "+v"(ho)); const uint2* hp = (const uint2*)HB + ho; const float4* gp = (const float4*)fng + lane;
; #pragma unroll
;           for (int jq = 0; jq < 4; ++jq) { hv[jq] = hp[64 * jq]; gv[jq] = gp[64 * jq]; } }
;         VDMA(0, 0); VDMA(1, 1);
; #pragma unroll
;         for (int m = 0; m < 2; ++m) {
;             const int idx = lane + 64 * m, tau = idx >> 4, sr = idx & 15, k = 16 * (sr & 7) + 2 * tau + (sr >> 3);
;             const int aq = (int)*(const LAS signed char*)(AL + tl * 128 + k); const int tq = aq + 8;
;             const unsigned lo = (((unsigned)tq & 15u) ^ 8u) * 0x11111111u, hi = ((unsigned)(tq >> 4) & 15u) * 0x11111111u;
;             typedef unsigned u2v __attribute__((ext_vector_type(2)));
;             u2v l2; l2.x = lo; l2.y = lo; u2v h2; h2.x = hi; h2.y = hi;
;             *(LAS u2v*)(ATL + 8 * idx) = l2; *(LAS u2v*)(ATL + 1024 + 8 * idx) = h2;
;         }
;         const float asc = ASC[tl]; const int sa = SAL[tl];
;         CFENCE();
;         int accH[4], accL[4];
; #pragma unroll
;         for (int st = 0; st < 16; ++st) {
;             const int p = st >> 2, q = st & 3;
;             if (st < 14) VDMA(st + 2, (st + 2) % 3);
;             if (st < 14) asm volatile("s_waitcnt vmcnt(8)" ::: "memory");
;             else if (st == 14) asm volatile("s_waitcnt vmcnt(4)" ::: "memory");
;             else asm volatile("s_waitcnt vmcnt(0)" ::: "memory");
;             if (q == 0) {
; #pragma unroll
;                 for (int r = 0; r < 4; ++r) { accH[r] = 0; accL[r] = 0; } }
; #pragma unroll
;             for (int tp = 0; tp < 2; ++tp) {
;                 const v2i ao = TR4(ATL + (2 * q + tp) * 128 + 8 * s16), ah = TR4(ATL + 1024 + (2 * q + tp) * 128 + 8 * s16);
; #pragma unroll
;                 for (int r = 0; r < 4; ++r) {
	v_dot8c_i32_i4_e32 v38, v122, v48
	v_dot8c_i32_i4_e32 v39, v122, v46
	v_dot8c_i32_i4_e32 v40, v124, v48
	v_dot8c_i32_i4_e32 v41, v124, v46
	v_dot8c_i32_i4_e32 v42, v126, v48
	v_dot8c_i32_i4_e32 v43, v126, v46
	v_dot8c_i32_i4_e32 v44, v128, v48
	v_dot8c_i32_i4_e32 v45, v128, v46
	v_dot8c_i32_i4_e32 v38, v123, v49
	v_dot8c_i32_i4_e32 v39, v123, v47
	v_dot8c_i32_i4_e32 v40, v125, v49
	v_dot8c_i32_i4_e32 v41, v125, v47
	v_dot8c_i32_i4_e32 v42, v127, v49
	v_dot8c_i32_i4_e32 v43, v127, v47
	v_dot8c_i32_i4_e32 v44, v129, v49
	v_dot8c_i32_i4_e32 v45, v129, v47
	v_and_b32_e32 v78, 0xffff, v30
	v_lshrrev_b32_e32 v79, 16, v30
	v_lshl_add_u32 v78, v78, 7, v150
	v_lshl_add_u32 v79, v79, 7, v151
	s_mov_b32 m0, s76
	s_add_i32 s43, s76, 0x400
	global_load_lds_dwordx4 v78, s[50:51]
	s_mov_b32 m0, s43
	s_nop 0
	global_load_lds_dwordx4 v79, s[50:51]
	s_waitcnt vmcnt(8)
	v_add_u32_e32 v54, s78, v59
	v_add_u32_e32 v55, s78, v60
	v_add_u32_e32 v56, s78, v61
	v_add_u32_e32 v57, s78, v62
	ds_read_b64_tr_b4 v[46:47], v160
	ds_read_b64_tr_b4 v[48:49], v160 offset:1024
	ds_read_b64_tr_b4 v[122:123], v54
	ds_read_b64_tr_b4 v[124:125], v55
	ds_read_b64_tr_b4 v[126:127], v56
	ds_read_b64_tr_b4 v[128:129], v57
	s_waitcnt lgkmcnt(6)
	v_dot8c_i32_i4_e32 v38, v130, v52
	v_dot8c_i32_i4_e32 v39, v130, v50
	v_dot8c_i32_i4_e32 v40, v132, v52
	v_dot8c_i32_i4_e32 v41, v132, v50
	v_dot8c_i32_i4_e32 v42, v134, v52
	v_dot8c_i32_i4_e32 v43, v134, v50
	v_dot8c_i32_i4_e32 v44, v136, v52
	v_dot8c_i32_i4_e32 v45, v136, v50
	v_dot8c_i32_i4_e32 v38, v131, v53
	v_dot8c_i32_i4_e32 v39, v131, v51
	v_dot8c_i32_i4_e32 v40, v133, v53
	v_dot8c_i32_i4_e32 v41, v133, v51
	v_dot8c_i32_i4_e32 v42, v135, v53
	v_dot8c_i32_i4_e32 v43, v135, v51
	v_dot8c_i32_i4_e32 v44, v137, v53
	v_dot8c_i32_i4_e32 v45, v137, v51
	s_nop 3
	s_waitcnt lgkmcnt(15)
	v_lshlrev_b32_e32 v38, 5, v38
	v_lshlrev_b32_e32 v39, 1, v39
	v_add3_u32 v38, v39, v229, v38
	v_cvt_f32_i32_e32 v38, v38
	v_mul_f32_e32 v38, v228, v38
	v_lshlrev_b32_e32 v40, 5, v40
	v_lshlrev_b32_e32 v41, 1, v41
	v_add3_u32 v40, v41, v229, v40
	v_cvt_f32_i32_e32 v40, v40
	v_mul_f32_e32 v40, v228, v40
	v_lshlrev_b32_e32 v42, 5, v42
	v_lshlrev_b32_e32 v43, 1, v43
	v_add3_u32 v42, v43, v229, v42
	v_cvt_f32_i32_e32 v42, v42
	v_mul_f32_e32 v42, v228, v42
	v_lshlrev_b32_e32 v44, 5, v44
	v_lshlrev_b32_e32 v45, 1, v45
	v_add3_u32 v44, v45, v229, v44
	v_cvt_f32_i32_e32 v44, v44
	v_mul_f32_e32 v44, v228, v44
	v_cvt_pk_bf16_f32 v178, v38, v40
	v_cvt_pk_bf16_f32 v179, v42, v44
	v_add_u32_e32 v147, 8, v140
	v_and_b32_e32 v146, 15, v147
	v_xor_b32_e32 v146, 8, v146
	v_bfe_u32 v148, v147, 4, 4
	v_mul_lo_u32 v146, v146, s92
	v_mul_lo_u32 v148, v148, s92
	v_mov_b32_e32 v147, v146
	v_mov_b32_e32 v149, v148
	ds_write2st64_b64 v77, v[146:147], v[148:149] offset1:2
	v_add_u32_e32 v138, 0x1800, v74
	ds_read_u8 v139, v138
	v_add_u32_e32 v141, 0x1800, v73
	ds_read_u8 v140, v141
	s_add_i32 s43, s67, 224
	v_mov_b32_e32 v138, s43
	ds_read2st64_b32 v[228:229], v138 offset1:1
	ds_read_b128 v[18:21], v227 offset:12288
	ds_read_b128 v[22:25], v227 offset:12304
	v_add_u32_e32 v152, 0x200000, v63
	v_add_u32_e32 v153, 0x200000, v64
	v_mov_b32_e32 v38, 0
	v_mov_b32_e32 v39, 0
	v_mov_b32_e32 v40, 0
	v_mov_b32_e32 v41, 0
	v_mov_b32_e32 v42, 0
	v_mov_b32_e32 v43, 0
	v_mov_b32_e32 v44, 0
	v_mov_b32_e32 v45, 0
	v_and_b32_e32 v78, 0xffff, v31
	v_lshrrev_b32_e32 v79, 16, v31
	v_lshl_add_u32 v78, v78, 7, v150
	v_lshl_add_u32 v79, v79, 7, v151
	s_mov_b32 m0, s77
	s_add_i32 s43, s77, 0x400
	global_load_lds_dwordx4 v78, s[50:51]
	s_mov_b32 m0, s43
	s_nop 0
	global_load_lds_dwordx4 v79, s[50:51]
	s_waitcnt vmcnt(8)
	v_add_u32_e32 v54, s79, v59
	v_add_u32_e32 v55, s79, v60
	v_add_u32_e32 v56, s79, v61
	v_add_u32_e32 v57, s79, v62
	ds_read_b64_tr_b4 v[50:51], v160 offset:128
	ds_read_b64_tr_b4 v[52:53], v160 offset:1152
	ds_read_b64_tr_b4 v[130:131], v54
	ds_read_b64_tr_b4 v[132:133], v55
	ds_read_b64_tr_b4 v[134:135], v56
	ds_read_b64_tr_b4 v[136:137], v57
	s_waitcnt lgkmcnt(12)
	s_waitcnt vmcnt(35) lgkmcnt(15)
	v_lshlrev_b32_e32 v210, 16, v194
	v_and_b32_e32 v211, 0xffff0000, v194
	v_lshlrev_b32_e32 v142, 16, v202
	v_and_b32_e32 v143, 0xffff0000, v202
	v_add_f32_e32 v210, v210, v142
	v_add_f32_e32 v211, v211, v143
	v_lshlrev_b32_e32 v212, 16, v195
	v_and_b32_e32 v213, 0xffff0000, v195
	v_lshlrev_b32_e32 v142, 16, v203
	v_and_b32_e32 v143, 0xffff0000, v203
	v_add_f32_e32 v212, v212, v142
	v_add_f32_e32 v213, v213, v143
	v_lshlrev_b32_e32 v214, 16, v196
	v_and_b32_e32 v215, 0xffff0000, v196
	v_lshlrev_b32_e32 v142, 16, v204
	v_and_b32_e32 v143, 0xffff0000, v204
	v_add_f32_e32 v214, v214, v142
	v_add_f32_e32 v215, v215, v143
	v_lshlrev_b32_e32 v216, 16, v197
	v_and_b32_e32 v217, 0xffff0000, v197
	v_lshlrev_b32_e32 v142, 16, v205
	v_and_b32_e32 v143, 0xffff0000, v205
	v_add_f32_e32 v216, v216, v142
	v_add_f32_e32 v217, v217, v143
	v_lshlrev_b32_e32 v218, 16, v198
	v_and_b32_e32 v219, 0xffff0000, v198
	v_lshlrev_b32_e32 v142, 16, v206
	v_and_b32_e32 v143, 0xffff0000, v206
	v_add_f32_e32 v218, v218, v142
	v_add_f32_e32 v219, v219, v143
	v_lshlrev_b32_e32 v220, 16, v199
	v_and_b32_e32 v221, 0xffff0000, v199
	v_lshlrev_b32_e32 v142, 16, v207
	v_and_b32_e32 v143, 0xffff0000, v207
	v_add_f32_e32 v220, v220, v142
	v_add_f32_e32 v221, v221, v143
	v_lshlrev_b32_e32 v222, 16, v200
	v_and_b32_e32 v223, 0xffff0000, v200
	v_lshlrev_b32_e32 v142, 16, v208
	v_and_b32_e32 v143, 0xffff0000, v208
	v_add_f32_e32 v222, v222, v142
	v_add_f32_e32 v223, v223, v143
	v_lshlrev_b32_e32 v224, 16, v201
	v_and_b32_e32 v225, 0xffff0000, v201
	v_lshlrev_b32_e32 v142, 16, v209
	v_and_b32_e32 v143, 0xffff0000, v209
	v_add_f32_e32 v224, v224, v142
; #define LAS __attribute__((address_space(3)))
; #define TR4(p_) __builtin_amdgcn_ds_read_tr4_b64_v2i32((LAS v2i*)(p_))
; __device__ __forceinline__ void peer_v_tokens(int j, const LAS unsigned short* EL, const LAS unsigned char* AL  , const LAS float* ASC  , const LAS int* SAL  , ...
;     ...
;         for (int st = 0; st < 16; ++st) {
;             const int p = st >> 2, q = st & 3;
;             if (st < 14) VDMA(st + 2, (st + 2) % 3);
;             if (st < 14) asm volatile("s_waitcnt vmcnt(8)" ::: "memory");
;             else if (st == 14) asm volatile("s_waitcnt vmcnt(4)" ::: "memory");
;             else asm volatile("s_waitcnt vmcnt(0)" ::: "memory");
;             if (q == 0) {
; #pragma unroll
;                 for (int r = 0; r < 4; ++r) { accH[r] = 0; accL[r] = 0; } }
; #pragma unroll
;             for (int tp = 0; tp < 2; ++tp) {
;                 const v2i ao = TR4(ATL + (2 * q + tp) * 128 + 8 * s16), ah = TR4(ATL + 1024 + (2 * q + tp) * 128 + 8 * s16);
; #pragma unroll
;                 for (int r = 0; r < 4; ++r) {
;                     const v2i d = TR4(ldsb + BUF[st % 3] + 2048 * tp + roff[r]);
;                     accH[r] = __builtin_amdgcn_sdot8(d.x, ah.x, accH[r], false); accH[r] = __builtin_amdgcn_sdot8(d.y, ah.y, accH[r], false);
;                     accL[r] = __builtin_amdgcn_sdot8(d.x, ao.x, accL[r], false); accL[r] = __builtin_amdgcn_sdot8(d.y, ao.y, accL[r], false);
;                 }
;             }
;             asm volatile("s_waitcnt lgkmcnt(0)" ::: "memory");
;     ...
;             float4 v[4]; float ss = 0.f;
; #pragma unroll
;             for (int jq = 0; jq < 4; ++jq) { typedef unsigned u2v __attribute__((ext_vector_type(2))); const u2v pw = *(const LAS u2v*)(STASH + 4 * lane + 256 * jq); const uint2 hw = hv[jq];
;                 v[jq] = make_float4(__uint_as_float(hw.x << 16) + __uint_as_float(pw.x << 16), __uint_as_float(hw.x & 0xffff0000u) + __uint_as_float(pw.x & 0xffff0000u),
;                                     __uint_as_float(hw.y << 16) + __uint_as_float(pw.y << 16), __uint_as_float(hw.y & 0xffff0000u) + __uint_as_float(pw.y & 0xffff0000u));
;                 ss += v[jq].x * v[jq].x + v[jq].y * v[jq].y + v[jq].z * v[jq].z + v[jq].w * v[jq].w; }
;             ss = wave_sum(ss);
;             const float r3 = rsqrtf(ss * (1.f / D) + EPS);
	v_add_f32_e32 v225, v225, v143
	v_mov_b32_e32 v144, 0
	v_mul_f32_e32 v145, v210, v210
	v_fmac_f32_e32 v145, v211, v211
	v_fmac_f32_e32 v145, v212, v212
	v_fmac_f32_e32 v145, v213, v213
	v_add_f32_e32 v144, v144, v145
	v_mul_f32_e32 v145, v214, v214
	v_fmac_f32_e32 v145, v215, v215
	v_fmac_f32_e32 v145, v216, v216
	v_fmac_f32_e32 v145, v217, v217
	v_add_f32_e32 v144, v144, v145
	v_mul_f32_e32 v145, v218, v218
	v_fmac_f32_e32 v145, v219, v219
	v_fmac_f32_e32 v145, v220, v220
	v_fmac_f32_e32 v145, v221, v221
	v_add_f32_e32 v144, v144, v145
	v_mul_f32_e32 v145, v222, v222
	v_fmac_f32_e32 v145, v223, v223
	v_fmac_f32_e32 v145, v224, v224
	v_fmac_f32_e32 v145, v225, v225
	v_add_f32_e32 v144, v144, v145
	s_nop 1
	v_add_f32_dpp v144, v144, v144 quad_perm:[1,0,3,2] row_mask:0xf bank_mask:0xf bound_ctrl:1
	s_nop 1
	v_add_f32_dpp v144, v144, v144 quad_perm:[2,3,0,1] row_mask:0xf bank_mask:0xf bound_ctrl:1
	s_nop 1
	v_add_f32_dpp v144, v144, v144 row_half_mirror row_mask:0xf bank_mask:0xf bound_ctrl:1
	s_nop 1
	v_add_f32_dpp v144, v144, v144 row_mirror row_mask:0xf bank_mask:0xf bound_ctrl:1
	s_nop 1
	v_readlane_b32 s10, v144, 0
	v_readlane_b32 s11, v144, 16
	v_readlane_b32 s14, v144, 32
	v_readlane_b32 s15, v144, 48
	s_nop 3
	v_mov_b32_e32 v144, s11
	v_mov_b32_e32 v145, s15
	v_add_f32_e32 v144, s10, v144
	v_add_f32_e32 v145, s14, v145
	v_add_f32_e32 v144, v144, v145
	v_fmamk_f32 v144, v144, 0x3a800000, v111
	v_rsq_f32_e32 v144, v144
	s_nop 0
	v_mul_f32_e32 v210, v210, v144
	v_mul_f32_e32 v211, v211, v144
	v_mul_f32_e32 v212, v212, v144
	v_mul_f32_e32 v213, v213, v144
	v_mul_f32_e32 v214, v214, v144
	v_mul_f32_e32 v215, v215, v144
	v_mul_f32_e32 v216, v216, v144
	v_mul_f32_e32 v217, v217, v144
	v_mul_f32_e32 v218, v218, v144
	v_mul_f32_e32 v219, v219, v144
	v_mul_f32_e32 v220, v220, v144
	v_mul_f32_e32 v221, v221, v144
	v_mul_f32_e32 v222, v222, v144
	v_mul_f32_e32 v223, v223, v144
	v_mul_f32_e32 v224, v224, v144
	v_mul_f32_e32 v225, v225, v144
	v_dot8c_i32_i4_e32 v38, v122, v48
	v_dot8c_i32_i4_e32 v39, v122, v46
	v_dot8c_i32_i4_e32 v40, v124, v48
	v_dot8c_i32_i4_e32 v41, v124, v46
	v_dot8c_i32_i4_e32 v42, v126, v48
	v_dot8c_i32_i4_e32 v43, v126, v46
	v_dot8c_i32_i4_e32 v44, v128, v48
	v_dot8c_i32_i4_e32 v45, v128, v46
	v_dot8c_i32_i4_e32 v38, v123, v49
	v_dot8c_i32_i4_e32 v39, v123, v47
	v_dot8c_i32_i4_e32 v40, v125, v49
	v_dot8c_i32_i4_e32 v41, v125, v47
	v_dot8c_i32_i4_e32 v42, v127, v49
	v_dot8c_i32_i4_e32 v43, v127, v47
	v_dot8c_i32_i4_e32 v44, v129, v49
	v_dot8c_i32_i4_e32 v45, v129, v47
	v_and_b32_e32 v78, 0xffff, v32
	v_lshrrev_b32_e32 v79, 16, v32
	v_lshl_add_u32 v78, v78, 7, v150
	v_lshl_add_u32 v79, v79, 7, v151
	s_mov_b32 m0, s78
	s_add_i32 s43, s78, 0x400
	global_load_lds_dwordx4 v78, s[50:51]
	s_mov_b32 m0, s43
	s_nop 0
	global_load_lds_dwordx4 v79, s[50:51]
	s_waitcnt vmcnt(8)
	v_add_u32_e32 v54, s98, v59
	v_add_u32_e32 v55, s98, v60
	v_add_u32_e32 v56, s98, v61
	v_add_u32_e32 v57, s98, v62
	ds_read_b64_tr_b4 v[46:47], v160 offset:256
	ds_read_b64_tr_b4 v[48:49], v160 offset:1280
	ds_read_b64_tr_b4 v[122:123], v54
	ds_read_b64_tr_b4 v[124:125], v55
	ds_read_b64_tr_b4 v[126:127], v56
	ds_read_b64_tr_b4 v[128:129], v57
	s_waitcnt lgkmcnt(6)
	v_dot8c_i32_i4_e32 v38, v130, v52
	v_dot8c_i32_i4_e32 v39, v130, v50
	v_dot8c_i32_i4_e32 v40, v132, v52
	v_dot8c_i32_i4_e32 v41, v132, v50
	v_dot8c_i32_i4_e32 v42, v134, v52
	v_dot8c_i32_i4_e32 v43, v134, v50
	v_dot8c_i32_i4_e32 v44, v136, v52
	v_dot8c_i32_i4_e32 v45, v136, v50
	v_dot8c_i32_i4_e32 v38, v131, v53
	v_dot8c_i32_i4_e32 v39, v131, v51
	v_dot8c_i32_i4_e32 v40, v133, v53
	v_dot8c_i32_i4_e32 v41, v133, v51
	v_dot8c_i32_i4_e32 v42, v135, v53
	v_dot8c_i32_i4_e32 v43, v135, v51
	v_dot8c_i32_i4_e32 v44, v137, v53
	v_dot8c_i32_i4_e32 v45, v137, v51
	v_and_b32_e32 v78, 0xffff, v33
	v_lshrrev_b32_e32 v79, 16, v33
	v_lshl_add_u32 v78, v78, 7, v150
	v_lshl_add_u32 v79, v79, 7, v151
	s_mov_b32 m0, s79
	s_add_i32 s43, s79, 0x400
	global_load_lds_dwordx4 v78, s[50:51]
	s_mov_b32 m0, s43
	s_nop 0
	global_load_lds_dwordx4 v79, s[50:51]
	s_waitcnt vmcnt(8)
	v_add_u32_e32 v54, s99, v59
	v_add_u32_e32 v55, s99, v60
	v_add_u32_e32 v56, s99, v61
	v_add_u32_e32 v57, s99, v62
	ds_read_b64_tr_b4 v[50:51], v160 offset:384
	ds_read_b64_tr_b4 v[52:53], v160 offset:1408
	ds_read_b64_tr_b4 v[130:131], v54
	ds_read_b64_tr_b4 v[132:133], v55
	ds_read_b64_tr_b4 v[134:135], v56
	ds_read_b64_tr_b4 v[136:137], v57
	s_waitcnt lgkmcnt(6)
	v_dot8c_i32_i4_e32 v38, v122, v48
	v_dot8c_i32_i4_e32 v39, v122, v46
	v_dot8c_i32_i4_e32 v40, v124, v48
	v_dot8c_i32_i4_e32 v41, v124, v46
	v_dot8c_i32_i4_e32 v42, v126, v48
	v_dot8c_i32_i4_e32 v43, v126, v46
	v_dot8c_i32_i4_e32 v44, v128, v48
	v_dot8c_i32_i4_e32 v45, v128, v46
	v_dot8c_i32_i4_e32 v38, v123, v49
	v_dot8c_i32_i4_e32 v39, v123, v47
	v_dot8c_i32_i4_e32 v40, v125, v49
	v_dot8c_i32_i4_e32 v41, v125, v47
	v_dot8c_i32_i4_e32 v42, v127, v49
	v_dot8c_i32_i4_e32 v43, v127, v47
	v_dot8c_i32_i4_e32 v44, v129, v49
	v_dot8c_i32_i4_e32 v45, v129, v47
	s_waitcnt lgkmcnt(15)
	v_and_b32_e32 v78, 0xffff, v18
	v_lshrrev_b32_e32 v79, 16, v18
	v_lshl_add_u32 v78, v78, 7, v152
	v_lshl_add_u32 v79, v79, 7, v153
	s_mov_b32 m0, s98
	s_add_i32 s43, s98, 0x400
	global_load_lds_dwordx4 v78, s[50:51]
	s_mov_b32 m0, s43
	s_nop 0
	global_load_lds_dwordx4 v79, s[50:51]
	s_waitcnt vmcnt(8)
	v_add_u32_e32 v54, s76, v59
	v_add_u32_e32 v55, s76, v60
	v_add_u32_e32 v56, s76, v61
	v_add_u32_e32 v57, s76, v62
	ds_read_b64_tr_b4 v[46:47], v160 offset:512
	ds_read_b64_tr_b4 v[48:49], v160 offset:1536
	ds_read_b64_tr_b4 v[122:123], v54
	ds_read_b64_tr_b4 v[124:125], v55
	ds_read_b64_tr_b4 v[126:127], v56
	ds_read_b64_tr_b4 v[128:129], v57
	s_waitcnt lgkmcnt(6)
; #define LAS __attribute__((address_space(3)))
; __device__ __forceinline__ bf16 f2bf(float f) { return (bf16)f2bfu(f); }
; #define TR4(p_) __builtin_amdgcn_ds_read_tr4_b64_v2i32((LAS v2i*)(p_))
; __device__ __forceinline__ void peer_v_tokens(int j, const LAS unsigned short* EL, const LAS unsigned char* AL  , const LAS float* ASC  , const LAS int* SAL  , ...
;     ...
;             const int idx = lane + 64 * m, tau = idx >> 4, sr = idx & 15, k = 16 * (sr & 7) + 2 * tau + (sr >> 3);
;             const int aq = (int)*(const LAS signed char*)(AL + tl * 128 + k); const int tq = aq + 8;
;             const unsigned lo = (((unsigned)tq & 15u) ^ 8u) * 0x11111111u, hi = ((unsigned)(tq >> 4) & 15u) * 0x11111111u;
;             typedef unsigned u2v __attribute__((ext_vector_type(2)));
;             u2v l2; l2.x = lo; l2.y = lo; u2v h2; h2.x = hi; h2.y = hi;
;             *(LAS u2v*)(ATL + 8 * idx) = l2; *(LAS u2v*)(ATL + 1024 + 8 * idx) = h2;
;     ...
;         for (int st = 0; st < 16; ++st) {
;             const int p = st >> 2, q = st & 3;
;             if (st < 14) VDMA(st + 2, (st + 2) % 3);
;             if (st < 14) asm volatile("s_waitcnt vmcnt(8)" ::: "memory");
;             else if (st == 14) asm volatile("s_waitcnt vmcnt(4)" ::: "memory");
;             else asm volatile("s_waitcnt vmcnt(0)" ::: "memory");
;             if (q == 0) {
; #pragma unroll
;                 for (int r = 0; r < 4; ++r) { accH[r] = 0; accL[r] = 0; } }
; #pragma unroll
;             for (int tp = 0; tp < 2; ++tp) {
;                 const v2i ao = TR4(ATL + (2 * q + tp) * 128 + 8 * s16), ah = TR4(ATL + 1024 + (2 * q + tp) * 128 + 8 * s16);
; #pragma unroll
;                 for (int r = 0; r < 4; ++r) {
;                     const v2i d = TR4(ldsb + BUF[st % 3] + 2048 * tp + roff[r]);
;                     accH[r] = __builtin_amdgcn_sdot8(d.x, ah.x, accH[r], false); accH[r] = __builtin_amdgcn_sdot8(d.y, ah.y, accH[r], false);
;                     accL[r] = __builtin_amdgcn_sdot8(d.x, ao.x, accL[r], false); accL[r] = __builtin_amdgcn_sdot8(d.y, ao.y, accL[r], false);
;                 }
;             }
;             asm volatile("s_waitcnt lgkmcnt(0)" ::: "memory");
;             if (q == 3) {
; #pragma unroll
;                 for (int r = 0; r < 4; ++r) STASH[256 * p + 16 * (grp + 4 * r) + pc] = f2bf(asc * (float)(2 * ((accH[r] << 4) + accL[r]) + sa));
	v_dot8c_i32_i4_e32 v38, v130, v52
	v_dot8c_i32_i4_e32 v39, v130, v50
	v_dot8c_i32_i4_e32 v40, v132, v52
	v_dot8c_i32_i4_e32 v41, v132, v50
	v_dot8c_i32_i4_e32 v42, v134, v52
	v_dot8c_i32_i4_e32 v43, v134, v50
	v_dot8c_i32_i4_e32 v44, v136, v52
	v_dot8c_i32_i4_e32 v45, v136, v50
	v_dot8c_i32_i4_e32 v38, v131, v53
	v_dot8c_i32_i4_e32 v39, v131, v51
	v_dot8c_i32_i4_e32 v40, v133, v53
	v_dot8c_i32_i4_e32 v41, v133, v51
	v_dot8c_i32_i4_e32 v42, v135, v53
	v_dot8c_i32_i4_e32 v43, v135, v51
	v_dot8c_i32_i4_e32 v44, v137, v53
	v_dot8c_i32_i4_e32 v45, v137, v51
	v_and_b32_e32 v78, 0xffff, v19
	v_lshrrev_b32_e32 v79, 16, v19
	v_lshl_add_u32 v78, v78, 7, v152
	v_lshl_add_u32 v79, v79, 7, v153
	s_mov_b32 m0, s99
	s_add_i32 s43, s99, 0x400
	global_load_lds_dwordx4 v78, s[50:51]
	s_mov_b32 m0, s43
	s_nop 0
	global_load_lds_dwordx4 v79, s[50:51]
	s_waitcnt vmcnt(8)
	v_add_u32_e32 v54, s77, v59
	v_add_u32_e32 v55, s77, v60
	v_add_u32_e32 v56, s77, v61
	v_add_u32_e32 v57, s77, v62
	ds_read_b64_tr_b4 v[50:51], v160 offset:640
	ds_read_b64_tr_b4 v[52:53], v160 offset:1664
	ds_read_b64_tr_b4 v[130:131], v54
	ds_read_b64_tr_b4 v[132:133], v55
	ds_read_b64_tr_b4 v[134:135], v56
	ds_read_b64_tr_b4 v[136:137], v57
	s_waitcnt lgkmcnt(6)
	v_dot8c_i32_i4_e32 v38, v122, v48
	v_dot8c_i32_i4_e32 v39, v122, v46
	v_dot8c_i32_i4_e32 v40, v124, v48
	v_dot8c_i32_i4_e32 v41, v124, v46
	v_dot8c_i32_i4_e32 v42, v126, v48
	v_dot8c_i32_i4_e32 v43, v126, v46
	v_dot8c_i32_i4_e32 v44, v128, v48
	v_dot8c_i32_i4_e32 v45, v128, v46
	v_dot8c_i32_i4_e32 v38, v123, v49
	v_dot8c_i32_i4_e32 v39, v123, v47
	v_dot8c_i32_i4_e32 v40, v125, v49
	v_dot8c_i32_i4_e32 v41, v125, v47
	v_dot8c_i32_i4_e32 v42, v127, v49
	v_dot8c_i32_i4_e32 v43, v127, v47
	v_dot8c_i32_i4_e32 v44, v129, v49
	v_dot8c_i32_i4_e32 v45, v129, v47
	s_waitcnt lgkmcnt(15)
	v_add_u32_e32 v143, 8, v139
	v_and_b32_e32 v142, 15, v143
	v_xor_b32_e32 v142, 8, v142
	v_bfe_u32 v144, v143, 4, 4
	v_mul_lo_u32 v142, v142, s92
	v_mul_lo_u32 v144, v144, s92
	v_mov_b32_e32 v143, v142
	v_mov_b32_e32 v145, v144
	ds_write2st64_b64 v159, v[142:143], v[144:145] offset1:2
	v_and_b32_e32 v78, 0xffff, v20
	v_lshrrev_b32_e32 v79, 16, v20
	v_lshl_add_u32 v78, v78, 7, v152
	v_lshl_add_u32 v79, v79, 7, v153
	s_mov_b32 m0, s76
	s_add_i32 s43, s76, 0x400
	global_load_lds_dwordx4 v78, s[50:51]
	s_mov_b32 m0, s43
	s_nop 0
	global_load_lds_dwordx4 v79, s[50:51]
	s_waitcnt vmcnt(8)
	v_add_u32_e32 v54, s78, v59
	v_add_u32_e32 v55, s78, v60
	v_add_u32_e32 v56, s78, v61
	v_add_u32_e32 v57, s78, v62
	ds_read_b64_tr_b4 v[46:47], v160 offset:768
	ds_read_b64_tr_b4 v[48:49], v160 offset:1792
	ds_read_b64_tr_b4 v[122:123], v54
	ds_read_b64_tr_b4 v[124:125], v55
	ds_read_b64_tr_b4 v[126:127], v56
	ds_read_b64_tr_b4 v[128:129], v57
	s_waitcnt lgkmcnt(7)
	v_dot8c_i32_i4_e32 v38, v130, v52
	v_dot8c_i32_i4_e32 v39, v130, v50
	v_dot8c_i32_i4_e32 v40, v132, v52
	v_dot8c_i32_i4_e32 v41, v132, v50
	v_dot8c_i32_i4_e32 v42, v134, v52
	v_dot8c_i32_i4_e32 v43, v134, v50
	v_dot8c_i32_i4_e32 v44, v136, v52
	v_dot8c_i32_i4_e32 v45, v136, v50
	v_dot8c_i32_i4_e32 v38, v131, v53
	v_dot8c_i32_i4_e32 v39, v131, v51
	v_dot8c_i32_i4_e32 v40, v133, v53
	v_dot8c_i32_i4_e32 v41, v133, v51
	v_dot8c_i32_i4_e32 v42, v135, v53
	v_dot8c_i32_i4_e32 v43, v135, v51
	v_dot8c_i32_i4_e32 v44, v137, v53
	v_dot8c_i32_i4_e32 v45, v137, v51
	v_and_b32_e32 v78, 0xffff, v21
	v_lshrrev_b32_e32 v79, 16, v21
	v_lshl_add_u32 v78, v78, 7, v152
	v_lshl_add_u32 v79, v79, 7, v153
	s_mov_b32 m0, s77
	s_add_i32 s43, s77, 0x400
	global_load_lds_dwordx4 v78, s[50:51]
	s_mov_b32 m0, s43
	s_nop 0
	global_load_lds_dwordx4 v79, s[50:51]
	s_waitcnt vmcnt(8)
	v_add_u32_e32 v54, s79, v59
	v_add_u32_e32 v55, s79, v60
	v_add_u32_e32 v56, s79, v61
	v_add_u32_e32 v57, s79, v62
	ds_read_b64_tr_b4 v[50:51], v160 offset:896
	ds_read_b64_tr_b4 v[52:53], v160 offset:1920
	ds_read_b64_tr_b4 v[130:131], v54
	ds_read_b64_tr_b4 v[132:133], v55
	ds_read_b64_tr_b4 v[134:135], v56
	ds_read_b64_tr_b4 v[136:137], v57
	s_waitcnt lgkmcnt(6)
	v_dot8c_i32_i4_e32 v38, v122, v48
	v_dot8c_i32_i4_e32 v39, v122, v46
	v_dot8c_i32_i4_e32 v40, v124, v48
	v_dot8c_i32_i4_e32 v41, v124, v46
	v_dot8c_i32_i4_e32 v42, v126, v48
	v_dot8c_i32_i4_e32 v43, v126, v46
	v_dot8c_i32_i4_e32 v44, v128, v48
	v_dot8c_i32_i4_e32 v45, v128, v46
	v_dot8c_i32_i4_e32 v38, v123, v49
	v_dot8c_i32_i4_e32 v39, v123, v47
	v_dot8c_i32_i4_e32 v40, v125, v49
	v_dot8c_i32_i4_e32 v41, v125, v47
	v_dot8c_i32_i4_e32 v42, v127, v49
	v_dot8c_i32_i4_e32 v43, v127, v47
	v_dot8c_i32_i4_e32 v44, v129, v49
	v_dot8c_i32_i4_e32 v45, v129, v47
	v_and_b32_e32 v78, 0xffff, v22
	v_lshrrev_b32_e32 v79, 16, v22
	v_lshl_add_u32 v78, v78, 7, v152
	v_lshl_add_u32 v79, v79, 7, v153
	s_mov_b32 m0, s78
	s_add_i32 s43, s78, 0x400
	global_load_lds_dwordx4 v78, s[50:51]
	s_mov_b32 m0, s43
	s_nop 0
	global_load_lds_dwordx4 v79, s[50:51]
	s_waitcnt vmcnt(8)
	v_add_u32_e32 v54, s98, v59
	v_add_u32_e32 v55, s98, v60
	v_add_u32_e32 v56, s98, v61
	v_add_u32_e32 v57, s98, v62
	ds_read_b64_tr_b4 v[46:47], v160
	ds_read_b64_tr_b4 v[48:49], v160 offset:1024
	ds_read_b64_tr_b4 v[122:123], v54
	ds_read_b64_tr_b4 v[124:125], v55
	ds_read_b64_tr_b4 v[126:127], v56
	ds_read_b64_tr_b4 v[128:129], v57
	s_waitcnt lgkmcnt(6)
	v_dot8c_i32_i4_e32 v38, v130, v52
	v_dot8c_i32_i4_e32 v39, v130, v50
	v_dot8c_i32_i4_e32 v40, v132, v52
	v_dot8c_i32_i4_e32 v41, v132, v50
	v_dot8c_i32_i4_e32 v42, v134, v52
	v_dot8c_i32_i4_e32 v43, v134, v50
	v_dot8c_i32_i4_e32 v44, v136, v52
	v_dot8c_i32_i4_e32 v45, v136, v50
	v_dot8c_i32_i4_e32 v38, v131, v53
	v_dot8c_i32_i4_e32 v39, v131, v51
	v_dot8c_i32_i4_e32 v40, v133, v53
	v_dot8c_i32_i4_e32 v41, v133, v51
	v_dot8c_i32_i4_e32 v42, v135, v53
	v_dot8c_i32_i4_e32 v43, v135, v51
	v_dot8c_i32_i4_e32 v44, v137, v53
	v_dot8c_i32_i4_e32 v45, v137, v51
	s_nop 3
	s_waitcnt lgkmcnt(15)
; #define LAS __attribute__((address_space(3)))
; #define CFENCE() asm volatile("" ::: "memory")
; __device__ __forceinline__ void peer_v_tokens(int j, const LAS unsigned short* EL, const LAS unsigned char* AL  , const LAS float* ASC  , const LAS int* SAL  , ...
;     ...
;         const int tl = it * 8 + wave, t = j * 64 + tl;
;         unsigned E[8];
;         { const LAS v4u* ep = (const LAS v4u*)(EL + tl * 128 + 16 * g); const v4u e0 = ep[0], e1 = ep[1];
;           E[0] = e0.x; E[1] = e0.y; E[2] = e0.z; E[3] = e0.w; E[4] = e1.x; E[5] = e1.y; E[6] = e1.z; E[7] = e1.w; }
;         uint2 hv[4]; float4 gv[4];
;         { unsigned ho = (unsigned)t * (D / 4) + (unsigned)lane; asm volatile("" : "+v"(ho)); const uint2* hp = (const uint2*)HB + ho; const float4* gp = (const float4*)fng + lane;
; #pragma unroll
;           for (int jq = 0; jq < 4; ++jq) { hv[jq] = hp[64 * jq]; gv[jq] = gp[64 * jq]; } }
;         VDMA(0, 0); VDMA(1, 1);
; #pragma unroll
;         for (int m = 0; m < 2; ++m) {
;     ...
;                 for (int r = 0; r < 4; ++r) STASH[256 * p + 16 * (grp + 4 * r) + pc] = f2bf(asc * (float)(2 * ((accH[r] << 4) + accL[r]) + sa));
;             }
;         }
;         CFENCE();
;         {
;             float4 v[4]; float ss = 0.f;
; #pragma unroll
;             for (int jq = 0; jq < 4; ++jq) { typedef unsigned u2v __attribute__((ext_vector_type(2))); const u2v pw = *(const LAS u2v*)(STASH + 4 * lane + 256 * jq); const uint2 hw = hv[jq];
;                 v[jq] = make_float4(__uint_as_float(hw.x << 16) + __uint_as_float(pw.x << 16), __uint_as_float(hw.x & 0xffff0000u) + __uint_as_float(pw.x & 0xffff0000u),
;                                     __uint_as_float(hw.y << 16) + __uint_as_float(pw.y << 16), __uint_as_float(hw.y & 0xffff0000u) + __uint_as_float(pw.y & 0xffff0000u));
;                 ss += v[jq].x * v[jq].x + v[jq].y * v[jq].y + v[jq].z * v[jq].z + v[jq].w * v[jq].w; }
;             ss = wave_sum(ss);
;             const float r3 = rsqrtf(ss * (1.f / D) + EPS);
;             float4* op = (float4*)(outp + (size_t)t * D) + lane;
; #pragma unroll
;             for (int jq = 0; jq < 4; ++jq) { typedef float f4v __attribute__((ext_vector_type(4))); f4v o4; o4.x = v[jq].x * r3 * gv[jq].x; o4.y = v[jq].y * r3 * gv[jq].y; o4.z = v[jq].z * r3 * gv[jq].z; o4.w = v[jq].w * r3 * gv[jq].w;
;                 __builtin_nontemporal_store(o4, (f4v*)op + 64 * jq); }
	v_lshlrev_b32_e32 v38, 5, v38
	v_lshlrev_b32_e32 v39, 1, v39
	v_add3_u32 v38, v39, v229, v38
	v_cvt_f32_i32_e32 v38, v38
	v_mul_f32_e32 v38, v228, v38
	v_lshlrev_b32_e32 v40, 5, v40
	v_lshlrev_b32_e32 v41, 1, v41
	v_add3_u32 v40, v41, v229, v40
	v_cvt_f32_i32_e32 v40, v40
	v_mul_f32_e32 v40, v228, v40
	v_lshlrev_b32_e32 v42, 5, v42
	v_lshlrev_b32_e32 v43, 1, v43
	v_add3_u32 v42, v43, v229, v42
	v_cvt_f32_i32_e32 v42, v42
	v_mul_f32_e32 v42, v228, v42
	v_lshlrev_b32_e32 v44, 5, v44
	v_lshlrev_b32_e32 v45, 1, v45
	v_add3_u32 v44, v45, v229, v44
	v_cvt_f32_i32_e32 v44, v44
	v_mul_f32_e32 v44, v228, v44
	v_cvt_pk_bf16_f32 v186, v38, v40
	v_cvt_pk_bf16_f32 v187, v42, v44
	ds_read_b128 v[252:255], v155
	s_add_i32 s44, s40, 32
	s_ashr_i32 s45, s44, 31
	s_lshl_b64 s[44:45], s[44:45], 12
	v_lshl_add_u64 v[80:81], v[36:37], 0, s[44:45]
	s_waitcnt lgkmcnt(0)
	v_mul_f32_e32 v210, v210, v252
	v_mul_f32_e32 v211, v211, v253
	v_mul_f32_e32 v212, v212, v254
	v_mul_f32_e32 v213, v213, v255
	global_store_dwordx4 v[80:81], v[210:213], off nt
	s_add_i32 s43, s40, 40
	s_lshl_b32 s43, s43, 11
	v_add_u32_e32 v138, s43, v66
	global_load_dwordx2 v[194:195], v138, s[70:71]
	global_load_dwordx2 v[196:197], v138, s[70:71] offset:512
	global_load_dwordx2 v[198:199], v138, s[70:71] offset:1024
	global_load_dwordx2 v[200:201], v138, s[70:71] offset:1536
	v_add_u32_e32 v147, 8, v140
	v_and_b32_e32 v146, 15, v147
	v_xor_b32_e32 v146, 8, v146
	v_bfe_u32 v148, v147, 4, 4
	v_mul_lo_u32 v146, v146, s92
	v_mul_lo_u32 v148, v148, s92
	v_mov_b32_e32 v147, v146
	v_mov_b32_e32 v149, v148
	ds_write2st64_b64 v77, v[146:147], v[148:149] offset1:2
	v_add_u32_e32 v138, 0x1c00, v74
	ds_read_u8 v139, v138
	v_add_u32_e32 v141, 0x1c00, v73
	ds_read_u8 v140, v141
	s_add_i32 s43, s67, 192
	v_mov_b32_e32 v138, s43
	ds_read2st64_b32 v[228:229], v138 offset1:1
	ds_read_b128 v[26:29], v227 offset:14336
	ds_read_b128 v[30:33], v227 offset:14352
	v_mov_b32_e32 v38, 0
	v_mov_b32_e32 v39, 0
	v_mov_b32_e32 v40, 0
	v_mov_b32_e32 v41, 0
	v_mov_b32_e32 v42, 0
	v_mov_b32_e32 v43, 0
	v_mov_b32_e32 v44, 0
	v_mov_b32_e32 v45, 0
	v_and_b32_e32 v78, 0xffff, v23
	v_lshrrev_b32_e32 v79, 16, v23
	v_lshl_add_u32 v78, v78, 7, v152
	v_lshl_add_u32 v79, v79, 7, v153
	s_mov_b32 m0, s79
	s_add_i32 s43, s79, 0x400
	global_load_lds_dwordx4 v78, s[50:51]
	s_mov_b32 m0, s43
	s_nop 0
	global_load_lds_dwordx4 v79, s[50:51]
	s_waitcnt vmcnt(13)
	v_add_u32_e32 v54, s99, v59
	v_add_u32_e32 v55, s99, v60
	v_add_u32_e32 v56, s99, v61
	v_add_u32_e32 v57, s99, v62
	ds_read_b64_tr_b4 v[50:51], v160 offset:128
	ds_read_b64_tr_b4 v[52:53], v160 offset:1152
	ds_read_b64_tr_b4 v[130:131], v54
	ds_read_b64_tr_b4 v[132:133], v55
	ds_read_b64_tr_b4 v[134:135], v56
	ds_read_b64_tr_b4 v[136:137], v57
	s_waitcnt lgkmcnt(13)
	v_dot8c_i32_i4_e32 v38, v122, v48
	v_dot8c_i32_i4_e32 v39, v122, v46
	v_dot8c_i32_i4_e32 v40, v124, v48
	v_dot8c_i32_i4_e32 v41, v124, v46
	v_dot8c_i32_i4_e32 v42, v126, v48
	v_dot8c_i32_i4_e32 v43, v126, v46
	v_dot8c_i32_i4_e32 v44, v128, v48
	v_dot8c_i32_i4_e32 v45, v128, v46
	v_dot8c_i32_i4_e32 v38, v123, v49
	v_dot8c_i32_i4_e32 v39, v123, v47
	v_dot8c_i32_i4_e32 v40, v125, v49
	v_dot8c_i32_i4_e32 v41, v125, v47
	v_dot8c_i32_i4_e32 v42, v127, v49
	v_dot8c_i32_i4_e32 v43, v127, v47
	v_dot8c_i32_i4_e32 v44, v129, v49
	v_dot8c_i32_i4_e32 v45, v129, v47
	v_and_b32_e32 v78, 0xffff, v24
	v_lshrrev_b32_e32 v79, 16, v24
	v_lshl_add_u32 v78, v78, 7, v152
	v_lshl_add_u32 v79, v79, 7, v153
	s_mov_b32 m0, s98
	s_add_i32 s43, s98, 0x400
	global_load_lds_dwordx4 v78, s[50:51]
	s_mov_b32 m0, s43
	s_nop 0
	global_load_lds_dwordx4 v79, s[50:51]
	s_waitcnt vmcnt(13)
	v_add_u32_e32 v54, s76, v59
	v_add_u32_e32 v55, s76, v60
	v_add_u32_e32 v56, s76, v61
	v_add_u32_e32 v57, s76, v62
	ds_read_b64_tr_b4 v[46:47], v160 offset:256
	ds_read_b64_tr_b4 v[48:49], v160 offset:1280
	ds_read_b64_tr_b4 v[122:123], v54
	ds_read_b64_tr_b4 v[124:125], v55
	ds_read_b64_tr_b4 v[126:127], v56
	ds_read_b64_tr_b4 v[128:129], v57
	s_waitcnt lgkmcnt(6)
	v_dot8c_i32_i4_e32 v38, v130, v52
	v_dot8c_i32_i4_e32 v39, v130, v50
	v_dot8c_i32_i4_e32 v40, v132, v52
	v_dot8c_i32_i4_e32 v41, v132, v50
	v_dot8c_i32_i4_e32 v42, v134, v52
	v_dot8c_i32_i4_e32 v43, v134, v50
	v_dot8c_i32_i4_e32 v44, v136, v52
	v_dot8c_i32_i4_e32 v45, v136, v50
	v_dot8c_i32_i4_e32 v38, v131, v53
	v_dot8c_i32_i4_e32 v39, v131, v51
	v_dot8c_i32_i4_e32 v40, v133, v53
	v_dot8c_i32_i4_e32 v41, v133, v51
	v_dot8c_i32_i4_e32 v42, v135, v53
	v_dot8c_i32_i4_e32 v43, v135, v51
	v_dot8c_i32_i4_e32 v44, v137, v53
	v_dot8c_i32_i4_e32 v45, v137, v51
	v_and_b32_e32 v78, 0xffff, v25
	v_lshrrev_b32_e32 v79, 16, v25
	v_lshl_add_u32 v78, v78, 7, v152
	v_lshl_add_u32 v79, v79, 7, v153
	s_mov_b32 m0, s99
	s_add_i32 s43, s99, 0x400
	global_load_lds_dwordx4 v78, s[50:51]
	s_mov_b32 m0, s43
	s_nop 0
	global_load_lds_dwordx4 v79, s[50:51]
	s_waitcnt vmcnt(13)
	v_add_u32_e32 v54, s77, v59
	v_add_u32_e32 v55, s77, v60
	v_add_u32_e32 v56, s77, v61
	v_add_u32_e32 v57, s77, v62
	ds_read_b64_tr_b4 v[50:51], v160 offset:384
	ds_read_b64_tr_b4 v[52:53], v160 offset:1408
	ds_read_b64_tr_b4 v[130:131], v54
	ds_read_b64_tr_b4 v[132:133], v55
	ds_read_b64_tr_b4 v[134:135], v56
	ds_read_b64_tr_b4 v[136:137], v57
	s_waitcnt lgkmcnt(6)
	v_dot8c_i32_i4_e32 v38, v122, v48
	v_dot8c_i32_i4_e32 v39, v122, v46
	v_dot8c_i32_i4_e32 v40, v124, v48
	v_dot8c_i32_i4_e32 v41, v124, v46
	v_dot8c_i32_i4_e32 v42, v126, v48
	v_dot8c_i32_i4_e32 v43, v126, v46
	v_dot8c_i32_i4_e32 v44, v128, v48
	v_dot8c_i32_i4_e32 v45, v128, v46
	v_dot8c_i32_i4_e32 v38, v123, v49
	v_dot8c_i32_i4_e32 v39, v123, v47
	v_dot8c_i32_i4_e32 v40, v125, v49
	v_dot8c_i32_i4_e32 v41, v125, v47
	v_dot8c_i32_i4_e32 v42, v127, v49
	v_dot8c_i32_i4_e32 v43, v127, v47
	v_dot8c_i32_i4_e32 v44, v129, v49
	v_dot8c_i32_i4_e32 v45, v129, v47
	s_waitcnt lgkmcnt(15)
; #define LAS __attribute__((address_space(3)))
; #define TR4(p_) __builtin_amdgcn_ds_read_tr4_b64_v2i32((LAS v2i*)(p_))
; __device__ __forceinline__ void peer_v_tokens(int j, const LAS unsigned short* EL, const LAS unsigned char* AL  , const LAS float* ASC  , const LAS int* SAL  , ...
;     ...
;             const int idx = lane + 64 * m, tau = idx >> 4, sr = idx & 15, k = 16 * (sr & 7) + 2 * tau + (sr >> 3);
;             const int aq = (int)*(const LAS signed char*)(AL + tl * 128 + k); const int tq = aq + 8;
;             const unsigned lo = (((unsigned)tq & 15u) ^ 8u) * 0x11111111u, hi = ((unsigned)(tq >> 4) & 15u) * 0x11111111u;
;             typedef unsigned u2v __attribute__((ext_vector_type(2)));
;             u2v l2; l2.x = lo; l2.y = lo; u2v h2; h2.x = hi; h2.y = hi;
;             *(LAS u2v*)(ATL + 8 * idx) = l2; *(LAS u2v*)(ATL + 1024 + 8 * idx) = h2;
;     ...
;         for (int st = 0; st < 16; ++st) {
;             const int p = st >> 2, q = st & 3;
;             if (st < 14) VDMA(st + 2, (st + 2) % 3);
;             if (st < 14) asm volatile("s_waitcnt vmcnt(8)" ::: "memory");
;             else if (st == 14) asm volatile("s_waitcnt vmcnt(4)" ::: "memory");
;             else asm volatile("s_waitcnt vmcnt(0)" ::: "memory");
;             if (q == 0) {
; #pragma unroll
;                 for (int r = 0; r < 4; ++r) { accH[r] = 0; accL[r] = 0; } }
; #pragma unroll
;             for (int tp = 0; tp < 2; ++tp) {
;                 const v2i ao = TR4(ATL + (2 * q + tp) * 128 + 8 * s16), ah = TR4(ATL + 1024 + (2 * q + tp) * 128 + 8 * s16);
; #pragma unroll
;                 for (int r = 0; r < 4; ++r) {
;                     const v2i d = TR4(ldsb + BUF[st % 3] + 2048 * tp + roff[r]);
;                     accH[r] = __builtin_amdgcn_sdot8(d.x, ah.x, accH[r], false); accH[r] = __builtin_amdgcn_sdot8(d.y, ah.y, accH[r], false);
;                     accL[r] = __builtin_amdgcn_sdot8(d.x, ao.x, accL[r], false); accL[r] = __builtin_amdgcn_sdot8(d.y, ao.y, accL[r], false);
;                 }
;             }
;             asm volatile("s_waitcnt lgkmcnt(0)" ::: "memory");
	v_and_b32_e32 v78, 0xffff, v26
	v_lshrrev_b32_e32 v79, 16, v26
	v_lshl_add_u32 v78, v78, 7, v152
	v_lshl_add_u32 v79, v79, 7, v153
	s_mov_b32 m0, s76
	s_add_i32 s43, s76, 0x400
	global_load_lds_dwordx4 v78, s[50:51]
	s_mov_b32 m0, s43
	s_nop 0
	global_load_lds_dwordx4 v79, s[50:51]
	s_waitcnt vmcnt(13)
	v_add_u32_e32 v54, s78, v59
	v_add_u32_e32 v55, s78, v60
	v_add_u32_e32 v56, s78, v61
	v_add_u32_e32 v57, s78, v62
	ds_read_b64_tr_b4 v[46:47], v160 offset:512
	ds_read_b64_tr_b4 v[48:49], v160 offset:1536
	ds_read_b64_tr_b4 v[122:123], v54
	ds_read_b64_tr_b4 v[124:125], v55
	ds_read_b64_tr_b4 v[126:127], v56
	ds_read_b64_tr_b4 v[128:129], v57
	s_waitcnt lgkmcnt(6)
	v_dot8c_i32_i4_e32 v38, v130, v52
	v_dot8c_i32_i4_e32 v39, v130, v50
	v_dot8c_i32_i4_e32 v40, v132, v52
	v_dot8c_i32_i4_e32 v41, v132, v50
	v_dot8c_i32_i4_e32 v42, v134, v52
	v_dot8c_i32_i4_e32 v43, v134, v50
	v_dot8c_i32_i4_e32 v44, v136, v52
	v_dot8c_i32_i4_e32 v45, v136, v50
	v_dot8c_i32_i4_e32 v38, v131, v53
	v_dot8c_i32_i4_e32 v39, v131, v51
	v_dot8c_i32_i4_e32 v40, v133, v53
	v_dot8c_i32_i4_e32 v41, v133, v51
	v_dot8c_i32_i4_e32 v42, v135, v53
	v_dot8c_i32_i4_e32 v43, v135, v51
	v_dot8c_i32_i4_e32 v44, v137, v53
	v_dot8c_i32_i4_e32 v45, v137, v51
	v_and_b32_e32 v78, 0xffff, v27
	v_lshrrev_b32_e32 v79, 16, v27
	v_lshl_add_u32 v78, v78, 7, v152
	v_lshl_add_u32 v79, v79, 7, v153
	s_mov_b32 m0, s77
	s_add_i32 s43, s77, 0x400
	global_load_lds_dwordx4 v78, s[50:51]
	s_mov_b32 m0, s43
	s_nop 0
	global_load_lds_dwordx4 v79, s[50:51]
	s_waitcnt vmcnt(8)
	v_add_u32_e32 v54, s79, v59
	v_add_u32_e32 v55, s79, v60
	v_add_u32_e32 v56, s79, v61
	v_add_u32_e32 v57, s79, v62
	ds_read_b64_tr_b4 v[50:51], v160 offset:640
	ds_read_b64_tr_b4 v[52:53], v160 offset:1664
	ds_read_b64_tr_b4 v[130:131], v54
	ds_read_b64_tr_b4 v[132:133], v55
	ds_read_b64_tr_b4 v[134:135], v56
	ds_read_b64_tr_b4 v[136:137], v57
	s_waitcnt lgkmcnt(6)
	v_dot8c_i32_i4_e32 v38, v122, v48
	v_dot8c_i32_i4_e32 v39, v122, v46
	v_dot8c_i32_i4_e32 v40, v124, v48
	v_dot8c_i32_i4_e32 v41, v124, v46
	v_dot8c_i32_i4_e32 v42, v126, v48
	v_dot8c_i32_i4_e32 v43, v126, v46
	v_dot8c_i32_i4_e32 v44, v128, v48
	v_dot8c_i32_i4_e32 v45, v128, v46
	v_dot8c_i32_i4_e32 v38, v123, v49
	v_dot8c_i32_i4_e32 v39, v123, v47
	v_dot8c_i32_i4_e32 v40, v125, v49
	v_dot8c_i32_i4_e32 v41, v125, v47
	v_dot8c_i32_i4_e32 v42, v127, v49
	v_dot8c_i32_i4_e32 v43, v127, v47
	v_dot8c_i32_i4_e32 v44, v129, v49
	v_dot8c_i32_i4_e32 v45, v129, v47
	s_waitcnt lgkmcnt(15)
	v_add_u32_e32 v143, 8, v139
	v_and_b32_e32 v142, 15, v143
	v_xor_b32_e32 v142, 8, v142
	v_bfe_u32 v144, v143, 4, 4
	v_mul_lo_u32 v142, v142, s92
	v_mul_lo_u32 v144, v144, s92
	v_mov_b32_e32 v143, v142
	v_mov_b32_e32 v145, v144
	ds_write2st64_b64 v159, v[142:143], v[144:145] offset1:2
	v_and_b32_e32 v78, 0xffff, v28
	v_lshrrev_b32_e32 v79, 16, v28
	v_lshl_add_u32 v78, v78, 7, v152
	v_lshl_add_u32 v79, v79, 7, v153
	s_mov_b32 m0, s78
	s_add_i32 s43, s78, 0x400
	global_load_lds_dwordx4 v78, s[50:51]
	s_mov_b32 m0, s43
	s_nop 0
	global_load_lds_dwordx4 v79, s[50:51]
	s_waitcnt vmcnt(8)
	v_add_u32_e32 v54, s98, v59
	v_add_u32_e32 v55, s98, v60
	v_add_u32_e32 v56, s98, v61
	v_add_u32_e32 v57, s98, v62
	ds_read_b64_tr_b4 v[46:47], v160 offset:768
	ds_read_b64_tr_b4 v[48:49], v160 offset:1792
	ds_read_b64_tr_b4 v[122:123], v54
	ds_read_b64_tr_b4 v[124:125], v55
	ds_read_b64_tr_b4 v[126:127], v56
	ds_read_b64_tr_b4 v[128:129], v57
	s_waitcnt lgkmcnt(7)
	v_dot8c_i32_i4_e32 v38, v130, v52
	v_dot8c_i32_i4_e32 v39, v130, v50
	v_dot8c_i32_i4_e32 v40, v132, v52
	v_dot8c_i32_i4_e32 v41, v132, v50
	v_dot8c_i32_i4_e32 v42, v134, v52
	v_dot8c_i32_i4_e32 v43, v134, v50
	v_dot8c_i32_i4_e32 v44, v136, v52
	v_dot8c_i32_i4_e32 v45, v136, v50
	v_dot8c_i32_i4_e32 v38, v131, v53
	v_dot8c_i32_i4_e32 v39, v131, v51
	v_dot8c_i32_i4_e32 v40, v133, v53
	v_dot8c_i32_i4_e32 v41, v133, v51
	v_dot8c_i32_i4_e32 v42, v135, v53
	v_dot8c_i32_i4_e32 v43, v135, v51
	v_dot8c_i32_i4_e32 v44, v137, v53
	v_dot8c_i32_i4_e32 v45, v137, v51
	v_and_b32_e32 v78, 0xffff, v29
	v_lshrrev_b32_e32 v79, 16, v29
	v_lshl_add_u32 v78, v78, 7, v152
	v_lshl_add_u32 v79, v79, 7, v153
	s_mov_b32 m0, s79
	s_add_i32 s43, s79, 0x400
	global_load_lds_dwordx4 v78, s[50:51]
	s_mov_b32 m0, s43
	s_nop 0
	global_load_lds_dwordx4 v79, s[50:51]
	s_waitcnt vmcnt(8)
	v_add_u32_e32 v54, s99, v59
	v_add_u32_e32 v55, s99, v60
	v_add_u32_e32 v56, s99, v61
	v_add_u32_e32 v57, s99, v62
	ds_read_b64_tr_b4 v[50:51], v160 offset:896
	ds_read_b64_tr_b4 v[52:53], v160 offset:1920
	ds_read_b64_tr_b4 v[130:131], v54
	ds_read_b64_tr_b4 v[132:133], v55
	ds_read_b64_tr_b4 v[134:135], v56
	ds_read_b64_tr_b4 v[136:137], v57
	s_waitcnt lgkmcnt(6)
	v_dot8c_i32_i4_e32 v38, v122, v48
	v_dot8c_i32_i4_e32 v39, v122, v46
	v_dot8c_i32_i4_e32 v40, v124, v48
	v_dot8c_i32_i4_e32 v41, v124, v46
	v_dot8c_i32_i4_e32 v42, v126, v48
	v_dot8c_i32_i4_e32 v43, v126, v46
	v_dot8c_i32_i4_e32 v44, v128, v48
	v_dot8c_i32_i4_e32 v45, v128, v46
	v_dot8c_i32_i4_e32 v38, v123, v49
	v_dot8c_i32_i4_e32 v39, v123, v47
	v_dot8c_i32_i4_e32 v40, v125, v49
	v_dot8c_i32_i4_e32 v41, v125, v47
	v_dot8c_i32_i4_e32 v42, v127, v49
	v_dot8c_i32_i4_e32 v43, v127, v47
	v_dot8c_i32_i4_e32 v44, v129, v49
	v_dot8c_i32_i4_e32 v45, v129, v47
	v_and_b32_e32 v78, 0xffff, v30
	v_lshrrev_b32_e32 v79, 16, v30
	v_lshl_add_u32 v78, v78, 7, v152
	v_lshl_add_u32 v79, v79, 7, v153
	s_mov_b32 m0, s98
	s_add_i32 s43, s98, 0x400
	global_load_lds_dwordx4 v78, s[50:51]
	s_mov_b32 m0, s43
	s_nop 0
	global_load_lds_dwordx4 v79, s[50:51]
	s_waitcnt vmcnt(8)
; #define LAS __attribute__((address_space(3)))
; __device__ __forceinline__ bf16 f2bf(float f) { return (bf16)f2bfu(f); }
; __device__ __forceinline__ void peer_v_tokens(int j, const LAS unsigned short* EL, const LAS unsigned char* AL  , const LAS float* ASC  , const LAS int* SAL  , ...
;     ...
;         const int tl = it * 8 + wave, t = j * 64 + tl;
;         unsigned E[8];
;         { const LAS v4u* ep = (const LAS v4u*)(EL + tl * 128 + 16 * g); const v4u e0 = ep[0], e1 = ep[1];
;           E[0] = e0.x; E[1] = e0.y; E[2] = e0.z; E[3] = e0.w; E[4] = e1.x; E[5] = e1.y; E[6] = e1.z; E[7] = e1.w; }
;         uint2 hv[4]; float4 gv[4];
;     ...
;         for (int st = 0; st < 16; ++st) {
;             const int p = st >> 2, q = st & 3;
;             if (st < 14) VDMA(st + 2, (st + 2) % 3);
;             if (st < 14) asm volatile("s_waitcnt vmcnt(8)" ::: "memory");
;             else if (st == 14) asm volatile("s_waitcnt vmcnt(4)" ::: "memory");
;             else asm volatile("s_waitcnt vmcnt(0)" ::: "memory");
;             if (q == 0) {
; #pragma unroll
;                 for (int r = 0; r < 4; ++r) { accH[r] = 0; accL[r] = 0; } }
; #pragma unroll
;             for (int tp = 0; tp < 2; ++tp) {
;                 const v2i ao = TR4(ATL + (2 * q + tp) * 128 + 8 * s16), ah = TR4(ATL + 1024 + (2 * q + tp) * 128 + 8 * s16);
; #pragma unroll
;                 for (int r = 0; r < 4; ++r) {
;                     const v2i d = TR4(ldsb + BUF[st % 3] + 2048 * tp + roff[r]);
;                     accH[r] = __builtin_amdgcn_sdot8(d.x, ah.x, accH[r], false); accH[r] = __builtin_amdgcn_sdot8(d.y, ah.y, accH[r], false);
;                     accL[r] = __builtin_amdgcn_sdot8(d.x, ao.x, accL[r], false); accL[r] = __builtin_amdgcn_sdot8(d.y, ao.y, accL[r], false);
;                 }
;             }
;             asm volatile("s_waitcnt lgkmcnt(0)" ::: "memory");
;             if (q == 3) {
; #pragma unroll
;                 for (int r = 0; r < 4; ++r) STASH[256 * p + 16 * (grp + 4 * r) + pc] = f2bf(asc * (float)(2 * ((accH[r] << 4) + accL[r]) + sa));
;             }
;         }
;         CFENCE();
;         {
;             float4 v[4]; float ss = 0.f;
; #pragma unroll
;             for (int jq = 0; jq < 4; ++jq) { typedef unsigned u2v __attribute__((ext_vector_type(2))); const u2v pw = *(const LAS u2v*)(STASH + 4 * lane + 256 * jq); const uint2 hw = hv[jq];
	v_add_u32_e32 v54, s76, v59
	v_add_u32_e32 v55, s76, v60
	v_add_u32_e32 v56, s76, v61
	v_add_u32_e32 v57, s76, v62
	ds_read_b64_tr_b4 v[46:47], v160
	ds_read_b64_tr_b4 v[48:49], v160 offset:1024
	ds_read_b64_tr_b4 v[122:123], v54
	ds_read_b64_tr_b4 v[124:125], v55
	ds_read_b64_tr_b4 v[126:127], v56
	ds_read_b64_tr_b4 v[128:129], v57
	s_waitcnt lgkmcnt(6)
	v_dot8c_i32_i4_e32 v38, v130, v52
	v_dot8c_i32_i4_e32 v39, v130, v50
	v_dot8c_i32_i4_e32 v40, v132, v52
	v_dot8c_i32_i4_e32 v41, v132, v50
	v_dot8c_i32_i4_e32 v42, v134, v52
	v_dot8c_i32_i4_e32 v43, v134, v50
	v_dot8c_i32_i4_e32 v44, v136, v52
	v_dot8c_i32_i4_e32 v45, v136, v50
	v_dot8c_i32_i4_e32 v38, v131, v53
	v_dot8c_i32_i4_e32 v39, v131, v51
	v_dot8c_i32_i4_e32 v40, v133, v53
	v_dot8c_i32_i4_e32 v41, v133, v51
	v_dot8c_i32_i4_e32 v42, v135, v53
	v_dot8c_i32_i4_e32 v43, v135, v51
	v_dot8c_i32_i4_e32 v44, v137, v53
	v_dot8c_i32_i4_e32 v45, v137, v51
	s_nop 3
	s_waitcnt lgkmcnt(15)
	v_lshlrev_b32_e32 v38, 5, v38
	v_lshlrev_b32_e32 v39, 1, v39
	v_add3_u32 v38, v39, v229, v38
	v_cvt_f32_i32_e32 v38, v38
	v_mul_f32_e32 v38, v228, v38
	v_lshlrev_b32_e32 v40, 5, v40
	v_lshlrev_b32_e32 v41, 1, v41
	v_add3_u32 v40, v41, v229, v40
	v_cvt_f32_i32_e32 v40, v40
	v_mul_f32_e32 v40, v228, v40
	v_lshlrev_b32_e32 v42, 5, v42
	v_lshlrev_b32_e32 v43, 1, v43
	v_add3_u32 v42, v43, v229, v42
	v_cvt_f32_i32_e32 v42, v42
	v_mul_f32_e32 v42, v228, v42
	v_lshlrev_b32_e32 v44, 5, v44
	v_lshlrev_b32_e32 v45, 1, v45
	v_add3_u32 v44, v45, v229, v44
	v_cvt_f32_i32_e32 v44, v44
	v_mul_f32_e32 v44, v228, v44
	v_cvt_pk_bf16_f32 v180, v38, v40
	v_cvt_pk_bf16_f32 v181, v42, v44
	ds_read_b128 v[252:255], v155 offset:1024
	s_add_i32 s44, s40, 32
	s_ashr_i32 s45, s44, 31
	s_lshl_b64 s[44:45], s[44:45], 12
	v_lshl_add_u64 v[80:81], v[36:37], 0, s[44:45]
	s_waitcnt lgkmcnt(0)
	v_mul_f32_e32 v214, v214, v252
	v_mul_f32_e32 v215, v215, v253
	v_mul_f32_e32 v216, v216, v254
	v_mul_f32_e32 v217, v217, v255
	global_store_dwordx4 v[80:81], v[214:217], off offset:1024 nt
	v_add_u32_e32 v147, 8, v140
	v_and_b32_e32 v146, 15, v147
	v_xor_b32_e32 v146, 8, v146
	v_bfe_u32 v148, v147, 4, 4
	v_mul_lo_u32 v146, v146, s92
	v_mul_lo_u32 v148, v148, s92
	v_mov_b32_e32 v147, v146
	v_mov_b32_e32 v149, v148
	ds_write2st64_b64 v77, v[146:147], v[148:149] offset1:2
	v_add_u32_e32 v138, 0x1800, v74
	ds_read_u8 v139, v138
	v_add_u32_e32 v141, 0x1800, v73
	ds_read_u8 v140, v141
	s_add_i32 s43, s67, 224
	v_mov_b32_e32 v138, s43
	ds_read2st64_b32 v[228:229], v138 offset1:1
	ds_read_b128 v[18:21], v227 offset:12288
	ds_read_b128 v[22:25], v227 offset:12304
	v_add_u32_e32 v150, 0x400000, v63
	v_add_u32_e32 v151, 0x400000, v64
	v_mov_b32_e32 v38, 0
	v_mov_b32_e32 v39, 0
	v_mov_b32_e32 v40, 0
	v_mov_b32_e32 v41, 0
	v_mov_b32_e32 v42, 0
	v_mov_b32_e32 v43, 0
	v_mov_b32_e32 v44, 0
	v_mov_b32_e32 v45, 0
	v_and_b32_e32 v78, 0xffff, v31
	v_lshrrev_b32_e32 v79, 16, v31
	v_lshl_add_u32 v78, v78, 7, v152
	v_lshl_add_u32 v79, v79, 7, v153
	s_mov_b32 m0, s99
	s_add_i32 s43, s99, 0x400
	global_load_lds_dwordx4 v78, s[50:51]
	s_mov_b32 m0, s43
	s_nop 0
	global_load_lds_dwordx4 v79, s[50:51]
	s_waitcnt vmcnt(9)
	v_add_u32_e32 v54, s77, v59
	v_add_u32_e32 v55, s77, v60
	v_add_u32_e32 v56, s77, v61
	v_add_u32_e32 v57, s77, v62
	ds_read_b64_tr_b4 v[50:51], v160 offset:128
	ds_read_b64_tr_b4 v[52:53], v160 offset:1152
	ds_read_b64_tr_b4 v[130:131], v54
	ds_read_b64_tr_b4 v[132:133], v55
	ds_read_b64_tr_b4 v[134:135], v56
	ds_read_b64_tr_b4 v[136:137], v57
	s_waitcnt lgkmcnt(13)
	v_dot8c_i32_i4_e32 v38, v122, v48
	v_dot8c_i32_i4_e32 v39, v122, v46
	v_dot8c_i32_i4_e32 v40, v124, v48
	v_dot8c_i32_i4_e32 v41, v124, v46
	v_dot8c_i32_i4_e32 v42, v126, v48
	v_dot8c_i32_i4_e32 v43, v126, v46
	v_dot8c_i32_i4_e32 v44, v128, v48
	v_dot8c_i32_i4_e32 v45, v128, v46
	v_dot8c_i32_i4_e32 v38, v123, v49
	v_dot8c_i32_i4_e32 v39, v123, v47
	v_dot8c_i32_i4_e32 v40, v125, v49
	v_dot8c_i32_i4_e32 v41, v125, v47
	v_dot8c_i32_i4_e32 v42, v127, v49
	v_dot8c_i32_i4_e32 v43, v127, v47
	v_dot8c_i32_i4_e32 v44, v129, v49
	v_dot8c_i32_i4_e32 v45, v129, v47
	v_and_b32_e32 v78, 0xffff, v32
	v_lshrrev_b32_e32 v79, 16, v32
	v_lshl_add_u32 v78, v78, 7, v152
	v_lshl_add_u32 v79, v79, 7, v153
	s_mov_b32 m0, s76
	s_add_i32 s43, s76, 0x400
	global_load_lds_dwordx4 v78, s[50:51]
	s_mov_b32 m0, s43
	s_nop 0
	global_load_lds_dwordx4 v79, s[50:51]
	s_waitcnt vmcnt(9)
	v_add_u32_e32 v54, s78, v59
	v_add_u32_e32 v55, s78, v60
	v_add_u32_e32 v56, s78, v61
	v_add_u32_e32 v57, s78, v62
	ds_read_b64_tr_b4 v[46:47], v160 offset:256
	ds_read_b64_tr_b4 v[48:49], v160 offset:1280
	ds_read_b64_tr_b4 v[122:123], v54
	ds_read_b64_tr_b4 v[124:125], v55
	ds_read_b64_tr_b4 v[126:127], v56
	ds_read_b64_tr_b4 v[128:129], v57
	s_waitcnt lgkmcnt(6)
	v_dot8c_i32_i4_e32 v38, v130, v52
	v_dot8c_i32_i4_e32 v39, v130, v50
	v_dot8c_i32_i4_e32 v40, v132, v52
	v_dot8c_i32_i4_e32 v41, v132, v50
	v_dot8c_i32_i4_e32 v42, v134, v52
	v_dot8c_i32_i4_e32 v43, v134, v50
	v_dot8c_i32_i4_e32 v44, v136, v52
	v_dot8c_i32_i4_e32 v45, v136, v50
	v_dot8c_i32_i4_e32 v38, v131, v53
	v_dot8c_i32_i4_e32 v39, v131, v51
	v_dot8c_i32_i4_e32 v40, v133, v53
	v_dot8c_i32_i4_e32 v41, v133, v51
	v_dot8c_i32_i4_e32 v42, v135, v53
	v_dot8c_i32_i4_e32 v43, v135, v51
	v_dot8c_i32_i4_e32 v44, v137, v53
	v_dot8c_i32_i4_e32 v45, v137, v51
	ds_write_b16 v65, v170
	ds_write_b16_d16_hi v65, v170 offset:128
	ds_write_b16 v65, v171 offset:256
	ds_write_b16_d16_hi v65, v171 offset:384
	ds_write_b16 v65, v172 offset:512
	ds_write_b16_d16_hi v65, v172 offset:640
	ds_write_b16 v65, v173 offset:768
	ds_write_b16_d16_hi v65, v173 offset:896
	ds_write_b16 v65, v174 offset:1024
	ds_write_b16_d16_hi v65, v174 offset:1152
	ds_write_b16 v65, v175 offset:1280
	ds_write_b16_d16_hi v65, v175 offset:1408
	ds_write_b16 v65, v176 offset:1536
	ds_write_b16_d16_hi v65, v176 offset:1664
	ds_write_b16 v65, v177 offset:1792
	ds_write_b16_d16_hi v65, v177 offset:1920
	ds_read_b64 v[202:203], v154
	ds_read_b64 v[204:205], v154 offset:512
	ds_read_b64 v[206:207], v154 offset:1024
	ds_read_b64 v[208:209], v154 offset:1536
	v_and_b32_e32 v78, 0xffff, v33
	v_lshrrev_b32_e32 v79, 16, v33
	v_lshl_add_u32 v78, v78, 7, v152
	v_lshl_add_u32 v79, v79, 7, v153
	s_mov_b32 m0, s77
	s_add_i32 s43, s77, 0x400
	global_load_lds_dwordx4 v78, s[50:51]
	s_mov_b32 m0, s43
	s_nop 0
	global_load_lds_dwordx4 v79, s[50:51]
	s_waitcnt vmcnt(9)
; #define LAS __attribute__((address_space(3)))
; #define TR4(p_) __builtin_amdgcn_ds_read_tr4_b64_v2i32((LAS v2i*)(p_))
; __device__ __forceinline__ void peer_v_tokens(int j, const LAS unsigned short* EL, const LAS unsigned char* AL  , const LAS float* ASC  , const LAS int* SAL  , ...
;     ...
;             const int idx = lane + 64 * m, tau = idx >> 4, sr = idx & 15, k = 16 * (sr & 7) + 2 * tau + (sr >> 3);
;             const int aq = (int)*(const LAS signed char*)(AL + tl * 128 + k); const int tq = aq + 8;
;             const unsigned lo = (((unsigned)tq & 15u) ^ 8u) * 0x11111111u, hi = ((unsigned)(tq >> 4) & 15u) * 0x11111111u;
;             typedef unsigned u2v __attribute__((ext_vector_type(2)));
;             u2v l2; l2.x = lo; l2.y = lo; u2v h2; h2.x = hi; h2.y = hi;
;             *(LAS u2v*)(ATL + 8 * idx) = l2; *(LAS u2v*)(ATL + 1024 + 8 * idx) = h2;
;     ...
;         for (int st = 0; st < 16; ++st) {
;             const int p = st >> 2, q = st & 3;
;             if (st < 14) VDMA(st + 2, (st + 2) % 3);
;             if (st < 14) asm volatile("s_waitcnt vmcnt(8)" ::: "memory");
;             else if (st == 14) asm volatile("s_waitcnt vmcnt(4)" ::: "memory");
;             else asm volatile("s_waitcnt vmcnt(0)" ::: "memory");
;             if (q == 0) {
; #pragma unroll
;                 for (int r = 0; r < 4; ++r) { accH[r] = 0; accL[r] = 0; } }
; #pragma unroll
;             for (int tp = 0; tp < 2; ++tp) {
;                 const v2i ao = TR4(ATL + (2 * q + tp) * 128 + 8 * s16), ah = TR4(ATL + 1024 + (2 * q + tp) * 128 + 8 * s16);
; #pragma unroll
;                 for (int r = 0; r < 4; ++r) {
;                     const v2i d = TR4(ldsb + BUF[st % 3] + 2048 * tp + roff[r]);
;                     accH[r] = __builtin_amdgcn_sdot8(d.x, ah.x, accH[r], false); accH[r] = __builtin_amdgcn_sdot8(d.y, ah.y, accH[r], false);
;                     accL[r] = __builtin_amdgcn_sdot8(d.x, ao.x, accL[r], false); accL[r] = __builtin_amdgcn_sdot8(d.y, ao.y, accL[r], false);
;                 }
;             }
;             asm volatile("s_waitcnt lgkmcnt(0)" ::: "memory");
	v_add_u32_e32 v54, s79, v59
	v_add_u32_e32 v55, s79, v60
	v_add_u32_e32 v56, s79, v61
	v_add_u32_e32 v57, s79, v62
	ds_read_b64_tr_b4 v[50:51], v160 offset:384
	ds_read_b64_tr_b4 v[52:53], v160 offset:1408
	ds_read_b64_tr_b4 v[130:131], v54
	ds_read_b64_tr_b4 v[132:133], v55
	ds_read_b64_tr_b4 v[134:135], v56
	ds_read_b64_tr_b4 v[136:137], v57
	s_waitcnt lgkmcnt(15)
	v_dot8c_i32_i4_e32 v38, v122, v48
	v_dot8c_i32_i4_e32 v39, v122, v46
	v_dot8c_i32_i4_e32 v40, v124, v48
	v_dot8c_i32_i4_e32 v41, v124, v46
	v_dot8c_i32_i4_e32 v42, v126, v48
	v_dot8c_i32_i4_e32 v43, v126, v46
	v_dot8c_i32_i4_e32 v44, v128, v48
	v_dot8c_i32_i4_e32 v45, v128, v46
	v_dot8c_i32_i4_e32 v38, v123, v49
	v_dot8c_i32_i4_e32 v39, v123, v47
	v_dot8c_i32_i4_e32 v40, v125, v49
	v_dot8c_i32_i4_e32 v41, v125, v47
	v_dot8c_i32_i4_e32 v42, v127, v49
	v_dot8c_i32_i4_e32 v43, v127, v47
	v_dot8c_i32_i4_e32 v44, v129, v49
	v_dot8c_i32_i4_e32 v45, v129, v47
	s_waitcnt lgkmcnt(15)
	v_and_b32_e32 v78, 0xffff, v18
	v_lshrrev_b32_e32 v79, 16, v18
	v_lshl_add_u32 v78, v78, 7, v150
	v_lshl_add_u32 v79, v79, 7, v151
	s_mov_b32 m0, s78
	s_add_i32 s43, s78, 0x400
	global_load_lds_dwordx4 v78, s[50:51]
	s_mov_b32 m0, s43
	s_nop 0
	global_load_lds_dwordx4 v79, s[50:51]
	s_waitcnt vmcnt(9)
	v_add_u32_e32 v54, s98, v59
	v_add_u32_e32 v55, s98, v60
	v_add_u32_e32 v56, s98, v61
	v_add_u32_e32 v57, s98, v62
	ds_read_b64_tr_b4 v[46:47], v160 offset:512
	ds_read_b64_tr_b4 v[48:49], v160 offset:1536
	ds_read_b64_tr_b4 v[122:123], v54
	ds_read_b64_tr_b4 v[124:125], v55
	ds_read_b64_tr_b4 v[126:127], v56
	ds_read_b64_tr_b4 v[128:129], v57
	s_waitcnt lgkmcnt(6)
	v_dot8c_i32_i4_e32 v38, v130, v52
	v_dot8c_i32_i4_e32 v39, v130, v50
	v_dot8c_i32_i4_e32 v40, v132, v52
	v_dot8c_i32_i4_e32 v41, v132, v50
	v_dot8c_i32_i4_e32 v42, v134, v52
	v_dot8c_i32_i4_e32 v43, v134, v50
	v_dot8c_i32_i4_e32 v44, v136, v52
	v_dot8c_i32_i4_e32 v45, v136, v50
	v_dot8c_i32_i4_e32 v38, v131, v53
	v_dot8c_i32_i4_e32 v39, v131, v51
	v_dot8c_i32_i4_e32 v40, v133, v53
	v_dot8c_i32_i4_e32 v41, v133, v51
	v_dot8c_i32_i4_e32 v42, v135, v53
	v_dot8c_i32_i4_e32 v43, v135, v51
	v_dot8c_i32_i4_e32 v44, v137, v53
	v_dot8c_i32_i4_e32 v45, v137, v51
	v_and_b32_e32 v78, 0xffff, v19
	v_lshrrev_b32_e32 v79, 16, v19
	v_lshl_add_u32 v78, v78, 7, v150
	v_lshl_add_u32 v79, v79, 7, v151
	s_mov_b32 m0, s79
	s_add_i32 s43, s79, 0x400
	global_load_lds_dwordx4 v78, s[50:51]
	s_mov_b32 m0, s43
	s_nop 0
	global_load_lds_dwordx4 v79, s[50:51]
	s_waitcnt vmcnt(8)
	v_add_u32_e32 v54, s99, v59
	v_add_u32_e32 v55, s99, v60
	v_add_u32_e32 v56, s99, v61
	v_add_u32_e32 v57, s99, v62
	ds_read_b64_tr_b4 v[50:51], v160 offset:640
	ds_read_b64_tr_b4 v[52:53], v160 offset:1664
	ds_read_b64_tr_b4 v[130:131], v54
	ds_read_b64_tr_b4 v[132:133], v55
	ds_read_b64_tr_b4 v[134:135], v56
	ds_read_b64_tr_b4 v[136:137], v57
	s_waitcnt lgkmcnt(6)
	v_dot8c_i32_i4_e32 v38, v122, v48
	v_dot8c_i32_i4_e32 v39, v122, v46
	v_dot8c_i32_i4_e32 v40, v124, v48
	v_dot8c_i32_i4_e32 v41, v124, v46
	v_dot8c_i32_i4_e32 v42, v126, v48
	v_dot8c_i32_i4_e32 v43, v126, v46
	v_dot8c_i32_i4_e32 v44, v128, v48
	v_dot8c_i32_i4_e32 v45, v128, v46
	v_dot8c_i32_i4_e32 v38, v123, v49
	v_dot8c_i32_i4_e32 v39, v123, v47
	v_dot8c_i32_i4_e32 v40, v125, v49
	v_dot8c_i32_i4_e32 v41, v125, v47
	v_dot8c_i32_i4_e32 v42, v127, v49
	v_dot8c_i32_i4_e32 v43, v127, v47
	v_dot8c_i32_i4_e32 v44, v129, v49
	v_dot8c_i32_i4_e32 v45, v129, v47
	s_waitcnt lgkmcnt(15)
	v_add_u32_e32 v143, 8, v139
	v_and_b32_e32 v142, 15, v143
	v_xor_b32_e32 v142, 8, v142
	v_bfe_u32 v144, v143, 4, 4
	v_mul_lo_u32 v142, v142, s92
	v_mul_lo_u32 v144, v144, s92
	v_mov_b32_e32 v143, v142
	v_mov_b32_e32 v145, v144
	ds_write2st64_b64 v159, v[142:143], v[144:145] offset1:2
	v_and_b32_e32 v78, 0xffff, v20
	v_lshrrev_b32_e32 v79, 16, v20
	v_lshl_add_u32 v78, v78, 7, v150
	v_lshl_add_u32 v79, v79, 7, v151
	s_mov_b32 m0, s98
	s_add_i32 s43, s98, 0x400
	global_load_lds_dwordx4 v78, s[50:51]
	s_mov_b32 m0, s43
	s_nop 0
	global_load_lds_dwordx4 v79, s[50:51]
	s_waitcnt vmcnt(8)
	v_add_u32_e32 v54, s76, v59
	v_add_u32_e32 v55, s76, v60
	v_add_u32_e32 v56, s76, v61
	v_add_u32_e32 v57, s76, v62
	ds_read_b64_tr_b4 v[46:47], v160 offset:768
	ds_read_b64_tr_b4 v[48:49], v160 offset:1792
	ds_read_b64_tr_b4 v[122:123], v54
	ds_read_b64_tr_b4 v[124:125], v55
	ds_read_b64_tr_b4 v[126:127], v56
	ds_read_b64_tr_b4 v[128:129], v57
	s_waitcnt lgkmcnt(7)
	v_dot8c_i32_i4_e32 v38, v130, v52
	v_dot8c_i32_i4_e32 v39, v130, v50
	v_dot8c_i32_i4_e32 v40, v132, v52
	v_dot8c_i32_i4_e32 v41, v132, v50
	v_dot8c_i32_i4_e32 v42, v134, v52
	v_dot8c_i32_i4_e32 v43, v134, v50
	v_dot8c_i32_i4_e32 v44, v136, v52
	v_dot8c_i32_i4_e32 v45, v136, v50
	v_dot8c_i32_i4_e32 v38, v131, v53
	v_dot8c_i32_i4_e32 v39, v131, v51
	v_dot8c_i32_i4_e32 v40, v133, v53
	v_dot8c_i32_i4_e32 v41, v133, v51
	v_dot8c_i32_i4_e32 v42, v135, v53
	v_dot8c_i32_i4_e32 v43, v135, v51
	v_dot8c_i32_i4_e32 v44, v137, v53
	v_dot8c_i32_i4_e32 v45, v137, v51
	v_and_b32_e32 v78, 0xffff, v21
	v_lshrrev_b32_e32 v79, 16, v21
	v_lshl_add_u32 v78, v78, 7, v150
	v_lshl_add_u32 v79, v79, 7, v151
	s_mov_b32 m0, s99
	s_add_i32 s43, s99, 0x400
	global_load_lds_dwordx4 v78, s[50:51]
	s_mov_b32 m0, s43
	s_nop 0
	global_load_lds_dwordx4 v79, s[50:51]
	s_waitcnt vmcnt(8)
	v_add_u32_e32 v54, s77, v59
	v_add_u32_e32 v55, s77, v60
	v_add_u32_e32 v56, s77, v61
	v_add_u32_e32 v57, s77, v62
	ds_read_b64_tr_b4 v[50:51], v160 offset:896
	ds_read_b64_tr_b4 v[52:53], v160 offset:1920
	ds_read_b64_tr_b4 v[130:131], v54
	ds_read_b64_tr_b4 v[132:133], v55
	ds_read_b64_tr_b4 v[134:135], v56
	ds_read_b64_tr_b4 v[136:137], v57
	s_waitcnt lgkmcnt(6)
; __device__ __forceinline__ bf16 f2bf(float f) { return (bf16)f2bfu(f); }
; #define TR4(p_) __builtin_amdgcn_ds_read_tr4_b64_v2i32((LAS v2i*)(p_))
; __device__ __forceinline__ void peer_v_tokens(int j, const LAS unsigned short* EL, const LAS unsigned char* AL  , const LAS float* ASC  , const LAS int* SAL  , ...
;     ...
;         for (int st = 0; st < 16; ++st) {
;             const int p = st >> 2, q = st & 3;
;             if (st < 14) VDMA(st + 2, (st + 2) % 3);
;             if (st < 14) asm volatile("s_waitcnt vmcnt(8)" ::: "memory");
;             else if (st == 14) asm volatile("s_waitcnt vmcnt(4)" ::: "memory");
;             else asm volatile("s_waitcnt vmcnt(0)" ::: "memory");
;             if (q == 0) {
; #pragma unroll
;                 for (int r = 0; r < 4; ++r) { accH[r] = 0; accL[r] = 0; } }
; #pragma unroll
;             for (int tp = 0; tp < 2; ++tp) {
;                 const v2i ao = TR4(ATL + (2 * q + tp) * 128 + 8 * s16), ah = TR4(ATL + 1024 + (2 * q + tp) * 128 + 8 * s16);
; #pragma unroll
;                 for (int r = 0; r < 4; ++r) {
;                     const v2i d = TR4(ldsb + BUF[st % 3] + 2048 * tp + roff[r]);
;                     accH[r] = __builtin_amdgcn_sdot8(d.x, ah.x, accH[r], false); accH[r] = __builtin_amdgcn_sdot8(d.y, ah.y, accH[r], false);
;                     accL[r] = __builtin_amdgcn_sdot8(d.x, ao.x, accL[r], false); accL[r] = __builtin_amdgcn_sdot8(d.y, ao.y, accL[r], false);
;                 }
;             }
;             asm volatile("s_waitcnt lgkmcnt(0)" ::: "memory");
;             if (q == 3) {
; #pragma unroll
;                 for (int r = 0; r < 4; ++r) STASH[256 * p + 16 * (grp + 4 * r) + pc] = f2bf(asc * (float)(2 * ((accH[r] << 4) + accL[r]) + sa));
;     ...
;             float4* op = (float4*)(outp + (size_t)t * D) + lane;
; #pragma unroll
;             for (int jq = 0; jq < 4; ++jq) { typedef float f4v __attribute__((ext_vector_type(4))); f4v o4; o4.x = v[jq].x * r3 * gv[jq].x; o4.y = v[jq].y * r3 * gv[jq].y; o4.z = v[jq].z * r3 * gv[jq].z; o4.w = v[jq].w * r3 * gv[jq].w;
;                 __builtin_nontemporal_store(o4, (f4v*)op + 64 * jq); }
	v_dot8c_i32_i4_e32 v38, v122, v48
	v_dot8c_i32_i4_e32 v39, v122, v46
	v_dot8c_i32_i4_e32 v40, v124, v48
	v_dot8c_i32_i4_e32 v41, v124, v46
	v_dot8c_i32_i4_e32 v42, v126, v48
	v_dot8c_i32_i4_e32 v43, v126, v46
	v_dot8c_i32_i4_e32 v44, v128, v48
	v_dot8c_i32_i4_e32 v45, v128, v46
	v_dot8c_i32_i4_e32 v38, v123, v49
	v_dot8c_i32_i4_e32 v39, v123, v47
	v_dot8c_i32_i4_e32 v40, v125, v49
	v_dot8c_i32_i4_e32 v41, v125, v47
	v_dot8c_i32_i4_e32 v42, v127, v49
	v_dot8c_i32_i4_e32 v43, v127, v47
	v_dot8c_i32_i4_e32 v44, v129, v49
	v_dot8c_i32_i4_e32 v45, v129, v47
	v_and_b32_e32 v78, 0xffff, v22
	v_lshrrev_b32_e32 v79, 16, v22
	v_lshl_add_u32 v78, v78, 7, v150
	v_lshl_add_u32 v79, v79, 7, v151
	s_mov_b32 m0, s76
	s_add_i32 s43, s76, 0x400
	global_load_lds_dwordx4 v78, s[50:51]
	s_mov_b32 m0, s43
	s_nop 0
	global_load_lds_dwordx4 v79, s[50:51]
	s_waitcnt vmcnt(8)
	v_add_u32_e32 v54, s78, v59
	v_add_u32_e32 v55, s78, v60
	v_add_u32_e32 v56, s78, v61
	v_add_u32_e32 v57, s78, v62
	ds_read_b64_tr_b4 v[46:47], v160
	ds_read_b64_tr_b4 v[48:49], v160 offset:1024
	ds_read_b64_tr_b4 v[122:123], v54
	ds_read_b64_tr_b4 v[124:125], v55
	ds_read_b64_tr_b4 v[126:127], v56
	ds_read_b64_tr_b4 v[128:129], v57
	s_waitcnt lgkmcnt(6)
	v_dot8c_i32_i4_e32 v38, v130, v52
	v_dot8c_i32_i4_e32 v39, v130, v50
	v_dot8c_i32_i4_e32 v40, v132, v52
	v_dot8c_i32_i4_e32 v41, v132, v50
	v_dot8c_i32_i4_e32 v42, v134, v52
	v_dot8c_i32_i4_e32 v43, v134, v50
	v_dot8c_i32_i4_e32 v44, v136, v52
	v_dot8c_i32_i4_e32 v45, v136, v50
	v_dot8c_i32_i4_e32 v38, v131, v53
	v_dot8c_i32_i4_e32 v39, v131, v51
	v_dot8c_i32_i4_e32 v40, v133, v53
	v_dot8c_i32_i4_e32 v41, v133, v51
	v_dot8c_i32_i4_e32 v42, v135, v53
	v_dot8c_i32_i4_e32 v43, v135, v51
	v_dot8c_i32_i4_e32 v44, v137, v53
	v_dot8c_i32_i4_e32 v45, v137, v51
	s_nop 3
	s_waitcnt lgkmcnt(15)
	v_lshlrev_b32_e32 v38, 5, v38
	v_lshlrev_b32_e32 v39, 1, v39
	v_add3_u32 v38, v39, v229, v38
	v_cvt_f32_i32_e32 v38, v38
	v_mul_f32_e32 v38, v228, v38
	v_lshlrev_b32_e32 v40, 5, v40
	v_lshlrev_b32_e32 v41, 1, v41
	v_add3_u32 v40, v41, v229, v40
	v_cvt_f32_i32_e32 v40, v40
	v_mul_f32_e32 v40, v228, v40
	v_lshlrev_b32_e32 v42, 5, v42
	v_lshlrev_b32_e32 v43, 1, v43
	v_add3_u32 v42, v43, v229, v42
	v_cvt_f32_i32_e32 v42, v42
	v_mul_f32_e32 v42, v228, v42
	v_lshlrev_b32_e32 v44, 5, v44
	v_lshlrev_b32_e32 v45, 1, v45
	v_add3_u32 v44, v45, v229, v44
	v_cvt_f32_i32_e32 v44, v44
	v_mul_f32_e32 v44, v228, v44
	v_cvt_pk_bf16_f32 v188, v38, v40
	v_cvt_pk_bf16_f32 v189, v42, v44
	ds_read_b128 v[252:255], v156
	s_add_i32 s44, s40, 32
	s_ashr_i32 s45, s44, 31
	s_lshl_b64 s[44:45], s[44:45], 12
	v_lshl_add_u64 v[80:81], v[36:37], 0, s[44:45]
	s_waitcnt lgkmcnt(0)
	v_mul_f32_e32 v218, v218, v252
	v_mul_f32_e32 v219, v219, v253
	v_mul_f32_e32 v220, v220, v254
	v_mul_f32_e32 v221, v221, v255
	global_store_dwordx4 v[80:81], v[218:221], off offset:2048 nt
	v_add_u32_e32 v147, 8, v140
	v_and_b32_e32 v146, 15, v147
	v_xor_b32_e32 v146, 8, v146
	v_bfe_u32 v148, v147, 4, 4
	v_mul_lo_u32 v146, v146, s92
	v_mul_lo_u32 v148, v148, s92
	v_mov_b32_e32 v147, v146
	v_mov_b32_e32 v149, v148
	ds_write2st64_b64 v77, v[146:147], v[148:149] offset1:2
	v_add_u32_e32 v138, 0x1c00, v74
	ds_read_u8 v139, v138
	v_add_u32_e32 v141, 0x1c00, v73
	ds_read_u8 v140, v141
	s_add_i32 s43, s67, 192
	v_mov_b32_e32 v138, s43
	ds_read2st64_b32 v[228:229], v138 offset1:1
	ds_read_b128 v[26:29], v227 offset:14336
	ds_read_b128 v[30:33], v227 offset:14352
	v_mov_b32_e32 v38, 0
	v_mov_b32_e32 v39, 0
	v_mov_b32_e32 v40, 0
	v_mov_b32_e32 v41, 0
	v_mov_b32_e32 v42, 0
	v_mov_b32_e32 v43, 0
	v_mov_b32_e32 v44, 0
	v_mov_b32_e32 v45, 0
	v_and_b32_e32 v78, 0xffff, v23
	v_lshrrev_b32_e32 v79, 16, v23
	v_lshl_add_u32 v78, v78, 7, v150
	v_lshl_add_u32 v79, v79, 7, v151
	s_mov_b32 m0, s77
	s_add_i32 s43, s77, 0x400
	global_load_lds_dwordx4 v78, s[50:51]
	s_mov_b32 m0, s43
	s_nop 0
	global_load_lds_dwordx4 v79, s[50:51]
	s_waitcnt vmcnt(9)
	v_add_u32_e32 v54, s79, v59
	v_add_u32_e32 v55, s79, v60
	v_add_u32_e32 v56, s79, v61
	v_add_u32_e32 v57, s79, v62
	ds_read_b64_tr_b4 v[50:51], v160 offset:128
	ds_read_b64_tr_b4 v[52:53], v160 offset:1152
	ds_read_b64_tr_b4 v[130:131], v54
	ds_read_b64_tr_b4 v[132:133], v55
	ds_read_b64_tr_b4 v[134:135], v56
	ds_read_b64_tr_b4 v[136:137], v57
	s_waitcnt lgkmcnt(13)
	s_waitcnt vmcnt(36) lgkmcnt(15)
; #define LAS __attribute__((address_space(3)))
; #define TR4(p_) __builtin_amdgcn_ds_read_tr4_b64_v2i32((LAS v2i*)(p_))
; __device__ __forceinline__ void peer_v_tokens(int j, const LAS unsigned short* EL, const LAS unsigned char* AL  , const LAS float* ASC  , const LAS int* SAL  , ...
;     ...
;         for (int st = 0; st < 16; ++st) {
;             const int p = st >> 2, q = st & 3;
;             if (st < 14) VDMA(st + 2, (st + 2) % 3);
;             if (st < 14) asm volatile("s_waitcnt vmcnt(8)" ::: "memory");
;             else if (st == 14) asm volatile("s_waitcnt vmcnt(4)" ::: "memory");
;             else asm volatile("s_waitcnt vmcnt(0)" ::: "memory");
;             if (q == 0) {
; #pragma unroll
;                 for (int r = 0; r < 4; ++r) { accH[r] = 0; accL[r] = 0; } }
; #pragma unroll
;             for (int tp = 0; tp < 2; ++tp) {
;                 const v2i ao = TR4(ATL + (2 * q + tp) * 128 + 8 * s16), ah = TR4(ATL + 1024 + (2 * q + tp) * 128 + 8 * s16);
; #pragma unroll
;                 for (int r = 0; r < 4; ++r) {
;                     const v2i d = TR4(ldsb + BUF[st % 3] + 2048 * tp + roff[r]);
;                     accH[r] = __builtin_amdgcn_sdot8(d.x, ah.x, accH[r], false); accH[r] = __builtin_amdgcn_sdot8(d.y, ah.y, accH[r], false);
;                     accL[r] = __builtin_amdgcn_sdot8(d.x, ao.x, accL[r], false); accL[r] = __builtin_amdgcn_sdot8(d.y, ao.y, accL[r], false);
;                 }
;             }
;             asm volatile("s_waitcnt lgkmcnt(0)" ::: "memory");
;     ...
;             float4 v[4]; float ss = 0.f;
; #pragma unroll
;             for (int jq = 0; jq < 4; ++jq) { typedef unsigned u2v __attribute__((ext_vector_type(2))); const u2v pw = *(const LAS u2v*)(STASH + 4 * lane + 256 * jq); const uint2 hw = hv[jq];
;                 v[jq] = make_float4(__uint_as_float(hw.x << 16) + __uint_as_float(pw.x << 16), __uint_as_float(hw.x & 0xffff0000u) + __uint_as_float(pw.x & 0xffff0000u),
;                                     __uint_as_float(hw.y << 16) + __uint_as_float(pw.y << 16), __uint_as_float(hw.y & 0xffff0000u) + __uint_as_float(pw.y & 0xffff0000u));
;                 ss += v[jq].x * v[jq].x + v[jq].y * v[jq].y + v[jq].z * v[jq].z + v[jq].w * v[jq].w; }
;             ss = wave_sum(ss);
;             const float r3 = rsqrtf(ss * (1.f / D) + EPS);
	v_lshlrev_b32_e32 v236, 16, v194
	v_and_b32_e32 v237, 0xffff0000, v194
	v_lshlrev_b32_e32 v142, 16, v202
	v_and_b32_e32 v143, 0xffff0000, v202
	v_add_f32_e32 v236, v236, v142
	v_add_f32_e32 v237, v237, v143
	v_lshlrev_b32_e32 v238, 16, v195
	v_and_b32_e32 v239, 0xffff0000, v195
	v_lshlrev_b32_e32 v142, 16, v203
	v_and_b32_e32 v143, 0xffff0000, v203
	v_add_f32_e32 v238, v238, v142
	v_add_f32_e32 v239, v239, v143
	v_lshlrev_b32_e32 v240, 16, v196
	v_and_b32_e32 v241, 0xffff0000, v196
	v_lshlrev_b32_e32 v142, 16, v204
	v_and_b32_e32 v143, 0xffff0000, v204
	v_add_f32_e32 v240, v240, v142
	v_add_f32_e32 v241, v241, v143
	v_lshlrev_b32_e32 v242, 16, v197
	v_and_b32_e32 v243, 0xffff0000, v197
	v_lshlrev_b32_e32 v142, 16, v205
	v_and_b32_e32 v143, 0xffff0000, v205
	v_add_f32_e32 v242, v242, v142
	v_add_f32_e32 v243, v243, v143
	v_lshlrev_b32_e32 v244, 16, v198
	v_and_b32_e32 v245, 0xffff0000, v198
	v_lshlrev_b32_e32 v142, 16, v206
	v_and_b32_e32 v143, 0xffff0000, v206
	v_add_f32_e32 v244, v244, v142
	v_add_f32_e32 v245, v245, v143
	v_lshlrev_b32_e32 v246, 16, v199
	v_and_b32_e32 v247, 0xffff0000, v199
	v_lshlrev_b32_e32 v142, 16, v207
	v_and_b32_e32 v143, 0xffff0000, v207
	v_add_f32_e32 v246, v246, v142
	v_add_f32_e32 v247, v247, v143
	v_lshlrev_b32_e32 v248, 16, v200
	v_and_b32_e32 v249, 0xffff0000, v200
	v_lshlrev_b32_e32 v142, 16, v208
	v_and_b32_e32 v143, 0xffff0000, v208
	v_add_f32_e32 v248, v248, v142
	v_add_f32_e32 v249, v249, v143
	v_lshlrev_b32_e32 v250, 16, v201
	v_and_b32_e32 v251, 0xffff0000, v201
	v_lshlrev_b32_e32 v142, 16, v209
	v_and_b32_e32 v143, 0xffff0000, v209
	v_add_f32_e32 v250, v250, v142
	v_add_f32_e32 v251, v251, v143
	v_mov_b32_e32 v144, 0
	v_mul_f32_e32 v145, v236, v236
	v_fmac_f32_e32 v145, v237, v237
	v_fmac_f32_e32 v145, v238, v238
	v_fmac_f32_e32 v145, v239, v239
	v_add_f32_e32 v144, v144, v145
	v_mul_f32_e32 v145, v240, v240
	v_fmac_f32_e32 v145, v241, v241
	v_fmac_f32_e32 v145, v242, v242
	v_fmac_f32_e32 v145, v243, v243
	v_add_f32_e32 v144, v144, v145
	v_mul_f32_e32 v145, v244, v244
	v_fmac_f32_e32 v145, v245, v245
	v_fmac_f32_e32 v145, v246, v246
	v_fmac_f32_e32 v145, v247, v247
	v_add_f32_e32 v144, v144, v145
	v_mul_f32_e32 v145, v248, v248
	v_fmac_f32_e32 v145, v249, v249
	v_fmac_f32_e32 v145, v250, v250
	v_fmac_f32_e32 v145, v251, v251
	v_add_f32_e32 v144, v144, v145
	s_nop 1
	v_add_f32_dpp v144, v144, v144 quad_perm:[1,0,3,2] row_mask:0xf bank_mask:0xf bound_ctrl:1
	s_nop 1
	v_add_f32_dpp v144, v144, v144 quad_perm:[2,3,0,1] row_mask:0xf bank_mask:0xf bound_ctrl:1
	s_nop 1
	v_add_f32_dpp v144, v144, v144 row_half_mirror row_mask:0xf bank_mask:0xf bound_ctrl:1
	s_nop 1
	v_add_f32_dpp v144, v144, v144 row_mirror row_mask:0xf bank_mask:0xf bound_ctrl:1
	s_nop 1
	v_readlane_b32 s10, v144, 0
	v_readlane_b32 s11, v144, 16
	v_readlane_b32 s14, v144, 32
	v_readlane_b32 s15, v144, 48
	s_nop 3
	v_mov_b32_e32 v144, s11
	v_mov_b32_e32 v145, s15
	v_add_f32_e32 v144, s10, v144
	v_add_f32_e32 v145, s14, v145
	v_add_f32_e32 v144, v144, v145
	v_fmamk_f32 v144, v144, 0x3a800000, v111
	v_rsq_f32_e32 v144, v144
	s_nop 0
	v_mul_f32_e32 v236, v236, v144
	v_mul_f32_e32 v237, v237, v144
	v_mul_f32_e32 v238, v238, v144
	v_mul_f32_e32 v239, v239, v144
	v_mul_f32_e32 v240, v240, v144
	v_mul_f32_e32 v241, v241, v144
	v_mul_f32_e32 v242, v242, v144
	v_mul_f32_e32 v243, v243, v144
	v_mul_f32_e32 v244, v244, v144
	v_mul_f32_e32 v245, v245, v144
	v_mul_f32_e32 v246, v246, v144
	v_mul_f32_e32 v247, v247, v144
	v_mul_f32_e32 v248, v248, v144
	v_mul_f32_e32 v249, v249, v144
	v_mul_f32_e32 v250, v250, v144
	v_mul_f32_e32 v251, v251, v144
	v_dot8c_i32_i4_e32 v38, v122, v48
	v_dot8c_i32_i4_e32 v39, v122, v46
	v_dot8c_i32_i4_e32 v40, v124, v48
	v_dot8c_i32_i4_e32 v41, v124, v46
	v_dot8c_i32_i4_e32 v42, v126, v48
	v_dot8c_i32_i4_e32 v43, v126, v46
	v_dot8c_i32_i4_e32 v44, v128, v48
	v_dot8c_i32_i4_e32 v45, v128, v46
	v_dot8c_i32_i4_e32 v38, v123, v49
	v_dot8c_i32_i4_e32 v39, v123, v47
	v_dot8c_i32_i4_e32 v40, v125, v49
	v_dot8c_i32_i4_e32 v41, v125, v47
	v_dot8c_i32_i4_e32 v42, v127, v49
	v_dot8c_i32_i4_e32 v43, v127, v47
	v_dot8c_i32_i4_e32 v44, v129, v49
	v_dot8c_i32_i4_e32 v45, v129, v47
	v_and_b32_e32 v78, 0xffff, v24
	v_lshrrev_b32_e32 v79, 16, v24
	v_lshl_add_u32 v78, v78, 7, v150
	v_lshl_add_u32 v79, v79, 7, v151
	s_mov_b32 m0, s78
	s_add_i32 s43, s78, 0x400
	global_load_lds_dwordx4 v78, s[50:51]
	s_mov_b32 m0, s43
	s_nop 0
	global_load_lds_dwordx4 v79, s[50:51]
	s_waitcnt vmcnt(9)
	v_add_u32_e32 v54, s98, v59
	v_add_u32_e32 v55, s98, v60
	v_add_u32_e32 v56, s98, v61
	v_add_u32_e32 v57, s98, v62
	ds_read_b64_tr_b4 v[46:47], v160 offset:256
	ds_read_b64_tr_b4 v[48:49], v160 offset:1280
	ds_read_b64_tr_b4 v[122:123], v54
	ds_read_b64_tr_b4 v[124:125], v55
	ds_read_b64_tr_b4 v[126:127], v56
	ds_read_b64_tr_b4 v[128:129], v57
	s_waitcnt lgkmcnt(6)
	v_dot8c_i32_i4_e32 v38, v130, v52
	v_dot8c_i32_i4_e32 v39, v130, v50
	v_dot8c_i32_i4_e32 v40, v132, v52
	v_dot8c_i32_i4_e32 v41, v132, v50
	v_dot8c_i32_i4_e32 v42, v134, v52
	v_dot8c_i32_i4_e32 v43, v134, v50
	v_dot8c_i32_i4_e32 v44, v136, v52
	v_dot8c_i32_i4_e32 v45, v136, v50
	v_dot8c_i32_i4_e32 v38, v131, v53
	v_dot8c_i32_i4_e32 v39, v131, v51
	v_dot8c_i32_i4_e32 v40, v133, v53
	v_dot8c_i32_i4_e32 v41, v133, v51
	v_dot8c_i32_i4_e32 v42, v135, v53
	v_dot8c_i32_i4_e32 v43, v135, v51
	v_dot8c_i32_i4_e32 v44, v137, v53
	v_dot8c_i32_i4_e32 v45, v137, v51
	v_and_b32_e32 v78, 0xffff, v25
	v_lshrrev_b32_e32 v79, 16, v25
	v_lshl_add_u32 v78, v78, 7, v150
	v_lshl_add_u32 v79, v79, 7, v151
	s_mov_b32 m0, s79
	s_add_i32 s43, s79, 0x400
	global_load_lds_dwordx4 v78, s[50:51]
	s_mov_b32 m0, s43
	s_nop 0
	global_load_lds_dwordx4 v79, s[50:51]
	s_waitcnt vmcnt(9)
; #define LAS __attribute__((address_space(3)))
; #define TR4(p_) __builtin_amdgcn_ds_read_tr4_b64_v2i32((LAS v2i*)(p_))
; __device__ __forceinline__ void peer_v_tokens(int j, const LAS unsigned short* EL, const LAS unsigned char* AL  , const LAS float* ASC  , const LAS int* SAL  , ...
;     ...
;             const int idx = lane + 64 * m, tau = idx >> 4, sr = idx & 15, k = 16 * (sr & 7) + 2 * tau + (sr >> 3);
;             const int aq = (int)*(const LAS signed char*)(AL + tl * 128 + k); const int tq = aq + 8;
;             const unsigned lo = (((unsigned)tq & 15u) ^ 8u) * 0x11111111u, hi = ((unsigned)(tq >> 4) & 15u) * 0x11111111u;
;             typedef unsigned u2v __attribute__((ext_vector_type(2)));
;             u2v l2; l2.x = lo; l2.y = lo; u2v h2; h2.x = hi; h2.y = hi;
;             *(LAS u2v*)(ATL + 8 * idx) = l2; *(LAS u2v*)(ATL + 1024 + 8 * idx) = h2;
;     ...
;         for (int st = 0; st < 16; ++st) {
;             const int p = st >> 2, q = st & 3;
;             if (st < 14) VDMA(st + 2, (st + 2) % 3);
;             if (st < 14) asm volatile("s_waitcnt vmcnt(8)" ::: "memory");
;             else if (st == 14) asm volatile("s_waitcnt vmcnt(4)" ::: "memory");
;             else asm volatile("s_waitcnt vmcnt(0)" ::: "memory");
;             if (q == 0) {
; #pragma unroll
;                 for (int r = 0; r < 4; ++r) { accH[r] = 0; accL[r] = 0; } }
; #pragma unroll
;             for (int tp = 0; tp < 2; ++tp) {
;                 const v2i ao = TR4(ATL + (2 * q + tp) * 128 + 8 * s16), ah = TR4(ATL + 1024 + (2 * q + tp) * 128 + 8 * s16);
; #pragma unroll
;                 for (int r = 0; r < 4; ++r) {
;                     const v2i d = TR4(ldsb + BUF[st % 3] + 2048 * tp + roff[r]);
;                     accH[r] = __builtin_amdgcn_sdot8(d.x, ah.x, accH[r], false); accH[r] = __builtin_amdgcn_sdot8(d.y, ah.y, accH[r], false);
;                     accL[r] = __builtin_amdgcn_sdot8(d.x, ao.x, accL[r], false); accL[r] = __builtin_amdgcn_sdot8(d.y, ao.y, accL[r], false);
;                 }
;             }
;             asm volatile("s_waitcnt lgkmcnt(0)" ::: "memory");
	v_add_u32_e32 v54, s99, v59
	v_add_u32_e32 v55, s99, v60
	v_add_u32_e32 v56, s99, v61
	v_add_u32_e32 v57, s99, v62
	ds_read_b64_tr_b4 v[50:51], v160 offset:384
	ds_read_b64_tr_b4 v[52:53], v160 offset:1408
	ds_read_b64_tr_b4 v[130:131], v54
	ds_read_b64_tr_b4 v[132:133], v55
	ds_read_b64_tr_b4 v[134:135], v56
	ds_read_b64_tr_b4 v[136:137], v57
	s_waitcnt lgkmcnt(6)
	v_dot8c_i32_i4_e32 v38, v122, v48
	v_dot8c_i32_i4_e32 v39, v122, v46
	v_dot8c_i32_i4_e32 v40, v124, v48
	v_dot8c_i32_i4_e32 v41, v124, v46
	v_dot8c_i32_i4_e32 v42, v126, v48
	v_dot8c_i32_i4_e32 v43, v126, v46
	v_dot8c_i32_i4_e32 v44, v128, v48
	v_dot8c_i32_i4_e32 v45, v128, v46
	v_dot8c_i32_i4_e32 v38, v123, v49
	v_dot8c_i32_i4_e32 v39, v123, v47
	v_dot8c_i32_i4_e32 v40, v125, v49
	v_dot8c_i32_i4_e32 v41, v125, v47
	v_dot8c_i32_i4_e32 v42, v127, v49
	v_dot8c_i32_i4_e32 v43, v127, v47
	v_dot8c_i32_i4_e32 v44, v129, v49
	v_dot8c_i32_i4_e32 v45, v129, v47
	s_waitcnt lgkmcnt(15)
	v_and_b32_e32 v78, 0xffff, v26
	v_lshrrev_b32_e32 v79, 16, v26
	v_lshl_add_u32 v78, v78, 7, v150
	v_lshl_add_u32 v79, v79, 7, v151
	s_mov_b32 m0, s98
	s_add_i32 s43, s98, 0x400
	global_load_lds_dwordx4 v78, s[50:51]
	s_mov_b32 m0, s43
	s_nop 0
	global_load_lds_dwordx4 v79, s[50:51]
	s_waitcnt vmcnt(9)
	v_add_u32_e32 v54, s76, v59
	v_add_u32_e32 v55, s76, v60
	v_add_u32_e32 v56, s76, v61
	v_add_u32_e32 v57, s76, v62
	ds_read_b64_tr_b4 v[46:47], v160 offset:512
	ds_read_b64_tr_b4 v[48:49], v160 offset:1536
	ds_read_b64_tr_b4 v[122:123], v54
	ds_read_b64_tr_b4 v[124:125], v55
	ds_read_b64_tr_b4 v[126:127], v56
	ds_read_b64_tr_b4 v[128:129], v57
	s_waitcnt lgkmcnt(6)
	v_dot8c_i32_i4_e32 v38, v130, v52
	v_dot8c_i32_i4_e32 v39, v130, v50
	v_dot8c_i32_i4_e32 v40, v132, v52
	v_dot8c_i32_i4_e32 v41, v132, v50
	v_dot8c_i32_i4_e32 v42, v134, v52
	v_dot8c_i32_i4_e32 v43, v134, v50
	v_dot8c_i32_i4_e32 v44, v136, v52
	v_dot8c_i32_i4_e32 v45, v136, v50
	v_dot8c_i32_i4_e32 v38, v131, v53
	v_dot8c_i32_i4_e32 v39, v131, v51
	v_dot8c_i32_i4_e32 v40, v133, v53
	v_dot8c_i32_i4_e32 v41, v133, v51
	v_dot8c_i32_i4_e32 v42, v135, v53
	v_dot8c_i32_i4_e32 v43, v135, v51
	v_dot8c_i32_i4_e32 v44, v137, v53
	v_dot8c_i32_i4_e32 v45, v137, v51
	v_and_b32_e32 v78, 0xffff, v27
	v_lshrrev_b32_e32 v79, 16, v27
	v_lshl_add_u32 v78, v78, 7, v150
	v_lshl_add_u32 v79, v79, 7, v151
	s_mov_b32 m0, s99
	s_add_i32 s43, s99, 0x400
	global_load_lds_dwordx4 v78, s[50:51]
	s_mov_b32 m0, s43
	s_nop 0
	global_load_lds_dwordx4 v79, s[50:51]
	s_waitcnt vmcnt(8)
	v_add_u32_e32 v54, s77, v59
	v_add_u32_e32 v55, s77, v60
	v_add_u32_e32 v56, s77, v61
	v_add_u32_e32 v57, s77, v62
	ds_read_b64_tr_b4 v[50:51], v160 offset:640
	ds_read_b64_tr_b4 v[52:53], v160 offset:1664
	ds_read_b64_tr_b4 v[130:131], v54
	ds_read_b64_tr_b4 v[132:133], v55
	ds_read_b64_tr_b4 v[134:135], v56
	ds_read_b64_tr_b4 v[136:137], v57
	s_waitcnt lgkmcnt(6)
	v_dot8c_i32_i4_e32 v38, v122, v48
	v_dot8c_i32_i4_e32 v39, v122, v46
	v_dot8c_i32_i4_e32 v40, v124, v48
	v_dot8c_i32_i4_e32 v41, v124, v46
	v_dot8c_i32_i4_e32 v42, v126, v48
	v_dot8c_i32_i4_e32 v43, v126, v46
	v_dot8c_i32_i4_e32 v44, v128, v48
	v_dot8c_i32_i4_e32 v45, v128, v46
	v_dot8c_i32_i4_e32 v38, v123, v49
	v_dot8c_i32_i4_e32 v39, v123, v47
	v_dot8c_i32_i4_e32 v40, v125, v49
	v_dot8c_i32_i4_e32 v41, v125, v47
	v_dot8c_i32_i4_e32 v42, v127, v49
	v_dot8c_i32_i4_e32 v43, v127, v47
	v_dot8c_i32_i4_e32 v44, v129, v49
	v_dot8c_i32_i4_e32 v45, v129, v47
	s_waitcnt lgkmcnt(15)
	v_add_u32_e32 v143, 8, v139
	v_and_b32_e32 v142, 15, v143
	v_xor_b32_e32 v142, 8, v142
	v_bfe_u32 v144, v143, 4, 4
	v_mul_lo_u32 v142, v142, s92
	v_mul_lo_u32 v144, v144, s92
	v_mov_b32_e32 v143, v142
	v_mov_b32_e32 v145, v144
	ds_write2st64_b64 v159, v[142:143], v[144:145] offset1:2
	v_and_b32_e32 v78, 0xffff, v28
	v_lshrrev_b32_e32 v79, 16, v28
	v_lshl_add_u32 v78, v78, 7, v150
	v_lshl_add_u32 v79, v79, 7, v151
	s_mov_b32 m0, s76
	s_add_i32 s43, s76, 0x400
	global_load_lds_dwordx4 v78, s[50:51]
	s_mov_b32 m0, s43
	s_nop 0
	global_load_lds_dwordx4 v79, s[50:51]
	s_waitcnt vmcnt(8)
	v_add_u32_e32 v54, s78, v59
	v_add_u32_e32 v55, s78, v60
	v_add_u32_e32 v56, s78, v61
	v_add_u32_e32 v57, s78, v62
	ds_read_b64_tr_b4 v[46:47], v160 offset:768
	ds_read_b64_tr_b4 v[48:49], v160 offset:1792
	ds_read_b64_tr_b4 v[122:123], v54
	ds_read_b64_tr_b4 v[124:125], v55
	ds_read_b64_tr_b4 v[126:127], v56
	ds_read_b64_tr_b4 v[128:129], v57
	s_waitcnt lgkmcnt(7)
	v_dot8c_i32_i4_e32 v38, v130, v52
	v_dot8c_i32_i4_e32 v39, v130, v50
	v_dot8c_i32_i4_e32 v40, v132, v52
	v_dot8c_i32_i4_e32 v41, v132, v50
	v_dot8c_i32_i4_e32 v42, v134, v52
	v_dot8c_i32_i4_e32 v43, v134, v50
	v_dot8c_i32_i4_e32 v44, v136, v52
	v_dot8c_i32_i4_e32 v45, v136, v50
	v_dot8c_i32_i4_e32 v38, v131, v53
	v_dot8c_i32_i4_e32 v39, v131, v51
	v_dot8c_i32_i4_e32 v40, v133, v53
	v_dot8c_i32_i4_e32 v41, v133, v51
	v_dot8c_i32_i4_e32 v42, v135, v53
	v_dot8c_i32_i4_e32 v43, v135, v51
	v_dot8c_i32_i4_e32 v44, v137, v53
	v_dot8c_i32_i4_e32 v45, v137, v51
	v_and_b32_e32 v78, 0xffff, v29
	v_lshrrev_b32_e32 v79, 16, v29
	v_lshl_add_u32 v78, v78, 7, v150
	v_lshl_add_u32 v79, v79, 7, v151
	s_mov_b32 m0, s77
	s_add_i32 s43, s77, 0x400
	global_load_lds_dwordx4 v78, s[50:51]
	s_mov_b32 m0, s43
	s_nop 0
	global_load_lds_dwordx4 v79, s[50:51]
	s_waitcnt vmcnt(8)
	v_add_u32_e32 v54, s79, v59
	v_add_u32_e32 v55, s79, v60
	v_add_u32_e32 v56, s79, v61
	v_add_u32_e32 v57, s79, v62
	ds_read_b64_tr_b4 v[50:51], v160 offset:896
	ds_read_b64_tr_b4 v[52:53], v160 offset:1920
	ds_read_b64_tr_b4 v[130:131], v54
	ds_read_b64_tr_b4 v[132:133], v55
	ds_read_b64_tr_b4 v[134:135], v56
	ds_read_b64_tr_b4 v[136:137], v57
	s_waitcnt lgkmcnt(6)
; __device__ __forceinline__ void peer_v_tokens(int j, const LAS unsigned short* EL, const LAS unsigned char* AL  , const LAS float* ASC  , const LAS int* SAL  , ...
;     ...
;         for (int st = 0; st < 16; ++st) {
;             const int p = st >> 2, q = st & 3;
;             if (st < 14) VDMA(st + 2, (st + 2) % 3);
;             if (st < 14) asm volatile("s_waitcnt vmcnt(8)" ::: "memory");
;             else if (st == 14) asm volatile("s_waitcnt vmcnt(4)" ::: "memory");
;             else asm volatile("s_waitcnt vmcnt(0)" ::: "memory");
;             if (q == 0) {
; #pragma unroll
;                 for (int r = 0; r < 4; ++r) { accH[r] = 0; accL[r] = 0; } }
; #pragma unroll
;             for (int tp = 0; tp < 2; ++tp) {
;                 const v2i ao = TR4(ATL + (2 * q + tp) * 128 + 8 * s16), ah = TR4(ATL + 1024 + (2 * q + tp) * 128 + 8 * s16);
; #pragma unroll
;                 for (int r = 0; r < 4; ++r) {
;                     const v2i d = TR4(ldsb + BUF[st % 3] + 2048 * tp + roff[r]);
;                     accH[r] = __builtin_amdgcn_sdot8(d.x, ah.x, accH[r], false); accH[r] = __builtin_amdgcn_sdot8(d.y, ah.y, accH[r], false);
;                     accL[r] = __builtin_amdgcn_sdot8(d.x, ao.x, accL[r], false); accL[r] = __builtin_amdgcn_sdot8(d.y, ao.y, accL[r], false);
;                 }
;             }
;             asm volatile("s_waitcnt lgkmcnt(0)" ::: "memory");
;             if (q == 3) {
; #pragma unroll
;                 for (int r = 0; r < 4; ++r) STASH[256 * p + 16 * (grp + 4 * r) + pc] = f2bf(asc * (float)(2 * ((accH[r] << 4) + accL[r]) + sa));
;             }
;         }
;         CFENCE();
;         {
;             float4 v[4]; float ss = 0.f;
; #pragma unroll
;             for (int jq = 0; jq < 4; ++jq) { typedef unsigned u2v __attribute__((ext_vector_type(2))); const u2v pw = *(const LAS u2v*)(STASH + 4 * lane + 256 * jq); const uint2 hw = hv[jq];
;                 v[jq] = make_float4(__uint_as_float(hw.x << 16) + __uint_as_float(pw.x << 16), __uint_as_float(hw.x & 0xffff0000u) + __uint_as_float(pw.x & 0xffff0000u),
;                                     __uint_as_float(hw.y << 16) + __uint_as_float(pw.y << 16), __uint_as_float(hw.y & 0xffff0000u) + __uint_as_float(pw.y & 0xffff0000u));
;                 ss += v[jq].x * v[jq].x + v[jq].y * v[jq].y + v[jq].z * v[jq].z + v[jq].w * v[jq].w; }
;             ss = wave_sum(ss);
	v_dot8c_i32_i4_e32 v38, v122, v48
	v_dot8c_i32_i4_e32 v39, v122, v46
	v_dot8c_i32_i4_e32 v40, v124, v48
	v_dot8c_i32_i4_e32 v41, v124, v46
	v_dot8c_i32_i4_e32 v42, v126, v48
	v_dot8c_i32_i4_e32 v43, v126, v46
	v_dot8c_i32_i4_e32 v44, v128, v48
	v_dot8c_i32_i4_e32 v45, v128, v46
	v_dot8c_i32_i4_e32 v38, v123, v49
	v_dot8c_i32_i4_e32 v39, v123, v47
	v_dot8c_i32_i4_e32 v40, v125, v49
	v_dot8c_i32_i4_e32 v41, v125, v47
	v_dot8c_i32_i4_e32 v42, v127, v49
	v_dot8c_i32_i4_e32 v43, v127, v47
	v_dot8c_i32_i4_e32 v44, v129, v49
	v_dot8c_i32_i4_e32 v45, v129, v47
	v_and_b32_e32 v78, 0xffff, v30
	v_lshrrev_b32_e32 v79, 16, v30
	v_lshl_add_u32 v78, v78, 7, v150
	v_lshl_add_u32 v79, v79, 7, v151
	s_mov_b32 m0, s78
	s_add_i32 s43, s78, 0x400
	global_load_lds_dwordx4 v78, s[50:51]
	s_mov_b32 m0, s43
	s_nop 0
	global_load_lds_dwordx4 v79, s[50:51]
	s_waitcnt vmcnt(8)
	v_add_u32_e32 v54, s98, v59
	v_add_u32_e32 v55, s98, v60
	v_add_u32_e32 v56, s98, v61
	v_add_u32_e32 v57, s98, v62
	ds_read_b64_tr_b4 v[46:47], v160
	ds_read_b64_tr_b4 v[48:49], v160 offset:1024
	ds_read_b64_tr_b4 v[122:123], v54
	ds_read_b64_tr_b4 v[124:125], v55
	ds_read_b64_tr_b4 v[126:127], v56
	ds_read_b64_tr_b4 v[128:129], v57
	s_waitcnt lgkmcnt(6)
	v_dot8c_i32_i4_e32 v38, v130, v52
	v_dot8c_i32_i4_e32 v39, v130, v50
	v_dot8c_i32_i4_e32 v40, v132, v52
	v_dot8c_i32_i4_e32 v41, v132, v50
	v_dot8c_i32_i4_e32 v42, v134, v52
	v_dot8c_i32_i4_e32 v43, v134, v50
	v_dot8c_i32_i4_e32 v44, v136, v52
	v_dot8c_i32_i4_e32 v45, v136, v50
	v_dot8c_i32_i4_e32 v38, v131, v53
	v_dot8c_i32_i4_e32 v39, v131, v51
	v_dot8c_i32_i4_e32 v40, v133, v53
	v_dot8c_i32_i4_e32 v41, v133, v51
	v_dot8c_i32_i4_e32 v42, v135, v53
	v_dot8c_i32_i4_e32 v43, v135, v51
	v_dot8c_i32_i4_e32 v44, v137, v53
	v_dot8c_i32_i4_e32 v45, v137, v51
	s_nop 3
	s_waitcnt lgkmcnt(15)
	v_lshlrev_b32_e32 v38, 5, v38
	v_lshlrev_b32_e32 v39, 1, v39
	v_add3_u32 v38, v39, v229, v38
	v_cvt_f32_i32_e32 v38, v38
	v_mul_f32_e32 v38, v228, v38
	v_lshlrev_b32_e32 v40, 5, v40
	v_lshlrev_b32_e32 v41, 1, v41
	v_add3_u32 v40, v41, v229, v40
	v_cvt_f32_i32_e32 v40, v40
	v_mul_f32_e32 v40, v228, v40
	v_lshlrev_b32_e32 v42, 5, v42
	v_lshlrev_b32_e32 v43, 1, v43
	v_add3_u32 v42, v43, v229, v42
	v_cvt_f32_i32_e32 v42, v42
	v_mul_f32_e32 v42, v228, v42
	v_lshlrev_b32_e32 v44, 5, v44
	v_lshlrev_b32_e32 v45, 1, v45
	v_add3_u32 v44, v45, v229, v44
	v_cvt_f32_i32_e32 v44, v44
	v_mul_f32_e32 v44, v228, v44
	v_cvt_pk_bf16_f32 v182, v38, v40
	v_cvt_pk_bf16_f32 v183, v42, v44
	ds_read_b128 v[252:255], v156 offset:1024
	s_add_i32 s44, s40, 32
	s_ashr_i32 s45, s44, 31
	s_lshl_b64 s[44:45], s[44:45], 12
	v_lshl_add_u64 v[80:81], v[36:37], 0, s[44:45]
	s_waitcnt lgkmcnt(0)
	v_mul_f32_e32 v222, v222, v252
	v_mul_f32_e32 v223, v223, v253
	v_mul_f32_e32 v224, v224, v254
	v_mul_f32_e32 v225, v225, v255
	global_store_dwordx4 v[80:81], v[222:225], off offset:3072 nt
	ds_read_b128 v[252:255], v155
	s_add_i32 s44, s40, 40
	s_ashr_i32 s45, s44, 31
	s_lshl_b64 s[44:45], s[44:45], 12
	v_lshl_add_u64 v[80:81], v[36:37], 0, s[44:45]
	s_waitcnt lgkmcnt(0)
	v_mul_f32_e32 v236, v236, v252
	v_mul_f32_e32 v237, v237, v253
	v_mul_f32_e32 v238, v238, v254
	v_mul_f32_e32 v239, v239, v255
	global_store_dwordx4 v[80:81], v[236:239], off nt
	v_add_u32_e32 v147, 8, v140
	v_and_b32_e32 v146, 15, v147
	v_xor_b32_e32 v146, 8, v146
	v_bfe_u32 v148, v147, 4, 4
	v_mul_lo_u32 v146, v146, s92
	v_mul_lo_u32 v148, v148, s92
	v_mov_b32_e32 v147, v146
	v_mov_b32_e32 v149, v148
	ds_write2st64_b64 v77, v[146:147], v[148:149] offset1:2
	v_add_u32_e32 v138, 0x1800, v74
	ds_read_u8 v139, v138
	v_add_u32_e32 v141, 0x1800, v73
	ds_read_u8 v140, v141
	s_add_i32 s43, s67, 224
	v_mov_b32_e32 v138, s43
	ds_read2st64_b32 v[228:229], v138 offset1:1
	ds_read_b128 v[18:21], v227 offset:12288
	ds_read_b128 v[22:25], v227 offset:12304
	v_add_u32_e32 v152, 0x600000, v63
	v_add_u32_e32 v153, 0x600000, v64
	v_mov_b32_e32 v38, 0
	v_mov_b32_e32 v39, 0
	v_mov_b32_e32 v40, 0
	v_mov_b32_e32 v41, 0
	v_mov_b32_e32 v42, 0
	v_mov_b32_e32 v43, 0
	v_mov_b32_e32 v44, 0
	v_mov_b32_e32 v45, 0
	v_and_b32_e32 v78, 0xffff, v31
	v_lshrrev_b32_e32 v79, 16, v31
	v_lshl_add_u32 v78, v78, 7, v150
	v_lshl_add_u32 v79, v79, 7, v151
	s_mov_b32 m0, s79
	s_add_i32 s43, s79, 0x400
	global_load_lds_dwordx4 v78, s[50:51]
	s_mov_b32 m0, s43
	s_nop 0
	global_load_lds_dwordx4 v79, s[50:51]
	s_waitcnt vmcnt(10)
	v_add_u32_e32 v54, s99, v59
	v_add_u32_e32 v55, s99, v60
	v_add_u32_e32 v56, s99, v61
	v_add_u32_e32 v57, s99, v62
	ds_read_b64_tr_b4 v[50:51], v160 offset:128
	ds_read_b64_tr_b4 v[52:53], v160 offset:1152
	ds_read_b64_tr_b4 v[130:131], v54
	ds_read_b64_tr_b4 v[132:133], v55
	ds_read_b64_tr_b4 v[134:135], v56
	ds_read_b64_tr_b4 v[136:137], v57
	s_waitcnt lgkmcnt(14)
	v_dot8c_i32_i4_e32 v38, v122, v48
	v_dot8c_i32_i4_e32 v39, v122, v46
	v_dot8c_i32_i4_e32 v40, v124, v48
	v_dot8c_i32_i4_e32 v41, v124, v46
	v_dot8c_i32_i4_e32 v42, v126, v48
	v_dot8c_i32_i4_e32 v43, v126, v46
	v_dot8c_i32_i4_e32 v44, v128, v48
	v_dot8c_i32_i4_e32 v45, v128, v46
	v_dot8c_i32_i4_e32 v38, v123, v49
	v_dot8c_i32_i4_e32 v39, v123, v47
	v_dot8c_i32_i4_e32 v40, v125, v49
	v_dot8c_i32_i4_e32 v41, v125, v47
	v_dot8c_i32_i4_e32 v42, v127, v49
	v_dot8c_i32_i4_e32 v43, v127, v47
	v_dot8c_i32_i4_e32 v44, v129, v49
	v_dot8c_i32_i4_e32 v45, v129, v47
	v_and_b32_e32 v78, 0xffff, v32
	v_lshrrev_b32_e32 v79, 16, v32
	v_lshl_add_u32 v78, v78, 7, v150
	v_lshl_add_u32 v79, v79, 7, v151
	s_mov_b32 m0, s98
	s_add_i32 s43, s98, 0x400
	global_load_lds_dwordx4 v78, s[50:51]
	s_mov_b32 m0, s43
	s_nop 0
	global_load_lds_dwordx4 v79, s[50:51]
	s_waitcnt vmcnt(10)
; #define LAS __attribute__((address_space(3)))
; #define TR4(p_) __builtin_amdgcn_ds_read_tr4_b64_v2i32((LAS v2i*)(p_))
; __device__ __forceinline__ void peer_v_tokens(int j, const LAS unsigned short* EL, const LAS unsigned char* AL  , const LAS float* ASC  , const LAS int* SAL  , ...
;     ...
;             const int idx = lane + 64 * m, tau = idx >> 4, sr = idx & 15, k = 16 * (sr & 7) + 2 * tau + (sr >> 3);
;             const int aq = (int)*(const LAS signed char*)(AL + tl * 128 + k); const int tq = aq + 8;
;             const unsigned lo = (((unsigned)tq & 15u) ^ 8u) * 0x11111111u, hi = ((unsigned)(tq >> 4) & 15u) * 0x11111111u;
;             typedef unsigned u2v __attribute__((ext_vector_type(2)));
;             u2v l2; l2.x = lo; l2.y = lo; u2v h2; h2.x = hi; h2.y = hi;
;             *(LAS u2v*)(ATL + 8 * idx) = l2; *(LAS u2v*)(ATL + 1024 + 8 * idx) = h2;
;     ...
;         for (int st = 0; st < 16; ++st) {
;             const int p = st >> 2, q = st & 3;
;             if (st < 14) VDMA(st + 2, (st + 2) % 3);
;             if (st < 14) asm volatile("s_waitcnt vmcnt(8)" ::: "memory");
;             else if (st == 14) asm volatile("s_waitcnt vmcnt(4)" ::: "memory");
;             else asm volatile("s_waitcnt vmcnt(0)" ::: "memory");
;             if (q == 0) {
; #pragma unroll
;                 for (int r = 0; r < 4; ++r) { accH[r] = 0; accL[r] = 0; } }
; #pragma unroll
;             for (int tp = 0; tp < 2; ++tp) {
;                 const v2i ao = TR4(ATL + (2 * q + tp) * 128 + 8 * s16), ah = TR4(ATL + 1024 + (2 * q + tp) * 128 + 8 * s16);
; #pragma unroll
;                 for (int r = 0; r < 4; ++r) {
;                     const v2i d = TR4(ldsb + BUF[st % 3] + 2048 * tp + roff[r]);
;                     accH[r] = __builtin_amdgcn_sdot8(d.x, ah.x, accH[r], false); accH[r] = __builtin_amdgcn_sdot8(d.y, ah.y, accH[r], false);
;                     accL[r] = __builtin_amdgcn_sdot8(d.x, ao.x, accL[r], false); accL[r] = __builtin_amdgcn_sdot8(d.y, ao.y, accL[r], false);
;                 }
;             }
;             asm volatile("s_waitcnt lgkmcnt(0)" ::: "memory");
	v_add_u32_e32 v54, s76, v59
	v_add_u32_e32 v55, s76, v60
	v_add_u32_e32 v56, s76, v61
	v_add_u32_e32 v57, s76, v62
	ds_read_b64_tr_b4 v[46:47], v160 offset:256
	ds_read_b64_tr_b4 v[48:49], v160 offset:1280
	ds_read_b64_tr_b4 v[122:123], v54
	ds_read_b64_tr_b4 v[124:125], v55
	ds_read_b64_tr_b4 v[126:127], v56
	ds_read_b64_tr_b4 v[128:129], v57
	s_waitcnt lgkmcnt(6)
	v_dot8c_i32_i4_e32 v38, v130, v52
	v_dot8c_i32_i4_e32 v39, v130, v50
	v_dot8c_i32_i4_e32 v40, v132, v52
	v_dot8c_i32_i4_e32 v41, v132, v50
	v_dot8c_i32_i4_e32 v42, v134, v52
	v_dot8c_i32_i4_e32 v43, v134, v50
	v_dot8c_i32_i4_e32 v44, v136, v52
	v_dot8c_i32_i4_e32 v45, v136, v50
	v_dot8c_i32_i4_e32 v38, v131, v53
	v_dot8c_i32_i4_e32 v39, v131, v51
	v_dot8c_i32_i4_e32 v40, v133, v53
	v_dot8c_i32_i4_e32 v41, v133, v51
	v_dot8c_i32_i4_e32 v42, v135, v53
	v_dot8c_i32_i4_e32 v43, v135, v51
	v_dot8c_i32_i4_e32 v44, v137, v53
	v_dot8c_i32_i4_e32 v45, v137, v51
	v_and_b32_e32 v78, 0xffff, v33
	v_lshrrev_b32_e32 v79, 16, v33
	v_lshl_add_u32 v78, v78, 7, v150
	v_lshl_add_u32 v79, v79, 7, v151
	s_mov_b32 m0, s99
	s_add_i32 s43, s99, 0x400
	global_load_lds_dwordx4 v78, s[50:51]
	s_mov_b32 m0, s43
	s_nop 0
	global_load_lds_dwordx4 v79, s[50:51]
	s_waitcnt vmcnt(10)
	v_add_u32_e32 v54, s77, v59
	v_add_u32_e32 v55, s77, v60
	v_add_u32_e32 v56, s77, v61
	v_add_u32_e32 v57, s77, v62
	ds_read_b64_tr_b4 v[50:51], v160 offset:384
	ds_read_b64_tr_b4 v[52:53], v160 offset:1408
	ds_read_b64_tr_b4 v[130:131], v54
	ds_read_b64_tr_b4 v[132:133], v55
	ds_read_b64_tr_b4 v[134:135], v56
	ds_read_b64_tr_b4 v[136:137], v57
	s_waitcnt lgkmcnt(6)
	v_dot8c_i32_i4_e32 v38, v122, v48
	v_dot8c_i32_i4_e32 v39, v122, v46
	v_dot8c_i32_i4_e32 v40, v124, v48
	v_dot8c_i32_i4_e32 v41, v124, v46
	v_dot8c_i32_i4_e32 v42, v126, v48
	v_dot8c_i32_i4_e32 v43, v126, v46
	v_dot8c_i32_i4_e32 v44, v128, v48
	v_dot8c_i32_i4_e32 v45, v128, v46
	v_dot8c_i32_i4_e32 v38, v123, v49
	v_dot8c_i32_i4_e32 v39, v123, v47
	v_dot8c_i32_i4_e32 v40, v125, v49
	v_dot8c_i32_i4_e32 v41, v125, v47
	v_dot8c_i32_i4_e32 v42, v127, v49
	v_dot8c_i32_i4_e32 v43, v127, v47
	v_dot8c_i32_i4_e32 v44, v129, v49
	v_dot8c_i32_i4_e32 v45, v129, v47
	s_waitcnt lgkmcnt(15)
	v_and_b32_e32 v78, 0xffff, v18
	v_lshrrev_b32_e32 v79, 16, v18
	v_lshl_add_u32 v78, v78, 7, v152
	v_lshl_add_u32 v79, v79, 7, v153
	s_mov_b32 m0, s76
	s_add_i32 s43, s76, 0x400
	global_load_lds_dwordx4 v78, s[50:51]
	s_mov_b32 m0, s43
	s_nop 0
	global_load_lds_dwordx4 v79, s[50:51]
	s_waitcnt vmcnt(10)
	v_add_u32_e32 v54, s78, v59
	v_add_u32_e32 v55, s78, v60
	v_add_u32_e32 v56, s78, v61
	v_add_u32_e32 v57, s78, v62
	ds_read_b64_tr_b4 v[46:47], v160 offset:512
	ds_read_b64_tr_b4 v[48:49], v160 offset:1536
	ds_read_b64_tr_b4 v[122:123], v54
	ds_read_b64_tr_b4 v[124:125], v55
	ds_read_b64_tr_b4 v[126:127], v56
	ds_read_b64_tr_b4 v[128:129], v57
	s_waitcnt lgkmcnt(6)
	v_dot8c_i32_i4_e32 v38, v130, v52
	v_dot8c_i32_i4_e32 v39, v130, v50
	v_dot8c_i32_i4_e32 v40, v132, v52
	v_dot8c_i32_i4_e32 v41, v132, v50
	v_dot8c_i32_i4_e32 v42, v134, v52
	v_dot8c_i32_i4_e32 v43, v134, v50
	v_dot8c_i32_i4_e32 v44, v136, v52
	v_dot8c_i32_i4_e32 v45, v136, v50
	v_dot8c_i32_i4_e32 v38, v131, v53
	v_dot8c_i32_i4_e32 v39, v131, v51
	v_dot8c_i32_i4_e32 v40, v133, v53
	v_dot8c_i32_i4_e32 v41, v133, v51
	v_dot8c_i32_i4_e32 v42, v135, v53
	v_dot8c_i32_i4_e32 v43, v135, v51
	v_dot8c_i32_i4_e32 v44, v137, v53
	v_dot8c_i32_i4_e32 v45, v137, v51
	v_and_b32_e32 v78, 0xffff, v19
	v_lshrrev_b32_e32 v79, 16, v19
	v_lshl_add_u32 v78, v78, 7, v152
	v_lshl_add_u32 v79, v79, 7, v153
	s_mov_b32 m0, s77
	s_add_i32 s43, s77, 0x400
	global_load_lds_dwordx4 v78, s[50:51]
	s_mov_b32 m0, s43
	s_nop 0
	global_load_lds_dwordx4 v79, s[50:51]
	s_waitcnt vmcnt(8)
	v_add_u32_e32 v54, s79, v59
	v_add_u32_e32 v55, s79, v60
	v_add_u32_e32 v56, s79, v61
	v_add_u32_e32 v57, s79, v62
	ds_read_b64_tr_b4 v[50:51], v160 offset:640
	ds_read_b64_tr_b4 v[52:53], v160 offset:1664
	ds_read_b64_tr_b4 v[130:131], v54
	ds_read_b64_tr_b4 v[132:133], v55
	ds_read_b64_tr_b4 v[134:135], v56
	ds_read_b64_tr_b4 v[136:137], v57
	s_waitcnt lgkmcnt(6)
	v_dot8c_i32_i4_e32 v38, v122, v48
	v_dot8c_i32_i4_e32 v39, v122, v46
	v_dot8c_i32_i4_e32 v40, v124, v48
	v_dot8c_i32_i4_e32 v41, v124, v46
	v_dot8c_i32_i4_e32 v42, v126, v48
	v_dot8c_i32_i4_e32 v43, v126, v46
	v_dot8c_i32_i4_e32 v44, v128, v48
	v_dot8c_i32_i4_e32 v45, v128, v46
	v_dot8c_i32_i4_e32 v38, v123, v49
	v_dot8c_i32_i4_e32 v39, v123, v47
	v_dot8c_i32_i4_e32 v40, v125, v49
	v_dot8c_i32_i4_e32 v41, v125, v47
	v_dot8c_i32_i4_e32 v42, v127, v49
	v_dot8c_i32_i4_e32 v43, v127, v47
	v_dot8c_i32_i4_e32 v44, v129, v49
	v_dot8c_i32_i4_e32 v45, v129, v47
	s_waitcnt lgkmcnt(15)
	v_add_u32_e32 v143, 8, v139
	v_and_b32_e32 v142, 15, v143
	v_xor_b32_e32 v142, 8, v142
	v_bfe_u32 v144, v143, 4, 4
	v_mul_lo_u32 v142, v142, s92
	v_mul_lo_u32 v144, v144, s92
	v_mov_b32_e32 v143, v142
	v_mov_b32_e32 v145, v144
	ds_write2st64_b64 v159, v[142:143], v[144:145] offset1:2
	v_and_b32_e32 v78, 0xffff, v20
	v_lshrrev_b32_e32 v79, 16, v20
	v_lshl_add_u32 v78, v78, 7, v152
	v_lshl_add_u32 v79, v79, 7, v153
	s_mov_b32 m0, s78
	s_add_i32 s43, s78, 0x400
	global_load_lds_dwordx4 v78, s[50:51]
	s_mov_b32 m0, s43
	s_nop 0
	global_load_lds_dwordx4 v79, s[50:51]
	s_waitcnt vmcnt(8)
	v_add_u32_e32 v54, s98, v59
	v_add_u32_e32 v55, s98, v60
	v_add_u32_e32 v56, s98, v61
	v_add_u32_e32 v57, s98, v62
	ds_read_b64_tr_b4 v[46:47], v160 offset:768
	ds_read_b64_tr_b4 v[48:49], v160 offset:1792
	ds_read_b64_tr_b4 v[122:123], v54
	ds_read_b64_tr_b4 v[124:125], v55
	ds_read_b64_tr_b4 v[126:127], v56
	ds_read_b64_tr_b4 v[128:129], v57
	s_waitcnt lgkmcnt(7)
; #define LAS __attribute__((address_space(3)))
; __device__ __forceinline__ bf16 f2bf(float f) { return (bf16)f2bfu(f); }
; __device__ __forceinline__ void peer_v_tokens(int j, const LAS unsigned short* EL, const LAS unsigned char* AL  , const LAS float* ASC  , const LAS int* SAL  , ...
;     ...
;         for (int m = 0; m < 2; ++m) {
;             const int idx = lane + 64 * m, tau = idx >> 4, sr = idx & 15, k = 16 * (sr & 7) + 2 * tau + (sr >> 3);
;             const int aq = (int)*(const LAS signed char*)(AL + tl * 128 + k); const int tq = aq + 8;
;             const unsigned lo = (((unsigned)tq & 15u) ^ 8u) * 0x11111111u, hi = ((unsigned)(tq >> 4) & 15u) * 0x11111111u;
;             typedef unsigned u2v __attribute__((ext_vector_type(2)));
;             u2v l2; l2.x = lo; l2.y = lo; u2v h2; h2.x = hi; h2.y = hi;
;             *(LAS u2v*)(ATL + 8 * idx) = l2; *(LAS u2v*)(ATL + 1024 + 8 * idx) = h2;
;         }
;     ...
;         for (int st = 0; st < 16; ++st) {
;             const int p = st >> 2, q = st & 3;
;             if (st < 14) VDMA(st + 2, (st + 2) % 3);
;             if (st < 14) asm volatile("s_waitcnt vmcnt(8)" ::: "memory");
;             else if (st == 14) asm volatile("s_waitcnt vmcnt(4)" ::: "memory");
;             else asm volatile("s_waitcnt vmcnt(0)" ::: "memory");
;             if (q == 0) {
; #pragma unroll
;                 for (int r = 0; r < 4; ++r) { accH[r] = 0; accL[r] = 0; } }
; #pragma unroll
;             for (int tp = 0; tp < 2; ++tp) {
;                 const v2i ao = TR4(ATL + (2 * q + tp) * 128 + 8 * s16), ah = TR4(ATL + 1024 + (2 * q + tp) * 128 + 8 * s16);
; #pragma unroll
;                 for (int r = 0; r < 4; ++r) {
;                     const v2i d = TR4(ldsb + BUF[st % 3] + 2048 * tp + roff[r]);
;                     accH[r] = __builtin_amdgcn_sdot8(d.x, ah.x, accH[r], false); accH[r] = __builtin_amdgcn_sdot8(d.y, ah.y, accH[r], false);
;                     accL[r] = __builtin_amdgcn_sdot8(d.x, ao.x, accL[r], false); accL[r] = __builtin_amdgcn_sdot8(d.y, ao.y, accL[r], false);
;                 }
;             }
;             asm volatile("s_waitcnt lgkmcnt(0)" ::: "memory");
;             if (q == 3) {
; #pragma unroll
;                 for (int r = 0; r < 4; ++r) STASH[256 * p + 16 * (grp + 4 * r) + pc] = f2bf(asc * (float)(2 * ((accH[r] << 4) + accL[r]) + sa));
;             }
;         }
	v_dot8c_i32_i4_e32 v38, v130, v52
	v_dot8c_i32_i4_e32 v39, v130, v50
	v_dot8c_i32_i4_e32 v40, v132, v52
	v_dot8c_i32_i4_e32 v41, v132, v50
	v_dot8c_i32_i4_e32 v42, v134, v52
	v_dot8c_i32_i4_e32 v43, v134, v50
	v_dot8c_i32_i4_e32 v44, v136, v52
	v_dot8c_i32_i4_e32 v45, v136, v50
	v_dot8c_i32_i4_e32 v38, v131, v53
	v_dot8c_i32_i4_e32 v39, v131, v51
	v_dot8c_i32_i4_e32 v40, v133, v53
	v_dot8c_i32_i4_e32 v41, v133, v51
	v_dot8c_i32_i4_e32 v42, v135, v53
	v_dot8c_i32_i4_e32 v43, v135, v51
	v_dot8c_i32_i4_e32 v44, v137, v53
	v_dot8c_i32_i4_e32 v45, v137, v51
	v_and_b32_e32 v78, 0xffff, v21
	v_lshrrev_b32_e32 v79, 16, v21
	v_lshl_add_u32 v78, v78, 7, v152
	v_lshl_add_u32 v79, v79, 7, v153
	s_mov_b32 m0, s79
	s_add_i32 s43, s79, 0x400
	global_load_lds_dwordx4 v78, s[50:51]
	s_mov_b32 m0, s43
	s_nop 0
	global_load_lds_dwordx4 v79, s[50:51]
	s_waitcnt vmcnt(8)
	v_add_u32_e32 v54, s99, v59
	v_add_u32_e32 v55, s99, v60
	v_add_u32_e32 v56, s99, v61
	v_add_u32_e32 v57, s99, v62
	ds_read_b64_tr_b4 v[50:51], v160 offset:896
	ds_read_b64_tr_b4 v[52:53], v160 offset:1920
	ds_read_b64_tr_b4 v[130:131], v54
	ds_read_b64_tr_b4 v[132:133], v55
	ds_read_b64_tr_b4 v[134:135], v56
	ds_read_b64_tr_b4 v[136:137], v57
	s_waitcnt lgkmcnt(6)
	v_dot8c_i32_i4_e32 v38, v122, v48
	v_dot8c_i32_i4_e32 v39, v122, v46
	v_dot8c_i32_i4_e32 v40, v124, v48
	v_dot8c_i32_i4_e32 v41, v124, v46
	v_dot8c_i32_i4_e32 v42, v126, v48
	v_dot8c_i32_i4_e32 v43, v126, v46
	v_dot8c_i32_i4_e32 v44, v128, v48
	v_dot8c_i32_i4_e32 v45, v128, v46
	v_dot8c_i32_i4_e32 v38, v123, v49
	v_dot8c_i32_i4_e32 v39, v123, v47
	v_dot8c_i32_i4_e32 v40, v125, v49
	v_dot8c_i32_i4_e32 v41, v125, v47
	v_dot8c_i32_i4_e32 v42, v127, v49
	v_dot8c_i32_i4_e32 v43, v127, v47
	v_dot8c_i32_i4_e32 v44, v129, v49
	v_dot8c_i32_i4_e32 v45, v129, v47
	v_and_b32_e32 v78, 0xffff, v22
	v_lshrrev_b32_e32 v79, 16, v22
	v_lshl_add_u32 v78, v78, 7, v152
	v_lshl_add_u32 v79, v79, 7, v153
	s_mov_b32 m0, s98
	s_add_i32 s43, s98, 0x400
	global_load_lds_dwordx4 v78, s[50:51]
	s_mov_b32 m0, s43
	s_nop 0
	global_load_lds_dwordx4 v79, s[50:51]
	s_waitcnt vmcnt(8)
	v_add_u32_e32 v54, s76, v59
	v_add_u32_e32 v55, s76, v60
	v_add_u32_e32 v56, s76, v61
	v_add_u32_e32 v57, s76, v62
	ds_read_b64_tr_b4 v[46:47], v160
	ds_read_b64_tr_b4 v[48:49], v160 offset:1024
	ds_read_b64_tr_b4 v[122:123], v54
	ds_read_b64_tr_b4 v[124:125], v55
	ds_read_b64_tr_b4 v[126:127], v56
	ds_read_b64_tr_b4 v[128:129], v57
	s_waitcnt lgkmcnt(6)
	v_dot8c_i32_i4_e32 v38, v130, v52
	v_dot8c_i32_i4_e32 v39, v130, v50
	v_dot8c_i32_i4_e32 v40, v132, v52
	v_dot8c_i32_i4_e32 v41, v132, v50
	v_dot8c_i32_i4_e32 v42, v134, v52
	v_dot8c_i32_i4_e32 v43, v134, v50
	v_dot8c_i32_i4_e32 v44, v136, v52
	v_dot8c_i32_i4_e32 v45, v136, v50
	v_dot8c_i32_i4_e32 v38, v131, v53
	v_dot8c_i32_i4_e32 v39, v131, v51
	v_dot8c_i32_i4_e32 v40, v133, v53
	v_dot8c_i32_i4_e32 v41, v133, v51
	v_dot8c_i32_i4_e32 v42, v135, v53
	v_dot8c_i32_i4_e32 v43, v135, v51
	v_dot8c_i32_i4_e32 v44, v137, v53
	v_dot8c_i32_i4_e32 v45, v137, v51
	s_nop 3
	s_waitcnt lgkmcnt(15)
	v_lshlrev_b32_e32 v38, 5, v38
	v_lshlrev_b32_e32 v39, 1, v39
	v_add3_u32 v38, v39, v229, v38
	v_cvt_f32_i32_e32 v38, v38
	v_mul_f32_e32 v38, v228, v38
	v_lshlrev_b32_e32 v40, 5, v40
	v_lshlrev_b32_e32 v41, 1, v41
	v_add3_u32 v40, v41, v229, v40
	v_cvt_f32_i32_e32 v40, v40
	v_mul_f32_e32 v40, v228, v40
	v_lshlrev_b32_e32 v42, 5, v42
	v_lshlrev_b32_e32 v43, 1, v43
	v_add3_u32 v42, v43, v229, v42
	v_cvt_f32_i32_e32 v42, v42
	v_mul_f32_e32 v42, v228, v42
	v_lshlrev_b32_e32 v44, 5, v44
	v_lshlrev_b32_e32 v45, 1, v45
	v_add3_u32 v44, v45, v229, v44
	v_cvt_f32_i32_e32 v44, v44
	v_mul_f32_e32 v44, v228, v44
	v_cvt_pk_bf16_f32 v190, v38, v40
	v_cvt_pk_bf16_f32 v191, v42, v44
	ds_read_b128 v[252:255], v155 offset:1024
	s_add_i32 s44, s40, 40
	s_ashr_i32 s45, s44, 31
	s_lshl_b64 s[44:45], s[44:45], 12
	v_lshl_add_u64 v[80:81], v[36:37], 0, s[44:45]
	s_waitcnt lgkmcnt(0)
	v_mul_f32_e32 v240, v240, v252
	v_mul_f32_e32 v241, v241, v253
	v_mul_f32_e32 v242, v242, v254
	v_mul_f32_e32 v243, v243, v255
	global_store_dwordx4 v[80:81], v[240:243], off offset:1024 nt
	v_add_u32_e32 v147, 8, v140
	v_and_b32_e32 v146, 15, v147
	v_xor_b32_e32 v146, 8, v146
	v_bfe_u32 v148, v147, 4, 4
	v_mul_lo_u32 v146, v146, s92
	v_mul_lo_u32 v148, v148, s92
	v_mov_b32_e32 v147, v146
	v_mov_b32_e32 v149, v148
	ds_write2st64_b64 v77, v[146:147], v[148:149] offset1:2
	v_add_u32_e32 v138, 0x1c00, v74
	ds_read_u8 v139, v138
	v_add_u32_e32 v141, 0x1c00, v73
	ds_read_u8 v140, v141
	s_add_i32 s43, s67, 192
	v_mov_b32_e32 v138, s43
	ds_read2st64_b32 v[228:229], v138 offset1:1
	ds_read_b128 v[26:29], v227 offset:14336
	ds_read_b128 v[30:33], v227 offset:14352
	v_mov_b32_e32 v38, 0
	v_mov_b32_e32 v39, 0
	v_mov_b32_e32 v40, 0
	v_mov_b32_e32 v41, 0
	v_mov_b32_e32 v42, 0
	v_mov_b32_e32 v43, 0
	v_mov_b32_e32 v44, 0
	v_mov_b32_e32 v45, 0
	v_and_b32_e32 v78, 0xffff, v23
	v_lshrrev_b32_e32 v79, 16, v23
	v_lshl_add_u32 v78, v78, 7, v152
	v_lshl_add_u32 v79, v79, 7, v153
	s_mov_b32 m0, s99
	s_add_i32 s43, s99, 0x400
	global_load_lds_dwordx4 v78, s[50:51]
	s_mov_b32 m0, s43
	s_nop 0
	global_load_lds_dwordx4 v79, s[50:51]
	s_waitcnt vmcnt(9)
	v_add_u32_e32 v54, s77, v59
	v_add_u32_e32 v55, s77, v60
	v_add_u32_e32 v56, s77, v61
	v_add_u32_e32 v57, s77, v62
	ds_read_b64_tr_b4 v[50:51], v160 offset:128
	ds_read_b64_tr_b4 v[52:53], v160 offset:1152
	ds_read_b64_tr_b4 v[130:131], v54
	ds_read_b64_tr_b4 v[132:133], v55
	ds_read_b64_tr_b4 v[134:135], v56
	ds_read_b64_tr_b4 v[136:137], v57
	s_waitcnt lgkmcnt(13)
; #define TR4(p_) __builtin_amdgcn_ds_read_tr4_b64_v2i32((LAS v2i*)(p_))
; #define VDMA(st_, k_) do { _Pragma("unroll") for (int i_ = 0; i_ < 4; ++i_) { \
;         const unsigned off_ = (unsigned)((st_) >> 2) * (16384u * 128u) + (PE_ID(E, 4 * ((st_) & 3) + i_) << 7) + ((i_ & 1) ? cx1 : cx0); \
;         __builtin_amdgcn_global_load_lds((const unsigned*)(V4 + off_), (LAS unsigned*)(ldsb + BUF[k_] + 1024 * i_), 16, 0, 0); } } while (0)
; __device__ __forceinline__ void peer_v_tokens(int j, const LAS unsigned short* EL, const LAS unsigned char* AL  , const LAS float* ASC  , const LAS int* SAL  , ...
;     ...
;         for (int st = 0; st < 16; ++st) {
;             const int p = st >> 2, q = st & 3;
;             if (st < 14) VDMA(st + 2, (st + 2) % 3);
;             if (st < 14) asm volatile("s_waitcnt vmcnt(8)" ::: "memory");
;             else if (st == 14) asm volatile("s_waitcnt vmcnt(4)" ::: "memory");
;             else asm volatile("s_waitcnt vmcnt(0)" ::: "memory");
;             if (q == 0) {
; #pragma unroll
;                 for (int r = 0; r < 4; ++r) { accH[r] = 0; accL[r] = 0; } }
; #pragma unroll
;             for (int tp = 0; tp < 2; ++tp) {
;                 const v2i ao = TR4(ATL + (2 * q + tp) * 128 + 8 * s16), ah = TR4(ATL + 1024 + (2 * q + tp) * 128 + 8 * s16);
; #pragma unroll
;                 for (int r = 0; r < 4; ++r) {
;                     const v2i d = TR4(ldsb + BUF[st % 3] + 2048 * tp + roff[r]);
;                     accH[r] = __builtin_amdgcn_sdot8(d.x, ah.x, accH[r], false); accH[r] = __builtin_amdgcn_sdot8(d.y, ah.y, accH[r], false);
;                     accL[r] = __builtin_amdgcn_sdot8(d.x, ao.x, accL[r], false); accL[r] = __builtin_amdgcn_sdot8(d.y, ao.y, accL[r], false);
;                 }
;             }
;             asm volatile("s_waitcnt lgkmcnt(0)" ::: "memory");
	v_dot8c_i32_i4_e32 v38, v122, v48
	v_dot8c_i32_i4_e32 v39, v122, v46
	v_dot8c_i32_i4_e32 v40, v124, v48
	v_dot8c_i32_i4_e32 v41, v124, v46
	v_dot8c_i32_i4_e32 v42, v126, v48
	v_dot8c_i32_i4_e32 v43, v126, v46
	v_dot8c_i32_i4_e32 v44, v128, v48
	v_dot8c_i32_i4_e32 v45, v128, v46
	v_dot8c_i32_i4_e32 v38, v123, v49
	v_dot8c_i32_i4_e32 v39, v123, v47
	v_dot8c_i32_i4_e32 v40, v125, v49
	v_dot8c_i32_i4_e32 v41, v125, v47
	v_dot8c_i32_i4_e32 v42, v127, v49
	v_dot8c_i32_i4_e32 v43, v127, v47
	v_dot8c_i32_i4_e32 v44, v129, v49
	v_dot8c_i32_i4_e32 v45, v129, v47
	v_and_b32_e32 v78, 0xffff, v24
	v_lshrrev_b32_e32 v79, 16, v24
	v_lshl_add_u32 v78, v78, 7, v152
	v_lshl_add_u32 v79, v79, 7, v153
	s_mov_b32 m0, s76
	s_add_i32 s43, s76, 0x400
	global_load_lds_dwordx4 v78, s[50:51]
	s_mov_b32 m0, s43
	s_nop 0
	global_load_lds_dwordx4 v79, s[50:51]
	s_waitcnt vmcnt(9)
	v_add_u32_e32 v54, s78, v59
	v_add_u32_e32 v55, s78, v60
	v_add_u32_e32 v56, s78, v61
	v_add_u32_e32 v57, s78, v62
	ds_read_b64_tr_b4 v[46:47], v160 offset:256
	ds_read_b64_tr_b4 v[48:49], v160 offset:1280
	ds_read_b64_tr_b4 v[122:123], v54
	ds_read_b64_tr_b4 v[124:125], v55
	ds_read_b64_tr_b4 v[126:127], v56
	ds_read_b64_tr_b4 v[128:129], v57
	s_waitcnt lgkmcnt(6)
	v_dot8c_i32_i4_e32 v38, v130, v52
	v_dot8c_i32_i4_e32 v39, v130, v50
	v_dot8c_i32_i4_e32 v40, v132, v52
	v_dot8c_i32_i4_e32 v41, v132, v50
	v_dot8c_i32_i4_e32 v42, v134, v52
	v_dot8c_i32_i4_e32 v43, v134, v50
	v_dot8c_i32_i4_e32 v44, v136, v52
	v_dot8c_i32_i4_e32 v45, v136, v50
	v_dot8c_i32_i4_e32 v38, v131, v53
	v_dot8c_i32_i4_e32 v39, v131, v51
	v_dot8c_i32_i4_e32 v40, v133, v53
	v_dot8c_i32_i4_e32 v41, v133, v51
	v_dot8c_i32_i4_e32 v42, v135, v53
	v_dot8c_i32_i4_e32 v43, v135, v51
	v_dot8c_i32_i4_e32 v44, v137, v53
	v_dot8c_i32_i4_e32 v45, v137, v51
	v_and_b32_e32 v78, 0xffff, v25
	v_lshrrev_b32_e32 v79, 16, v25
	v_lshl_add_u32 v78, v78, 7, v152
	v_lshl_add_u32 v79, v79, 7, v153
	s_mov_b32 m0, s77
	s_add_i32 s43, s77, 0x400
	global_load_lds_dwordx4 v78, s[50:51]
	s_mov_b32 m0, s43
	s_nop 0
	global_load_lds_dwordx4 v79, s[50:51]
	s_waitcnt vmcnt(9)
	v_add_u32_e32 v54, s79, v59
	v_add_u32_e32 v55, s79, v60
	v_add_u32_e32 v56, s79, v61
	v_add_u32_e32 v57, s79, v62
	ds_read_b64_tr_b4 v[50:51], v160 offset:384
	ds_read_b64_tr_b4 v[52:53], v160 offset:1408
	ds_read_b64_tr_b4 v[130:131], v54
	ds_read_b64_tr_b4 v[132:133], v55
	ds_read_b64_tr_b4 v[134:135], v56
	ds_read_b64_tr_b4 v[136:137], v57
	s_waitcnt lgkmcnt(6)
	v_dot8c_i32_i4_e32 v38, v122, v48
	v_dot8c_i32_i4_e32 v39, v122, v46
	v_dot8c_i32_i4_e32 v40, v124, v48
	v_dot8c_i32_i4_e32 v41, v124, v46
	v_dot8c_i32_i4_e32 v42, v126, v48
	v_dot8c_i32_i4_e32 v43, v126, v46
	v_dot8c_i32_i4_e32 v44, v128, v48
	v_dot8c_i32_i4_e32 v45, v128, v46
	v_dot8c_i32_i4_e32 v38, v123, v49
	v_dot8c_i32_i4_e32 v39, v123, v47
	v_dot8c_i32_i4_e32 v40, v125, v49
	v_dot8c_i32_i4_e32 v41, v125, v47
	v_dot8c_i32_i4_e32 v42, v127, v49
	v_dot8c_i32_i4_e32 v43, v127, v47
	v_dot8c_i32_i4_e32 v44, v129, v49
	v_dot8c_i32_i4_e32 v45, v129, v47
	s_waitcnt lgkmcnt(15)
	v_and_b32_e32 v78, 0xffff, v26
	v_lshrrev_b32_e32 v79, 16, v26
	v_lshl_add_u32 v78, v78, 7, v152
	v_lshl_add_u32 v79, v79, 7, v153
	s_mov_b32 m0, s78
	s_add_i32 s43, s78, 0x400
	global_load_lds_dwordx4 v78, s[50:51]
	s_mov_b32 m0, s43
	s_nop 0
	global_load_lds_dwordx4 v79, s[50:51]
	s_waitcnt vmcnt(9)
	v_add_u32_e32 v54, s98, v59
	v_add_u32_e32 v55, s98, v60
	v_add_u32_e32 v56, s98, v61
	v_add_u32_e32 v57, s98, v62
	ds_read_b64_tr_b4 v[46:47], v160 offset:512
	ds_read_b64_tr_b4 v[48:49], v160 offset:1536
	ds_read_b64_tr_b4 v[122:123], v54
	ds_read_b64_tr_b4 v[124:125], v55
	ds_read_b64_tr_b4 v[126:127], v56
	ds_read_b64_tr_b4 v[128:129], v57
	s_waitcnt lgkmcnt(6)
	v_dot8c_i32_i4_e32 v38, v130, v52
	v_dot8c_i32_i4_e32 v39, v130, v50
	v_dot8c_i32_i4_e32 v40, v132, v52
	v_dot8c_i32_i4_e32 v41, v132, v50
	v_dot8c_i32_i4_e32 v42, v134, v52
	v_dot8c_i32_i4_e32 v43, v134, v50
	v_dot8c_i32_i4_e32 v44, v136, v52
	v_dot8c_i32_i4_e32 v45, v136, v50
	v_dot8c_i32_i4_e32 v38, v131, v53
	v_dot8c_i32_i4_e32 v39, v131, v51
	v_dot8c_i32_i4_e32 v40, v133, v53
	v_dot8c_i32_i4_e32 v41, v133, v51
	v_dot8c_i32_i4_e32 v42, v135, v53
	v_dot8c_i32_i4_e32 v43, v135, v51
	v_dot8c_i32_i4_e32 v44, v137, v53
	v_dot8c_i32_i4_e32 v45, v137, v51
	v_and_b32_e32 v78, 0xffff, v27
	v_lshrrev_b32_e32 v79, 16, v27
	v_lshl_add_u32 v78, v78, 7, v152
	v_lshl_add_u32 v79, v79, 7, v153
	s_mov_b32 m0, s79
	s_add_i32 s43, s79, 0x400
	global_load_lds_dwordx4 v78, s[50:51]
	s_mov_b32 m0, s43
	s_nop 0
	global_load_lds_dwordx4 v79, s[50:51]
	s_waitcnt vmcnt(8)
	v_add_u32_e32 v54, s99, v59
	v_add_u32_e32 v55, s99, v60
	v_add_u32_e32 v56, s99, v61
	v_add_u32_e32 v57, s99, v62
	ds_read_b64_tr_b4 v[50:51], v160 offset:640
	ds_read_b64_tr_b4 v[52:53], v160 offset:1664
	ds_read_b64_tr_b4 v[130:131], v54
	ds_read_b64_tr_b4 v[132:133], v55
	ds_read_b64_tr_b4 v[134:135], v56
	ds_read_b64_tr_b4 v[136:137], v57
	s_waitcnt lgkmcnt(6)
	v_dot8c_i32_i4_e32 v38, v122, v48
	v_dot8c_i32_i4_e32 v39, v122, v46
	v_dot8c_i32_i4_e32 v40, v124, v48
	v_dot8c_i32_i4_e32 v41, v124, v46
	v_dot8c_i32_i4_e32 v42, v126, v48
	v_dot8c_i32_i4_e32 v43, v126, v46
	v_dot8c_i32_i4_e32 v44, v128, v48
	v_dot8c_i32_i4_e32 v45, v128, v46
	v_dot8c_i32_i4_e32 v38, v123, v49
	v_dot8c_i32_i4_e32 v39, v123, v47
	v_dot8c_i32_i4_e32 v40, v125, v49
	v_dot8c_i32_i4_e32 v41, v125, v47
	v_dot8c_i32_i4_e32 v42, v127, v49
	v_dot8c_i32_i4_e32 v43, v127, v47
	v_dot8c_i32_i4_e32 v44, v129, v49
	v_dot8c_i32_i4_e32 v45, v129, v47
	s_waitcnt lgkmcnt(15)
; __device__ __forceinline__ bf16 f2bf(float f) { return (bf16)f2bfu(f); }
; #define TR4(p_) __builtin_amdgcn_ds_read_tr4_b64_v2i32((LAS v2i*)(p_))
; #define VDMA(st_, k_) do { _Pragma("unroll") for (int i_ = 0; i_ < 4; ++i_) { \
;         const unsigned off_ = (unsigned)((st_) >> 2) * (16384u * 128u) + (PE_ID(E, 4 * ((st_) & 3) + i_) << 7) + ((i_ & 1) ? cx1 : cx0); \
;         __builtin_amdgcn_global_load_lds((const unsigned*)(V4 + off_), (LAS unsigned*)(ldsb + BUF[k_] + 1024 * i_), 16, 0, 0); } } while (0)
; __device__ __forceinline__ void peer_v_tokens(int j, const LAS unsigned short* EL, const LAS unsigned char* AL  , const LAS float* ASC  , const LAS int* SAL  , ...
;     ...
;         for (int st = 0; st < 16; ++st) {
;             const int p = st >> 2, q = st & 3;
;             if (st < 14) VDMA(st + 2, (st + 2) % 3);
;             if (st < 14) asm volatile("s_waitcnt vmcnt(8)" ::: "memory");
;             else if (st == 14) asm volatile("s_waitcnt vmcnt(4)" ::: "memory");
;             else asm volatile("s_waitcnt vmcnt(0)" ::: "memory");
;             if (q == 0) {
; #pragma unroll
;                 for (int r = 0; r < 4; ++r) { accH[r] = 0; accL[r] = 0; } }
; #pragma unroll
;             for (int tp = 0; tp < 2; ++tp) {
;                 const v2i ao = TR4(ATL + (2 * q + tp) * 128 + 8 * s16), ah = TR4(ATL + 1024 + (2 * q + tp) * 128 + 8 * s16);
; #pragma unroll
;                 for (int r = 0; r < 4; ++r) {
;                     const v2i d = TR4(ldsb + BUF[st % 3] + 2048 * tp + roff[r]);
;                     accH[r] = __builtin_amdgcn_sdot8(d.x, ah.x, accH[r], false); accH[r] = __builtin_amdgcn_sdot8(d.y, ah.y, accH[r], false);
;                     accL[r] = __builtin_amdgcn_sdot8(d.x, ao.x, accL[r], false); accL[r] = __builtin_amdgcn_sdot8(d.y, ao.y, accL[r], false);
;                 }
;             }
;             asm volatile("s_waitcnt lgkmcnt(0)" ::: "memory");
;             if (q == 3) {
; #pragma unroll
;                 for (int r = 0; r < 4; ++r) STASH[256 * p + 16 * (grp + 4 * r) + pc] = f2bf(asc * (float)(2 * ((accH[r] << 4) + accL[r]) + sa));
;             }
;         }
	v_add_u32_e32 v143, 8, v139
	v_and_b32_e32 v142, 15, v143
	v_xor_b32_e32 v142, 8, v142
	v_bfe_u32 v144, v143, 4, 4
	v_mul_lo_u32 v142, v142, s92
	v_mul_lo_u32 v144, v144, s92
	v_mov_b32_e32 v143, v142
	v_mov_b32_e32 v145, v144
	ds_write2st64_b64 v159, v[142:143], v[144:145] offset1:2
	v_and_b32_e32 v78, 0xffff, v28
	v_lshrrev_b32_e32 v79, 16, v28
	v_lshl_add_u32 v78, v78, 7, v152
	v_lshl_add_u32 v79, v79, 7, v153
	s_mov_b32 m0, s98
	s_add_i32 s43, s98, 0x400
	global_load_lds_dwordx4 v78, s[50:51]
	s_mov_b32 m0, s43
	s_nop 0
	global_load_lds_dwordx4 v79, s[50:51]
	s_waitcnt vmcnt(8)
	v_add_u32_e32 v54, s76, v59
	v_add_u32_e32 v55, s76, v60
	v_add_u32_e32 v56, s76, v61
	v_add_u32_e32 v57, s76, v62
	ds_read_b64_tr_b4 v[46:47], v160 offset:768
	ds_read_b64_tr_b4 v[48:49], v160 offset:1792
	ds_read_b64_tr_b4 v[122:123], v54
	ds_read_b64_tr_b4 v[124:125], v55
	ds_read_b64_tr_b4 v[126:127], v56
	ds_read_b64_tr_b4 v[128:129], v57
	s_waitcnt lgkmcnt(7)
	v_dot8c_i32_i4_e32 v38, v130, v52
	v_dot8c_i32_i4_e32 v39, v130, v50
	v_dot8c_i32_i4_e32 v40, v132, v52
	v_dot8c_i32_i4_e32 v41, v132, v50
	v_dot8c_i32_i4_e32 v42, v134, v52
	v_dot8c_i32_i4_e32 v43, v134, v50
	v_dot8c_i32_i4_e32 v44, v136, v52
	v_dot8c_i32_i4_e32 v45, v136, v50
	v_dot8c_i32_i4_e32 v38, v131, v53
	v_dot8c_i32_i4_e32 v39, v131, v51
	v_dot8c_i32_i4_e32 v40, v133, v53
	v_dot8c_i32_i4_e32 v41, v133, v51
	v_dot8c_i32_i4_e32 v42, v135, v53
	v_dot8c_i32_i4_e32 v43, v135, v51
	v_dot8c_i32_i4_e32 v44, v137, v53
	v_dot8c_i32_i4_e32 v45, v137, v51
	v_and_b32_e32 v78, 0xffff, v29
	v_lshrrev_b32_e32 v79, 16, v29
	v_lshl_add_u32 v78, v78, 7, v152
	v_lshl_add_u32 v79, v79, 7, v153
	s_mov_b32 m0, s99
	s_add_i32 s43, s99, 0x400
	global_load_lds_dwordx4 v78, s[50:51]
	s_mov_b32 m0, s43
	s_nop 0
	global_load_lds_dwordx4 v79, s[50:51]
	s_waitcnt vmcnt(8)
	v_add_u32_e32 v54, s77, v59
	v_add_u32_e32 v55, s77, v60
	v_add_u32_e32 v56, s77, v61
	v_add_u32_e32 v57, s77, v62
	ds_read_b64_tr_b4 v[50:51], v160 offset:896
	ds_read_b64_tr_b4 v[52:53], v160 offset:1920
	ds_read_b64_tr_b4 v[130:131], v54
	ds_read_b64_tr_b4 v[132:133], v55
	ds_read_b64_tr_b4 v[134:135], v56
	ds_read_b64_tr_b4 v[136:137], v57
	s_waitcnt lgkmcnt(6)
	v_dot8c_i32_i4_e32 v38, v122, v48
	v_dot8c_i32_i4_e32 v39, v122, v46
	v_dot8c_i32_i4_e32 v40, v124, v48
	v_dot8c_i32_i4_e32 v41, v124, v46
	v_dot8c_i32_i4_e32 v42, v126, v48
	v_dot8c_i32_i4_e32 v43, v126, v46
	v_dot8c_i32_i4_e32 v44, v128, v48
	v_dot8c_i32_i4_e32 v45, v128, v46
	v_dot8c_i32_i4_e32 v38, v123, v49
	v_dot8c_i32_i4_e32 v39, v123, v47
	v_dot8c_i32_i4_e32 v40, v125, v49
	v_dot8c_i32_i4_e32 v41, v125, v47
	v_dot8c_i32_i4_e32 v42, v127, v49
	v_dot8c_i32_i4_e32 v43, v127, v47
	v_dot8c_i32_i4_e32 v44, v129, v49
	v_dot8c_i32_i4_e32 v45, v129, v47
	v_and_b32_e32 v78, 0xffff, v30
	v_lshrrev_b32_e32 v79, 16, v30
	v_lshl_add_u32 v78, v78, 7, v152
	v_lshl_add_u32 v79, v79, 7, v153
	s_mov_b32 m0, s76
	s_add_i32 s43, s76, 0x400
	global_load_lds_dwordx4 v78, s[50:51]
	s_mov_b32 m0, s43
	s_nop 0
	global_load_lds_dwordx4 v79, s[50:51]
	s_waitcnt vmcnt(8)
	v_add_u32_e32 v54, s78, v59
	v_add_u32_e32 v55, s78, v60
	v_add_u32_e32 v56, s78, v61
	v_add_u32_e32 v57, s78, v62
	ds_read_b64_tr_b4 v[46:47], v160
	ds_read_b64_tr_b4 v[48:49], v160 offset:1024
	ds_read_b64_tr_b4 v[122:123], v54
	ds_read_b64_tr_b4 v[124:125], v55
	ds_read_b64_tr_b4 v[126:127], v56
	ds_read_b64_tr_b4 v[128:129], v57
	s_waitcnt lgkmcnt(6)
	v_dot8c_i32_i4_e32 v38, v130, v52
	v_dot8c_i32_i4_e32 v39, v130, v50
	v_dot8c_i32_i4_e32 v40, v132, v52
	v_dot8c_i32_i4_e32 v41, v132, v50
	v_dot8c_i32_i4_e32 v42, v134, v52
	v_dot8c_i32_i4_e32 v43, v134, v50
	v_dot8c_i32_i4_e32 v44, v136, v52
	v_dot8c_i32_i4_e32 v45, v136, v50
	v_dot8c_i32_i4_e32 v38, v131, v53
	v_dot8c_i32_i4_e32 v39, v131, v51
	v_dot8c_i32_i4_e32 v40, v133, v53
	v_dot8c_i32_i4_e32 v41, v133, v51
	v_dot8c_i32_i4_e32 v42, v135, v53
	v_dot8c_i32_i4_e32 v43, v135, v51
	v_dot8c_i32_i4_e32 v44, v137, v53
	v_dot8c_i32_i4_e32 v45, v137, v51
	s_nop 3
	s_waitcnt lgkmcnt(15)
	v_lshlrev_b32_e32 v38, 5, v38
	v_lshlrev_b32_e32 v39, 1, v39
	v_add3_u32 v38, v39, v229, v38
	v_cvt_f32_i32_e32 v38, v38
	v_mul_f32_e32 v38, v228, v38
	v_lshlrev_b32_e32 v40, 5, v40
	v_lshlrev_b32_e32 v41, 1, v41
	v_add3_u32 v40, v41, v229, v40
	v_cvt_f32_i32_e32 v40, v40
	v_mul_f32_e32 v40, v228, v40
	v_lshlrev_b32_e32 v42, 5, v42
	v_lshlrev_b32_e32 v43, 1, v43
	v_add3_u32 v42, v43, v229, v42
	v_cvt_f32_i32_e32 v42, v42
	v_mul_f32_e32 v42, v228, v42
	v_lshlrev_b32_e32 v44, 5, v44
	v_lshlrev_b32_e32 v45, 1, v45
	v_add3_u32 v44, v45, v229, v44
	v_cvt_f32_i32_e32 v44, v44
	v_mul_f32_e32 v44, v228, v44
	v_cvt_pk_bf16_f32 v184, v38, v40
	v_cvt_pk_bf16_f32 v185, v42, v44
	ds_read_b128 v[252:255], v156
	s_add_i32 s44, s40, 40
	s_ashr_i32 s45, s44, 31
	s_lshl_b64 s[44:45], s[44:45], 12
	v_lshl_add_u64 v[80:81], v[36:37], 0, s[44:45]
	s_waitcnt lgkmcnt(0)
; #define TR4(p_) __builtin_amdgcn_ds_read_tr4_b64_v2i32((LAS v2i*)(p_))
; #define VDMA(st_, k_) do { _Pragma("unroll") for (int i_ = 0; i_ < 4; ++i_) { \
;         const unsigned off_ = (unsigned)((st_) >> 2) * (16384u * 128u) + (PE_ID(E, 4 * ((st_) & 3) + i_) << 7) + ((i_ & 1) ? cx1 : cx0); \
;         __builtin_amdgcn_global_load_lds((const unsigned*)(V4 + off_), (LAS unsigned*)(ldsb + BUF[k_] + 1024 * i_), 16, 0, 0); } } while (0)
; __device__ __forceinline__ void peer_v_tokens(int j, const LAS unsigned short* EL, const LAS unsigned char* AL  , const LAS float* ASC  , const LAS int* SAL  , ...
;     ...
;         { unsigned ho = (unsigned)t * (D / 4) + (unsigned)lane; asm volatile("" : "+v"(ho)); const uint2* hp = (const uint2*)HB + ho; const float4* gp = (const float4*)fng + lane;
; #pragma unroll
;           for (int jq = 0; jq < 4; ++jq) { hv[jq] = hp[64 * jq]; gv[jq] = gp[64 * jq]; } }
;     ...
;         for (int st = 0; st < 16; ++st) {
;             const int p = st >> 2, q = st & 3;
;             if (st < 14) VDMA(st + 2, (st + 2) % 3);
;             if (st < 14) asm volatile("s_waitcnt vmcnt(8)" ::: "memory");
;             else if (st == 14) asm volatile("s_waitcnt vmcnt(4)" ::: "memory");
;             else asm volatile("s_waitcnt vmcnt(0)" ::: "memory");
;             if (q == 0) {
; #pragma unroll
;                 for (int r = 0; r < 4; ++r) { accH[r] = 0; accL[r] = 0; } }
; #pragma unroll
;             for (int tp = 0; tp < 2; ++tp) {
;                 const v2i ao = TR4(ATL + (2 * q + tp) * 128 + 8 * s16), ah = TR4(ATL + 1024 + (2 * q + tp) * 128 + 8 * s16);
; #pragma unroll
;                 for (int r = 0; r < 4; ++r) {
;                     const v2i d = TR4(ldsb + BUF[st % 3] + 2048 * tp + roff[r]);
;                     accH[r] = __builtin_amdgcn_sdot8(d.x, ah.x, accH[r], false); accH[r] = __builtin_amdgcn_sdot8(d.y, ah.y, accH[r], false);
;                     accL[r] = __builtin_amdgcn_sdot8(d.x, ao.x, accL[r], false); accL[r] = __builtin_amdgcn_sdot8(d.y, ao.y, accL[r], false);
;                 }
;             }
;             asm volatile("s_waitcnt lgkmcnt(0)" ::: "memory");
	v_mul_f32_e32 v244, v244, v252
	v_mul_f32_e32 v245, v245, v253
	v_mul_f32_e32 v246, v246, v254
	v_mul_f32_e32 v247, v247, v255
	global_store_dwordx4 v[80:81], v[244:247], off offset:2048 nt
	s_add_i32 s43, s40, 48
	s_lshl_b32 s43, s43, 11
	v_add_u32_e32 v138, s43, v66
	global_load_dwordx2 v[194:195], v138, s[70:71]
	global_load_dwordx2 v[196:197], v138, s[70:71] offset:512
	global_load_dwordx2 v[198:199], v138, s[70:71] offset:1024
	global_load_dwordx2 v[200:201], v138, s[70:71] offset:1536
	s_add_i32 s43, s40, 56
	s_lshl_b32 s43, s43, 11
	v_add_u32_e32 v138, s43, v66
	global_load_dwordx2 v[18:19], v138, s[70:71]
	global_load_dwordx2 v[20:21], v138, s[70:71] offset:512
	global_load_dwordx2 v[22:23], v138, s[70:71] offset:1024
	global_load_dwordx2 v[24:25], v138, s[70:71] offset:1536
	v_add_u32_e32 v147, 8, v140
	v_and_b32_e32 v146, 15, v147
	v_xor_b32_e32 v146, 8, v146
	v_bfe_u32 v148, v147, 4, 4
	v_mul_lo_u32 v146, v146, s92
	v_mul_lo_u32 v148, v148, s92
	v_mov_b32_e32 v147, v146
	v_mov_b32_e32 v149, v148
	ds_write2st64_b64 v77, v[146:147], v[148:149] offset1:2
	s_add_i32 s43, s67, 224
	v_mov_b32_e32 v138, s43
	ds_read2st64_b32 v[228:229], v138 offset1:1
	v_mov_b32_e32 v38, 0
	v_mov_b32_e32 v39, 0
	v_mov_b32_e32 v40, 0
	v_mov_b32_e32 v41, 0
	v_mov_b32_e32 v42, 0
	v_mov_b32_e32 v43, 0
	v_mov_b32_e32 v44, 0
	v_mov_b32_e32 v45, 0
	v_and_b32_e32 v78, 0xffff, v31
	v_lshrrev_b32_e32 v79, 16, v31
	v_lshl_add_u32 v78, v78, 7, v152
	v_lshl_add_u32 v79, v79, 7, v153
	s_mov_b32 m0, s77
	s_add_i32 s43, s77, 0x400
	global_load_lds_dwordx4 v78, s[50:51]
	s_mov_b32 m0, s43
	s_nop 0
	global_load_lds_dwordx4 v79, s[50:51]
	s_waitcnt vmcnt(17)
	v_add_u32_e32 v54, s79, v59
	v_add_u32_e32 v55, s79, v60
	v_add_u32_e32 v56, s79, v61
	v_add_u32_e32 v57, s79, v62
	ds_read_b64_tr_b4 v[50:51], v160 offset:128
	ds_read_b64_tr_b4 v[52:53], v160 offset:1152
	ds_read_b64_tr_b4 v[130:131], v54
	ds_read_b64_tr_b4 v[132:133], v55
	ds_read_b64_tr_b4 v[134:135], v56
	ds_read_b64_tr_b4 v[136:137], v57
	s_waitcnt lgkmcnt(9)
	v_dot8c_i32_i4_e32 v38, v122, v48
	v_dot8c_i32_i4_e32 v39, v122, v46
	v_dot8c_i32_i4_e32 v40, v124, v48
	v_dot8c_i32_i4_e32 v41, v124, v46
	v_dot8c_i32_i4_e32 v42, v126, v48
	v_dot8c_i32_i4_e32 v43, v126, v46
	v_dot8c_i32_i4_e32 v44, v128, v48
	v_dot8c_i32_i4_e32 v45, v128, v46
	v_dot8c_i32_i4_e32 v38, v123, v49
	v_dot8c_i32_i4_e32 v39, v123, v47
	v_dot8c_i32_i4_e32 v40, v125, v49
	v_dot8c_i32_i4_e32 v41, v125, v47
	v_dot8c_i32_i4_e32 v42, v127, v49
	v_dot8c_i32_i4_e32 v43, v127, v47
	v_dot8c_i32_i4_e32 v44, v129, v49
	v_dot8c_i32_i4_e32 v45, v129, v47
	v_and_b32_e32 v78, 0xffff, v32
	v_lshrrev_b32_e32 v79, 16, v32
	v_lshl_add_u32 v78, v78, 7, v152
	v_lshl_add_u32 v79, v79, 7, v153
	s_mov_b32 m0, s78
	s_add_i32 s43, s78, 0x400
	global_load_lds_dwordx4 v78, s[50:51]
	s_mov_b32 m0, s43
	s_nop 0
	global_load_lds_dwordx4 v79, s[50:51]
	s_waitcnt vmcnt(17)
	v_add_u32_e32 v54, s98, v59
	v_add_u32_e32 v55, s98, v60
	v_add_u32_e32 v56, s98, v61
	v_add_u32_e32 v57, s98, v62
	ds_read_b64_tr_b4 v[46:47], v160 offset:256
	ds_read_b64_tr_b4 v[48:49], v160 offset:1280
	ds_read_b64_tr_b4 v[122:123], v54
	ds_read_b64_tr_b4 v[124:125], v55
	ds_read_b64_tr_b4 v[126:127], v56
	ds_read_b64_tr_b4 v[128:129], v57
	s_waitcnt lgkmcnt(6)
	v_dot8c_i32_i4_e32 v38, v130, v52
	v_dot8c_i32_i4_e32 v39, v130, v50
	v_dot8c_i32_i4_e32 v40, v132, v52
	v_dot8c_i32_i4_e32 v41, v132, v50
	v_dot8c_i32_i4_e32 v42, v134, v52
	v_dot8c_i32_i4_e32 v43, v134, v50
	v_dot8c_i32_i4_e32 v44, v136, v52
	v_dot8c_i32_i4_e32 v45, v136, v50
	v_dot8c_i32_i4_e32 v38, v131, v53
	v_dot8c_i32_i4_e32 v39, v131, v51
	v_dot8c_i32_i4_e32 v40, v133, v53
	v_dot8c_i32_i4_e32 v41, v133, v51
	v_dot8c_i32_i4_e32 v42, v135, v53
	v_dot8c_i32_i4_e32 v43, v135, v51
	v_dot8c_i32_i4_e32 v44, v137, v53
	v_dot8c_i32_i4_e32 v45, v137, v51
	v_and_b32_e32 v78, 0xffff, v33
	v_lshrrev_b32_e32 v79, 16, v33
	v_lshl_add_u32 v78, v78, 7, v152
	v_lshl_add_u32 v79, v79, 7, v153
	s_mov_b32 m0, s79
	s_add_i32 s43, s79, 0x400
	global_load_lds_dwordx4 v78, s[50:51]
	s_mov_b32 m0, s43
	s_nop 0
	global_load_lds_dwordx4 v79, s[50:51]
	s_waitcnt vmcnt(17)
	v_add_u32_e32 v54, s99, v59
	v_add_u32_e32 v55, s99, v60
	v_add_u32_e32 v56, s99, v61
	v_add_u32_e32 v57, s99, v62
	ds_read_b64_tr_b4 v[50:51], v160 offset:384
	ds_read_b64_tr_b4 v[52:53], v160 offset:1408
	ds_read_b64_tr_b4 v[130:131], v54
	ds_read_b64_tr_b4 v[132:133], v55
	ds_read_b64_tr_b4 v[134:135], v56
	ds_read_b64_tr_b4 v[136:137], v57
	s_waitcnt lgkmcnt(6)
	v_dot8c_i32_i4_e32 v38, v122, v48
	v_dot8c_i32_i4_e32 v39, v122, v46
	v_dot8c_i32_i4_e32 v40, v124, v48
	v_dot8c_i32_i4_e32 v41, v124, v46
	v_dot8c_i32_i4_e32 v42, v126, v48
	v_dot8c_i32_i4_e32 v43, v126, v46
	v_dot8c_i32_i4_e32 v44, v128, v48
	v_dot8c_i32_i4_e32 v45, v128, v46
	v_dot8c_i32_i4_e32 v38, v123, v49
	v_dot8c_i32_i4_e32 v39, v123, v47
	v_dot8c_i32_i4_e32 v40, v125, v49
	v_dot8c_i32_i4_e32 v41, v125, v47
	v_dot8c_i32_i4_e32 v42, v127, v49
	v_dot8c_i32_i4_e32 v43, v127, v47
	v_dot8c_i32_i4_e32 v44, v129, v49
	v_dot8c_i32_i4_e32 v45, v129, v47
	s_waitcnt vmcnt(15)
	v_add_u32_e32 v54, s76, v59
	v_add_u32_e32 v55, s76, v60
	v_add_u32_e32 v56, s76, v61
	v_add_u32_e32 v57, s76, v62
	ds_read_b64_tr_b4 v[46:47], v160 offset:512
	ds_read_b64_tr_b4 v[48:49], v160 offset:1536
	ds_read_b64_tr_b4 v[122:123], v54
	ds_read_b64_tr_b4 v[124:125], v55
	ds_read_b64_tr_b4 v[126:127], v56
	ds_read_b64_tr_b4 v[128:129], v57
	s_waitcnt lgkmcnt(6)
; #define LAS __attribute__((address_space(3)))
; __device__ __forceinline__ bf16 f2bf(float f) { return (bf16)f2bfu(f); }
; #define TR4(p_) __builtin_amdgcn_ds_read_tr4_b64_v2i32((LAS v2i*)(p_))
; #define CFENCE() asm volatile("" ::: "memory")
; __device__ __forceinline__ void peer_v_tokens(int j, const LAS unsigned short* EL, const LAS unsigned char* AL  , const LAS float* ASC  , const LAS int* SAL  , ...
;     ...
;         for (int st = 0; st < 16; ++st) {
;             const int p = st >> 2, q = st & 3;
;             if (st < 14) VDMA(st + 2, (st + 2) % 3);
;             if (st < 14) asm volatile("s_waitcnt vmcnt(8)" ::: "memory");
;             else if (st == 14) asm volatile("s_waitcnt vmcnt(4)" ::: "memory");
;             else asm volatile("s_waitcnt vmcnt(0)" ::: "memory");
;             if (q == 0) {
; #pragma unroll
;                 for (int r = 0; r < 4; ++r) { accH[r] = 0; accL[r] = 0; } }
; #pragma unroll
;             for (int tp = 0; tp < 2; ++tp) {
;                 const v2i ao = TR4(ATL + (2 * q + tp) * 128 + 8 * s16), ah = TR4(ATL + 1024 + (2 * q + tp) * 128 + 8 * s16);
; #pragma unroll
;                 for (int r = 0; r < 4; ++r) {
;                     const v2i d = TR4(ldsb + BUF[st % 3] + 2048 * tp + roff[r]);
;                     accH[r] = __builtin_amdgcn_sdot8(d.x, ah.x, accH[r], false); accH[r] = __builtin_amdgcn_sdot8(d.y, ah.y, accH[r], false);
;                     accL[r] = __builtin_amdgcn_sdot8(d.x, ao.x, accL[r], false); accL[r] = __builtin_amdgcn_sdot8(d.y, ao.y, accL[r], false);
;                 }
;             }
;             asm volatile("s_waitcnt lgkmcnt(0)" ::: "memory");
;             if (q == 3) {
; #pragma unroll
;                 for (int r = 0; r < 4; ++r) STASH[256 * p + 16 * (grp + 4 * r) + pc] = f2bf(asc * (float)(2 * ((accH[r] << 4) + accL[r]) + sa));
;             }
;         }
;         CFENCE();
;         {
;             float4 v[4]; float ss = 0.f;
; #pragma unroll
;             for (int jq = 0; jq < 4; ++jq) { typedef unsigned u2v __attribute__((ext_vector_type(2))); const u2v pw = *(const LAS u2v*)(STASH + 4 * lane + 256 * jq); const uint2 hw = hv[jq];
	v_dot8c_i32_i4_e32 v38, v130, v52
	v_dot8c_i32_i4_e32 v39, v130, v50
	v_dot8c_i32_i4_e32 v40, v132, v52
	v_dot8c_i32_i4_e32 v41, v132, v50
	v_dot8c_i32_i4_e32 v42, v134, v52
	v_dot8c_i32_i4_e32 v43, v134, v50
	v_dot8c_i32_i4_e32 v44, v136, v52
	v_dot8c_i32_i4_e32 v45, v136, v50
	v_dot8c_i32_i4_e32 v38, v131, v53
	v_dot8c_i32_i4_e32 v39, v131, v51
	v_dot8c_i32_i4_e32 v40, v133, v53
	v_dot8c_i32_i4_e32 v41, v133, v51
	v_dot8c_i32_i4_e32 v42, v135, v53
	v_dot8c_i32_i4_e32 v43, v135, v51
	v_dot8c_i32_i4_e32 v44, v137, v53
	v_dot8c_i32_i4_e32 v45, v137, v51
	s_waitcnt vmcnt(4)
	v_add_u32_e32 v54, s77, v59
	v_add_u32_e32 v55, s77, v60
	v_add_u32_e32 v56, s77, v61
	v_add_u32_e32 v57, s77, v62
	ds_read_b64_tr_b4 v[50:51], v160 offset:640
	ds_read_b64_tr_b4 v[52:53], v160 offset:1664
	ds_read_b64_tr_b4 v[130:131], v54
	ds_read_b64_tr_b4 v[132:133], v55
	ds_read_b64_tr_b4 v[134:135], v56
	ds_read_b64_tr_b4 v[136:137], v57
	s_waitcnt lgkmcnt(6)
	v_dot8c_i32_i4_e32 v38, v122, v48
	v_dot8c_i32_i4_e32 v39, v122, v46
	v_dot8c_i32_i4_e32 v40, v124, v48
	v_dot8c_i32_i4_e32 v41, v124, v46
	v_dot8c_i32_i4_e32 v42, v126, v48
	v_dot8c_i32_i4_e32 v43, v126, v46
	v_dot8c_i32_i4_e32 v44, v128, v48
	v_dot8c_i32_i4_e32 v45, v128, v46
	v_dot8c_i32_i4_e32 v38, v123, v49
	v_dot8c_i32_i4_e32 v39, v123, v47
	v_dot8c_i32_i4_e32 v40, v125, v49
	v_dot8c_i32_i4_e32 v41, v125, v47
	v_dot8c_i32_i4_e32 v42, v127, v49
	v_dot8c_i32_i4_e32 v43, v127, v47
	v_dot8c_i32_i4_e32 v44, v129, v49
	v_dot8c_i32_i4_e32 v45, v129, v47
	s_waitcnt vmcnt(2)
	v_add_u32_e32 v54, s78, v59
	v_add_u32_e32 v55, s78, v60
	v_add_u32_e32 v56, s78, v61
	v_add_u32_e32 v57, s78, v62
	ds_read_b64_tr_b4 v[46:47], v160 offset:768
	ds_read_b64_tr_b4 v[48:49], v160 offset:1792
	ds_read_b64_tr_b4 v[122:123], v54
	ds_read_b64_tr_b4 v[124:125], v55
	ds_read_b64_tr_b4 v[126:127], v56
	ds_read_b64_tr_b4 v[128:129], v57
	s_waitcnt lgkmcnt(6)
	v_dot8c_i32_i4_e32 v38, v130, v52
	v_dot8c_i32_i4_e32 v39, v130, v50
	v_dot8c_i32_i4_e32 v40, v132, v52
	v_dot8c_i32_i4_e32 v41, v132, v50
	v_dot8c_i32_i4_e32 v42, v134, v52
	v_dot8c_i32_i4_e32 v43, v134, v50
	v_dot8c_i32_i4_e32 v44, v136, v52
	v_dot8c_i32_i4_e32 v45, v136, v50
	v_dot8c_i32_i4_e32 v38, v131, v53
	v_dot8c_i32_i4_e32 v39, v131, v51
	v_dot8c_i32_i4_e32 v40, v133, v53
	v_dot8c_i32_i4_e32 v41, v133, v51
	v_dot8c_i32_i4_e32 v42, v135, v53
	v_dot8c_i32_i4_e32 v43, v135, v51
	v_dot8c_i32_i4_e32 v44, v137, v53
	v_dot8c_i32_i4_e32 v45, v137, v51
	s_waitcnt vmcnt(0)
	v_add_u32_e32 v54, s79, v59
	v_add_u32_e32 v55, s79, v60
	v_add_u32_e32 v56, s79, v61
	v_add_u32_e32 v57, s79, v62
	ds_read_b64_tr_b4 v[50:51], v160 offset:896
	ds_read_b64_tr_b4 v[52:53], v160 offset:1920
	ds_read_b64_tr_b4 v[130:131], v54
	ds_read_b64_tr_b4 v[132:133], v55
	ds_read_b64_tr_b4 v[134:135], v56
	ds_read_b64_tr_b4 v[136:137], v57
	s_waitcnt lgkmcnt(6)
	v_dot8c_i32_i4_e32 v38, v122, v48
	v_dot8c_i32_i4_e32 v39, v122, v46
	v_dot8c_i32_i4_e32 v40, v124, v48
	v_dot8c_i32_i4_e32 v41, v124, v46
	v_dot8c_i32_i4_e32 v42, v126, v48
	v_dot8c_i32_i4_e32 v43, v126, v46
	v_dot8c_i32_i4_e32 v44, v128, v48
	v_dot8c_i32_i4_e32 v45, v128, v46
	v_dot8c_i32_i4_e32 v38, v123, v49
	v_dot8c_i32_i4_e32 v39, v123, v47
	v_dot8c_i32_i4_e32 v40, v125, v49
	v_dot8c_i32_i4_e32 v41, v125, v47
	v_dot8c_i32_i4_e32 v42, v127, v49
	v_dot8c_i32_i4_e32 v43, v127, v47
	v_dot8c_i32_i4_e32 v44, v129, v49
	v_dot8c_i32_i4_e32 v45, v129, v47
	s_waitcnt lgkmcnt(0)
	v_dot8c_i32_i4_e32 v38, v130, v52
	v_dot8c_i32_i4_e32 v39, v130, v50
	v_dot8c_i32_i4_e32 v40, v132, v52
	v_dot8c_i32_i4_e32 v41, v132, v50
	v_dot8c_i32_i4_e32 v42, v134, v52
	v_dot8c_i32_i4_e32 v43, v134, v50
	v_dot8c_i32_i4_e32 v44, v136, v52
	v_dot8c_i32_i4_e32 v45, v136, v50
	v_dot8c_i32_i4_e32 v38, v131, v53
	v_dot8c_i32_i4_e32 v39, v131, v51
	v_dot8c_i32_i4_e32 v40, v133, v53
	v_dot8c_i32_i4_e32 v41, v133, v51
	v_dot8c_i32_i4_e32 v42, v135, v53
	v_dot8c_i32_i4_e32 v43, v135, v51
	v_dot8c_i32_i4_e32 v44, v137, v53
	v_dot8c_i32_i4_e32 v45, v137, v51
	s_nop 3
	s_waitcnt lgkmcnt(15)
	v_lshlrev_b32_e32 v38, 5, v38
	v_lshlrev_b32_e32 v39, 1, v39
	v_add3_u32 v38, v39, v229, v38
	v_cvt_f32_i32_e32 v38, v38
	v_mul_f32_e32 v38, v228, v38
	v_lshlrev_b32_e32 v40, 5, v40
	v_lshlrev_b32_e32 v41, 1, v41
	v_add3_u32 v40, v41, v229, v40
	v_cvt_f32_i32_e32 v40, v40
	v_mul_f32_e32 v40, v228, v40
	v_lshlrev_b32_e32 v42, 5, v42
	v_lshlrev_b32_e32 v43, 1, v43
	v_add3_u32 v42, v43, v229, v42
	v_cvt_f32_i32_e32 v42, v42
	v_mul_f32_e32 v42, v228, v42
	v_lshlrev_b32_e32 v44, 5, v44
	v_lshlrev_b32_e32 v45, 1, v45
	v_add3_u32 v44, v45, v229, v44
	v_cvt_f32_i32_e32 v44, v44
	v_mul_f32_e32 v44, v228, v44
	v_cvt_pk_bf16_f32 v192, v38, v40
	v_cvt_pk_bf16_f32 v193, v42, v44
	ds_read_b128 v[252:255], v156 offset:1024
	s_add_i32 s44, s40, 40
	s_ashr_i32 s45, s44, 31
	s_lshl_b64 s[44:45], s[44:45], 12
	v_lshl_add_u64 v[80:81], v[36:37], 0, s[44:45]
	s_waitcnt lgkmcnt(0)
	v_mul_f32_e32 v248, v248, v252
	v_mul_f32_e32 v249, v249, v253
	v_mul_f32_e32 v250, v250, v254
	v_mul_f32_e32 v251, v251, v255
	global_store_dwordx4 v[80:81], v[248:251], off offset:3072 nt
	ds_write_b16 v65, v178
	ds_write_b16_d16_hi v65, v178 offset:128
	ds_write_b16 v65, v179 offset:256
	ds_write_b16_d16_hi v65, v179 offset:384
	ds_write_b16 v65, v180 offset:512
	ds_write_b16_d16_hi v65, v180 offset:640
	ds_write_b16 v65, v181 offset:768
	ds_write_b16_d16_hi v65, v181 offset:896
	ds_write_b16 v65, v182 offset:1024
	ds_write_b16_d16_hi v65, v182 offset:1152
	ds_write_b16 v65, v183 offset:1280
	ds_write_b16_d16_hi v65, v183 offset:1408
	ds_write_b16 v65, v184 offset:1536
	ds_write_b16_d16_hi v65, v184 offset:1664
	ds_write_b16 v65, v185 offset:1792
	ds_write_b16_d16_hi v65, v185 offset:1920
	ds_read_b64 v[202:203], v154
	ds_read_b64 v[204:205], v154 offset:512
	ds_read_b64 v[206:207], v154 offset:1024
	ds_read_b64 v[208:209], v154 offset:1536
	s_waitcnt vmcnt(11) lgkmcnt(0)
; #define LAS __attribute__((address_space(3)))
; __device__ __forceinline__ bf16 f2bf(float f) { return (bf16)f2bfu(f); }
; #define CFENCE() asm volatile("" ::: "memory")
; __device__ __forceinline__ void peer_v_tokens(int j, const LAS unsigned short* EL, const LAS unsigned char* AL  , const LAS float* ASC  , const LAS int* SAL  , ...
;     ...
;                 for (int r = 0; r < 4; ++r) STASH[256 * p + 16 * (grp + 4 * r) + pc] = f2bf(asc * (float)(2 * ((accH[r] << 4) + accL[r]) + sa));
;             }
;         }
;         CFENCE();
;         {
;             float4 v[4]; float ss = 0.f;
; #pragma unroll
;             for (int jq = 0; jq < 4; ++jq) { typedef unsigned u2v __attribute__((ext_vector_type(2))); const u2v pw = *(const LAS u2v*)(STASH + 4 * lane + 256 * jq); const uint2 hw = hv[jq];
;                 v[jq] = make_float4(__uint_as_float(hw.x << 16) + __uint_as_float(pw.x << 16), __uint_as_float(hw.x & 0xffff0000u) + __uint_as_float(pw.x & 0xffff0000u),
;                                     __uint_as_float(hw.y << 16) + __uint_as_float(pw.y << 16), __uint_as_float(hw.y & 0xffff0000u) + __uint_as_float(pw.y & 0xffff0000u));
;                 ss += v[jq].x * v[jq].x + v[jq].y * v[jq].y + v[jq].z * v[jq].z + v[jq].w * v[jq].w; }
;             ss = wave_sum(ss);
;             const float r3 = rsqrtf(ss * (1.f / D) + EPS);
;             float4* op = (float4*)(outp + (size_t)t * D) + lane;
; #pragma unroll
;             for (int jq = 0; jq < 4; ++jq) { typedef float f4v __attribute__((ext_vector_type(4))); f4v o4; o4.x = v[jq].x * r3 * gv[jq].x; o4.y = v[jq].y * r3 * gv[jq].y; o4.z = v[jq].z * r3 * gv[jq].z; o4.w = v[jq].w * r3 * gv[jq].w;
;                 __builtin_nontemporal_store(o4, (f4v*)op + 64 * jq); }
	v_lshlrev_b32_e32 v210, 16, v194
	v_and_b32_e32 v211, 0xffff0000, v194
	v_lshlrev_b32_e32 v142, 16, v202
	v_and_b32_e32 v143, 0xffff0000, v202
	v_add_f32_e32 v210, v210, v142
	v_add_f32_e32 v211, v211, v143
	v_lshlrev_b32_e32 v212, 16, v195
	v_and_b32_e32 v213, 0xffff0000, v195
	v_lshlrev_b32_e32 v142, 16, v203
	v_and_b32_e32 v143, 0xffff0000, v203
	v_add_f32_e32 v212, v212, v142
	v_add_f32_e32 v213, v213, v143
	v_lshlrev_b32_e32 v214, 16, v196
	v_and_b32_e32 v215, 0xffff0000, v196
	v_lshlrev_b32_e32 v142, 16, v204
	v_and_b32_e32 v143, 0xffff0000, v204
	v_add_f32_e32 v214, v214, v142
	v_add_f32_e32 v215, v215, v143
	v_lshlrev_b32_e32 v216, 16, v197
	v_and_b32_e32 v217, 0xffff0000, v197
	v_lshlrev_b32_e32 v142, 16, v205
	v_and_b32_e32 v143, 0xffff0000, v205
	v_add_f32_e32 v216, v216, v142
	v_add_f32_e32 v217, v217, v143
	v_lshlrev_b32_e32 v218, 16, v198
	v_and_b32_e32 v219, 0xffff0000, v198
	v_lshlrev_b32_e32 v142, 16, v206
	v_and_b32_e32 v143, 0xffff0000, v206
	v_add_f32_e32 v218, v218, v142
	v_add_f32_e32 v219, v219, v143
	v_lshlrev_b32_e32 v220, 16, v199
	v_and_b32_e32 v221, 0xffff0000, v199
	v_lshlrev_b32_e32 v142, 16, v207
	v_and_b32_e32 v143, 0xffff0000, v207
	v_add_f32_e32 v220, v220, v142
	v_add_f32_e32 v221, v221, v143
	v_lshlrev_b32_e32 v222, 16, v200
	v_and_b32_e32 v223, 0xffff0000, v200
	v_lshlrev_b32_e32 v142, 16, v208
	v_and_b32_e32 v143, 0xffff0000, v208
	v_add_f32_e32 v222, v222, v142
	v_add_f32_e32 v223, v223, v143
	v_lshlrev_b32_e32 v224, 16, v201
	v_and_b32_e32 v225, 0xffff0000, v201
	v_lshlrev_b32_e32 v142, 16, v209
	v_and_b32_e32 v143, 0xffff0000, v209
	v_add_f32_e32 v224, v224, v142
	v_add_f32_e32 v225, v225, v143
	v_mov_b32_e32 v144, 0
	v_mul_f32_e32 v145, v210, v210
	v_fmac_f32_e32 v145, v211, v211
	v_fmac_f32_e32 v145, v212, v212
	v_fmac_f32_e32 v145, v213, v213
	v_add_f32_e32 v144, v144, v145
	v_mul_f32_e32 v145, v214, v214
	v_fmac_f32_e32 v145, v215, v215
	v_fmac_f32_e32 v145, v216, v216
	v_fmac_f32_e32 v145, v217, v217
	v_add_f32_e32 v144, v144, v145
	v_mul_f32_e32 v145, v218, v218
	v_fmac_f32_e32 v145, v219, v219
	v_fmac_f32_e32 v145, v220, v220
	v_fmac_f32_e32 v145, v221, v221
	v_add_f32_e32 v144, v144, v145
	v_mul_f32_e32 v145, v222, v222
	v_fmac_f32_e32 v145, v223, v223
	v_fmac_f32_e32 v145, v224, v224
	v_fmac_f32_e32 v145, v225, v225
	v_add_f32_e32 v144, v144, v145
	s_nop 1
	v_add_f32_dpp v144, v144, v144 quad_perm:[1,0,3,2] row_mask:0xf bank_mask:0xf bound_ctrl:1
	s_nop 1
	v_add_f32_dpp v144, v144, v144 quad_perm:[2,3,0,1] row_mask:0xf bank_mask:0xf bound_ctrl:1
	s_nop 1
	v_add_f32_dpp v144, v144, v144 row_half_mirror row_mask:0xf bank_mask:0xf bound_ctrl:1
	s_nop 1
	v_add_f32_dpp v144, v144, v144 row_mirror row_mask:0xf bank_mask:0xf bound_ctrl:1
	s_nop 1
	v_readlane_b32 s10, v144, 0
	v_readlane_b32 s11, v144, 16
	v_readlane_b32 s14, v144, 32
	v_readlane_b32 s15, v144, 48
	s_nop 3
	v_mov_b32_e32 v144, s11
	v_mov_b32_e32 v145, s15
	v_add_f32_e32 v144, s10, v144
	v_add_f32_e32 v145, s14, v145
	v_add_f32_e32 v144, v144, v145
	v_fmamk_f32 v144, v144, 0x3a800000, v111
	v_rsq_f32_e32 v144, v144
	s_nop 0
	v_mul_f32_e32 v210, v210, v144
	v_mul_f32_e32 v211, v211, v144
	v_mul_f32_e32 v212, v212, v144
	v_mul_f32_e32 v213, v213, v144
	v_mul_f32_e32 v214, v214, v144
	v_mul_f32_e32 v215, v215, v144
	v_mul_f32_e32 v216, v216, v144
	v_mul_f32_e32 v217, v217, v144
	v_mul_f32_e32 v218, v218, v144
	v_mul_f32_e32 v219, v219, v144
	v_mul_f32_e32 v220, v220, v144
	v_mul_f32_e32 v221, v221, v144
	v_mul_f32_e32 v222, v222, v144
	v_mul_f32_e32 v223, v223, v144
	v_mul_f32_e32 v224, v224, v144
	v_mul_f32_e32 v225, v225, v144
	ds_read_b128 v[252:255], v155
	s_add_i32 s44, s40, 48
	s_ashr_i32 s45, s44, 31
	s_lshl_b64 s[44:45], s[44:45], 12
	v_lshl_add_u64 v[80:81], v[36:37], 0, s[44:45]
	s_waitcnt lgkmcnt(0)
	v_mul_f32_e32 v210, v210, v252
	v_mul_f32_e32 v211, v211, v253
	v_mul_f32_e32 v212, v212, v254
	v_mul_f32_e32 v213, v213, v255
	global_store_dwordx4 v[80:81], v[210:213], off nt
	ds_read_b128 v[252:255], v155 offset:1024
	s_add_i32 s44, s40, 48
	s_ashr_i32 s45, s44, 31
	s_lshl_b64 s[44:45], s[44:45], 12
	v_lshl_add_u64 v[80:81], v[36:37], 0, s[44:45]
	s_waitcnt lgkmcnt(0)
	v_mul_f32_e32 v214, v214, v252
	v_mul_f32_e32 v215, v215, v253
	v_mul_f32_e32 v216, v216, v254
	v_mul_f32_e32 v217, v217, v255
	global_store_dwordx4 v[80:81], v[214:217], off offset:1024 nt
	ds_read_b128 v[252:255], v156
	s_add_i32 s44, s40, 48
	s_ashr_i32 s45, s44, 31
	s_lshl_b64 s[44:45], s[44:45], 12
	v_lshl_add_u64 v[80:81], v[36:37], 0, s[44:45]
	s_waitcnt lgkmcnt(0)
	v_mul_f32_e32 v218, v218, v252
	v_mul_f32_e32 v219, v219, v253
	v_mul_f32_e32 v220, v220, v254
	v_mul_f32_e32 v221, v221, v255
	global_store_dwordx4 v[80:81], v[218:221], off offset:2048 nt
	ds_read_b128 v[252:255], v156 offset:1024
	s_add_i32 s44, s40, 48
	s_ashr_i32 s45, s44, 31
	s_lshl_b64 s[44:45], s[44:45], 12
	v_lshl_add_u64 v[80:81], v[36:37], 0, s[44:45]
	s_waitcnt lgkmcnt(0)
	v_mul_f32_e32 v222, v222, v252
	v_mul_f32_e32 v223, v223, v253
	v_mul_f32_e32 v224, v224, v254
	v_mul_f32_e32 v225, v225, v255
	global_store_dwordx4 v[80:81], v[222:225], off offset:3072 nt
	ds_write_b16 v65, v186
	ds_write_b16_d16_hi v65, v186 offset:128
	ds_write_b16 v65, v187 offset:256
	ds_write_b16_d16_hi v65, v187 offset:384
	ds_write_b16 v65, v188 offset:512
	ds_write_b16_d16_hi v65, v188 offset:640
	ds_write_b16 v65, v189 offset:768
	ds_write_b16_d16_hi v65, v189 offset:896
	ds_write_b16 v65, v190 offset:1024
	ds_write_b16_d16_hi v65, v190 offset:1152
	ds_write_b16 v65, v191 offset:1280
	ds_write_b16_d16_hi v65, v191 offset:1408
	ds_write_b16 v65, v192 offset:1536
	ds_write_b16_d16_hi v65, v192 offset:1664
	ds_write_b16 v65, v193 offset:1792
	ds_write_b16_d16_hi v65, v193 offset:1920
	ds_read_b64 v[202:203], v154
	ds_read_b64 v[204:205], v154 offset:512
	ds_read_b64 v[206:207], v154 offset:1024
	ds_read_b64 v[208:209], v154 offset:1536
	s_waitcnt vmcnt(11) lgkmcnt(0)
; #define LAS __attribute__((address_space(3)))
; __device__ __forceinline__ void peer_v_tokens(int j, const LAS unsigned short* EL, const LAS unsigned char* AL  , const LAS float* ASC  , const LAS int* SAL  , ...
;     ...
;         {
;             float4 v[4]; float ss = 0.f;
; #pragma unroll
;             for (int jq = 0; jq < 4; ++jq) { typedef unsigned u2v __attribute__((ext_vector_type(2))); const u2v pw = *(const LAS u2v*)(STASH + 4 * lane + 256 * jq); const uint2 hw = hv[jq];
;                 v[jq] = make_float4(__uint_as_float(hw.x << 16) + __uint_as_float(pw.x << 16), __uint_as_float(hw.x & 0xffff0000u) + __uint_as_float(pw.x & 0xffff0000u),
;                                     __uint_as_float(hw.y << 16) + __uint_as_float(pw.y << 16), __uint_as_float(hw.y & 0xffff0000u) + __uint_as_float(pw.y & 0xffff0000u));
;                 ss += v[jq].x * v[jq].x + v[jq].y * v[jq].y + v[jq].z * v[jq].z + v[jq].w * v[jq].w; }
;             ss = wave_sum(ss);
;             const float r3 = rsqrtf(ss * (1.f / D) + EPS);
;             float4* op = (float4*)(outp + (size_t)t * D) + lane;
; #pragma unroll
;             for (int jq = 0; jq < 4; ++jq) { typedef float f4v __attribute__((ext_vector_type(4))); f4v o4; o4.x = v[jq].x * r3 * gv[jq].x; o4.y = v[jq].y * r3 * gv[jq].y; o4.z = v[jq].z * r3 * gv[jq].z; o4.w = v[jq].w * r3 * gv[jq].w;
;                 __builtin_nontemporal_store(o4, (f4v*)op + 64 * jq); }
	v_lshlrev_b32_e32 v236, 16, v18
	v_and_b32_e32 v237, 0xffff0000, v18
	v_lshlrev_b32_e32 v142, 16, v202
	v_and_b32_e32 v143, 0xffff0000, v202
	v_add_f32_e32 v236, v236, v142
	v_add_f32_e32 v237, v237, v143
	v_lshlrev_b32_e32 v238, 16, v19
	v_and_b32_e32 v239, 0xffff0000, v19
	v_lshlrev_b32_e32 v142, 16, v203
	v_and_b32_e32 v143, 0xffff0000, v203
	v_add_f32_e32 v238, v238, v142
	v_add_f32_e32 v239, v239, v143
	v_lshlrev_b32_e32 v240, 16, v20
	v_and_b32_e32 v241, 0xffff0000, v20
	v_lshlrev_b32_e32 v142, 16, v204
	v_and_b32_e32 v143, 0xffff0000, v204
	v_add_f32_e32 v240, v240, v142
	v_add_f32_e32 v241, v241, v143
	v_lshlrev_b32_e32 v242, 16, v21
	v_and_b32_e32 v243, 0xffff0000, v21
	v_lshlrev_b32_e32 v142, 16, v205
	v_and_b32_e32 v143, 0xffff0000, v205
	v_add_f32_e32 v242, v242, v142
	v_add_f32_e32 v243, v243, v143
	v_lshlrev_b32_e32 v244, 16, v22
	v_and_b32_e32 v245, 0xffff0000, v22
	v_lshlrev_b32_e32 v142, 16, v206
	v_and_b32_e32 v143, 0xffff0000, v206
	v_add_f32_e32 v244, v244, v142
	v_add_f32_e32 v245, v245, v143
	v_lshlrev_b32_e32 v246, 16, v23
	v_and_b32_e32 v247, 0xffff0000, v23
	v_lshlrev_b32_e32 v142, 16, v207
	v_and_b32_e32 v143, 0xffff0000, v207
	v_add_f32_e32 v246, v246, v142
	v_add_f32_e32 v247, v247, v143
	v_lshlrev_b32_e32 v248, 16, v24
	v_and_b32_e32 v249, 0xffff0000, v24
	v_lshlrev_b32_e32 v142, 16, v208
	v_and_b32_e32 v143, 0xffff0000, v208
	v_add_f32_e32 v248, v248, v142
	v_add_f32_e32 v249, v249, v143
	v_lshlrev_b32_e32 v250, 16, v25
	v_and_b32_e32 v251, 0xffff0000, v25
	v_lshlrev_b32_e32 v142, 16, v209
	v_and_b32_e32 v143, 0xffff0000, v209
	v_add_f32_e32 v250, v250, v142
	v_add_f32_e32 v251, v251, v143
	v_mov_b32_e32 v144, 0
	v_mul_f32_e32 v145, v236, v236
	v_fmac_f32_e32 v145, v237, v237
	v_fmac_f32_e32 v145, v238, v238
	v_fmac_f32_e32 v145, v239, v239
	v_add_f32_e32 v144, v144, v145
	v_mul_f32_e32 v145, v240, v240
	v_fmac_f32_e32 v145, v241, v241
	v_fmac_f32_e32 v145, v242, v242
	v_fmac_f32_e32 v145, v243, v243
	v_add_f32_e32 v144, v144, v145
	v_mul_f32_e32 v145, v244, v244
	v_fmac_f32_e32 v145, v245, v245
	v_fmac_f32_e32 v145, v246, v246
	v_fmac_f32_e32 v145, v247, v247
	v_add_f32_e32 v144, v144, v145
	v_mul_f32_e32 v145, v248, v248
	v_fmac_f32_e32 v145, v249, v249
	v_fmac_f32_e32 v145, v250, v250
	v_fmac_f32_e32 v145, v251, v251
	v_add_f32_e32 v144, v144, v145
	s_nop 1
	v_add_f32_dpp v144, v144, v144 quad_perm:[1,0,3,2] row_mask:0xf bank_mask:0xf bound_ctrl:1
	s_nop 1
	v_add_f32_dpp v144, v144, v144 quad_perm:[2,3,0,1] row_mask:0xf bank_mask:0xf bound_ctrl:1
	s_nop 1
	v_add_f32_dpp v144, v144, v144 row_half_mirror row_mask:0xf bank_mask:0xf bound_ctrl:1
	s_nop 1
	v_add_f32_dpp v144, v144, v144 row_mirror row_mask:0xf bank_mask:0xf bound_ctrl:1
	s_nop 1
	v_readlane_b32 s10, v144, 0
	v_readlane_b32 s11, v144, 16
	v_readlane_b32 s14, v144, 32
	v_readlane_b32 s15, v144, 48
	s_nop 3
	v_mov_b32_e32 v144, s11
	v_mov_b32_e32 v145, s15
	v_add_f32_e32 v144, s10, v144
	v_add_f32_e32 v145, s14, v145
	v_add_f32_e32 v144, v144, v145
	v_fmamk_f32 v144, v144, 0x3a800000, v111
	v_rsq_f32_e32 v144, v144
	s_nop 0
	v_mul_f32_e32 v236, v236, v144
	v_mul_f32_e32 v237, v237, v144
	v_mul_f32_e32 v238, v238, v144
	v_mul_f32_e32 v239, v239, v144
	v_mul_f32_e32 v240, v240, v144
	v_mul_f32_e32 v241, v241, v144
	v_mul_f32_e32 v242, v242, v144
	v_mul_f32_e32 v243, v243, v144
	v_mul_f32_e32 v244, v244, v144
	v_mul_f32_e32 v245, v245, v144
	v_mul_f32_e32 v246, v246, v144
	v_mul_f32_e32 v247, v247, v144
	v_mul_f32_e32 v248, v248, v144
	v_mul_f32_e32 v249, v249, v144
	v_mul_f32_e32 v250, v250, v144
	v_mul_f32_e32 v251, v251, v144
	ds_read_b128 v[252:255], v155
	s_add_i32 s44, s40, 56
	s_ashr_i32 s45, s44, 31
	s_lshl_b64 s[44:45], s[44:45], 12
	v_lshl_add_u64 v[80:81], v[36:37], 0, s[44:45]
	s_waitcnt lgkmcnt(0)
	v_mul_f32_e32 v236, v236, v252
	v_mul_f32_e32 v237, v237, v253
	v_mul_f32_e32 v238, v238, v254
	v_mul_f32_e32 v239, v239, v255
	global_store_dwordx4 v[80:81], v[236:239], off nt
	ds_read_b128 v[252:255], v155 offset:1024
	s_add_i32 s44, s40, 56
	s_ashr_i32 s45, s44, 31
	s_lshl_b64 s[44:45], s[44:45], 12
	v_lshl_add_u64 v[80:81], v[36:37], 0, s[44:45]
	s_waitcnt lgkmcnt(0)
	v_mul_f32_e32 v240, v240, v252
	v_mul_f32_e32 v241, v241, v253
	v_mul_f32_e32 v242, v242, v254
	v_mul_f32_e32 v243, v243, v255
	global_store_dwordx4 v[80:81], v[240:243], off offset:1024 nt
	ds_read_b128 v[252:255], v156
	s_add_i32 s44, s40, 56
	s_ashr_i32 s45, s44, 31
	s_lshl_b64 s[44:45], s[44:45], 12
	v_lshl_add_u64 v[80:81], v[36:37], 0, s[44:45]
	s_waitcnt lgkmcnt(0)
	v_mul_f32_e32 v244, v244, v252
	v_mul_f32_e32 v245, v245, v253
	v_mul_f32_e32 v246, v246, v254
	v_mul_f32_e32 v247, v247, v255
	global_store_dwordx4 v[80:81], v[244:247], off offset:2048 nt
	ds_read_b128 v[252:255], v156 offset:1024
	s_add_i32 s44, s40, 56
	s_ashr_i32 s45, s44, 31
	s_lshl_b64 s[44:45], s[44:45], 12
	v_lshl_add_u64 v[80:81], v[36:37], 0, s[44:45]
	s_waitcnt lgkmcnt(0)
	v_mul_f32_e32 v248, v248, v252
	v_mul_f32_e32 v249, v249, v253
	v_mul_f32_e32 v250, v250, v254
	v_mul_f32_e32 v251, v251, v255
	global_store_dwordx4 v[80:81], v[248:251], off offset:3072 nt
	s_add_i32 s2, s2, s33
	s_add_i32 s40, s40, s63
	s_add_i32 s73, s73, s74
	s_cmpk_lt_i32 s2, 0x100
	s_cbranch_scc1 .LBB0_648
